# hand-scheduled main loop applied to gates and both ffn1 GEMMs; DPP row reductions in windowed/dilated attention softmax
# speedup vs baseline: 1.2242x; 1.0186x over previous
; template <int DIR>
; DI void dn_solve4(const float* M, const h16* Ki, const h16* Vi, const float* betal, const float* gcl, int half, int c, int pp, float (&x)[16]) {
;   const h16* src = half ? (Ki + c) : (Vi + c);
; #pragma unroll
;   for (int k = 0; k < 16; ++k) x[k] = 0.f;
; #pragma unroll
;   for (int il = 0; il < 64; ++il) {
;     const int ri = DIR ? 63 - il : il;
;     float part = 0.f;
; #pragma unroll
;     for (int k = 0; k < (il + 3) / 4; ++k) {
;       const int jl0 = 4 * k;
;       float mv = DIR ? M[ri * MLD + 63 - jl0 - pp] : M[ri * MLD + jl0 + pp];
;       if (jl0 + 3 >= il) mv = (jl0 + pp < il) ? mv : 0.f;
;       part += mv * x[k];
;     }
;     part += __shfl_xor(part, 1); part += __shfl_xor(part, 2);
;     const float e = half ? __expf(gcl[ri]) : 1.f;
;     const float xi = betal[ri] * (float)src[ri * LDH] * e - part;
; DI void dn_c1_unit(const Params& p, int l, int head, int oc, h16* lds) {
;     ...
;     for (int dh2 = 0; dh2 < 4; ++dh2) {
;       const int dir = dh2 >> 1, half = dh2 & 1;
;       const int nloc = dir ? 255 - oc : oc;
;       const size_t unit = (size_t)(dir * 4 + head) * 256 + nloc;
;       float x[16];
;       if (dir == 0) dn_solve4<0>(M, Ki, Vi, betal, gcl, half, c, pp, x);
;       else dn_solve4<1>(M, Ki, Vi, betal + 64, gcl + 64, half, c, pp, x);
.LBB0_312:
	s_and_b32 s2, s9, 1
	s_cmp_lt_u32 s9, 2
	s_cselect_b64 s[76:77], -1, 0
	s_cmp_eq_u32 s2, 0
	s_cselect_b64 vcc, -1, 0
	s_cmp_eq_u32 s2, 1
	v_cndmask_b32_e32 v1, v183, v184, vcc
	s_cselect_b64 s[2:3], -1, 0
	v_lshl_add_u32 v114, v129, 1, v1
	v_cndmask_b32_e64 v1, 0, 1, s[2:3]
	s_cmp_gt_u32 s9, 1
	s_mov_b64 s[4:5], -1
	v_cmp_ne_u32_e64 s[78:79], 1, v1
	s_cbranch_scc0 .Lsolve_dir0
	v_and_b32_e32 v116, 3, v182
	v_cmp_eq_u32_e64 s[88:89], 0, v116
	v_cmp_eq_u32_e64 s[90:91], 1, v116
	v_cmp_eq_u32_e64 s[92:93], 2, v116
	v_cmp_eq_u32_e64 s[98:99], 3, v116
	v_cmp_gt_u32_e64 s[34:35], 1, v116
	v_cmp_gt_u32_e64 s[18:19], 2, v116
	v_cmp_gt_u32_e64 s[22:23], 3, v116
	v_lshlrev_b32_e32 v125, 2, v116
	v_sub_u32_e32 v117, v183, v125
	v_sub_u32_e32 v126, 3, v116
	v_mul_u32_u24_e32 v126, 0x90, v126
	v_add_u32_e32 v118, v114, v126
	v_mov_b32_e32 v2, 0
	v_mov_b32_e32 v3, 0
	v_mov_b32_e32 v4, 0
	v_mov_b32_e32 v5, 0
	v_mov_b32_e32 v6, 0
	v_mov_b32_e32 v7, 0
	v_mov_b32_e32 v8, 0
	v_mov_b32_e32 v9, 0
	v_mov_b32_e32 v10, 0
	v_mov_b32_e32 v11, 0
	v_mov_b32_e32 v12, 0
	v_mov_b32_e32 v13, 0
	v_mov_b32_e32 v14, 0
	v_mov_b32_e32 v15, 0
	v_mov_b32_e32 v16, 0
	v_mov_b32_e32 v17, 0
	ds_read_b32 v18, v117 offset:36348
	ds_read_u16 v35, v118 offset:8640
	ds_read_b32 v19, v117 offset:36332
	ds_read_u16 v36, v118 offset:8064
	ds_read_b32 v20, v117 offset:36316
	ds_read_u16 v37, v118 offset:7488
	ds_read_b32 v21, v117 offset:36300
	ds_read_u16 v38, v118 offset:6912
	s_waitcnt lgkmcnt(6)
	v_cvt_f32_f16_e32 v35, v35
	s_waitcnt lgkmcnt(4)
	v_cvt_f32_f16_e32 v36, v36
	s_waitcnt lgkmcnt(2)
	v_cvt_f32_f16_e32 v37, v37
	s_waitcnt lgkmcnt(0)
	v_cvt_f32_f16_e32 v38, v38
	v_mul_f32_e32 v18, v18, v35
	v_mul_f32_e32 v19, v19, v36
	v_mul_f32_e32 v20, v20, v37
	v_mul_f32_e32 v21, v21, v38
	ds_read_b32 v22, v117 offset:36284
	ds_read_u16 v39, v118 offset:6336
	ds_read_b32 v23, v117 offset:36268
	ds_read_u16 v40, v118 offset:5760
	ds_read_b32 v24, v117 offset:36252
	ds_read_u16 v41, v118 offset:5184
	ds_read_b32 v25, v117 offset:36236
	ds_read_u16 v42, v118 offset:4608
	s_waitcnt lgkmcnt(6)
	v_cvt_f32_f16_e32 v39, v39
	s_waitcnt lgkmcnt(4)
	v_cvt_f32_f16_e32 v40, v40
	s_waitcnt lgkmcnt(2)
	v_cvt_f32_f16_e32 v41, v41
	s_waitcnt lgkmcnt(0)
	v_cvt_f32_f16_e32 v42, v42
	v_mul_f32_e32 v22, v22, v39
	v_mul_f32_e32 v23, v23, v40
	v_mul_f32_e32 v24, v24, v41
	v_mul_f32_e32 v25, v25, v42
	ds_read_b32 v26, v117 offset:36220
	ds_read_u16 v43, v118 offset:4032
	ds_read_b32 v27, v117 offset:36204
	ds_read_u16 v44, v118 offset:3456
	ds_read_b32 v28, v117 offset:36188
	ds_read_u16 v45, v118 offset:2880
	ds_read_b32 v30, v117 offset:36172
	ds_read_u16 v46, v118 offset:2304
	s_waitcnt lgkmcnt(6)
	v_cvt_f32_f16_e32 v43, v43
	s_waitcnt lgkmcnt(4)
	v_cvt_f32_f16_e32 v44, v44
	s_waitcnt lgkmcnt(2)
	v_cvt_f32_f16_e32 v45, v45
	s_waitcnt lgkmcnt(0)
	v_cvt_f32_f16_e32 v46, v46
	v_mul_f32_e32 v26, v26, v43
	v_mul_f32_e32 v27, v27, v44
	v_mul_f32_e32 v28, v28, v45
	v_mul_f32_e32 v30, v30, v46
	ds_read_b32 v31, v117 offset:36156
	ds_read_u16 v47, v118 offset:1728
	ds_read_b32 v32, v117 offset:36140
	ds_read_u16 v48, v118 offset:1152
	ds_read_b32 v33, v117 offset:36124
	ds_read_u16 v49, v118 offset:576
	ds_read_b32 v34, v117 offset:36108
	ds_read_u16 v115, v118 offset:0
	s_waitcnt lgkmcnt(6)
	v_cvt_f32_f16_e32 v47, v47
	s_waitcnt lgkmcnt(4)
	v_cvt_f32_f16_e32 v48, v48
	s_waitcnt lgkmcnt(2)
	v_cvt_f32_f16_e32 v49, v49
	s_waitcnt lgkmcnt(0)
	v_cvt_f32_f16_e32 v115, v115
	v_mul_f32_e32 v31, v31, v47
	v_mul_f32_e32 v32, v32, v48
	v_mul_f32_e32 v33, v33, v49
	v_mul_f32_e32 v34, v34, v115
	s_and_b64 vcc, exec, s[78:79]
	s_cbranch_vccnz .Lsolved1_noexp
	ds_read_b32 v35, v117 offset:36860
	ds_read_b32 v36, v117 offset:36844
	ds_read_b32 v37, v117 offset:36828
	ds_read_b32 v38, v117 offset:36812
	ds_read_b32 v39, v117 offset:36796
	ds_read_b32 v40, v117 offset:36780
	ds_read_b32 v41, v117 offset:36764
	ds_read_b32 v42, v117 offset:36748
	s_waitcnt lgkmcnt(7)
	v_mul_f32_e32 v35, 0x3fb8aa3b, v35
	s_waitcnt lgkmcnt(6)
	v_mul_f32_e32 v36, 0x3fb8aa3b, v36
	s_waitcnt lgkmcnt(5)
	v_mul_f32_e32 v37, 0x3fb8aa3b, v37
	s_waitcnt lgkmcnt(4)
	v_mul_f32_e32 v38, 0x3fb8aa3b, v38
	s_waitcnt lgkmcnt(3)
	v_mul_f32_e32 v39, 0x3fb8aa3b, v39
	s_waitcnt lgkmcnt(2)
	v_mul_f32_e32 v40, 0x3fb8aa3b, v40
	s_waitcnt lgkmcnt(1)
	v_mul_f32_e32 v41, 0x3fb8aa3b, v41
	s_waitcnt lgkmcnt(0)
	v_mul_f32_e32 v42, 0x3fb8aa3b, v42
	v_exp_f32_e32 v35, v35
	v_exp_f32_e32 v36, v36
	v_exp_f32_e32 v37, v37
	v_exp_f32_e32 v38, v38
	v_exp_f32_e32 v39, v39
	v_exp_f32_e32 v40, v40
	v_exp_f32_e32 v41, v41
	v_exp_f32_e32 v42, v42
	ds_read_b32 v43, v117 offset:36732
	ds_read_b32 v44, v117 offset:36716
	ds_read_b32 v45, v117 offset:36700
	ds_read_b32 v46, v117 offset:36684
	ds_read_b32 v47, v117 offset:36668
	ds_read_b32 v48, v117 offset:36652
	ds_read_b32 v49, v117 offset:36636
	ds_read_b32 v115, v117 offset:36620
	s_waitcnt lgkmcnt(7)
	v_mul_f32_e32 v43, 0x3fb8aa3b, v43
	s_waitcnt lgkmcnt(6)
	v_mul_f32_e32 v44, 0x3fb8aa3b, v44
	s_waitcnt lgkmcnt(5)
	v_mul_f32_e32 v45, 0x3fb8aa3b, v45
	s_waitcnt lgkmcnt(4)
	v_mul_f32_e32 v46, 0x3fb8aa3b, v46
	s_waitcnt lgkmcnt(3)
	v_mul_f32_e32 v47, 0x3fb8aa3b, v47
	s_waitcnt lgkmcnt(2)
	v_mul_f32_e32 v48, 0x3fb8aa3b, v48
	s_waitcnt lgkmcnt(1)
	v_mul_f32_e32 v49, 0x3fb8aa3b, v49
	s_waitcnt lgkmcnt(0)
	v_mul_f32_e32 v115, 0x3fb8aa3b, v115
	v_exp_f32_e32 v43, v43
	v_exp_f32_e32 v44, v44
	v_exp_f32_e32 v45, v45
	v_exp_f32_e32 v46, v46
	v_exp_f32_e32 v47, v47
	v_exp_f32_e32 v48, v48
	v_exp_f32_e32 v49, v49
	v_exp_f32_e32 v115, v115
	s_branch .Lsolved1_go

; template <int DIR>
; DI void dn_solve4(const float* M, const h16* Ki, const h16* Vi, const float* betal, const float* gcl, int half, int c, int pp, float (&x)[16]) {
;     ...
; #pragma unroll
;   for (int il = 0; il < 64; ++il) {
;     const int ri = DIR ? 63 - il : il;
;     float part = 0.f;
; #pragma unroll
;     for (int k = 0; k < (il + 3) / 4; ++k) {
;       const int jl0 = 4 * k;
;       float mv = DIR ? M[ri * MLD + 63 - jl0 - pp] : M[ri * MLD + jl0 + pp];
;       if (jl0 + 3 >= il) mv = (jl0 + pp < il) ? mv : 0.f;
;       part += mv * x[k];
;     }
;     part += __shfl_xor(part, 1); part += __shfl_xor(part, 2);
;     const float e = half ? __expf(gcl[ri]) : 1.f;
;     const float xi = betal[ri] * (float)src[ri * LDH] * e - part;
;     if ((il & 3) == pp) x[il >> 2] = xi;
;   }
.Lsolved1_go:
	s_nop 0
	s_waitcnt lgkmcnt(0)
	v_add_u32_e32 v120, 0x8adc, v117
	ds_read_b32 v148, v120
	v_add_u32_e32 v121, 0x89cc, v117
	ds_read_b32 v216, v121
	v_mul_f32_e32 v125, v35, v18
	v_cndmask_b32_e64 v2, v2, v125, s[88:89]
	v_add_u32_e32 v119, 0x88bc, v117
	ds_read_b32 v132, v119
	s_waitcnt lgkmcnt(2)
	v_cndmask_b32_e64 v126, 0, v148, s[34:35]
	v_mul_f32_e32 v125, v126, v2
	s_nop 1
	v_add_f32_dpp v127, v125, v125 quad_perm:[1,0,3,2] row_mask:0xf bank_mask:0xf
	s_nop 1
	v_add_f32_dpp v125, v127, v127 quad_perm:[2,3,0,1] row_mask:0xf bank_mask:0xf
	v_fma_f32 v127, v35, v18, -v125
	v_cndmask_b32_e64 v2, v2, v127, s[90:91]
	v_add_u32_e32 v120, 0x87ac, v117
	ds_read_b32 v148, v120
	s_waitcnt lgkmcnt(2)
	v_cndmask_b32_e64 v126, 0, v216, s[18:19]
	v_mul_f32_e32 v125, v126, v2
	s_nop 1
	v_add_f32_dpp v127, v125, v125 quad_perm:[1,0,3,2] row_mask:0xf bank_mask:0xf
	s_nop 1
	v_add_f32_dpp v125, v127, v127 quad_perm:[2,3,0,1] row_mask:0xf bank_mask:0xf
	v_fma_f32 v127, v35, v18, -v125
	v_cndmask_b32_e64 v2, v2, v127, s[92:93]
	v_add_u32_e32 v121, 0x868c, v117
	ds_read2_b32 v[216:217], v121 offset0:4 offset1:0
	s_waitcnt lgkmcnt(2)
	v_cndmask_b32_e64 v126, 0, v132, s[22:23]
	v_mul_f32_e32 v125, v126, v2
	s_nop 1
	v_add_f32_dpp v127, v125, v125 quad_perm:[1,0,3,2] row_mask:0xf bank_mask:0xf
	s_nop 1
	v_add_f32_dpp v125, v127, v127 quad_perm:[2,3,0,1] row_mask:0xf bank_mask:0xf
	v_fma_f32 v127, v35, v18, -v125
	v_cndmask_b32_e64 v2, v2, v127, s[98:99]
	v_add_u32_e32 v119, 0x857c, v117
	ds_read2_b32 v[132:133], v119 offset0:4 offset1:0
	s_waitcnt lgkmcnt(2)
	v_mul_f32_e32 v125, v148, v2
	s_waitcnt lgkmcnt(1)
	v_mul_f32_e32 v124, v216, v2
	s_nop 0
	v_add_f32_dpp v127, v125, v125 quad_perm:[1,0,3,2] row_mask:0xf bank_mask:0xf
	s_nop 1
	v_add_f32_dpp v125, v127, v127 quad_perm:[2,3,0,1] row_mask:0xf bank_mask:0xf
	v_fma_f32 v127, v36, v19, -v125
	v_cndmask_b32_e64 v3, v3, v127, s[88:89]
	v_add_u32_e32 v120, 0x846c, v117
	ds_read2_b32 v[148:149], v120 offset0:4 offset1:0
	v_cndmask_b32_e64 v126, 0, v217, s[34:35]
	v_fma_f32 v125, v126, v3, v124
	s_waitcnt lgkmcnt(1)
	v_mul_f32_e32 v122, v132, v2
	s_nop 0
	v_add_f32_dpp v127, v125, v125 quad_perm:[1,0,3,2] row_mask:0xf bank_mask:0xf
	s_nop 1
	v_add_f32_dpp v125, v127, v127 quad_perm:[2,3,0,1] row_mask:0xf bank_mask:0xf
	v_fma_f32 v127, v36, v19, -v125
	v_cndmask_b32_e64 v3, v3, v127, s[90:91]
	v_add_u32_e32 v121, 0x835c, v117
	ds_read2_b32 v[216:217], v121 offset0:4 offset1:0
	v_cndmask_b32_e64 v126, 0, v133, s[18:19]
	v_fma_f32 v125, v126, v3, v122
	s_waitcnt lgkmcnt(1)
	v_mul_f32_e32 v123, v148, v2
	s_nop 0
	v_add_f32_dpp v127, v125, v125 quad_perm:[1,0,3,2] row_mask:0xf bank_mask:0xf
	s_nop 1
	v_add_f32_dpp v125, v127, v127 quad_perm:[2,3,0,1] row_mask:0xf bank_mask:0xf
	v_fma_f32 v127, v36, v19, -v125
	v_cndmask_b32_e64 v3, v3, v127, s[92:93]
	v_add_u32_e32 v119, 0x823c, v117
	ds_read2_b32 v[132:133], v119 offset0:8 offset1:4
	ds_read_b32 v134, v119
	v_cndmask_b32_e64 v126, 0, v149, s[22:23]
	v_fma_f32 v125, v126, v3, v123
	s_waitcnt lgkmcnt(2)
	v_mul_f32_e32 v124, v216, v2
	s_nop 0
	v_add_f32_dpp v127, v125, v125 quad_perm:[1,0,3,2] row_mask:0xf bank_mask:0xf
	s_nop 1
	v_add_f32_dpp v125, v127, v127 quad_perm:[2,3,0,1] row_mask:0xf bank_mask:0xf
	v_fma_f32 v127, v36, v19, -v125
	v_cndmask_b32_e64 v3, v3, v127, s[98:99]
	v_add_u32_e32 v120, 0x812c, v117
	ds_read2_b32 v[148:149], v120 offset0:8 offset1:4
	ds_read_b32 v150, v120
	v_fma_f32 v125, v217, v3, v124
	s_waitcnt lgkmcnt(3)
	v_mul_f32_e32 v122, v132, v2
	v_fmac_f32_e32 v122, v133, v3
	v_add_f32_dpp v127, v125, v125 quad_perm:[1,0,3,2] row_mask:0xf bank_mask:0xf
	s_nop 1
	v_add_f32_dpp v125, v127, v127 quad_perm:[2,3,0,1] row_mask:0xf bank_mask:0xf
	v_fma_f32 v127, v37, v20, -v125
	v_cndmask_b32_e64 v4, v4, v127, s[88:89]
	v_add_u32_e32 v121, 0x801c, v117
	ds_read2_b32 v[216:217], v121 offset0:8 offset1:4
	ds_read_b32 v218, v121
	s_waitcnt lgkmcnt(4)
	v_cndmask_b32_e64 v126, 0, v134, s[34:35]
	v_fma_f32 v125, v126, v4, v122
	s_waitcnt lgkmcnt(3)
	v_mul_f32_e32 v123, v148, v2
	v_fmac_f32_e32 v123, v149, v3
	v_add_f32_dpp v127, v125, v125 quad_perm:[1,0,3,2] row_mask:0xf bank_mask:0xf
	s_nop 1
	v_add_f32_dpp v125, v127, v127 quad_perm:[2,3,0,1] row_mask:0xf bank_mask:0xf
	v_fma_f32 v127, v37, v20, -v125
	v_cndmask_b32_e64 v4, v4, v127, s[90:91]
	v_add_u32_e32 v119, 0x7f0c, v117
	ds_read2_b32 v[132:133], v119 offset0:8 offset1:4
	ds_read_b32 v134, v119
	s_waitcnt lgkmcnt(4)
	v_cndmask_b32_e64 v126, 0, v150, s[18:19]
	v_fma_f32 v125, v126, v4, v123
	s_waitcnt lgkmcnt(3)
	v_mul_f32_e32 v124, v216, v2
	v_fmac_f32_e32 v124, v217, v3
	v_add_f32_dpp v127, v125, v125 quad_perm:[1,0,3,2] row_mask:0xf bank_mask:0xf
	s_nop 1
	v_add_f32_dpp v125, v127, v127 quad_perm:[2,3,0,1] row_mask:0xf bank_mask:0xf
	v_fma_f32 v127, v37, v20, -v125
	v_cndmask_b32_e64 v4, v4, v127, s[92:93]
	v_add_u32_e32 v120, 0x7dec, v117
	ds_read2_b32 v[148:149], v120 offset0:12 offset1:8
	ds_read2_b32 v[150:151], v120 offset0:4 offset1:0
	s_waitcnt lgkmcnt(4)
	v_cndmask_b32_e64 v126, 0, v218, s[22:23]
	v_fma_f32 v125, v126, v4, v124
	s_waitcnt lgkmcnt(3)
	v_mul_f32_e32 v122, v132, v2
	v_fmac_f32_e32 v122, v133, v3
	v_add_f32_dpp v127, v125, v125 quad_perm:[1,0,3,2] row_mask:0xf bank_mask:0xf
	s_nop 1
	v_add_f32_dpp v125, v127, v127 quad_perm:[2,3,0,1] row_mask:0xf bank_mask:0xf
	v_fma_f32 v127, v37, v20, -v125
	v_cndmask_b32_e64 v4, v4, v127, s[98:99]
	v_add_u32_e32 v121, 0x7cdc, v117
	ds_read2_b32 v[216:217], v121 offset0:12 offset1:8
	ds_read2_b32 v[218:219], v121 offset0:4 offset1:0
	s_waitcnt lgkmcnt(4)
	v_fma_f32 v125, v134, v4, v122
	s_waitcnt lgkmcnt(3)
; template <int DIR>
; DI void dn_solve4(const float* M, const h16* Ki, const h16* Vi, const float* betal, const float* gcl, int half, int c, int pp, float (&x)[16]) {
;     ...
; #pragma unroll
;   for (int il = 0; il < 64; ++il) {
;     const int ri = DIR ? 63 - il : il;
;     float part = 0.f;
; #pragma unroll
;     for (int k = 0; k < (il + 3) / 4; ++k) {
;       const int jl0 = 4 * k;
;       float mv = DIR ? M[ri * MLD + 63 - jl0 - pp] : M[ri * MLD + jl0 + pp];
;       if (jl0 + 3 >= il) mv = (jl0 + pp < il) ? mv : 0.f;
;       part += mv * x[k];
;     }
;     part += __shfl_xor(part, 1); part += __shfl_xor(part, 2);
;     const float e = half ? __expf(gcl[ri]) : 1.f;
;     const float xi = betal[ri] * (float)src[ri * LDH] * e - part;
;     if ((il & 3) == pp) x[il >> 2] = xi;
;   }
	v_mul_f32_e32 v123, v148, v2
	v_fmac_f32_e32 v123, v149, v3
	v_add_f32_dpp v127, v125, v125 quad_perm:[1,0,3,2] row_mask:0xf bank_mask:0xf
	s_waitcnt lgkmcnt(2)
	v_fmac_f32_e32 v123, v150, v4
	s_nop 0
	v_add_f32_dpp v125, v127, v127 quad_perm:[2,3,0,1] row_mask:0xf bank_mask:0xf
	v_fma_f32 v127, v38, v21, -v125
	v_cndmask_b32_e64 v5, v5, v127, s[88:89]
	v_add_u32_e32 v119, 0x7bcc, v117
	ds_read2_b32 v[132:133], v119 offset0:12 offset1:8
	ds_read2_b32 v[134:135], v119 offset0:4 offset1:0
	v_cndmask_b32_e64 v126, 0, v151, s[34:35]
	v_fma_f32 v125, v126, v5, v123
	s_waitcnt lgkmcnt(3)
	v_mul_f32_e32 v124, v216, v2
	v_fmac_f32_e32 v124, v217, v3
	v_add_f32_dpp v127, v125, v125 quad_perm:[1,0,3,2] row_mask:0xf bank_mask:0xf
	s_waitcnt lgkmcnt(2)
	v_fmac_f32_e32 v124, v218, v4
	s_nop 0
	v_add_f32_dpp v125, v127, v127 quad_perm:[2,3,0,1] row_mask:0xf bank_mask:0xf
	v_fma_f32 v127, v38, v21, -v125
	v_cndmask_b32_e64 v5, v5, v127, s[90:91]
	v_add_u32_e32 v120, 0x7abc, v117
	ds_read2_b32 v[148:149], v120 offset0:12 offset1:8
	ds_read2_b32 v[150:151], v120 offset0:4 offset1:0
	v_cndmask_b32_e64 v126, 0, v219, s[18:19]
	v_fma_f32 v125, v126, v5, v124
	s_waitcnt lgkmcnt(3)
	v_mul_f32_e32 v122, v132, v2
	v_fmac_f32_e32 v122, v133, v3
	v_add_f32_dpp v127, v125, v125 quad_perm:[1,0,3,2] row_mask:0xf bank_mask:0xf
	s_waitcnt lgkmcnt(2)
	v_fmac_f32_e32 v122, v134, v4
	s_nop 0
	v_add_f32_dpp v125, v127, v127 quad_perm:[2,3,0,1] row_mask:0xf bank_mask:0xf
	v_fma_f32 v127, v38, v21, -v125
	v_cndmask_b32_e64 v5, v5, v127, s[92:93]
	v_add_u32_e32 v121, 0x799c, v117
	ds_read2_b32 v[216:217], v121 offset0:16 offset1:12
	ds_read2_b32 v[218:219], v121 offset0:8 offset1:4
	ds_read_b32 v220, v121
	v_cndmask_b32_e64 v126, 0, v135, s[22:23]
	v_fma_f32 v125, v126, v5, v122
	s_waitcnt lgkmcnt(4)
	v_mul_f32_e32 v123, v148, v2
	v_fmac_f32_e32 v123, v149, v3
	v_add_f32_dpp v127, v125, v125 quad_perm:[1,0,3,2] row_mask:0xf bank_mask:0xf
	s_waitcnt lgkmcnt(3)
	v_fmac_f32_e32 v123, v150, v4
	s_nop 0
	v_add_f32_dpp v125, v127, v127 quad_perm:[2,3,0,1] row_mask:0xf bank_mask:0xf
	v_fma_f32 v127, v38, v21, -v125
	v_cndmask_b32_e64 v5, v5, v127, s[98:99]
	v_add_u32_e32 v119, 0x788c, v117
	ds_read2_b32 v[132:133], v119 offset0:16 offset1:12
	ds_read2_b32 v[134:135], v119 offset0:8 offset1:4
	ds_read_b32 v136, v119
	v_fma_f32 v125, v151, v5, v123
	s_waitcnt lgkmcnt(5)
	v_mul_f32_e32 v124, v216, v2
	v_fmac_f32_e32 v124, v217, v3
	v_add_f32_dpp v127, v125, v125 quad_perm:[1,0,3,2] row_mask:0xf bank_mask:0xf
	s_waitcnt lgkmcnt(4)
	v_fmac_f32_e32 v124, v218, v4
	v_fmac_f32_e32 v124, v219, v5
	v_add_f32_dpp v125, v127, v127 quad_perm:[2,3,0,1] row_mask:0xf bank_mask:0xf
	v_fma_f32 v127, v39, v22, -v125
	v_cndmask_b32_e64 v6, v6, v127, s[88:89]
	v_add_u32_e32 v120, 0x777c, v117
	ds_read2_b32 v[148:149], v120 offset0:16 offset1:12
	ds_read2_b32 v[150:151], v120 offset0:8 offset1:4
	ds_read_b32 v152, v120
	s_waitcnt lgkmcnt(6)
	v_cndmask_b32_e64 v126, 0, v220, s[34:35]
	v_fma_f32 v125, v126, v6, v124
	s_waitcnt lgkmcnt(5)
	v_mul_f32_e32 v122, v132, v2
	v_fmac_f32_e32 v122, v133, v3
	v_add_f32_dpp v127, v125, v125 quad_perm:[1,0,3,2] row_mask:0xf bank_mask:0xf
	s_waitcnt lgkmcnt(4)
	v_fmac_f32_e32 v122, v134, v4
	v_fmac_f32_e32 v122, v135, v5
	v_add_f32_dpp v125, v127, v127 quad_perm:[2,3,0,1] row_mask:0xf bank_mask:0xf
	v_fma_f32 v127, v39, v22, -v125
	v_cndmask_b32_e64 v6, v6, v127, s[90:91]
	v_add_u32_e32 v121, 0x766c, v117
	ds_read2_b32 v[216:217], v121 offset0:16 offset1:12
	ds_read2_b32 v[218:219], v121 offset0:8 offset1:4
	ds_read_b32 v220, v121
	s_waitcnt lgkmcnt(6)
	v_cndmask_b32_e64 v126, 0, v136, s[18:19]
	v_fma_f32 v125, v126, v6, v122
	s_waitcnt lgkmcnt(5)
	v_mul_f32_e32 v123, v148, v2
	v_fmac_f32_e32 v123, v149, v3
	v_add_f32_dpp v127, v125, v125 quad_perm:[1,0,3,2] row_mask:0xf bank_mask:0xf
	s_waitcnt lgkmcnt(4)
	v_fmac_f32_e32 v123, v150, v4
	v_fmac_f32_e32 v123, v151, v5
	v_add_f32_dpp v125, v127, v127 quad_perm:[2,3,0,1] row_mask:0xf bank_mask:0xf
	v_fma_f32 v127, v39, v22, -v125
	v_cndmask_b32_e64 v6, v6, v127, s[92:93]
	v_add_u32_e32 v119, 0x754c, v117
	ds_read2_b32 v[132:133], v119 offset0:20 offset1:16
	ds_read2_b32 v[134:135], v119 offset0:12 offset1:8
	ds_read2_b32 v[136:137], v119 offset0:4 offset1:0
	s_waitcnt lgkmcnt(6)
	v_cndmask_b32_e64 v126, 0, v152, s[22:23]
	v_fma_f32 v125, v126, v6, v123
	s_waitcnt lgkmcnt(5)
	v_mul_f32_e32 v124, v216, v2
	v_fmac_f32_e32 v124, v217, v3
	v_add_f32_dpp v127, v125, v125 quad_perm:[1,0,3,2] row_mask:0xf bank_mask:0xf
	s_waitcnt lgkmcnt(4)
	v_fmac_f32_e32 v124, v218, v4
	v_fmac_f32_e32 v124, v219, v5
	v_add_f32_dpp v125, v127, v127 quad_perm:[2,3,0,1] row_mask:0xf bank_mask:0xf
	v_fma_f32 v127, v39, v22, -v125
	v_cndmask_b32_e64 v6, v6, v127, s[98:99]
	v_add_u32_e32 v120, 0x743c, v117
	ds_read2_b32 v[148:149], v120 offset0:20 offset1:16
	ds_read2_b32 v[150:151], v120 offset0:12 offset1:8
	ds_read2_b32 v[152:153], v120 offset0:4 offset1:0
	s_waitcnt lgkmcnt(6)
	v_fma_f32 v125, v220, v6, v124
	s_waitcnt lgkmcnt(5)
	v_mul_f32_e32 v122, v132, v2
	v_fmac_f32_e32 v122, v133, v3
	v_add_f32_dpp v127, v125, v125 quad_perm:[1,0,3,2] row_mask:0xf bank_mask:0xf
	s_waitcnt lgkmcnt(4)
	v_fmac_f32_e32 v122, v134, v4
	v_fmac_f32_e32 v122, v135, v5
	v_add_f32_dpp v125, v127, v127 quad_perm:[2,3,0,1] row_mask:0xf bank_mask:0xf
	v_fma_f32 v127, v40, v23, -v125
	v_cndmask_b32_e64 v7, v7, v127, s[88:89]
	s_waitcnt lgkmcnt(3)
	v_fmac_f32_e32 v122, v136, v6
	v_add_u32_e32 v121, 0x732c, v117
	ds_read2_b32 v[216:217], v121 offset0:20 offset1:16
	ds_read2_b32 v[218:219], v121 offset0:12 offset1:8
	ds_read2_b32 v[220:221], v121 offset0:4 offset1:0
	v_cndmask_b32_e64 v126, 0, v137, s[34:35]
	v_fma_f32 v125, v126, v7, v122
	s_waitcnt lgkmcnt(5)
; template <int DIR>
; DI void dn_solve4(const float* M, const h16* Ki, const h16* Vi, const float* betal, const float* gcl, int half, int c, int pp, float (&x)[16]) {
;     ...
; #pragma unroll
;   for (int il = 0; il < 64; ++il) {
;     const int ri = DIR ? 63 - il : il;
;     float part = 0.f;
; #pragma unroll
;     for (int k = 0; k < (il + 3) / 4; ++k) {
;       const int jl0 = 4 * k;
;       float mv = DIR ? M[ri * MLD + 63 - jl0 - pp] : M[ri * MLD + jl0 + pp];
;       if (jl0 + 3 >= il) mv = (jl0 + pp < il) ? mv : 0.f;
;       part += mv * x[k];
;     }
;     part += __shfl_xor(part, 1); part += __shfl_xor(part, 2);
;     const float e = half ? __expf(gcl[ri]) : 1.f;
;     const float xi = betal[ri] * (float)src[ri * LDH] * e - part;
;     if ((il & 3) == pp) x[il >> 2] = xi;
;   }
	v_mul_f32_e32 v123, v148, v2
	v_fmac_f32_e32 v123, v149, v3
	v_add_f32_dpp v127, v125, v125 quad_perm:[1,0,3,2] row_mask:0xf bank_mask:0xf
	s_waitcnt lgkmcnt(4)
	v_fmac_f32_e32 v123, v150, v4
	v_fmac_f32_e32 v123, v151, v5
	v_add_f32_dpp v125, v127, v127 quad_perm:[2,3,0,1] row_mask:0xf bank_mask:0xf
	v_fma_f32 v127, v40, v23, -v125
	v_cndmask_b32_e64 v7, v7, v127, s[90:91]
	s_waitcnt lgkmcnt(3)
	v_fmac_f32_e32 v123, v152, v6
	v_add_u32_e32 v119, 0x721c, v117
	ds_read2_b32 v[132:133], v119 offset0:20 offset1:16
	ds_read2_b32 v[134:135], v119 offset0:12 offset1:8
	ds_read2_b32 v[136:137], v119 offset0:4 offset1:0
	v_cndmask_b32_e64 v126, 0, v153, s[18:19]
	v_fma_f32 v125, v126, v7, v123
	s_waitcnt lgkmcnt(5)
	v_mul_f32_e32 v124, v216, v2
	v_fmac_f32_e32 v124, v217, v3
	v_add_f32_dpp v127, v125, v125 quad_perm:[1,0,3,2] row_mask:0xf bank_mask:0xf
	s_waitcnt lgkmcnt(4)
	v_fmac_f32_e32 v124, v218, v4
	v_fmac_f32_e32 v124, v219, v5
	v_add_f32_dpp v125, v127, v127 quad_perm:[2,3,0,1] row_mask:0xf bank_mask:0xf
	v_fma_f32 v127, v40, v23, -v125
	v_cndmask_b32_e64 v7, v7, v127, s[92:93]
	s_waitcnt lgkmcnt(3)
	v_fmac_f32_e32 v124, v220, v6
	v_add_u32_e32 v120, 0x70fc, v117
	ds_read2_b32 v[148:149], v120 offset0:24 offset1:20
	ds_read2_b32 v[150:151], v120 offset0:16 offset1:12
	ds_read2_b32 v[152:153], v120 offset0:8 offset1:4
	ds_read_b32 v154, v120
	v_cndmask_b32_e64 v126, 0, v221, s[22:23]
	v_fma_f32 v125, v126, v7, v124
	s_waitcnt lgkmcnt(6)
	v_mul_f32_e32 v122, v132, v2
	v_fmac_f32_e32 v122, v133, v3
	v_add_f32_dpp v127, v125, v125 quad_perm:[1,0,3,2] row_mask:0xf bank_mask:0xf
	s_waitcnt lgkmcnt(5)
	v_fmac_f32_e32 v122, v134, v4
	v_fmac_f32_e32 v122, v135, v5
	v_add_f32_dpp v125, v127, v127 quad_perm:[2,3,0,1] row_mask:0xf bank_mask:0xf
	v_fma_f32 v127, v40, v23, -v125
	v_cndmask_b32_e64 v7, v7, v127, s[98:99]
	s_waitcnt lgkmcnt(4)
	v_fmac_f32_e32 v122, v136, v6
	v_add_u32_e32 v121, 0x6fec, v117
	ds_read2_b32 v[216:217], v121 offset0:24 offset1:20
	ds_read2_b32 v[218:219], v121 offset0:16 offset1:12
	ds_read2_b32 v[220:221], v121 offset0:8 offset1:4
	ds_read_b32 v222, v121
	v_fma_f32 v125, v137, v7, v122
	s_waitcnt lgkmcnt(7)
	v_mul_f32_e32 v123, v148, v2
	v_fmac_f32_e32 v123, v149, v3
	v_add_f32_dpp v127, v125, v125 quad_perm:[1,0,3,2] row_mask:0xf bank_mask:0xf
	s_waitcnt lgkmcnt(6)
	v_fmac_f32_e32 v123, v150, v4
	v_fmac_f32_e32 v123, v151, v5
	v_add_f32_dpp v125, v127, v127 quad_perm:[2,3,0,1] row_mask:0xf bank_mask:0xf
	v_fma_f32 v127, v41, v24, -v125
	v_cndmask_b32_e64 v8, v8, v127, s[88:89]
	s_waitcnt lgkmcnt(5)
	v_fmac_f32_e32 v123, v152, v6
	v_fmac_f32_e32 v123, v153, v7
	v_add_u32_e32 v119, 0x6edc, v117
	ds_read2_b32 v[132:133], v119 offset0:24 offset1:20
	ds_read2_b32 v[134:135], v119 offset0:16 offset1:12
	ds_read2_b32 v[136:137], v119 offset0:8 offset1:4
	ds_read_b32 v138, v119
	s_waitcnt lgkmcnt(8)
	v_cndmask_b32_e64 v126, 0, v154, s[34:35]
	v_fma_f32 v125, v126, v8, v123
	s_waitcnt lgkmcnt(7)
	v_mul_f32_e32 v124, v216, v2
	v_fmac_f32_e32 v124, v217, v3
	v_add_f32_dpp v127, v125, v125 quad_perm:[1,0,3,2] row_mask:0xf bank_mask:0xf
	s_waitcnt lgkmcnt(6)
	v_fmac_f32_e32 v124, v218, v4
	v_fmac_f32_e32 v124, v219, v5
	v_add_f32_dpp v125, v127, v127 quad_perm:[2,3,0,1] row_mask:0xf bank_mask:0xf
	v_fma_f32 v127, v41, v24, -v125
	v_cndmask_b32_e64 v8, v8, v127, s[90:91]
	s_waitcnt lgkmcnt(5)
	v_fmac_f32_e32 v124, v220, v6
	v_fmac_f32_e32 v124, v221, v7
	v_add_u32_e32 v120, 0x6dcc, v117
	ds_read2_b32 v[148:149], v120 offset0:24 offset1:20
	ds_read2_b32 v[150:151], v120 offset0:16 offset1:12
	ds_read2_b32 v[152:153], v120 offset0:8 offset1:4
	ds_read_b32 v154, v120
	s_waitcnt lgkmcnt(8)
	v_cndmask_b32_e64 v126, 0, v222, s[18:19]
	v_fma_f32 v125, v126, v8, v124
	s_waitcnt lgkmcnt(7)
	v_mul_f32_e32 v122, v132, v2
	v_fmac_f32_e32 v122, v133, v3
	v_add_f32_dpp v127, v125, v125 quad_perm:[1,0,3,2] row_mask:0xf bank_mask:0xf
	s_waitcnt lgkmcnt(6)
	v_fmac_f32_e32 v122, v134, v4
	v_fmac_f32_e32 v122, v135, v5
	v_add_f32_dpp v125, v127, v127 quad_perm:[2,3,0,1] row_mask:0xf bank_mask:0xf
	v_fma_f32 v127, v41, v24, -v125
	v_cndmask_b32_e64 v8, v8, v127, s[92:93]
	s_waitcnt lgkmcnt(5)
	v_fmac_f32_e32 v122, v136, v6
	v_fmac_f32_e32 v122, v137, v7
	v_add_u32_e32 v121, 0x6cac, v117
	ds_read2_b32 v[216:217], v121 offset0:28 offset1:24
	ds_read2_b32 v[218:219], v121 offset0:20 offset1:16
	ds_read2_b32 v[220:221], v121 offset0:12 offset1:8
	ds_read2_b32 v[222:223], v121 offset0:4 offset1:0
	s_waitcnt lgkmcnt(8)
	v_cndmask_b32_e64 v126, 0, v138, s[22:23]
	v_fma_f32 v125, v126, v8, v122
	s_waitcnt lgkmcnt(7)
	v_mul_f32_e32 v123, v148, v2
	v_fmac_f32_e32 v123, v149, v3
	v_add_f32_dpp v127, v125, v125 quad_perm:[1,0,3,2] row_mask:0xf bank_mask:0xf
	s_waitcnt lgkmcnt(6)
	v_fmac_f32_e32 v123, v150, v4
	v_fmac_f32_e32 v123, v151, v5
	v_add_f32_dpp v125, v127, v127 quad_perm:[2,3,0,1] row_mask:0xf bank_mask:0xf
	v_fma_f32 v127, v41, v24, -v125
	v_cndmask_b32_e64 v8, v8, v127, s[98:99]
	s_waitcnt lgkmcnt(5)
	v_fmac_f32_e32 v123, v152, v6
	v_fmac_f32_e32 v123, v153, v7
	v_add_u32_e32 v119, 0x6b9c, v117
	ds_read2_b32 v[132:133], v119 offset0:28 offset1:24
	ds_read2_b32 v[134:135], v119 offset0:20 offset1:16
	ds_read2_b32 v[136:137], v119 offset0:12 offset1:8
	ds_read2_b32 v[138:139], v119 offset0:4 offset1:0
	s_waitcnt lgkmcnt(8)
	v_fma_f32 v125, v154, v8, v123
	s_waitcnt lgkmcnt(7)
	v_mul_f32_e32 v124, v216, v2
	v_fmac_f32_e32 v124, v217, v3
	v_add_f32_dpp v127, v125, v125 quad_perm:[1,0,3,2] row_mask:0xf bank_mask:0xf
	s_waitcnt lgkmcnt(6)
	v_fmac_f32_e32 v124, v218, v4
	v_fmac_f32_e32 v124, v219, v5
	v_add_f32_dpp v125, v127, v127 quad_perm:[2,3,0,1] row_mask:0xf bank_mask:0xf
	v_fma_f32 v127, v42, v25, -v125
	v_cndmask_b32_e64 v9, v9, v127, s[88:89]
	s_waitcnt lgkmcnt(5)
; template <int DIR>
; DI void dn_solve4(const float* M, const h16* Ki, const h16* Vi, const float* betal, const float* gcl, int half, int c, int pp, float (&x)[16]) {
;     ...
; #pragma unroll
;   for (int il = 0; il < 64; ++il) {
;     const int ri = DIR ? 63 - il : il;
;     float part = 0.f;
; #pragma unroll
;     for (int k = 0; k < (il + 3) / 4; ++k) {
;       const int jl0 = 4 * k;
;       float mv = DIR ? M[ri * MLD + 63 - jl0 - pp] : M[ri * MLD + jl0 + pp];
;       if (jl0 + 3 >= il) mv = (jl0 + pp < il) ? mv : 0.f;
;       part += mv * x[k];
;     }
;     part += __shfl_xor(part, 1); part += __shfl_xor(part, 2);
;     const float e = half ? __expf(gcl[ri]) : 1.f;
;     const float xi = betal[ri] * (float)src[ri * LDH] * e - part;
;     if ((il & 3) == pp) x[il >> 2] = xi;
;   }
	v_fmac_f32_e32 v124, v220, v6
	v_fmac_f32_e32 v124, v221, v7
	s_waitcnt lgkmcnt(4)
	v_fmac_f32_e32 v124, v222, v8
	v_add_u32_e32 v120, 0x6a8c, v117
	ds_read2_b32 v[148:149], v120 offset0:28 offset1:24
	ds_read2_b32 v[150:151], v120 offset0:20 offset1:16
	ds_read2_b32 v[152:153], v120 offset0:12 offset1:8
	ds_read2_b32 v[154:155], v120 offset0:4 offset1:0
	v_cndmask_b32_e64 v126, 0, v223, s[34:35]
	v_fma_f32 v125, v126, v9, v124
	s_waitcnt lgkmcnt(7)
	v_mul_f32_e32 v122, v132, v2
	v_fmac_f32_e32 v122, v133, v3
	v_add_f32_dpp v127, v125, v125 quad_perm:[1,0,3,2] row_mask:0xf bank_mask:0xf
	s_waitcnt lgkmcnt(6)
	v_fmac_f32_e32 v122, v134, v4
	v_fmac_f32_e32 v122, v135, v5
	v_add_f32_dpp v125, v127, v127 quad_perm:[2,3,0,1] row_mask:0xf bank_mask:0xf
	v_fma_f32 v127, v42, v25, -v125
	v_cndmask_b32_e64 v9, v9, v127, s[90:91]
	s_waitcnt lgkmcnt(5)
	v_fmac_f32_e32 v122, v136, v6
	v_fmac_f32_e32 v122, v137, v7
	s_waitcnt lgkmcnt(4)
	v_fmac_f32_e32 v122, v138, v8
	v_add_u32_e32 v121, 0x697c, v117
	ds_read2_b32 v[216:217], v121 offset0:28 offset1:24
	ds_read2_b32 v[218:219], v121 offset0:20 offset1:16
	ds_read2_b32 v[220:221], v121 offset0:12 offset1:8
	ds_read2_b32 v[222:223], v121 offset0:4 offset1:0
	v_cndmask_b32_e64 v126, 0, v139, s[18:19]
	v_fma_f32 v125, v126, v9, v122
	s_waitcnt lgkmcnt(7)
	v_mul_f32_e32 v123, v148, v2
	v_fmac_f32_e32 v123, v149, v3
	v_add_f32_dpp v127, v125, v125 quad_perm:[1,0,3,2] row_mask:0xf bank_mask:0xf
	s_waitcnt lgkmcnt(6)
	v_fmac_f32_e32 v123, v150, v4
	v_fmac_f32_e32 v123, v151, v5
	v_add_f32_dpp v125, v127, v127 quad_perm:[2,3,0,1] row_mask:0xf bank_mask:0xf
	v_fma_f32 v127, v42, v25, -v125
	v_cndmask_b32_e64 v9, v9, v127, s[92:93]
	s_waitcnt lgkmcnt(5)
	v_fmac_f32_e32 v123, v152, v6
	v_fmac_f32_e32 v123, v153, v7
	s_waitcnt lgkmcnt(4)
	v_fmac_f32_e32 v123, v154, v8
	v_add_u32_e32 v119, 0x685c, v117
	ds_read2_b32 v[132:133], v119 offset0:32 offset1:28
	ds_read2_b32 v[134:135], v119 offset0:24 offset1:20
	ds_read2_b32 v[136:137], v119 offset0:16 offset1:12
	ds_read2_b32 v[138:139], v119 offset0:8 offset1:4
	ds_read_b32 v140, v119
	v_cndmask_b32_e64 v126, 0, v155, s[22:23]
	v_fma_f32 v125, v126, v9, v123
	s_waitcnt lgkmcnt(8)
	v_mul_f32_e32 v124, v216, v2
	v_fmac_f32_e32 v124, v217, v3
	v_add_f32_dpp v127, v125, v125 quad_perm:[1,0,3,2] row_mask:0xf bank_mask:0xf
	s_waitcnt lgkmcnt(7)
	v_fmac_f32_e32 v124, v218, v4
	v_fmac_f32_e32 v124, v219, v5
	v_add_f32_dpp v125, v127, v127 quad_perm:[2,3,0,1] row_mask:0xf bank_mask:0xf
	v_fma_f32 v127, v42, v25, -v125
	v_cndmask_b32_e64 v9, v9, v127, s[98:99]
	s_waitcnt lgkmcnt(6)
	v_fmac_f32_e32 v124, v220, v6
	v_fmac_f32_e32 v124, v221, v7
	s_waitcnt lgkmcnt(5)
	v_fmac_f32_e32 v124, v222, v8
	v_add_u32_e32 v120, 0x674c, v117
	ds_read2_b32 v[148:149], v120 offset0:32 offset1:28
	ds_read2_b32 v[150:151], v120 offset0:24 offset1:20
	ds_read2_b32 v[152:153], v120 offset0:16 offset1:12
	ds_read2_b32 v[154:155], v120 offset0:8 offset1:4
	ds_read_b32 v156, v120
	v_fma_f32 v125, v223, v9, v124
	s_waitcnt lgkmcnt(9)
	v_mul_f32_e32 v122, v132, v2
	v_fmac_f32_e32 v122, v133, v3
	v_add_f32_dpp v127, v125, v125 quad_perm:[1,0,3,2] row_mask:0xf bank_mask:0xf
	s_waitcnt lgkmcnt(8)
	v_fmac_f32_e32 v122, v134, v4
	v_fmac_f32_e32 v122, v135, v5
	v_add_f32_dpp v125, v127, v127 quad_perm:[2,3,0,1] row_mask:0xf bank_mask:0xf
	v_fma_f32 v127, v43, v26, -v125
	v_cndmask_b32_e64 v10, v10, v127, s[88:89]
	s_waitcnt lgkmcnt(7)
	v_fmac_f32_e32 v122, v136, v6
	v_fmac_f32_e32 v122, v137, v7
	s_waitcnt lgkmcnt(6)
	v_fmac_f32_e32 v122, v138, v8
	v_fmac_f32_e32 v122, v139, v9
	v_add_u32_e32 v121, 0x663c, v117
	ds_read2_b32 v[216:217], v121 offset0:32 offset1:28
	ds_read2_b32 v[218:219], v121 offset0:24 offset1:20
	ds_read2_b32 v[220:221], v121 offset0:16 offset1:12
	ds_read2_b32 v[222:223], v121 offset0:8 offset1:4
	ds_read_b32 v224, v121
	s_waitcnt lgkmcnt(10)
	v_cndmask_b32_e64 v126, 0, v140, s[34:35]
	v_fma_f32 v125, v126, v10, v122
	s_waitcnt lgkmcnt(9)
	v_mul_f32_e32 v123, v148, v2
	v_fmac_f32_e32 v123, v149, v3
	v_add_f32_dpp v127, v125, v125 quad_perm:[1,0,3,2] row_mask:0xf bank_mask:0xf
	s_waitcnt lgkmcnt(8)
	v_fmac_f32_e32 v123, v150, v4
	v_fmac_f32_e32 v123, v151, v5
	v_add_f32_dpp v125, v127, v127 quad_perm:[2,3,0,1] row_mask:0xf bank_mask:0xf
	v_fma_f32 v127, v43, v26, -v125
	v_cndmask_b32_e64 v10, v10, v127, s[90:91]
	s_waitcnt lgkmcnt(7)
	v_fmac_f32_e32 v123, v152, v6
	v_fmac_f32_e32 v123, v153, v7
	s_waitcnt lgkmcnt(6)
	v_fmac_f32_e32 v123, v154, v8
	v_fmac_f32_e32 v123, v155, v9
	v_add_u32_e32 v119, 0x652c, v117
	ds_read2_b32 v[132:133], v119 offset0:32 offset1:28
	ds_read2_b32 v[134:135], v119 offset0:24 offset1:20
	ds_read2_b32 v[136:137], v119 offset0:16 offset1:12
	ds_read2_b32 v[138:139], v119 offset0:8 offset1:4
	ds_read_b32 v140, v119
	s_waitcnt lgkmcnt(10)
	v_cndmask_b32_e64 v126, 0, v156, s[18:19]
	v_fma_f32 v125, v126, v10, v123
	s_waitcnt lgkmcnt(9)
	v_mul_f32_e32 v124, v216, v2
	v_fmac_f32_e32 v124, v217, v3
	v_add_f32_dpp v127, v125, v125 quad_perm:[1,0,3,2] row_mask:0xf bank_mask:0xf
	s_waitcnt lgkmcnt(8)
	v_fmac_f32_e32 v124, v218, v4
	v_fmac_f32_e32 v124, v219, v5
	v_add_f32_dpp v125, v127, v127 quad_perm:[2,3,0,1] row_mask:0xf bank_mask:0xf
	v_fma_f32 v127, v43, v26, -v125
	v_cndmask_b32_e64 v10, v10, v127, s[92:93]
	s_waitcnt lgkmcnt(7)
	v_fmac_f32_e32 v124, v220, v6
	v_fmac_f32_e32 v124, v221, v7
	s_waitcnt lgkmcnt(6)
	v_fmac_f32_e32 v124, v222, v8
	v_fmac_f32_e32 v124, v223, v9
	v_add_u32_e32 v120, 0x640c, v117
	ds_read2_b32 v[148:149], v120 offset0:36 offset1:32
	ds_read2_b32 v[150:151], v120 offset0:28 offset1:24
	ds_read2_b32 v[152:153], v120 offset0:20 offset1:16
	ds_read2_b32 v[154:155], v120 offset0:12 offset1:8
	ds_read2_b32 v[156:157], v120 offset0:4 offset1:0
	s_waitcnt lgkmcnt(10)
; template <int DIR>
; DI void dn_solve4(const float* M, const h16* Ki, const h16* Vi, const float* betal, const float* gcl, int half, int c, int pp, float (&x)[16]) {
;     ...
; #pragma unroll
;   for (int il = 0; il < 64; ++il) {
;     const int ri = DIR ? 63 - il : il;
;     float part = 0.f;
; #pragma unroll
;     for (int k = 0; k < (il + 3) / 4; ++k) {
;       const int jl0 = 4 * k;
;       float mv = DIR ? M[ri * MLD + 63 - jl0 - pp] : M[ri * MLD + jl0 + pp];
;       if (jl0 + 3 >= il) mv = (jl0 + pp < il) ? mv : 0.f;
;       part += mv * x[k];
;     }
;     part += __shfl_xor(part, 1); part += __shfl_xor(part, 2);
;     const float e = half ? __expf(gcl[ri]) : 1.f;
;     const float xi = betal[ri] * (float)src[ri * LDH] * e - part;
;     if ((il & 3) == pp) x[il >> 2] = xi;
;   }
	v_cndmask_b32_e64 v126, 0, v224, s[22:23]
	v_fma_f32 v125, v126, v10, v124
	s_waitcnt lgkmcnt(9)
	v_mul_f32_e32 v122, v132, v2
	v_fmac_f32_e32 v122, v133, v3
	v_add_f32_dpp v127, v125, v125 quad_perm:[1,0,3,2] row_mask:0xf bank_mask:0xf
	s_waitcnt lgkmcnt(8)
	v_fmac_f32_e32 v122, v134, v4
	v_fmac_f32_e32 v122, v135, v5
	v_add_f32_dpp v125, v127, v127 quad_perm:[2,3,0,1] row_mask:0xf bank_mask:0xf
	v_fma_f32 v127, v43, v26, -v125
	v_cndmask_b32_e64 v10, v10, v127, s[98:99]
	s_waitcnt lgkmcnt(7)
	v_fmac_f32_e32 v122, v136, v6
	v_fmac_f32_e32 v122, v137, v7
	s_waitcnt lgkmcnt(6)
	v_fmac_f32_e32 v122, v138, v8
	v_fmac_f32_e32 v122, v139, v9
	v_add_u32_e32 v121, 0x62fc, v117
	ds_read2_b32 v[216:217], v121 offset0:36 offset1:32
	ds_read2_b32 v[218:219], v121 offset0:28 offset1:24
	ds_read2_b32 v[220:221], v121 offset0:20 offset1:16
	ds_read2_b32 v[222:223], v121 offset0:12 offset1:8
	ds_read2_b32 v[224:225], v121 offset0:4 offset1:0
	s_waitcnt lgkmcnt(10)
	v_fma_f32 v125, v140, v10, v122
	s_waitcnt lgkmcnt(9)
	v_mul_f32_e32 v123, v148, v2
	v_fmac_f32_e32 v123, v149, v3
	v_add_f32_dpp v127, v125, v125 quad_perm:[1,0,3,2] row_mask:0xf bank_mask:0xf
	s_waitcnt lgkmcnt(8)
	v_fmac_f32_e32 v123, v150, v4
	v_fmac_f32_e32 v123, v151, v5
	v_add_f32_dpp v125, v127, v127 quad_perm:[2,3,0,1] row_mask:0xf bank_mask:0xf
	v_fma_f32 v127, v44, v27, -v125
	v_cndmask_b32_e64 v11, v11, v127, s[88:89]
	s_waitcnt lgkmcnt(7)
	v_fmac_f32_e32 v123, v152, v6
	v_fmac_f32_e32 v123, v153, v7
	s_waitcnt lgkmcnt(6)
	v_fmac_f32_e32 v123, v154, v8
	v_fmac_f32_e32 v123, v155, v9
	s_waitcnt lgkmcnt(5)
	v_fmac_f32_e32 v123, v156, v10
	v_add_u32_e32 v119, 0x61ec, v117
	ds_read2_b32 v[132:133], v119 offset0:36 offset1:32
	ds_read2_b32 v[134:135], v119 offset0:28 offset1:24
	ds_read2_b32 v[136:137], v119 offset0:20 offset1:16
	ds_read2_b32 v[138:139], v119 offset0:12 offset1:8
	ds_read2_b32 v[140:141], v119 offset0:4 offset1:0
	v_cndmask_b32_e64 v126, 0, v157, s[34:35]
	v_fma_f32 v125, v126, v11, v123
	s_waitcnt lgkmcnt(9)
	v_mul_f32_e32 v124, v216, v2
	v_fmac_f32_e32 v124, v217, v3
	v_add_f32_dpp v127, v125, v125 quad_perm:[1,0,3,2] row_mask:0xf bank_mask:0xf
	s_waitcnt lgkmcnt(8)
	v_fmac_f32_e32 v124, v218, v4
	v_fmac_f32_e32 v124, v219, v5
	v_add_f32_dpp v125, v127, v127 quad_perm:[2,3,0,1] row_mask:0xf bank_mask:0xf
	v_fma_f32 v127, v44, v27, -v125
	v_cndmask_b32_e64 v11, v11, v127, s[90:91]
	s_waitcnt lgkmcnt(7)
	v_fmac_f32_e32 v124, v220, v6
	v_fmac_f32_e32 v124, v221, v7
	s_waitcnt lgkmcnt(6)
	v_fmac_f32_e32 v124, v222, v8
	v_fmac_f32_e32 v124, v223, v9
	s_waitcnt lgkmcnt(5)
	v_fmac_f32_e32 v124, v224, v10
	v_add_u32_e32 v120, 0x60dc, v117
	ds_read2_b32 v[148:149], v120 offset0:36 offset1:32
	ds_read2_b32 v[150:151], v120 offset0:28 offset1:24
	ds_read2_b32 v[152:153], v120 offset0:20 offset1:16
	ds_read2_b32 v[154:155], v120 offset0:12 offset1:8
	ds_read2_b32 v[156:157], v120 offset0:4 offset1:0
	v_cndmask_b32_e64 v126, 0, v225, s[18:19]
	v_fma_f32 v125, v126, v11, v124
	s_waitcnt lgkmcnt(9)
	v_mul_f32_e32 v122, v132, v2
	v_fmac_f32_e32 v122, v133, v3
	v_add_f32_dpp v127, v125, v125 quad_perm:[1,0,3,2] row_mask:0xf bank_mask:0xf
	s_waitcnt lgkmcnt(8)
	v_fmac_f32_e32 v122, v134, v4
	v_fmac_f32_e32 v122, v135, v5
	v_add_f32_dpp v125, v127, v127 quad_perm:[2,3,0,1] row_mask:0xf bank_mask:0xf
	v_fma_f32 v127, v44, v27, -v125
	v_cndmask_b32_e64 v11, v11, v127, s[92:93]
	s_waitcnt lgkmcnt(7)
	v_fmac_f32_e32 v122, v136, v6
	v_fmac_f32_e32 v122, v137, v7
	s_waitcnt lgkmcnt(6)
	v_fmac_f32_e32 v122, v138, v8
	v_fmac_f32_e32 v122, v139, v9
	s_waitcnt lgkmcnt(5)
	v_fmac_f32_e32 v122, v140, v10
	v_add_u32_e32 v121, 0x5fbc, v117
	ds_read2_b32 v[216:217], v121 offset0:40 offset1:36
	ds_read2_b32 v[218:219], v121 offset0:32 offset1:28
	ds_read2_b32 v[220:221], v121 offset0:24 offset1:20
	ds_read2_b32 v[222:223], v121 offset0:16 offset1:12
	ds_read2_b32 v[224:225], v121 offset0:8 offset1:4
	ds_read_b32 v226, v121
	v_cndmask_b32_e64 v126, 0, v141, s[22:23]
	v_fma_f32 v125, v126, v11, v122
	s_waitcnt lgkmcnt(10)
	v_mul_f32_e32 v123, v148, v2
	v_fmac_f32_e32 v123, v149, v3
	v_add_f32_dpp v127, v125, v125 quad_perm:[1,0,3,2] row_mask:0xf bank_mask:0xf
	s_waitcnt lgkmcnt(9)
	v_fmac_f32_e32 v123, v150, v4
	v_fmac_f32_e32 v123, v151, v5
	v_add_f32_dpp v125, v127, v127 quad_perm:[2,3,0,1] row_mask:0xf bank_mask:0xf
	v_fma_f32 v127, v44, v27, -v125
	v_cndmask_b32_e64 v11, v11, v127, s[98:99]
	s_waitcnt lgkmcnt(8)
	v_fmac_f32_e32 v123, v152, v6
	v_fmac_f32_e32 v123, v153, v7
	s_waitcnt lgkmcnt(7)
	v_fmac_f32_e32 v123, v154, v8
	v_fmac_f32_e32 v123, v155, v9
	s_waitcnt lgkmcnt(6)
	v_fmac_f32_e32 v123, v156, v10
	v_add_u32_e32 v119, 0x5eac, v117
	ds_read2_b32 v[132:133], v119 offset0:40 offset1:36
	ds_read2_b32 v[134:135], v119 offset0:32 offset1:28
	ds_read2_b32 v[136:137], v119 offset0:24 offset1:20
	ds_read2_b32 v[138:139], v119 offset0:16 offset1:12
	ds_read2_b32 v[140:141], v119 offset0:8 offset1:4
	ds_read_b32 v142, v119
	v_fma_f32 v125, v157, v11, v123
	s_waitcnt lgkmcnt(11)
	v_mul_f32_e32 v124, v216, v2
	v_fmac_f32_e32 v124, v217, v3
	v_add_f32_dpp v127, v125, v125 quad_perm:[1,0,3,2] row_mask:0xf bank_mask:0xf
	s_waitcnt lgkmcnt(10)
	v_fmac_f32_e32 v124, v218, v4
	v_fmac_f32_e32 v124, v219, v5
	v_add_f32_dpp v125, v127, v127 quad_perm:[2,3,0,1] row_mask:0xf bank_mask:0xf
	v_fma_f32 v127, v45, v28, -v125
	v_cndmask_b32_e64 v12, v12, v127, s[88:89]
	s_waitcnt lgkmcnt(9)
	v_fmac_f32_e32 v124, v220, v6
	v_fmac_f32_e32 v124, v221, v7
	s_waitcnt lgkmcnt(8)
	v_fmac_f32_e32 v124, v222, v8
	v_fmac_f32_e32 v124, v223, v9
	s_waitcnt lgkmcnt(7)
; template <int DIR>
; DI void dn_solve4(const float* M, const h16* Ki, const h16* Vi, const float* betal, const float* gcl, int half, int c, int pp, float (&x)[16]) {
;     ...
; #pragma unroll
;   for (int il = 0; il < 64; ++il) {
;     const int ri = DIR ? 63 - il : il;
;     float part = 0.f;
; #pragma unroll
;     for (int k = 0; k < (il + 3) / 4; ++k) {
;       const int jl0 = 4 * k;
;       float mv = DIR ? M[ri * MLD + 63 - jl0 - pp] : M[ri * MLD + jl0 + pp];
;       if (jl0 + 3 >= il) mv = (jl0 + pp < il) ? mv : 0.f;
;       part += mv * x[k];
;     }
;     part += __shfl_xor(part, 1); part += __shfl_xor(part, 2);
;     const float e = half ? __expf(gcl[ri]) : 1.f;
;     const float xi = betal[ri] * (float)src[ri * LDH] * e - part;
;     if ((il & 3) == pp) x[il >> 2] = xi;
;   }
	v_fmac_f32_e32 v124, v224, v10
	v_fmac_f32_e32 v124, v225, v11
	v_add_u32_e32 v120, 0x5d9c, v117
	ds_read2_b32 v[148:149], v120 offset0:40 offset1:36
	ds_read2_b32 v[150:151], v120 offset0:32 offset1:28
	ds_read2_b32 v[152:153], v120 offset0:24 offset1:20
	ds_read2_b32 v[154:155], v120 offset0:16 offset1:12
	ds_read2_b32 v[156:157], v120 offset0:8 offset1:4
	ds_read_b32 v158, v120
	s_waitcnt lgkmcnt(12)
	v_cndmask_b32_e64 v126, 0, v226, s[34:35]
	v_fma_f32 v125, v126, v12, v124
	s_waitcnt lgkmcnt(11)
	v_mul_f32_e32 v122, v132, v2
	v_fmac_f32_e32 v122, v133, v3
	v_add_f32_dpp v127, v125, v125 quad_perm:[1,0,3,2] row_mask:0xf bank_mask:0xf
	s_waitcnt lgkmcnt(10)
	v_fmac_f32_e32 v122, v134, v4
	v_fmac_f32_e32 v122, v135, v5
	v_add_f32_dpp v125, v127, v127 quad_perm:[2,3,0,1] row_mask:0xf bank_mask:0xf
	v_fma_f32 v127, v45, v28, -v125
	v_cndmask_b32_e64 v12, v12, v127, s[90:91]
	s_waitcnt lgkmcnt(9)
	v_fmac_f32_e32 v122, v136, v6
	v_fmac_f32_e32 v122, v137, v7
	s_waitcnt lgkmcnt(8)
	v_fmac_f32_e32 v122, v138, v8
	v_fmac_f32_e32 v122, v139, v9
	s_waitcnt lgkmcnt(7)
	v_fmac_f32_e32 v122, v140, v10
	v_fmac_f32_e32 v122, v141, v11
	v_add_u32_e32 v121, 0x5c8c, v117
	ds_read2_b32 v[216:217], v121 offset0:40 offset1:36
	ds_read2_b32 v[218:219], v121 offset0:32 offset1:28
	ds_read2_b32 v[220:221], v121 offset0:24 offset1:20
	ds_read2_b32 v[222:223], v121 offset0:16 offset1:12
	ds_read2_b32 v[224:225], v121 offset0:8 offset1:4
	ds_read_b32 v226, v121
	s_waitcnt lgkmcnt(12)
	v_cndmask_b32_e64 v126, 0, v142, s[18:19]
	v_fma_f32 v125, v126, v12, v122
	s_waitcnt lgkmcnt(11)
	v_mul_f32_e32 v123, v148, v2
	v_fmac_f32_e32 v123, v149, v3
	v_add_f32_dpp v127, v125, v125 quad_perm:[1,0,3,2] row_mask:0xf bank_mask:0xf
	s_waitcnt lgkmcnt(10)
	v_fmac_f32_e32 v123, v150, v4
	v_fmac_f32_e32 v123, v151, v5
	v_add_f32_dpp v125, v127, v127 quad_perm:[2,3,0,1] row_mask:0xf bank_mask:0xf
	v_fma_f32 v127, v45, v28, -v125
	v_cndmask_b32_e64 v12, v12, v127, s[92:93]
	s_waitcnt lgkmcnt(9)
	v_fmac_f32_e32 v123, v152, v6
	v_fmac_f32_e32 v123, v153, v7
	s_waitcnt lgkmcnt(8)
	v_fmac_f32_e32 v123, v154, v8
	v_fmac_f32_e32 v123, v155, v9
	s_waitcnt lgkmcnt(7)
	v_fmac_f32_e32 v123, v156, v10
	v_fmac_f32_e32 v123, v157, v11
	v_add_u32_e32 v119, 0x5b6c, v117
	ds_read2_b32 v[132:133], v119 offset0:44 offset1:40
	ds_read2_b32 v[134:135], v119 offset0:36 offset1:32
	ds_read2_b32 v[136:137], v119 offset0:28 offset1:24
	ds_read2_b32 v[138:139], v119 offset0:20 offset1:16
	ds_read2_b32 v[140:141], v119 offset0:12 offset1:8
	ds_read2_b32 v[142:143], v119 offset0:4 offset1:0
	s_waitcnt lgkmcnt(12)
	v_cndmask_b32_e64 v126, 0, v158, s[22:23]
	v_fma_f32 v125, v126, v12, v123
	s_waitcnt lgkmcnt(11)
	v_mul_f32_e32 v124, v216, v2
	v_fmac_f32_e32 v124, v217, v3
	v_add_f32_dpp v127, v125, v125 quad_perm:[1,0,3,2] row_mask:0xf bank_mask:0xf
	s_waitcnt lgkmcnt(10)
	v_fmac_f32_e32 v124, v218, v4
	v_fmac_f32_e32 v124, v219, v5
	v_add_f32_dpp v125, v127, v127 quad_perm:[2,3,0,1] row_mask:0xf bank_mask:0xf
	v_fma_f32 v127, v45, v28, -v125
	v_cndmask_b32_e64 v12, v12, v127, s[98:99]
	s_waitcnt lgkmcnt(9)
	v_fmac_f32_e32 v124, v220, v6
	v_fmac_f32_e32 v124, v221, v7
	s_waitcnt lgkmcnt(8)
	v_fmac_f32_e32 v124, v222, v8
	v_fmac_f32_e32 v124, v223, v9
	s_waitcnt lgkmcnt(7)
	v_fmac_f32_e32 v124, v224, v10
	v_fmac_f32_e32 v124, v225, v11
	v_add_u32_e32 v120, 0x5a5c, v117
	ds_read2_b32 v[148:149], v120 offset0:44 offset1:40
	ds_read2_b32 v[150:151], v120 offset0:36 offset1:32
	ds_read2_b32 v[152:153], v120 offset0:28 offset1:24
	ds_read2_b32 v[154:155], v120 offset0:20 offset1:16
	ds_read2_b32 v[156:157], v120 offset0:12 offset1:8
	ds_read2_b32 v[158:159], v120 offset0:4 offset1:0
	s_waitcnt lgkmcnt(12)
	v_fma_f32 v125, v226, v12, v124
	s_waitcnt lgkmcnt(11)
	v_mul_f32_e32 v122, v132, v2
	v_fmac_f32_e32 v122, v133, v3
	v_add_f32_dpp v127, v125, v125 quad_perm:[1,0,3,2] row_mask:0xf bank_mask:0xf
	s_waitcnt lgkmcnt(10)
	v_fmac_f32_e32 v122, v134, v4
	v_fmac_f32_e32 v122, v135, v5
	v_add_f32_dpp v125, v127, v127 quad_perm:[2,3,0,1] row_mask:0xf bank_mask:0xf
	v_fma_f32 v127, v46, v30, -v125
	v_cndmask_b32_e64 v13, v13, v127, s[88:89]
	s_waitcnt lgkmcnt(9)
	v_fmac_f32_e32 v122, v136, v6
	v_fmac_f32_e32 v122, v137, v7
	s_waitcnt lgkmcnt(8)
	v_fmac_f32_e32 v122, v138, v8
	v_fmac_f32_e32 v122, v139, v9
	s_waitcnt lgkmcnt(7)
	v_fmac_f32_e32 v122, v140, v10
	v_fmac_f32_e32 v122, v141, v11
	s_waitcnt lgkmcnt(6)
	v_fmac_f32_e32 v122, v142, v12
	v_add_u32_e32 v121, 0x594c, v117
	ds_read2_b32 v[216:217], v121 offset0:44 offset1:40
	ds_read2_b32 v[218:219], v121 offset0:36 offset1:32
	ds_read2_b32 v[220:221], v121 offset0:28 offset1:24
	ds_read2_b32 v[222:223], v121 offset0:20 offset1:16
	ds_read2_b32 v[224:225], v121 offset0:12 offset1:8
	ds_read2_b32 v[226:227], v121 offset0:4 offset1:0
	v_cndmask_b32_e64 v126, 0, v143, s[34:35]
	v_fma_f32 v125, v126, v13, v122
	s_waitcnt lgkmcnt(11)
	v_mul_f32_e32 v123, v148, v2
	v_fmac_f32_e32 v123, v149, v3
	v_add_f32_dpp v127, v125, v125 quad_perm:[1,0,3,2] row_mask:0xf bank_mask:0xf
	s_waitcnt lgkmcnt(10)
	v_fmac_f32_e32 v123, v150, v4
	v_fmac_f32_e32 v123, v151, v5
	v_add_f32_dpp v125, v127, v127 quad_perm:[2,3,0,1] row_mask:0xf bank_mask:0xf
	v_fma_f32 v127, v46, v30, -v125
	v_cndmask_b32_e64 v13, v13, v127, s[90:91]
	s_waitcnt lgkmcnt(9)
	v_fmac_f32_e32 v123, v152, v6
	v_fmac_f32_e32 v123, v153, v7
	s_waitcnt lgkmcnt(8)
	v_fmac_f32_e32 v123, v154, v8
	v_fmac_f32_e32 v123, v155, v9
	s_waitcnt lgkmcnt(7)
	v_fmac_f32_e32 v123, v156, v10
	v_fmac_f32_e32 v123, v157, v11
	s_waitcnt lgkmcnt(6)
; template <int DIR>
; DI void dn_solve4(const float* M, const h16* Ki, const h16* Vi, const float* betal, const float* gcl, int half, int c, int pp, float (&x)[16]) {
;     ...
; #pragma unroll
;   for (int il = 0; il < 64; ++il) {
;     const int ri = DIR ? 63 - il : il;
;     float part = 0.f;
; #pragma unroll
;     for (int k = 0; k < (il + 3) / 4; ++k) {
;       const int jl0 = 4 * k;
;       float mv = DIR ? M[ri * MLD + 63 - jl0 - pp] : M[ri * MLD + jl0 + pp];
;       if (jl0 + 3 >= il) mv = (jl0 + pp < il) ? mv : 0.f;
;       part += mv * x[k];
;     }
;     part += __shfl_xor(part, 1); part += __shfl_xor(part, 2);
;     const float e = half ? __expf(gcl[ri]) : 1.f;
;     const float xi = betal[ri] * (float)src[ri * LDH] * e - part;
;     if ((il & 3) == pp) x[il >> 2] = xi;
;   }
	v_fmac_f32_e32 v123, v158, v12
	v_add_u32_e32 v119, 0x583c, v117
	ds_read2_b32 v[132:133], v119 offset0:44 offset1:40
	ds_read2_b32 v[134:135], v119 offset0:36 offset1:32
	ds_read2_b32 v[136:137], v119 offset0:28 offset1:24
	ds_read2_b32 v[138:139], v119 offset0:20 offset1:16
	ds_read2_b32 v[140:141], v119 offset0:12 offset1:8
	ds_read2_b32 v[142:143], v119 offset0:4 offset1:0
	v_cndmask_b32_e64 v126, 0, v159, s[18:19]
	v_fma_f32 v125, v126, v13, v123
	s_waitcnt lgkmcnt(11)
	v_mul_f32_e32 v124, v216, v2
	v_fmac_f32_e32 v124, v217, v3
	v_add_f32_dpp v127, v125, v125 quad_perm:[1,0,3,2] row_mask:0xf bank_mask:0xf
	s_waitcnt lgkmcnt(10)
	v_fmac_f32_e32 v124, v218, v4
	v_fmac_f32_e32 v124, v219, v5
	v_add_f32_dpp v125, v127, v127 quad_perm:[2,3,0,1] row_mask:0xf bank_mask:0xf
	v_fma_f32 v127, v46, v30, -v125
	v_cndmask_b32_e64 v13, v13, v127, s[92:93]
	s_waitcnt lgkmcnt(9)
	v_fmac_f32_e32 v124, v220, v6
	v_fmac_f32_e32 v124, v221, v7
	s_waitcnt lgkmcnt(8)
	v_fmac_f32_e32 v124, v222, v8
	v_fmac_f32_e32 v124, v223, v9
	s_waitcnt lgkmcnt(7)
	v_fmac_f32_e32 v124, v224, v10
	v_fmac_f32_e32 v124, v225, v11
	s_waitcnt lgkmcnt(6)
	v_fmac_f32_e32 v124, v226, v12
	v_add_u32_e32 v120, 0x571c, v117
	ds_read2_b32 v[148:149], v120 offset0:48 offset1:44
	ds_read2_b32 v[150:151], v120 offset0:40 offset1:36
	ds_read2_b32 v[152:153], v120 offset0:32 offset1:28
	ds_read2_b32 v[154:155], v120 offset0:24 offset1:20
	ds_read2_b32 v[156:157], v120 offset0:16 offset1:12
	ds_read2_b32 v[158:159], v120 offset0:8 offset1:4
	ds_read_b32 v160, v120
	v_cndmask_b32_e64 v126, 0, v227, s[22:23]
	v_fma_f32 v125, v126, v13, v124
	s_waitcnt lgkmcnt(12)
	v_mul_f32_e32 v122, v132, v2
	v_fmac_f32_e32 v122, v133, v3
	v_add_f32_dpp v127, v125, v125 quad_perm:[1,0,3,2] row_mask:0xf bank_mask:0xf
	s_waitcnt lgkmcnt(11)
	v_fmac_f32_e32 v122, v134, v4
	v_fmac_f32_e32 v122, v135, v5
	v_add_f32_dpp v125, v127, v127 quad_perm:[2,3,0,1] row_mask:0xf bank_mask:0xf
	v_fma_f32 v127, v46, v30, -v125
	v_cndmask_b32_e64 v13, v13, v127, s[98:99]
	s_waitcnt lgkmcnt(10)
	v_fmac_f32_e32 v122, v136, v6
	v_fmac_f32_e32 v122, v137, v7
	s_waitcnt lgkmcnt(9)
	v_fmac_f32_e32 v122, v138, v8
	v_fmac_f32_e32 v122, v139, v9
	s_waitcnt lgkmcnt(8)
	v_fmac_f32_e32 v122, v140, v10
	v_fmac_f32_e32 v122, v141, v11
	s_waitcnt lgkmcnt(7)
	v_fmac_f32_e32 v122, v142, v12
	v_add_u32_e32 v121, 0x560c, v117
	ds_read2_b32 v[216:217], v121 offset0:48 offset1:44
	ds_read2_b32 v[218:219], v121 offset0:40 offset1:36
	ds_read2_b32 v[220:221], v121 offset0:32 offset1:28
	ds_read2_b32 v[222:223], v121 offset0:24 offset1:20
	ds_read2_b32 v[224:225], v121 offset0:16 offset1:12
	ds_read2_b32 v[226:227], v121 offset0:8 offset1:4
	ds_read_b32 v228, v121
	v_fma_f32 v125, v143, v13, v122
	s_waitcnt lgkmcnt(13)
	v_mul_f32_e32 v123, v148, v2
	v_fmac_f32_e32 v123, v149, v3
	v_add_f32_dpp v127, v125, v125 quad_perm:[1,0,3,2] row_mask:0xf bank_mask:0xf
	s_waitcnt lgkmcnt(12)
	v_fmac_f32_e32 v123, v150, v4
	v_fmac_f32_e32 v123, v151, v5
	v_add_f32_dpp v125, v127, v127 quad_perm:[2,3,0,1] row_mask:0xf bank_mask:0xf
	v_fma_f32 v127, v47, v31, -v125
	v_cndmask_b32_e64 v14, v14, v127, s[88:89]
	s_waitcnt lgkmcnt(11)
	v_fmac_f32_e32 v123, v152, v6
	v_fmac_f32_e32 v123, v153, v7
	s_waitcnt lgkmcnt(10)
	v_fmac_f32_e32 v123, v154, v8
	v_fmac_f32_e32 v123, v155, v9
	s_waitcnt lgkmcnt(9)
	v_fmac_f32_e32 v123, v156, v10
	v_fmac_f32_e32 v123, v157, v11
	s_waitcnt lgkmcnt(8)
	v_fmac_f32_e32 v123, v158, v12
	v_fmac_f32_e32 v123, v159, v13
	v_add_u32_e32 v119, 0x54fc, v117
	ds_read2_b32 v[132:133], v119 offset0:48 offset1:44
	ds_read2_b32 v[134:135], v119 offset0:40 offset1:36
	ds_read2_b32 v[136:137], v119 offset0:32 offset1:28
	ds_read2_b32 v[138:139], v119 offset0:24 offset1:20
	ds_read2_b32 v[140:141], v119 offset0:16 offset1:12
	ds_read2_b32 v[142:143], v119 offset0:8 offset1:4
	ds_read_b32 v144, v119
	s_waitcnt lgkmcnt(14)
	v_cndmask_b32_e64 v126, 0, v160, s[34:35]
	v_fma_f32 v125, v126, v14, v123
	s_waitcnt lgkmcnt(13)
	v_mul_f32_e32 v124, v216, v2
	v_fmac_f32_e32 v124, v217, v3
	v_add_f32_dpp v127, v125, v125 quad_perm:[1,0,3,2] row_mask:0xf bank_mask:0xf
	s_waitcnt lgkmcnt(12)
	v_fmac_f32_e32 v124, v218, v4
	v_fmac_f32_e32 v124, v219, v5
	v_add_f32_dpp v125, v127, v127 quad_perm:[2,3,0,1] row_mask:0xf bank_mask:0xf
	v_fma_f32 v127, v47, v31, -v125
	v_cndmask_b32_e64 v14, v14, v127, s[90:91]
	s_waitcnt lgkmcnt(11)
	v_fmac_f32_e32 v124, v220, v6
	v_fmac_f32_e32 v124, v221, v7
	s_waitcnt lgkmcnt(10)
	v_fmac_f32_e32 v124, v222, v8
	v_fmac_f32_e32 v124, v223, v9
	s_waitcnt lgkmcnt(9)
	v_fmac_f32_e32 v124, v224, v10
	v_fmac_f32_e32 v124, v225, v11
	s_waitcnt lgkmcnt(8)
	v_fmac_f32_e32 v124, v226, v12
	v_fmac_f32_e32 v124, v227, v13
	v_add_u32_e32 v120, 0x53ec, v117
	ds_read2_b32 v[148:149], v120 offset0:48 offset1:44
	ds_read2_b32 v[150:151], v120 offset0:40 offset1:36
	ds_read2_b32 v[152:153], v120 offset0:32 offset1:28
	ds_read2_b32 v[154:155], v120 offset0:24 offset1:20
	ds_read2_b32 v[156:157], v120 offset0:16 offset1:12
	ds_read2_b32 v[158:159], v120 offset0:8 offset1:4
	ds_read_b32 v160, v120
	s_waitcnt lgkmcnt(14)
	v_cndmask_b32_e64 v126, 0, v228, s[18:19]
	v_fma_f32 v125, v126, v14, v124
	s_waitcnt lgkmcnt(13)
	v_mul_f32_e32 v122, v132, v2
	v_fmac_f32_e32 v122, v133, v3
	v_add_f32_dpp v127, v125, v125 quad_perm:[1,0,3,2] row_mask:0xf bank_mask:0xf
	s_waitcnt lgkmcnt(12)
	v_fmac_f32_e32 v122, v134, v4
	v_fmac_f32_e32 v122, v135, v5
	v_add_f32_dpp v125, v127, v127 quad_perm:[2,3,0,1] row_mask:0xf bank_mask:0xf
	v_fma_f32 v127, v47, v31, -v125
	v_cndmask_b32_e64 v14, v14, v127, s[92:93]
	s_waitcnt lgkmcnt(11)
; template <int DIR>
; DI void dn_solve4(const float* M, const h16* Ki, const h16* Vi, const float* betal, const float* gcl, int half, int c, int pp, float (&x)[16]) {
;     ...
; #pragma unroll
;   for (int il = 0; il < 64; ++il) {
;     const int ri = DIR ? 63 - il : il;
;     float part = 0.f;
; #pragma unroll
;     for (int k = 0; k < (il + 3) / 4; ++k) {
;       const int jl0 = 4 * k;
;       float mv = DIR ? M[ri * MLD + 63 - jl0 - pp] : M[ri * MLD + jl0 + pp];
;       if (jl0 + 3 >= il) mv = (jl0 + pp < il) ? mv : 0.f;
;       part += mv * x[k];
;     }
;     part += __shfl_xor(part, 1); part += __shfl_xor(part, 2);
;     const float e = half ? __expf(gcl[ri]) : 1.f;
;     const float xi = betal[ri] * (float)src[ri * LDH] * e - part;
;     if ((il & 3) == pp) x[il >> 2] = xi;
;   }
	v_fmac_f32_e32 v122, v136, v6
	v_fmac_f32_e32 v122, v137, v7
	s_waitcnt lgkmcnt(10)
	v_fmac_f32_e32 v122, v138, v8
	v_fmac_f32_e32 v122, v139, v9
	s_waitcnt lgkmcnt(9)
	v_fmac_f32_e32 v122, v140, v10
	v_fmac_f32_e32 v122, v141, v11
	s_waitcnt lgkmcnt(8)
	v_fmac_f32_e32 v122, v142, v12
	v_fmac_f32_e32 v122, v143, v13
	v_add_u32_e32 v121, 0x52cc, v117
	ds_read2_b32 v[216:217], v121 offset0:52 offset1:48
	ds_read2_b32 v[218:219], v121 offset0:44 offset1:40
	ds_read2_b32 v[220:221], v121 offset0:36 offset1:32
	ds_read2_b32 v[222:223], v121 offset0:28 offset1:24
	ds_read2_b32 v[224:225], v121 offset0:20 offset1:16
	ds_read2_b32 v[226:227], v121 offset0:12 offset1:8
	ds_read2_b32 v[228:229], v121 offset0:4 offset1:0
	s_waitcnt lgkmcnt(14)
	v_cndmask_b32_e64 v126, 0, v144, s[22:23]
	v_fma_f32 v125, v126, v14, v122
	s_waitcnt lgkmcnt(13)
	v_mul_f32_e32 v123, v148, v2
	v_fmac_f32_e32 v123, v149, v3
	v_add_f32_dpp v127, v125, v125 quad_perm:[1,0,3,2] row_mask:0xf bank_mask:0xf
	s_waitcnt lgkmcnt(12)
	v_fmac_f32_e32 v123, v150, v4
	v_fmac_f32_e32 v123, v151, v5
	v_add_f32_dpp v125, v127, v127 quad_perm:[2,3,0,1] row_mask:0xf bank_mask:0xf
	v_fma_f32 v127, v47, v31, -v125
	v_cndmask_b32_e64 v14, v14, v127, s[98:99]
	s_waitcnt lgkmcnt(11)
	v_fmac_f32_e32 v123, v152, v6
	v_fmac_f32_e32 v123, v153, v7
	s_waitcnt lgkmcnt(10)
	v_fmac_f32_e32 v123, v154, v8
	v_fmac_f32_e32 v123, v155, v9
	s_waitcnt lgkmcnt(9)
	v_fmac_f32_e32 v123, v156, v10
	v_fmac_f32_e32 v123, v157, v11
	s_waitcnt lgkmcnt(8)
	v_fmac_f32_e32 v123, v158, v12
	v_fmac_f32_e32 v123, v159, v13
	v_add_u32_e32 v119, 0x51bc, v117
	ds_read2_b32 v[132:133], v119 offset0:52 offset1:48
	ds_read2_b32 v[134:135], v119 offset0:44 offset1:40
	ds_read2_b32 v[136:137], v119 offset0:36 offset1:32
	ds_read2_b32 v[138:139], v119 offset0:28 offset1:24
	ds_read2_b32 v[140:141], v119 offset0:20 offset1:16
	ds_read2_b32 v[142:143], v119 offset0:12 offset1:8
	ds_read2_b32 v[144:145], v119 offset0:4 offset1:0
	s_waitcnt lgkmcnt(14)
	v_fma_f32 v125, v160, v14, v123
	s_waitcnt lgkmcnt(13)
	v_mul_f32_e32 v124, v216, v2
	v_fmac_f32_e32 v124, v217, v3
	v_add_f32_dpp v127, v125, v125 quad_perm:[1,0,3,2] row_mask:0xf bank_mask:0xf
	s_waitcnt lgkmcnt(12)
	v_fmac_f32_e32 v124, v218, v4
	v_fmac_f32_e32 v124, v219, v5
	v_add_f32_dpp v125, v127, v127 quad_perm:[2,3,0,1] row_mask:0xf bank_mask:0xf
	v_fma_f32 v127, v48, v32, -v125
	v_cndmask_b32_e64 v15, v15, v127, s[88:89]
	s_waitcnt lgkmcnt(11)
	v_fmac_f32_e32 v124, v220, v6
	v_fmac_f32_e32 v124, v221, v7
	s_waitcnt lgkmcnt(10)
	v_fmac_f32_e32 v124, v222, v8
	v_fmac_f32_e32 v124, v223, v9
	s_waitcnt lgkmcnt(9)
	v_fmac_f32_e32 v124, v224, v10
	v_fmac_f32_e32 v124, v225, v11
	s_waitcnt lgkmcnt(8)
	v_fmac_f32_e32 v124, v226, v12
	v_fmac_f32_e32 v124, v227, v13
	s_waitcnt lgkmcnt(7)
	v_fmac_f32_e32 v124, v228, v14
	v_add_u32_e32 v120, 0x50ac, v117
	ds_read2_b32 v[148:149], v120 offset0:52 offset1:48
	ds_read2_b32 v[150:151], v120 offset0:44 offset1:40
	ds_read2_b32 v[152:153], v120 offset0:36 offset1:32
	ds_read2_b32 v[154:155], v120 offset0:28 offset1:24
	ds_read2_b32 v[156:157], v120 offset0:20 offset1:16
	ds_read2_b32 v[158:159], v120 offset0:12 offset1:8
	ds_read2_b32 v[160:161], v120 offset0:4 offset1:0
	v_cndmask_b32_e64 v126, 0, v229, s[34:35]
	v_fma_f32 v125, v126, v15, v124
	s_waitcnt lgkmcnt(13)
	v_mul_f32_e32 v122, v132, v2
	v_fmac_f32_e32 v122, v133, v3
	v_add_f32_dpp v127, v125, v125 quad_perm:[1,0,3,2] row_mask:0xf bank_mask:0xf
	s_waitcnt lgkmcnt(12)
	v_fmac_f32_e32 v122, v134, v4
	v_fmac_f32_e32 v122, v135, v5
	v_add_f32_dpp v125, v127, v127 quad_perm:[2,3,0,1] row_mask:0xf bank_mask:0xf
	v_fma_f32 v127, v48, v32, -v125
	v_cndmask_b32_e64 v15, v15, v127, s[90:91]
	s_waitcnt lgkmcnt(11)
	v_fmac_f32_e32 v122, v136, v6
	v_fmac_f32_e32 v122, v137, v7
	s_waitcnt lgkmcnt(10)
	v_fmac_f32_e32 v122, v138, v8
	v_fmac_f32_e32 v122, v139, v9
	s_waitcnt lgkmcnt(9)
	v_fmac_f32_e32 v122, v140, v10
	v_fmac_f32_e32 v122, v141, v11
	s_waitcnt lgkmcnt(8)
	v_fmac_f32_e32 v122, v142, v12
	v_fmac_f32_e32 v122, v143, v13
	s_waitcnt lgkmcnt(7)
	v_fmac_f32_e32 v122, v144, v14
	v_add_u32_e32 v121, 0x4f9c, v117
	ds_read2_b32 v[216:217], v121 offset0:52 offset1:48
	ds_read2_b32 v[218:219], v121 offset0:44 offset1:40
	ds_read2_b32 v[220:221], v121 offset0:36 offset1:32
	ds_read2_b32 v[222:223], v121 offset0:28 offset1:24
	ds_read2_b32 v[224:225], v121 offset0:20 offset1:16
	ds_read2_b32 v[226:227], v121 offset0:12 offset1:8
	ds_read2_b32 v[228:229], v121 offset0:4 offset1:0
	v_cndmask_b32_e64 v126, 0, v145, s[18:19]
	v_fma_f32 v125, v126, v15, v122
	s_waitcnt lgkmcnt(13)
	v_mul_f32_e32 v123, v148, v2
	v_fmac_f32_e32 v123, v149, v3
	v_add_f32_dpp v127, v125, v125 quad_perm:[1,0,3,2] row_mask:0xf bank_mask:0xf
	s_waitcnt lgkmcnt(12)
	v_fmac_f32_e32 v123, v150, v4
	v_fmac_f32_e32 v123, v151, v5
	v_add_f32_dpp v125, v127, v127 quad_perm:[2,3,0,1] row_mask:0xf bank_mask:0xf
	v_fma_f32 v127, v48, v32, -v125
	v_cndmask_b32_e64 v15, v15, v127, s[92:93]
	s_waitcnt lgkmcnt(11)
	v_fmac_f32_e32 v123, v152, v6
	v_fmac_f32_e32 v123, v153, v7
	s_waitcnt lgkmcnt(10)
	v_fmac_f32_e32 v123, v154, v8
	v_fmac_f32_e32 v123, v155, v9
	s_waitcnt lgkmcnt(9)
	v_fmac_f32_e32 v123, v156, v10
	v_fmac_f32_e32 v123, v157, v11
	s_waitcnt lgkmcnt(8)
	v_fmac_f32_e32 v123, v158, v12
	v_fmac_f32_e32 v123, v159, v13
	s_waitcnt lgkmcnt(7)
	v_fmac_f32_e32 v123, v160, v14
	v_add_u32_e32 v119, 0x4e7c, v117
	ds_read2_b32 v[132:133], v119 offset0:56 offset1:52
	ds_read2_b32 v[134:135], v119 offset0:48 offset1:44
	ds_read2_b32 v[136:137], v119 offset0:40 offset1:36
	ds_read2_b32 v[138:139], v119 offset0:32 offset1:28
	ds_read2_b32 v[140:141], v119 offset0:24 offset1:20
	ds_read2_b32 v[142:143], v119 offset0:16 offset1:12
	ds_read2_b32 v[144:145], v119 offset0:8 offset1:4
	ds_read_b32 v146, v119
	v_cndmask_b32_e64 v126, 0, v161, s[22:23]
	v_fma_f32 v125, v126, v15, v123
	s_waitcnt lgkmcnt(14)
; template <int DIR>
; DI void dn_solve4(const float* M, const h16* Ki, const h16* Vi, const float* betal, const float* gcl, int half, int c, int pp, float (&x)[16]) {
;     ...
; #pragma unroll
;   for (int il = 0; il < 64; ++il) {
;     const int ri = DIR ? 63 - il : il;
;     float part = 0.f;
; #pragma unroll
;     for (int k = 0; k < (il + 3) / 4; ++k) {
;       const int jl0 = 4 * k;
;       float mv = DIR ? M[ri * MLD + 63 - jl0 - pp] : M[ri * MLD + jl0 + pp];
;       if (jl0 + 3 >= il) mv = (jl0 + pp < il) ? mv : 0.f;
;       part += mv * x[k];
;     }
;     part += __shfl_xor(part, 1); part += __shfl_xor(part, 2);
;     const float e = half ? __expf(gcl[ri]) : 1.f;
;     const float xi = betal[ri] * (float)src[ri * LDH] * e - part;
;     if ((il & 3) == pp) x[il >> 2] = xi;
;   }
	v_mul_f32_e32 v124, v216, v2
	v_fmac_f32_e32 v124, v217, v3
	v_add_f32_dpp v127, v125, v125 quad_perm:[1,0,3,2] row_mask:0xf bank_mask:0xf
	s_waitcnt lgkmcnt(13)
	v_fmac_f32_e32 v124, v218, v4
	v_fmac_f32_e32 v124, v219, v5
	v_add_f32_dpp v125, v127, v127 quad_perm:[2,3,0,1] row_mask:0xf bank_mask:0xf
	v_fma_f32 v127, v48, v32, -v125
	v_cndmask_b32_e64 v15, v15, v127, s[98:99]
	s_waitcnt lgkmcnt(12)
	v_fmac_f32_e32 v124, v220, v6
	v_fmac_f32_e32 v124, v221, v7
	s_waitcnt lgkmcnt(11)
	v_fmac_f32_e32 v124, v222, v8
	v_fmac_f32_e32 v124, v223, v9
	s_waitcnt lgkmcnt(10)
	v_fmac_f32_e32 v124, v224, v10
	v_fmac_f32_e32 v124, v225, v11
	s_waitcnt lgkmcnt(9)
	v_fmac_f32_e32 v124, v226, v12
	v_fmac_f32_e32 v124, v227, v13
	s_waitcnt lgkmcnt(8)
	v_fmac_f32_e32 v124, v228, v14
	v_add_u32_e32 v120, 0x4d6c, v117
	ds_read2_b32 v[148:149], v120 offset0:56 offset1:52
	ds_read2_b32 v[150:151], v120 offset0:48 offset1:44
	ds_read2_b32 v[152:153], v120 offset0:40 offset1:36
	ds_read2_b32 v[154:155], v120 offset0:32 offset1:28
	ds_read2_b32 v[156:157], v120 offset0:24 offset1:20
	ds_read2_b32 v[158:159], v120 offset0:16 offset1:12
	ds_read2_b32 v[160:161], v120 offset0:8 offset1:4
	ds_read_b32 v162, v120
	v_fma_f32 v125, v229, v15, v124
	s_waitcnt lgkmcnt(15)
	v_mul_f32_e32 v122, v132, v2
	v_fmac_f32_e32 v122, v133, v3
	v_add_f32_dpp v127, v125, v125 quad_perm:[1,0,3,2] row_mask:0xf bank_mask:0xf
	s_waitcnt lgkmcnt(14)
	v_fmac_f32_e32 v122, v134, v4
	v_fmac_f32_e32 v122, v135, v5
	v_add_f32_dpp v125, v127, v127 quad_perm:[2,3,0,1] row_mask:0xf bank_mask:0xf
	v_fma_f32 v127, v49, v33, -v125
	v_cndmask_b32_e64 v16, v16, v127, s[88:89]
	s_waitcnt lgkmcnt(13)
	v_fmac_f32_e32 v122, v136, v6
	v_fmac_f32_e32 v122, v137, v7
	s_waitcnt lgkmcnt(12)
	v_fmac_f32_e32 v122, v138, v8
	v_fmac_f32_e32 v122, v139, v9
	s_waitcnt lgkmcnt(11)
	v_fmac_f32_e32 v122, v140, v10
	v_fmac_f32_e32 v122, v141, v11
	s_waitcnt lgkmcnt(10)
	v_fmac_f32_e32 v122, v142, v12
	v_fmac_f32_e32 v122, v143, v13
	s_waitcnt lgkmcnt(9)
	v_fmac_f32_e32 v122, v144, v14
	v_fmac_f32_e32 v122, v145, v15
	v_add_u32_e32 v121, 0x4c5c, v117
	ds_read2_b32 v[216:217], v121 offset0:56 offset1:52
	ds_read2_b32 v[218:219], v121 offset0:48 offset1:44
	ds_read2_b32 v[220:221], v121 offset0:40 offset1:36
	ds_read2_b32 v[222:223], v121 offset0:32 offset1:28
	ds_read2_b32 v[224:225], v121 offset0:24 offset1:20
	ds_read2_b32 v[226:227], v121 offset0:16 offset1:12
	ds_read2_b32 v[228:229], v121 offset0:8 offset1:4
	ds_read_b32 v230, v121
	s_waitcnt lgkmcnt(15)
	v_cndmask_b32_e64 v126, 0, v146, s[34:35]
	v_fma_f32 v125, v126, v16, v122
	s_waitcnt lgkmcnt(15)
	v_mul_f32_e32 v123, v148, v2
	v_fmac_f32_e32 v123, v149, v3
	v_add_f32_dpp v127, v125, v125 quad_perm:[1,0,3,2] row_mask:0xf bank_mask:0xf
	s_waitcnt lgkmcnt(14)
	v_fmac_f32_e32 v123, v150, v4
	v_fmac_f32_e32 v123, v151, v5
	v_add_f32_dpp v125, v127, v127 quad_perm:[2,3,0,1] row_mask:0xf bank_mask:0xf
	v_fma_f32 v127, v49, v33, -v125
	v_cndmask_b32_e64 v16, v16, v127, s[90:91]
	s_waitcnt lgkmcnt(13)
	v_fmac_f32_e32 v123, v152, v6
	v_fmac_f32_e32 v123, v153, v7
	s_waitcnt lgkmcnt(12)
	v_fmac_f32_e32 v123, v154, v8
	v_fmac_f32_e32 v123, v155, v9
	s_waitcnt lgkmcnt(11)
	v_fmac_f32_e32 v123, v156, v10
	v_fmac_f32_e32 v123, v157, v11
	s_waitcnt lgkmcnt(10)
	v_fmac_f32_e32 v123, v158, v12
	v_fmac_f32_e32 v123, v159, v13
	s_waitcnt lgkmcnt(9)
	v_fmac_f32_e32 v123, v160, v14
	v_fmac_f32_e32 v123, v161, v15
	v_add_u32_e32 v119, 0x4b4c, v117
	ds_read2_b32 v[132:133], v119 offset0:56 offset1:52
	ds_read2_b32 v[134:135], v119 offset0:48 offset1:44
	ds_read2_b32 v[136:137], v119 offset0:40 offset1:36
	ds_read2_b32 v[138:139], v119 offset0:32 offset1:28
	ds_read2_b32 v[140:141], v119 offset0:24 offset1:20
	ds_read2_b32 v[142:143], v119 offset0:16 offset1:12
	ds_read2_b32 v[144:145], v119 offset0:8 offset1:4
	ds_read_b32 v146, v119
	s_waitcnt lgkmcnt(15)
	v_cndmask_b32_e64 v126, 0, v162, s[18:19]
	v_fma_f32 v125, v126, v16, v123
	s_waitcnt lgkmcnt(15)
	v_mul_f32_e32 v124, v216, v2
	v_fmac_f32_e32 v124, v217, v3
	v_add_f32_dpp v127, v125, v125 quad_perm:[1,0,3,2] row_mask:0xf bank_mask:0xf
	s_waitcnt lgkmcnt(14)
	v_fmac_f32_e32 v124, v218, v4
	v_fmac_f32_e32 v124, v219, v5
	v_add_f32_dpp v125, v127, v127 quad_perm:[2,3,0,1] row_mask:0xf bank_mask:0xf
	v_fma_f32 v127, v49, v33, -v125
	v_cndmask_b32_e64 v16, v16, v127, s[92:93]
	s_waitcnt lgkmcnt(13)
	v_fmac_f32_e32 v124, v220, v6
	v_fmac_f32_e32 v124, v221, v7
	s_waitcnt lgkmcnt(12)
	v_fmac_f32_e32 v124, v222, v8
	v_fmac_f32_e32 v124, v223, v9
	s_waitcnt lgkmcnt(11)
	v_fmac_f32_e32 v124, v224, v10
	v_fmac_f32_e32 v124, v225, v11
	s_waitcnt lgkmcnt(10)
	v_fmac_f32_e32 v124, v226, v12
	v_fmac_f32_e32 v124, v227, v13
	s_waitcnt lgkmcnt(9)
	v_fmac_f32_e32 v124, v228, v14
	v_fmac_f32_e32 v124, v229, v15
	v_add_u32_e32 v120, 0x4a2c, v117
	ds_read2_b32 v[148:149], v120 offset0:60 offset1:56
	ds_read2_b32 v[150:151], v120 offset0:52 offset1:48
	ds_read2_b32 v[152:153], v120 offset0:44 offset1:40
	ds_read2_b32 v[154:155], v120 offset0:36 offset1:32
	ds_read2_b32 v[156:157], v120 offset0:28 offset1:24
	ds_read2_b32 v[158:159], v120 offset0:20 offset1:16
	ds_read2_b32 v[160:161], v120 offset0:12 offset1:8
	ds_read2_b32 v[162:163], v120 offset0:4 offset1:0
	s_waitcnt lgkmcnt(15)
	v_cndmask_b32_e64 v126, 0, v230, s[22:23]
	v_fma_f32 v125, v126, v16, v124
	s_waitcnt lgkmcnt(15)
	v_mul_f32_e32 v122, v132, v2
	v_fmac_f32_e32 v122, v133, v3
	v_add_f32_dpp v127, v125, v125 quad_perm:[1,0,3,2] row_mask:0xf bank_mask:0xf
	s_waitcnt lgkmcnt(14)
; template <int DIR>
; DI void dn_solve4(const float* M, const h16* Ki, const h16* Vi, const float* betal, const float* gcl, int half, int c, int pp, float (&x)[16]) {
;     ...
; #pragma unroll
;   for (int il = 0; il < 64; ++il) {
;     const int ri = DIR ? 63 - il : il;
;     float part = 0.f;
; #pragma unroll
;     for (int k = 0; k < (il + 3) / 4; ++k) {
;       const int jl0 = 4 * k;
;       float mv = DIR ? M[ri * MLD + 63 - jl0 - pp] : M[ri * MLD + jl0 + pp];
;       if (jl0 + 3 >= il) mv = (jl0 + pp < il) ? mv : 0.f;
;       part += mv * x[k];
;     }
;     part += __shfl_xor(part, 1); part += __shfl_xor(part, 2);
;     const float e = half ? __expf(gcl[ri]) : 1.f;
;     const float xi = betal[ri] * (float)src[ri * LDH] * e - part;
;     if ((il & 3) == pp) x[il >> 2] = xi;
;   }
	v_fmac_f32_e32 v122, v134, v4
	v_fmac_f32_e32 v122, v135, v5
	v_add_f32_dpp v125, v127, v127 quad_perm:[2,3,0,1] row_mask:0xf bank_mask:0xf
	v_fma_f32 v127, v49, v33, -v125
	v_cndmask_b32_e64 v16, v16, v127, s[98:99]
	s_waitcnt lgkmcnt(13)
	v_fmac_f32_e32 v122, v136, v6
	v_fmac_f32_e32 v122, v137, v7
	s_waitcnt lgkmcnt(12)
	v_fmac_f32_e32 v122, v138, v8
	v_fmac_f32_e32 v122, v139, v9
	s_waitcnt lgkmcnt(11)
	v_fmac_f32_e32 v122, v140, v10
	v_fmac_f32_e32 v122, v141, v11
	s_waitcnt lgkmcnt(10)
	v_fmac_f32_e32 v122, v142, v12
	v_fmac_f32_e32 v122, v143, v13
	s_waitcnt lgkmcnt(9)
	v_fmac_f32_e32 v122, v144, v14
	v_fmac_f32_e32 v122, v145, v15
	v_add_u32_e32 v121, 0x491c, v117
	ds_read2_b32 v[216:217], v121 offset0:60 offset1:56
	ds_read2_b32 v[218:219], v121 offset0:52 offset1:48
	ds_read2_b32 v[220:221], v121 offset0:44 offset1:40
	ds_read2_b32 v[222:223], v121 offset0:36 offset1:32
	ds_read2_b32 v[224:225], v121 offset0:28 offset1:24
	ds_read2_b32 v[226:227], v121 offset0:20 offset1:16
	ds_read2_b32 v[228:229], v121 offset0:12 offset1:8
	ds_read2_b32 v[230:231], v121 offset0:4 offset1:0
	s_waitcnt lgkmcnt(15)
	v_fma_f32 v125, v146, v16, v122
	s_waitcnt lgkmcnt(15)
	v_mul_f32_e32 v123, v148, v2
	v_fmac_f32_e32 v123, v149, v3
	v_add_f32_dpp v127, v125, v125 quad_perm:[1,0,3,2] row_mask:0xf bank_mask:0xf
	s_waitcnt lgkmcnt(14)
	v_fmac_f32_e32 v123, v150, v4
	v_fmac_f32_e32 v123, v151, v5
	v_add_f32_dpp v125, v127, v127 quad_perm:[2,3,0,1] row_mask:0xf bank_mask:0xf
	v_fma_f32 v127, v115, v34, -v125
	v_cndmask_b32_e64 v17, v17, v127, s[88:89]
	s_waitcnt lgkmcnt(13)
	v_fmac_f32_e32 v123, v152, v6
	v_fmac_f32_e32 v123, v153, v7
	s_waitcnt lgkmcnt(12)
	v_fmac_f32_e32 v123, v154, v8
	v_fmac_f32_e32 v123, v155, v9
	s_waitcnt lgkmcnt(11)
	v_fmac_f32_e32 v123, v156, v10
	v_fmac_f32_e32 v123, v157, v11
	s_waitcnt lgkmcnt(10)
	v_fmac_f32_e32 v123, v158, v12
	v_fmac_f32_e32 v123, v159, v13
	s_waitcnt lgkmcnt(9)
	v_fmac_f32_e32 v123, v160, v14
	v_fmac_f32_e32 v123, v161, v15
	s_waitcnt lgkmcnt(8)
	v_fmac_f32_e32 v123, v162, v16
	v_add_u32_e32 v119, 0x480c, v117
	ds_read2_b32 v[132:133], v119 offset0:60 offset1:56
	ds_read2_b32 v[134:135], v119 offset0:52 offset1:48
	ds_read2_b32 v[136:137], v119 offset0:44 offset1:40
	ds_read2_b32 v[138:139], v119 offset0:36 offset1:32
	ds_read2_b32 v[140:141], v119 offset0:28 offset1:24
	ds_read2_b32 v[142:143], v119 offset0:20 offset1:16
	ds_read2_b32 v[144:145], v119 offset0:12 offset1:8
	ds_read2_b32 v[146:147], v119 offset0:4 offset1:0
	v_cndmask_b32_e64 v126, 0, v163, s[34:35]
	v_fma_f32 v125, v126, v17, v123
	s_waitcnt lgkmcnt(15)
	v_mul_f32_e32 v124, v216, v2
	v_fmac_f32_e32 v124, v217, v3
	v_add_f32_dpp v127, v125, v125 quad_perm:[1,0,3,2] row_mask:0xf bank_mask:0xf
	s_waitcnt lgkmcnt(14)
	v_fmac_f32_e32 v124, v218, v4
	v_fmac_f32_e32 v124, v219, v5
	v_add_f32_dpp v125, v127, v127 quad_perm:[2,3,0,1] row_mask:0xf bank_mask:0xf
	v_fma_f32 v127, v115, v34, -v125
	v_cndmask_b32_e64 v17, v17, v127, s[90:91]
	s_waitcnt lgkmcnt(13)
	v_fmac_f32_e32 v124, v220, v6
	v_fmac_f32_e32 v124, v221, v7
	s_waitcnt lgkmcnt(12)
	v_fmac_f32_e32 v124, v222, v8
	v_fmac_f32_e32 v124, v223, v9
	s_waitcnt lgkmcnt(11)
	v_fmac_f32_e32 v124, v224, v10
	v_fmac_f32_e32 v124, v225, v11
	s_waitcnt lgkmcnt(10)
	v_fmac_f32_e32 v124, v226, v12
	v_fmac_f32_e32 v124, v227, v13
	s_waitcnt lgkmcnt(9)
	v_fmac_f32_e32 v124, v228, v14
	v_fmac_f32_e32 v124, v229, v15
	s_waitcnt lgkmcnt(8)
	v_fmac_f32_e32 v124, v230, v16
	v_cndmask_b32_e64 v126, 0, v231, s[18:19]
	v_fma_f32 v125, v126, v17, v124
	s_waitcnt lgkmcnt(7)
	v_mul_f32_e32 v122, v132, v2
	v_fmac_f32_e32 v122, v133, v3
	v_add_f32_dpp v127, v125, v125 quad_perm:[1,0,3,2] row_mask:0xf bank_mask:0xf
	s_waitcnt lgkmcnt(6)
	v_fmac_f32_e32 v122, v134, v4
	v_fmac_f32_e32 v122, v135, v5
	v_add_f32_dpp v125, v127, v127 quad_perm:[2,3,0,1] row_mask:0xf bank_mask:0xf
	v_fma_f32 v127, v115, v34, -v125
	v_cndmask_b32_e64 v17, v17, v127, s[92:93]
	s_waitcnt lgkmcnt(5)
	v_fmac_f32_e32 v122, v136, v6
	v_fmac_f32_e32 v122, v137, v7
	s_waitcnt lgkmcnt(4)
	v_fmac_f32_e32 v122, v138, v8
	v_fmac_f32_e32 v122, v139, v9
	s_waitcnt lgkmcnt(3)
	v_fmac_f32_e32 v122, v140, v10
	v_fmac_f32_e32 v122, v141, v11
	s_waitcnt lgkmcnt(2)
	v_fmac_f32_e32 v122, v142, v12
	v_fmac_f32_e32 v122, v143, v13
	s_waitcnt lgkmcnt(1)
	v_fmac_f32_e32 v122, v144, v14
	v_fmac_f32_e32 v122, v145, v15
	s_waitcnt lgkmcnt(0)
	v_fmac_f32_e32 v122, v146, v16
	v_cndmask_b32_e64 v126, 0, v147, s[22:23]
	v_fma_f32 v125, v126, v17, v122
	s_nop 1
	v_add_f32_dpp v127, v125, v125 quad_perm:[1,0,3,2] row_mask:0xf bank_mask:0xf
	s_nop 1
	v_add_f32_dpp v125, v127, v127 quad_perm:[2,3,0,1] row_mask:0xf bank_mask:0xf
	v_fma_f32 v127, v115, v34, -v125
	v_cndmask_b32_e64 v17, v17, v127, s[98:99]
	v_mov_b32_e32 v29, v93
	s_branch .LBB0_828
; template <int DIR>
; DI void dn_solve4(const float* M, const h16* Ki, const h16* Vi, const float* betal, const float* gcl, int half, int c, int pp, float (&x)[16]) {
;   const h16* src = half ? (Ki + c) : (Vi + c);
; #pragma unroll
;   for (int k = 0; k < 16; ++k) x[k] = 0.f;
; #pragma unroll
;   for (int il = 0; il < 64; ++il) {
;     const int ri = DIR ? 63 - il : il;
;     float part = 0.f;
; #pragma unroll
;     for (int k = 0; k < (il + 3) / 4; ++k) {
;       const int jl0 = 4 * k;
;       float mv = DIR ? M[ri * MLD + 63 - jl0 - pp] : M[ri * MLD + jl0 + pp];
;       if (jl0 + 3 >= il) mv = (jl0 + pp < il) ? mv : 0.f;
;       part += mv * x[k];
;     }
;     part += __shfl_xor(part, 1); part += __shfl_xor(part, 2);
;     const float e = half ? __expf(gcl[ri]) : 1.f;
;     const float xi = betal[ri] * (float)src[ri * LDH] * e - part;
.Lsolve_dir0:
	v_and_b32_e32 v116, 3, v182
	v_cmp_eq_u32_e64 s[88:89], 0, v116
	v_cmp_eq_u32_e64 s[90:91], 1, v116
	v_cmp_eq_u32_e64 s[92:93], 2, v116
	v_cmp_eq_u32_e64 s[98:99], 3, v116
	v_cmp_gt_u32_e64 s[34:35], 1, v116
	v_cmp_gt_u32_e64 s[18:19], 2, v116
	v_cmp_gt_u32_e64 s[22:23], 3, v116
	v_lshlrev_b32_e32 v125, 2, v116
	v_add_u32_e32 v117, v183, v125
	v_mul_u32_u24_e32 v126, 0x90, v116
	v_add_u32_e32 v118, v114, v126
	v_mov_b32_e32 v2, 0
	v_mov_b32_e32 v3, 0
	v_mov_b32_e32 v4, 0
	v_mov_b32_e32 v5, 0
	v_mov_b32_e32 v6, 0
	v_mov_b32_e32 v7, 0
	v_mov_b32_e32 v8, 0
	v_mov_b32_e32 v9, 0
	v_mov_b32_e32 v10, 0
	v_mov_b32_e32 v11, 0
	v_mov_b32_e32 v12, 0
	v_mov_b32_e32 v13, 0
	v_mov_b32_e32 v14, 0
	v_mov_b32_e32 v15, 0
	v_mov_b32_e32 v16, 0
	v_mov_b32_e32 v17, 0
	ds_read_b32 v18, v117 offset:35840
	ds_read_u16 v35, v118 offset:0
	ds_read_b32 v19, v117 offset:35856
	ds_read_u16 v36, v118 offset:576
	ds_read_b32 v20, v117 offset:35872
	ds_read_u16 v37, v118 offset:1152
	ds_read_b32 v21, v117 offset:35888
	ds_read_u16 v38, v118 offset:1728
	s_waitcnt lgkmcnt(6)
	v_cvt_f32_f16_e32 v35, v35
	s_waitcnt lgkmcnt(4)
	v_cvt_f32_f16_e32 v36, v36
	s_waitcnt lgkmcnt(2)
	v_cvt_f32_f16_e32 v37, v37
	s_waitcnt lgkmcnt(0)
	v_cvt_f32_f16_e32 v38, v38
	v_mul_f32_e32 v18, v18, v35
	v_mul_f32_e32 v19, v19, v36
	v_mul_f32_e32 v20, v20, v37
	v_mul_f32_e32 v21, v21, v38
	ds_read_b32 v22, v117 offset:35904
	ds_read_u16 v39, v118 offset:2304
	ds_read_b32 v23, v117 offset:35920
	ds_read_u16 v40, v118 offset:2880
	ds_read_b32 v24, v117 offset:35936
	ds_read_u16 v41, v118 offset:3456
	ds_read_b32 v25, v117 offset:35952
	ds_read_u16 v42, v118 offset:4032
	s_waitcnt lgkmcnt(6)
	v_cvt_f32_f16_e32 v39, v39
	s_waitcnt lgkmcnt(4)
	v_cvt_f32_f16_e32 v40, v40
	s_waitcnt lgkmcnt(2)
	v_cvt_f32_f16_e32 v41, v41
	s_waitcnt lgkmcnt(0)
	v_cvt_f32_f16_e32 v42, v42
	v_mul_f32_e32 v22, v22, v39
	v_mul_f32_e32 v23, v23, v40
	v_mul_f32_e32 v24, v24, v41
	v_mul_f32_e32 v25, v25, v42
	ds_read_b32 v26, v117 offset:35968
	ds_read_u16 v43, v118 offset:4608
	ds_read_b32 v27, v117 offset:35984
	ds_read_u16 v44, v118 offset:5184
	ds_read_b32 v28, v117 offset:36000
	ds_read_u16 v45, v118 offset:5760
	ds_read_b32 v30, v117 offset:36016
	ds_read_u16 v46, v118 offset:6336
	s_waitcnt lgkmcnt(6)
	v_cvt_f32_f16_e32 v43, v43
	s_waitcnt lgkmcnt(4)
	v_cvt_f32_f16_e32 v44, v44
	s_waitcnt lgkmcnt(2)
	v_cvt_f32_f16_e32 v45, v45
	s_waitcnt lgkmcnt(0)
	v_cvt_f32_f16_e32 v46, v46
	v_mul_f32_e32 v26, v26, v43
	v_mul_f32_e32 v27, v27, v44
	v_mul_f32_e32 v28, v28, v45
	v_mul_f32_e32 v30, v30, v46
	ds_read_b32 v31, v117 offset:36032
	ds_read_u16 v47, v118 offset:6912
	ds_read_b32 v32, v117 offset:36048
	ds_read_u16 v48, v118 offset:7488
	ds_read_b32 v33, v117 offset:36064
	ds_read_u16 v49, v118 offset:8064
	ds_read_b32 v34, v117 offset:36080
	ds_read_u16 v115, v118 offset:8640
	s_waitcnt lgkmcnt(6)
	v_cvt_f32_f16_e32 v47, v47
	s_waitcnt lgkmcnt(4)
	v_cvt_f32_f16_e32 v48, v48
	s_waitcnt lgkmcnt(2)
	v_cvt_f32_f16_e32 v49, v49
	s_waitcnt lgkmcnt(0)
	v_cvt_f32_f16_e32 v115, v115
	v_mul_f32_e32 v31, v31, v47
	v_mul_f32_e32 v32, v32, v48
	v_mul_f32_e32 v33, v33, v49
	v_mul_f32_e32 v34, v34, v115
	s_and_b64 vcc, exec, s[78:79]
	s_cbranch_vccnz .Lsolved0_noexp
	ds_read_b32 v35, v117 offset:36352
	ds_read_b32 v36, v117 offset:36368
	ds_read_b32 v37, v117 offset:36384
	ds_read_b32 v38, v117 offset:36400
	ds_read_b32 v39, v117 offset:36416
	ds_read_b32 v40, v117 offset:36432
	ds_read_b32 v41, v117 offset:36448
	ds_read_b32 v42, v117 offset:36464
	s_waitcnt lgkmcnt(7)
	v_mul_f32_e32 v35, 0x3fb8aa3b, v35
	s_waitcnt lgkmcnt(6)
	v_mul_f32_e32 v36, 0x3fb8aa3b, v36
	s_waitcnt lgkmcnt(5)
	v_mul_f32_e32 v37, 0x3fb8aa3b, v37
	s_waitcnt lgkmcnt(4)
	v_mul_f32_e32 v38, 0x3fb8aa3b, v38
	s_waitcnt lgkmcnt(3)
	v_mul_f32_e32 v39, 0x3fb8aa3b, v39
	s_waitcnt lgkmcnt(2)
	v_mul_f32_e32 v40, 0x3fb8aa3b, v40
	s_waitcnt lgkmcnt(1)
	v_mul_f32_e32 v41, 0x3fb8aa3b, v41
	s_waitcnt lgkmcnt(0)
	v_mul_f32_e32 v42, 0x3fb8aa3b, v42
	v_exp_f32_e32 v35, v35
	v_exp_f32_e32 v36, v36
	v_exp_f32_e32 v37, v37
	v_exp_f32_e32 v38, v38
	v_exp_f32_e32 v39, v39
	v_exp_f32_e32 v40, v40
	v_exp_f32_e32 v41, v41
	v_exp_f32_e32 v42, v42
	ds_read_b32 v43, v117 offset:36480
	ds_read_b32 v44, v117 offset:36496
	ds_read_b32 v45, v117 offset:36512
	ds_read_b32 v46, v117 offset:36528
	ds_read_b32 v47, v117 offset:36544
	ds_read_b32 v48, v117 offset:36560
	ds_read_b32 v49, v117 offset:36576
	ds_read_b32 v115, v117 offset:36592
	s_waitcnt lgkmcnt(7)
	v_mul_f32_e32 v43, 0x3fb8aa3b, v43
	s_waitcnt lgkmcnt(6)
	v_mul_f32_e32 v44, 0x3fb8aa3b, v44
	s_waitcnt lgkmcnt(5)
	v_mul_f32_e32 v45, 0x3fb8aa3b, v45
	s_waitcnt lgkmcnt(4)
	v_mul_f32_e32 v46, 0x3fb8aa3b, v46
	s_waitcnt lgkmcnt(3)
	v_mul_f32_e32 v47, 0x3fb8aa3b, v47
	s_waitcnt lgkmcnt(2)
	v_mul_f32_e32 v48, 0x3fb8aa3b, v48
	s_waitcnt lgkmcnt(1)
	v_mul_f32_e32 v49, 0x3fb8aa3b, v49
	s_waitcnt lgkmcnt(0)
	v_mul_f32_e32 v115, 0x3fb8aa3b, v115
	v_exp_f32_e32 v43, v43
	v_exp_f32_e32 v44, v44
	v_exp_f32_e32 v45, v45
	v_exp_f32_e32 v46, v46
	v_exp_f32_e32 v47, v47
	v_exp_f32_e32 v48, v48
	v_exp_f32_e32 v49, v49
	v_exp_f32_e32 v115, v115
	s_branch .Lsolved0_go

; template <int DIR>
; DI void dn_solve4(const float* M, const h16* Ki, const h16* Vi, const float* betal, const float* gcl, int half, int c, int pp, float (&x)[16]) {
;     ...
; #pragma unroll
;   for (int il = 0; il < 64; ++il) {
;     const int ri = DIR ? 63 - il : il;
;     float part = 0.f;
; #pragma unroll
;     for (int k = 0; k < (il + 3) / 4; ++k) {
;       const int jl0 = 4 * k;
;       float mv = DIR ? M[ri * MLD + 63 - jl0 - pp] : M[ri * MLD + jl0 + pp];
;       if (jl0 + 3 >= il) mv = (jl0 + pp < il) ? mv : 0.f;
;       part += mv * x[k];
;     }
;     part += __shfl_xor(part, 1); part += __shfl_xor(part, 2);
;     const float e = half ? __expf(gcl[ri]) : 1.f;
;     const float xi = betal[ri] * (float)src[ri * LDH] * e - part;
;     if ((il & 3) == pp) x[il >> 2] = xi;
;   }
.Lsolved0_go:
	s_nop 0
	s_waitcnt lgkmcnt(0)
	v_add_u32_e32 v120, 0x4910, v117
	ds_read_b32 v148, v120
	v_add_u32_e32 v121, 0x4a20, v117
	ds_read_b32 v216, v121
	v_mul_f32_e32 v125, v35, v18
	v_cndmask_b32_e64 v2, v2, v125, s[88:89]
	v_add_u32_e32 v119, 0x4b30, v117
	ds_read_b32 v132, v119
	s_waitcnt lgkmcnt(2)
	v_cndmask_b32_e64 v126, 0, v148, s[34:35]
	v_mul_f32_e32 v125, v126, v2
	s_nop 1
	v_add_f32_dpp v127, v125, v125 quad_perm:[1,0,3,2] row_mask:0xf bank_mask:0xf
	s_nop 1
	v_add_f32_dpp v125, v127, v127 quad_perm:[2,3,0,1] row_mask:0xf bank_mask:0xf
	v_fma_f32 v127, v35, v18, -v125
	v_cndmask_b32_e64 v2, v2, v127, s[90:91]
	v_add_u32_e32 v120, 0x4c40, v117
	ds_read_b32 v148, v120
	s_waitcnt lgkmcnt(2)
	v_cndmask_b32_e64 v126, 0, v216, s[18:19]
	v_mul_f32_e32 v125, v126, v2
	s_nop 1
	v_add_f32_dpp v127, v125, v125 quad_perm:[1,0,3,2] row_mask:0xf bank_mask:0xf
	s_nop 1
	v_add_f32_dpp v125, v127, v127 quad_perm:[2,3,0,1] row_mask:0xf bank_mask:0xf
	v_fma_f32 v127, v35, v18, -v125
	v_cndmask_b32_e64 v2, v2, v127, s[92:93]
	v_add_u32_e32 v121, 0x4d50, v117
	ds_read2_b32 v[216:217], v121 offset0:0 offset1:4
	s_waitcnt lgkmcnt(2)
	v_cndmask_b32_e64 v126, 0, v132, s[22:23]
	v_mul_f32_e32 v125, v126, v2
	s_nop 1
	v_add_f32_dpp v127, v125, v125 quad_perm:[1,0,3,2] row_mask:0xf bank_mask:0xf
	s_nop 1
	v_add_f32_dpp v125, v127, v127 quad_perm:[2,3,0,1] row_mask:0xf bank_mask:0xf
	v_fma_f32 v127, v35, v18, -v125
	v_cndmask_b32_e64 v2, v2, v127, s[98:99]
	v_add_u32_e32 v119, 0x4e60, v117
	ds_read2_b32 v[132:133], v119 offset0:0 offset1:4
	s_waitcnt lgkmcnt(2)
	v_mul_f32_e32 v125, v148, v2
	s_waitcnt lgkmcnt(1)
	v_mul_f32_e32 v124, v216, v2
	s_nop 0
	v_add_f32_dpp v127, v125, v125 quad_perm:[1,0,3,2] row_mask:0xf bank_mask:0xf
	s_nop 1
	v_add_f32_dpp v125, v127, v127 quad_perm:[2,3,0,1] row_mask:0xf bank_mask:0xf
	v_fma_f32 v127, v36, v19, -v125
	v_cndmask_b32_e64 v3, v3, v127, s[88:89]
	v_add_u32_e32 v120, 0x4f70, v117
	ds_read2_b32 v[148:149], v120 offset0:0 offset1:4
	v_cndmask_b32_e64 v126, 0, v217, s[34:35]
	v_fma_f32 v125, v126, v3, v124
	s_waitcnt lgkmcnt(1)
	v_mul_f32_e32 v122, v132, v2
	s_nop 0
	v_add_f32_dpp v127, v125, v125 quad_perm:[1,0,3,2] row_mask:0xf bank_mask:0xf
	s_nop 1
	v_add_f32_dpp v125, v127, v127 quad_perm:[2,3,0,1] row_mask:0xf bank_mask:0xf
	v_fma_f32 v127, v36, v19, -v125
	v_cndmask_b32_e64 v3, v3, v127, s[90:91]
	v_add_u32_e32 v121, 0x5080, v117
	ds_read2_b32 v[216:217], v121 offset0:0 offset1:4
	v_cndmask_b32_e64 v126, 0, v133, s[18:19]
	v_fma_f32 v125, v126, v3, v122
	s_waitcnt lgkmcnt(1)
	v_mul_f32_e32 v123, v148, v2
	s_nop 0
	v_add_f32_dpp v127, v125, v125 quad_perm:[1,0,3,2] row_mask:0xf bank_mask:0xf
	s_nop 1
	v_add_f32_dpp v125, v127, v127 quad_perm:[2,3,0,1] row_mask:0xf bank_mask:0xf
	v_fma_f32 v127, v36, v19, -v125
	v_cndmask_b32_e64 v3, v3, v127, s[92:93]
	v_add_u32_e32 v119, 0x5190, v117
	ds_read2_b32 v[132:133], v119 offset0:0 offset1:4
	ds_read_b32 v134, v119 offset:32
	v_cndmask_b32_e64 v126, 0, v149, s[22:23]
	v_fma_f32 v125, v126, v3, v123
	s_waitcnt lgkmcnt(2)
	v_mul_f32_e32 v124, v216, v2
	s_nop 0
	v_add_f32_dpp v127, v125, v125 quad_perm:[1,0,3,2] row_mask:0xf bank_mask:0xf
	s_nop 1
	v_add_f32_dpp v125, v127, v127 quad_perm:[2,3,0,1] row_mask:0xf bank_mask:0xf
	v_fma_f32 v127, v36, v19, -v125
	v_cndmask_b32_e64 v3, v3, v127, s[98:99]
	v_add_u32_e32 v120, 0x52a0, v117
	ds_read2_b32 v[148:149], v120 offset0:0 offset1:4
	ds_read_b32 v150, v120 offset:32
	v_fma_f32 v125, v217, v3, v124
	s_waitcnt lgkmcnt(3)
	v_mul_f32_e32 v122, v132, v2
	v_fmac_f32_e32 v122, v133, v3
	v_add_f32_dpp v127, v125, v125 quad_perm:[1,0,3,2] row_mask:0xf bank_mask:0xf
	s_nop 1
	v_add_f32_dpp v125, v127, v127 quad_perm:[2,3,0,1] row_mask:0xf bank_mask:0xf
	v_fma_f32 v127, v37, v20, -v125
	v_cndmask_b32_e64 v4, v4, v127, s[88:89]
	v_add_u32_e32 v121, 0x53b0, v117
	ds_read2_b32 v[216:217], v121 offset0:0 offset1:4
	ds_read_b32 v218, v121 offset:32
	s_waitcnt lgkmcnt(4)
	v_cndmask_b32_e64 v126, 0, v134, s[34:35]
	v_fma_f32 v125, v126, v4, v122
	s_waitcnt lgkmcnt(3)
	v_mul_f32_e32 v123, v148, v2
	v_fmac_f32_e32 v123, v149, v3
	v_add_f32_dpp v127, v125, v125 quad_perm:[1,0,3,2] row_mask:0xf bank_mask:0xf
	s_nop 1
	v_add_f32_dpp v125, v127, v127 quad_perm:[2,3,0,1] row_mask:0xf bank_mask:0xf
	v_fma_f32 v127, v37, v20, -v125
	v_cndmask_b32_e64 v4, v4, v127, s[90:91]
	v_add_u32_e32 v119, 0x54c0, v117
	ds_read2_b32 v[132:133], v119 offset0:0 offset1:4
	ds_read_b32 v134, v119 offset:32
	s_waitcnt lgkmcnt(4)
	v_cndmask_b32_e64 v126, 0, v150, s[18:19]
	v_fma_f32 v125, v126, v4, v123
	s_waitcnt lgkmcnt(3)
	v_mul_f32_e32 v124, v216, v2
	v_fmac_f32_e32 v124, v217, v3
	v_add_f32_dpp v127, v125, v125 quad_perm:[1,0,3,2] row_mask:0xf bank_mask:0xf
	s_nop 1
	v_add_f32_dpp v125, v127, v127 quad_perm:[2,3,0,1] row_mask:0xf bank_mask:0xf
	v_fma_f32 v127, v37, v20, -v125
	v_cndmask_b32_e64 v4, v4, v127, s[92:93]
	v_add_u32_e32 v120, 0x55d0, v117
	ds_read2_b32 v[148:149], v120 offset0:0 offset1:4
	ds_read2_b32 v[150:151], v120 offset0:8 offset1:12
	s_waitcnt lgkmcnt(4)
	v_cndmask_b32_e64 v126, 0, v218, s[22:23]
	v_fma_f32 v125, v126, v4, v124
	s_waitcnt lgkmcnt(3)
	v_mul_f32_e32 v122, v132, v2
	v_fmac_f32_e32 v122, v133, v3
	v_add_f32_dpp v127, v125, v125 quad_perm:[1,0,3,2] row_mask:0xf bank_mask:0xf
	s_nop 1
	v_add_f32_dpp v125, v127, v127 quad_perm:[2,3,0,1] row_mask:0xf bank_mask:0xf
	v_fma_f32 v127, v37, v20, -v125
	v_cndmask_b32_e64 v4, v4, v127, s[98:99]
	v_add_u32_e32 v121, 0x56e0, v117
	ds_read2_b32 v[216:217], v121 offset0:0 offset1:4
	ds_read2_b32 v[218:219], v121 offset0:8 offset1:12
	s_waitcnt lgkmcnt(4)
	v_fma_f32 v125, v134, v4, v122
	s_waitcnt lgkmcnt(3)
; template <int DIR>
; DI void dn_solve4(const float* M, const h16* Ki, const h16* Vi, const float* betal, const float* gcl, int half, int c, int pp, float (&x)[16]) {
;     ...
; #pragma unroll
;   for (int il = 0; il < 64; ++il) {
;     const int ri = DIR ? 63 - il : il;
;     float part = 0.f;
; #pragma unroll
;     for (int k = 0; k < (il + 3) / 4; ++k) {
;       const int jl0 = 4 * k;
;       float mv = DIR ? M[ri * MLD + 63 - jl0 - pp] : M[ri * MLD + jl0 + pp];
;       if (jl0 + 3 >= il) mv = (jl0 + pp < il) ? mv : 0.f;
;       part += mv * x[k];
;     }
;     part += __shfl_xor(part, 1); part += __shfl_xor(part, 2);
;     const float e = half ? __expf(gcl[ri]) : 1.f;
;     const float xi = betal[ri] * (float)src[ri * LDH] * e - part;
;     if ((il & 3) == pp) x[il >> 2] = xi;
;   }
	v_mul_f32_e32 v123, v148, v2
	v_fmac_f32_e32 v123, v149, v3
	v_add_f32_dpp v127, v125, v125 quad_perm:[1,0,3,2] row_mask:0xf bank_mask:0xf
	s_waitcnt lgkmcnt(2)
	v_fmac_f32_e32 v123, v150, v4
	s_nop 0
	v_add_f32_dpp v125, v127, v127 quad_perm:[2,3,0,1] row_mask:0xf bank_mask:0xf
	v_fma_f32 v127, v38, v21, -v125
	v_cndmask_b32_e64 v5, v5, v127, s[88:89]
	v_add_u32_e32 v119, 0x57f0, v117
	ds_read2_b32 v[132:133], v119 offset0:0 offset1:4
	ds_read2_b32 v[134:135], v119 offset0:8 offset1:12
	v_cndmask_b32_e64 v126, 0, v151, s[34:35]
	v_fma_f32 v125, v126, v5, v123
	s_waitcnt lgkmcnt(3)
	v_mul_f32_e32 v124, v216, v2
	v_fmac_f32_e32 v124, v217, v3
	v_add_f32_dpp v127, v125, v125 quad_perm:[1,0,3,2] row_mask:0xf bank_mask:0xf
	s_waitcnt lgkmcnt(2)
	v_fmac_f32_e32 v124, v218, v4
	s_nop 0
	v_add_f32_dpp v125, v127, v127 quad_perm:[2,3,0,1] row_mask:0xf bank_mask:0xf
	v_fma_f32 v127, v38, v21, -v125
	v_cndmask_b32_e64 v5, v5, v127, s[90:91]
	v_add_u32_e32 v120, 0x5900, v117
	ds_read2_b32 v[148:149], v120 offset0:0 offset1:4
	ds_read2_b32 v[150:151], v120 offset0:8 offset1:12
	v_cndmask_b32_e64 v126, 0, v219, s[18:19]
	v_fma_f32 v125, v126, v5, v124
	s_waitcnt lgkmcnt(3)
	v_mul_f32_e32 v122, v132, v2
	v_fmac_f32_e32 v122, v133, v3
	v_add_f32_dpp v127, v125, v125 quad_perm:[1,0,3,2] row_mask:0xf bank_mask:0xf
	s_waitcnt lgkmcnt(2)
	v_fmac_f32_e32 v122, v134, v4
	s_nop 0
	v_add_f32_dpp v125, v127, v127 quad_perm:[2,3,0,1] row_mask:0xf bank_mask:0xf
	v_fma_f32 v127, v38, v21, -v125
	v_cndmask_b32_e64 v5, v5, v127, s[92:93]
	v_add_u32_e32 v121, 0x5a10, v117
	ds_read2_b32 v[216:217], v121 offset0:0 offset1:4
	ds_read2_b32 v[218:219], v121 offset0:8 offset1:12
	ds_read_b32 v220, v121 offset:64
	v_cndmask_b32_e64 v126, 0, v135, s[22:23]
	v_fma_f32 v125, v126, v5, v122
	s_waitcnt lgkmcnt(4)
	v_mul_f32_e32 v123, v148, v2
	v_fmac_f32_e32 v123, v149, v3
	v_add_f32_dpp v127, v125, v125 quad_perm:[1,0,3,2] row_mask:0xf bank_mask:0xf
	s_waitcnt lgkmcnt(3)
	v_fmac_f32_e32 v123, v150, v4
	s_nop 0
	v_add_f32_dpp v125, v127, v127 quad_perm:[2,3,0,1] row_mask:0xf bank_mask:0xf
	v_fma_f32 v127, v38, v21, -v125
	v_cndmask_b32_e64 v5, v5, v127, s[98:99]
	v_add_u32_e32 v119, 0x5b20, v117
	ds_read2_b32 v[132:133], v119 offset0:0 offset1:4
	ds_read2_b32 v[134:135], v119 offset0:8 offset1:12
	ds_read_b32 v136, v119 offset:64
	v_fma_f32 v125, v151, v5, v123
	s_waitcnt lgkmcnt(5)
	v_mul_f32_e32 v124, v216, v2
	v_fmac_f32_e32 v124, v217, v3
	v_add_f32_dpp v127, v125, v125 quad_perm:[1,0,3,2] row_mask:0xf bank_mask:0xf
	s_waitcnt lgkmcnt(4)
	v_fmac_f32_e32 v124, v218, v4
	v_fmac_f32_e32 v124, v219, v5
	v_add_f32_dpp v125, v127, v127 quad_perm:[2,3,0,1] row_mask:0xf bank_mask:0xf
	v_fma_f32 v127, v39, v22, -v125
	v_cndmask_b32_e64 v6, v6, v127, s[88:89]
	v_add_u32_e32 v120, 0x5c30, v117
	ds_read2_b32 v[148:149], v120 offset0:0 offset1:4
	ds_read2_b32 v[150:151], v120 offset0:8 offset1:12
	ds_read_b32 v152, v120 offset:64
	s_waitcnt lgkmcnt(6)
	v_cndmask_b32_e64 v126, 0, v220, s[34:35]
	v_fma_f32 v125, v126, v6, v124
	s_waitcnt lgkmcnt(5)
	v_mul_f32_e32 v122, v132, v2
	v_fmac_f32_e32 v122, v133, v3
	v_add_f32_dpp v127, v125, v125 quad_perm:[1,0,3,2] row_mask:0xf bank_mask:0xf
	s_waitcnt lgkmcnt(4)
	v_fmac_f32_e32 v122, v134, v4
	v_fmac_f32_e32 v122, v135, v5
	v_add_f32_dpp v125, v127, v127 quad_perm:[2,3,0,1] row_mask:0xf bank_mask:0xf
	v_fma_f32 v127, v39, v22, -v125
	v_cndmask_b32_e64 v6, v6, v127, s[90:91]
	v_add_u32_e32 v121, 0x5d40, v117
	ds_read2_b32 v[216:217], v121 offset0:0 offset1:4
	ds_read2_b32 v[218:219], v121 offset0:8 offset1:12
	ds_read_b32 v220, v121 offset:64
	s_waitcnt lgkmcnt(6)
	v_cndmask_b32_e64 v126, 0, v136, s[18:19]
	v_fma_f32 v125, v126, v6, v122
	s_waitcnt lgkmcnt(5)
	v_mul_f32_e32 v123, v148, v2
	v_fmac_f32_e32 v123, v149, v3
	v_add_f32_dpp v127, v125, v125 quad_perm:[1,0,3,2] row_mask:0xf bank_mask:0xf
	s_waitcnt lgkmcnt(4)
	v_fmac_f32_e32 v123, v150, v4
	v_fmac_f32_e32 v123, v151, v5
	v_add_f32_dpp v125, v127, v127 quad_perm:[2,3,0,1] row_mask:0xf bank_mask:0xf
	v_fma_f32 v127, v39, v22, -v125
	v_cndmask_b32_e64 v6, v6, v127, s[92:93]
	v_add_u32_e32 v119, 0x5e50, v117
	ds_read2_b32 v[132:133], v119 offset0:0 offset1:4
	ds_read2_b32 v[134:135], v119 offset0:8 offset1:12
	ds_read2_b32 v[136:137], v119 offset0:16 offset1:20
	s_waitcnt lgkmcnt(6)
	v_cndmask_b32_e64 v126, 0, v152, s[22:23]
	v_fma_f32 v125, v126, v6, v123
	s_waitcnt lgkmcnt(5)
	v_mul_f32_e32 v124, v216, v2
	v_fmac_f32_e32 v124, v217, v3
	v_add_f32_dpp v127, v125, v125 quad_perm:[1,0,3,2] row_mask:0xf bank_mask:0xf
	s_waitcnt lgkmcnt(4)
	v_fmac_f32_e32 v124, v218, v4
	v_fmac_f32_e32 v124, v219, v5
	v_add_f32_dpp v125, v127, v127 quad_perm:[2,3,0,1] row_mask:0xf bank_mask:0xf
	v_fma_f32 v127, v39, v22, -v125
	v_cndmask_b32_e64 v6, v6, v127, s[98:99]
	v_add_u32_e32 v120, 0x5f60, v117
	ds_read2_b32 v[148:149], v120 offset0:0 offset1:4
	ds_read2_b32 v[150:151], v120 offset0:8 offset1:12
	ds_read2_b32 v[152:153], v120 offset0:16 offset1:20
	s_waitcnt lgkmcnt(6)
	v_fma_f32 v125, v220, v6, v124
	s_waitcnt lgkmcnt(5)
	v_mul_f32_e32 v122, v132, v2
	v_fmac_f32_e32 v122, v133, v3
	v_add_f32_dpp v127, v125, v125 quad_perm:[1,0,3,2] row_mask:0xf bank_mask:0xf
	s_waitcnt lgkmcnt(4)
	v_fmac_f32_e32 v122, v134, v4
	v_fmac_f32_e32 v122, v135, v5
	v_add_f32_dpp v125, v127, v127 quad_perm:[2,3,0,1] row_mask:0xf bank_mask:0xf
	v_fma_f32 v127, v40, v23, -v125
	v_cndmask_b32_e64 v7, v7, v127, s[88:89]
	s_waitcnt lgkmcnt(3)
	v_fmac_f32_e32 v122, v136, v6
	v_add_u32_e32 v121, 0x6070, v117
	ds_read2_b32 v[216:217], v121 offset0:0 offset1:4
	ds_read2_b32 v[218:219], v121 offset0:8 offset1:12
	ds_read2_b32 v[220:221], v121 offset0:16 offset1:20
	v_cndmask_b32_e64 v126, 0, v137, s[34:35]
	v_fma_f32 v125, v126, v7, v122
	s_waitcnt lgkmcnt(5)
; template <int DIR>
; DI void dn_solve4(const float* M, const h16* Ki, const h16* Vi, const float* betal, const float* gcl, int half, int c, int pp, float (&x)[16]) {
;     ...
; #pragma unroll
;   for (int il = 0; il < 64; ++il) {
;     const int ri = DIR ? 63 - il : il;
;     float part = 0.f;
; #pragma unroll
;     for (int k = 0; k < (il + 3) / 4; ++k) {
;       const int jl0 = 4 * k;
;       float mv = DIR ? M[ri * MLD + 63 - jl0 - pp] : M[ri * MLD + jl0 + pp];
;       if (jl0 + 3 >= il) mv = (jl0 + pp < il) ? mv : 0.f;
;       part += mv * x[k];
;     }
;     part += __shfl_xor(part, 1); part += __shfl_xor(part, 2);
;     const float e = half ? __expf(gcl[ri]) : 1.f;
;     const float xi = betal[ri] * (float)src[ri * LDH] * e - part;
;     if ((il & 3) == pp) x[il >> 2] = xi;
;   }
	v_mul_f32_e32 v123, v148, v2
	v_fmac_f32_e32 v123, v149, v3
	v_add_f32_dpp v127, v125, v125 quad_perm:[1,0,3,2] row_mask:0xf bank_mask:0xf
	s_waitcnt lgkmcnt(4)
	v_fmac_f32_e32 v123, v150, v4
	v_fmac_f32_e32 v123, v151, v5
	v_add_f32_dpp v125, v127, v127 quad_perm:[2,3,0,1] row_mask:0xf bank_mask:0xf
	v_fma_f32 v127, v40, v23, -v125
	v_cndmask_b32_e64 v7, v7, v127, s[90:91]
	s_waitcnt lgkmcnt(3)
	v_fmac_f32_e32 v123, v152, v6
	v_add_u32_e32 v119, 0x6180, v117
	ds_read2_b32 v[132:133], v119 offset0:0 offset1:4
	ds_read2_b32 v[134:135], v119 offset0:8 offset1:12
	ds_read2_b32 v[136:137], v119 offset0:16 offset1:20
	v_cndmask_b32_e64 v126, 0, v153, s[18:19]
	v_fma_f32 v125, v126, v7, v123
	s_waitcnt lgkmcnt(5)
	v_mul_f32_e32 v124, v216, v2
	v_fmac_f32_e32 v124, v217, v3
	v_add_f32_dpp v127, v125, v125 quad_perm:[1,0,3,2] row_mask:0xf bank_mask:0xf
	s_waitcnt lgkmcnt(4)
	v_fmac_f32_e32 v124, v218, v4
	v_fmac_f32_e32 v124, v219, v5
	v_add_f32_dpp v125, v127, v127 quad_perm:[2,3,0,1] row_mask:0xf bank_mask:0xf
	v_fma_f32 v127, v40, v23, -v125
	v_cndmask_b32_e64 v7, v7, v127, s[92:93]
	s_waitcnt lgkmcnt(3)
	v_fmac_f32_e32 v124, v220, v6
	v_add_u32_e32 v120, 0x6290, v117
	ds_read2_b32 v[148:149], v120 offset0:0 offset1:4
	ds_read2_b32 v[150:151], v120 offset0:8 offset1:12
	ds_read2_b32 v[152:153], v120 offset0:16 offset1:20
	ds_read_b32 v154, v120 offset:96
	v_cndmask_b32_e64 v126, 0, v221, s[22:23]
	v_fma_f32 v125, v126, v7, v124
	s_waitcnt lgkmcnt(6)
	v_mul_f32_e32 v122, v132, v2
	v_fmac_f32_e32 v122, v133, v3
	v_add_f32_dpp v127, v125, v125 quad_perm:[1,0,3,2] row_mask:0xf bank_mask:0xf
	s_waitcnt lgkmcnt(5)
	v_fmac_f32_e32 v122, v134, v4
	v_fmac_f32_e32 v122, v135, v5
	v_add_f32_dpp v125, v127, v127 quad_perm:[2,3,0,1] row_mask:0xf bank_mask:0xf
	v_fma_f32 v127, v40, v23, -v125
	v_cndmask_b32_e64 v7, v7, v127, s[98:99]
	s_waitcnt lgkmcnt(4)
	v_fmac_f32_e32 v122, v136, v6
	v_add_u32_e32 v121, 0x63a0, v117
	ds_read2_b32 v[216:217], v121 offset0:0 offset1:4
	ds_read2_b32 v[218:219], v121 offset0:8 offset1:12
	ds_read2_b32 v[220:221], v121 offset0:16 offset1:20
	ds_read_b32 v222, v121 offset:96
	v_fma_f32 v125, v137, v7, v122
	s_waitcnt lgkmcnt(7)
	v_mul_f32_e32 v123, v148, v2
	v_fmac_f32_e32 v123, v149, v3
	v_add_f32_dpp v127, v125, v125 quad_perm:[1,0,3,2] row_mask:0xf bank_mask:0xf
	s_waitcnt lgkmcnt(6)
	v_fmac_f32_e32 v123, v150, v4
	v_fmac_f32_e32 v123, v151, v5
	v_add_f32_dpp v125, v127, v127 quad_perm:[2,3,0,1] row_mask:0xf bank_mask:0xf
	v_fma_f32 v127, v41, v24, -v125
	v_cndmask_b32_e64 v8, v8, v127, s[88:89]
	s_waitcnt lgkmcnt(5)
	v_fmac_f32_e32 v123, v152, v6
	v_fmac_f32_e32 v123, v153, v7
	v_add_u32_e32 v119, 0x64b0, v117
	ds_read2_b32 v[132:133], v119 offset0:0 offset1:4
	ds_read2_b32 v[134:135], v119 offset0:8 offset1:12
	ds_read2_b32 v[136:137], v119 offset0:16 offset1:20
	ds_read_b32 v138, v119 offset:96
	s_waitcnt lgkmcnt(8)
	v_cndmask_b32_e64 v126, 0, v154, s[34:35]
	v_fma_f32 v125, v126, v8, v123
	s_waitcnt lgkmcnt(7)
	v_mul_f32_e32 v124, v216, v2
	v_fmac_f32_e32 v124, v217, v3
	v_add_f32_dpp v127, v125, v125 quad_perm:[1,0,3,2] row_mask:0xf bank_mask:0xf
	s_waitcnt lgkmcnt(6)
	v_fmac_f32_e32 v124, v218, v4
	v_fmac_f32_e32 v124, v219, v5
	v_add_f32_dpp v125, v127, v127 quad_perm:[2,3,0,1] row_mask:0xf bank_mask:0xf
	v_fma_f32 v127, v41, v24, -v125
	v_cndmask_b32_e64 v8, v8, v127, s[90:91]
	s_waitcnt lgkmcnt(5)
	v_fmac_f32_e32 v124, v220, v6
	v_fmac_f32_e32 v124, v221, v7
	v_add_u32_e32 v120, 0x65c0, v117
	ds_read2_b32 v[148:149], v120 offset0:0 offset1:4
	ds_read2_b32 v[150:151], v120 offset0:8 offset1:12
	ds_read2_b32 v[152:153], v120 offset0:16 offset1:20
	ds_read_b32 v154, v120 offset:96
	s_waitcnt lgkmcnt(8)
	v_cndmask_b32_e64 v126, 0, v222, s[18:19]
	v_fma_f32 v125, v126, v8, v124
	s_waitcnt lgkmcnt(7)
	v_mul_f32_e32 v122, v132, v2
	v_fmac_f32_e32 v122, v133, v3
	v_add_f32_dpp v127, v125, v125 quad_perm:[1,0,3,2] row_mask:0xf bank_mask:0xf
	s_waitcnt lgkmcnt(6)
	v_fmac_f32_e32 v122, v134, v4
	v_fmac_f32_e32 v122, v135, v5
	v_add_f32_dpp v125, v127, v127 quad_perm:[2,3,0,1] row_mask:0xf bank_mask:0xf
	v_fma_f32 v127, v41, v24, -v125
	v_cndmask_b32_e64 v8, v8, v127, s[92:93]
	s_waitcnt lgkmcnt(5)
	v_fmac_f32_e32 v122, v136, v6
	v_fmac_f32_e32 v122, v137, v7
	v_add_u32_e32 v121, 0x66d0, v117
	ds_read2_b32 v[216:217], v121 offset0:0 offset1:4
	ds_read2_b32 v[218:219], v121 offset0:8 offset1:12
	ds_read2_b32 v[220:221], v121 offset0:16 offset1:20
	ds_read2_b32 v[222:223], v121 offset0:24 offset1:28
	s_waitcnt lgkmcnt(8)
	v_cndmask_b32_e64 v126, 0, v138, s[22:23]
	v_fma_f32 v125, v126, v8, v122
	s_waitcnt lgkmcnt(7)
	v_mul_f32_e32 v123, v148, v2
	v_fmac_f32_e32 v123, v149, v3
	v_add_f32_dpp v127, v125, v125 quad_perm:[1,0,3,2] row_mask:0xf bank_mask:0xf
	s_waitcnt lgkmcnt(6)
	v_fmac_f32_e32 v123, v150, v4
	v_fmac_f32_e32 v123, v151, v5
	v_add_f32_dpp v125, v127, v127 quad_perm:[2,3,0,1] row_mask:0xf bank_mask:0xf
	v_fma_f32 v127, v41, v24, -v125
	v_cndmask_b32_e64 v8, v8, v127, s[98:99]
	s_waitcnt lgkmcnt(5)
	v_fmac_f32_e32 v123, v152, v6
	v_fmac_f32_e32 v123, v153, v7
	v_add_u32_e32 v119, 0x67e0, v117
	ds_read2_b32 v[132:133], v119 offset0:0 offset1:4
	ds_read2_b32 v[134:135], v119 offset0:8 offset1:12
	ds_read2_b32 v[136:137], v119 offset0:16 offset1:20
	ds_read2_b32 v[138:139], v119 offset0:24 offset1:28
	s_waitcnt lgkmcnt(8)
	v_fma_f32 v125, v154, v8, v123
	s_waitcnt lgkmcnt(7)
	v_mul_f32_e32 v124, v216, v2
	v_fmac_f32_e32 v124, v217, v3
	v_add_f32_dpp v127, v125, v125 quad_perm:[1,0,3,2] row_mask:0xf bank_mask:0xf
	s_waitcnt lgkmcnt(6)
; template <int DIR>
; DI void dn_solve4(const float* M, const h16* Ki, const h16* Vi, const float* betal, const float* gcl, int half, int c, int pp, float (&x)[16]) {
;     ...
; #pragma unroll
;   for (int il = 0; il < 64; ++il) {
;     const int ri = DIR ? 63 - il : il;
;     float part = 0.f;
; #pragma unroll
;     for (int k = 0; k < (il + 3) / 4; ++k) {
;       const int jl0 = 4 * k;
;       float mv = DIR ? M[ri * MLD + 63 - jl0 - pp] : M[ri * MLD + jl0 + pp];
;       if (jl0 + 3 >= il) mv = (jl0 + pp < il) ? mv : 0.f;
;       part += mv * x[k];
;     }
;     part += __shfl_xor(part, 1); part += __shfl_xor(part, 2);
;     const float e = half ? __expf(gcl[ri]) : 1.f;
;     const float xi = betal[ri] * (float)src[ri * LDH] * e - part;
;     if ((il & 3) == pp) x[il >> 2] = xi;
;   }
	v_fmac_f32_e32 v124, v218, v4
	v_fmac_f32_e32 v124, v219, v5
	v_add_f32_dpp v125, v127, v127 quad_perm:[2,3,0,1] row_mask:0xf bank_mask:0xf
	v_fma_f32 v127, v42, v25, -v125
	v_cndmask_b32_e64 v9, v9, v127, s[88:89]
	s_waitcnt lgkmcnt(5)
	v_fmac_f32_e32 v124, v220, v6
	v_fmac_f32_e32 v124, v221, v7
	s_waitcnt lgkmcnt(4)
	v_fmac_f32_e32 v124, v222, v8
	v_add_u32_e32 v120, 0x68f0, v117
	ds_read2_b32 v[148:149], v120 offset0:0 offset1:4
	ds_read2_b32 v[150:151], v120 offset0:8 offset1:12
	ds_read2_b32 v[152:153], v120 offset0:16 offset1:20
	ds_read2_b32 v[154:155], v120 offset0:24 offset1:28
	v_cndmask_b32_e64 v126, 0, v223, s[34:35]
	v_fma_f32 v125, v126, v9, v124
	s_waitcnt lgkmcnt(7)
	v_mul_f32_e32 v122, v132, v2
	v_fmac_f32_e32 v122, v133, v3
	v_add_f32_dpp v127, v125, v125 quad_perm:[1,0,3,2] row_mask:0xf bank_mask:0xf
	s_waitcnt lgkmcnt(6)
	v_fmac_f32_e32 v122, v134, v4
	v_fmac_f32_e32 v122, v135, v5
	v_add_f32_dpp v125, v127, v127 quad_perm:[2,3,0,1] row_mask:0xf bank_mask:0xf
	v_fma_f32 v127, v42, v25, -v125
	v_cndmask_b32_e64 v9, v9, v127, s[90:91]
	s_waitcnt lgkmcnt(5)
	v_fmac_f32_e32 v122, v136, v6
	v_fmac_f32_e32 v122, v137, v7
	s_waitcnt lgkmcnt(4)
	v_fmac_f32_e32 v122, v138, v8
	v_add_u32_e32 v121, 0x6a00, v117
	ds_read2_b32 v[216:217], v121 offset0:0 offset1:4
	ds_read2_b32 v[218:219], v121 offset0:8 offset1:12
	ds_read2_b32 v[220:221], v121 offset0:16 offset1:20
	ds_read2_b32 v[222:223], v121 offset0:24 offset1:28
	v_cndmask_b32_e64 v126, 0, v139, s[18:19]
	v_fma_f32 v125, v126, v9, v122
	s_waitcnt lgkmcnt(7)
	v_mul_f32_e32 v123, v148, v2
	v_fmac_f32_e32 v123, v149, v3
	v_add_f32_dpp v127, v125, v125 quad_perm:[1,0,3,2] row_mask:0xf bank_mask:0xf
	s_waitcnt lgkmcnt(6)
	v_fmac_f32_e32 v123, v150, v4
	v_fmac_f32_e32 v123, v151, v5
	v_add_f32_dpp v125, v127, v127 quad_perm:[2,3,0,1] row_mask:0xf bank_mask:0xf
	v_fma_f32 v127, v42, v25, -v125
	v_cndmask_b32_e64 v9, v9, v127, s[92:93]
	s_waitcnt lgkmcnt(5)
	v_fmac_f32_e32 v123, v152, v6
	v_fmac_f32_e32 v123, v153, v7
	s_waitcnt lgkmcnt(4)
	v_fmac_f32_e32 v123, v154, v8
	v_add_u32_e32 v119, 0x6b10, v117
	ds_read2_b32 v[132:133], v119 offset0:0 offset1:4
	ds_read2_b32 v[134:135], v119 offset0:8 offset1:12
	ds_read2_b32 v[136:137], v119 offset0:16 offset1:20
	ds_read2_b32 v[138:139], v119 offset0:24 offset1:28
	ds_read_b32 v140, v119 offset:128
	v_cndmask_b32_e64 v126, 0, v155, s[22:23]
	v_fma_f32 v125, v126, v9, v123
	s_waitcnt lgkmcnt(8)
	v_mul_f32_e32 v124, v216, v2
	v_fmac_f32_e32 v124, v217, v3
	v_add_f32_dpp v127, v125, v125 quad_perm:[1,0,3,2] row_mask:0xf bank_mask:0xf
	s_waitcnt lgkmcnt(7)
	v_fmac_f32_e32 v124, v218, v4
	v_fmac_f32_e32 v124, v219, v5
	v_add_f32_dpp v125, v127, v127 quad_perm:[2,3,0,1] row_mask:0xf bank_mask:0xf
	v_fma_f32 v127, v42, v25, -v125
	v_cndmask_b32_e64 v9, v9, v127, s[98:99]
	s_waitcnt lgkmcnt(6)
	v_fmac_f32_e32 v124, v220, v6
	v_fmac_f32_e32 v124, v221, v7
	s_waitcnt lgkmcnt(5)
	v_fmac_f32_e32 v124, v222, v8
	v_add_u32_e32 v120, 0x6c20, v117
	ds_read2_b32 v[148:149], v120 offset0:0 offset1:4
	ds_read2_b32 v[150:151], v120 offset0:8 offset1:12
	ds_read2_b32 v[152:153], v120 offset0:16 offset1:20
	ds_read2_b32 v[154:155], v120 offset0:24 offset1:28
	ds_read_b32 v156, v120 offset:128
	v_fma_f32 v125, v223, v9, v124
	s_waitcnt lgkmcnt(9)
	v_mul_f32_e32 v122, v132, v2
	v_fmac_f32_e32 v122, v133, v3
	v_add_f32_dpp v127, v125, v125 quad_perm:[1,0,3,2] row_mask:0xf bank_mask:0xf
	s_waitcnt lgkmcnt(8)
	v_fmac_f32_e32 v122, v134, v4
	v_fmac_f32_e32 v122, v135, v5
	v_add_f32_dpp v125, v127, v127 quad_perm:[2,3,0,1] row_mask:0xf bank_mask:0xf
	v_fma_f32 v127, v43, v26, -v125
	v_cndmask_b32_e64 v10, v10, v127, s[88:89]
	s_waitcnt lgkmcnt(7)
	v_fmac_f32_e32 v122, v136, v6
	v_fmac_f32_e32 v122, v137, v7
	s_waitcnt lgkmcnt(6)
	v_fmac_f32_e32 v122, v138, v8
	v_fmac_f32_e32 v122, v139, v9
	v_add_u32_e32 v121, 0x6d30, v117
	ds_read2_b32 v[216:217], v121 offset0:0 offset1:4
	ds_read2_b32 v[218:219], v121 offset0:8 offset1:12
	ds_read2_b32 v[220:221], v121 offset0:16 offset1:20
	ds_read2_b32 v[222:223], v121 offset0:24 offset1:28
	ds_read_b32 v224, v121 offset:128
	s_waitcnt lgkmcnt(10)
	v_cndmask_b32_e64 v126, 0, v140, s[34:35]
	v_fma_f32 v125, v126, v10, v122
	s_waitcnt lgkmcnt(9)
	v_mul_f32_e32 v123, v148, v2
	v_fmac_f32_e32 v123, v149, v3
	v_add_f32_dpp v127, v125, v125 quad_perm:[1,0,3,2] row_mask:0xf bank_mask:0xf
	s_waitcnt lgkmcnt(8)
	v_fmac_f32_e32 v123, v150, v4
	v_fmac_f32_e32 v123, v151, v5
	v_add_f32_dpp v125, v127, v127 quad_perm:[2,3,0,1] row_mask:0xf bank_mask:0xf
	v_fma_f32 v127, v43, v26, -v125
	v_cndmask_b32_e64 v10, v10, v127, s[90:91]
	s_waitcnt lgkmcnt(7)
	v_fmac_f32_e32 v123, v152, v6
	v_fmac_f32_e32 v123, v153, v7
	s_waitcnt lgkmcnt(6)
	v_fmac_f32_e32 v123, v154, v8
	v_fmac_f32_e32 v123, v155, v9
	v_add_u32_e32 v119, 0x6e40, v117
	ds_read2_b32 v[132:133], v119 offset0:0 offset1:4
	ds_read2_b32 v[134:135], v119 offset0:8 offset1:12
	ds_read2_b32 v[136:137], v119 offset0:16 offset1:20
	ds_read2_b32 v[138:139], v119 offset0:24 offset1:28
	ds_read_b32 v140, v119 offset:128
	s_waitcnt lgkmcnt(10)
	v_cndmask_b32_e64 v126, 0, v156, s[18:19]
	v_fma_f32 v125, v126, v10, v123
	s_waitcnt lgkmcnt(9)
	v_mul_f32_e32 v124, v216, v2
	v_fmac_f32_e32 v124, v217, v3
	v_add_f32_dpp v127, v125, v125 quad_perm:[1,0,3,2] row_mask:0xf bank_mask:0xf
	s_waitcnt lgkmcnt(8)
	v_fmac_f32_e32 v124, v218, v4
	v_fmac_f32_e32 v124, v219, v5
	v_add_f32_dpp v125, v127, v127 quad_perm:[2,3,0,1] row_mask:0xf bank_mask:0xf
	v_fma_f32 v127, v43, v26, -v125
	v_cndmask_b32_e64 v10, v10, v127, s[92:93]
	s_waitcnt lgkmcnt(7)
	v_fmac_f32_e32 v124, v220, v6
	v_fmac_f32_e32 v124, v221, v7
	s_waitcnt lgkmcnt(6)
; template <int DIR>
; DI void dn_solve4(const float* M, const h16* Ki, const h16* Vi, const float* betal, const float* gcl, int half, int c, int pp, float (&x)[16]) {
;     ...
;   for (int il = 0; il < 64; ++il) {
;     const int ri = DIR ? 63 - il : il;
;     float part = 0.f;
; #pragma unroll
;     for (int k = 0; k < (il + 3) / 4; ++k) {
;       const int jl0 = 4 * k;
;       float mv = DIR ? M[ri * MLD + 63 - jl0 - pp] : M[ri * MLD + jl0 + pp];
;       if (jl0 + 3 >= il) mv = (jl0 + pp < il) ? mv : 0.f;
;       part += mv * x[k];
;     }
;     part += __shfl_xor(part, 1); part += __shfl_xor(part, 2);
;     const float e = half ? __expf(gcl[ri]) : 1.f;
;     const float xi = betal[ri] * (float)src[ri * LDH] * e - part;
;     if ((il & 3) == pp) x[il >> 2] = xi;
;   }
	v_fmac_f32_e32 v124, v222, v8
	v_fmac_f32_e32 v124, v223, v9
	v_add_u32_e32 v120, 0x6f50, v117
	ds_read2_b32 v[148:149], v120 offset0:0 offset1:4
	ds_read2_b32 v[150:151], v120 offset0:8 offset1:12
	ds_read2_b32 v[152:153], v120 offset0:16 offset1:20
	ds_read2_b32 v[154:155], v120 offset0:24 offset1:28
	ds_read2_b32 v[156:157], v120 offset0:32 offset1:36
	s_waitcnt lgkmcnt(10)
	v_cndmask_b32_e64 v126, 0, v224, s[22:23]
	v_fma_f32 v125, v126, v10, v124
	s_waitcnt lgkmcnt(9)
	v_mul_f32_e32 v122, v132, v2
	v_fmac_f32_e32 v122, v133, v3
	v_add_f32_dpp v127, v125, v125 quad_perm:[1,0,3,2] row_mask:0xf bank_mask:0xf
	s_waitcnt lgkmcnt(8)
	v_fmac_f32_e32 v122, v134, v4
	v_fmac_f32_e32 v122, v135, v5
	v_add_f32_dpp v125, v127, v127 quad_perm:[2,3,0,1] row_mask:0xf bank_mask:0xf
	v_fma_f32 v127, v43, v26, -v125
	v_cndmask_b32_e64 v10, v10, v127, s[98:99]
	s_waitcnt lgkmcnt(7)
	v_fmac_f32_e32 v122, v136, v6
	v_fmac_f32_e32 v122, v137, v7
	s_waitcnt lgkmcnt(6)
	v_fmac_f32_e32 v122, v138, v8
	v_fmac_f32_e32 v122, v139, v9
	v_add_u32_e32 v121, 0x7060, v117
	ds_read2_b32 v[216:217], v121 offset0:0 offset1:4
	ds_read2_b32 v[218:219], v121 offset0:8 offset1:12
	ds_read2_b32 v[220:221], v121 offset0:16 offset1:20
	ds_read2_b32 v[222:223], v121 offset0:24 offset1:28
	ds_read2_b32 v[224:225], v121 offset0:32 offset1:36
	s_waitcnt lgkmcnt(10)
	v_fma_f32 v125, v140, v10, v122
	s_waitcnt lgkmcnt(9)
	v_mul_f32_e32 v123, v148, v2
	v_fmac_f32_e32 v123, v149, v3
	v_add_f32_dpp v127, v125, v125 quad_perm:[1,0,3,2] row_mask:0xf bank_mask:0xf
	s_waitcnt lgkmcnt(8)
	v_fmac_f32_e32 v123, v150, v4
	v_fmac_f32_e32 v123, v151, v5
	v_add_f32_dpp v125, v127, v127 quad_perm:[2,3,0,1] row_mask:0xf bank_mask:0xf
	v_fma_f32 v127, v44, v27, -v125
	v_cndmask_b32_e64 v11, v11, v127, s[88:89]
	s_waitcnt lgkmcnt(7)
	v_fmac_f32_e32 v123, v152, v6
	v_fmac_f32_e32 v123, v153, v7
	s_waitcnt lgkmcnt(6)
	v_fmac_f32_e32 v123, v154, v8
	v_fmac_f32_e32 v123, v155, v9
	s_waitcnt lgkmcnt(5)
	v_fmac_f32_e32 v123, v156, v10
	v_add_u32_e32 v119, 0x7170, v117
	ds_read2_b32 v[132:133], v119 offset0:0 offset1:4
	ds_read2_b32 v[134:135], v119 offset0:8 offset1:12
	ds_read2_b32 v[136:137], v119 offset0:16 offset1:20
	ds_read2_b32 v[138:139], v119 offset0:24 offset1:28
	ds_read2_b32 v[140:141], v119 offset0:32 offset1:36
	v_cndmask_b32_e64 v126, 0, v157, s[34:35]
	v_fma_f32 v125, v126, v11, v123
	s_waitcnt lgkmcnt(9)
	v_mul_f32_e32 v124, v216, v2
	v_fmac_f32_e32 v124, v217, v3
	v_add_f32_dpp v127, v125, v125 quad_perm:[1,0,3,2] row_mask:0xf bank_mask:0xf
	s_waitcnt lgkmcnt(8)
	v_fmac_f32_e32 v124, v218, v4
	v_fmac_f32_e32 v124, v219, v5
	v_add_f32_dpp v125, v127, v127 quad_perm:[2,3,0,1] row_mask:0xf bank_mask:0xf
	v_fma_f32 v127, v44, v27, -v125
	v_cndmask_b32_e64 v11, v11, v127, s[90:91]
	s_waitcnt lgkmcnt(7)
	v_fmac_f32_e32 v124, v220, v6
	v_fmac_f32_e32 v124, v221, v7
	s_waitcnt lgkmcnt(6)
	v_fmac_f32_e32 v124, v222, v8
	v_fmac_f32_e32 v124, v223, v9
	s_waitcnt lgkmcnt(5)
	v_fmac_f32_e32 v124, v224, v10
	v_add_u32_e32 v120, 0x7280, v117
	ds_read2_b32 v[148:149], v120 offset0:0 offset1:4
	ds_read2_b32 v[150:151], v120 offset0:8 offset1:12
	ds_read2_b32 v[152:153], v120 offset0:16 offset1:20
	ds_read2_b32 v[154:155], v120 offset0:24 offset1:28
	ds_read2_b32 v[156:157], v120 offset0:32 offset1:36
	v_cndmask_b32_e64 v126, 0, v225, s[18:19]
	v_fma_f32 v125, v126, v11, v124
	s_waitcnt lgkmcnt(9)
	v_mul_f32_e32 v122, v132, v2
	v_fmac_f32_e32 v122, v133, v3
	v_add_f32_dpp v127, v125, v125 quad_perm:[1,0,3,2] row_mask:0xf bank_mask:0xf
	s_waitcnt lgkmcnt(8)
	v_fmac_f32_e32 v122, v134, v4
	v_fmac_f32_e32 v122, v135, v5
	v_add_f32_dpp v125, v127, v127 quad_perm:[2,3,0,1] row_mask:0xf bank_mask:0xf
	v_fma_f32 v127, v44, v27, -v125
	v_cndmask_b32_e64 v11, v11, v127, s[92:93]
	s_waitcnt lgkmcnt(7)
	v_fmac_f32_e32 v122, v136, v6
	v_fmac_f32_e32 v122, v137, v7
	s_waitcnt lgkmcnt(6)
	v_fmac_f32_e32 v122, v138, v8
	v_fmac_f32_e32 v122, v139, v9
	s_waitcnt lgkmcnt(5)
	v_fmac_f32_e32 v122, v140, v10
	v_add_u32_e32 v121, 0x7390, v117
	ds_read2_b32 v[216:217], v121 offset0:0 offset1:4
	ds_read2_b32 v[218:219], v121 offset0:8 offset1:12
	ds_read2_b32 v[220:221], v121 offset0:16 offset1:20
	ds_read2_b32 v[222:223], v121 offset0:24 offset1:28
	ds_read2_b32 v[224:225], v121 offset0:32 offset1:36
	ds_read_b32 v226, v121 offset:160
	v_cndmask_b32_e64 v126, 0, v141, s[22:23]
	v_fma_f32 v125, v126, v11, v122
	s_waitcnt lgkmcnt(10)
	v_mul_f32_e32 v123, v148, v2
	v_fmac_f32_e32 v123, v149, v3
	v_add_f32_dpp v127, v125, v125 quad_perm:[1,0,3,2] row_mask:0xf bank_mask:0xf
	s_waitcnt lgkmcnt(9)
	v_fmac_f32_e32 v123, v150, v4
	v_fmac_f32_e32 v123, v151, v5
	v_add_f32_dpp v125, v127, v127 quad_perm:[2,3,0,1] row_mask:0xf bank_mask:0xf
	v_fma_f32 v127, v44, v27, -v125
	v_cndmask_b32_e64 v11, v11, v127, s[98:99]
	s_waitcnt lgkmcnt(8)
	v_fmac_f32_e32 v123, v152, v6
	v_fmac_f32_e32 v123, v153, v7
	s_waitcnt lgkmcnt(7)
	v_fmac_f32_e32 v123, v154, v8
	v_fmac_f32_e32 v123, v155, v9
	s_waitcnt lgkmcnt(6)
	v_fmac_f32_e32 v123, v156, v10
	v_add_u32_e32 v119, 0x74a0, v117
	ds_read2_b32 v[132:133], v119 offset0:0 offset1:4
	ds_read2_b32 v[134:135], v119 offset0:8 offset1:12
	ds_read2_b32 v[136:137], v119 offset0:16 offset1:20
	ds_read2_b32 v[138:139], v119 offset0:24 offset1:28
	ds_read2_b32 v[140:141], v119 offset0:32 offset1:36
	ds_read_b32 v142, v119 offset:160
	v_fma_f32 v125, v157, v11, v123
	s_waitcnt lgkmcnt(11)
	v_mul_f32_e32 v124, v216, v2
	v_fmac_f32_e32 v124, v217, v3
	v_add_f32_dpp v127, v125, v125 quad_perm:[1,0,3,2] row_mask:0xf bank_mask:0xf
	s_waitcnt lgkmcnt(10)
; template <int DIR>
; DI void dn_solve4(const float* M, const h16* Ki, const h16* Vi, const float* betal, const float* gcl, int half, int c, int pp, float (&x)[16]) {
;     ...
;   for (int il = 0; il < 64; ++il) {
;     const int ri = DIR ? 63 - il : il;
;     float part = 0.f;
; #pragma unroll
;     for (int k = 0; k < (il + 3) / 4; ++k) {
;       const int jl0 = 4 * k;
;       float mv = DIR ? M[ri * MLD + 63 - jl0 - pp] : M[ri * MLD + jl0 + pp];
;       if (jl0 + 3 >= il) mv = (jl0 + pp < il) ? mv : 0.f;
;       part += mv * x[k];
;     }
;     part += __shfl_xor(part, 1); part += __shfl_xor(part, 2);
;     const float e = half ? __expf(gcl[ri]) : 1.f;
;     const float xi = betal[ri] * (float)src[ri * LDH] * e - part;
;     if ((il & 3) == pp) x[il >> 2] = xi;
;   }
	v_fmac_f32_e32 v124, v218, v4
	v_fmac_f32_e32 v124, v219, v5
	v_add_f32_dpp v125, v127, v127 quad_perm:[2,3,0,1] row_mask:0xf bank_mask:0xf
	v_fma_f32 v127, v45, v28, -v125
	v_cndmask_b32_e64 v12, v12, v127, s[88:89]
	s_waitcnt lgkmcnt(9)
	v_fmac_f32_e32 v124, v220, v6
	v_fmac_f32_e32 v124, v221, v7
	s_waitcnt lgkmcnt(8)
	v_fmac_f32_e32 v124, v222, v8
	v_fmac_f32_e32 v124, v223, v9
	s_waitcnt lgkmcnt(7)
	v_fmac_f32_e32 v124, v224, v10
	v_fmac_f32_e32 v124, v225, v11
	v_add_u32_e32 v120, 0x75b0, v117
	ds_read2_b32 v[148:149], v120 offset0:0 offset1:4
	ds_read2_b32 v[150:151], v120 offset0:8 offset1:12
	ds_read2_b32 v[152:153], v120 offset0:16 offset1:20
	ds_read2_b32 v[154:155], v120 offset0:24 offset1:28
	ds_read2_b32 v[156:157], v120 offset0:32 offset1:36
	ds_read_b32 v158, v120 offset:160
	s_waitcnt lgkmcnt(12)
	v_cndmask_b32_e64 v126, 0, v226, s[34:35]
	v_fma_f32 v125, v126, v12, v124
	s_waitcnt lgkmcnt(11)
	v_mul_f32_e32 v122, v132, v2
	v_fmac_f32_e32 v122, v133, v3
	v_add_f32_dpp v127, v125, v125 quad_perm:[1,0,3,2] row_mask:0xf bank_mask:0xf
	s_waitcnt lgkmcnt(10)
	v_fmac_f32_e32 v122, v134, v4
	v_fmac_f32_e32 v122, v135, v5
	v_add_f32_dpp v125, v127, v127 quad_perm:[2,3,0,1] row_mask:0xf bank_mask:0xf
	v_fma_f32 v127, v45, v28, -v125
	v_cndmask_b32_e64 v12, v12, v127, s[90:91]
	s_waitcnt lgkmcnt(9)
	v_fmac_f32_e32 v122, v136, v6
	v_fmac_f32_e32 v122, v137, v7
	s_waitcnt lgkmcnt(8)
	v_fmac_f32_e32 v122, v138, v8
	v_fmac_f32_e32 v122, v139, v9
	s_waitcnt lgkmcnt(7)
	v_fmac_f32_e32 v122, v140, v10
	v_fmac_f32_e32 v122, v141, v11
	v_add_u32_e32 v121, 0x76c0, v117
	ds_read2_b32 v[216:217], v121 offset0:0 offset1:4
	ds_read2_b32 v[218:219], v121 offset0:8 offset1:12
	ds_read2_b32 v[220:221], v121 offset0:16 offset1:20
	ds_read2_b32 v[222:223], v121 offset0:24 offset1:28
	ds_read2_b32 v[224:225], v121 offset0:32 offset1:36
	ds_read_b32 v226, v121 offset:160
	s_waitcnt lgkmcnt(12)
	v_cndmask_b32_e64 v126, 0, v142, s[18:19]
	v_fma_f32 v125, v126, v12, v122
	s_waitcnt lgkmcnt(11)
	v_mul_f32_e32 v123, v148, v2
	v_fmac_f32_e32 v123, v149, v3
	v_add_f32_dpp v127, v125, v125 quad_perm:[1,0,3,2] row_mask:0xf bank_mask:0xf
	s_waitcnt lgkmcnt(10)
	v_fmac_f32_e32 v123, v150, v4
	v_fmac_f32_e32 v123, v151, v5
	v_add_f32_dpp v125, v127, v127 quad_perm:[2,3,0,1] row_mask:0xf bank_mask:0xf
	v_fma_f32 v127, v45, v28, -v125
	v_cndmask_b32_e64 v12, v12, v127, s[92:93]
	s_waitcnt lgkmcnt(9)
	v_fmac_f32_e32 v123, v152, v6
	v_fmac_f32_e32 v123, v153, v7
	s_waitcnt lgkmcnt(8)
	v_fmac_f32_e32 v123, v154, v8
	v_fmac_f32_e32 v123, v155, v9
	s_waitcnt lgkmcnt(7)
	v_fmac_f32_e32 v123, v156, v10
	v_fmac_f32_e32 v123, v157, v11
	v_add_u32_e32 v119, 0x77d0, v117
	ds_read2_b32 v[132:133], v119 offset0:0 offset1:4
	ds_read2_b32 v[134:135], v119 offset0:8 offset1:12
	ds_read2_b32 v[136:137], v119 offset0:16 offset1:20
	ds_read2_b32 v[138:139], v119 offset0:24 offset1:28
	ds_read2_b32 v[140:141], v119 offset0:32 offset1:36
	ds_read2_b32 v[142:143], v119 offset0:40 offset1:44
	s_waitcnt lgkmcnt(12)
	v_cndmask_b32_e64 v126, 0, v158, s[22:23]
	v_fma_f32 v125, v126, v12, v123
	s_waitcnt lgkmcnt(11)
	v_mul_f32_e32 v124, v216, v2
	v_fmac_f32_e32 v124, v217, v3
	v_add_f32_dpp v127, v125, v125 quad_perm:[1,0,3,2] row_mask:0xf bank_mask:0xf
	s_waitcnt lgkmcnt(10)
	v_fmac_f32_e32 v124, v218, v4
	v_fmac_f32_e32 v124, v219, v5
	v_add_f32_dpp v125, v127, v127 quad_perm:[2,3,0,1] row_mask:0xf bank_mask:0xf
	v_fma_f32 v127, v45, v28, -v125
	v_cndmask_b32_e64 v12, v12, v127, s[98:99]
	s_waitcnt lgkmcnt(9)
	v_fmac_f32_e32 v124, v220, v6
	v_fmac_f32_e32 v124, v221, v7
	s_waitcnt lgkmcnt(8)
	v_fmac_f32_e32 v124, v222, v8
	v_fmac_f32_e32 v124, v223, v9
	s_waitcnt lgkmcnt(7)
	v_fmac_f32_e32 v124, v224, v10
	v_fmac_f32_e32 v124, v225, v11
	v_add_u32_e32 v120, 0x78e0, v117
	ds_read2_b32 v[148:149], v120 offset0:0 offset1:4
	ds_read2_b32 v[150:151], v120 offset0:8 offset1:12
	ds_read2_b32 v[152:153], v120 offset0:16 offset1:20
	ds_read2_b32 v[154:155], v120 offset0:24 offset1:28
	ds_read2_b32 v[156:157], v120 offset0:32 offset1:36
	ds_read2_b32 v[158:159], v120 offset0:40 offset1:44
	s_waitcnt lgkmcnt(12)
	v_fma_f32 v125, v226, v12, v124
	s_waitcnt lgkmcnt(11)
	v_mul_f32_e32 v122, v132, v2
	v_fmac_f32_e32 v122, v133, v3
	v_add_f32_dpp v127, v125, v125 quad_perm:[1,0,3,2] row_mask:0xf bank_mask:0xf
	s_waitcnt lgkmcnt(10)
	v_fmac_f32_e32 v122, v134, v4
	v_fmac_f32_e32 v122, v135, v5
	v_add_f32_dpp v125, v127, v127 quad_perm:[2,3,0,1] row_mask:0xf bank_mask:0xf
	v_fma_f32 v127, v46, v30, -v125
	v_cndmask_b32_e64 v13, v13, v127, s[88:89]
	s_waitcnt lgkmcnt(9)
	v_fmac_f32_e32 v122, v136, v6
	v_fmac_f32_e32 v122, v137, v7
	s_waitcnt lgkmcnt(8)
	v_fmac_f32_e32 v122, v138, v8
	v_fmac_f32_e32 v122, v139, v9
	s_waitcnt lgkmcnt(7)
	v_fmac_f32_e32 v122, v140, v10
	v_fmac_f32_e32 v122, v141, v11
	s_waitcnt lgkmcnt(6)
	v_fmac_f32_e32 v122, v142, v12
	v_add_u32_e32 v121, 0x79f0, v117
	ds_read2_b32 v[216:217], v121 offset0:0 offset1:4
	ds_read2_b32 v[218:219], v121 offset0:8 offset1:12
	ds_read2_b32 v[220:221], v121 offset0:16 offset1:20
	ds_read2_b32 v[222:223], v121 offset0:24 offset1:28
	ds_read2_b32 v[224:225], v121 offset0:32 offset1:36
	ds_read2_b32 v[226:227], v121 offset0:40 offset1:44
	v_cndmask_b32_e64 v126, 0, v143, s[34:35]
	v_fma_f32 v125, v126, v13, v122
	s_waitcnt lgkmcnt(11)
	v_mul_f32_e32 v123, v148, v2
	v_fmac_f32_e32 v123, v149, v3
	v_add_f32_dpp v127, v125, v125 quad_perm:[1,0,3,2] row_mask:0xf bank_mask:0xf
	s_waitcnt lgkmcnt(10)
	v_fmac_f32_e32 v123, v150, v4
	v_fmac_f32_e32 v123, v151, v5
	v_add_f32_dpp v125, v127, v127 quad_perm:[2,3,0,1] row_mask:0xf bank_mask:0xf
	v_fma_f32 v127, v46, v30, -v125
	v_cndmask_b32_e64 v13, v13, v127, s[90:91]
	s_waitcnt lgkmcnt(9)
; template <int DIR>
; DI void dn_solve4(const float* M, const h16* Ki, const h16* Vi, const float* betal, const float* gcl, int half, int c, int pp, float (&x)[16]) {
;     ...
;   for (int il = 0; il < 64; ++il) {
;     const int ri = DIR ? 63 - il : il;
;     float part = 0.f;
; #pragma unroll
;     for (int k = 0; k < (il + 3) / 4; ++k) {
;       const int jl0 = 4 * k;
;       float mv = DIR ? M[ri * MLD + 63 - jl0 - pp] : M[ri * MLD + jl0 + pp];
;       if (jl0 + 3 >= il) mv = (jl0 + pp < il) ? mv : 0.f;
;       part += mv * x[k];
;     }
;     part += __shfl_xor(part, 1); part += __shfl_xor(part, 2);
;     const float e = half ? __expf(gcl[ri]) : 1.f;
;     const float xi = betal[ri] * (float)src[ri * LDH] * e - part;
;     if ((il & 3) == pp) x[il >> 2] = xi;
;   }
	v_fmac_f32_e32 v123, v152, v6
	v_fmac_f32_e32 v123, v153, v7
	s_waitcnt lgkmcnt(8)
	v_fmac_f32_e32 v123, v154, v8
	v_fmac_f32_e32 v123, v155, v9
	s_waitcnt lgkmcnt(7)
	v_fmac_f32_e32 v123, v156, v10
	v_fmac_f32_e32 v123, v157, v11
	s_waitcnt lgkmcnt(6)
	v_fmac_f32_e32 v123, v158, v12
	v_add_u32_e32 v119, 0x7b00, v117
	ds_read2_b32 v[132:133], v119 offset0:0 offset1:4
	ds_read2_b32 v[134:135], v119 offset0:8 offset1:12
	ds_read2_b32 v[136:137], v119 offset0:16 offset1:20
	ds_read2_b32 v[138:139], v119 offset0:24 offset1:28
	ds_read2_b32 v[140:141], v119 offset0:32 offset1:36
	ds_read2_b32 v[142:143], v119 offset0:40 offset1:44
	v_cndmask_b32_e64 v126, 0, v159, s[18:19]
	v_fma_f32 v125, v126, v13, v123
	s_waitcnt lgkmcnt(11)
	v_mul_f32_e32 v124, v216, v2
	v_fmac_f32_e32 v124, v217, v3
	v_add_f32_dpp v127, v125, v125 quad_perm:[1,0,3,2] row_mask:0xf bank_mask:0xf
	s_waitcnt lgkmcnt(10)
	v_fmac_f32_e32 v124, v218, v4
	v_fmac_f32_e32 v124, v219, v5
	v_add_f32_dpp v125, v127, v127 quad_perm:[2,3,0,1] row_mask:0xf bank_mask:0xf
	v_fma_f32 v127, v46, v30, -v125
	v_cndmask_b32_e64 v13, v13, v127, s[92:93]
	s_waitcnt lgkmcnt(9)
	v_fmac_f32_e32 v124, v220, v6
	v_fmac_f32_e32 v124, v221, v7
	s_waitcnt lgkmcnt(8)
	v_fmac_f32_e32 v124, v222, v8
	v_fmac_f32_e32 v124, v223, v9
	s_waitcnt lgkmcnt(7)
	v_fmac_f32_e32 v124, v224, v10
	v_fmac_f32_e32 v124, v225, v11
	s_waitcnt lgkmcnt(6)
	v_fmac_f32_e32 v124, v226, v12
	v_add_u32_e32 v120, 0x7c10, v117
	ds_read2_b32 v[148:149], v120 offset0:0 offset1:4
	ds_read2_b32 v[150:151], v120 offset0:8 offset1:12
	ds_read2_b32 v[152:153], v120 offset0:16 offset1:20
	ds_read2_b32 v[154:155], v120 offset0:24 offset1:28
	ds_read2_b32 v[156:157], v120 offset0:32 offset1:36
	ds_read2_b32 v[158:159], v120 offset0:40 offset1:44
	ds_read_b32 v160, v120 offset:192
	v_cndmask_b32_e64 v126, 0, v227, s[22:23]
	v_fma_f32 v125, v126, v13, v124
	s_waitcnt lgkmcnt(12)
	v_mul_f32_e32 v122, v132, v2
	v_fmac_f32_e32 v122, v133, v3
	v_add_f32_dpp v127, v125, v125 quad_perm:[1,0,3,2] row_mask:0xf bank_mask:0xf
	s_waitcnt lgkmcnt(11)
	v_fmac_f32_e32 v122, v134, v4
	v_fmac_f32_e32 v122, v135, v5
	v_add_f32_dpp v125, v127, v127 quad_perm:[2,3,0,1] row_mask:0xf bank_mask:0xf
	v_fma_f32 v127, v46, v30, -v125
	v_cndmask_b32_e64 v13, v13, v127, s[98:99]
	s_waitcnt lgkmcnt(10)
	v_fmac_f32_e32 v122, v136, v6
	v_fmac_f32_e32 v122, v137, v7
	s_waitcnt lgkmcnt(9)
	v_fmac_f32_e32 v122, v138, v8
	v_fmac_f32_e32 v122, v139, v9
	s_waitcnt lgkmcnt(8)
	v_fmac_f32_e32 v122, v140, v10
	v_fmac_f32_e32 v122, v141, v11
	s_waitcnt lgkmcnt(7)
	v_fmac_f32_e32 v122, v142, v12
	v_add_u32_e32 v121, 0x7d20, v117
	ds_read2_b32 v[216:217], v121 offset0:0 offset1:4
	ds_read2_b32 v[218:219], v121 offset0:8 offset1:12
	ds_read2_b32 v[220:221], v121 offset0:16 offset1:20
	ds_read2_b32 v[222:223], v121 offset0:24 offset1:28
	ds_read2_b32 v[224:225], v121 offset0:32 offset1:36
	ds_read2_b32 v[226:227], v121 offset0:40 offset1:44
	ds_read_b32 v228, v121 offset:192
	v_fma_f32 v125, v143, v13, v122
	s_waitcnt lgkmcnt(13)
	v_mul_f32_e32 v123, v148, v2
	v_fmac_f32_e32 v123, v149, v3
	v_add_f32_dpp v127, v125, v125 quad_perm:[1,0,3,2] row_mask:0xf bank_mask:0xf
	s_waitcnt lgkmcnt(12)
	v_fmac_f32_e32 v123, v150, v4
	v_fmac_f32_e32 v123, v151, v5
	v_add_f32_dpp v125, v127, v127 quad_perm:[2,3,0,1] row_mask:0xf bank_mask:0xf
	v_fma_f32 v127, v47, v31, -v125
	v_cndmask_b32_e64 v14, v14, v127, s[88:89]
	s_waitcnt lgkmcnt(11)
	v_fmac_f32_e32 v123, v152, v6
	v_fmac_f32_e32 v123, v153, v7
	s_waitcnt lgkmcnt(10)
	v_fmac_f32_e32 v123, v154, v8
	v_fmac_f32_e32 v123, v155, v9
	s_waitcnt lgkmcnt(9)
	v_fmac_f32_e32 v123, v156, v10
	v_fmac_f32_e32 v123, v157, v11
	s_waitcnt lgkmcnt(8)
	v_fmac_f32_e32 v123, v158, v12
	v_fmac_f32_e32 v123, v159, v13
	v_add_u32_e32 v119, 0x7e30, v117
	ds_read2_b32 v[132:133], v119 offset0:0 offset1:4
	ds_read2_b32 v[134:135], v119 offset0:8 offset1:12
	ds_read2_b32 v[136:137], v119 offset0:16 offset1:20
	ds_read2_b32 v[138:139], v119 offset0:24 offset1:28
	ds_read2_b32 v[140:141], v119 offset0:32 offset1:36
	ds_read2_b32 v[142:143], v119 offset0:40 offset1:44
	ds_read_b32 v144, v119 offset:192
	s_waitcnt lgkmcnt(14)
	v_cndmask_b32_e64 v126, 0, v160, s[34:35]
	v_fma_f32 v125, v126, v14, v123
	s_waitcnt lgkmcnt(13)
	v_mul_f32_e32 v124, v216, v2
	v_fmac_f32_e32 v124, v217, v3
	v_add_f32_dpp v127, v125, v125 quad_perm:[1,0,3,2] row_mask:0xf bank_mask:0xf
	s_waitcnt lgkmcnt(12)
	v_fmac_f32_e32 v124, v218, v4
	v_fmac_f32_e32 v124, v219, v5
	v_add_f32_dpp v125, v127, v127 quad_perm:[2,3,0,1] row_mask:0xf bank_mask:0xf
	v_fma_f32 v127, v47, v31, -v125
	v_cndmask_b32_e64 v14, v14, v127, s[90:91]
	s_waitcnt lgkmcnt(11)
	v_fmac_f32_e32 v124, v220, v6
	v_fmac_f32_e32 v124, v221, v7
	s_waitcnt lgkmcnt(10)
	v_fmac_f32_e32 v124, v222, v8
	v_fmac_f32_e32 v124, v223, v9
	s_waitcnt lgkmcnt(9)
	v_fmac_f32_e32 v124, v224, v10
	v_fmac_f32_e32 v124, v225, v11
	s_waitcnt lgkmcnt(8)
	v_fmac_f32_e32 v124, v226, v12
	v_fmac_f32_e32 v124, v227, v13
	v_add_u32_e32 v120, 0x7f40, v117
	ds_read2_b32 v[148:149], v120 offset0:0 offset1:4
	ds_read2_b32 v[150:151], v120 offset0:8 offset1:12
	ds_read2_b32 v[152:153], v120 offset0:16 offset1:20
	ds_read2_b32 v[154:155], v120 offset0:24 offset1:28
	ds_read2_b32 v[156:157], v120 offset0:32 offset1:36
	ds_read2_b32 v[158:159], v120 offset0:40 offset1:44
	ds_read_b32 v160, v120 offset:192
	s_waitcnt lgkmcnt(14)
	v_cndmask_b32_e64 v126, 0, v228, s[18:19]
	v_fma_f32 v125, v126, v14, v124
	s_waitcnt lgkmcnt(13)
	v_mul_f32_e32 v122, v132, v2
	v_fmac_f32_e32 v122, v133, v3
	v_add_f32_dpp v127, v125, v125 quad_perm:[1,0,3,2] row_mask:0xf bank_mask:0xf
	s_waitcnt lgkmcnt(12)
; template <int DIR>
; DI void dn_solve4(const float* M, const h16* Ki, const h16* Vi, const float* betal, const float* gcl, int half, int c, int pp, float (&x)[16]) {
;     ...
;   for (int il = 0; il < 64; ++il) {
;     const int ri = DIR ? 63 - il : il;
;     float part = 0.f;
; #pragma unroll
;     for (int k = 0; k < (il + 3) / 4; ++k) {
;       const int jl0 = 4 * k;
;       float mv = DIR ? M[ri * MLD + 63 - jl0 - pp] : M[ri * MLD + jl0 + pp];
;       if (jl0 + 3 >= il) mv = (jl0 + pp < il) ? mv : 0.f;
;       part += mv * x[k];
;     }
;     part += __shfl_xor(part, 1); part += __shfl_xor(part, 2);
;     const float e = half ? __expf(gcl[ri]) : 1.f;
;     const float xi = betal[ri] * (float)src[ri * LDH] * e - part;
;     if ((il & 3) == pp) x[il >> 2] = xi;
;   }
	v_fmac_f32_e32 v122, v134, v4
	v_fmac_f32_e32 v122, v135, v5
	v_add_f32_dpp v125, v127, v127 quad_perm:[2,3,0,1] row_mask:0xf bank_mask:0xf
	v_fma_f32 v127, v47, v31, -v125
	v_cndmask_b32_e64 v14, v14, v127, s[92:93]
	s_waitcnt lgkmcnt(11)
	v_fmac_f32_e32 v122, v136, v6
	v_fmac_f32_e32 v122, v137, v7
	s_waitcnt lgkmcnt(10)
	v_fmac_f32_e32 v122, v138, v8
	v_fmac_f32_e32 v122, v139, v9
	s_waitcnt lgkmcnt(9)
	v_fmac_f32_e32 v122, v140, v10
	v_fmac_f32_e32 v122, v141, v11
	s_waitcnt lgkmcnt(8)
	v_fmac_f32_e32 v122, v142, v12
	v_fmac_f32_e32 v122, v143, v13
	v_add_u32_e32 v121, 0x8050, v117
	ds_read2_b32 v[216:217], v121 offset0:0 offset1:4
	ds_read2_b32 v[218:219], v121 offset0:8 offset1:12
	ds_read2_b32 v[220:221], v121 offset0:16 offset1:20
	ds_read2_b32 v[222:223], v121 offset0:24 offset1:28
	ds_read2_b32 v[224:225], v121 offset0:32 offset1:36
	ds_read2_b32 v[226:227], v121 offset0:40 offset1:44
	ds_read2_b32 v[228:229], v121 offset0:48 offset1:52
	s_waitcnt lgkmcnt(14)
	v_cndmask_b32_e64 v126, 0, v144, s[22:23]
	v_fma_f32 v125, v126, v14, v122
	s_waitcnt lgkmcnt(13)
	v_mul_f32_e32 v123, v148, v2
	v_fmac_f32_e32 v123, v149, v3
	v_add_f32_dpp v127, v125, v125 quad_perm:[1,0,3,2] row_mask:0xf bank_mask:0xf
	s_waitcnt lgkmcnt(12)
	v_fmac_f32_e32 v123, v150, v4
	v_fmac_f32_e32 v123, v151, v5
	v_add_f32_dpp v125, v127, v127 quad_perm:[2,3,0,1] row_mask:0xf bank_mask:0xf
	v_fma_f32 v127, v47, v31, -v125
	v_cndmask_b32_e64 v14, v14, v127, s[98:99]
	s_waitcnt lgkmcnt(11)
	v_fmac_f32_e32 v123, v152, v6
	v_fmac_f32_e32 v123, v153, v7
	s_waitcnt lgkmcnt(10)
	v_fmac_f32_e32 v123, v154, v8
	v_fmac_f32_e32 v123, v155, v9
	s_waitcnt lgkmcnt(9)
	v_fmac_f32_e32 v123, v156, v10
	v_fmac_f32_e32 v123, v157, v11
	s_waitcnt lgkmcnt(8)
	v_fmac_f32_e32 v123, v158, v12
	v_fmac_f32_e32 v123, v159, v13
	v_add_u32_e32 v119, 0x8160, v117
	ds_read2_b32 v[132:133], v119 offset0:0 offset1:4
	ds_read2_b32 v[134:135], v119 offset0:8 offset1:12
	ds_read2_b32 v[136:137], v119 offset0:16 offset1:20
	ds_read2_b32 v[138:139], v119 offset0:24 offset1:28
	ds_read2_b32 v[140:141], v119 offset0:32 offset1:36
	ds_read2_b32 v[142:143], v119 offset0:40 offset1:44
	ds_read2_b32 v[144:145], v119 offset0:48 offset1:52
	s_waitcnt lgkmcnt(14)
	v_fma_f32 v125, v160, v14, v123
	s_waitcnt lgkmcnt(13)
	v_mul_f32_e32 v124, v216, v2
	v_fmac_f32_e32 v124, v217, v3
	v_add_f32_dpp v127, v125, v125 quad_perm:[1,0,3,2] row_mask:0xf bank_mask:0xf
	s_waitcnt lgkmcnt(12)
	v_fmac_f32_e32 v124, v218, v4
	v_fmac_f32_e32 v124, v219, v5
	v_add_f32_dpp v125, v127, v127 quad_perm:[2,3,0,1] row_mask:0xf bank_mask:0xf
	v_fma_f32 v127, v48, v32, -v125
	v_cndmask_b32_e64 v15, v15, v127, s[88:89]
	s_waitcnt lgkmcnt(11)
	v_fmac_f32_e32 v124, v220, v6
	v_fmac_f32_e32 v124, v221, v7
	s_waitcnt lgkmcnt(10)
	v_fmac_f32_e32 v124, v222, v8
	v_fmac_f32_e32 v124, v223, v9
	s_waitcnt lgkmcnt(9)
	v_fmac_f32_e32 v124, v224, v10
	v_fmac_f32_e32 v124, v225, v11
	s_waitcnt lgkmcnt(8)
	v_fmac_f32_e32 v124, v226, v12
	v_fmac_f32_e32 v124, v227, v13
	s_waitcnt lgkmcnt(7)
	v_fmac_f32_e32 v124, v228, v14
	v_add_u32_e32 v120, 0x8270, v117
	ds_read2_b32 v[148:149], v120 offset0:0 offset1:4
	ds_read2_b32 v[150:151], v120 offset0:8 offset1:12
	ds_read2_b32 v[152:153], v120 offset0:16 offset1:20
	ds_read2_b32 v[154:155], v120 offset0:24 offset1:28
	ds_read2_b32 v[156:157], v120 offset0:32 offset1:36
	ds_read2_b32 v[158:159], v120 offset0:40 offset1:44
	ds_read2_b32 v[160:161], v120 offset0:48 offset1:52
	v_cndmask_b32_e64 v126, 0, v229, s[34:35]
	v_fma_f32 v125, v126, v15, v124
	s_waitcnt lgkmcnt(13)
	v_mul_f32_e32 v122, v132, v2
	v_fmac_f32_e32 v122, v133, v3
	v_add_f32_dpp v127, v125, v125 quad_perm:[1,0,3,2] row_mask:0xf bank_mask:0xf
	s_waitcnt lgkmcnt(12)
	v_fmac_f32_e32 v122, v134, v4
	v_fmac_f32_e32 v122, v135, v5
	v_add_f32_dpp v125, v127, v127 quad_perm:[2,3,0,1] row_mask:0xf bank_mask:0xf
	v_fma_f32 v127, v48, v32, -v125
	v_cndmask_b32_e64 v15, v15, v127, s[90:91]
	s_waitcnt lgkmcnt(11)
	v_fmac_f32_e32 v122, v136, v6
	v_fmac_f32_e32 v122, v137, v7
	s_waitcnt lgkmcnt(10)
	v_fmac_f32_e32 v122, v138, v8
	v_fmac_f32_e32 v122, v139, v9
	s_waitcnt lgkmcnt(9)
	v_fmac_f32_e32 v122, v140, v10
	v_fmac_f32_e32 v122, v141, v11
	s_waitcnt lgkmcnt(8)
	v_fmac_f32_e32 v122, v142, v12
	v_fmac_f32_e32 v122, v143, v13
	s_waitcnt lgkmcnt(7)
	v_fmac_f32_e32 v122, v144, v14
	v_add_u32_e32 v121, 0x8380, v117
	ds_read2_b32 v[216:217], v121 offset0:0 offset1:4
	ds_read2_b32 v[218:219], v121 offset0:8 offset1:12
	ds_read2_b32 v[220:221], v121 offset0:16 offset1:20
	ds_read2_b32 v[222:223], v121 offset0:24 offset1:28
	ds_read2_b32 v[224:225], v121 offset0:32 offset1:36
	ds_read2_b32 v[226:227], v121 offset0:40 offset1:44
	ds_read2_b32 v[228:229], v121 offset0:48 offset1:52
	v_cndmask_b32_e64 v126, 0, v145, s[18:19]
	v_fma_f32 v125, v126, v15, v122
	s_waitcnt lgkmcnt(13)
	v_mul_f32_e32 v123, v148, v2
	v_fmac_f32_e32 v123, v149, v3
	v_add_f32_dpp v127, v125, v125 quad_perm:[1,0,3,2] row_mask:0xf bank_mask:0xf
	s_waitcnt lgkmcnt(12)
	v_fmac_f32_e32 v123, v150, v4
	v_fmac_f32_e32 v123, v151, v5
	v_add_f32_dpp v125, v127, v127 quad_perm:[2,3,0,1] row_mask:0xf bank_mask:0xf
	v_fma_f32 v127, v48, v32, -v125
	v_cndmask_b32_e64 v15, v15, v127, s[92:93]
	s_waitcnt lgkmcnt(11)
	v_fmac_f32_e32 v123, v152, v6
	v_fmac_f32_e32 v123, v153, v7
	s_waitcnt lgkmcnt(10)
	v_fmac_f32_e32 v123, v154, v8
	v_fmac_f32_e32 v123, v155, v9
	s_waitcnt lgkmcnt(9)
	v_fmac_f32_e32 v123, v156, v10
	v_fmac_f32_e32 v123, v157, v11
	s_waitcnt lgkmcnt(8)
	v_fmac_f32_e32 v123, v158, v12
	v_fmac_f32_e32 v123, v159, v13
	s_waitcnt lgkmcnt(7)
; template <int DIR>
; DI void dn_solve4(const float* M, const h16* Ki, const h16* Vi, const float* betal, const float* gcl, int half, int c, int pp, float (&x)[16]) {
;     ...
;   for (int il = 0; il < 64; ++il) {
;     const int ri = DIR ? 63 - il : il;
;     float part = 0.f;
; #pragma unroll
;     for (int k = 0; k < (il + 3) / 4; ++k) {
;       const int jl0 = 4 * k;
;       float mv = DIR ? M[ri * MLD + 63 - jl0 - pp] : M[ri * MLD + jl0 + pp];
;       if (jl0 + 3 >= il) mv = (jl0 + pp < il) ? mv : 0.f;
;       part += mv * x[k];
;     }
;     part += __shfl_xor(part, 1); part += __shfl_xor(part, 2);
;     const float e = half ? __expf(gcl[ri]) : 1.f;
;     const float xi = betal[ri] * (float)src[ri * LDH] * e - part;
;     if ((il & 3) == pp) x[il >> 2] = xi;
;   }
	v_fmac_f32_e32 v123, v160, v14
	v_add_u32_e32 v119, 0x8490, v117
	ds_read2_b32 v[132:133], v119 offset0:0 offset1:4
	ds_read2_b32 v[134:135], v119 offset0:8 offset1:12
	ds_read2_b32 v[136:137], v119 offset0:16 offset1:20
	ds_read2_b32 v[138:139], v119 offset0:24 offset1:28
	ds_read2_b32 v[140:141], v119 offset0:32 offset1:36
	ds_read2_b32 v[142:143], v119 offset0:40 offset1:44
	ds_read2_b32 v[144:145], v119 offset0:48 offset1:52
	ds_read_b32 v146, v119 offset:224
	v_cndmask_b32_e64 v126, 0, v161, s[22:23]
	v_fma_f32 v125, v126, v15, v123
	s_waitcnt lgkmcnt(14)
	v_mul_f32_e32 v124, v216, v2
	v_fmac_f32_e32 v124, v217, v3
	v_add_f32_dpp v127, v125, v125 quad_perm:[1,0,3,2] row_mask:0xf bank_mask:0xf
	s_waitcnt lgkmcnt(13)
	v_fmac_f32_e32 v124, v218, v4
	v_fmac_f32_e32 v124, v219, v5
	v_add_f32_dpp v125, v127, v127 quad_perm:[2,3,0,1] row_mask:0xf bank_mask:0xf
	v_fma_f32 v127, v48, v32, -v125
	v_cndmask_b32_e64 v15, v15, v127, s[98:99]
	s_waitcnt lgkmcnt(12)
	v_fmac_f32_e32 v124, v220, v6
	v_fmac_f32_e32 v124, v221, v7
	s_waitcnt lgkmcnt(11)
	v_fmac_f32_e32 v124, v222, v8
	v_fmac_f32_e32 v124, v223, v9
	s_waitcnt lgkmcnt(10)
	v_fmac_f32_e32 v124, v224, v10
	v_fmac_f32_e32 v124, v225, v11
	s_waitcnt lgkmcnt(9)
	v_fmac_f32_e32 v124, v226, v12
	v_fmac_f32_e32 v124, v227, v13
	s_waitcnt lgkmcnt(8)
	v_fmac_f32_e32 v124, v228, v14
	v_add_u32_e32 v120, 0x85a0, v117
	ds_read2_b32 v[148:149], v120 offset0:0 offset1:4
	ds_read2_b32 v[150:151], v120 offset0:8 offset1:12
	ds_read2_b32 v[152:153], v120 offset0:16 offset1:20
	ds_read2_b32 v[154:155], v120 offset0:24 offset1:28
	ds_read2_b32 v[156:157], v120 offset0:32 offset1:36
	ds_read2_b32 v[158:159], v120 offset0:40 offset1:44
	ds_read2_b32 v[160:161], v120 offset0:48 offset1:52
	ds_read_b32 v162, v120 offset:224
	v_fma_f32 v125, v229, v15, v124
	s_waitcnt lgkmcnt(15)
	v_mul_f32_e32 v122, v132, v2
	v_fmac_f32_e32 v122, v133, v3
	v_add_f32_dpp v127, v125, v125 quad_perm:[1,0,3,2] row_mask:0xf bank_mask:0xf
	s_waitcnt lgkmcnt(14)
	v_fmac_f32_e32 v122, v134, v4
	v_fmac_f32_e32 v122, v135, v5
	v_add_f32_dpp v125, v127, v127 quad_perm:[2,3,0,1] row_mask:0xf bank_mask:0xf
	v_fma_f32 v127, v49, v33, -v125
	v_cndmask_b32_e64 v16, v16, v127, s[88:89]
	s_waitcnt lgkmcnt(13)
	v_fmac_f32_e32 v122, v136, v6
	v_fmac_f32_e32 v122, v137, v7
	s_waitcnt lgkmcnt(12)
	v_fmac_f32_e32 v122, v138, v8
	v_fmac_f32_e32 v122, v139, v9
	s_waitcnt lgkmcnt(11)
	v_fmac_f32_e32 v122, v140, v10
	v_fmac_f32_e32 v122, v141, v11
	s_waitcnt lgkmcnt(10)
	v_fmac_f32_e32 v122, v142, v12
	v_fmac_f32_e32 v122, v143, v13
	s_waitcnt lgkmcnt(9)
	v_fmac_f32_e32 v122, v144, v14
	v_fmac_f32_e32 v122, v145, v15
	v_add_u32_e32 v121, 0x86b0, v117
	ds_read2_b32 v[216:217], v121 offset0:0 offset1:4
	ds_read2_b32 v[218:219], v121 offset0:8 offset1:12
	ds_read2_b32 v[220:221], v121 offset0:16 offset1:20
	ds_read2_b32 v[222:223], v121 offset0:24 offset1:28
	ds_read2_b32 v[224:225], v121 offset0:32 offset1:36
	ds_read2_b32 v[226:227], v121 offset0:40 offset1:44
	ds_read2_b32 v[228:229], v121 offset0:48 offset1:52
	ds_read_b32 v230, v121 offset:224
	s_waitcnt lgkmcnt(15)
	v_cndmask_b32_e64 v126, 0, v146, s[34:35]
	v_fma_f32 v125, v126, v16, v122
	s_waitcnt lgkmcnt(15)
	v_mul_f32_e32 v123, v148, v2
	v_fmac_f32_e32 v123, v149, v3
	v_add_f32_dpp v127, v125, v125 quad_perm:[1,0,3,2] row_mask:0xf bank_mask:0xf
	s_waitcnt lgkmcnt(14)
	v_fmac_f32_e32 v123, v150, v4
	v_fmac_f32_e32 v123, v151, v5
	v_add_f32_dpp v125, v127, v127 quad_perm:[2,3,0,1] row_mask:0xf bank_mask:0xf
	v_fma_f32 v127, v49, v33, -v125
	v_cndmask_b32_e64 v16, v16, v127, s[90:91]
	s_waitcnt lgkmcnt(13)
	v_fmac_f32_e32 v123, v152, v6
	v_fmac_f32_e32 v123, v153, v7
	s_waitcnt lgkmcnt(12)
	v_fmac_f32_e32 v123, v154, v8
	v_fmac_f32_e32 v123, v155, v9
	s_waitcnt lgkmcnt(11)
	v_fmac_f32_e32 v123, v156, v10
	v_fmac_f32_e32 v123, v157, v11
	s_waitcnt lgkmcnt(10)
	v_fmac_f32_e32 v123, v158, v12
	v_fmac_f32_e32 v123, v159, v13
	s_waitcnt lgkmcnt(9)
	v_fmac_f32_e32 v123, v160, v14
	v_fmac_f32_e32 v123, v161, v15
	v_add_u32_e32 v119, 0x87c0, v117
	ds_read2_b32 v[132:133], v119 offset0:0 offset1:4
	ds_read2_b32 v[134:135], v119 offset0:8 offset1:12
	ds_read2_b32 v[136:137], v119 offset0:16 offset1:20
	ds_read2_b32 v[138:139], v119 offset0:24 offset1:28
	ds_read2_b32 v[140:141], v119 offset0:32 offset1:36
	ds_read2_b32 v[142:143], v119 offset0:40 offset1:44
	ds_read2_b32 v[144:145], v119 offset0:48 offset1:52
	ds_read_b32 v146, v119 offset:224
	s_waitcnt lgkmcnt(15)
	v_cndmask_b32_e64 v126, 0, v162, s[18:19]
	v_fma_f32 v125, v126, v16, v123
	s_waitcnt lgkmcnt(15)
	v_mul_f32_e32 v124, v216, v2
	v_fmac_f32_e32 v124, v217, v3
	v_add_f32_dpp v127, v125, v125 quad_perm:[1,0,3,2] row_mask:0xf bank_mask:0xf
	s_waitcnt lgkmcnt(14)
	v_fmac_f32_e32 v124, v218, v4
	v_fmac_f32_e32 v124, v219, v5
	v_add_f32_dpp v125, v127, v127 quad_perm:[2,3,0,1] row_mask:0xf bank_mask:0xf
	v_fma_f32 v127, v49, v33, -v125
	v_cndmask_b32_e64 v16, v16, v127, s[92:93]
	s_waitcnt lgkmcnt(13)
	v_fmac_f32_e32 v124, v220, v6
	v_fmac_f32_e32 v124, v221, v7
	s_waitcnt lgkmcnt(12)
	v_fmac_f32_e32 v124, v222, v8
	v_fmac_f32_e32 v124, v223, v9
	s_waitcnt lgkmcnt(11)
	v_fmac_f32_e32 v124, v224, v10
	v_fmac_f32_e32 v124, v225, v11
	s_waitcnt lgkmcnt(10)
	v_fmac_f32_e32 v124, v226, v12
	v_fmac_f32_e32 v124, v227, v13
	s_waitcnt lgkmcnt(9)
; template <int DIR>
; DI void dn_solve4(const float* M, const h16* Ki, const h16* Vi, const float* betal, const float* gcl, int half, int c, int pp, float (&x)[16]) {
;     ...
;   for (int il = 0; il < 64; ++il) {
;     const int ri = DIR ? 63 - il : il;
;     float part = 0.f;
; #pragma unroll
;     for (int k = 0; k < (il + 3) / 4; ++k) {
;       const int jl0 = 4 * k;
;       float mv = DIR ? M[ri * MLD + 63 - jl0 - pp] : M[ri * MLD + jl0 + pp];
;       if (jl0 + 3 >= il) mv = (jl0 + pp < il) ? mv : 0.f;
;       part += mv * x[k];
;     }
;     part += __shfl_xor(part, 1); part += __shfl_xor(part, 2);
;     const float e = half ? __expf(gcl[ri]) : 1.f;
;     const float xi = betal[ri] * (float)src[ri * LDH] * e - part;
;     if ((il & 3) == pp) x[il >> 2] = xi;
;   }
	v_fmac_f32_e32 v124, v228, v14
	v_fmac_f32_e32 v124, v229, v15
	v_add_u32_e32 v120, 0x88d0, v117
	ds_read2_b32 v[148:149], v120 offset0:0 offset1:4
	ds_read2_b32 v[150:151], v120 offset0:8 offset1:12
	ds_read2_b32 v[152:153], v120 offset0:16 offset1:20
	ds_read2_b32 v[154:155], v120 offset0:24 offset1:28
	ds_read2_b32 v[156:157], v120 offset0:32 offset1:36
	ds_read2_b32 v[158:159], v120 offset0:40 offset1:44
	ds_read2_b32 v[160:161], v120 offset0:48 offset1:52
	ds_read2_b32 v[162:163], v120 offset0:56 offset1:60
	s_waitcnt lgkmcnt(15)
	v_cndmask_b32_e64 v126, 0, v230, s[22:23]
	v_fma_f32 v125, v126, v16, v124
	s_waitcnt lgkmcnt(15)
	v_mul_f32_e32 v122, v132, v2
	v_fmac_f32_e32 v122, v133, v3
	v_add_f32_dpp v127, v125, v125 quad_perm:[1,0,3,2] row_mask:0xf bank_mask:0xf
	s_waitcnt lgkmcnt(14)
	v_fmac_f32_e32 v122, v134, v4
	v_fmac_f32_e32 v122, v135, v5
	v_add_f32_dpp v125, v127, v127 quad_perm:[2,3,0,1] row_mask:0xf bank_mask:0xf
	v_fma_f32 v127, v49, v33, -v125
	v_cndmask_b32_e64 v16, v16, v127, s[98:99]
	s_waitcnt lgkmcnt(13)
	v_fmac_f32_e32 v122, v136, v6
	v_fmac_f32_e32 v122, v137, v7
	s_waitcnt lgkmcnt(12)
	v_fmac_f32_e32 v122, v138, v8
	v_fmac_f32_e32 v122, v139, v9
	s_waitcnt lgkmcnt(11)
	v_fmac_f32_e32 v122, v140, v10
	v_fmac_f32_e32 v122, v141, v11
	s_waitcnt lgkmcnt(10)
	v_fmac_f32_e32 v122, v142, v12
	v_fmac_f32_e32 v122, v143, v13
	s_waitcnt lgkmcnt(9)
	v_fmac_f32_e32 v122, v144, v14
	v_fmac_f32_e32 v122, v145, v15
	v_add_u32_e32 v121, 0x89e0, v117
	ds_read2_b32 v[216:217], v121 offset0:0 offset1:4
	ds_read2_b32 v[218:219], v121 offset0:8 offset1:12
	ds_read2_b32 v[220:221], v121 offset0:16 offset1:20
	ds_read2_b32 v[222:223], v121 offset0:24 offset1:28
	ds_read2_b32 v[224:225], v121 offset0:32 offset1:36
	ds_read2_b32 v[226:227], v121 offset0:40 offset1:44
	ds_read2_b32 v[228:229], v121 offset0:48 offset1:52
	ds_read2_b32 v[230:231], v121 offset0:56 offset1:60
	s_waitcnt lgkmcnt(15)
	v_fma_f32 v125, v146, v16, v122
	s_waitcnt lgkmcnt(15)
	v_mul_f32_e32 v123, v148, v2
	v_fmac_f32_e32 v123, v149, v3
	v_add_f32_dpp v127, v125, v125 quad_perm:[1,0,3,2] row_mask:0xf bank_mask:0xf
	s_waitcnt lgkmcnt(14)
	v_fmac_f32_e32 v123, v150, v4
	v_fmac_f32_e32 v123, v151, v5
	v_add_f32_dpp v125, v127, v127 quad_perm:[2,3,0,1] row_mask:0xf bank_mask:0xf
	v_fma_f32 v127, v115, v34, -v125
	v_cndmask_b32_e64 v17, v17, v127, s[88:89]
	s_waitcnt lgkmcnt(13)
	v_fmac_f32_e32 v123, v152, v6
	v_fmac_f32_e32 v123, v153, v7
	s_waitcnt lgkmcnt(12)
	v_fmac_f32_e32 v123, v154, v8
	v_fmac_f32_e32 v123, v155, v9
	s_waitcnt lgkmcnt(11)
	v_fmac_f32_e32 v123, v156, v10
	v_fmac_f32_e32 v123, v157, v11
	s_waitcnt lgkmcnt(10)
	v_fmac_f32_e32 v123, v158, v12
	v_fmac_f32_e32 v123, v159, v13
	s_waitcnt lgkmcnt(9)
	v_fmac_f32_e32 v123, v160, v14
	v_fmac_f32_e32 v123, v161, v15
	s_waitcnt lgkmcnt(8)
	v_fmac_f32_e32 v123, v162, v16
	v_add_u32_e32 v119, 0x8af0, v117
	ds_read2_b32 v[132:133], v119 offset0:0 offset1:4
	ds_read2_b32 v[134:135], v119 offset0:8 offset1:12
	ds_read2_b32 v[136:137], v119 offset0:16 offset1:20
	ds_read2_b32 v[138:139], v119 offset0:24 offset1:28
	ds_read2_b32 v[140:141], v119 offset0:32 offset1:36
	ds_read2_b32 v[142:143], v119 offset0:40 offset1:44
	ds_read2_b32 v[144:145], v119 offset0:48 offset1:52
	ds_read2_b32 v[146:147], v119 offset0:56 offset1:60
	v_cndmask_b32_e64 v126, 0, v163, s[34:35]
	v_fma_f32 v125, v126, v17, v123
	s_waitcnt lgkmcnt(15)
	v_mul_f32_e32 v124, v216, v2
	v_fmac_f32_e32 v124, v217, v3
	v_add_f32_dpp v127, v125, v125 quad_perm:[1,0,3,2] row_mask:0xf bank_mask:0xf
	s_waitcnt lgkmcnt(14)
	v_fmac_f32_e32 v124, v218, v4
	v_fmac_f32_e32 v124, v219, v5
	v_add_f32_dpp v125, v127, v127 quad_perm:[2,3,0,1] row_mask:0xf bank_mask:0xf
	v_fma_f32 v127, v115, v34, -v125
	v_cndmask_b32_e64 v17, v17, v127, s[90:91]
	s_waitcnt lgkmcnt(13)
	v_fmac_f32_e32 v124, v220, v6
	v_fmac_f32_e32 v124, v221, v7
	s_waitcnt lgkmcnt(12)
	v_fmac_f32_e32 v124, v222, v8
	v_fmac_f32_e32 v124, v223, v9
	s_waitcnt lgkmcnt(11)
	v_fmac_f32_e32 v124, v224, v10
	v_fmac_f32_e32 v124, v225, v11
	s_waitcnt lgkmcnt(10)
	v_fmac_f32_e32 v124, v226, v12
	v_fmac_f32_e32 v124, v227, v13
	s_waitcnt lgkmcnt(9)
	v_fmac_f32_e32 v124, v228, v14
	v_fmac_f32_e32 v124, v229, v15
	s_waitcnt lgkmcnt(8)
	v_fmac_f32_e32 v124, v230, v16
	v_cndmask_b32_e64 v126, 0, v231, s[18:19]
	v_fma_f32 v125, v126, v17, v124
	s_waitcnt lgkmcnt(7)
	v_mul_f32_e32 v122, v132, v2
	v_fmac_f32_e32 v122, v133, v3
	v_add_f32_dpp v127, v125, v125 quad_perm:[1,0,3,2] row_mask:0xf bank_mask:0xf
	s_waitcnt lgkmcnt(6)
	v_fmac_f32_e32 v122, v134, v4
	v_fmac_f32_e32 v122, v135, v5
	v_add_f32_dpp v125, v127, v127 quad_perm:[2,3,0,1] row_mask:0xf bank_mask:0xf
	v_fma_f32 v127, v115, v34, -v125
	v_cndmask_b32_e64 v17, v17, v127, s[92:93]
	s_waitcnt lgkmcnt(5)
	v_fmac_f32_e32 v122, v136, v6
	v_fmac_f32_e32 v122, v137, v7
	s_waitcnt lgkmcnt(4)
	v_fmac_f32_e32 v122, v138, v8
	v_fmac_f32_e32 v122, v139, v9
	s_waitcnt lgkmcnt(3)
	v_fmac_f32_e32 v122, v140, v10
	v_fmac_f32_e32 v122, v141, v11
	s_waitcnt lgkmcnt(2)
	v_fmac_f32_e32 v122, v142, v12
	v_fmac_f32_e32 v122, v143, v13
	s_waitcnt lgkmcnt(1)
	v_fmac_f32_e32 v122, v144, v14
	v_fmac_f32_e32 v122, v145, v15
	s_waitcnt lgkmcnt(0)
	v_fmac_f32_e32 v122, v146, v16
	v_cndmask_b32_e64 v126, 0, v147, s[22:23]
	v_fma_f32 v125, v126, v17, v122
	s_nop 1
	v_add_f32_dpp v127, v125, v125 quad_perm:[1,0,3,2] row_mask:0xf bank_mask:0xf
	s_nop 1
	v_add_f32_dpp v125, v127, v127 quad_perm:[2,3,0,1] row_mask:0xf bank_mask:0xf
	v_fma_f32 v127, v115, v34, -v125
	v_cndmask_b32_e64 v17, v17, v127, s[98:99]
	v_mov_b32_e32 v29, v130

; DI int otid() { int t = threadIdx.x & 255; asm volatile("" : "+v"(t)); return t; }
; template <int NKB>
; DI void attn_unit(const Params& p, int l, int mode, int grp, int head, int r0, int dil, int i0, int sub_len, int W, h16* lds) {
;     ...
;   const int tid = otid(), lane = tid & 63, w = tid >> 6, r = lane & 15, q = lane >> 4;
;   const int lrow = tid >> 2, seg = tid & 3;
;   int qcol, kcol, vcol;
;   if (mode == 0) { qcol = 1024 + grp * 256 + head * 64; kcol = 1792 + grp * 256 + head * 64; vcol = 2560 + grp * 256 + head * 64; }
;   else { qcol = 4352 + head * 64; kcol = 4864 + (head >> 2) * 64; vcol = 4992 + (head >> 2) * 64; }
;   __syncthreads();
;   {
;     const size_t pos = (size_t)r0 + (size_t)dil * (i0 + lrow);
;     const h16* g = P + pos * NSM + qcol + 16 * seg;
;     img_store_nat(Qi, lrow, seg, *(const u4v*)g, *(const u4v*)(g + 8));
;   }
;   float mrow[4], lsum[4];
;   f4v O[4];
;   float m_init = -1e30f, l_init = 0.f;
;   if (mode == 1) { m_init = p.d_sink[l * 8 + head]; l_init = 1.f; }
; #pragma unroll
;   for (int i = 0; i < 4; ++i) { mrow[i] = m_init; lsum[i] = l_init; O[i] = (f4v){0.f, 0.f, 0.f, 0.f}; }
;   u4v pk0, pk1, pv0, pv1;
;     ...
;   ATT_PREFETCH(0);
;   for (int kb = 0; kb < NKB; ++kb) {
;     const int j0 = i0 - W + 64 * kb;
;     const bool inr = (j0 >= 0) && (j0 < sub_len);
;     __syncthreads();
;     img_store_nat(Ki, lrow, seg, pk0, pk1);
;     img_store_T(Vt, lrow, seg, pv0, pv1);
;     __syncthreads();
; DI void phase_m2(const Params& p, int l, int bid, int nb, h16* lds) {
;     ...
;     if (v >= 5288) { v -= 5288; if (v < nA) conv_one(p, l, 2560 + v, lds); else conv_one(p, l + 1, v - nA, lds); continue; }
;     if (v < 32) { dn_c2_unit(p, v >> 2, v & 3); continue; }
;     if ((v -= 32) < 136) { mlstm_a2_unit(p, v); continue; }
;     if ((v -= 136) < 2048) { attn_unit<5>(p, l, 1, 0, v & 7, 0, 1, (v >> 3) * 64, SEQ, 128, lds); continue; }
;     v -= 2048;
;     const int grp = v >> 10, x = v & 1023, head = x & 3, tl = x >> 2;
;     const int dil = (grp == 0) ? 1 : (grp == 1) ? 4 : 16;
;     const int sub = SEQ / dil, tps = sub >> 6;
;     const int res = tl / tps, ti = tl % tps;
;     attn_unit<3>(p, l, 0, grp, head, res, dil, ti * 64, sub, 64, lds);
.LBB0_897:
	s_movk_i32 s2, 0x14a8
	v_cmp_gt_i32_e32 vcc, s2, v1
	s_and_saveexec_b64 s[2:3], vcc
	s_xor_b64 s[84:85], exec, s[2:3]
	s_cbranch_execz .LBB0_960
	v_cmp_lt_i32_e32 vcc, 31, v1
	s_and_saveexec_b64 s[2:3], vcc
	s_xor_b64 s[86:87], exec, s[2:3]
	s_cbranch_execz .LBB0_953
	s_movk_i32 s2, 0xa7
	v_cmp_lt_u32_e32 vcc, s2, v1
	s_and_saveexec_b64 s[2:3], vcc
	s_xor_b64 s[88:89], exec, s[2:3]
	s_cbranch_execz .LBB0_915
	s_movk_i32 s2, 0x8a7
	v_cmp_lt_u32_e32 vcc, s2, v1
	s_and_saveexec_b64 s[2:3], vcc
	s_xor_b64 s[34:35], exec, s[2:3]
	s_cbranch_execz .LBB0_910
	v_add_u32_e32 v2, 0xfffff758, v1
	v_lshrrev_b32_e32 v49, 10, v2
	s_movk_i32 s2, 0x400
	v_cmp_gt_u32_e32 vcc, s2, v2
	v_cmp_eq_u32_e64 s[2:3], 1, v49
	v_lshrrev_b32_e32 v3, 2, v2
	v_bfe_u32 v4, v2, 2, 8
	v_cndmask_b32_e64 v2, 4, 2, s[2:3]
	v_cndmask_b32_e64 v58, v2, 0, vcc
	s_movk_i32 s2, 0x4000
	v_lshrrev_b32_e64 v52, v58, s2
	s_movk_i32 s2, 0x100
	v_lshrrev_b32_e64 v2, v58, s2
	v_add_u32_e32 v2, -1, v2
	s_movk_i32 s2, 0xff
	v_bitop3_b32 v14, v2, v3, s2 bitop3:0x80
	v_mov_b32_e32 v15, v182
	v_lshlrev_b32_e32 v60, 6, v14
	v_sub_u32_e32 v5, 8, v58
	v_ashrrev_i32_e32 v53, 2, v15
	v_add_u32_e32 v2, v53, v60
	v_ashrrev_i32_e32 v3, 31, v2
	v_lshrrev_b32_e32 v46, v5, v4
	v_mov_b32_e32 v47, v0
	v_lshlrev_b64 v[2:3], v58, v[2:3]
	v_and_b32_e32 v51, 3, v1
	v_lshl_add_u64 v[2:3], v[2:3], 0, v[46:47]
	v_mov_b64_e32 v[38:39], s[0:1]
	s_movk_i32 s8, 0x2800
	v_mad_u64_u32 v[10:11], s[2:3], v2, s8, v[38:39]
	v_lshlrev_b32_e32 v48, 7, v51
	v_and_b32_e32 v16, 3, v15
	v_mad_i32_i24 v11, v3, s8, v11
	v_lshl_or_b32 v42, v49, 9, v48
	v_mov_b32_e32 v43, v0
	v_lshlrev_b32_e32 v40, 5, v16
	v_mov_b32_e32 v41, v0
	v_lshl_add_u64 v[2:3], v[10:11], 0, v[42:43]
	v_lshl_add_u64 v[12:13], v[2:3], 0, v[40:41]
	s_waitcnt vmcnt(63) expcnt(7) lgkmcnt(15)
	s_barrier
	global_load_dwordx4 v[2:5], v[12:13], off offset:2064
	global_load_dwordx4 v[6:9], v[12:13], off offset:2048
	v_mul_lo_u32 v17, v53, s96
	v_lshl_add_u32 v17, v16, 4, v17
	v_lshl_add_u32 v77, v17, 1, v183
	v_cmp_ne_u32_e64 s[2:3], 0, v14
	v_mul_u32_u24_e32 v14, 0x480, v16
	v_lshlrev_b32_e32 v14, 1, v14
	v_lshlrev_b32_e32 v16, 1, v53
	v_add3_u32 v78, v183, v14, v16
	v_add3_u32 v79, v183, v16, v14
	v_lshrrev_b32_e32 v14, 1, v15
	v_and_b32_e32 v59, 15, v15
	v_bfi_b32 v16, -16, v53, v15
	v_and_b32_e32 v14, 24, v14
	v_add_u32_e32 v44, 0x1400, v42
	v_mov_b32_e32 v45, v0
	v_and_b32_e32 v61, -16, v53
	s_movk_i32 s16, 0x81
	v_sub_u32_e32 v80, -16, v59
	v_sub_u32_e32 v81, 0xffffffe0, v59
	v_sub_u32_e32 v82, 0xffffffd0, v59
	s_mov_b32 s17, 0xf149f2ca
	s_mov_b32 s9, 0x3e000000
	v_lshlrev_b32_e32 v50, 1, v59
	s_movk_i32 s95, 0x2800
	s_waitcnt vmcnt(0)
	ds_write_b128 v77, v[6:9]
	ds_write_b128 v77, v[2:5] offset:16
	v_subrev_u32_e32 v2, 64, v60
	v_cmp_lt_u32_e32 vcc, v2, v52
	s_and_b64 s[2:3], s[2:3], vcc
	v_cndmask_b32_e64 v2, v60, v2, s[2:3]
	v_add_u32_e32 v2, v53, v2
	v_mad_u64_u32 v[16:17], s[2:3], v16, s96, v[14:15]
	v_mad_u32_u24 v14, v59, s96, v14
	v_ashrrev_i32_e32 v3, 31, v2
	v_lshl_add_u32 v63, v14, 1, v183
	v_lshrrev_b32_e32 v14, 2, v15
	v_lshlrev_b64 v[2:3], v58, v[2:3]
	v_and_b32_e32 v62, 12, v14
	v_mbcnt_hi_u32_b32 v14, -1, v195
	v_lshl_add_u64 v[2:3], v[2:3], 0, v[46:47]
	v_lshl_add_u32 v64, v16, 1, v183
	v_and_b32_e32 v16, 64, v14
	v_mad_u64_u32 v[4:5], s[2:3], v2, s8, v[38:39]
	v_xor_b32_e32 v15, 1, v14
	v_add_u32_e32 v16, 64, v16
	v_cmp_lt_i32_e64 s[2:3], v15, v16
	v_mad_i32_i24 v5, v3, s8, v5
	v_lshl_add_u64 v[2:3], v[4:5], 0, v[42:43]
	v_cndmask_b32_e64 v15, v14, v15, s[2:3]
	v_lshlrev_b32_e32 v65, 2, v15
	v_xor_b32_e32 v15, 2, v14
	v_cmp_lt_i32_e64 s[2:3], v15, v16
	v_lshl_add_u64 v[6:7], v[2:3], 0, v[40:41]
	v_lshl_add_u64 v[2:3], v[4:5], 0, v[44:45]
	v_cndmask_b32_e64 v15, v14, v15, s[2:3]
	v_lshlrev_b32_e32 v66, 2, v15
	v_xor_b32_e32 v15, 4, v14
	v_cmp_lt_i32_e64 s[2:3], v15, v16
	v_lshl_add_u64 v[18:19], v[2:3], 0, v[40:41]
	global_load_dwordx4 v[2:5], v[6:7], off offset:3600
	s_nop 0
	global_load_dwordx4 v[6:9], v[6:7], off offset:3584
	v_cndmask_b32_e64 v15, v14, v15, s[2:3]
	v_lshlrev_b32_e32 v67, 2, v15
	v_xor_b32_e32 v15, 8, v14
	v_cmp_lt_i32_e64 s[2:3], v15, v16
	v_or_b32_e32 v69, v62, v61
	v_add_u32_e32 v28, 0x80, v69
	v_cndmask_b32_e64 v14, v14, v15, s[2:3]
	v_lshlrev_b32_e32 v68, 2, v14
	global_load_dwordx4 v[14:17], v[18:19], off
	s_nop 0
	global_load_dwordx4 v[18:21], v[18:19], off offset:16
	s_waitcnt lgkmcnt(0)
	s_barrier
	v_sub_u32_e32 v29, v28, v59
	v_cmp_gt_u32_e64 s[2:3], s16, v29
	s_and_b64 s[58:59], vcc, s[2:3]
	s_waitcnt vmcnt(2)
	ds_write_b128 v77, v[6:9] offset:9216
	ds_write_b128 v77, v[2:5] offset:9232
	s_waitcnt vmcnt(1)
	ds_write_b16 v78, v14 offset:18432
	s_waitcnt vmcnt(0)
	ds_write_b16 v79, v18 offset:19584
	ds_write_b16_d16_hi v78, v14 offset:18576
	ds_write_b16_d16_hi v78, v18 offset:19728
	ds_write_b16 v78, v15 offset:18720
	ds_write_b16 v78, v19 offset:19872
	ds_write_b16_d16_hi v78, v15 offset:18864
	ds_write_b16_d16_hi v78, v19 offset:20016
	ds_write_b16 v78, v16 offset:19008
	ds_write_b16 v78, v20 offset:20160
	ds_write_b16_d16_hi v78, v16 offset:19152
	ds_write_b16_d16_hi v78, v20 offset:20304
	ds_write_b16 v78, v17 offset:19296
	ds_write_b16 v78, v21 offset:20448
	ds_write_b16_d16_hi v78, v17 offset:19440
	ds_write_b16_d16_hi v78, v21 offset:20592
	v_lshl_add_u64 v[2:3], v[10:11], 0, v[44:45]
	s_waitcnt lgkmcnt(0)
	s_barrier
; DI float grp16_sum(float v) { v += __shfl_xor(v, 1); v += __shfl_xor(v, 2); v += __shfl_xor(v, 4); v += __shfl_xor(v, 8); return v; }
; DI float grp16_max(float v) { v = fmaxf(v, __shfl_xor(v, 1)); v = fmaxf(v, __shfl_xor(v, 2)); v = fmaxf(v, __shfl_xor(v, 4)); v = fmaxf(v, __shfl_xor(v, 8)); return v; }
; template <int NKB>
; DI void attn_unit(const Params& p, int l, int mode, int grp, int head, int r0, int dil, int i0, int sub_len, int W, h16* lds) {
;     ...
;     mm64(Qi, Ki, S, w, lane);
;     float mx[4], al[4], rsum[4];
;     bool vm[4][4];
; #pragma unroll
;     for (int rg = 0; rg < 4; ++rg) {
;       const int row = 16 * w + 4 * q + rg;
;       float m_ = -1e30f;
; #pragma unroll
;       for (int nt = 0; nt < 4; ++nt) {
;         const int key = 16 * nt + r;
;         const int delta = row - key + W - 64 * kb;
;         const bool ok = inr && (delta >= -W) && (delta <= W);
;         vm[nt][rg] = ok;
;         float s = S[nt][rg] * 0.125f;
;         S[nt][rg] = s;
;         if (ok) m_ = fmaxf(m_, s);
;       }
;       mx[rg] = grp16_max(m_);
;     }
; #pragma unroll
;     for (int rg = 0; rg < 4; ++rg) {
;       const float mn = fmaxf(mrow[rg], mx[rg]);
;       al[rg] = __expf(mrow[rg] - mn);
;       mrow[rg] = mn;
;       float rs_ = 0.f;
; #pragma unroll
;       for (int nt = 0; nt < 4; ++nt) {
;         float pv = vm[nt][rg] ? __expf(S[nt][rg] - mn) : 0.f;
;         rs_ += pv;
;         Pi[(16 * w + 4 * q + rg) * LDH + 16 * nt + r] = (h16)pv;
;       }
;       rsum[rg] = grp16_sum(rs_);
;       lsum[rg] = lsum[rg] * al[rg] + rsum[rg];
	v_lshl_add_u64 v[26:27], v[2:3], 0, v[40:41]
	global_load_dwordx4 v[6:9], v[12:13], off offset:3600
	s_nop 0
	global_load_dwordx4 v[10:13], v[12:13], off offset:3584
	ds_read_b128 v[2:5], v64
	ds_read_b128 v[14:17], v63 offset:9216
	ds_read_b128 v[18:21], v63 offset:11520
	ds_read_b128 v[22:25], v63 offset:13824
	ds_read_b128 v[30:33], v63 offset:16128
	s_waitcnt lgkmcnt(3)
	v_mfma_f32_16x16x32_f16 v[14:17], v[2:5], v[14:17], 0
	s_waitcnt lgkmcnt(2)
	v_mfma_f32_16x16x32_f16 v[18:21], v[2:5], v[18:21], 0
	s_waitcnt lgkmcnt(1)
	v_mfma_f32_16x16x32_f16 v[22:25], v[2:5], v[22:25], 0
	s_waitcnt lgkmcnt(0)
	v_mfma_f32_16x16x32_f16 v[30:33], v[2:5], v[30:33], 0
	ds_read_b128 v[34:37], v64 offset:64
	ds_read_b128 v[2:5], v63 offset:9280
	s_waitcnt lgkmcnt(0)
	v_mfma_f32_16x16x32_f16 v[2:5], v[34:37], v[2:5], v[14:17]
	s_nop 2
	ds_read_b128 v[14:17], v63 offset:11584
	s_waitcnt lgkmcnt(0)
	v_mfma_f32_16x16x32_f16 v[14:17], v[34:37], v[14:17], v[18:21]
	s_nop 2
	ds_read_b128 v[18:21], v63 offset:13888
	v_mul_f32_e32 v29, 0x3e000000, v2
	v_max_f32_e32 v29, 0xf149f2ca, v29
	s_waitcnt lgkmcnt(0)
	v_mfma_f32_16x16x32_f16 v[18:21], v[34:37], v[18:21], v[22:25]
	v_cndmask_b32_e64 v29, v199, v29, s[58:59]
	s_nop 1
	ds_read_b128 v[22:25], v63 offset:16192
	s_waitcnt lgkmcnt(0)
	v_mfma_f32_16x16x32_f16 v[22:25], v[34:37], v[22:25], v[30:33]
	s_nop 2
	v_add_u32_e32 v30, v28, v80
	v_cmp_gt_u32_e64 s[2:3], s16, v30
	v_mul_f32_e32 v30, 0x3e000000, v14
	s_and_b64 s[56:57], vcc, s[2:3]
	v_max_f32_e32 v30, v29, v30
	v_cndmask_b32_e64 v29, v29, v30, s[56:57]
	v_add_u32_e32 v30, v28, v81
	v_cmp_gt_u32_e64 s[2:3], s16, v30
	v_mul_f32_e32 v30, 0x3e000000, v18
	s_and_b64 s[54:55], vcc, s[2:3]
	v_max_f32_e32 v30, v29, v30
	v_cndmask_b32_e64 v29, v29, v30, s[54:55]
	v_add_u32_e32 v28, v28, v82
	v_add_u32_e32 v30, 0x81, v69
	v_cmp_gt_u32_e64 s[2:3], s16, v28
	v_sub_u32_e32 v31, v30, v59
	s_and_b64 s[52:53], vcc, s[2:3]
	v_cmp_gt_u32_e64 s[2:3], s16, v31
	v_mul_f32_e32 v31, 0x3e000000, v3
	s_and_b64 s[50:51], vcc, s[2:3]
	v_max_f32_e32 v31, 0xf149f2ca, v31
	v_add_u32_e32 v32, v30, v80
	v_cndmask_b32_e64 v31, v199, v31, s[50:51]
	v_cmp_gt_u32_e64 s[2:3], s16, v32
	v_mul_f32_e32 v32, 0x3e000000, v15
	s_and_b64 s[48:49], vcc, s[2:3]
	v_max_f32_e32 v32, v31, v32
	v_cndmask_b32_e64 v31, v31, v32, s[48:49]
	v_add_u32_e32 v32, v30, v81
	v_cmp_gt_u32_e64 s[2:3], s16, v32
	v_mul_f32_e32 v32, 0x3e000000, v19
	s_and_b64 s[46:47], vcc, s[2:3]
	v_max_f32_e32 v32, v31, v32
	v_add_u32_e32 v30, v30, v82
	v_cndmask_b32_e64 v31, v31, v32, s[46:47]
	v_cmp_gt_u32_e64 s[2:3], s16, v30
	v_mul_f32_e32 v30, 0x3e000000, v23
	s_and_b64 s[38:39], vcc, s[2:3]
	v_max_f32_e32 v30, v31, v30
	v_mul_f32_e32 v28, 0x3e000000, v22
	v_cndmask_b32_e64 v30, v31, v30, s[38:39]
	v_max_f32_e32 v28, v29, v28
	s_nop 1
	v_mov_b32_dpp v31, v30 quad_perm:[1,0,3,2] row_mask:0xf bank_mask:0xf
	v_cndmask_b32_e64 v28, v29, v28, s[52:53]
	s_nop 1
	v_mov_b32_dpp v29, v28 quad_perm:[1,0,3,2] row_mask:0xf bank_mask:0xf
	s_waitcnt lgkmcnt(0)
	v_max_f32_e32 v31, v31, v31
	v_max_f32_e32 v30, v30, v31
	s_waitcnt lgkmcnt(0)
	v_max_f32_e32 v29, v29, v29
	s_nop 1
	v_mov_b32_dpp v31, v30 quad_perm:[2,3,0,1] row_mask:0xf bank_mask:0xf
	v_max_f32_e32 v28, v28, v29
	s_nop 1
	v_mov_b32_dpp v29, v28 quad_perm:[2,3,0,1] row_mask:0xf bank_mask:0xf
	s_waitcnt lgkmcnt(0)
	v_max_f32_e32 v31, v31, v31
	v_max_f32_e32 v30, v30, v31
	s_waitcnt lgkmcnt(0)
	v_max_f32_e32 v29, v29, v29
	s_nop 1
	v_mov_b32_dpp v31, v30 row_half_mirror row_mask:0xf bank_mask:0xf
	v_max_f32_e32 v28, v28, v29
	s_nop 1
	v_mov_b32_dpp v29, v28 row_half_mirror row_mask:0xf bank_mask:0xf
	s_waitcnt lgkmcnt(0)
	v_max_f32_e32 v31, v31, v31
	v_max_f32_e32 v32, v30, v31
	v_add_u32_e32 v30, 0x82, v69
	s_waitcnt lgkmcnt(0)
	v_max_f32_e32 v29, v29, v29
	v_sub_u32_e32 v31, v30, v59
	v_max_f32_e32 v28, v28, v29
	v_cmp_gt_u32_e64 s[2:3], s16, v31
	v_mul_f32_e32 v31, 0x3e000000, v4
	s_nop 1
	v_mov_b32_dpp v29, v28 row_mirror row_mask:0xf bank_mask:0xf
	s_and_b64 s[36:37], vcc, s[2:3]
	v_max_f32_e32 v31, 0xf149f2ca, v31
	v_add_u32_e32 v34, v30, v80
	v_cndmask_b32_e64 v31, v199, v31, s[36:37]
	v_cmp_gt_u32_e64 s[2:3], s16, v34
	v_mul_f32_e32 v34, 0x3e000000, v16
	s_and_b64 s[6:7], vcc, s[2:3]
	v_max_f32_e32 v34, v31, v34
	v_cndmask_b32_e64 v31, v31, v34, s[6:7]
	v_add_u32_e32 v34, v30, v81
	v_cmp_gt_u32_e64 s[2:3], s16, v34
	v_mul_f32_e32 v34, 0x3e000000, v20
	s_and_b64 s[2:3], vcc, s[2:3]
	v_max_f32_e32 v34, v31, v34
	s_waitcnt lgkmcnt(0)
	v_max3_f32 v54, v28, v29, s17
	v_cndmask_b32_e64 v31, v31, v34, s[2:3]
	v_add_u32_e32 v34, 0x83, v69
	v_fma_f32 v2, v2, s9, -v54
	v_sub_u32_e32 v35, v34, v59
	v_mul_f32_e32 v2, 0x3fb8aa3b, v2
	v_cmp_gt_u32_e64 s[40:41], s16, v35
	v_mul_f32_e32 v35, 0x3e000000, v5
	v_exp_f32_e32 v2, v2
	s_and_b64 s[40:41], vcc, s[40:41]
	v_max_f32_e32 v35, 0xf149f2ca, v35
	v_add_u32_e32 v36, v34, v80
	v_cndmask_b32_e64 v35, v199, v35, s[40:41]
	v_cmp_gt_u32_e64 s[42:43], s16, v36
	v_mul_f32_e32 v36, 0x3e000000, v17
	s_and_b64 s[42:43], vcc, s[42:43]
	v_max_f32_e32 v36, v35, v36
	v_cndmask_b32_e64 v35, v35, v36, s[42:43]
	v_add_u32_e32 v36, v34, v81
	v_cndmask_b32_e64 v2, 0, v2, s[58:59]
	v_cmp_gt_u32_e64 s[44:45], s16, v36
	v_mul_f32_e32 v36, 0x3e000000, v21
	v_add_f32_e32 v29, 0, v2
	v_cvt_f16_f32_e32 v2, v2
	s_and_b64 s[44:45], vcc, s[44:45]
	v_max_f32_e32 v36, v35, v36
	v_cndmask_b32_e64 v35, v35, v36, s[44:45]
	v_mul_lo_u32 v36, v69, s33
	v_add3_u32 v72, v183, v36, v50
	ds_write_b16 v72, v2 offset:27648
	v_fma_f32 v2, v14, s9, -v54
	v_mul_f32_e32 v2, 0x3fb8aa3b, v2
	v_exp_f32_e32 v2, v2
	v_add_u32_e32 v30, v30, v82
	v_cmp_gt_u32_e64 s[4:5], s16, v30
	v_mul_f32_e32 v30, 0x3e000000, v24
	v_cndmask_b32_e64 v2, 0, v2, s[56:57]
	v_add_f32_e32 v14, v2, v29
	v_cvt_f16_f32_e32 v2, v2
	s_and_b64 s[4:5], vcc, s[4:5]
	v_max_f32_e32 v30, v31, v30
	v_cndmask_b32_e64 v30, v31, v30, s[4:5]
	ds_write_b16 v72, v2 offset:27680
	v_fma_f32 v2, v18, s9, -v54
	v_mul_f32_e32 v2, 0x3fb8aa3b, v2
	v_exp_f32_e32 v2, v2
	s_nop 1
	v_mov_b32_dpp v31, v30 quad_perm:[1,0,3,2] row_mask:0xf bank_mask:0xf
	s_nop 1
	v_mov_b32_dpp v33, v32 row_mirror row_mask:0xf bank_mask:0xf
	v_add_u32_e32 v34, v34, v82
	v_cndmask_b32_e64 v2, 0, v2, s[54:55]
	v_add_f32_e32 v14, v2, v14
	v_cvt_f16_f32_e32 v2, v2
	s_waitcnt lgkmcnt(0)
; DI float grp16_sum(float v) { v += __shfl_xor(v, 1); v += __shfl_xor(v, 2); v += __shfl_xor(v, 4); v += __shfl_xor(v, 8); return v; }
; template <int NKB>
; DI void attn_unit(const Params& p, int l, int mode, int grp, int head, int r0, int dil, int i0, int sub_len, int W, h16* lds) {
;     ...
;     for (int rg = 0; rg < 4; ++rg) {
;       const float mn = fmaxf(mrow[rg], mx[rg]);
;       al[rg] = __expf(mrow[rg] - mn);
;       mrow[rg] = mn;
;       float rs_ = 0.f;
; #pragma unroll
;       for (int nt = 0; nt < 4; ++nt) {
;         float pv = vm[nt][rg] ? __expf(S[nt][rg] - mn) : 0.f;
;         rs_ += pv;
;         Pi[(16 * w + 4 * q + rg) * LDH + 16 * nt + r] = (h16)pv;
;       }
;       rsum[rg] = grp16_sum(rs_);
;       lsum[rg] = lsum[rg] * al[rg] + rsum[rg];
;     }
; #pragma unroll
;     for (int et = 0; et < 4; ++et)
; #pragma unroll
;       for (int rg = 0; rg < 4; ++rg) O[et][rg] *= al[rg];
	v_max_f32_e32 v31, v31, v31
	v_max_f32_e32 v30, v30, v31
	s_nop 1
	v_mov_b32_dpp v31, v30 quad_perm:[2,3,0,1] row_mask:0xf bank_mask:0xf
	ds_write_b16 v72, v2 offset:27712
	v_fma_f32 v2, v22, s9, -v54
	v_mul_f32_e32 v2, 0x3fb8aa3b, v2
	v_exp_f32_e32 v2, v2
	s_waitcnt lgkmcnt(1)
	v_max_f32_e32 v31, v31, v31
	v_max_f32_e32 v30, v30, v31
	s_nop 1
	v_mov_b32_dpp v31, v30 row_half_mirror row_mask:0xf bank_mask:0xf
	v_cndmask_b32_e64 v2, 0, v2, s[52:53]
	v_add_f32_e32 v14, v2, v14
	v_cvt_f16_f32_e32 v2, v2
	v_max3_f32 v55, v32, v33, s17
	s_waitcnt lgkmcnt(0)
	v_max_f32_e32 v31, v31, v31
	v_max_f32_e32 v30, v30, v31
	ds_write_b16 v72, v2 offset:27744
	s_nop 1
	v_mov_b32_dpp v2, v14 quad_perm:[1,0,3,2] row_mask:0xf bank_mask:0xf
	s_nop 1
	v_mov_b32_dpp v31, v30 row_mirror row_mask:0xf bank_mask:0xf
	v_cmp_gt_u32_e64 s[60:61], s16, v34
	v_mul_f32_e32 v34, 0x3e000000, v25
	s_and_b64 vcc, vcc, s[60:61]
	s_waitcnt lgkmcnt(0)
	v_add_f32_e32 v2, v14, v2
	s_nop 1
	v_mov_b32_dpp v14, v2 quad_perm:[2,3,0,1] row_mask:0xf bank_mask:0xf
	s_waitcnt lgkmcnt(0)
	v_max3_f32 v84, v30, v31, s17
	v_fma_f32 v4, v4, s9, -v84
	v_mul_f32_e32 v4, 0x3fb8aa3b, v4
	v_exp_f32_e32 v4, v4
	s_waitcnt lgkmcnt(0)
	v_add_f32_e32 v2, v2, v14
	s_nop 1
	v_mov_b32_dpp v14, v2 row_half_mirror row_mask:0xf bank_mask:0xf
	v_max_f32_e32 v34, v35, v34
	v_cndmask_b32_e64 v4, 0, v4, s[36:37]
	v_cndmask_b32_e32 v34, v35, v34, vcc
	s_nop 1
	v_mov_b32_dpp v35, v34 quad_perm:[1,0,3,2] row_mask:0xf bank_mask:0xf
	s_waitcnt lgkmcnt(0)
	v_add_f32_e32 v2, v2, v14
	s_nop 1
	v_mov_b32_dpp v14, v2 row_mirror row_mask:0xf bank_mask:0xf
	v_sub_f32_e32 v28, 0xf149f2ca, v54
	v_mul_f32_e32 v28, 0x3fb8aa3b, v28
	s_waitcnt lgkmcnt(0)
	v_max_f32_e32 v35, v35, v35
	v_max_f32_e32 v34, v34, v35
	s_waitcnt lgkmcnt(0)
	v_add_f32_e32 v14, v2, v14
	v_sub_f32_e32 v2, 0xf149f2ca, v55
	v_mul_f32_e32 v2, 0x3fb8aa3b, v2
	v_exp_f32_e32 v29, v2
	v_fma_f32 v2, v3, s9, -v55
	v_mul_f32_e32 v2, 0x3fb8aa3b, v2
	v_exp_f32_e32 v2, v2
	s_nop 1
	v_mov_b32_dpp v35, v34 quad_perm:[2,3,0,1] row_mask:0xf bank_mask:0xf
	v_exp_f32_e32 v28, v28
	v_cndmask_b32_e64 v2, 0, v2, s[50:51]
	v_add_f32_e32 v3, 0, v2
	v_cvt_f16_f32_e32 v2, v2
	s_waitcnt lgkmcnt(0)
	v_max_f32_e32 v35, v35, v35
	v_max_f32_e32 v34, v34, v35
	s_nop 1
	v_mov_b32_dpp v35, v34 row_half_mirror row_mask:0xf bank_mask:0xf
	ds_write_b16 v72, v2 offset:27792
	v_fma_f32 v2, v15, s9, -v55
	v_add_f32_e32 v15, 0, v4
	v_cvt_f16_f32_e32 v4, v4
	s_waitcnt lgkmcnt(1)
	v_max_f32_e32 v35, v35, v35
	v_max_f32_e32 v34, v34, v35
	s_nop 1
	v_mov_b32_dpp v35, v34 row_mirror row_mask:0xf bank_mask:0xf
	ds_write_b16 v72, v4 offset:27936
	v_fma_f32 v4, v16, s9, -v84
	v_mul_f32_e32 v4, 0x3fb8aa3b, v4
	v_exp_f32_e32 v4, v4
	s_waitcnt lgkmcnt(1)
	v_max3_f32 v85, v34, v35, s17
	v_mul_f32_e32 v2, 0x3fb8aa3b, v2
	v_exp_f32_e32 v2, v2
	v_cndmask_b32_e64 v4, 0, v4, s[6:7]
	v_add_f32_e32 v15, v4, v15
	v_cvt_f16_f32_e32 v4, v4
	v_cndmask_b32_e64 v2, 0, v2, s[48:49]
	v_add_f32_e32 v3, v2, v3
	v_cvt_f16_f32_e32 v2, v2
	ds_write_b16 v72, v4 offset:27968
	v_fma_f32 v4, v20, s9, -v84
	v_mul_f32_e32 v4, 0x3fb8aa3b, v4
	v_exp_f32_e32 v4, v4
	ds_write_b16 v72, v2 offset:27824
	v_fma_f32 v2, v19, s9, -v55
	v_mul_f32_e32 v2, 0x3fb8aa3b, v2
	v_cndmask_b32_e64 v4, 0, v4, s[2:3]
	v_add_f32_e32 v15, v4, v15
	v_cvt_f16_f32_e32 v4, v4
	v_exp_f32_e32 v2, v2
	v_cmp_lt_u32_e64 s[2:3], v60, v52
	ds_write_b16 v72, v4 offset:28000
	v_fma_f32 v4, v24, s9, -v84
	v_mul_f32_e32 v4, 0x3fb8aa3b, v4
	v_exp_f32_e32 v4, v4
	v_cndmask_b32_e64 v2, 0, v2, s[46:47]
	v_add_f32_e32 v3, v2, v3
	v_cvt_f16_f32_e32 v2, v2
	v_cndmask_b32_e64 v4, 0, v4, s[4:5]
	v_add_f32_e32 v15, v4, v15
	v_cvt_f16_f32_e32 v4, v4
	ds_write_b16 v72, v2 offset:27856
	v_fma_f32 v2, v23, s9, -v55
	v_mul_f32_e32 v2, 0x3fb8aa3b, v2
	ds_write_b16 v72, v4 offset:28032
	s_nop 1
	v_mov_b32_dpp v4, v15 quad_perm:[1,0,3,2] row_mask:0xf bank_mask:0xf
	v_exp_f32_e32 v2, v2
	s_waitcnt lgkmcnt(0)
	v_add_f32_e32 v4, v15, v4
	s_nop 1
	v_mov_b32_dpp v15, v4 quad_perm:[2,3,0,1] row_mask:0xf bank_mask:0xf
	v_cndmask_b32_e64 v2, 0, v2, s[38:39]
	v_add_f32_e32 v3, v2, v3
	v_cvt_f16_f32_e32 v2, v2
	s_waitcnt lgkmcnt(0)
	v_add_f32_e32 v4, v4, v15
	s_nop 1
	v_mov_b32_dpp v15, v4 row_half_mirror row_mask:0xf bank_mask:0xf
	ds_write_b16 v72, v2 offset:27888
	s_nop 1
	v_mov_b32_dpp v2, v3 quad_perm:[1,0,3,2] row_mask:0xf bank_mask:0xf
	s_waitcnt lgkmcnt(1)
	v_add_f32_e32 v75, v4, v15
	v_sub_f32_e32 v4, 0xf149f2ca, v85
	v_mul_f32_e32 v4, 0x3fb8aa3b, v4
	v_exp_f32_e32 v15, v4
	v_fma_f32 v4, v5, s9, -v85
	v_mul_f32_e32 v4, 0x3fb8aa3b, v4
	v_exp_f32_e32 v4, v4
	s_waitcnt lgkmcnt(0)
	v_add_f32_e32 v2, v3, v2
	s_nop 1
	v_mov_b32_dpp v3, v2 quad_perm:[2,3,0,1] row_mask:0xf bank_mask:0xf
	s_nop 1
	v_mov_b32_dpp v76, v75 row_mirror row_mask:0xf bank_mask:0xf
	v_cndmask_b32_e64 v4, 0, v4, s[40:41]
	v_add_f32_e32 v5, 0, v4
	v_cvt_f16_f32_e32 v4, v4
	s_waitcnt lgkmcnt(0)
	v_add_f32_e32 v2, v2, v3
	s_nop 1
	v_mov_b32_dpp v3, v2 row_half_mirror row_mask:0xf bank_mask:0xf
	ds_write_b16 v72, v4 offset:28080
	v_fma_f32 v4, v17, s9, -v85
	v_mul_f32_e32 v4, 0x3fb8aa3b, v4
	v_exp_f32_e32 v4, v4
	s_waitcnt lgkmcnt(1)
	v_add_f32_e32 v70, v2, v3
	v_pk_mul_f32 v[2:3], v[28:29], 0 op_sel_hi:[1,0]
	s_nop 1
	v_mov_b32_dpp v71, v70 row_mirror row_mask:0xf bank_mask:0xf
	v_cndmask_b32_e64 v4, 0, v4, s[42:43]
	v_add_f32_e32 v5, v4, v5
	v_cvt_f16_f32_e32 v4, v4
	v_add_f32_e32 v83, v2, v14
	v_sub_f32_e32 v14, 0xf149f2ca, v84
	v_mul_f32_e32 v14, 0x3fb8aa3b, v14
	ds_write_b16 v72, v4 offset:28112
	v_fma_f32 v4, v21, s9, -v85
	v_mul_f32_e32 v4, 0x3fb8aa3b, v4
	v_exp_f32_e32 v4, v4
	v_exp_f32_e32 v14, v14
	v_cndmask_b32_e64 v4, 0, v4, s[44:45]
	v_add_f32_e32 v5, v4, v5
	v_cvt_f16_f32_e32 v4, v4
	ds_write_b16 v72, v4 offset:28144
	v_fma_f32 v4, v25, s9, -v85
	v_mul_f32_e32 v4, 0x3fb8aa3b, v4
	v_exp_f32_e32 v4, v4
	s_nop 0
	v_cndmask_b32_e32 v4, 0, v4, vcc
	v_add_f32_e32 v5, v4, v5
	v_cvt_f16_f32_e32 v4, v4
	ds_write_b16 v72, v4 offset:28176
	global_load_dwordx4 v[30:33], v[26:27], off
	global_load_dwordx4 v[34:37], v[26:27], off offset:16
	s_nop 1
	v_mov_b32_dpp v4, v5 quad_perm:[1,0,3,2] row_mask:0xf bank_mask:0xf
	s_waitcnt lgkmcnt(0)
	s_barrier
; template <int NKB>
; DI void attn_unit(const Params& p, int l, int mode, int grp, int head, int r0, int dil, int i0, int sub_len, int W, h16* lds) {
;     ...
;   for (int kb = 0; kb < NKB; ++kb) {
;     const int j0 = i0 - W + 64 * kb;
;     const bool inr = (j0 >= 0) && (j0 < sub_len);
;     __syncthreads();
;     img_store_nat(Ki, lrow, seg, pk0, pk1);
;     img_store_T(Vt, lrow, seg, pv0, pv1);
;     __syncthreads();
;     if (kb + 1 < NKB) ATT_PREFETCH(kb + 1);
;     f4v S[4];
; #pragma unroll
;     for (int i = 0; i < 4; ++i) S[i] = (f4v){0.f, 0.f, 0.f, 0.f};
;     mm64(Qi, Ki, S, w, lane);
;     float mx[4], al[4], rsum[4];
;     bool vm[4][4];
; #pragma unroll
;     for (int rg = 0; rg < 4; ++rg) {
;       const int row = 16 * w + 4 * q + rg;
;       float m_ = -1e30f;
; #pragma unroll
;       for (int nt = 0; nt < 4; ++nt) {
;         const int key = 16 * nt + r;
;         const int delta = row - key + W - 64 * kb;
;         const bool ok = inr && (delta >= -W) && (delta <= W);
;         vm[nt][rg] = ok;
;         float s = S[nt][rg] * 0.125f;
;         S[nt][rg] = s;
;         if (ok) m_ = fmaxf(m_, s);
;       }
;     ...
; #pragma unroll
;     for (int et = 0; et < 4; ++et)
; #pragma unroll
;       for (int rg = 0; rg < 4; ++rg) O[et][rg] *= al[rg];
;     __syncthreads();
;     mm64(Pi, Vt, O, w, lane);
;   }
	v_add_f32_e32 v4, v5, v4
	s_nop 1
	v_mov_b32_dpp v5, v4 quad_perm:[2,3,0,1] row_mask:0xf bank_mask:0xf
	s_waitcnt lgkmcnt(0)
	v_add_f32_e32 v4, v4, v5
	s_nop 1
	v_mov_b32_dpp v5, v4 row_half_mirror row_mask:0xf bank_mask:0xf
	s_waitcnt lgkmcnt(0)
	v_add_f32_e32 v73, v4, v5
	v_pk_mul_f32 v[4:5], v[14:15], 0 op_sel_hi:[1,0]
	ds_read_b128 v[14:17], v64 offset:27648
	ds_read_b128 v[18:21], v63 offset:18432
	ds_read_b128 v[22:25], v63 offset:20736
	ds_read_b128 v[26:29], v63 offset:23040
	ds_read_b128 v[86:89], v63 offset:25344
	s_waitcnt lgkmcnt(3)
	v_mfma_f32_16x16x32_f16 v[18:21], v[14:17], v[18:21], v[2:5]
	s_nop 1
	v_mov_b32_dpp v74, v73 row_mirror row_mask:0xf bank_mask:0xf
	s_waitcnt lgkmcnt(2)
	v_mfma_f32_16x16x32_f16 v[22:25], v[14:17], v[22:25], v[2:5]
	s_waitcnt lgkmcnt(1)
	v_mfma_f32_16x16x32_f16 v[26:29], v[14:17], v[26:29], v[2:5]
	s_waitcnt lgkmcnt(0)
	v_mfma_f32_16x16x32_f16 v[86:89], v[14:17], v[86:89], v[2:5]
	ds_read_b128 v[90:93], v64 offset:27712
	ds_read_b128 v[14:17], v63 offset:18496
	s_nop 0
	v_add_u32_e32 v2, 64, v60
	s_waitcnt lgkmcnt(0)
	v_mfma_f32_16x16x32_f16 v[14:17], v[90:93], v[14:17], v[18:21]
	v_cmp_lt_u32_e32 vcc, v2, v52
	s_nop 1
	ds_read_b128 v[18:21], v63 offset:20800
	s_waitcnt lgkmcnt(0)
	v_mfma_f32_16x16x32_f16 v[18:21], v[90:93], v[18:21], v[22:25]
	s_nop 2
	ds_read_b128 v[22:25], v63 offset:23104
	v_cndmask_b32_e32 v2, v60, v2, vcc
	s_waitcnt lgkmcnt(0)
	v_mfma_f32_16x16x32_f16 v[22:25], v[90:93], v[22:25], v[26:29]
	s_nop 2
	ds_read_b128 v[26:29], v63 offset:25408
	s_waitcnt lgkmcnt(0)
	s_barrier
	s_waitcnt vmcnt(2)
	ds_write_b128 v77, v[10:13] offset:9216
	ds_write_b128 v77, v[6:9] offset:9232
	s_waitcnt vmcnt(1)
	ds_write_b16 v78, v30 offset:18432
	s_waitcnt vmcnt(0)
	ds_write_b16 v79, v34 offset:19584
	ds_write_b16_d16_hi v78, v30 offset:18576
	ds_write_b16_d16_hi v78, v34 offset:19728
	ds_write_b16 v78, v31 offset:18720
	ds_write_b16 v78, v35 offset:19872
	ds_write_b16_d16_hi v78, v31 offset:18864
	ds_write_b16_d16_hi v78, v35 offset:20016
	ds_write_b16 v78, v32 offset:19008
	ds_write_b16 v78, v36 offset:20160
	ds_write_b16_d16_hi v78, v32 offset:19152
	ds_write_b16_d16_hi v78, v36 offset:20304
	ds_write_b16 v78, v33 offset:19296
	ds_write_b16 v78, v37 offset:20448
	ds_write_b16_d16_hi v78, v33 offset:19440
	ds_write_b16_d16_hi v78, v37 offset:20592
	v_add_u32_e32 v6, v53, v2
	v_ashrrev_i32_e32 v7, 31, v6
	v_lshlrev_b64 v[6:7], v58, v[6:7]
	v_lshl_add_u64 v[6:7], v[6:7], 0, v[46:47]
	v_mad_u64_u32 v[8:9], s[4:5], v6, s8, v[38:39]
	v_mad_i32_i24 v9, v7, s8, v9
	v_lshl_add_u64 v[6:7], v[8:9], 0, v[42:43]
	v_lshl_add_u64 v[10:11], v[6:7], 0, v[40:41]
	v_lshl_add_u64 v[6:7], v[8:9], 0, v[44:45]
	v_mfma_f32_16x16x32_f16 v[26:29], v[90:93], v[26:29], v[86:89]
	s_waitcnt lgkmcnt(0)
	s_barrier
	v_lshl_add_u64 v[56:57], v[6:7], 0, v[40:41]
	global_load_dwordx4 v[6:9], v[10:11], off offset:3600
	s_nop 0
	global_load_dwordx4 v[10:13], v[10:11], off offset:3584
	ds_read_b128 v[30:33], v64
	ds_read_b128 v[34:37], v63 offset:9216
	ds_read_b128 v[38:41], v63 offset:11520
	ds_read_b128 v[42:45], v63 offset:13824
	ds_read_b128 v[86:89], v63 offset:16128
	s_waitcnt lgkmcnt(3)
	v_mfma_f32_16x16x32_f16 v[34:37], v[30:33], v[34:37], 0
	v_add_u32_e32 v2, 64, v69
	v_sub_u32_e32 v47, v2, v59
	v_cmp_gt_u32_e64 s[4:5], s16, v47
	s_waitcnt lgkmcnt(2)
	v_mfma_f32_16x16x32_f16 v[38:41], v[30:33], v[38:41], 0
	s_and_b64 s[60:61], s[2:3], s[4:5]
	v_add_u32_e32 v52, v2, v80
	v_cmp_gt_u32_e64 s[4:5], s16, v52
	s_waitcnt lgkmcnt(1)
	v_mfma_f32_16x16x32_f16 v[42:45], v[30:33], v[42:45], 0
	s_and_b64 s[58:59], s[2:3], s[4:5]
	s_waitcnt lgkmcnt(0)
	v_mfma_f32_16x16x32_f16 v[86:89], v[30:33], v[86:89], 0
	ds_read_b128 v[90:93], v64 offset:64
	ds_read_b128 v[30:33], v63 offset:9280
	s_waitcnt lgkmcnt(0)
	v_mfma_f32_16x16x32_f16 v[30:33], v[90:93], v[30:33], v[34:37]
	s_nop 2
	ds_read_b128 v[34:37], v63 offset:11584
	s_waitcnt lgkmcnt(0)
	v_mfma_f32_16x16x32_f16 v[34:37], v[90:93], v[34:37], v[38:41]
	s_nop 2
	ds_read_b128 v[38:41], v63 offset:13888
	v_mul_f32_e32 v47, 0x3e000000, v30
	v_max_f32_e32 v47, 0xf149f2ca, v47
	s_waitcnt lgkmcnt(0)
	v_mfma_f32_16x16x32_f16 v[38:41], v[90:93], v[38:41], v[42:45]
	v_cndmask_b32_e64 v47, v199, v47, s[60:61]
	v_mul_f32_e32 v52, 0x3e000000, v34
	v_max_f32_e32 v52, v47, v52
	v_cndmask_b32_e64 v47, v47, v52, s[58:59]
	v_add_u32_e32 v52, v2, v81
	ds_read_b128 v[42:45], v63 offset:16192
	v_cmp_gt_u32_e64 s[4:5], s16, v52
	s_nop 0
	v_mul_f32_e32 v52, 0x3e000000, v38
	s_and_b64 s[56:57], s[2:3], s[4:5]
	v_max_f32_e32 v52, v47, v52
	v_cndmask_b32_e64 v47, v47, v52, s[56:57]
	v_add_u32_e32 v2, v2, v82
	v_add_u32_e32 v52, 0x41, v69
	v_cmp_gt_u32_e64 s[4:5], s16, v2
	v_sub_u32_e32 v53, v52, v59
	s_and_b64 s[54:55], s[2:3], s[4:5]
	v_cmp_gt_u32_e64 s[4:5], s16, v53
	v_mul_f32_e32 v53, 0x3e000000, v31
	s_waitcnt lgkmcnt(0)
	v_mfma_f32_16x16x32_f16 v[42:45], v[90:93], v[42:45], v[86:89]
	s_and_b64 s[46:47], s[2:3], s[4:5]
	v_max_f32_e32 v53, 0xf149f2ca, v53
	v_cndmask_b32_e64 v53, v199, v53, s[46:47]
	v_add_u32_e32 v86, v52, v80
	v_cmp_gt_u32_e64 s[4:5], s16, v86
	v_mul_f32_e32 v86, 0x3e000000, v35
	s_and_b64 s[42:43], s[2:3], s[4:5]
	v_max_f32_e32 v86, v53, v86
	v_cndmask_b32_e64 v53, v53, v86, s[42:43]
	v_add_u32_e32 v86, v52, v81
	v_cmp_gt_u32_e64 s[4:5], s16, v86
	v_mul_f32_e32 v86, 0x3e000000, v39
	s_and_b64 s[44:45], s[2:3], s[4:5]
	v_max_f32_e32 v86, v53, v86
	v_add_u32_e32 v52, v52, v82
	v_cndmask_b32_e64 v53, v53, v86, s[44:45]
	v_cmp_gt_u32_e64 s[4:5], s16, v52
	v_mul_f32_e32 v52, 0x3e000000, v43
	s_and_b64 s[6:7], s[2:3], s[4:5]
	v_max_f32_e32 v52, v53, v52
	v_cndmask_b32_e64 v52, v53, v52, s[6:7]
	s_nop 1
	v_mov_b32_dpp v53, v52 quad_perm:[1,0,3,2] row_mask:0xf bank_mask:0xf
	v_mul_f32_e32 v2, 0x3e000000, v42
	v_max_f32_e32 v2, v47, v2
	v_cndmask_b32_e64 v2, v47, v2, s[54:55]
	s_nop 1
	v_mov_b32_dpp v47, v2 quad_perm:[1,0,3,2] row_mask:0xf bank_mask:0xf
	s_waitcnt lgkmcnt(0)
; DI float grp16_sum(float v) { v += __shfl_xor(v, 1); v += __shfl_xor(v, 2); v += __shfl_xor(v, 4); v += __shfl_xor(v, 8); return v; }
; DI float grp16_max(float v) { v = fmaxf(v, __shfl_xor(v, 1)); v = fmaxf(v, __shfl_xor(v, 2)); v = fmaxf(v, __shfl_xor(v, 4)); v = fmaxf(v, __shfl_xor(v, 8)); return v; }
; template <int NKB>
; DI void attn_unit(const Params& p, int l, int mode, int grp, int head, int r0, int dil, int i0, int sub_len, int W, h16* lds) {
;     ...
;     for (int rg = 0; rg < 4; ++rg) {
;       const int row = 16 * w + 4 * q + rg;
;       float m_ = -1e30f;
; #pragma unroll
;       for (int nt = 0; nt < 4; ++nt) {
;         const int key = 16 * nt + r;
;         const int delta = row - key + W - 64 * kb;
;         const bool ok = inr && (delta >= -W) && (delta <= W);
;         vm[nt][rg] = ok;
;         float s = S[nt][rg] * 0.125f;
;         S[nt][rg] = s;
;         if (ok) m_ = fmaxf(m_, s);
;       }
;       mx[rg] = grp16_max(m_);
;     }
; #pragma unroll
;     for (int rg = 0; rg < 4; ++rg) {
;       const float mn = fmaxf(mrow[rg], mx[rg]);
;       al[rg] = __expf(mrow[rg] - mn);
;       mrow[rg] = mn;
;       float rs_ = 0.f;
; #pragma unroll
;       for (int nt = 0; nt < 4; ++nt) {
;         float pv = vm[nt][rg] ? __expf(S[nt][rg] - mn) : 0.f;
;         rs_ += pv;
;         Pi[(16 * w + 4 * q + rg) * LDH + 16 * nt + r] = (h16)pv;
;       }
;       rsum[rg] = grp16_sum(rs_);
;       lsum[rg] = lsum[rg] * al[rg] + rsum[rg];
	v_max_f32_e32 v53, v53, v53
	v_max_f32_e32 v52, v52, v53
	s_nop 1
	v_mov_b32_dpp v53, v52 quad_perm:[2,3,0,1] row_mask:0xf bank_mask:0xf
	s_waitcnt lgkmcnt(0)
	v_max_f32_e32 v47, v47, v47
	v_max_f32_e32 v2, v2, v47
	s_nop 1
	v_mov_b32_dpp v47, v2 quad_perm:[2,3,0,1] row_mask:0xf bank_mask:0xf
	s_waitcnt lgkmcnt(0)
	v_max_f32_e32 v53, v53, v53
	v_max_f32_e32 v52, v52, v53
	s_nop 1
	v_mov_b32_dpp v53, v52 row_half_mirror row_mask:0xf bank_mask:0xf
	s_waitcnt lgkmcnt(0)
	v_max_f32_e32 v47, v47, v47
	v_max_f32_e32 v2, v2, v47
	s_nop 1
	v_mov_b32_dpp v47, v2 row_half_mirror row_mask:0xf bank_mask:0xf
	s_waitcnt lgkmcnt(0)
	v_max_f32_e32 v53, v53, v53
	v_max_f32_e32 v53, v52, v53
	v_add_u32_e32 v52, 0x42, v69
	v_sub_u32_e32 v87, v52, v59
	v_cmp_gt_u32_e64 s[4:5], s16, v87
	v_mul_f32_e32 v87, 0x3e000000, v32
	s_and_b64 s[40:41], s[2:3], s[4:5]
	v_max_f32_e32 v87, 0xf149f2ca, v87
	v_add_u32_e32 v88, v52, v80
	v_cndmask_b32_e64 v87, v199, v87, s[40:41]
	v_cmp_gt_u32_e64 s[4:5], s16, v88
	v_mul_f32_e32 v88, 0x3e000000, v36
	s_and_b64 s[4:5], s[2:3], s[4:5]
	v_max_f32_e32 v88, v87, v88
	v_cndmask_b32_e64 v87, v87, v88, s[4:5]
	v_add_u32_e32 v88, v52, v81
	v_cmp_gt_u32_e64 s[36:37], s16, v88
	v_mul_f32_e32 v88, 0x3e000000, v40
	s_and_b64 s[36:37], s[2:3], s[36:37]
	v_max_f32_e32 v88, v87, v88
	v_add_u32_e32 v52, v52, v82
	v_cndmask_b32_e64 v87, v87, v88, s[36:37]
	v_cmp_gt_u32_e64 s[38:39], s16, v52
	v_mul_f32_e32 v52, 0x3e000000, v44
	s_and_b64 s[38:39], s[2:3], s[38:39]
	v_max_f32_e32 v52, v87, v52
	v_cndmask_b32_e64 v52, v87, v52, s[38:39]
	s_nop 1
	v_mov_b32_dpp v87, v52 quad_perm:[1,0,3,2] row_mask:0xf bank_mask:0xf
	s_waitcnt lgkmcnt(0)
	v_max_f32_e32 v47, v47, v47
	v_max_f32_e32 v2, v2, v47
	s_nop 1
	v_mov_b32_dpp v47, v2 row_mirror row_mask:0xf bank_mask:0xf
	s_nop 1
	v_mov_b32_dpp v86, v53 row_mirror row_mask:0xf bank_mask:0xf
	s_waitcnt lgkmcnt(0)
	v_max_f32_e32 v87, v87, v87
	v_max_f32_e32 v52, v52, v87
	s_nop 1
	v_mov_b32_dpp v87, v52 quad_perm:[2,3,0,1] row_mask:0xf bank_mask:0xf
	s_waitcnt lgkmcnt(0)
	v_max3_f32 v91, v55, v53, v86
	s_waitcnt lgkmcnt(0)
	v_max_f32_e32 v87, v87, v87
	v_max_f32_e32 v52, v52, v87
	s_nop 1
	v_mov_b32_dpp v87, v52 row_half_mirror row_mask:0xf bank_mask:0xf
	s_waitcnt lgkmcnt(0)
	v_max_f32_e32 v87, v87, v87
	v_max_f32_e32 v87, v52, v87
	v_add_u32_e32 v52, 0x43, v69
	v_sub_u32_e32 v89, v52, v59
	v_cmp_gt_u32_e64 s[48:49], s16, v89
	v_mul_f32_e32 v89, 0x3e000000, v33
	s_and_b64 s[48:49], s[2:3], s[48:49]
	v_max_f32_e32 v89, 0xf149f2ca, v89
	v_add_u32_e32 v90, v52, v80
	v_cndmask_b32_e64 v89, v199, v89, s[48:49]
	v_cmp_gt_u32_e64 s[50:51], s16, v90
	v_mul_f32_e32 v90, 0x3e000000, v37
	s_and_b64 s[50:51], s[2:3], s[50:51]
	v_max_f32_e32 v90, v89, v90
	v_cndmask_b32_e64 v89, v89, v90, s[50:51]
	v_add_u32_e32 v90, v52, v81
	v_cmp_gt_u32_e64 s[52:53], s16, v90
	v_mul_f32_e32 v90, 0x3e000000, v41
	s_and_b64 s[52:53], s[2:3], s[52:53]
	v_max_f32_e32 v90, v89, v90
	v_add_u32_e32 v52, v52, v82
	v_cndmask_b32_e64 v89, v89, v90, s[52:53]
	v_cmp_gt_u32_e64 s[62:63], s16, v52
	v_mul_f32_e32 v52, 0x3e000000, v45
	s_and_b64 s[2:3], s[2:3], s[62:63]
	v_max_f32_e32 v52, v89, v52
	v_cndmask_b32_e64 v52, v89, v52, s[2:3]
	s_nop 1
	v_mov_b32_dpp v89, v52 quad_perm:[1,0,3,2] row_mask:0xf bank_mask:0xf
	v_max3_f32 v90, v54, v2, v47
	v_sub_f32_e32 v2, v54, v90
	v_mul_f32_e32 v2, 0x3fb8aa3b, v2
	s_nop 1
	v_mov_b32_dpp v88, v87 row_mirror row_mask:0xf bank_mask:0xf
	s_waitcnt lgkmcnt(0)
	v_max_f32_e32 v89, v89, v89
	v_max_f32_e32 v52, v52, v89
	s_nop 1
	v_mov_b32_dpp v89, v52 quad_perm:[2,3,0,1] row_mask:0xf bank_mask:0xf
	s_waitcnt lgkmcnt(0)
	v_max_f32_e32 v89, v89, v89
	v_max_f32_e32 v52, v52, v89
	s_nop 1
	v_mov_b32_dpp v89, v52 row_half_mirror row_mask:0xf bank_mask:0xf
	s_waitcnt lgkmcnt(0)
	v_max_f32_e32 v89, v89, v89
	v_max_f32_e32 v92, v52, v89
	v_exp_f32_e32 v52, v2
	v_fma_f32 v2, v30, s9, -v90
	v_mul_f32_e32 v2, 0x3fb8aa3b, v2
	v_exp_f32_e32 v2, v2
	v_max3_f32 v89, v84, v87, v88
	s_nop 1
	v_mov_b32_dpp v93, v92 row_mirror row_mask:0xf bank_mask:0xf
	v_cndmask_b32_e64 v2, 0, v2, s[60:61]
	v_add_f32_e32 v30, 0, v2
	v_cvt_f16_f32_e32 v2, v2
	s_waitcnt lgkmcnt(0)
	v_max3_f32 v88, v85, v92, v93
	ds_write_b16 v72, v2 offset:27648
	v_fma_f32 v2, v34, s9, -v90
	v_mul_f32_e32 v2, 0x3fb8aa3b, v2
	v_exp_f32_e32 v2, v2
	s_nop 0
	v_cndmask_b32_e64 v2, 0, v2, s[58:59]
	v_add_f32_e32 v30, v2, v30
	v_cvt_f16_f32_e32 v2, v2
	ds_write_b16 v72, v2 offset:27680
	v_fma_f32 v2, v38, s9, -v90
	v_mul_f32_e32 v2, 0x3fb8aa3b, v2
	v_exp_f32_e32 v2, v2
	s_nop 0
	v_cndmask_b32_e64 v2, 0, v2, s[56:57]
	v_add_f32_e32 v30, v2, v30
	v_cvt_f16_f32_e32 v2, v2
	ds_write_b16 v72, v2 offset:27712
	v_fma_f32 v2, v42, s9, -v90
	v_mul_f32_e32 v2, 0x3fb8aa3b, v2
	v_exp_f32_e32 v2, v2
	s_nop 0
	v_cndmask_b32_e64 v2, 0, v2, s[54:55]
	v_add_f32_e32 v30, v2, v30
	v_cvt_f16_f32_e32 v2, v2
	ds_write_b16 v72, v2 offset:27744
	s_nop 1
	v_mov_b32_dpp v2, v30 quad_perm:[1,0,3,2] row_mask:0xf bank_mask:0xf
	s_waitcnt lgkmcnt(0)
	v_add_f32_e32 v2, v30, v2
	s_nop 1
	v_mov_b32_dpp v30, v2 quad_perm:[2,3,0,1] row_mask:0xf bank_mask:0xf
	s_waitcnt lgkmcnt(0)
	v_add_f32_e32 v2, v2, v30
	s_nop 1
	v_mov_b32_dpp v30, v2 row_half_mirror row_mask:0xf bank_mask:0xf
	s_waitcnt lgkmcnt(0)
	v_add_f32_e32 v2, v2, v30
	s_nop 1
	v_mov_b32_dpp v30, v2 row_mirror row_mask:0xf bank_mask:0xf
	s_waitcnt lgkmcnt(0)
; DI float grp16_sum(float v) { v += __shfl_xor(v, 1); v += __shfl_xor(v, 2); v += __shfl_xor(v, 4); v += __shfl_xor(v, 8); return v; }
; template <int NKB>
; DI void attn_unit(const Params& p, int l, int mode, int grp, int head, int r0, int dil, int i0, int sub_len, int W, h16* lds) {
;     ...
;     for (int rg = 0; rg < 4; ++rg) {
;       const float mn = fmaxf(mrow[rg], mx[rg]);
;       al[rg] = __expf(mrow[rg] - mn);
;       mrow[rg] = mn;
;       float rs_ = 0.f;
; #pragma unroll
;       for (int nt = 0; nt < 4; ++nt) {
;         float pv = vm[nt][rg] ? __expf(S[nt][rg] - mn) : 0.f;
;         rs_ += pv;
;         Pi[(16 * w + 4 * q + rg) * LDH + 16 * nt + r] = (h16)pv;
;       }
;       rsum[rg] = grp16_sum(rs_);
;       lsum[rg] = lsum[rg] * al[rg] + rsum[rg];
;     }
; #pragma unroll
;     for (int et = 0; et < 4; ++et)
; #pragma unroll
;       for (int rg = 0; rg < 4; ++rg) O[et][rg] *= al[rg];
;     __syncthreads();
;     mm64(Pi, Vt, O, w, lane);
;   }
	v_add_f32_e32 v2, v2, v30
	v_sub_f32_e32 v30, v55, v91
	v_mul_f32_e32 v30, 0x3fb8aa3b, v30
	v_exp_f32_e32 v53, v30
	v_fma_f32 v30, v31, s9, -v91
	v_mul_f32_e32 v30, 0x3fb8aa3b, v30
	v_exp_f32_e32 v30, v30
	v_fmac_f32_e32 v2, v83, v52
	v_cndmask_b32_e64 v30, 0, v30, s[46:47]
	v_add_f32_e32 v31, 0, v30
	v_cvt_f16_f32_e32 v30, v30
	ds_write_b16 v72, v30 offset:27792
	v_fma_f32 v30, v35, s9, -v91
	v_mul_f32_e32 v30, 0x3fb8aa3b, v30
	v_exp_f32_e32 v30, v30
	v_pk_mul_f32 v[34:35], v[14:15], v[52:53]
	v_pk_mul_f32 v[14:15], v[26:27], v[52:53]
	v_cndmask_b32_e64 v30, 0, v30, s[42:43]
	v_add_f32_e32 v31, v30, v31
	v_cvt_f16_f32_e32 v30, v30
	ds_write_b16 v72, v30 offset:27824
	v_fma_f32 v30, v39, s9, -v91
	v_mul_f32_e32 v30, 0x3fb8aa3b, v30
	v_exp_f32_e32 v30, v30
	s_nop 0
	v_cndmask_b32_e64 v30, 0, v30, s[44:45]
	v_add_f32_e32 v31, v30, v31
	v_cvt_f16_f32_e32 v30, v30
	ds_write_b16 v72, v30 offset:27856
	v_fma_f32 v30, v43, s9, -v91
	v_mul_f32_e32 v30, 0x3fb8aa3b, v30
	v_exp_f32_e32 v30, v30
	s_nop 0
	v_cndmask_b32_e64 v30, 0, v30, s[6:7]
	v_add_f32_e32 v31, v30, v31
	v_cvt_f16_f32_e32 v30, v30
	ds_write_b16 v72, v30 offset:27888
	s_nop 1
	v_mov_b32_dpp v30, v31 quad_perm:[1,0,3,2] row_mask:0xf bank_mask:0xf
	s_waitcnt lgkmcnt(0)
	v_add_f32_e32 v30, v31, v30
	s_nop 1
	v_mov_b32_dpp v31, v30 quad_perm:[2,3,0,1] row_mask:0xf bank_mask:0xf
	s_waitcnt lgkmcnt(0)
	v_add_f32_e32 v30, v30, v31
	s_nop 1
	v_mov_b32_dpp v31, v30 row_half_mirror row_mask:0xf bank_mask:0xf
	s_waitcnt lgkmcnt(0)
	v_add_f32_e32 v47, v30, v31
	v_sub_f32_e32 v30, v84, v89
	v_mul_f32_e32 v30, 0x3fb8aa3b, v30
	v_exp_f32_e32 v54, v30
	v_fma_f32 v30, v32, s9, -v89
	v_mul_f32_e32 v30, 0x3fb8aa3b, v30
	v_exp_f32_e32 v30, v30
	s_nop 1
	v_mov_b32_dpp v83, v47 row_mirror row_mask:0xf bank_mask:0xf
	v_cndmask_b32_e64 v30, 0, v30, s[40:41]
	v_add_f32_e32 v31, 0, v30
	v_cvt_f16_f32_e32 v30, v30
	ds_write_b16 v72, v30 offset:27936
	v_fma_f32 v30, v36, s9, -v89
	v_mul_f32_e32 v30, 0x3fb8aa3b, v30
	v_exp_f32_e32 v30, v30
	s_nop 0
	v_cndmask_b32_e64 v30, 0, v30, s[4:5]
	v_add_f32_e32 v31, v30, v31
	v_cvt_f16_f32_e32 v30, v30
	ds_write_b16 v72, v30 offset:27968
	v_fma_f32 v30, v40, s9, -v89
	v_mul_f32_e32 v30, 0x3fb8aa3b, v30
	v_exp_f32_e32 v30, v30
	s_nop 0
	v_cndmask_b32_e64 v30, 0, v30, s[36:37]
	v_add_f32_e32 v31, v30, v31
	v_cvt_f16_f32_e32 v30, v30
	ds_write_b16 v72, v30 offset:28000
	v_fma_f32 v30, v44, s9, -v89
	v_mul_f32_e32 v30, 0x3fb8aa3b, v30
	v_exp_f32_e32 v30, v30
	s_nop 0
	v_cndmask_b32_e64 v30, 0, v30, s[38:39]
	v_add_f32_e32 v31, v30, v31
	v_cvt_f16_f32_e32 v30, v30
	ds_write_b16 v72, v30 offset:28032
	s_nop 1
	v_mov_b32_dpp v30, v31 quad_perm:[1,0,3,2] row_mask:0xf bank_mask:0xf
	s_waitcnt lgkmcnt(0)
	v_add_f32_e32 v30, v31, v30
	s_nop 1
	v_mov_b32_dpp v31, v30 quad_perm:[2,3,0,1] row_mask:0xf bank_mask:0xf
	s_waitcnt lgkmcnt(0)
	v_add_f32_e32 v30, v30, v31
	s_nop 1
	v_mov_b32_dpp v31, v30 row_half_mirror row_mask:0xf bank_mask:0xf
	s_waitcnt lgkmcnt(0)
	v_add_f32_e32 v86, v30, v31
	v_sub_f32_e32 v30, v85, v88
	v_mul_f32_e32 v30, 0x3fb8aa3b, v30
	v_exp_f32_e32 v55, v30
	v_fma_f32 v30, v33, s9, -v88
	v_mul_f32_e32 v30, 0x3fb8aa3b, v30
	v_exp_f32_e32 v30, v30
	v_pk_mul_f32 v[32:33], v[20:21], v[54:55]
	v_pk_mul_f32 v[20:21], v[24:25], v[54:55]
	s_nop 1
	v_mov_b32_dpp v87, v86 row_mirror row_mask:0xf bank_mask:0xf
	v_cndmask_b32_e64 v30, 0, v30, s[48:49]
	v_add_f32_e32 v31, 0, v30
	v_cvt_f16_f32_e32 v30, v30
	ds_write_b16 v72, v30 offset:28080
	v_fma_f32 v30, v37, s9, -v88
	v_mul_f32_e32 v30, 0x3fb8aa3b, v30
	v_exp_f32_e32 v30, v30
	v_pk_mul_f32 v[36:37], v[16:17], v[54:55]
	v_pk_mul_f32 v[16:17], v[28:29], v[54:55]
	v_cndmask_b32_e64 v30, 0, v30, s[50:51]
	v_add_f32_e32 v31, v30, v31
	v_cvt_f16_f32_e32 v30, v30
	ds_write_b16 v72, v30 offset:28112
	v_fma_f32 v30, v41, s9, -v88
	v_mul_f32_e32 v30, 0x3fb8aa3b, v30
	v_exp_f32_e32 v30, v30
	s_nop 0
	v_cndmask_b32_e64 v30, 0, v30, s[52:53]
	v_add_f32_e32 v31, v30, v31
	v_cvt_f16_f32_e32 v30, v30
	ds_write_b16 v72, v30 offset:28144
	v_fma_f32 v30, v45, s9, -v88
	v_mul_f32_e32 v30, 0x3fb8aa3b, v30
	v_exp_f32_e32 v30, v30
	s_nop 0
	v_cndmask_b32_e64 v30, 0, v30, s[2:3]
	v_add_f32_e32 v31, v30, v31
	v_cvt_f16_f32_e32 v30, v30
	ds_write_b16 v72, v30 offset:28176
	global_load_dwordx4 v[38:41], v[56:57], off
	global_load_dwordx4 v[42:45], v[56:57], off offset:16
	s_nop 1
	v_mov_b32_dpp v30, v31 quad_perm:[1,0,3,2] row_mask:0xf bank_mask:0xf
	s_waitcnt lgkmcnt(0)
	s_barrier
	v_add_f32_e32 v30, v31, v30
	s_nop 1
	v_mov_b32_dpp v31, v30 quad_perm:[2,3,0,1] row_mask:0xf bank_mask:0xf
	s_waitcnt lgkmcnt(0)
	v_add_f32_e32 v30, v30, v31
	s_nop 1
	v_mov_b32_dpp v31, v30 row_half_mirror row_mask:0xf bank_mask:0xf
	s_waitcnt lgkmcnt(0)
	v_add_f32_e32 v84, v30, v31
	v_pk_mul_f32 v[30:31], v[18:19], v[52:53]
	v_pk_mul_f32 v[18:19], v[22:23], v[52:53]
	ds_read_b128 v[22:25], v64 offset:27648
	ds_read_b128 v[26:29], v63 offset:18432
	s_waitcnt lgkmcnt(0)
	v_mfma_f32_16x16x32_f16 v[26:29], v[22:25], v[26:29], v[34:37]
	s_nop 2
	ds_read_b128 v[34:37], v63 offset:20736
	s_nop 1
	v_mov_b32_dpp v85, v84 row_mirror row_mask:0xf bank_mask:0xf
	s_waitcnt lgkmcnt(0)
	v_mfma_f32_16x16x32_f16 v[30:33], v[22:25], v[34:37], v[30:33]
	ds_read_b128 v[34:37], v63 offset:23040
	s_waitcnt lgkmcnt(0)
	v_mfma_f32_16x16x32_f16 v[34:37], v[22:25], v[34:37], v[18:21]
	s_nop 2
	ds_read_b128 v[18:21], v63 offset:25344
	s_waitcnt lgkmcnt(0)
	v_mfma_f32_16x16x32_f16 v[92:95], v[22:25], v[18:21], v[14:17]
	ds_read_b128 v[96:99], v64 offset:27712
	s_nop 1
	ds_read_b128 v[14:17], v63 offset:18496
	ds_read_b128 v[18:21], v63 offset:20800
	ds_read_b128 v[22:25], v63 offset:23104
	s_waitcnt lgkmcnt(2)
	v_mfma_f32_16x16x32_f16 v[14:17], v[96:99], v[14:17], v[26:29]
	s_nop 2
	ds_read_b128 v[26:29], v63 offset:25408
	s_waitcnt lgkmcnt(0)
	v_mfma_f32_16x16x32_f16 v[18:21], v[96:99], v[18:21], v[30:33]
	s_barrier
; DI float grp16_max(float v) { v = fmaxf(v, __shfl_xor(v, 1)); v = fmaxf(v, __shfl_xor(v, 2)); v = fmaxf(v, __shfl_xor(v, 4)); v = fmaxf(v, __shfl_xor(v, 8)); return v; }
; template <int NKB>
; DI void attn_unit(const Params& p, int l, int mode, int grp, int head, int r0, int dil, int i0, int sub_len, int W, h16* lds) {
;     ...
;   for (int kb = 0; kb < NKB; ++kb) {
;     const int j0 = i0 - W + 64 * kb;
;     const bool inr = (j0 >= 0) && (j0 < sub_len);
;     __syncthreads();
;     img_store_nat(Ki, lrow, seg, pk0, pk1);
;     img_store_T(Vt, lrow, seg, pv0, pv1);
;     __syncthreads();
;     if (kb + 1 < NKB) ATT_PREFETCH(kb + 1);
;     f4v S[4];
; #pragma unroll
;     for (int i = 0; i < 4; ++i) S[i] = (f4v){0.f, 0.f, 0.f, 0.f};
;     mm64(Qi, Ki, S, w, lane);
;     float mx[4], al[4], rsum[4];
;     bool vm[4][4];
; #pragma unroll
;     for (int rg = 0; rg < 4; ++rg) {
;       const int row = 16 * w + 4 * q + rg;
;       float m_ = -1e30f;
; #pragma unroll
;       for (int nt = 0; nt < 4; ++nt) {
;         const int key = 16 * nt + r;
;         const int delta = row - key + W - 64 * kb;
;         const bool ok = inr && (delta >= -W) && (delta <= W);
;         vm[nt][rg] = ok;
;         float s = S[nt][rg] * 0.125f;
;         S[nt][rg] = s;
;         if (ok) m_ = fmaxf(m_, s);
;       }
;       mx[rg] = grp16_max(m_);
;     }
	s_waitcnt vmcnt(2)
	ds_write_b128 v77, v[10:13] offset:9216
	ds_write_b128 v77, v[6:9] offset:9232
	s_waitcnt vmcnt(1)
	ds_write_b16 v78, v38 offset:18432
	s_waitcnt vmcnt(0)
	ds_write_b16 v79, v42 offset:19584
	ds_write_b16_d16_hi v78, v38 offset:18576
	ds_write_b16_d16_hi v78, v42 offset:19728
	ds_write_b16 v78, v39 offset:18720
	ds_write_b16 v78, v43 offset:19872
	ds_write_b16_d16_hi v78, v39 offset:18864
	ds_write_b16_d16_hi v78, v43 offset:20016
	ds_write_b16 v78, v40 offset:19008
	ds_write_b16 v78, v44 offset:20160
	ds_write_b16_d16_hi v78, v40 offset:19152
	ds_write_b16_d16_hi v78, v44 offset:20304
	ds_write_b16 v78, v41 offset:19296
	ds_write_b16 v78, v45 offset:20448
	ds_write_b16_d16_hi v78, v41 offset:19440
	ds_write_b16_d16_hi v78, v45 offset:20592
	s_waitcnt lgkmcnt(0)
	s_barrier
	ds_read_b128 v[6:9], v64
	ds_read_b128 v[10:13], v63 offset:9216
	ds_read_b128 v[30:33], v63 offset:11520
	v_mfma_f32_16x16x32_f16 v[22:25], v[96:99], v[22:25], v[34:37]
	s_waitcnt lgkmcnt(0)
	v_mfma_f32_16x16x32_f16 v[34:37], v[6:9], v[30:33], 0
	ds_read_b128 v[30:33], v63 offset:13824
	s_waitcnt lgkmcnt(0)
	v_mfma_f32_16x16x32_f16 v[38:41], v[6:9], v[30:33], 0
	ds_read_b128 v[30:33], v63 offset:16128
	v_mfma_f32_16x16x32_f16 v[26:29], v[96:99], v[26:29], v[92:95]
	v_mfma_f32_16x16x32_f16 v[10:13], v[6:9], v[10:13], 0
	s_waitcnt lgkmcnt(0)
	v_mfma_f32_16x16x32_f16 v[42:45], v[6:9], v[30:33], 0
	ds_read_b128 v[92:95], v64 offset:64
	ds_read_b128 v[6:9], v63 offset:9280
	s_waitcnt lgkmcnt(0)
	v_mfma_f32_16x16x32_f16 v[30:33], v[92:95], v[6:9], v[10:13]
	ds_read_b128 v[6:9], v63 offset:11584
	s_waitcnt lgkmcnt(0)
	v_mfma_f32_16x16x32_f16 v[10:13], v[92:95], v[6:9], v[34:37]
	ds_read_b128 v[6:9], v63 offset:13888
	s_nop 1
	ds_read_b128 v[34:37], v63 offset:16192
	s_waitcnt lgkmcnt(1)
	v_mfma_f32_16x16x32_f16 v[6:9], v[92:95], v[6:9], v[38:41]
	s_nop 2
	v_sub_u32_e32 v38, v69, v59
	v_cmp_gt_u32_e64 s[2:3], s16, v38
	v_mul_f32_e32 v38, 0x3e000000, v30
	s_and_b64 s[58:59], vcc, s[2:3]
	v_max_f32_e32 v38, 0xf149f2ca, v38
	v_add_u32_e32 v39, v69, v80
	v_cndmask_b32_e64 v38, v199, v38, s[58:59]
	v_cmp_gt_u32_e64 s[2:3], s16, v39
	v_mul_f32_e32 v39, 0x3e000000, v10
	s_and_b64 s[56:57], vcc, s[2:3]
	v_max_f32_e32 v39, v38, v39
	v_cndmask_b32_e64 v38, v38, v39, s[56:57]
	v_add_u32_e32 v39, v69, v81
	v_cmp_gt_u32_e64 s[2:3], s16, v39
	v_mul_f32_e32 v39, 0x3e000000, v6
	s_and_b64 s[54:55], vcc, s[2:3]
	v_max_f32_e32 v39, v38, v39
	v_cndmask_b32_e64 v38, v38, v39, s[54:55]
	v_add_u32_e32 v39, v69, v82
	v_or_b32_e32 v40, 1, v69
	v_cmp_gt_u32_e64 s[2:3], s16, v39
	v_sub_u32_e32 v41, v40, v59
	s_and_b64 s[52:53], vcc, s[2:3]
	v_cmp_gt_u32_e64 s[2:3], s16, v41
	v_mul_f32_e32 v41, 0x3e000000, v31
	s_waitcnt lgkmcnt(0)
	v_mfma_f32_16x16x32_f16 v[34:37], v[92:95], v[34:37], v[42:45]
	s_and_b64 s[50:51], vcc, s[2:3]
	v_max_f32_e32 v41, 0xf149f2ca, v41
	v_cndmask_b32_e64 v41, v199, v41, s[50:51]
	v_add_u32_e32 v42, v40, v80
	v_cmp_gt_u32_e64 s[2:3], s16, v42
	v_mul_f32_e32 v42, 0x3e000000, v11
	s_and_b64 s[48:49], vcc, s[2:3]
	v_max_f32_e32 v42, v41, v42
	v_cndmask_b32_e64 v41, v41, v42, s[48:49]
	v_add_u32_e32 v42, v40, v81
	v_cmp_gt_u32_e64 s[2:3], s16, v42
	v_mul_f32_e32 v42, 0x3e000000, v7
	s_and_b64 s[46:47], vcc, s[2:3]
	v_max_f32_e32 v42, v41, v42
	v_add_u32_e32 v40, v40, v82
	v_cndmask_b32_e64 v41, v41, v42, s[46:47]
	v_cmp_gt_u32_e64 s[2:3], s16, v40
	v_mul_f32_e32 v40, 0x3e000000, v35
	s_and_b64 s[44:45], vcc, s[2:3]
	v_max_f32_e32 v40, v41, v40
	v_cndmask_b32_e64 v40, v41, v40, s[44:45]
	s_nop 1
	v_mov_b32_dpp v41, v40 quad_perm:[1,0,3,2] row_mask:0xf bank_mask:0xf
	v_mul_f32_e32 v39, 0x3e000000, v34
	v_max_f32_e32 v39, v38, v39
	v_cndmask_b32_e64 v38, v38, v39, s[52:53]
	s_nop 1
	v_mov_b32_dpp v39, v38 quad_perm:[1,0,3,2] row_mask:0xf bank_mask:0xf
	s_waitcnt lgkmcnt(0)
	v_max_f32_e32 v41, v41, v41
	v_max_f32_e32 v40, v40, v41
	s_nop 1
	v_mov_b32_dpp v41, v40 quad_perm:[2,3,0,1] row_mask:0xf bank_mask:0xf
	s_waitcnt lgkmcnt(0)
	v_max_f32_e32 v39, v39, v39
	v_max_f32_e32 v38, v38, v39
	s_nop 1
	v_mov_b32_dpp v39, v38 quad_perm:[2,3,0,1] row_mask:0xf bank_mask:0xf
	s_waitcnt lgkmcnt(0)
	v_max_f32_e32 v41, v41, v41
	v_max_f32_e32 v40, v40, v41
	s_nop 1
	v_mov_b32_dpp v41, v40 row_half_mirror row_mask:0xf bank_mask:0xf
	s_waitcnt lgkmcnt(0)
	v_max_f32_e32 v39, v39, v39
	v_max_f32_e32 v38, v38, v39
	s_nop 1
	v_mov_b32_dpp v39, v38 row_half_mirror row_mask:0xf bank_mask:0xf
	s_waitcnt lgkmcnt(0)
	v_max_f32_e32 v41, v41, v41
	v_max_f32_e32 v42, v40, v41
	v_or_b32_e32 v40, 2, v69
	v_sub_u32_e32 v41, v40, v59
	v_cmp_gt_u32_e64 s[2:3], s16, v41
	v_mul_f32_e32 v41, 0x3e000000, v32
	s_and_b64 s[42:43], vcc, s[2:3]
	v_max_f32_e32 v41, 0xf149f2ca, v41
	v_add_u32_e32 v44, v40, v80
	v_cndmask_b32_e64 v41, v199, v41, s[42:43]
	v_cmp_gt_u32_e64 s[2:3], s16, v44
	v_mul_f32_e32 v44, 0x3e000000, v12
	s_and_b64 s[40:41], vcc, s[2:3]
	v_max_f32_e32 v44, v41, v44
	v_cndmask_b32_e64 v41, v41, v44, s[40:41]
	v_add_u32_e32 v44, v40, v81
	v_cmp_gt_u32_e64 s[2:3], s16, v44
	v_mul_f32_e32 v44, 0x3e000000, v8
	s_and_b64 s[38:39], vcc, s[2:3]
	v_max_f32_e32 v44, v41, v44
	v_add_u32_e32 v40, v40, v82
	v_cndmask_b32_e64 v41, v41, v44, s[38:39]
	v_cmp_gt_u32_e64 s[2:3], s16, v40
	v_mul_f32_e32 v40, 0x3e000000, v36
	s_and_b64 s[36:37], vcc, s[2:3]
	v_max_f32_e32 v40, v41, v40
	v_cndmask_b32_e64 v40, v41, v40, s[36:37]
	s_nop 1
	v_mov_b32_dpp v41, v40 quad_perm:[1,0,3,2] row_mask:0xf bank_mask:0xf
	s_waitcnt lgkmcnt(0)
	v_max_f32_e32 v39, v39, v39
	v_max_f32_e32 v38, v38, v39
	s_nop 1
	v_mov_b32_dpp v39, v38 row_mirror row_mask:0xf bank_mask:0xf
	s_nop 1
	v_mov_b32_dpp v43, v42 row_mirror row_mask:0xf bank_mask:0xf
	s_waitcnt lgkmcnt(0)
; DI float grp16_sum(float v) { v += __shfl_xor(v, 1); v += __shfl_xor(v, 2); v += __shfl_xor(v, 4); v += __shfl_xor(v, 8); return v; }
; DI float grp16_max(float v) { v = fmaxf(v, __shfl_xor(v, 1)); v = fmaxf(v, __shfl_xor(v, 2)); v = fmaxf(v, __shfl_xor(v, 4)); v = fmaxf(v, __shfl_xor(v, 8)); return v; }
; template <int NKB>
; DI void attn_unit(const Params& p, int l, int mode, int grp, int head, int r0, int dil, int i0, int sub_len, int W, h16* lds) {
;     ...
;     for (int rg = 0; rg < 4; ++rg) {
;       const int row = 16 * w + 4 * q + rg;
;       float m_ = -1e30f;
; #pragma unroll
;       for (int nt = 0; nt < 4; ++nt) {
;         const int key = 16 * nt + r;
;         const int delta = row - key + W - 64 * kb;
;         const bool ok = inr && (delta >= -W) && (delta <= W);
;         vm[nt][rg] = ok;
;         float s = S[nt][rg] * 0.125f;
;         S[nt][rg] = s;
;         if (ok) m_ = fmaxf(m_, s);
;       }
;       mx[rg] = grp16_max(m_);
;     }
; #pragma unroll
;     for (int rg = 0; rg < 4; ++rg) {
;       const float mn = fmaxf(mrow[rg], mx[rg]);
;       al[rg] = __expf(mrow[rg] - mn);
;       mrow[rg] = mn;
;       float rs_ = 0.f;
; #pragma unroll
;       for (int nt = 0; nt < 4; ++nt) {
;         float pv = vm[nt][rg] ? __expf(S[nt][rg] - mn) : 0.f;
;         rs_ += pv;
;         Pi[(16 * w + 4 * q + rg) * LDH + 16 * nt + r] = (h16)pv;
;       }
;       rsum[rg] = grp16_sum(rs_);
;       lsum[rg] = lsum[rg] * al[rg] + rsum[rg];
	v_max_f32_e32 v41, v41, v41
	v_max_f32_e32 v40, v40, v41
	s_nop 1
	v_mov_b32_dpp v41, v40 quad_perm:[2,3,0,1] row_mask:0xf bank_mask:0xf
	s_waitcnt lgkmcnt(0)
	v_max_f32_e32 v41, v41, v41
	v_max_f32_e32 v40, v40, v41
	s_nop 1
	v_mov_b32_dpp v41, v40 row_half_mirror row_mask:0xf bank_mask:0xf
	s_waitcnt lgkmcnt(0)
	v_max_f32_e32 v41, v41, v41
	v_max_f32_e32 v44, v40, v41
	v_or_b32_e32 v40, 3, v69
	v_sub_u32_e32 v41, v40, v59
	v_cmp_gt_u32_e64 s[2:3], s16, v41
	v_mul_f32_e32 v41, 0x3e000000, v33
	s_and_b64 s[6:7], vcc, s[2:3]
	v_max_f32_e32 v41, 0xf149f2ca, v41
	v_add_u32_e32 v45, v40, v80
	v_cndmask_b32_e64 v41, v199, v41, s[6:7]
	v_cmp_gt_u32_e64 s[2:3], s16, v45
	v_mul_f32_e32 v45, 0x3e000000, v13
	s_and_b64 s[2:3], vcc, s[2:3]
	v_max_f32_e32 v45, v41, v45
	v_cndmask_b32_e64 v41, v41, v45, s[2:3]
	v_add_u32_e32 v45, v40, v81
	v_cmp_gt_u32_e64 s[4:5], s16, v45
	v_mul_f32_e32 v45, 0x3e000000, v9
	s_and_b64 s[4:5], vcc, s[4:5]
	v_max_f32_e32 v45, v41, v45
	v_add_u32_e32 v40, v40, v82
	v_cndmask_b32_e64 v41, v41, v45, s[4:5]
	v_cmp_gt_u32_e64 s[60:61], s16, v40
	v_mul_f32_e32 v40, 0x3e000000, v37
	s_and_b64 vcc, vcc, s[60:61]
	v_max_f32_e32 v40, v41, v40
	v_cndmask_b32_e32 v40, v41, v40, vcc
	s_nop 1
	v_mov_b32_dpp v41, v40 quad_perm:[1,0,3,2] row_mask:0xf bank_mask:0xf
	s_nop 1
	v_mov_b32_dpp v56, v44 row_mirror row_mask:0xf bank_mask:0xf
	s_waitcnt lgkmcnt(0)
	v_max_f32_e32 v41, v41, v41
	v_max_f32_e32 v40, v40, v41
	s_nop 1
	v_mov_b32_dpp v41, v40 quad_perm:[2,3,0,1] row_mask:0xf bank_mask:0xf
	s_waitcnt lgkmcnt(0)
	v_max_f32_e32 v41, v41, v41
	v_max_f32_e32 v40, v40, v41
	s_nop 1
	v_mov_b32_dpp v41, v40 row_half_mirror row_mask:0xf bank_mask:0xf
	s_waitcnt lgkmcnt(0)
	v_max_f32_e32 v41, v41, v41
	v_max_f32_e32 v45, v40, v41
	v_max3_f32 v40, v90, v38, v39
	v_fma_f32 v30, v30, s9, -v40
	v_mul_f32_e32 v30, 0x3fb8aa3b, v30
	v_exp_f32_e32 v30, v30
	v_fma_f32 v10, v10, s9, -v40
	v_mul_f32_e32 v10, 0x3fb8aa3b, v10
	v_exp_f32_e32 v10, v10
	v_cndmask_b32_e64 v30, 0, v30, s[58:59]
	v_add_f32_e32 v39, 0, v30
	v_cvt_f16_f32_e32 v30, v30
	v_fma_f32 v6, v6, s9, -v40
	v_mul_f32_e32 v6, 0x3fb8aa3b, v6
	v_cndmask_b32_e64 v10, 0, v10, s[56:57]
	v_exp_f32_e32 v6, v6
	ds_write_b16 v72, v30 offset:27648
	v_add_f32_e32 v30, v10, v39
	v_cvt_f16_f32_e32 v10, v10
	v_cndmask_b32_e64 v6, 0, v6, s[54:55]
	v_sub_f32_e32 v38, v90, v40
	v_mul_f32_e32 v38, 0x3fb8aa3b, v38
	ds_write_b16 v72, v10 offset:27680
	v_add_f32_e32 v10, v6, v30
	v_cvt_f16_f32_e32 v6, v6
	v_exp_f32_e32 v38, v38
	s_nop 1
	v_mov_b32_dpp v52, v45 row_mirror row_mask:0xf bank_mask:0xf
	ds_write_b16 v72, v6 offset:27712
	v_fma_f32 v6, v34, s9, -v40
	v_mul_f32_e32 v6, 0x3fb8aa3b, v6
	v_exp_f32_e32 v6, v6
	v_max3_f32 v34, v89, v44, v56
	v_cndmask_b32_e64 v6, 0, v6, s[52:53]
	v_add_f32_e32 v10, v6, v10
	v_cvt_f16_f32_e32 v6, v6
	ds_write_b16 v72, v6 offset:27744
	s_nop 1
	v_mov_b32_dpp v6, v10 quad_perm:[1,0,3,2] row_mask:0xf bank_mask:0xf
	s_waitcnt lgkmcnt(0)
	v_add_f32_e32 v6, v10, v6
	s_nop 1
	v_mov_b32_dpp v10, v6 quad_perm:[2,3,0,1] row_mask:0xf bank_mask:0xf
	s_waitcnt lgkmcnt(0)
	v_add_f32_e32 v6, v6, v10
	s_nop 1
	v_mov_b32_dpp v10, v6 row_half_mirror row_mask:0xf bank_mask:0xf
	s_waitcnt lgkmcnt(0)
	v_add_f32_e32 v6, v6, v10
	s_nop 1
	v_mov_b32_dpp v10, v6 row_mirror row_mask:0xf bank_mask:0xf
	s_waitcnt lgkmcnt(0)
	v_add_f32_e32 v41, v6, v10
	v_fmac_f32_e32 v41, v2, v38
	v_max3_f32 v2, v91, v42, v43
	v_sub_f32_e32 v6, v91, v2
	v_mul_f32_e32 v6, 0x3fb8aa3b, v6
	v_exp_f32_e32 v39, v6
	v_fma_f32 v6, v31, s9, -v2
	v_mul_f32_e32 v6, 0x3fb8aa3b, v6
	v_exp_f32_e32 v6, v6
	s_nop 0
	v_cndmask_b32_e64 v6, 0, v6, s[50:51]
	v_add_f32_e32 v10, 0, v6
	v_cvt_f16_f32_e32 v6, v6
	ds_write_b16 v72, v6 offset:27792
	v_fma_f32 v6, v11, s9, -v2
	v_mul_f32_e32 v6, 0x3fb8aa3b, v6
	v_exp_f32_e32 v6, v6
	s_nop 0
	v_cndmask_b32_e64 v6, 0, v6, s[48:49]
	v_add_f32_e32 v10, v6, v10
	v_cvt_f16_f32_e32 v6, v6
	ds_write_b16 v72, v6 offset:27824
	v_fma_f32 v6, v7, s9, -v2
	v_mul_f32_e32 v6, 0x3fb8aa3b, v6
	v_exp_f32_e32 v6, v6
	s_nop 0
	v_cndmask_b32_e64 v6, 0, v6, s[46:47]
	v_add_f32_e32 v7, v6, v10
	v_cvt_f16_f32_e32 v6, v6
	v_pk_mul_f32 v[10:11], v[18:19], v[38:39]
	v_pk_mul_f32 v[18:19], v[26:27], v[38:39]
	ds_write_b16 v72, v6 offset:27856
	v_fma_f32 v6, v35, s9, -v2
	v_mul_f32_e32 v6, 0x3fb8aa3b, v6
	v_exp_f32_e32 v6, v6
	s_nop 0
	v_cndmask_b32_e64 v6, 0, v6, s[44:45]
	v_add_f32_e32 v7, v6, v7
	v_cvt_f16_f32_e32 v6, v6
	ds_write_b16 v72, v6 offset:27888
	s_nop 1
	v_mov_b32_dpp v6, v7 quad_perm:[1,0,3,2] row_mask:0xf bank_mask:0xf
	s_waitcnt lgkmcnt(0)
	v_add_f32_e32 v6, v7, v6
	s_nop 1
	v_mov_b32_dpp v7, v6 quad_perm:[2,3,0,1] row_mask:0xf bank_mask:0xf
	s_waitcnt lgkmcnt(0)
	v_add_f32_e32 v6, v6, v7
	s_nop 1
	v_mov_b32_dpp v7, v6 row_half_mirror row_mask:0xf bank_mask:0xf
	s_waitcnt lgkmcnt(0)
; DI float grp16_sum(float v) { v += __shfl_xor(v, 1); v += __shfl_xor(v, 2); v += __shfl_xor(v, 4); v += __shfl_xor(v, 8); return v; }
; template <int NKB>
; DI void attn_unit(const Params& p, int l, int mode, int grp, int head, int r0, int dil, int i0, int sub_len, int W, h16* lds) {
;     ...
;     for (int rg = 0; rg < 4; ++rg) {
;       const float mn = fmaxf(mrow[rg], mx[rg]);
;       al[rg] = __expf(mrow[rg] - mn);
;       mrow[rg] = mn;
;       float rs_ = 0.f;
; #pragma unroll
;       for (int nt = 0; nt < 4; ++nt) {
;         float pv = vm[nt][rg] ? __expf(S[nt][rg] - mn) : 0.f;
;         rs_ += pv;
;         Pi[(16 * w + 4 * q + rg) * LDH + 16 * nt + r] = (h16)pv;
;       }
;       rsum[rg] = grp16_sum(rs_);
;       lsum[rg] = lsum[rg] * al[rg] + rsum[rg];
;     }
; #pragma unroll
;     for (int et = 0; et < 4; ++et)
; #pragma unroll
;       for (int rg = 0; rg < 4; ++rg) O[et][rg] *= al[rg];
;     __syncthreads();
;     mm64(Pi, Vt, O, w, lane);
;   }
; #pragma unroll
;   for (int rg = 0; rg < 4; ++rg) {
;     const int row = 16 * w + 4 * q + rg;
;     const size_t pos = (size_t)r0 + (size_t)dil * (i0 + row);
;     const float inv = 1.f / lsum[rg];
;     if (mode == 0) {
;       h16* ob = (h16*)(ws + OFF_OB) + ((size_t)grp * SEQ + pos) * 256 + head * 64;
; #pragma unroll
;       for (int et = 0; et < 4; ++et) ob[16 * et + r] = (h16)(O[et][rg] * inv);
;       if (r == 0) {
;         float* ml = (float*)(ws + OFF_MLB) + (((size_t)grp * SEQ + pos) * 4 + head) * 2;
;         ml[0] = mrow[rg]; ml[1] = lsum[rg];
;       }
	v_add_f32_e32 v35, v6, v7
	v_sub_f32_e32 v6, v89, v34
	v_mul_f32_e32 v6, 0x3fb8aa3b, v6
	v_exp_f32_e32 v30, v6
	v_fma_f32 v6, v32, s9, -v34
	v_mul_f32_e32 v6, 0x3fb8aa3b, v6
	v_exp_f32_e32 v6, v6
	v_max3_f32 v32, v88, v45, v52
	s_nop 1
	v_mov_b32_dpp v42, v35 row_mirror row_mask:0xf bank_mask:0xf
	v_cndmask_b32_e64 v6, 0, v6, s[42:43]
	v_add_f32_e32 v7, 0, v6
	v_cvt_f16_f32_e32 v6, v6
	ds_write_b16 v72, v6 offset:27936
	v_fma_f32 v6, v12, s9, -v34
	v_mul_f32_e32 v6, 0x3fb8aa3b, v6
	v_exp_f32_e32 v6, v6
	s_nop 0
	v_cndmask_b32_e64 v6, 0, v6, s[40:41]
	v_add_f32_e32 v7, v6, v7
	v_cvt_f16_f32_e32 v6, v6
	ds_write_b16 v72, v6 offset:27968
	v_fma_f32 v6, v8, s9, -v34
	v_mul_f32_e32 v6, 0x3fb8aa3b, v6
	v_exp_f32_e32 v6, v6
	s_nop 0
	v_cndmask_b32_e64 v6, 0, v6, s[38:39]
	v_add_f32_e32 v7, v6, v7
	v_cvt_f16_f32_e32 v6, v6
	ds_write_b16 v72, v6 offset:28000
	v_fma_f32 v6, v36, s9, -v34
	v_mul_f32_e32 v6, 0x3fb8aa3b, v6
	v_exp_f32_e32 v6, v6
	s_nop 0
	v_cndmask_b32_e64 v6, 0, v6, s[36:37]
	v_add_f32_e32 v7, v6, v7
	v_cvt_f16_f32_e32 v6, v6
	ds_write_b16 v72, v6 offset:28032
	s_nop 1
	v_mov_b32_dpp v6, v7 quad_perm:[1,0,3,2] row_mask:0xf bank_mask:0xf
	s_waitcnt lgkmcnt(0)
	v_add_f32_e32 v6, v7, v6
	s_nop 1
	v_mov_b32_dpp v7, v6 quad_perm:[2,3,0,1] row_mask:0xf bank_mask:0xf
	s_waitcnt lgkmcnt(0)
	v_add_f32_e32 v6, v6, v7
	s_nop 1
	v_mov_b32_dpp v7, v6 row_half_mirror row_mask:0xf bank_mask:0xf
	s_waitcnt lgkmcnt(0)
	v_add_f32_e32 v43, v6, v7
	v_sub_f32_e32 v6, v88, v32
	v_mul_f32_e32 v6, 0x3fb8aa3b, v6
	v_exp_f32_e32 v31, v6
	v_fma_f32 v6, v33, s9, -v32
	v_mul_f32_e32 v6, 0x3fb8aa3b, v6
	v_exp_f32_e32 v6, v6
	s_nop 1
	v_mov_b32_dpp v44, v43 row_mirror row_mask:0xf bank_mask:0xf
	v_cndmask_b32_e64 v6, 0, v6, s[6:7]
	v_add_f32_e32 v7, 0, v6
	v_cvt_f16_f32_e32 v6, v6
	ds_write_b16 v72, v6 offset:28080
	v_fma_f32 v6, v13, s9, -v32
	v_mul_f32_e32 v6, 0x3fb8aa3b, v6
	v_exp_f32_e32 v6, v6
	v_pk_mul_f32 v[12:13], v[20:21], v[30:31]
	v_pk_mul_f32 v[20:21], v[28:29], v[30:31]
	v_cndmask_b32_e64 v6, 0, v6, s[2:3]
	v_add_f32_e32 v7, v6, v7
	v_cvt_f16_f32_e32 v6, v6
	v_readlane_b32 s2, v254, 32
	v_readlane_b32 s3, v254, 33
	ds_write_b16 v72, v6 offset:28112
	v_fma_f32 v6, v9, s9, -v32
	v_mul_f32_e32 v6, 0x3fb8aa3b, v6
	v_exp_f32_e32 v6, v6
	v_pk_mul_f32 v[8:9], v[16:17], v[30:31]
	v_pk_mul_f32 v[16:17], v[24:25], v[30:31]
	v_cndmask_b32_e64 v6, 0, v6, s[4:5]
	v_add_f32_e32 v7, v6, v7
	v_cvt_f16_f32_e32 v6, v6
	v_readlane_b32 s4, v254, 34
	v_readlane_b32 s5, v254, 35
	ds_write_b16 v72, v6 offset:28144
	v_fma_f32 v6, v37, s9, -v32
	v_mul_f32_e32 v6, 0x3fb8aa3b, v6
	v_exp_f32_e32 v6, v6
	s_nop 0
	v_cndmask_b32_e32 v6, 0, v6, vcc
	v_add_f32_e32 v7, v6, v7
	v_cvt_f16_f32_e32 v6, v6
	ds_write_b16 v72, v6 offset:28176
	s_nop 1
	v_mov_b32_dpp v6, v7 quad_perm:[1,0,3,2] row_mask:0xf bank_mask:0xf
	s_waitcnt lgkmcnt(0)
	s_barrier
	v_add_f32_e32 v6, v7, v6
	s_nop 1
	v_mov_b32_dpp v7, v6 quad_perm:[2,3,0,1] row_mask:0xf bank_mask:0xf
	s_waitcnt lgkmcnt(0)
	v_add_f32_e32 v6, v6, v7
	s_nop 1
	v_mov_b32_dpp v7, v6 row_half_mirror row_mask:0xf bank_mask:0xf
	s_waitcnt lgkmcnt(0)
	v_add_f32_e32 v33, v6, v7
	v_pk_mul_f32 v[6:7], v[14:15], v[38:39]
	v_pk_mul_f32 v[14:15], v[22:23], v[38:39]
	ds_read_b128 v[22:25], v64 offset:27648
	ds_read_b128 v[26:29], v63 offset:18432
	s_waitcnt lgkmcnt(0)
	v_mfma_f32_16x16x32_f16 v[6:9], v[22:25], v[26:29], v[6:9]
	ds_read_b128 v[26:29], v63 offset:20736
	s_nop 1
	v_mov_b32_dpp v45, v33 row_mirror row_mask:0xf bank_mask:0xf
	s_waitcnt lgkmcnt(0)
	v_mfma_f32_16x16x32_f16 v[10:13], v[22:25], v[26:29], v[10:13]
	ds_read_b128 v[26:29], v63 offset:23040
	s_waitcnt lgkmcnt(0)
	v_mfma_f32_16x16x32_f16 v[14:17], v[22:25], v[26:29], v[14:17]
	ds_read_b128 v[26:29], v63 offset:25344
	s_waitcnt lgkmcnt(0)
	v_mfma_f32_16x16x32_f16 v[18:21], v[22:25], v[26:29], v[18:21]
	ds_read_b128 v[22:25], v64 offset:27712
	ds_read_b128 v[26:29], v63 offset:18496
	s_waitcnt lgkmcnt(0)
	v_mfma_f32_16x16x32_f16 v[6:9], v[22:25], v[26:29], v[6:9]
	ds_read_b128 v[26:29], v63 offset:20800
	s_waitcnt lgkmcnt(0)
	v_mfma_f32_16x16x32_f16 v[10:13], v[22:25], v[26:29], v[10:13]
	ds_read_b128 v[26:29], v63 offset:23104
	s_waitcnt lgkmcnt(0)
	v_mfma_f32_16x16x32_f16 v[14:17], v[22:25], v[26:29], v[14:17]
	ds_read_b128 v[26:29], v63 offset:25408
	s_waitcnt lgkmcnt(0)
	v_mfma_f32_16x16x32_f16 v[18:21], v[22:25], v[26:29], v[18:21]
	v_add_u32_e32 v22, v61, v60
	v_or_b32_e32 v26, v22, v62
	v_lshlrev_b32_e32 v22, 3, v51
	v_mov_b32_e32 v23, v0
	v_lshl_add_u64 v[22:23], s[4:5], 0, v[22:23]
	v_div_scale_f32 v27, s[4:5], v41, v41, 1.0
	v_rcp_f32_e32 v36, v27
	v_lshl_or_b32 v24, v49, 14, v46
	v_mov_b32_e32 v25, v0
	v_mov_b32_e32 v49, v0
	v_fma_f32 v37, -v27, v36, 1.0
	v_fmac_f32_e32 v36, v37, v36
	v_div_scale_f32 v37, vcc, 1.0, v41, 1.0
	v_mul_f32_e32 v38, v37, v36
	v_fma_f32 v46, -v27, v38, v37
	v_fmac_f32_e32 v38, v46, v36
	v_fma_f32 v27, -v27, v38, v37
	v_div_fmas_f32 v27, v27, v36, v38
	v_div_fixup_f32 v38, v27, v41, 1.0
	v_ashrrev_i32_e32 v27, 31, v26
	v_lshlrev_b64 v[36:37], v58, v[26:27]
	v_lshl_add_u64 v[36:37], v[36:37], 0, v[24:25]
	v_lshl_add_u64 v[28:29], s[2:3], 0, v[48:49]
	v_lshlrev_b64 v[48:49], 9, v[36:37]
	v_lshl_add_u64 v[48:49], v[28:29], 0, v[48:49]
	v_mov_b32_e32 v51, v0
	v_fma_mixlo_f16 v6, v38, v6, 0
	v_lshl_add_u64 v[48:49], v[48:49], 0, v[50:51]
	global_store_short v[48:49], v6, off
	v_fma_mixlo_f16 v6, v38, v10, 0
	global_store_short v[48:49], v6, off offset:32
	v_fma_mixlo_f16 v6, v38, v14, 0
	v_cmp_eq_u32_e64 s[2:3], 0, v59
	global_store_short v[48:49], v6, off offset:64
	v_fma_mixlo_f16 v6, v38, v18, 0
	global_store_short v[48:49], v6, off offset:96
	s_and_saveexec_b64 s[4:5], s[2:3]
	s_cbranch_execz .LBB0_903
	v_lshlrev_b64 v[36:37], 5, v[36:37]
	v_lshl_add_u64 v[36:37], v[22:23], 0, v[36:37]
	global_store_dwordx2 v[36:37], v[40:41], off

; DI float grp16_max(float v) { v = fmaxf(v, __shfl_xor(v, 1)); v = fmaxf(v, __shfl_xor(v, 2)); v = fmaxf(v, __shfl_xor(v, 4)); v = fmaxf(v, __shfl_xor(v, 8)); return v; }
; template <int NKB>
; DI void attn_unit(const Params& p, int l, int mode, int grp, int head, int r0, int dil, int i0, int sub_len, int W, h16* lds) {
;     ...
;   for (int kb = 0; kb < NKB; ++kb) {
;     const int j0 = i0 - W + 64 * kb;
;     const bool inr = (j0 >= 0) && (j0 < sub_len);
;     __syncthreads();
;     img_store_nat(Ki, lrow, seg, pk0, pk1);
;     img_store_T(Vt, lrow, seg, pv0, pv1);
;     __syncthreads();
;     if (kb + 1 < NKB) ATT_PREFETCH(kb + 1);
;     f4v S[4];
; #pragma unroll
;     for (int i = 0; i < 4; ++i) S[i] = (f4v){0.f, 0.f, 0.f, 0.f};
;     mm64(Qi, Ki, S, w, lane);
;     float mx[4], al[4], rsum[4];
;     bool vm[4][4];
; #pragma unroll
;     for (int rg = 0; rg < 4; ++rg) {
;       const int row = 16 * w + 4 * q + rg;
;       float m_ = -1e30f;
; #pragma unroll
;       for (int nt = 0; nt < 4; ++nt) {
;         const int key = 16 * nt + r;
;         const int delta = row - key + W - 64 * kb;
;         const bool ok = inr && (delta >= -W) && (delta <= W);
;         vm[nt][rg] = ok;
;         float s = S[nt][rg] * 0.125f;
;         S[nt][rg] = s;
;         if (ok) m_ = fmaxf(m_, s);
;       }
;       mx[rg] = grp16_max(m_);
;     }
.LBB0_912:
	v_cmp_gt_u32_e32 vcc, s17, v71
	v_add_u32_e32 v71, 64, v71
	v_cmp_gt_u32_e64 s[2:3], s17, v71
	s_waitcnt lgkmcnt(0)
	s_barrier
	s_waitcnt vmcnt(2)
	ds_write_b128 v69, v[30:33] offset:9216
	ds_write_b128 v69, v[26:29] offset:9232
	s_waitcnt vmcnt(1)
	ds_write_b16 v68, v18 offset:18432
	s_waitcnt vmcnt(0)
	ds_write_b16 v70, v22 offset:19584
	ds_write_b16_d16_hi v68, v18 offset:18576
	ds_write_b16_d16_hi v68, v22 offset:19728
	ds_write_b16 v68, v19 offset:18720
	ds_write_b16 v68, v23 offset:19872
	ds_write_b16_d16_hi v68, v19 offset:18864
	ds_write_b16_d16_hi v68, v23 offset:20016
	ds_write_b16 v68, v20 offset:19008
	ds_write_b16 v68, v24 offset:20160
	ds_write_b16_d16_hi v68, v20 offset:19152
	ds_write_b16_d16_hi v68, v24 offset:20304
	ds_write_b16 v68, v21 offset:19296
	ds_write_b16 v68, v25 offset:20448
	ds_write_b16_d16_hi v68, v21 offset:19440
	ds_write_b16_d16_hi v68, v25 offset:20592
	v_cndmask_b32_e64 v18, v51, v71, s[2:3]
	v_add_u32_e32 v20, v18, v67
	v_mov_b64_e32 v[18:19], s[0:1]
	v_mov_b32_e32 v87, v55
	v_mad_i64_i32 v[18:19], s[2:3], v20, s9, v[18:19]
	v_mov_b32_e32 v55, v0
	v_mov_b32_e32 v59, v0
	v_lshl_add_u64 v[20:21], v[18:19], 0, v[54:55]
	v_mov_b32_e32 v57, v0
	v_lshl_add_u64 v[18:19], v[18:19], 0, v[58:59]
	v_lshl_add_u64 v[20:21], v[20:21], 0, v[56:57]
	v_lshl_add_u64 v[22:23], v[18:19], 0, v[56:57]
	v_mov_b32_e32 v75, v38
	v_mov_b32_e32 v84, v39
	v_mov_b32_e32 v85, v36
	v_mov_b32_e32 v86, v35
	v_mov_b32_e32 v88, v42
	v_mov_b32_e32 v89, v43
	v_mov_b32_e32 v90, v34
	s_waitcnt lgkmcnt(0)
	s_barrier
	global_load_dwordx4 v[26:29], v[20:21], off offset:16
	global_load_dwordx4 v[30:33], v[20:21], off
	s_nop 0
	global_load_dwordx4 v[18:21], v[22:23], off
	s_nop 0
	global_load_dwordx4 v[22:25], v[22:23], off offset:16
	ds_read_b128 v[34:37], v60
	ds_read_b128 v[38:41], v53 offset:9216
	ds_read_b128 v[42:45], v53 offset:11520
	ds_read_b128 v[46:49], v53 offset:13824
	ds_read_b128 v[76:79], v53 offset:16128
	s_waitcnt lgkmcnt(3)
	v_mfma_f32_16x16x32_f16 v[38:41], v[34:37], v[38:41], 0
	v_add_u32_e32 v55, s8, v74
	v_add_u32_e32 v57, 0x100, v55
	v_cmp_gt_u32_e64 s[2:3], s18, v57
	s_waitcnt lgkmcnt(2)
	v_mfma_f32_16x16x32_f16 v[42:45], v[34:37], v[42:45], 0
	s_and_b64 s[58:59], vcc, s[2:3]
	v_add_u32_e32 v59, 0xf0, v55
	v_cmp_gt_u32_e64 s[2:3], s18, v59
	s_waitcnt lgkmcnt(1)
	v_mfma_f32_16x16x32_f16 v[46:49], v[34:37], v[46:49], 0
	s_and_b64 s[56:57], vcc, s[2:3]
	s_sub_i32 s8, s8, 64
	s_waitcnt lgkmcnt(0)
	v_mfma_f32_16x16x32_f16 v[76:79], v[34:37], v[76:79], 0
	ds_read_b128 v[80:83], v60 offset:64
	ds_read_b128 v[34:37], v53 offset:9280
	s_waitcnt lgkmcnt(0)
	v_mfma_f32_16x16x32_f16 v[34:37], v[80:83], v[34:37], v[38:41]
	s_nop 2
	ds_read_b128 v[38:41], v53 offset:11584
	s_waitcnt lgkmcnt(0)
	v_mfma_f32_16x16x32_f16 v[38:41], v[80:83], v[38:41], v[42:45]
	s_nop 2
	ds_read_b128 v[42:45], v53 offset:13888
	v_mul_f32_e32 v57, 0x3e000000, v34
	v_max_f32_e32 v57, 0xf149f2ca, v57
	s_waitcnt lgkmcnt(0)
	v_mfma_f32_16x16x32_f16 v[42:45], v[80:83], v[42:45], v[46:49]
	v_cndmask_b32_e64 v57, v199, v57, s[58:59]
	v_mul_f32_e32 v59, 0x3e000000, v38
	v_max_f32_e32 v59, v57, v59
	ds_read_b128 v[46:49], v53 offset:16192
	v_cndmask_b32_e64 v57, v57, v59, s[56:57]
	v_add_u32_e32 v59, 0xe0, v55
	v_cmp_gt_u32_e64 s[2:3], s18, v59
	s_nop 0
	v_mul_f32_e32 v59, 0x3e000000, v42
	s_and_b64 s[54:55], vcc, s[2:3]
	v_max_f32_e32 v59, v57, v59
	v_cndmask_b32_e64 v57, v57, v59, s[54:55]
	v_add_u32_e32 v59, 0xd0, v55
	v_cmp_gt_u32_e64 s[2:3], s18, v59
	s_waitcnt lgkmcnt(0)
	v_mfma_f32_16x16x32_f16 v[46:49], v[80:83], v[46:49], v[76:79]
	s_and_b64 s[52:53], vcc, s[2:3]
	v_add_u32_e32 v81, 0xf3, v55
	s_nop 0
	v_add_co_u32_e64 v76, s[2:3], s18, v55
	v_mul_f32_e32 v76, 0x3e000000, v35
	s_and_b64 s[50:51], vcc, s[2:3]
	v_max_f32_e32 v76, 0xf149f2ca, v76
	v_add_u32_e32 v77, 0xf1, v55
	v_cndmask_b32_e64 v76, v199, v76, s[50:51]
	v_cmp_gt_u32_e64 s[2:3], s18, v77
	v_mul_f32_e32 v77, 0x3e000000, v39
	s_and_b64 s[48:49], vcc, s[2:3]
	v_max_f32_e32 v77, v76, v77
	v_cndmask_b32_e64 v76, v76, v77, s[48:49]
	v_add_u32_e32 v77, 0xe1, v55
	v_cmp_gt_u32_e64 s[2:3], s18, v77
	v_mul_f32_e32 v77, 0x3e000000, v43
	s_and_b64 s[46:47], vcc, s[2:3]
	v_max_f32_e32 v77, v76, v77
	v_cndmask_b32_e64 v76, v76, v77, s[46:47]
	v_add_u32_e32 v77, 0xd1, v55
	v_cmp_gt_u32_e64 s[2:3], s18, v77
	v_mul_f32_e32 v77, 0x3e000000, v47
	s_and_b64 s[44:45], vcc, s[2:3]
	v_max_f32_e32 v77, v76, v77
	v_cndmask_b32_e64 v76, v76, v77, s[44:45]
	s_nop 1
	v_mov_b32_dpp v77, v76 quad_perm:[1,0,3,2] row_mask:0xf bank_mask:0xf
	v_add_u32_e32 v79, 0xf2, v55
	v_mul_f32_e32 v59, 0x3e000000, v46
	v_max_f32_e32 v59, v57, v59
	v_cndmask_b32_e64 v57, v57, v59, s[52:53]
	s_waitcnt lgkmcnt(0)
	v_max_f32_e32 v77, v77, v77
	v_max_f32_e32 v76, v76, v77
	s_nop 1
	v_mov_b32_dpp v77, v76 quad_perm:[2,3,0,1] row_mask:0xf bank_mask:0xf
	s_nop 1
	v_mov_b32_dpp v59, v57 quad_perm:[1,0,3,2] row_mask:0xf bank_mask:0xf
	s_waitcnt lgkmcnt(0)
	v_max_f32_e32 v77, v77, v77
	v_max_f32_e32 v76, v76, v77
	s_nop 1
	v_mov_b32_dpp v77, v76 row_half_mirror row_mask:0xf bank_mask:0xf
	s_waitcnt lgkmcnt(0)
	v_max_f32_e32 v59, v59, v59
	v_max_f32_e32 v57, v57, v59
	s_nop 1
	v_mov_b32_dpp v59, v57 quad_perm:[2,3,0,1] row_mask:0xf bank_mask:0xf
	s_waitcnt lgkmcnt(0)
; DI float grp16_sum(float v) { v += __shfl_xor(v, 1); v += __shfl_xor(v, 2); v += __shfl_xor(v, 4); v += __shfl_xor(v, 8); return v; }
; DI float grp16_max(float v) { v = fmaxf(v, __shfl_xor(v, 1)); v = fmaxf(v, __shfl_xor(v, 2)); v = fmaxf(v, __shfl_xor(v, 4)); v = fmaxf(v, __shfl_xor(v, 8)); return v; }
; template <int NKB>
; DI void attn_unit(const Params& p, int l, int mode, int grp, int head, int r0, int dil, int i0, int sub_len, int W, h16* lds) {
;     ...
;     for (int rg = 0; rg < 4; ++rg) {
;       const int row = 16 * w + 4 * q + rg;
;       float m_ = -1e30f;
; #pragma unroll
;       for (int nt = 0; nt < 4; ++nt) {
;         const int key = 16 * nt + r;
;         const int delta = row - key + W - 64 * kb;
;         const bool ok = inr && (delta >= -W) && (delta <= W);
;         vm[nt][rg] = ok;
;         float s = S[nt][rg] * 0.125f;
;         S[nt][rg] = s;
;         if (ok) m_ = fmaxf(m_, s);
;       }
;       mx[rg] = grp16_max(m_);
;     }
; #pragma unroll
;     for (int rg = 0; rg < 4; ++rg) {
;       const float mn = fmaxf(mrow[rg], mx[rg]);
;       al[rg] = __expf(mrow[rg] - mn);
;       mrow[rg] = mn;
;       float rs_ = 0.f;
; #pragma unroll
;       for (int nt = 0; nt < 4; ++nt) {
;         float pv = vm[nt][rg] ? __expf(S[nt][rg] - mn) : 0.f;
;         rs_ += pv;
;         Pi[(16 * w + 4 * q + rg) * LDH + 16 * nt + r] = (h16)pv;
;       }
;       rsum[rg] = grp16_sum(rs_);
;       lsum[rg] = lsum[rg] * al[rg] + rsum[rg];
;     }
; #pragma unroll
;     for (int et = 0; et < 4; ++et)
; #pragma unroll
;       for (int rg = 0; rg < 4; ++rg) O[et][rg] *= al[rg];
	v_max_f32_e32 v77, v77, v77
	v_max_f32_e32 v77, v76, v77
	v_add_u32_e32 v76, 0x102, v55
	v_cmp_gt_u32_e64 s[2:3], s18, v76
	v_mul_f32_e32 v76, 0x3e000000, v36
	s_and_b64 s[42:43], vcc, s[2:3]
	v_max_f32_e32 v76, 0xf149f2ca, v76
	v_cndmask_b32_e64 v76, v199, v76, s[42:43]
	v_cmp_gt_u32_e64 s[2:3], s18, v79
	v_mul_f32_e32 v79, 0x3e000000, v40
	s_and_b64 s[40:41], vcc, s[2:3]
	v_max_f32_e32 v79, v76, v79
	v_cndmask_b32_e64 v76, v76, v79, s[40:41]
	v_add_u32_e32 v79, 0xe2, v55
	v_cmp_gt_u32_e64 s[2:3], s18, v79
	v_mul_f32_e32 v79, 0x3e000000, v44
	s_and_b64 s[38:39], vcc, s[2:3]
	v_max_f32_e32 v79, v76, v79
	v_cndmask_b32_e64 v76, v76, v79, s[38:39]
	v_add_u32_e32 v79, 0xd2, v55
	v_cmp_gt_u32_e64 s[2:3], s18, v79
	v_mul_f32_e32 v79, 0x3e000000, v48
	s_and_b64 s[36:37], vcc, s[2:3]
	v_max_f32_e32 v79, v76, v79
	v_cndmask_b32_e64 v76, v76, v79, s[36:37]
	s_nop 1
	v_mov_b32_dpp v79, v76 quad_perm:[1,0,3,2] row_mask:0xf bank_mask:0xf
	s_waitcnt lgkmcnt(0)
	v_max_f32_e32 v59, v59, v59
	v_max_f32_e32 v57, v57, v59
	s_nop 1
	v_mov_b32_dpp v59, v57 row_half_mirror row_mask:0xf bank_mask:0xf
	s_nop 1
	v_mov_b32_dpp v78, v77 row_mirror row_mask:0xf bank_mask:0xf
	s_waitcnt lgkmcnt(0)
	v_max_f32_e32 v79, v79, v79
	v_max_f32_e32 v76, v76, v79
	s_nop 1
	v_mov_b32_dpp v79, v76 quad_perm:[2,3,0,1] row_mask:0xf bank_mask:0xf
	s_waitcnt lgkmcnt(0)
	v_max_f32_e32 v59, v59, v59
	v_max_f32_e32 v57, v57, v59
	s_nop 1
	v_mov_b32_dpp v59, v57 row_mirror row_mask:0xf bank_mask:0xf
	s_waitcnt lgkmcnt(0)
	v_max_f32_e32 v79, v79, v79
	v_max_f32_e32 v76, v76, v79
	s_nop 1
	v_mov_b32_dpp v79, v76 row_half_mirror row_mask:0xf bank_mask:0xf
	s_waitcnt lgkmcnt(0)
	v_max_f32_e32 v79, v79, v79
	v_max_f32_e32 v79, v76, v79
	v_add_u32_e32 v76, 0x103, v55
	v_cmp_gt_u32_e64 s[2:3], s18, v76
	v_mul_f32_e32 v76, 0x3e000000, v37
	s_and_b64 s[6:7], vcc, s[2:3]
	v_max_f32_e32 v76, 0xf149f2ca, v76
	v_cndmask_b32_e64 v76, v199, v76, s[6:7]
	v_cmp_gt_u32_e64 s[2:3], s18, v81
	v_mul_f32_e32 v81, 0x3e000000, v41
	s_and_b64 s[4:5], vcc, s[2:3]
	v_max_f32_e32 v81, v76, v81
	v_cndmask_b32_e64 v76, v76, v81, s[4:5]
	v_add_u32_e32 v81, 0xe3, v55
	v_cmp_gt_u32_e64 s[2:3], s18, v81
	v_mul_f32_e32 v81, 0x3e000000, v45
	s_and_b64 s[2:3], vcc, s[2:3]
	v_max_f32_e32 v81, v76, v81
	v_add_u32_e32 v55, 0xd3, v55
	v_cndmask_b32_e64 v76, v76, v81, s[2:3]
	v_cmp_gt_u32_e64 s[60:61], s18, v55
	v_mul_f32_e32 v55, 0x3e000000, v49
	s_and_b64 vcc, vcc, s[60:61]
	v_max_f32_e32 v55, v76, v55
	v_cndmask_b32_e32 v55, v76, v55, vcc
	s_nop 1
	v_mov_b32_dpp v76, v55 quad_perm:[1,0,3,2] row_mask:0xf bank_mask:0xf
	s_nop 1
	v_mov_b32_dpp v80, v79 row_mirror row_mask:0xf bank_mask:0xf
	s_cmpk_lg_i32 s8, 0xff00
	s_waitcnt lgkmcnt(0)
	v_max_f32_e32 v76, v76, v76
	v_max_f32_e32 v55, v55, v76
	s_nop 1
	v_mov_b32_dpp v76, v55 quad_perm:[2,3,0,1] row_mask:0xf bank_mask:0xf
	s_waitcnt lgkmcnt(0)
	v_max_f32_e32 v76, v76, v76
	v_max_f32_e32 v55, v55, v76
	s_nop 1
	v_mov_b32_dpp v76, v55 row_half_mirror row_mask:0xf bank_mask:0xf
	s_waitcnt lgkmcnt(0)
	v_max_f32_e32 v76, v76, v76
	v_max_f32_e32 v81, v55, v76
	v_max3_f32 v55, v87, v57, v59
	v_fma_f32 v34, v34, s16, -v55
	v_mul_f32_e32 v34, 0x3fb8aa3b, v34
	v_exp_f32_e32 v34, v34
	v_sub_f32_e32 v57, v87, v55
	v_mul_f32_e32 v57, 0x3fb8aa3b, v57
	v_exp_f32_e32 v76, v57
	v_cndmask_b32_e64 v34, 0, v34, s[58:59]
	v_add_f32_e32 v57, 0, v34
	v_cvt_f16_f32_e32 v34, v34
	s_nop 1
	v_mov_b32_dpp v82, v81 row_mirror row_mask:0xf bank_mask:0xf
	ds_write_b16 v65, v34 offset:27648
	v_fma_f32 v34, v38, s16, -v55
	v_mul_f32_e32 v34, 0x3fb8aa3b, v34
	v_exp_f32_e32 v34, v34
	s_nop 0
	v_cndmask_b32_e64 v34, 0, v34, s[56:57]
	v_add_f32_e32 v38, v34, v57
	v_cvt_f16_f32_e32 v34, v34
	ds_write_b16 v65, v34 offset:27680
	v_fma_f32 v34, v42, s16, -v55
	v_mul_f32_e32 v34, 0x3fb8aa3b, v34
	v_exp_f32_e32 v34, v34
	v_max3_f32 v42, v88, v77, v78
	v_cndmask_b32_e64 v34, 0, v34, s[54:55]
	v_add_f32_e32 v38, v34, v38
	v_cvt_f16_f32_e32 v34, v34
	ds_write_b16 v65, v34 offset:27712
	v_fma_f32 v34, v46, s16, -v55
	v_mul_f32_e32 v34, 0x3fb8aa3b, v34
	v_exp_f32_e32 v34, v34
	s_nop 0
	v_cndmask_b32_e64 v34, 0, v34, s[52:53]
	v_add_f32_e32 v38, v34, v38
	v_cvt_f16_f32_e32 v34, v34
	ds_write_b16 v65, v34 offset:27744
	s_nop 1
	v_mov_b32_dpp v34, v38 quad_perm:[1,0,3,2] row_mask:0xf bank_mask:0xf
	s_waitcnt lgkmcnt(0)
	v_add_f32_e32 v34, v38, v34
	s_nop 1
	v_mov_b32_dpp v38, v34 quad_perm:[2,3,0,1] row_mask:0xf bank_mask:0xf
	s_waitcnt lgkmcnt(0)
	v_add_f32_e32 v34, v34, v38
	s_nop 1
	v_mov_b32_dpp v38, v34 row_half_mirror row_mask:0xf bank_mask:0xf
	s_waitcnt lgkmcnt(0)
	v_add_f32_e32 v34, v34, v38
	s_nop 1
	v_mov_b32_dpp v38, v34 row_mirror row_mask:0xf bank_mask:0xf
	s_waitcnt lgkmcnt(0)
	v_add_f32_e32 v38, v34, v38
	v_sub_f32_e32 v34, v88, v42
	v_mul_f32_e32 v34, 0x3fb8aa3b, v34
	v_exp_f32_e32 v77, v34
	v_fma_f32 v34, v35, s16, -v42
	v_mul_f32_e32 v34, 0x3fb8aa3b, v34
	v_exp_f32_e32 v34, v34
	v_fmac_f32_e32 v38, v75, v76
	v_pk_mul_f32 v[2:3], v[2:3], v[76:77]
	v_pk_mul_f32 v[6:7], v[6:7], v[76:77]
	v_cndmask_b32_e64 v34, 0, v34, s[50:51]
	v_add_f32_e32 v35, 0, v34
	v_cvt_f16_f32_e32 v34, v34
	v_pk_mul_f32 v[10:11], v[10:11], v[76:77]
	v_pk_mul_f32 v[14:15], v[14:15], v[76:77]
	ds_write_b16 v65, v34 offset:27792
	v_fma_f32 v34, v39, s16, -v42
	v_mul_f32_e32 v34, 0x3fb8aa3b, v34
	v_exp_f32_e32 v34, v34
	s_nop 0
	v_cndmask_b32_e64 v34, 0, v34, s[48:49]
	v_add_f32_e32 v35, v34, v35
	v_cvt_f16_f32_e32 v34, v34
	ds_write_b16 v65, v34 offset:27824
	v_fma_f32 v34, v43, s16, -v42
	v_mul_f32_e32 v34, 0x3fb8aa3b, v34
	v_exp_f32_e32 v34, v34
	v_max3_f32 v43, v89, v79, v80
	v_cndmask_b32_e64 v34, 0, v34, s[46:47]
	v_add_f32_e32 v35, v34, v35
	v_cvt_f16_f32_e32 v34, v34
	ds_write_b16 v65, v34 offset:27856
	v_fma_f32 v34, v47, s16, -v42
	v_mul_f32_e32 v34, 0x3fb8aa3b, v34
	v_exp_f32_e32 v34, v34
	s_nop 0
	v_cndmask_b32_e64 v34, 0, v34, s[44:45]
	v_add_f32_e32 v35, v34, v35
	v_cvt_f16_f32_e32 v34, v34
	ds_write_b16 v65, v34 offset:27888
	s_nop 1
	v_mov_b32_dpp v34, v35 quad_perm:[1,0,3,2] row_mask:0xf bank_mask:0xf
	s_waitcnt lgkmcnt(0)
; DI float grp16_sum(float v) { v += __shfl_xor(v, 1); v += __shfl_xor(v, 2); v += __shfl_xor(v, 4); v += __shfl_xor(v, 8); return v; }
; template <int NKB>
; DI void attn_unit(const Params& p, int l, int mode, int grp, int head, int r0, int dil, int i0, int sub_len, int W, h16* lds) {
;     ...
;     __syncthreads();
;     img_store_nat(Ki, lrow, seg, pk0, pk1);
;     img_store_T(Vt, lrow, seg, pv0, pv1);
;     __syncthreads();
;     ...
;     for (int rg = 0; rg < 4; ++rg) {
;       const float mn = fmaxf(mrow[rg], mx[rg]);
;       al[rg] = __expf(mrow[rg] - mn);
;       mrow[rg] = mn;
;       float rs_ = 0.f;
; #pragma unroll
;       for (int nt = 0; nt < 4; ++nt) {
;         float pv = vm[nt][rg] ? __expf(S[nt][rg] - mn) : 0.f;
;         rs_ += pv;
;         Pi[(16 * w + 4 * q + rg) * LDH + 16 * nt + r] = (h16)pv;
;       }
;       rsum[rg] = grp16_sum(rs_);
;       lsum[rg] = lsum[rg] * al[rg] + rsum[rg];
;     }
; #pragma unroll
;     for (int et = 0; et < 4; ++et)
; #pragma unroll
;       for (int rg = 0; rg < 4; ++rg) O[et][rg] *= al[rg];
;     __syncthreads();
;     mm64(Pi, Vt, O, w, lane);
;   }
	v_add_f32_e32 v34, v35, v34
	s_nop 1
	v_mov_b32_dpp v35, v34 quad_perm:[2,3,0,1] row_mask:0xf bank_mask:0xf
	s_waitcnt lgkmcnt(0)
	v_add_f32_e32 v34, v34, v35
	s_nop 1
	v_mov_b32_dpp v35, v34 row_half_mirror row_mask:0xf bank_mask:0xf
	s_waitcnt lgkmcnt(0)
	v_add_f32_e32 v34, v34, v35
	s_nop 1
	v_mov_b32_dpp v35, v34 row_mirror row_mask:0xf bank_mask:0xf
	s_waitcnt lgkmcnt(0)
	v_add_f32_e32 v39, v34, v35
	v_sub_f32_e32 v34, v89, v43
	v_mul_f32_e32 v34, 0x3fb8aa3b, v34
	v_exp_f32_e32 v46, v34
	v_fma_f32 v34, v36, s16, -v43
	v_mul_f32_e32 v34, 0x3fb8aa3b, v34
	v_exp_f32_e32 v34, v34
	v_fmac_f32_e32 v39, v84, v77
	v_cndmask_b32_e64 v34, 0, v34, s[42:43]
	v_add_f32_e32 v35, 0, v34
	v_cvt_f16_f32_e32 v34, v34
	ds_write_b16 v65, v34 offset:27936
	v_fma_f32 v34, v40, s16, -v43
	v_mul_f32_e32 v34, 0x3fb8aa3b, v34
	v_exp_f32_e32 v34, v34
	s_nop 0
	v_cndmask_b32_e64 v34, 0, v34, s[40:41]
	v_add_f32_e32 v35, v34, v35
	v_cvt_f16_f32_e32 v34, v34
	ds_write_b16 v65, v34 offset:27968
	v_fma_f32 v34, v44, s16, -v43
	v_mul_f32_e32 v34, 0x3fb8aa3b, v34
	v_exp_f32_e32 v34, v34
	s_nop 0
	v_cndmask_b32_e64 v34, 0, v34, s[38:39]
	v_add_f32_e32 v35, v34, v35
	v_cvt_f16_f32_e32 v34, v34
	ds_write_b16 v65, v34 offset:28000
	v_fma_f32 v34, v48, s16, -v43
	v_mul_f32_e32 v34, 0x3fb8aa3b, v34
	v_exp_f32_e32 v34, v34
	s_nop 0
	v_cndmask_b32_e64 v34, 0, v34, s[36:37]
	v_add_f32_e32 v35, v34, v35
	v_cvt_f16_f32_e32 v34, v34
	ds_write_b16 v65, v34 offset:28032
	s_nop 1
	v_mov_b32_dpp v34, v35 quad_perm:[1,0,3,2] row_mask:0xf bank_mask:0xf
	s_waitcnt lgkmcnt(0)
	v_add_f32_e32 v34, v35, v34
	s_nop 1
	v_mov_b32_dpp v35, v34 quad_perm:[2,3,0,1] row_mask:0xf bank_mask:0xf
	s_waitcnt lgkmcnt(0)
	v_add_f32_e32 v34, v34, v35
	s_nop 1
	v_mov_b32_dpp v35, v34 row_half_mirror row_mask:0xf bank_mask:0xf
	s_waitcnt lgkmcnt(0)
	v_add_f32_e32 v34, v34, v35
	s_nop 1
	v_mov_b32_dpp v35, v34 row_mirror row_mask:0xf bank_mask:0xf
	s_waitcnt lgkmcnt(0)
	v_add_f32_e32 v36, v34, v35
	v_max3_f32 v34, v90, v81, v82
	v_sub_f32_e32 v35, v90, v34
	v_mul_f32_e32 v35, 0x3fb8aa3b, v35
	v_exp_f32_e32 v47, v35
	v_fma_f32 v35, v37, s16, -v34
	v_mul_f32_e32 v35, 0x3fb8aa3b, v35
	v_exp_f32_e32 v35, v35
	v_fmac_f32_e32 v36, v85, v46
	v_pk_mul_f32 v[4:5], v[4:5], v[46:47]
	v_pk_mul_f32 v[8:9], v[8:9], v[46:47]
	v_cndmask_b32_e64 v35, 0, v35, s[6:7]
	v_add_f32_e32 v37, 0, v35
	v_cvt_f16_f32_e32 v35, v35
	v_pk_mul_f32 v[12:13], v[12:13], v[46:47]
	v_pk_mul_f32 v[16:17], v[16:17], v[46:47]
	ds_write_b16 v65, v35 offset:28080
	v_fma_f32 v35, v41, s16, -v34
	v_mul_f32_e32 v35, 0x3fb8aa3b, v35
	v_exp_f32_e32 v35, v35
	s_nop 0
	v_cndmask_b32_e64 v35, 0, v35, s[4:5]
	v_add_f32_e32 v37, v35, v37
	v_cvt_f16_f32_e32 v35, v35
	ds_write_b16 v65, v35 offset:28112
	v_fma_f32 v35, v45, s16, -v34
	v_mul_f32_e32 v35, 0x3fb8aa3b, v35
	v_exp_f32_e32 v35, v35
	s_nop 0
	v_cndmask_b32_e64 v35, 0, v35, s[2:3]
	v_add_f32_e32 v37, v35, v37
	v_cvt_f16_f32_e32 v35, v35
	ds_write_b16 v65, v35 offset:28144
	v_fma_f32 v35, v49, s16, -v34
	v_mul_f32_e32 v35, 0x3fb8aa3b, v35
	v_exp_f32_e32 v35, v35
	s_nop 0
	v_cndmask_b32_e32 v35, 0, v35, vcc
	v_add_f32_e32 v37, v35, v37
	v_cvt_f16_f32_e32 v35, v35
	ds_write_b16 v65, v35 offset:28176
	s_nop 1
	v_mov_b32_dpp v35, v37 quad_perm:[1,0,3,2] row_mask:0xf bank_mask:0xf
	s_waitcnt lgkmcnt(0)
	s_barrier
	v_add_f32_e32 v35, v37, v35
	s_nop 1
	v_mov_b32_dpp v37, v35 quad_perm:[2,3,0,1] row_mask:0xf bank_mask:0xf
	s_waitcnt lgkmcnt(0)
	v_add_f32_e32 v35, v35, v37
	s_nop 1
	v_mov_b32_dpp v37, v35 row_half_mirror row_mask:0xf bank_mask:0xf
	s_waitcnt lgkmcnt(0)
	v_add_f32_e32 v35, v35, v37
	s_nop 1
	v_mov_b32_dpp v37, v35 row_mirror row_mask:0xf bank_mask:0xf
	s_waitcnt lgkmcnt(0)
	v_add_f32_e32 v35, v35, v37
	v_fmac_f32_e32 v35, v86, v47
	ds_read_b128 v[44:47], v60 offset:27648
	ds_read_b128 v[76:79], v53 offset:18432
	s_waitcnt lgkmcnt(0)
	v_mfma_f32_16x16x32_f16 v[2:5], v[44:47], v[76:79], v[2:5]
	ds_read_b128 v[76:79], v53 offset:20736
	s_waitcnt lgkmcnt(0)
	v_mfma_f32_16x16x32_f16 v[6:9], v[44:47], v[76:79], v[6:9]
	ds_read_b128 v[76:79], v53 offset:23040
	s_waitcnt lgkmcnt(0)
	v_mfma_f32_16x16x32_f16 v[10:13], v[44:47], v[76:79], v[10:13]
	ds_read_b128 v[76:79], v53 offset:25344
	s_waitcnt lgkmcnt(0)
	v_mfma_f32_16x16x32_f16 v[14:17], v[44:47], v[76:79], v[14:17]
	ds_read_b128 v[44:47], v60 offset:27712
	ds_read_b128 v[76:79], v53 offset:18496
	s_waitcnt lgkmcnt(0)
	v_mfma_f32_16x16x32_f16 v[2:5], v[44:47], v[76:79], v[2:5]
	ds_read_b128 v[76:79], v53 offset:20800
	s_waitcnt lgkmcnt(0)
	v_mfma_f32_16x16x32_f16 v[6:9], v[44:47], v[76:79], v[6:9]
	ds_read_b128 v[76:79], v53 offset:23104
	s_waitcnt lgkmcnt(0)
	v_mfma_f32_16x16x32_f16 v[10:13], v[44:47], v[76:79], v[10:13]
	ds_read_b128 v[76:79], v53 offset:25408
	s_waitcnt lgkmcnt(0)
	v_mfma_f32_16x16x32_f16 v[14:17], v[44:47], v[76:79], v[14:17]
	s_cbranch_scc1 .LBB0_912
	s_barrier
	s_waitcnt vmcnt(2)
	ds_write_b128 v69, v[30:33] offset:9216
	ds_write_b128 v69, v[26:29] offset:9232
	s_waitcnt vmcnt(1)
	ds_write_b16 v68, v18 offset:18432
	s_waitcnt vmcnt(0)
	ds_write_b16 v70, v22 offset:19584
	ds_write_b16_d16_hi v68, v18 offset:18576
	ds_write_b16_d16_hi v68, v22 offset:19728
	ds_write_b16 v68, v19 offset:18720
	ds_write_b16 v68, v23 offset:19872
	ds_write_b16_d16_hi v68, v19 offset:18864
	ds_write_b16_d16_hi v68, v23 offset:20016
	ds_write_b16 v68, v20 offset:19008
	ds_write_b16 v68, v24 offset:20160
	ds_write_b16_d16_hi v68, v20 offset:19152
	ds_write_b16_d16_hi v68, v24 offset:20304
	ds_write_b16 v68, v21 offset:19296
	ds_write_b16 v68, v25 offset:20448
	ds_write_b16_d16_hi v68, v21 offset:19440
	ds_write_b16_d16_hi v68, v25 offset:20592
	s_waitcnt lgkmcnt(0)
	s_barrier
; DI float grp16_max(float v) { v = fmaxf(v, __shfl_xor(v, 1)); v = fmaxf(v, __shfl_xor(v, 2)); v = fmaxf(v, __shfl_xor(v, 4)); v = fmaxf(v, __shfl_xor(v, 8)); return v; }
; template <int NKB>
; DI void attn_unit(const Params& p, int l, int mode, int grp, int head, int r0, int dil, int i0, int sub_len, int W, h16* lds) {
;     ...
;     __syncthreads();
;     if (kb + 1 < NKB) ATT_PREFETCH(kb + 1);
;     f4v S[4];
; #pragma unroll
;     for (int i = 0; i < 4; ++i) S[i] = (f4v){0.f, 0.f, 0.f, 0.f};
;     mm64(Qi, Ki, S, w, lane);
;     float mx[4], al[4], rsum[4];
;     bool vm[4][4];
; #pragma unroll
;     for (int rg = 0; rg < 4; ++rg) {
;       const int row = 16 * w + 4 * q + rg;
;       float m_ = -1e30f;
; #pragma unroll
;       for (int nt = 0; nt < 4; ++nt) {
;         const int key = 16 * nt + r;
;         const int delta = row - key + W - 64 * kb;
;         const bool ok = inr && (delta >= -W) && (delta <= W);
;         vm[nt][rg] = ok;
;         float s = S[nt][rg] * 0.125f;
;         S[nt][rg] = s;
;         if (ok) m_ = fmaxf(m_, s);
;       }
;       mx[rg] = grp16_max(m_);
;     }
	ds_read_b128 v[18:21], v60
	ds_read_b128 v[22:25], v53 offset:9216
	ds_read_b128 v[26:29], v53 offset:11520
	s_waitcnt lgkmcnt(0)
	v_mfma_f32_16x16x32_f16 v[30:33], v[18:21], v[26:29], 0
	ds_read_b128 v[26:29], v53 offset:13824
	v_add_u32_e32 v37, v72, v73
	s_movk_i32 s8, 0x101
	s_waitcnt lgkmcnt(0)
	v_mfma_f32_16x16x32_f16 v[44:47], v[18:21], v[26:29], 0
	ds_read_b128 v[26:29], v53 offset:16128
	s_movk_i32 s2, 0x3f80
	v_sub_u32_e32 v40, -16, v66
	v_mfma_f32_16x16x32_f16 v[22:25], v[18:21], v[22:25], 0
	v_cmp_gt_u32_e32 vcc, s2, v51
	v_sub_u32_e32 v41, 0xffffffe0, v66
	v_sub_u32_e32 v48, 0xffffffd0, v66
	s_waitcnt lgkmcnt(0)
	v_mfma_f32_16x16x32_f16 v[56:59], v[18:21], v[26:29], 0
	ds_read_b128 v[68:71], v60 offset:64
	ds_read_b128 v[18:21], v53 offset:9280
	s_movk_i32 s95, 0x2800
	s_waitcnt lgkmcnt(0)
	v_mfma_f32_16x16x32_f16 v[26:29], v[68:71], v[18:21], v[22:25]
	ds_read_b128 v[18:21], v53 offset:11584
	s_waitcnt lgkmcnt(0)
	v_mfma_f32_16x16x32_f16 v[22:25], v[68:71], v[18:21], v[30:33]
	ds_read_b128 v[18:21], v53 offset:13888
	s_nop 1
	ds_read_b128 v[30:33], v53 offset:16192
	s_waitcnt lgkmcnt(1)
	v_mfma_f32_16x16x32_f16 v[18:21], v[68:71], v[18:21], v[44:47]
	s_nop 2
	v_sub_u32_e32 v44, v37, v66
	v_cmp_gt_u32_e64 s[2:3], s8, v44
	v_mul_f32_e32 v44, 0x3e000000, v26
	s_and_b64 s[58:59], vcc, s[2:3]
	v_max_f32_e32 v44, 0xf149f2ca, v44
	v_add_u32_e32 v45, v37, v40
	v_cndmask_b32_e64 v44, v199, v44, s[58:59]
	v_cmp_gt_u32_e64 s[2:3], s8, v45
	v_mul_f32_e32 v45, 0x3e000000, v22
	s_and_b64 s[56:57], vcc, s[2:3]
	v_max_f32_e32 v45, v44, v45
	v_cndmask_b32_e64 v44, v44, v45, s[56:57]
	v_add_u32_e32 v45, v37, v41
	v_cmp_gt_u32_e64 s[2:3], s8, v45
	v_mul_f32_e32 v45, 0x3e000000, v18
	s_and_b64 s[54:55], vcc, s[2:3]
	v_max_f32_e32 v45, v44, v45
	v_cndmask_b32_e64 v44, v44, v45, s[54:55]
	v_add_u32_e32 v45, v37, v48
	v_add_u32_e32 v46, 1, v37
	v_cmp_gt_u32_e64 s[2:3], s8, v45
	v_sub_u32_e32 v47, v46, v66
	s_and_b64 s[52:53], vcc, s[2:3]
	v_cmp_gt_u32_e64 s[2:3], s8, v47
	v_mul_f32_e32 v47, 0x3e000000, v27
	s_and_b64 s[50:51], vcc, s[2:3]
	v_max_f32_e32 v47, 0xf149f2ca, v47
	v_add_u32_e32 v49, v46, v40
	v_cndmask_b32_e64 v47, v199, v47, s[50:51]
	v_cmp_gt_u32_e64 s[2:3], s8, v49
	v_mul_f32_e32 v49, 0x3e000000, v23
	s_and_b64 s[48:49], vcc, s[2:3]
	v_max_f32_e32 v49, v47, v49
	v_cndmask_b32_e64 v47, v47, v49, s[48:49]
	v_add_u32_e32 v49, v46, v41
	v_cmp_gt_u32_e64 s[2:3], s8, v49
	v_mul_f32_e32 v49, 0x3e000000, v19
	s_and_b64 s[46:47], vcc, s[2:3]
	v_max_f32_e32 v49, v47, v49
	v_cndmask_b32_e64 v47, v47, v49, s[46:47]
	v_add_u32_e32 v46, v46, v48
	v_add_u32_e32 v49, 2, v37
	v_cmp_gt_u32_e64 s[2:3], s8, v46
	v_sub_u32_e32 v54, v49, v66
	s_and_b64 s[44:45], vcc, s[2:3]
	v_cmp_gt_u32_e64 s[2:3], s8, v54
	v_mul_f32_e32 v54, 0x3e000000, v28
	s_waitcnt lgkmcnt(0)
	v_mfma_f32_16x16x32_f16 v[30:33], v[68:71], v[30:33], v[56:59]
	s_and_b64 s[42:43], vcc, s[2:3]
	v_max_f32_e32 v54, 0xf149f2ca, v54
	v_cndmask_b32_e64 v54, v199, v54, s[42:43]
	v_add_u32_e32 v56, v49, v40
	v_cmp_gt_u32_e64 s[2:3], s8, v56
	v_mul_f32_e32 v56, 0x3e000000, v24
	s_and_b64 s[40:41], vcc, s[2:3]
	v_max_f32_e32 v56, v54, v56
	v_cndmask_b32_e64 v54, v54, v56, s[40:41]
	v_add_u32_e32 v56, v49, v41
	v_cmp_gt_u32_e64 s[2:3], s8, v56
	v_mul_f32_e32 v56, 0x3e000000, v20
	s_and_b64 s[38:39], vcc, s[2:3]
	v_max_f32_e32 v56, v54, v56
	v_cndmask_b32_e64 v54, v54, v56, s[38:39]
	v_add_u32_e32 v49, v49, v48
	v_add_u32_e32 v56, 3, v37
	v_cmp_gt_u32_e64 s[2:3], s8, v49
	v_sub_u32_e32 v57, v56, v66
	s_and_b64 s[36:37], vcc, s[2:3]
	v_cmp_gt_u32_e64 s[2:3], s8, v57
	v_mul_f32_e32 v57, 0x3e000000, v29
	v_mul_f32_e32 v45, 0x3e000000, v30
	s_and_b64 s[6:7], vcc, s[2:3]
	v_max_f32_e32 v57, 0xf149f2ca, v57
	v_add_u32_e32 v40, v56, v40
	v_max_f32_e32 v45, v44, v45
	v_cndmask_b32_e64 v57, v199, v57, s[6:7]
	v_cmp_gt_u32_e64 s[2:3], s8, v40
	v_mul_f32_e32 v40, 0x3e000000, v25
	v_cndmask_b32_e64 v44, v44, v45, s[52:53]
	s_and_b64 s[4:5], vcc, s[2:3]
	v_max_f32_e32 v40, v57, v40
	v_add_u32_e32 v41, v56, v41
	s_nop 1
	v_mov_b32_dpp v45, v44 quad_perm:[1,0,3,2] row_mask:0xf bank_mask:0xf
	v_cndmask_b32_e64 v40, v57, v40, s[4:5]
	v_cmp_gt_u32_e64 s[2:3], s8, v41
	v_mul_f32_e32 v41, 0x3e000000, v21
	s_and_b64 s[2:3], vcc, s[2:3]
	v_max_f32_e32 v41, v40, v41
	v_cndmask_b32_e64 v40, v40, v41, s[2:3]
	v_add_u32_e32 v41, v56, v48
	v_cmp_gt_u32_e64 s[60:61], s8, v41
	v_mul_f32_e32 v41, 0x3e000000, v33
	s_and_b64 vcc, vcc, s[60:61]
	v_max_f32_e32 v41, v40, v41
	s_waitcnt lgkmcnt(0)
	v_max_f32_e32 v45, v45, v45
	v_cndmask_b32_e32 v40, v40, v41, vcc
	v_max_f32_e32 v44, v44, v45
	s_nop 1
	v_mov_b32_dpp v41, v40 quad_perm:[1,0,3,2] row_mask:0xf bank_mask:0xf
	s_nop 1
	v_mov_b32_dpp v45, v44 quad_perm:[2,3,0,1] row_mask:0xf bank_mask:0xf
	v_mul_f32_e32 v46, 0x3e000000, v31
	v_max_f32_e32 v46, v47, v46
	v_cndmask_b32_e64 v46, v47, v46, s[44:45]
	s_waitcnt lgkmcnt(0)
	v_max_f32_e32 v41, v41, v41
	s_waitcnt lgkmcnt(0)
	v_max_f32_e32 v45, v45, v45
	v_max_f32_e32 v40, v40, v41
	v_max_f32_e32 v44, v44, v45
	s_nop 1
	v_mov_b32_dpp v41, v40 quad_perm:[2,3,0,1] row_mask:0xf bank_mask:0xf
	s_nop 1
	v_mov_b32_dpp v45, v44 row_half_mirror row_mask:0xf bank_mask:0xf
	s_nop 1
	v_mov_b32_dpp v47, v46 quad_perm:[1,0,3,2] row_mask:0xf bank_mask:0xf
	v_mul_f32_e32 v49, 0x3e000000, v32
	v_max_f32_e32 v49, v54, v49
	s_waitcnt lgkmcnt(0)
	v_max_f32_e32 v41, v41, v41
	s_waitcnt lgkmcnt(0)
	v_max_f32_e32 v45, v45, v45
	v_max_f32_e32 v40, v40, v41
	v_max_f32_e32 v44, v44, v45
	s_nop 1
	v_mov_b32_dpp v41, v40 row_half_mirror row_mask:0xf bank_mask:0xf
	s_nop 1
	v_mov_b32_dpp v45, v44 row_mirror row_mask:0xf bank_mask:0xf
	s_waitcnt lgkmcnt(0)
; DI float grp16_sum(float v) { v += __shfl_xor(v, 1); v += __shfl_xor(v, 2); v += __shfl_xor(v, 4); v += __shfl_xor(v, 8); return v; }
; DI float grp16_max(float v) { v = fmaxf(v, __shfl_xor(v, 1)); v = fmaxf(v, __shfl_xor(v, 2)); v = fmaxf(v, __shfl_xor(v, 4)); v = fmaxf(v, __shfl_xor(v, 8)); return v; }
; template <int NKB>
; DI void attn_unit(const Params& p, int l, int mode, int grp, int head, int r0, int dil, int i0, int sub_len, int W, h16* lds) {
;     ...
;     for (int rg = 0; rg < 4; ++rg) {
;       const int row = 16 * w + 4 * q + rg;
;       float m_ = -1e30f;
; #pragma unroll
;       for (int nt = 0; nt < 4; ++nt) {
;         const int key = 16 * nt + r;
;         const int delta = row - key + W - 64 * kb;
;         const bool ok = inr && (delta >= -W) && (delta <= W);
;         vm[nt][rg] = ok;
;         float s = S[nt][rg] * 0.125f;
;         S[nt][rg] = s;
;         if (ok) m_ = fmaxf(m_, s);
;       }
;       mx[rg] = grp16_max(m_);
;     }
; #pragma unroll
;     for (int rg = 0; rg < 4; ++rg) {
;       const float mn = fmaxf(mrow[rg], mx[rg]);
;       al[rg] = __expf(mrow[rg] - mn);
;       mrow[rg] = mn;
;       float rs_ = 0.f;
; #pragma unroll
;       for (int nt = 0; nt < 4; ++nt) {
;         float pv = vm[nt][rg] ? __expf(S[nt][rg] - mn) : 0.f;
;         rs_ += pv;
;         Pi[(16 * w + 4 * q + rg) * LDH + 16 * nt + r] = (h16)pv;
;       }
;       rsum[rg] = grp16_sum(rs_);
;       lsum[rg] = lsum[rg] * al[rg] + rsum[rg];
;     }
	v_max_f32_e32 v47, v47, v47
	v_max_f32_e32 v46, v46, v47
	s_nop 1
	v_mov_b32_dpp v47, v46 quad_perm:[2,3,0,1] row_mask:0xf bank_mask:0xf
	s_waitcnt lgkmcnt(0)
	v_max_f32_e32 v41, v41, v41
	v_max_f32_e32 v41, v40, v41
	s_waitcnt lgkmcnt(0)
	v_max3_f32 v40, v55, v44, v45
	v_fma_f32 v26, v26, s16, -v40
	v_mul_f32_e32 v26, 0x3fb8aa3b, v26
	v_exp_f32_e32 v26, v26
	v_fma_f32 v22, v22, s16, -v40
	v_mul_f32_e32 v22, 0x3fb8aa3b, v22
	v_exp_f32_e32 v22, v22
	v_cndmask_b32_e64 v26, 0, v26, s[58:59]
	v_add_f32_e32 v44, 0, v26
	v_cvt_f16_f32_e32 v26, v26
	v_fma_f32 v18, v18, s16, -v40
	v_mul_f32_e32 v18, 0x3fb8aa3b, v18
	v_cndmask_b32_e64 v22, 0, v22, s[56:57]
	v_exp_f32_e32 v18, v18
	ds_write_b16 v65, v26 offset:27648
	v_add_f32_e32 v26, v22, v44
	v_cvt_f16_f32_e32 v22, v22
	v_cndmask_b32_e64 v18, 0, v18, s[54:55]
	s_waitcnt lgkmcnt(1)
	v_max_f32_e32 v47, v47, v47
	v_max_f32_e32 v46, v46, v47
	ds_write_b16 v65, v22 offset:27680
	v_add_f32_e32 v22, v18, v26
	v_cvt_f16_f32_e32 v18, v18
	s_nop 1
	v_mov_b32_dpp v47, v46 row_half_mirror row_mask:0xf bank_mask:0xf
	v_cndmask_b32_e64 v49, v54, v49, s[36:37]
	s_nop 1
	v_mov_b32_dpp v54, v49 quad_perm:[1,0,3,2] row_mask:0xf bank_mask:0xf
	ds_write_b16 v65, v18 offset:27712
	v_fma_f32 v18, v30, s16, -v40
	v_mul_f32_e32 v18, 0x3fb8aa3b, v18
	v_exp_f32_e32 v18, v18
	s_waitcnt lgkmcnt(1)
	v_max_f32_e32 v47, v47, v47
	v_max_f32_e32 v46, v46, v47
	s_nop 1
	v_mov_b32_dpp v47, v46 row_mirror row_mask:0xf bank_mask:0xf
	v_cndmask_b32_e64 v18, 0, v18, s[52:53]
	v_add_f32_e32 v22, v18, v22
	v_cvt_f16_f32_e32 v18, v18
	s_waitcnt lgkmcnt(1)
	v_max_f32_e32 v54, v54, v54
	v_max_f32_e32 v49, v49, v54
	s_nop 1
	v_mov_b32_dpp v54, v49 quad_perm:[2,3,0,1] row_mask:0xf bank_mask:0xf
	ds_write_b16 v65, v18 offset:27744
	s_nop 1
	v_mov_b32_dpp v18, v22 quad_perm:[1,0,3,2] row_mask:0xf bank_mask:0xf
	s_nop 1
	v_mov_b32_dpp v48, v41 row_mirror row_mask:0xf bank_mask:0xf
	s_waitcnt lgkmcnt(1)
	v_max_f32_e32 v54, v54, v54
	v_max_f32_e32 v49, v49, v54
	s_waitcnt lgkmcnt(0)
	v_add_f32_e32 v18, v22, v18
	s_nop 1
	v_mov_b32_dpp v22, v18 quad_perm:[2,3,0,1] row_mask:0xf bank_mask:0xf
	s_nop 1
	v_mov_b32_dpp v54, v49 row_half_mirror row_mask:0xf bank_mask:0xf
	s_waitcnt lgkmcnt(0)
	v_add_f32_e32 v18, v18, v22
	s_nop 1
	v_mov_b32_dpp v22, v18 row_half_mirror row_mask:0xf bank_mask:0xf
	s_waitcnt lgkmcnt(0)
	v_max_f32_e32 v54, v54, v54
	v_max_f32_e32 v49, v49, v54
	s_nop 1
	v_mov_b32_dpp v54, v49 row_mirror row_mask:0xf bank_mask:0xf
	s_waitcnt lgkmcnt(0)
	v_add_f32_e32 v26, v18, v22
	v_max3_f32 v22, v42, v46, v47
	v_fma_f32 v18, v27, s16, -v22
	v_mul_f32_e32 v18, 0x3fb8aa3b, v18
	v_exp_f32_e32 v18, v18
	s_nop 1
	v_mov_b32_dpp v30, v26 row_mirror row_mask:0xf bank_mask:0xf
	v_cndmask_b32_e64 v18, 0, v18, s[50:51]
	v_add_f32_e32 v27, 0, v18
	v_cvt_f16_f32_e32 v18, v18
	ds_write_b16 v65, v18 offset:27792
	v_fma_f32 v18, v23, s16, -v22
	v_mul_f32_e32 v18, 0x3fb8aa3b, v18
	v_exp_f32_e32 v18, v18
	s_nop 0
	v_cndmask_b32_e64 v18, 0, v18, s[48:49]
	v_add_f32_e32 v23, v18, v27
	v_cvt_f16_f32_e32 v18, v18
	ds_write_b16 v65, v18 offset:27824
	v_fma_f32 v18, v19, s16, -v22
	v_mul_f32_e32 v18, 0x3fb8aa3b, v18
	v_exp_f32_e32 v18, v18
	s_nop 0
	v_cndmask_b32_e64 v18, 0, v18, s[46:47]
	v_add_f32_e32 v19, v18, v23
	v_cvt_f16_f32_e32 v18, v18
	ds_write_b16 v65, v18 offset:27856
	v_fma_f32 v18, v31, s16, -v22
	v_mul_f32_e32 v18, 0x3fb8aa3b, v18
	v_exp_f32_e32 v18, v18
	v_sub_f32_e32 v22, v42, v22
	v_mul_f32_e32 v22, 0x3fb8aa3b, v22
	v_cndmask_b32_e64 v18, 0, v18, s[44:45]
	v_add_f32_e32 v19, v18, v19
	v_cvt_f16_f32_e32 v18, v18
	ds_write_b16 v65, v18 offset:27888
	s_nop 1
	v_mov_b32_dpp v18, v19 quad_perm:[1,0,3,2] row_mask:0xf bank_mask:0xf
	s_waitcnt lgkmcnt(0)
	v_add_f32_e32 v18, v19, v18
	s_nop 1
	v_mov_b32_dpp v19, v18 quad_perm:[2,3,0,1] row_mask:0xf bank_mask:0xf
	s_waitcnt lgkmcnt(0)
	v_add_f32_e32 v18, v18, v19
	s_nop 1
	v_mov_b32_dpp v19, v18 row_half_mirror row_mask:0xf bank_mask:0xf
	s_waitcnt lgkmcnt(0)
	v_add_f32_e32 v19, v18, v19
	v_max3_f32 v18, v43, v49, v54
	v_fma_f32 v23, v28, s16, -v18
	v_mul_f32_e32 v23, 0x3fb8aa3b, v23
	v_exp_f32_e32 v23, v23
	v_fma_f32 v20, v20, s16, -v18
	v_mul_f32_e32 v20, 0x3fb8aa3b, v20
	v_exp_f32_e32 v20, v20
	v_cndmask_b32_e64 v23, 0, v23, s[42:43]
	v_add_f32_e32 v28, 0, v23
	v_cvt_f16_f32_e32 v23, v23
	v_cndmask_b32_e64 v20, 0, v20, s[38:39]
	s_nop 1
	v_mov_b32_dpp v27, v19 row_mirror row_mask:0xf bank_mask:0xf
	ds_write_b16 v65, v23 offset:27936
	v_fma_f32 v23, v24, s16, -v18
	v_mul_f32_e32 v23, 0x3fb8aa3b, v23
	v_exp_f32_e32 v23, v23
	s_waitcnt lgkmcnt(1)
	v_add_f32_e32 v19, v19, v27
	v_cndmask_b32_e64 v23, 0, v23, s[40:41]
	v_add_f32_e32 v24, v23, v28
	v_cvt_f16_f32_e32 v23, v23
	ds_write_b16 v65, v23 offset:27968
	v_add_f32_e32 v23, v20, v24
	v_cvt_f16_f32_e32 v20, v20
	ds_write_b16 v65, v20 offset:28000
	v_fma_f32 v20, v32, s16, -v18
	v_mul_f32_e32 v20, 0x3fb8aa3b, v20
	v_exp_f32_e32 v20, v20
	v_sub_f32_e32 v18, v43, v18
	v_mul_f32_e32 v18, 0x3fb8aa3b, v18
	v_cndmask_b32_e64 v20, 0, v20, s[36:37]
	v_add_f32_e32 v23, v20, v23
	v_cvt_f16_f32_e32 v20, v20
	ds_write_b16 v65, v20 offset:28032
	s_nop 1
	v_mov_b32_dpp v20, v23 quad_perm:[1,0,3,2] row_mask:0xf bank_mask:0xf
	s_waitcnt lgkmcnt(0)
	v_add_f32_e32 v20, v23, v20
	s_nop 1
	v_mov_b32_dpp v23, v20 quad_perm:[2,3,0,1] row_mask:0xf bank_mask:0xf
	s_waitcnt lgkmcnt(0)
	v_add_f32_e32 v20, v20, v23
	s_nop 1
	v_mov_b32_dpp v23, v20 row_half_mirror row_mask:0xf bank_mask:0xf
	s_waitcnt lgkmcnt(0)
; DI float grp16_sum(float v) { v += __shfl_xor(v, 1); v += __shfl_xor(v, 2); v += __shfl_xor(v, 4); v += __shfl_xor(v, 8); return v; }
; template <int NKB>
; DI void attn_unit(const Params& p, int l, int mode, int grp, int head, int r0, int dil, int i0, int sub_len, int W, h16* lds) {
;     ...
;     for (int rg = 0; rg < 4; ++rg) {
;       const float mn = fmaxf(mrow[rg], mx[rg]);
;       al[rg] = __expf(mrow[rg] - mn);
;       mrow[rg] = mn;
;       float rs_ = 0.f;
; #pragma unroll
;       for (int nt = 0; nt < 4; ++nt) {
;         float pv = vm[nt][rg] ? __expf(S[nt][rg] - mn) : 0.f;
;         rs_ += pv;
;         Pi[(16 * w + 4 * q + rg) * LDH + 16 * nt + r] = (h16)pv;
;       }
;       rsum[rg] = grp16_sum(rs_);
;       lsum[rg] = lsum[rg] * al[rg] + rsum[rg];
;     }
; #pragma unroll
;     for (int et = 0; et < 4; ++et)
; #pragma unroll
;       for (int rg = 0; rg < 4; ++rg) O[et][rg] *= al[rg];
;     __syncthreads();
;     mm64(Pi, Vt, O, w, lane);
	v_add_f32_e32 v23, v20, v23
	v_max3_f32 v20, v34, v41, v48
	v_fma_f32 v28, v29, s16, -v20
	v_mul_f32_e32 v28, 0x3fb8aa3b, v28
	v_exp_f32_e32 v28, v28
	v_fma_f32 v25, v25, s16, -v20
	v_mul_f32_e32 v25, 0x3fb8aa3b, v25
	v_exp_f32_e32 v25, v25
	v_cndmask_b32_e64 v28, 0, v28, s[6:7]
	v_cvt_f16_f32_e32 v29, v28
	v_fma_f32 v21, v21, s16, -v20
	v_mul_f32_e32 v21, 0x3fb8aa3b, v21
	v_cndmask_b32_e64 v25, 0, v25, s[4:5]
	v_exp_f32_e32 v21, v21
	ds_write_b16 v65, v29 offset:28080
	v_cvt_f16_f32_e32 v29, v25
	s_nop 1
	v_mov_b32_dpp v24, v23 row_mirror row_mask:0xf bank_mask:0xf
	v_cndmask_b32_e64 v21, 0, v21, s[2:3]
	v_add_f32_e32 v28, 0, v28
	ds_write_b16 v65, v29 offset:28112
	v_cvt_f16_f32_e32 v29, v21
	v_add_f32_e32 v25, v25, v28
	v_add_f32_e32 v25, v21, v25
	v_add_f32_e32 v28, v26, v30
	ds_write_b16 v65, v29 offset:28144
	v_fma_f32 v29, v33, s16, -v20
	v_mul_f32_e32 v29, 0x3fb8aa3b, v29
	v_exp_f32_e32 v29, v29
	v_sub_f32_e32 v20, v34, v20
	v_mul_f32_e32 v20, 0x3fb8aa3b, v20
	v_exp_f32_e32 v21, v20
	v_cndmask_b32_e32 v29, 0, v29, vcc
	v_exp_f32_e32 v20, v18
	s_waitcnt lgkmcnt(2)
	v_add_f32_e32 v18, v23, v24
	v_add_f32_e32 v24, v29, v25
	v_cvt_f16_f32_e32 v25, v29
	v_exp_f32_e32 v23, v22
	v_sub_f32_e32 v22, v55, v40
	v_mul_f32_e32 v22, 0x3fb8aa3b, v22
	ds_write_b16 v65, v25 offset:28176
	s_nop 1
	v_mov_b32_dpp v25, v24 quad_perm:[1,0,3,2] row_mask:0xf bank_mask:0xf
	v_exp_f32_e32 v22, v22
	v_fmac_f32_e32 v18, v36, v20
	v_fmac_f32_e32 v19, v39, v23
	v_pk_mul_f32 v[4:5], v[4:5], v[20:21]
	s_waitcnt lgkmcnt(0)
	v_add_f32_e32 v24, v24, v25
	s_nop 1
	v_mov_b32_dpp v25, v24 quad_perm:[2,3,0,1] row_mask:0xf bank_mask:0xf
	v_fmac_f32_e32 v28, v38, v22
	v_pk_mul_f32 v[2:3], v[2:3], v[22:23]
	v_pk_mul_f32 v[8:9], v[8:9], v[20:21]
	v_pk_mul_f32 v[6:7], v[6:7], v[22:23]
	s_waitcnt lgkmcnt(0)
	v_add_f32_e32 v24, v24, v25
	s_nop 1
	v_mov_b32_dpp v25, v24 row_half_mirror row_mask:0xf bank_mask:0xf
	v_pk_mul_f32 v[12:13], v[12:13], v[20:21]
	v_pk_mul_f32 v[10:11], v[10:11], v[22:23]
	v_pk_mul_f32 v[16:17], v[16:17], v[20:21]
	v_pk_mul_f32 v[14:15], v[14:15], v[22:23]
	s_waitcnt lgkmcnt(0)
	v_add_f32_e32 v24, v24, v25
	s_nop 1
	v_mov_b32_dpp v25, v24 row_mirror row_mask:0xf bank_mask:0xf
	s_waitcnt lgkmcnt(0)
	s_barrier
; template <int NKB>
; DI void attn_unit(const Params& p, int l, int mode, int grp, int head, int r0, int dil, int i0, int sub_len, int W, h16* lds) {
;     ...
;     mm64(Pi, Vt, O, w, lane);
;   }
; #pragma unroll
;   for (int rg = 0; rg < 4; ++rg) {
;     const int row = 16 * w + 4 * q + rg;
;     const size_t pos = (size_t)r0 + (size_t)dil * (i0 + row);
;     const float inv = 1.f / lsum[rg];
;     if (mode == 0) {
;       h16* ob = (h16*)(ws + OFF_OB) + ((size_t)grp * SEQ + pos) * 256 + head * 64;
; #pragma unroll
;       for (int et = 0; et < 4; ++et) ob[16 * et + r] = (h16)(O[et][rg] * inv);
;       if (r == 0) {
;         float* ml = (float*)(ws + OFF_MLB) + (((size_t)grp * SEQ + pos) * 4 + head) * 2;
;         ml[0] = mrow[rg]; ml[1] = lsum[rg];
;       }
;     } else {
;       h16* y = (h16*)(ws + OFF_Y) + pos * 1280 + 768 + head * 64;
; #pragma unroll
;       for (int et = 0; et < 4; ++et) y[16 * et + r] = (h16)(O[et][rg] * inv);
;     }
	v_readlane_b32 s16, v252, 3
	v_add_f32_e32 v29, v24, v25
	v_fmac_f32_e32 v29, v35, v21
	ds_read_b128 v[20:23], v60 offset:27648
	ds_read_b128 v[24:27], v53 offset:18432
	s_waitcnt lgkmcnt(0)
	v_mfma_f32_16x16x32_f16 v[2:5], v[20:23], v[24:27], v[2:5]
	ds_read_b128 v[24:27], v53 offset:20736
	v_readlane_b32 s20, v252, 7
	v_readlane_b32 s21, v252, 8
	s_waitcnt lgkmcnt(0)
	v_mfma_f32_16x16x32_f16 v[6:9], v[20:23], v[24:27], v[6:9]
	ds_read_b128 v[24:27], v53 offset:23040
	v_add_u32_e32 v30, v37, v51
	v_mov_b32_e32 v51, v0
	s_waitcnt lgkmcnt(0)
	v_mfma_f32_16x16x32_f16 v[10:13], v[20:23], v[24:27], v[10:13]
	ds_read_b128 v[24:27], v53 offset:25344
	s_mov_b64 s[6:7], 0x11a80600
	s_mov_b32 s4, 0x11a80000
	s_waitcnt lgkmcnt(0)
	v_mfma_f32_16x16x32_f16 v[14:17], v[20:23], v[24:27], v[14:17]
	ds_read_b128 v[20:23], v60 offset:27712
	ds_read_b128 v[24:27], v53 offset:18496
	v_readlane_b32 s17, v252, 4
	v_readlane_b32 s18, v252, 5
	s_waitcnt lgkmcnt(0)
	v_mfma_f32_16x16x32_f16 v[2:5], v[20:23], v[24:27], v[2:5]
	ds_read_b128 v[24:27], v53 offset:20800
	v_readlane_b32 s19, v252, 6
	v_readlane_b32 s22, v252, 9
	s_waitcnt lgkmcnt(0)
	v_mfma_f32_16x16x32_f16 v[6:9], v[20:23], v[24:27], v[6:9]
	ds_read_b128 v[24:27], v53 offset:23104
	v_readlane_b32 s23, v252, 10
	s_waitcnt lgkmcnt(0)
	v_mfma_f32_16x16x32_f16 v[10:13], v[20:23], v[24:27], v[10:13]
	ds_read_b128 v[24:27], v53 offset:25408
	s_waitcnt lgkmcnt(0)
	v_mfma_f32_16x16x32_f16 v[14:17], v[20:23], v[24:27], v[14:17]
	v_div_scale_f32 v20, s[2:3], v28, v28, 1.0
	v_rcp_f32_e32 v21, v20
	v_mov_b32_e32 v25, v0
	v_fma_f32 v22, -v20, v21, 1.0
	v_fmac_f32_e32 v21, v22, v21
	v_div_scale_f32 v22, vcc, 1.0, v28, 1.0
	v_mul_f32_e32 v23, v22, v21
	v_fma_f32 v24, -v20, v23, v22
	v_fmac_f32_e32 v23, v24, v21
	v_fma_f32 v20, -v20, v23, v22
	v_div_fmas_f32 v20, v20, v21, v23
	v_div_fixup_f32 v28, v20, v28, 1.0
	v_mov_b64_e32 v[20:21], s[20:21]
	v_mad_i64_i32 v[22:23], s[2:3], v30, s11, v[20:21]
	v_lshlrev_b32_e32 v24, 1, v52
	v_lshl_add_u64 v[22:23], v[22:23], 0, v[24:25]
	v_lshl_add_u64 v[22:23], v[22:23], 0, v[50:51]
	v_lshl_add_u64 v[26:27], v[22:23], 0, s[6:7]
	v_add_co_u32_e32 v22, vcc, s4, v22
	v_fma_mixlo_f16 v2, v28, v2, 0
	s_nop 0
	v_addc_co_u32_e32 v23, vcc, 0, v23, vcc
	global_store_short v[22:23], v2, off offset:1536
	v_fma_mixlo_f16 v2, v28, v6, 0
	global_store_short v[26:27], v2, off offset:32
	v_fma_mixlo_f16 v2, v28, v10, 0
	global_store_short v[26:27], v2, off offset:64
	v_fma_mixlo_f16 v2, v28, v14, 0
	global_store_short v[26:27], v2, off offset:96
	v_div_scale_f32 v2, s[2:3], v19, v19, 1.0
	v_rcp_f32_e32 v6, v2
	s_nop 0
	v_fma_f32 v10, -v2, v6, 1.0
	v_fmac_f32_e32 v6, v10, v6
	v_div_scale_f32 v10, vcc, 1.0, v19, 1.0
	v_mul_f32_e32 v14, v10, v6
	v_fma_f32 v22, -v2, v14, v10
	v_fmac_f32_e32 v14, v22, v6
	v_fma_f32 v2, -v2, v14, v10
	v_div_fmas_f32 v2, v2, v6, v14
	v_div_fixup_f32 v6, v2, v19, 1.0
	v_or_b32_e32 v2, 1, v30
	v_mad_i64_i32 v[22:23], s[2:3], v2, s11, v[20:21]
	v_lshl_add_u64 v[22:23], v[22:23], 0, v[24:25]
	v_fma_mixlo_f16 v10, v6, v3, 0
	v_lshl_add_u64 v[2:3], v[22:23], 0, v[50:51]
	v_lshl_add_u64 v[22:23], v[2:3], 0, s[6:7]
	v_add_co_u32_e32 v2, vcc, s4, v2
	s_nop 1
	v_addc_co_u32_e32 v3, vcc, 0, v3, vcc
	global_store_short v[2:3], v10, off offset:1536
	v_fma_mixlo_f16 v2, v6, v7, 0
	global_store_short v[22:23], v2, off offset:32
	v_fma_mixlo_f16 v2, v6, v11, 0
	global_store_short v[22:23], v2, off offset:64
	v_fma_mixlo_f16 v2, v6, v15, 0
	global_store_short v[22:23], v2, off offset:96
	v_div_scale_f32 v2, s[2:3], v18, v18, 1.0
	v_rcp_f32_e32 v3, v2
	s_nop 0
	v_fma_f32 v6, -v2, v3, 1.0
	v_fmac_f32_e32 v3, v6, v3
	v_div_scale_f32 v6, vcc, 1.0, v18, 1.0
	v_mul_f32_e32 v7, v6, v3
	v_fma_f32 v10, -v2, v7, v6
	v_fmac_f32_e32 v7, v10, v3
	v_fma_f32 v2, -v2, v7, v6
	v_div_fmas_f32 v2, v2, v3, v7
	v_div_fixup_f32 v10, v2, v18, 1.0
	v_or_b32_e32 v2, 2, v30
	v_mad_i64_i32 v[2:3], s[2:3], v2, s11, v[20:21]
	v_lshl_add_u64 v[2:3], v[2:3], 0, v[24:25]
	v_lshl_add_u64 v[2:3], v[2:3], 0, v[50:51]
	v_lshl_add_u64 v[6:7], v[2:3], 0, s[6:7]
	v_add_co_u32_e32 v2, vcc, s4, v2
	v_fma_mixlo_f16 v4, v10, v4, 0
	s_nop 0
	v_addc_co_u32_e32 v3, vcc, 0, v3, vcc
	global_store_short v[2:3], v4, off offset:1536
	v_fma_mixlo_f16 v2, v10, v8, 0
	global_store_short v[6:7], v2, off offset:32
	v_fma_mixlo_f16 v2, v10, v12, 0
	global_store_short v[6:7], v2, off offset:64
	v_fma_mixlo_f16 v2, v10, v16, 0
	global_store_short v[6:7], v2, off offset:96
	v_div_scale_f32 v2, s[2:3], v29, v29, 1.0
	v_rcp_f32_e32 v3, v2
	s_nop 0
	v_fma_f32 v4, -v2, v3, 1.0
	v_fmac_f32_e32 v3, v4, v3
	v_div_scale_f32 v4, vcc, 1.0, v29, 1.0
	v_mul_f32_e32 v6, v4, v3
	v_fma_f32 v7, -v2, v6, v4
	v_fmac_f32_e32 v6, v7, v3
	v_fma_f32 v2, -v2, v6, v4
	v_div_fmas_f32 v2, v2, v3, v6
	v_div_fixup_f32 v6, v2, v29, 1.0
	v_or_b32_e32 v2, 3, v30
	v_mad_i64_i32 v[2:3], s[2:3], v2, s11, v[20:21]
	v_lshl_add_u64 v[2:3], v[2:3], 0, v[24:25]
	v_lshl_add_u64 v[2:3], v[2:3], 0, v[50:51]
	v_fma_mixlo_f16 v7, v6, v5, 0
	v_lshl_add_u64 v[4:5], v[2:3], 0, s[6:7]
	v_add_co_u32_e32 v2, vcc, s4, v2
	s_nop 1
	v_addc_co_u32_e32 v3, vcc, 0, v3, vcc
	global_store_short v[2:3], v7, off offset:1536
	v_fma_mixlo_f16 v2, v6, v9, 0
	global_store_short v[4:5], v2, off offset:32
	v_fma_mixlo_f16 v2, v6, v13, 0
	global_store_short v[4:5], v2, off offset:64
	v_fma_mixlo_f16 v2, v6, v17, 0
	global_store_short v[4:5], v2, off offset:96

; template <bool GATHER>
; DI void gemm256_main(const h16* __restrict__ A, int lda, const int* __restrict__ idx, int m0,
;                      const h16* __restrict__ B, int ldb, int n0, int K, h16* lds, f16v (&acc)[4][2]) {
;   const int tid = otid512(), lane = tid & 63, wv = tid >> 6, wm = wv >> 2, wn = wv & 3;
;   const int lr = tid >> 1, lc = (tid & 1) * 32;
;   unsigned ao = (unsigned)(GATHER ? idx[m0 + lr] : (m0 + lr)) * (unsigned)lda + lc;
;   unsigned bo = (unsigned)(n0 + lr) * (unsigned)ldb + lc;
;   const h16* ap = A; const h16* bp = B;
;     ...
;   u4v ra[4], rb[4];
;   const int nk = K >> 6;
;   __syncthreads();
; #pragma unroll
;   for (int i = 0; i < 4; ++i) { ra[i] = *(const u4v*)(AP_ + 8 * i); rb[i] = *(const u4v*)(BP_ + 8 * i); }
;   ao += 64; bo += 64;
; #pragma unroll
;   for (int i = 0; i < 4; ++i) { *(u4v*)&lds[lr * LDH + lc + 8 * i] = ra[i]; *(u4v*)&lds[(256 + lr) * LDH + lc + 8 * i] = rb[i]; }
; #pragma unroll
;   for (int i = 0; i < 4; ++i) { ra[i] = *(const u4v*)(AP_ + 8 * i); rb[i] = *(const u4v*)(BP_ + 8 * i); }
;   ao += 64; bo += 64;
;   __syncthreads();
;   for (int kt = 0; kt < nk; ++kt) {
;     const h16* As = lds + (kt & 1) * (512 * LDH);
;     const h16* Bs = As + 256 * LDH;
;     h16* Wn = lds + ((kt & 1) ^ 1) * (512 * LDH);
;     if (kt + 1 < nk) {
; #pragma unroll
;       for (int i = 0; i < 4; ++i) { *(u4v*)&Wn[lr * LDH + lc + 8 * i] = ra[i]; *(u4v*)&Wn[(256 + lr) * LDH + lc + 8 * i] = rb[i]; }
;     }
;     if (kt + 2 < nk) {
; #pragma unroll
;       for (int i = 0; i < 4; ++i) { ra[i] = *(const u4v*)(AP_ + 8 * i); rb[i] = *(const u4v*)(BP_ + 8 * i); }
;       ao += 64; bo += 64;
;     }
; #pragma unroll
;     for (int ks = 0; ks < 4; ++ks) {
;       h8v af[4], bf[2];
; #pragma unroll
;       for (int i = 0; i < 4; ++i) af[i] = *(const h8v*)&As[(wm * 128 + i * 32 + (lane & 31)) * LDH + ks * 16 + 8 * (lane >> 5)];
; #pragma unroll
;       for (int j = 0; j < 2; ++j) bf[j] = *(const h8v*)&Bs[(wn * 64 + j * 32 + (lane & 31)) * LDH + ks * 16 + 8 * (lane >> 5)];
; #pragma unroll
;       for (int i = 0; i < 4; ++i)
; #pragma unroll
; DI void phase_gates(const Params& p, int bid, int nb, h16* lds) {
;     ...
;   for (int u = bid; u < 64 * 16; u += nb) {
;     const int m0 = (u >> 4) * 256, n0 = (u & 15) * 256;
;     f16v acc[4][2]; acc256_zero(acc);
;     gemm256_main<false>(x16, DM, nullptr, m0, wg, 1024, n0, 1024, lds, acc);
.LBB0_1246:
	v_mov_b32_e32 v1, v180
	s_and_b32 s6, s2, 0xffffff00
	s_and_b32 s5, s3, 0xf00
	v_mov_b32_e32 v177, v0
	v_ashrrev_i32_e32 v34, 1, v1
	v_lshlrev_b32_e32 v2, 5, v1
	v_and_b32_e32 v35, 32, v2
	v_add_u32_e32 v2, s6, v34
	v_add_u32_e32 v3, s5, v34
	v_lshl_or_b32 v2, v2, 10, v35
	v_lshl_or_b32 v176, v3, 10, v35
	v_mov_b32_e32 v3, v0
	v_lshl_add_u64 v[174:175], v[2:3], 1, s[20:21]
	v_lshl_add_u64 v[30:31], v[176:177], 1, s[16:17]
	s_barrier
	s_add_i32 s4, s4, s22
	s_add_i32 s3, s3, s9
	s_add_i32 s2, s2, s35
	s_cmpk_lt_i32 s4, 0x400
	v_mov_b32_e32 v130, v174
	v_mov_b32_e32 v131, v175
	v_mov_b32_e32 v202, v30
	v_mov_b32_e32 v203, v31
	v_lshrrev_b32_e32 v192, 1, v180
	v_and_b32_e32 v193, 1, v180
	v_mul_u32_u24_e32 v192, 0x90, v192
	v_lshl_add_u32 v178, v193, 6, v192
	v_add_u32_e32 v178, 16, v178
	v_add_u32_e32 v179, 0x12000, v178
	v_lshrrev_b32_e32 v192, 8, v180
	v_and_b32_e32 v194, 31, v180
	v_lshl_or_b32 v192, v192, 7, v194
	v_mul_u32_u24_e32 v192, 0x90, v192
	v_bfe_u32 v193, v180, 5, 1
	v_lshl_add_u32 v192, v193, 4, v192
	v_add_u32_e32 v215, 16, v192
	v_add_u32_e32 v212, 0x12000, v215
	v_bfe_u32 v192, v180, 6, 2
	v_lshl_or_b32 v192, v192, 6, v194
	v_mul_u32_u24_e32 v192, 0x90, v192
	v_lshl_add_u32 v192, v193, 4, v192
	v_add_u32_e32 v213, 0x9010, v192
	v_add_u32_e32 v214, 0x12000, v213
	global_load_dwordx4 v[134:137], v[130:131], off offset:0
	global_load_dwordx4 v[138:141], v[130:131], off offset:16
	global_load_dwordx4 v[142:145], v[130:131], off offset:32
	global_load_dwordx4 v[146:149], v[130:131], off offset:48
	global_load_dwordx4 v[150:153], v[202:203], off offset:0
	global_load_dwordx4 v[154:157], v[202:203], off offset:16
	global_load_dwordx4 v[158:161], v[202:203], off offset:32
	global_load_dwordx4 v[162:165], v[202:203], off offset:48
	s_waitcnt vmcnt(0)
	ds_write_b128 v178, v[134:137]
	ds_write_b128 v178, v[138:141] offset:16
	ds_write_b128 v178, v[142:145] offset:32
	ds_write_b128 v178, v[146:149] offset:48
	ds_write_b128 v178, v[150:153] offset:36864
	ds_write_b128 v178, v[154:157] offset:36880
	ds_write_b128 v178, v[158:161] offset:36896
	ds_write_b128 v178, v[162:165] offset:36912
	global_load_dwordx4 v[134:137], v[130:131], off offset:128
	global_load_dwordx4 v[138:141], v[130:131], off offset:144
	global_load_dwordx4 v[142:145], v[130:131], off offset:160
	global_load_dwordx4 v[146:149], v[130:131], off offset:176
	global_load_dwordx4 v[150:153], v[202:203], off offset:128
	global_load_dwordx4 v[154:157], v[202:203], off offset:144
	global_load_dwordx4 v[158:161], v[202:203], off offset:160
	global_load_dwordx4 v[162:165], v[202:203], off offset:176
	s_waitcnt lgkmcnt(0)
	s_barrier
	ds_read_b128 v[232:235], v213
	ds_read_b128 v[216:219], v215
	ds_read_b128 v[236:239], v213 offset:4608
	ds_read_b128 v[220:223], v215 offset:4608
	ds_read_b128 v[224:227], v215 offset:9216
	ds_read_b128 v[228:231], v215 offset:13824
	ds_read_b128 v[208:211], v213 offset:32
	ds_read_b128 v[240:243], v215 offset:32
	ds_read_b128 v[174:177], v213 offset:4640
	ds_read_b128 v[244:247], v215 offset:4640
	ds_read_b128 v[248:251], v215 offset:9248
	ds_read_b128 v[204:207], v215 offset:13856
	s_waitcnt vmcnt(4)
	ds_write_b128 v179, v[134:137]
	ds_write_b128 v179, v[138:141] offset:16
	ds_write_b128 v179, v[142:145] offset:32
	ds_write_b128 v179, v[146:149] offset:48
	global_load_dwordx4 v[134:137], v[130:131], off offset:256
	global_load_dwordx4 v[138:141], v[130:131], off offset:272
	global_load_dwordx4 v[142:145], v[130:131], off offset:288
	global_load_dwordx4 v[146:149], v[130:131], off offset:304
	s_waitcnt lgkmcnt(14)
	v_mfma_f32_32x32x16_f16 v[114:129], v[232:235], v[216:219], 0
	s_waitcnt lgkmcnt(13)
	v_mfma_f32_32x32x16_f16 v[98:113], v[236:239], v[216:219], 0
	s_waitcnt lgkmcnt(12)
	v_mfma_f32_32x32x16_f16 v[82:97], v[232:235], v[220:223], 0
	v_mfma_f32_32x32x16_f16 v[66:81], v[236:239], v[220:223], 0
	s_waitcnt lgkmcnt(11)
	v_mfma_f32_32x32x16_f16 v[50:65], v[232:235], v[224:227], 0
	v_mfma_f32_32x32x16_f16 v[34:49], v[236:239], v[224:227], 0
	s_waitcnt lgkmcnt(10)
	v_mfma_f32_32x32x16_f16 v[18:33], v[232:235], v[228:231], 0
	v_mfma_f32_32x32x16_f16 v[2:17], v[236:239], v[228:231], 0
	ds_read_b128 v[232:235], v213 offset:64
	ds_read_b128 v[216:219], v215 offset:64
	ds_read_b128 v[236:239], v213 offset:4672
	ds_read_b128 v[220:223], v215 offset:4672
	ds_read_b128 v[224:227], v215 offset:9280
	ds_read_b128 v[228:231], v215 offset:13888
	s_waitcnt vmcnt(4)
	ds_write_b128 v179, v[150:153] offset:36864
	ds_write_b128 v179, v[154:157] offset:36880
	ds_write_b128 v179, v[158:161] offset:36896
	ds_write_b128 v179, v[162:165] offset:36912
	global_load_dwordx4 v[150:153], v[202:203], off offset:256
	global_load_dwordx4 v[154:157], v[202:203], off offset:272
	global_load_dwordx4 v[158:161], v[202:203], off offset:288
	global_load_dwordx4 v[162:165], v[202:203], off offset:304
	s_waitcnt lgkmcnt(15)
	v_mfma_f32_32x32x16_f16 v[114:129], v[208:211], v[240:243], v[114:129]
	s_waitcnt lgkmcnt(15)
	v_mfma_f32_32x32x16_f16 v[98:113], v[174:177], v[240:243], v[98:113]
	s_waitcnt lgkmcnt(15)
	v_mfma_f32_32x32x16_f16 v[82:97], v[208:211], v[244:247], v[82:97]
	v_mfma_f32_32x32x16_f16 v[66:81], v[174:177], v[244:247], v[66:81]
	s_waitcnt lgkmcnt(15)
	v_mfma_f32_32x32x16_f16 v[50:65], v[208:211], v[248:251], v[50:65]
	v_mfma_f32_32x32x16_f16 v[34:49], v[174:177], v[248:251], v[34:49]
	s_waitcnt lgkmcnt(14)
	v_mfma_f32_32x32x16_f16 v[18:33], v[208:211], v[204:207], v[18:33]
	v_mfma_f32_32x32x16_f16 v[2:17], v[174:177], v[204:207], v[2:17]
	ds_read_b128 v[208:211], v213 offset:96
	ds_read_b128 v[240:243], v215 offset:96
	ds_read_b128 v[174:177], v213 offset:4704
	ds_read_b128 v[244:247], v215 offset:4704
	ds_read_b128 v[248:251], v215 offset:9312
	ds_read_b128 v[204:207], v215 offset:13920
	s_waitcnt lgkmcnt(14)
	v_mfma_f32_32x32x16_f16 v[114:129], v[232:235], v[216:219], v[114:129]
	s_waitcnt lgkmcnt(13)
	v_mfma_f32_32x32x16_f16 v[98:113], v[236:239], v[216:219], v[98:113]
	s_waitcnt lgkmcnt(12)
	v_mfma_f32_32x32x16_f16 v[82:97], v[232:235], v[220:223], v[82:97]
	v_mfma_f32_32x32x16_f16 v[66:81], v[236:239], v[220:223], v[66:81]
	s_waitcnt lgkmcnt(11)
	v_mfma_f32_32x32x16_f16 v[50:65], v[232:235], v[224:227], v[50:65]
	v_mfma_f32_32x32x16_f16 v[34:49], v[236:239], v[224:227], v[34:49]
	s_waitcnt lgkmcnt(10)
	v_mfma_f32_32x32x16_f16 v[18:33], v[232:235], v[228:231], v[18:33]
	v_mfma_f32_32x32x16_f16 v[2:17], v[236:239], v[228:231], v[2:17]
	s_waitcnt lgkmcnt(0)
	s_barrier
; DI f16v mfma32(h8v a, h8v b, f16v c) { return __builtin_amdgcn_mfma_f32_32x32x16_f16(a, b, c, 0, 0, 0); }
; template <bool GATHER>
; DI void gemm256_main(const h16* __restrict__ A, int lda, const int* __restrict__ idx, int m0,
;                      const h16* __restrict__ B, int ldb, int n0, int K, h16* lds, f16v (&acc)[4][2]) {
;     ...
;   for (int kt = 0; kt < nk; ++kt) {
;     const h16* As = lds + (kt & 1) * (512 * LDH);
;     const h16* Bs = As + 256 * LDH;
;     h16* Wn = lds + ((kt & 1) ^ 1) * (512 * LDH);
;     if (kt + 1 < nk) {
; #pragma unroll
;       for (int i = 0; i < 4; ++i) { *(u4v*)&Wn[lr * LDH + lc + 8 * i] = ra[i]; *(u4v*)&Wn[(256 + lr) * LDH + lc + 8 * i] = rb[i]; }
;     }
;     if (kt + 2 < nk) {
; #pragma unroll
;       for (int i = 0; i < 4; ++i) { ra[i] = *(const u4v*)(AP_ + 8 * i); rb[i] = *(const u4v*)(BP_ + 8 * i); }
;       ao += 64; bo += 64;
;     }
; #pragma unroll
;     for (int ks = 0; ks < 4; ++ks) {
;       h8v af[4], bf[2];
; #pragma unroll
;       for (int i = 0; i < 4; ++i) af[i] = *(const h8v*)&As[(wm * 128 + i * 32 + (lane & 31)) * LDH + ks * 16 + 8 * (lane >> 5)];
; #pragma unroll
;       for (int j = 0; j < 2; ++j) bf[j] = *(const h8v*)&Bs[(wn * 64 + j * 32 + (lane & 31)) * LDH + ks * 16 + 8 * (lane >> 5)];
; #pragma unroll
;       for (int i = 0; i < 4; ++i)
; #pragma unroll
;         for (int j = 0; j < 2; ++j) acc[i][j] = mfma32(bf[j], af[i], acc[i][j]);
;     }
;     __syncthreads();
	ds_read_b128 v[232:235], v214
	ds_read_b128 v[216:219], v212
	ds_read_b128 v[236:239], v214 offset:4608
	ds_read_b128 v[220:223], v212 offset:4608
	ds_read_b128 v[224:227], v212 offset:9216
	ds_read_b128 v[228:231], v212 offset:13824
	v_mfma_f32_32x32x16_f16 v[114:129], v[208:211], v[240:243], v[114:129]
	v_mfma_f32_32x32x16_f16 v[98:113], v[174:177], v[240:243], v[98:113]
	v_mfma_f32_32x32x16_f16 v[82:97], v[208:211], v[244:247], v[82:97]
	v_mfma_f32_32x32x16_f16 v[66:81], v[174:177], v[244:247], v[66:81]
	v_mfma_f32_32x32x16_f16 v[50:65], v[208:211], v[248:251], v[50:65]
	v_mfma_f32_32x32x16_f16 v[34:49], v[174:177], v[248:251], v[34:49]
	v_mfma_f32_32x32x16_f16 v[18:33], v[208:211], v[204:207], v[18:33]
	v_mfma_f32_32x32x16_f16 v[2:17], v[174:177], v[204:207], v[2:17]
	ds_read_b128 v[208:211], v214 offset:32
	ds_read_b128 v[240:243], v212 offset:32
	ds_read_b128 v[174:177], v214 offset:4640
	ds_read_b128 v[244:247], v212 offset:4640
	ds_read_b128 v[248:251], v212 offset:9248
	ds_read_b128 v[204:207], v212 offset:13856
	s_waitcnt vmcnt(4)
	ds_write_b128 v178, v[134:137]
	ds_write_b128 v178, v[138:141] offset:16
	ds_write_b128 v178, v[142:145] offset:32
	ds_write_b128 v178, v[146:149] offset:48
	global_load_dwordx4 v[134:137], v[130:131], off offset:384
	global_load_dwordx4 v[138:141], v[130:131], off offset:400
	global_load_dwordx4 v[142:145], v[130:131], off offset:416
	global_load_dwordx4 v[146:149], v[130:131], off offset:432
	s_waitcnt lgkmcnt(14)
	v_mfma_f32_32x32x16_f16 v[114:129], v[232:235], v[216:219], v[114:129]
	s_waitcnt lgkmcnt(13)
	v_mfma_f32_32x32x16_f16 v[98:113], v[236:239], v[216:219], v[98:113]
	s_waitcnt lgkmcnt(12)
	v_mfma_f32_32x32x16_f16 v[82:97], v[232:235], v[220:223], v[82:97]
	v_mfma_f32_32x32x16_f16 v[66:81], v[236:239], v[220:223], v[66:81]
	s_waitcnt lgkmcnt(11)
	v_mfma_f32_32x32x16_f16 v[50:65], v[232:235], v[224:227], v[50:65]
	v_mfma_f32_32x32x16_f16 v[34:49], v[236:239], v[224:227], v[34:49]
	s_waitcnt lgkmcnt(10)
	v_mfma_f32_32x32x16_f16 v[18:33], v[232:235], v[228:231], v[18:33]
	v_mfma_f32_32x32x16_f16 v[2:17], v[236:239], v[228:231], v[2:17]
	ds_read_b128 v[232:235], v214 offset:64
	ds_read_b128 v[216:219], v212 offset:64
	ds_read_b128 v[236:239], v214 offset:4672
	ds_read_b128 v[220:223], v212 offset:4672
	ds_read_b128 v[224:227], v212 offset:9280
	ds_read_b128 v[228:231], v212 offset:13888
	s_waitcnt vmcnt(4)
	ds_write_b128 v178, v[150:153] offset:36864
	ds_write_b128 v178, v[154:157] offset:36880
	ds_write_b128 v178, v[158:161] offset:36896
	ds_write_b128 v178, v[162:165] offset:36912
	global_load_dwordx4 v[150:153], v[202:203], off offset:384
	global_load_dwordx4 v[154:157], v[202:203], off offset:400
	global_load_dwordx4 v[158:161], v[202:203], off offset:416
	global_load_dwordx4 v[162:165], v[202:203], off offset:432
	s_waitcnt lgkmcnt(15)
	v_mfma_f32_32x32x16_f16 v[114:129], v[208:211], v[240:243], v[114:129]
	s_waitcnt lgkmcnt(15)
	v_mfma_f32_32x32x16_f16 v[98:113], v[174:177], v[240:243], v[98:113]
	s_waitcnt lgkmcnt(15)
	v_mfma_f32_32x32x16_f16 v[82:97], v[208:211], v[244:247], v[82:97]
	v_mfma_f32_32x32x16_f16 v[66:81], v[174:177], v[244:247], v[66:81]
	s_waitcnt lgkmcnt(15)
	v_mfma_f32_32x32x16_f16 v[50:65], v[208:211], v[248:251], v[50:65]
	v_mfma_f32_32x32x16_f16 v[34:49], v[174:177], v[248:251], v[34:49]
	s_waitcnt lgkmcnt(14)
	v_mfma_f32_32x32x16_f16 v[18:33], v[208:211], v[204:207], v[18:33]
	v_mfma_f32_32x32x16_f16 v[2:17], v[174:177], v[204:207], v[2:17]
	ds_read_b128 v[208:211], v214 offset:96
	ds_read_b128 v[240:243], v212 offset:96
	ds_read_b128 v[174:177], v214 offset:4704
	ds_read_b128 v[244:247], v212 offset:4704
	ds_read_b128 v[248:251], v212 offset:9312
	ds_read_b128 v[204:207], v212 offset:13920
	s_waitcnt lgkmcnt(14)
	v_mfma_f32_32x32x16_f16 v[114:129], v[232:235], v[216:219], v[114:129]
	s_waitcnt lgkmcnt(13)
	v_mfma_f32_32x32x16_f16 v[98:113], v[236:239], v[216:219], v[98:113]
	s_waitcnt lgkmcnt(12)
	v_mfma_f32_32x32x16_f16 v[82:97], v[232:235], v[220:223], v[82:97]
	v_mfma_f32_32x32x16_f16 v[66:81], v[236:239], v[220:223], v[66:81]
	s_waitcnt lgkmcnt(11)
	v_mfma_f32_32x32x16_f16 v[50:65], v[232:235], v[224:227], v[50:65]
	v_mfma_f32_32x32x16_f16 v[34:49], v[236:239], v[224:227], v[34:49]
	s_waitcnt lgkmcnt(10)
	v_mfma_f32_32x32x16_f16 v[18:33], v[232:235], v[228:231], v[18:33]
	v_mfma_f32_32x32x16_f16 v[2:17], v[236:239], v[228:231], v[2:17]
	s_waitcnt lgkmcnt(0)
	s_barrier
; DI f16v mfma32(h8v a, h8v b, f16v c) { return __builtin_amdgcn_mfma_f32_32x32x16_f16(a, b, c, 0, 0, 0); }
; template <bool GATHER>
; DI void gemm256_main(const h16* __restrict__ A, int lda, const int* __restrict__ idx, int m0,
;                      const h16* __restrict__ B, int ldb, int n0, int K, h16* lds, f16v (&acc)[4][2]) {
;     ...
;   for (int kt = 0; kt < nk; ++kt) {
;     const h16* As = lds + (kt & 1) * (512 * LDH);
;     const h16* Bs = As + 256 * LDH;
;     h16* Wn = lds + ((kt & 1) ^ 1) * (512 * LDH);
;     if (kt + 1 < nk) {
; #pragma unroll
;       for (int i = 0; i < 4; ++i) { *(u4v*)&Wn[lr * LDH + lc + 8 * i] = ra[i]; *(u4v*)&Wn[(256 + lr) * LDH + lc + 8 * i] = rb[i]; }
;     }
;     if (kt + 2 < nk) {
; #pragma unroll
;       for (int i = 0; i < 4; ++i) { ra[i] = *(const u4v*)(AP_ + 8 * i); rb[i] = *(const u4v*)(BP_ + 8 * i); }
;       ao += 64; bo += 64;
;     }
; #pragma unroll
;     for (int ks = 0; ks < 4; ++ks) {
;       h8v af[4], bf[2];
; #pragma unroll
;       for (int i = 0; i < 4; ++i) af[i] = *(const h8v*)&As[(wm * 128 + i * 32 + (lane & 31)) * LDH + ks * 16 + 8 * (lane >> 5)];
; #pragma unroll
;       for (int j = 0; j < 2; ++j) bf[j] = *(const h8v*)&Bs[(wn * 64 + j * 32 + (lane & 31)) * LDH + ks * 16 + 8 * (lane >> 5)];
; #pragma unroll
;       for (int i = 0; i < 4; ++i)
; #pragma unroll
;         for (int j = 0; j < 2; ++j) acc[i][j] = mfma32(bf[j], af[i], acc[i][j]);
;     }
;     __syncthreads();
	ds_read_b128 v[232:235], v213
	ds_read_b128 v[216:219], v215
	ds_read_b128 v[236:239], v213 offset:4608
	ds_read_b128 v[220:223], v215 offset:4608
	ds_read_b128 v[224:227], v215 offset:9216
	ds_read_b128 v[228:231], v215 offset:13824
	v_mfma_f32_32x32x16_f16 v[114:129], v[208:211], v[240:243], v[114:129]
	v_mfma_f32_32x32x16_f16 v[98:113], v[174:177], v[240:243], v[98:113]
	v_mfma_f32_32x32x16_f16 v[82:97], v[208:211], v[244:247], v[82:97]
	v_mfma_f32_32x32x16_f16 v[66:81], v[174:177], v[244:247], v[66:81]
	v_mfma_f32_32x32x16_f16 v[50:65], v[208:211], v[248:251], v[50:65]
	v_mfma_f32_32x32x16_f16 v[34:49], v[174:177], v[248:251], v[34:49]
	v_mfma_f32_32x32x16_f16 v[18:33], v[208:211], v[204:207], v[18:33]
	v_mfma_f32_32x32x16_f16 v[2:17], v[174:177], v[204:207], v[2:17]
	ds_read_b128 v[208:211], v213 offset:32
	ds_read_b128 v[240:243], v215 offset:32
	ds_read_b128 v[174:177], v213 offset:4640
	ds_read_b128 v[244:247], v215 offset:4640
	ds_read_b128 v[248:251], v215 offset:9248
	ds_read_b128 v[204:207], v215 offset:13856
	s_waitcnt vmcnt(4)
	ds_write_b128 v179, v[134:137]
	ds_write_b128 v179, v[138:141] offset:16
	ds_write_b128 v179, v[142:145] offset:32
	ds_write_b128 v179, v[146:149] offset:48
	global_load_dwordx4 v[134:137], v[130:131], off offset:512
	global_load_dwordx4 v[138:141], v[130:131], off offset:528
	global_load_dwordx4 v[142:145], v[130:131], off offset:544
	global_load_dwordx4 v[146:149], v[130:131], off offset:560
	s_waitcnt lgkmcnt(14)
	v_mfma_f32_32x32x16_f16 v[114:129], v[232:235], v[216:219], v[114:129]
	s_waitcnt lgkmcnt(13)
	v_mfma_f32_32x32x16_f16 v[98:113], v[236:239], v[216:219], v[98:113]
	s_waitcnt lgkmcnt(12)
	v_mfma_f32_32x32x16_f16 v[82:97], v[232:235], v[220:223], v[82:97]
	v_mfma_f32_32x32x16_f16 v[66:81], v[236:239], v[220:223], v[66:81]
	s_waitcnt lgkmcnt(11)
	v_mfma_f32_32x32x16_f16 v[50:65], v[232:235], v[224:227], v[50:65]
	v_mfma_f32_32x32x16_f16 v[34:49], v[236:239], v[224:227], v[34:49]
	s_waitcnt lgkmcnt(10)
	v_mfma_f32_32x32x16_f16 v[18:33], v[232:235], v[228:231], v[18:33]
	v_mfma_f32_32x32x16_f16 v[2:17], v[236:239], v[228:231], v[2:17]
	ds_read_b128 v[232:235], v213 offset:64
	ds_read_b128 v[216:219], v215 offset:64
	ds_read_b128 v[236:239], v213 offset:4672
	ds_read_b128 v[220:223], v215 offset:4672
	ds_read_b128 v[224:227], v215 offset:9280
	ds_read_b128 v[228:231], v215 offset:13888
	s_waitcnt vmcnt(4)
	ds_write_b128 v179, v[150:153] offset:36864
	ds_write_b128 v179, v[154:157] offset:36880
	ds_write_b128 v179, v[158:161] offset:36896
	ds_write_b128 v179, v[162:165] offset:36912
	global_load_dwordx4 v[150:153], v[202:203], off offset:512
	global_load_dwordx4 v[154:157], v[202:203], off offset:528
	global_load_dwordx4 v[158:161], v[202:203], off offset:544
	global_load_dwordx4 v[162:165], v[202:203], off offset:560
	s_waitcnt lgkmcnt(15)
	v_mfma_f32_32x32x16_f16 v[114:129], v[208:211], v[240:243], v[114:129]
	s_waitcnt lgkmcnt(15)
	v_mfma_f32_32x32x16_f16 v[98:113], v[174:177], v[240:243], v[98:113]
	s_waitcnt lgkmcnt(15)
	v_mfma_f32_32x32x16_f16 v[82:97], v[208:211], v[244:247], v[82:97]
	v_mfma_f32_32x32x16_f16 v[66:81], v[174:177], v[244:247], v[66:81]
	s_waitcnt lgkmcnt(15)
	v_mfma_f32_32x32x16_f16 v[50:65], v[208:211], v[248:251], v[50:65]
	v_mfma_f32_32x32x16_f16 v[34:49], v[174:177], v[248:251], v[34:49]
	s_waitcnt lgkmcnt(14)
	v_mfma_f32_32x32x16_f16 v[18:33], v[208:211], v[204:207], v[18:33]
	v_mfma_f32_32x32x16_f16 v[2:17], v[174:177], v[204:207], v[2:17]
	ds_read_b128 v[208:211], v213 offset:96
	ds_read_b128 v[240:243], v215 offset:96
	ds_read_b128 v[174:177], v213 offset:4704
	ds_read_b128 v[244:247], v215 offset:4704
	ds_read_b128 v[248:251], v215 offset:9312
	ds_read_b128 v[204:207], v215 offset:13920
	s_waitcnt lgkmcnt(14)
	v_mfma_f32_32x32x16_f16 v[114:129], v[232:235], v[216:219], v[114:129]
	s_waitcnt lgkmcnt(13)
	v_mfma_f32_32x32x16_f16 v[98:113], v[236:239], v[216:219], v[98:113]
	s_waitcnt lgkmcnt(12)
	v_mfma_f32_32x32x16_f16 v[82:97], v[232:235], v[220:223], v[82:97]
	v_mfma_f32_32x32x16_f16 v[66:81], v[236:239], v[220:223], v[66:81]
	s_waitcnt lgkmcnt(11)
	v_mfma_f32_32x32x16_f16 v[50:65], v[232:235], v[224:227], v[50:65]
	v_mfma_f32_32x32x16_f16 v[34:49], v[236:239], v[224:227], v[34:49]
	s_waitcnt lgkmcnt(10)
	v_mfma_f32_32x32x16_f16 v[18:33], v[232:235], v[228:231], v[18:33]
	v_mfma_f32_32x32x16_f16 v[2:17], v[236:239], v[228:231], v[2:17]
	s_waitcnt lgkmcnt(0)
	s_barrier
; DI f16v mfma32(h8v a, h8v b, f16v c) { return __builtin_amdgcn_mfma_f32_32x32x16_f16(a, b, c, 0, 0, 0); }
; template <bool GATHER>
; DI void gemm256_main(const h16* __restrict__ A, int lda, const int* __restrict__ idx, int m0,
;                      const h16* __restrict__ B, int ldb, int n0, int K, h16* lds, f16v (&acc)[4][2]) {
;     ...
;   for (int kt = 0; kt < nk; ++kt) {
;     const h16* As = lds + (kt & 1) * (512 * LDH);
;     const h16* Bs = As + 256 * LDH;
;     h16* Wn = lds + ((kt & 1) ^ 1) * (512 * LDH);
;     if (kt + 1 < nk) {
; #pragma unroll
;       for (int i = 0; i < 4; ++i) { *(u4v*)&Wn[lr * LDH + lc + 8 * i] = ra[i]; *(u4v*)&Wn[(256 + lr) * LDH + lc + 8 * i] = rb[i]; }
;     }
;     if (kt + 2 < nk) {
; #pragma unroll
;       for (int i = 0; i < 4; ++i) { ra[i] = *(const u4v*)(AP_ + 8 * i); rb[i] = *(const u4v*)(BP_ + 8 * i); }
;       ao += 64; bo += 64;
;     }
; #pragma unroll
;     for (int ks = 0; ks < 4; ++ks) {
;       h8v af[4], bf[2];
; #pragma unroll
;       for (int i = 0; i < 4; ++i) af[i] = *(const h8v*)&As[(wm * 128 + i * 32 + (lane & 31)) * LDH + ks * 16 + 8 * (lane >> 5)];
; #pragma unroll
;       for (int j = 0; j < 2; ++j) bf[j] = *(const h8v*)&Bs[(wn * 64 + j * 32 + (lane & 31)) * LDH + ks * 16 + 8 * (lane >> 5)];
; #pragma unroll
;       for (int i = 0; i < 4; ++i)
; #pragma unroll
;         for (int j = 0; j < 2; ++j) acc[i][j] = mfma32(bf[j], af[i], acc[i][j]);
;     }
;     __syncthreads();
	ds_read_b128 v[232:235], v214
	ds_read_b128 v[216:219], v212
	ds_read_b128 v[236:239], v214 offset:4608
	ds_read_b128 v[220:223], v212 offset:4608
	ds_read_b128 v[224:227], v212 offset:9216
	ds_read_b128 v[228:231], v212 offset:13824
	v_mfma_f32_32x32x16_f16 v[114:129], v[208:211], v[240:243], v[114:129]
	v_mfma_f32_32x32x16_f16 v[98:113], v[174:177], v[240:243], v[98:113]
	v_mfma_f32_32x32x16_f16 v[82:97], v[208:211], v[244:247], v[82:97]
	v_mfma_f32_32x32x16_f16 v[66:81], v[174:177], v[244:247], v[66:81]
	v_mfma_f32_32x32x16_f16 v[50:65], v[208:211], v[248:251], v[50:65]
	v_mfma_f32_32x32x16_f16 v[34:49], v[174:177], v[248:251], v[34:49]
	v_mfma_f32_32x32x16_f16 v[18:33], v[208:211], v[204:207], v[18:33]
	v_mfma_f32_32x32x16_f16 v[2:17], v[174:177], v[204:207], v[2:17]
	ds_read_b128 v[208:211], v214 offset:32
	ds_read_b128 v[240:243], v212 offset:32
	ds_read_b128 v[174:177], v214 offset:4640
	ds_read_b128 v[244:247], v212 offset:4640
	ds_read_b128 v[248:251], v212 offset:9248
	ds_read_b128 v[204:207], v212 offset:13856
	s_waitcnt vmcnt(4)
	ds_write_b128 v178, v[134:137]
	ds_write_b128 v178, v[138:141] offset:16
	ds_write_b128 v178, v[142:145] offset:32
	ds_write_b128 v178, v[146:149] offset:48
	global_load_dwordx4 v[134:137], v[130:131], off offset:640
	global_load_dwordx4 v[138:141], v[130:131], off offset:656
	global_load_dwordx4 v[142:145], v[130:131], off offset:672
	global_load_dwordx4 v[146:149], v[130:131], off offset:688
	s_waitcnt lgkmcnt(14)
	v_mfma_f32_32x32x16_f16 v[114:129], v[232:235], v[216:219], v[114:129]
	s_waitcnt lgkmcnt(13)
	v_mfma_f32_32x32x16_f16 v[98:113], v[236:239], v[216:219], v[98:113]
	s_waitcnt lgkmcnt(12)
	v_mfma_f32_32x32x16_f16 v[82:97], v[232:235], v[220:223], v[82:97]
	v_mfma_f32_32x32x16_f16 v[66:81], v[236:239], v[220:223], v[66:81]
	s_waitcnt lgkmcnt(11)
	v_mfma_f32_32x32x16_f16 v[50:65], v[232:235], v[224:227], v[50:65]
	v_mfma_f32_32x32x16_f16 v[34:49], v[236:239], v[224:227], v[34:49]
	s_waitcnt lgkmcnt(10)
	v_mfma_f32_32x32x16_f16 v[18:33], v[232:235], v[228:231], v[18:33]
	v_mfma_f32_32x32x16_f16 v[2:17], v[236:239], v[228:231], v[2:17]
	ds_read_b128 v[232:235], v214 offset:64
	ds_read_b128 v[216:219], v212 offset:64
	ds_read_b128 v[236:239], v214 offset:4672
	ds_read_b128 v[220:223], v212 offset:4672
	ds_read_b128 v[224:227], v212 offset:9280
	ds_read_b128 v[228:231], v212 offset:13888
	s_waitcnt vmcnt(4)
	ds_write_b128 v178, v[150:153] offset:36864
	ds_write_b128 v178, v[154:157] offset:36880
	ds_write_b128 v178, v[158:161] offset:36896
	ds_write_b128 v178, v[162:165] offset:36912
	global_load_dwordx4 v[150:153], v[202:203], off offset:640
	global_load_dwordx4 v[154:157], v[202:203], off offset:656
	global_load_dwordx4 v[158:161], v[202:203], off offset:672
	global_load_dwordx4 v[162:165], v[202:203], off offset:688
	s_waitcnt lgkmcnt(15)
	v_mfma_f32_32x32x16_f16 v[114:129], v[208:211], v[240:243], v[114:129]
	s_waitcnt lgkmcnt(15)
	v_mfma_f32_32x32x16_f16 v[98:113], v[174:177], v[240:243], v[98:113]
	s_waitcnt lgkmcnt(15)
	v_mfma_f32_32x32x16_f16 v[82:97], v[208:211], v[244:247], v[82:97]
	v_mfma_f32_32x32x16_f16 v[66:81], v[174:177], v[244:247], v[66:81]
	s_waitcnt lgkmcnt(15)
	v_mfma_f32_32x32x16_f16 v[50:65], v[208:211], v[248:251], v[50:65]
	v_mfma_f32_32x32x16_f16 v[34:49], v[174:177], v[248:251], v[34:49]
	s_waitcnt lgkmcnt(14)
	v_mfma_f32_32x32x16_f16 v[18:33], v[208:211], v[204:207], v[18:33]
	v_mfma_f32_32x32x16_f16 v[2:17], v[174:177], v[204:207], v[2:17]
	ds_read_b128 v[208:211], v214 offset:96
	ds_read_b128 v[240:243], v212 offset:96
	ds_read_b128 v[174:177], v214 offset:4704
	ds_read_b128 v[244:247], v212 offset:4704
	ds_read_b128 v[248:251], v212 offset:9312
	ds_read_b128 v[204:207], v212 offset:13920
	s_waitcnt lgkmcnt(14)
	v_mfma_f32_32x32x16_f16 v[114:129], v[232:235], v[216:219], v[114:129]
	s_waitcnt lgkmcnt(13)
	v_mfma_f32_32x32x16_f16 v[98:113], v[236:239], v[216:219], v[98:113]
	s_waitcnt lgkmcnt(12)
	v_mfma_f32_32x32x16_f16 v[82:97], v[232:235], v[220:223], v[82:97]
	v_mfma_f32_32x32x16_f16 v[66:81], v[236:239], v[220:223], v[66:81]
	s_waitcnt lgkmcnt(11)
	v_mfma_f32_32x32x16_f16 v[50:65], v[232:235], v[224:227], v[50:65]
	v_mfma_f32_32x32x16_f16 v[34:49], v[236:239], v[224:227], v[34:49]
	s_waitcnt lgkmcnt(10)
	v_mfma_f32_32x32x16_f16 v[18:33], v[232:235], v[228:231], v[18:33]
	v_mfma_f32_32x32x16_f16 v[2:17], v[236:239], v[228:231], v[2:17]
	s_waitcnt lgkmcnt(0)
	s_barrier
; DI f16v mfma32(h8v a, h8v b, f16v c) { return __builtin_amdgcn_mfma_f32_32x32x16_f16(a, b, c, 0, 0, 0); }
; template <bool GATHER>
; DI void gemm256_main(const h16* __restrict__ A, int lda, const int* __restrict__ idx, int m0,
;                      const h16* __restrict__ B, int ldb, int n0, int K, h16* lds, f16v (&acc)[4][2]) {
;     ...
;   for (int kt = 0; kt < nk; ++kt) {
;     const h16* As = lds + (kt & 1) * (512 * LDH);
;     const h16* Bs = As + 256 * LDH;
;     h16* Wn = lds + ((kt & 1) ^ 1) * (512 * LDH);
;     if (kt + 1 < nk) {
; #pragma unroll
;       for (int i = 0; i < 4; ++i) { *(u4v*)&Wn[lr * LDH + lc + 8 * i] = ra[i]; *(u4v*)&Wn[(256 + lr) * LDH + lc + 8 * i] = rb[i]; }
;     }
;     if (kt + 2 < nk) {
; #pragma unroll
;       for (int i = 0; i < 4; ++i) { ra[i] = *(const u4v*)(AP_ + 8 * i); rb[i] = *(const u4v*)(BP_ + 8 * i); }
;       ao += 64; bo += 64;
;     }
; #pragma unroll
;     for (int ks = 0; ks < 4; ++ks) {
;       h8v af[4], bf[2];
; #pragma unroll
;       for (int i = 0; i < 4; ++i) af[i] = *(const h8v*)&As[(wm * 128 + i * 32 + (lane & 31)) * LDH + ks * 16 + 8 * (lane >> 5)];
; #pragma unroll
;       for (int j = 0; j < 2; ++j) bf[j] = *(const h8v*)&Bs[(wn * 64 + j * 32 + (lane & 31)) * LDH + ks * 16 + 8 * (lane >> 5)];
; #pragma unroll
;       for (int i = 0; i < 4; ++i)
; #pragma unroll
;         for (int j = 0; j < 2; ++j) acc[i][j] = mfma32(bf[j], af[i], acc[i][j]);
;     }
;     __syncthreads();
	ds_read_b128 v[232:235], v213
	ds_read_b128 v[216:219], v215
	ds_read_b128 v[236:239], v213 offset:4608
	ds_read_b128 v[220:223], v215 offset:4608
	ds_read_b128 v[224:227], v215 offset:9216
	ds_read_b128 v[228:231], v215 offset:13824
	v_mfma_f32_32x32x16_f16 v[114:129], v[208:211], v[240:243], v[114:129]
	v_mfma_f32_32x32x16_f16 v[98:113], v[174:177], v[240:243], v[98:113]
	v_mfma_f32_32x32x16_f16 v[82:97], v[208:211], v[244:247], v[82:97]
	v_mfma_f32_32x32x16_f16 v[66:81], v[174:177], v[244:247], v[66:81]
	v_mfma_f32_32x32x16_f16 v[50:65], v[208:211], v[248:251], v[50:65]
	v_mfma_f32_32x32x16_f16 v[34:49], v[174:177], v[248:251], v[34:49]
	v_mfma_f32_32x32x16_f16 v[18:33], v[208:211], v[204:207], v[18:33]
	v_mfma_f32_32x32x16_f16 v[2:17], v[174:177], v[204:207], v[2:17]
	ds_read_b128 v[208:211], v213 offset:32
	ds_read_b128 v[240:243], v215 offset:32
	ds_read_b128 v[174:177], v213 offset:4640
	ds_read_b128 v[244:247], v215 offset:4640
	ds_read_b128 v[248:251], v215 offset:9248
	ds_read_b128 v[204:207], v215 offset:13856
	s_waitcnt vmcnt(4)
	ds_write_b128 v179, v[134:137]
	ds_write_b128 v179, v[138:141] offset:16
	ds_write_b128 v179, v[142:145] offset:32
	ds_write_b128 v179, v[146:149] offset:48
	global_load_dwordx4 v[134:137], v[130:131], off offset:768
	global_load_dwordx4 v[138:141], v[130:131], off offset:784
	global_load_dwordx4 v[142:145], v[130:131], off offset:800
	global_load_dwordx4 v[146:149], v[130:131], off offset:816
	s_waitcnt lgkmcnt(14)
	v_mfma_f32_32x32x16_f16 v[114:129], v[232:235], v[216:219], v[114:129]
	s_waitcnt lgkmcnt(13)
	v_mfma_f32_32x32x16_f16 v[98:113], v[236:239], v[216:219], v[98:113]
	s_waitcnt lgkmcnt(12)
	v_mfma_f32_32x32x16_f16 v[82:97], v[232:235], v[220:223], v[82:97]
	v_mfma_f32_32x32x16_f16 v[66:81], v[236:239], v[220:223], v[66:81]
	s_waitcnt lgkmcnt(11)
	v_mfma_f32_32x32x16_f16 v[50:65], v[232:235], v[224:227], v[50:65]
	v_mfma_f32_32x32x16_f16 v[34:49], v[236:239], v[224:227], v[34:49]
	s_waitcnt lgkmcnt(10)
	v_mfma_f32_32x32x16_f16 v[18:33], v[232:235], v[228:231], v[18:33]
	v_mfma_f32_32x32x16_f16 v[2:17], v[236:239], v[228:231], v[2:17]
	ds_read_b128 v[232:235], v213 offset:64
	ds_read_b128 v[216:219], v215 offset:64
	ds_read_b128 v[236:239], v213 offset:4672
	ds_read_b128 v[220:223], v215 offset:4672
	ds_read_b128 v[224:227], v215 offset:9280
	ds_read_b128 v[228:231], v215 offset:13888
	s_waitcnt vmcnt(4)
	ds_write_b128 v179, v[150:153] offset:36864
	ds_write_b128 v179, v[154:157] offset:36880
	ds_write_b128 v179, v[158:161] offset:36896
	ds_write_b128 v179, v[162:165] offset:36912
	global_load_dwordx4 v[150:153], v[202:203], off offset:768
	global_load_dwordx4 v[154:157], v[202:203], off offset:784
	global_load_dwordx4 v[158:161], v[202:203], off offset:800
	global_load_dwordx4 v[162:165], v[202:203], off offset:816
	s_waitcnt lgkmcnt(15)
	v_mfma_f32_32x32x16_f16 v[114:129], v[208:211], v[240:243], v[114:129]
	s_waitcnt lgkmcnt(15)
	v_mfma_f32_32x32x16_f16 v[98:113], v[174:177], v[240:243], v[98:113]
	s_waitcnt lgkmcnt(15)
	v_mfma_f32_32x32x16_f16 v[82:97], v[208:211], v[244:247], v[82:97]
	v_mfma_f32_32x32x16_f16 v[66:81], v[174:177], v[244:247], v[66:81]
	s_waitcnt lgkmcnt(15)
	v_mfma_f32_32x32x16_f16 v[50:65], v[208:211], v[248:251], v[50:65]
	v_mfma_f32_32x32x16_f16 v[34:49], v[174:177], v[248:251], v[34:49]
	s_waitcnt lgkmcnt(14)
	v_mfma_f32_32x32x16_f16 v[18:33], v[208:211], v[204:207], v[18:33]
	v_mfma_f32_32x32x16_f16 v[2:17], v[174:177], v[204:207], v[2:17]
	ds_read_b128 v[208:211], v213 offset:96
	ds_read_b128 v[240:243], v215 offset:96
	ds_read_b128 v[174:177], v213 offset:4704
	ds_read_b128 v[244:247], v215 offset:4704
	ds_read_b128 v[248:251], v215 offset:9312
	ds_read_b128 v[204:207], v215 offset:13920
	s_waitcnt lgkmcnt(14)
	v_mfma_f32_32x32x16_f16 v[114:129], v[232:235], v[216:219], v[114:129]
	s_waitcnt lgkmcnt(13)
	v_mfma_f32_32x32x16_f16 v[98:113], v[236:239], v[216:219], v[98:113]
	s_waitcnt lgkmcnt(12)
	v_mfma_f32_32x32x16_f16 v[82:97], v[232:235], v[220:223], v[82:97]
	v_mfma_f32_32x32x16_f16 v[66:81], v[236:239], v[220:223], v[66:81]
	s_waitcnt lgkmcnt(11)
	v_mfma_f32_32x32x16_f16 v[50:65], v[232:235], v[224:227], v[50:65]
	v_mfma_f32_32x32x16_f16 v[34:49], v[236:239], v[224:227], v[34:49]
	s_waitcnt lgkmcnt(10)
	v_mfma_f32_32x32x16_f16 v[18:33], v[232:235], v[228:231], v[18:33]
	v_mfma_f32_32x32x16_f16 v[2:17], v[236:239], v[228:231], v[2:17]
	s_waitcnt lgkmcnt(0)
	s_barrier
; DI f16v mfma32(h8v a, h8v b, f16v c) { return __builtin_amdgcn_mfma_f32_32x32x16_f16(a, b, c, 0, 0, 0); }
; template <bool GATHER>
; DI void gemm256_main(const h16* __restrict__ A, int lda, const int* __restrict__ idx, int m0,
;                      const h16* __restrict__ B, int ldb, int n0, int K, h16* lds, f16v (&acc)[4][2]) {
;     ...
;   for (int kt = 0; kt < nk; ++kt) {
;     const h16* As = lds + (kt & 1) * (512 * LDH);
;     const h16* Bs = As + 256 * LDH;
;     h16* Wn = lds + ((kt & 1) ^ 1) * (512 * LDH);
;     if (kt + 1 < nk) {
; #pragma unroll
;       for (int i = 0; i < 4; ++i) { *(u4v*)&Wn[lr * LDH + lc + 8 * i] = ra[i]; *(u4v*)&Wn[(256 + lr) * LDH + lc + 8 * i] = rb[i]; }
;     }
;     if (kt + 2 < nk) {
; #pragma unroll
;       for (int i = 0; i < 4; ++i) { ra[i] = *(const u4v*)(AP_ + 8 * i); rb[i] = *(const u4v*)(BP_ + 8 * i); }
;       ao += 64; bo += 64;
;     }
; #pragma unroll
;     for (int ks = 0; ks < 4; ++ks) {
;       h8v af[4], bf[2];
; #pragma unroll
;       for (int i = 0; i < 4; ++i) af[i] = *(const h8v*)&As[(wm * 128 + i * 32 + (lane & 31)) * LDH + ks * 16 + 8 * (lane >> 5)];
; #pragma unroll
;       for (int j = 0; j < 2; ++j) bf[j] = *(const h8v*)&Bs[(wn * 64 + j * 32 + (lane & 31)) * LDH + ks * 16 + 8 * (lane >> 5)];
; #pragma unroll
;       for (int i = 0; i < 4; ++i)
; #pragma unroll
;         for (int j = 0; j < 2; ++j) acc[i][j] = mfma32(bf[j], af[i], acc[i][j]);
;     }
;     __syncthreads();
	ds_read_b128 v[232:235], v214
	ds_read_b128 v[216:219], v212
	ds_read_b128 v[236:239], v214 offset:4608
	ds_read_b128 v[220:223], v212 offset:4608
	ds_read_b128 v[224:227], v212 offset:9216
	ds_read_b128 v[228:231], v212 offset:13824
	v_mfma_f32_32x32x16_f16 v[114:129], v[208:211], v[240:243], v[114:129]
	v_mfma_f32_32x32x16_f16 v[98:113], v[174:177], v[240:243], v[98:113]
	v_mfma_f32_32x32x16_f16 v[82:97], v[208:211], v[244:247], v[82:97]
	v_mfma_f32_32x32x16_f16 v[66:81], v[174:177], v[244:247], v[66:81]
	v_mfma_f32_32x32x16_f16 v[50:65], v[208:211], v[248:251], v[50:65]
	v_mfma_f32_32x32x16_f16 v[34:49], v[174:177], v[248:251], v[34:49]
	v_mfma_f32_32x32x16_f16 v[18:33], v[208:211], v[204:207], v[18:33]
	v_mfma_f32_32x32x16_f16 v[2:17], v[174:177], v[204:207], v[2:17]
	ds_read_b128 v[208:211], v214 offset:32
	ds_read_b128 v[240:243], v212 offset:32
	ds_read_b128 v[174:177], v214 offset:4640
	ds_read_b128 v[244:247], v212 offset:4640
	ds_read_b128 v[248:251], v212 offset:9248
	ds_read_b128 v[204:207], v212 offset:13856
	s_waitcnt vmcnt(4)
	ds_write_b128 v178, v[134:137]
	ds_write_b128 v178, v[138:141] offset:16
	ds_write_b128 v178, v[142:145] offset:32
	ds_write_b128 v178, v[146:149] offset:48
	global_load_dwordx4 v[134:137], v[130:131], off offset:896
	global_load_dwordx4 v[138:141], v[130:131], off offset:912
	global_load_dwordx4 v[142:145], v[130:131], off offset:928
	global_load_dwordx4 v[146:149], v[130:131], off offset:944
	s_waitcnt lgkmcnt(14)
	v_mfma_f32_32x32x16_f16 v[114:129], v[232:235], v[216:219], v[114:129]
	s_waitcnt lgkmcnt(13)
	v_mfma_f32_32x32x16_f16 v[98:113], v[236:239], v[216:219], v[98:113]
	s_waitcnt lgkmcnt(12)
	v_mfma_f32_32x32x16_f16 v[82:97], v[232:235], v[220:223], v[82:97]
	v_mfma_f32_32x32x16_f16 v[66:81], v[236:239], v[220:223], v[66:81]
	s_waitcnt lgkmcnt(11)
	v_mfma_f32_32x32x16_f16 v[50:65], v[232:235], v[224:227], v[50:65]
	v_mfma_f32_32x32x16_f16 v[34:49], v[236:239], v[224:227], v[34:49]
	s_waitcnt lgkmcnt(10)
	v_mfma_f32_32x32x16_f16 v[18:33], v[232:235], v[228:231], v[18:33]
	v_mfma_f32_32x32x16_f16 v[2:17], v[236:239], v[228:231], v[2:17]
	ds_read_b128 v[232:235], v214 offset:64
	ds_read_b128 v[216:219], v212 offset:64
	ds_read_b128 v[236:239], v214 offset:4672
	ds_read_b128 v[220:223], v212 offset:4672
	ds_read_b128 v[224:227], v212 offset:9280
	ds_read_b128 v[228:231], v212 offset:13888
	s_waitcnt vmcnt(4)
	ds_write_b128 v178, v[150:153] offset:36864
	ds_write_b128 v178, v[154:157] offset:36880
	ds_write_b128 v178, v[158:161] offset:36896
	ds_write_b128 v178, v[162:165] offset:36912
	global_load_dwordx4 v[150:153], v[202:203], off offset:896
	global_load_dwordx4 v[154:157], v[202:203], off offset:912
	global_load_dwordx4 v[158:161], v[202:203], off offset:928
	global_load_dwordx4 v[162:165], v[202:203], off offset:944
	s_waitcnt lgkmcnt(15)
	v_mfma_f32_32x32x16_f16 v[114:129], v[208:211], v[240:243], v[114:129]
	s_waitcnt lgkmcnt(15)
	v_mfma_f32_32x32x16_f16 v[98:113], v[174:177], v[240:243], v[98:113]
	s_waitcnt lgkmcnt(15)
	v_mfma_f32_32x32x16_f16 v[82:97], v[208:211], v[244:247], v[82:97]
	v_mfma_f32_32x32x16_f16 v[66:81], v[174:177], v[244:247], v[66:81]
	s_waitcnt lgkmcnt(15)
	v_mfma_f32_32x32x16_f16 v[50:65], v[208:211], v[248:251], v[50:65]
	v_mfma_f32_32x32x16_f16 v[34:49], v[174:177], v[248:251], v[34:49]
	s_waitcnt lgkmcnt(14)
	v_mfma_f32_32x32x16_f16 v[18:33], v[208:211], v[204:207], v[18:33]
	v_mfma_f32_32x32x16_f16 v[2:17], v[174:177], v[204:207], v[2:17]
	ds_read_b128 v[208:211], v214 offset:96
	ds_read_b128 v[240:243], v212 offset:96
	ds_read_b128 v[174:177], v214 offset:4704
	ds_read_b128 v[244:247], v212 offset:4704
	ds_read_b128 v[248:251], v212 offset:9312
	ds_read_b128 v[204:207], v212 offset:13920
	s_waitcnt lgkmcnt(14)
	v_mfma_f32_32x32x16_f16 v[114:129], v[232:235], v[216:219], v[114:129]
	s_waitcnt lgkmcnt(13)
	v_mfma_f32_32x32x16_f16 v[98:113], v[236:239], v[216:219], v[98:113]
	s_waitcnt lgkmcnt(12)
	v_mfma_f32_32x32x16_f16 v[82:97], v[232:235], v[220:223], v[82:97]
	v_mfma_f32_32x32x16_f16 v[66:81], v[236:239], v[220:223], v[66:81]
	s_waitcnt lgkmcnt(11)
	v_mfma_f32_32x32x16_f16 v[50:65], v[232:235], v[224:227], v[50:65]
	v_mfma_f32_32x32x16_f16 v[34:49], v[236:239], v[224:227], v[34:49]
	s_waitcnt lgkmcnt(10)
	v_mfma_f32_32x32x16_f16 v[18:33], v[232:235], v[228:231], v[18:33]
	v_mfma_f32_32x32x16_f16 v[2:17], v[236:239], v[228:231], v[2:17]
	s_waitcnt lgkmcnt(0)
	s_barrier
; DI f16v mfma32(h8v a, h8v b, f16v c) { return __builtin_amdgcn_mfma_f32_32x32x16_f16(a, b, c, 0, 0, 0); }
; template <bool GATHER>
; DI void gemm256_main(const h16* __restrict__ A, int lda, const int* __restrict__ idx, int m0,
;                      const h16* __restrict__ B, int ldb, int n0, int K, h16* lds, f16v (&acc)[4][2]) {
;     ...
;   for (int kt = 0; kt < nk; ++kt) {
;     const h16* As = lds + (kt & 1) * (512 * LDH);
;     const h16* Bs = As + 256 * LDH;
;     h16* Wn = lds + ((kt & 1) ^ 1) * (512 * LDH);
;     if (kt + 1 < nk) {
; #pragma unroll
;       for (int i = 0; i < 4; ++i) { *(u4v*)&Wn[lr * LDH + lc + 8 * i] = ra[i]; *(u4v*)&Wn[(256 + lr) * LDH + lc + 8 * i] = rb[i]; }
;     }
;     if (kt + 2 < nk) {
; #pragma unroll
;       for (int i = 0; i < 4; ++i) { ra[i] = *(const u4v*)(AP_ + 8 * i); rb[i] = *(const u4v*)(BP_ + 8 * i); }
;       ao += 64; bo += 64;
;     }
; #pragma unroll
;     for (int ks = 0; ks < 4; ++ks) {
;       h8v af[4], bf[2];
; #pragma unroll
;       for (int i = 0; i < 4; ++i) af[i] = *(const h8v*)&As[(wm * 128 + i * 32 + (lane & 31)) * LDH + ks * 16 + 8 * (lane >> 5)];
; #pragma unroll
;       for (int j = 0; j < 2; ++j) bf[j] = *(const h8v*)&Bs[(wn * 64 + j * 32 + (lane & 31)) * LDH + ks * 16 + 8 * (lane >> 5)];
; #pragma unroll
;       for (int i = 0; i < 4; ++i)
; #pragma unroll
;         for (int j = 0; j < 2; ++j) acc[i][j] = mfma32(bf[j], af[i], acc[i][j]);
;     }
;     __syncthreads();
	ds_read_b128 v[232:235], v213
	ds_read_b128 v[216:219], v215
	ds_read_b128 v[236:239], v213 offset:4608
	ds_read_b128 v[220:223], v215 offset:4608
	ds_read_b128 v[224:227], v215 offset:9216
	ds_read_b128 v[228:231], v215 offset:13824
	v_mfma_f32_32x32x16_f16 v[114:129], v[208:211], v[240:243], v[114:129]
	v_mfma_f32_32x32x16_f16 v[98:113], v[174:177], v[240:243], v[98:113]
	v_mfma_f32_32x32x16_f16 v[82:97], v[208:211], v[244:247], v[82:97]
	v_mfma_f32_32x32x16_f16 v[66:81], v[174:177], v[244:247], v[66:81]
	v_mfma_f32_32x32x16_f16 v[50:65], v[208:211], v[248:251], v[50:65]
	v_mfma_f32_32x32x16_f16 v[34:49], v[174:177], v[248:251], v[34:49]
	v_mfma_f32_32x32x16_f16 v[18:33], v[208:211], v[204:207], v[18:33]
	v_mfma_f32_32x32x16_f16 v[2:17], v[174:177], v[204:207], v[2:17]
	ds_read_b128 v[208:211], v213 offset:32
	ds_read_b128 v[240:243], v215 offset:32
	ds_read_b128 v[174:177], v213 offset:4640
	ds_read_b128 v[244:247], v215 offset:4640
	ds_read_b128 v[248:251], v215 offset:9248
	ds_read_b128 v[204:207], v215 offset:13856
	s_waitcnt vmcnt(4)
	ds_write_b128 v179, v[134:137]
	ds_write_b128 v179, v[138:141] offset:16
	ds_write_b128 v179, v[142:145] offset:32
	ds_write_b128 v179, v[146:149] offset:48
	global_load_dwordx4 v[134:137], v[130:131], off offset:1024
	global_load_dwordx4 v[138:141], v[130:131], off offset:1040
	global_load_dwordx4 v[142:145], v[130:131], off offset:1056
	global_load_dwordx4 v[146:149], v[130:131], off offset:1072
	s_waitcnt lgkmcnt(14)
	v_mfma_f32_32x32x16_f16 v[114:129], v[232:235], v[216:219], v[114:129]
	s_waitcnt lgkmcnt(13)
	v_mfma_f32_32x32x16_f16 v[98:113], v[236:239], v[216:219], v[98:113]
	s_waitcnt lgkmcnt(12)
	v_mfma_f32_32x32x16_f16 v[82:97], v[232:235], v[220:223], v[82:97]
	v_mfma_f32_32x32x16_f16 v[66:81], v[236:239], v[220:223], v[66:81]
	s_waitcnt lgkmcnt(11)
	v_mfma_f32_32x32x16_f16 v[50:65], v[232:235], v[224:227], v[50:65]
	v_mfma_f32_32x32x16_f16 v[34:49], v[236:239], v[224:227], v[34:49]
	s_waitcnt lgkmcnt(10)
	v_mfma_f32_32x32x16_f16 v[18:33], v[232:235], v[228:231], v[18:33]
	v_mfma_f32_32x32x16_f16 v[2:17], v[236:239], v[228:231], v[2:17]
	ds_read_b128 v[232:235], v213 offset:64
	ds_read_b128 v[216:219], v215 offset:64
	ds_read_b128 v[236:239], v213 offset:4672
	ds_read_b128 v[220:223], v215 offset:4672
	ds_read_b128 v[224:227], v215 offset:9280
	ds_read_b128 v[228:231], v215 offset:13888
	s_waitcnt vmcnt(4)
	ds_write_b128 v179, v[150:153] offset:36864
	ds_write_b128 v179, v[154:157] offset:36880
	ds_write_b128 v179, v[158:161] offset:36896
	ds_write_b128 v179, v[162:165] offset:36912
	global_load_dwordx4 v[150:153], v[202:203], off offset:1024
	global_load_dwordx4 v[154:157], v[202:203], off offset:1040
	global_load_dwordx4 v[158:161], v[202:203], off offset:1056
	global_load_dwordx4 v[162:165], v[202:203], off offset:1072
	s_waitcnt lgkmcnt(15)
	v_mfma_f32_32x32x16_f16 v[114:129], v[208:211], v[240:243], v[114:129]
	s_waitcnt lgkmcnt(15)
	v_mfma_f32_32x32x16_f16 v[98:113], v[174:177], v[240:243], v[98:113]
	s_waitcnt lgkmcnt(15)
	v_mfma_f32_32x32x16_f16 v[82:97], v[208:211], v[244:247], v[82:97]
	v_mfma_f32_32x32x16_f16 v[66:81], v[174:177], v[244:247], v[66:81]
	s_waitcnt lgkmcnt(15)
	v_mfma_f32_32x32x16_f16 v[50:65], v[208:211], v[248:251], v[50:65]
	v_mfma_f32_32x32x16_f16 v[34:49], v[174:177], v[248:251], v[34:49]
	s_waitcnt lgkmcnt(14)
	v_mfma_f32_32x32x16_f16 v[18:33], v[208:211], v[204:207], v[18:33]
	v_mfma_f32_32x32x16_f16 v[2:17], v[174:177], v[204:207], v[2:17]
	ds_read_b128 v[208:211], v213 offset:96
	ds_read_b128 v[240:243], v215 offset:96
	ds_read_b128 v[174:177], v213 offset:4704
	ds_read_b128 v[244:247], v215 offset:4704
	ds_read_b128 v[248:251], v215 offset:9312
	ds_read_b128 v[204:207], v215 offset:13920
	s_waitcnt lgkmcnt(14)
	v_mfma_f32_32x32x16_f16 v[114:129], v[232:235], v[216:219], v[114:129]
	s_waitcnt lgkmcnt(13)
	v_mfma_f32_32x32x16_f16 v[98:113], v[236:239], v[216:219], v[98:113]
	s_waitcnt lgkmcnt(12)
	v_mfma_f32_32x32x16_f16 v[82:97], v[232:235], v[220:223], v[82:97]
	v_mfma_f32_32x32x16_f16 v[66:81], v[236:239], v[220:223], v[66:81]
	s_waitcnt lgkmcnt(11)
	v_mfma_f32_32x32x16_f16 v[50:65], v[232:235], v[224:227], v[50:65]
	v_mfma_f32_32x32x16_f16 v[34:49], v[236:239], v[224:227], v[34:49]
	s_waitcnt lgkmcnt(10)
	v_mfma_f32_32x32x16_f16 v[18:33], v[232:235], v[228:231], v[18:33]
	v_mfma_f32_32x32x16_f16 v[2:17], v[236:239], v[228:231], v[2:17]
	s_waitcnt lgkmcnt(0)
	s_barrier
; DI f16v mfma32(h8v a, h8v b, f16v c) { return __builtin_amdgcn_mfma_f32_32x32x16_f16(a, b, c, 0, 0, 0); }
; template <bool GATHER>
; DI void gemm256_main(const h16* __restrict__ A, int lda, const int* __restrict__ idx, int m0,
;                      const h16* __restrict__ B, int ldb, int n0, int K, h16* lds, f16v (&acc)[4][2]) {
;     ...
;   for (int kt = 0; kt < nk; ++kt) {
;     const h16* As = lds + (kt & 1) * (512 * LDH);
;     const h16* Bs = As + 256 * LDH;
;     h16* Wn = lds + ((kt & 1) ^ 1) * (512 * LDH);
;     if (kt + 1 < nk) {
; #pragma unroll
;       for (int i = 0; i < 4; ++i) { *(u4v*)&Wn[lr * LDH + lc + 8 * i] = ra[i]; *(u4v*)&Wn[(256 + lr) * LDH + lc + 8 * i] = rb[i]; }
;     }
;     if (kt + 2 < nk) {
; #pragma unroll
;       for (int i = 0; i < 4; ++i) { ra[i] = *(const u4v*)(AP_ + 8 * i); rb[i] = *(const u4v*)(BP_ + 8 * i); }
;       ao += 64; bo += 64;
;     }
; #pragma unroll
;     for (int ks = 0; ks < 4; ++ks) {
;       h8v af[4], bf[2];
; #pragma unroll
;       for (int i = 0; i < 4; ++i) af[i] = *(const h8v*)&As[(wm * 128 + i * 32 + (lane & 31)) * LDH + ks * 16 + 8 * (lane >> 5)];
; #pragma unroll
;       for (int j = 0; j < 2; ++j) bf[j] = *(const h8v*)&Bs[(wn * 64 + j * 32 + (lane & 31)) * LDH + ks * 16 + 8 * (lane >> 5)];
; #pragma unroll
;       for (int i = 0; i < 4; ++i)
; #pragma unroll
;         for (int j = 0; j < 2; ++j) acc[i][j] = mfma32(bf[j], af[i], acc[i][j]);
;     }
;     __syncthreads();
	ds_read_b128 v[232:235], v214
	ds_read_b128 v[216:219], v212
	ds_read_b128 v[236:239], v214 offset:4608
	ds_read_b128 v[220:223], v212 offset:4608
	ds_read_b128 v[224:227], v212 offset:9216
	ds_read_b128 v[228:231], v212 offset:13824
	v_mfma_f32_32x32x16_f16 v[114:129], v[208:211], v[240:243], v[114:129]
	v_mfma_f32_32x32x16_f16 v[98:113], v[174:177], v[240:243], v[98:113]
	v_mfma_f32_32x32x16_f16 v[82:97], v[208:211], v[244:247], v[82:97]
	v_mfma_f32_32x32x16_f16 v[66:81], v[174:177], v[244:247], v[66:81]
	v_mfma_f32_32x32x16_f16 v[50:65], v[208:211], v[248:251], v[50:65]
	v_mfma_f32_32x32x16_f16 v[34:49], v[174:177], v[248:251], v[34:49]
	v_mfma_f32_32x32x16_f16 v[18:33], v[208:211], v[204:207], v[18:33]
	v_mfma_f32_32x32x16_f16 v[2:17], v[174:177], v[204:207], v[2:17]
	ds_read_b128 v[208:211], v214 offset:32
	ds_read_b128 v[240:243], v212 offset:32
	ds_read_b128 v[174:177], v214 offset:4640
	ds_read_b128 v[244:247], v212 offset:4640
	ds_read_b128 v[248:251], v212 offset:9248
	ds_read_b128 v[204:207], v212 offset:13856
	s_waitcnt vmcnt(4)
	ds_write_b128 v178, v[134:137]
	ds_write_b128 v178, v[138:141] offset:16
	ds_write_b128 v178, v[142:145] offset:32
	ds_write_b128 v178, v[146:149] offset:48
	global_load_dwordx4 v[134:137], v[130:131], off offset:1152
	global_load_dwordx4 v[138:141], v[130:131], off offset:1168
	global_load_dwordx4 v[142:145], v[130:131], off offset:1184
	global_load_dwordx4 v[146:149], v[130:131], off offset:1200
	s_waitcnt lgkmcnt(14)
	v_mfma_f32_32x32x16_f16 v[114:129], v[232:235], v[216:219], v[114:129]
	s_waitcnt lgkmcnt(13)
	v_mfma_f32_32x32x16_f16 v[98:113], v[236:239], v[216:219], v[98:113]
	s_waitcnt lgkmcnt(12)
	v_mfma_f32_32x32x16_f16 v[82:97], v[232:235], v[220:223], v[82:97]
	v_mfma_f32_32x32x16_f16 v[66:81], v[236:239], v[220:223], v[66:81]
	s_waitcnt lgkmcnt(11)
	v_mfma_f32_32x32x16_f16 v[50:65], v[232:235], v[224:227], v[50:65]
	v_mfma_f32_32x32x16_f16 v[34:49], v[236:239], v[224:227], v[34:49]
	s_waitcnt lgkmcnt(10)
	v_mfma_f32_32x32x16_f16 v[18:33], v[232:235], v[228:231], v[18:33]
	v_mfma_f32_32x32x16_f16 v[2:17], v[236:239], v[228:231], v[2:17]
	ds_read_b128 v[232:235], v214 offset:64
	ds_read_b128 v[216:219], v212 offset:64
	ds_read_b128 v[236:239], v214 offset:4672
	ds_read_b128 v[220:223], v212 offset:4672
	ds_read_b128 v[224:227], v212 offset:9280
	ds_read_b128 v[228:231], v212 offset:13888
	s_waitcnt vmcnt(4)
	ds_write_b128 v178, v[150:153] offset:36864
	ds_write_b128 v178, v[154:157] offset:36880
	ds_write_b128 v178, v[158:161] offset:36896
	ds_write_b128 v178, v[162:165] offset:36912
	global_load_dwordx4 v[150:153], v[202:203], off offset:1152
	global_load_dwordx4 v[154:157], v[202:203], off offset:1168
	global_load_dwordx4 v[158:161], v[202:203], off offset:1184
	global_load_dwordx4 v[162:165], v[202:203], off offset:1200
	s_waitcnt lgkmcnt(15)
	v_mfma_f32_32x32x16_f16 v[114:129], v[208:211], v[240:243], v[114:129]
	s_waitcnt lgkmcnt(15)
	v_mfma_f32_32x32x16_f16 v[98:113], v[174:177], v[240:243], v[98:113]
	s_waitcnt lgkmcnt(15)
	v_mfma_f32_32x32x16_f16 v[82:97], v[208:211], v[244:247], v[82:97]
	v_mfma_f32_32x32x16_f16 v[66:81], v[174:177], v[244:247], v[66:81]
	s_waitcnt lgkmcnt(15)
	v_mfma_f32_32x32x16_f16 v[50:65], v[208:211], v[248:251], v[50:65]
	v_mfma_f32_32x32x16_f16 v[34:49], v[174:177], v[248:251], v[34:49]
	s_waitcnt lgkmcnt(14)
	v_mfma_f32_32x32x16_f16 v[18:33], v[208:211], v[204:207], v[18:33]
	v_mfma_f32_32x32x16_f16 v[2:17], v[174:177], v[204:207], v[2:17]
	ds_read_b128 v[208:211], v214 offset:96
	ds_read_b128 v[240:243], v212 offset:96
	ds_read_b128 v[174:177], v214 offset:4704
	ds_read_b128 v[244:247], v212 offset:4704
	ds_read_b128 v[248:251], v212 offset:9312
	ds_read_b128 v[204:207], v212 offset:13920
	s_waitcnt lgkmcnt(14)
	v_mfma_f32_32x32x16_f16 v[114:129], v[232:235], v[216:219], v[114:129]
	s_waitcnt lgkmcnt(13)
	v_mfma_f32_32x32x16_f16 v[98:113], v[236:239], v[216:219], v[98:113]
	s_waitcnt lgkmcnt(12)
	v_mfma_f32_32x32x16_f16 v[82:97], v[232:235], v[220:223], v[82:97]
	v_mfma_f32_32x32x16_f16 v[66:81], v[236:239], v[220:223], v[66:81]
	s_waitcnt lgkmcnt(11)
	v_mfma_f32_32x32x16_f16 v[50:65], v[232:235], v[224:227], v[50:65]
	v_mfma_f32_32x32x16_f16 v[34:49], v[236:239], v[224:227], v[34:49]
	s_waitcnt lgkmcnt(10)
	v_mfma_f32_32x32x16_f16 v[18:33], v[232:235], v[228:231], v[18:33]
	v_mfma_f32_32x32x16_f16 v[2:17], v[236:239], v[228:231], v[2:17]
	s_waitcnt lgkmcnt(0)
	s_barrier
; DI f16v mfma32(h8v a, h8v b, f16v c) { return __builtin_amdgcn_mfma_f32_32x32x16_f16(a, b, c, 0, 0, 0); }
; template <bool GATHER>
; DI void gemm256_main(const h16* __restrict__ A, int lda, const int* __restrict__ idx, int m0,
;                      const h16* __restrict__ B, int ldb, int n0, int K, h16* lds, f16v (&acc)[4][2]) {
;     ...
;   for (int kt = 0; kt < nk; ++kt) {
;     const h16* As = lds + (kt & 1) * (512 * LDH);
;     const h16* Bs = As + 256 * LDH;
;     h16* Wn = lds + ((kt & 1) ^ 1) * (512 * LDH);
;     if (kt + 1 < nk) {
; #pragma unroll
;       for (int i = 0; i < 4; ++i) { *(u4v*)&Wn[lr * LDH + lc + 8 * i] = ra[i]; *(u4v*)&Wn[(256 + lr) * LDH + lc + 8 * i] = rb[i]; }
;     }
;     if (kt + 2 < nk) {
; #pragma unroll
;       for (int i = 0; i < 4; ++i) { ra[i] = *(const u4v*)(AP_ + 8 * i); rb[i] = *(const u4v*)(BP_ + 8 * i); }
;       ao += 64; bo += 64;
;     }
; #pragma unroll
;     for (int ks = 0; ks < 4; ++ks) {
;       h8v af[4], bf[2];
; #pragma unroll
;       for (int i = 0; i < 4; ++i) af[i] = *(const h8v*)&As[(wm * 128 + i * 32 + (lane & 31)) * LDH + ks * 16 + 8 * (lane >> 5)];
; #pragma unroll
;       for (int j = 0; j < 2; ++j) bf[j] = *(const h8v*)&Bs[(wn * 64 + j * 32 + (lane & 31)) * LDH + ks * 16 + 8 * (lane >> 5)];
; #pragma unroll
;       for (int i = 0; i < 4; ++i)
; #pragma unroll
;         for (int j = 0; j < 2; ++j) acc[i][j] = mfma32(bf[j], af[i], acc[i][j]);
;     }
;     __syncthreads();
	ds_read_b128 v[232:235], v213
	ds_read_b128 v[216:219], v215
	ds_read_b128 v[236:239], v213 offset:4608
	ds_read_b128 v[220:223], v215 offset:4608
	ds_read_b128 v[224:227], v215 offset:9216
	ds_read_b128 v[228:231], v215 offset:13824
	v_mfma_f32_32x32x16_f16 v[114:129], v[208:211], v[240:243], v[114:129]
	v_mfma_f32_32x32x16_f16 v[98:113], v[174:177], v[240:243], v[98:113]
	v_mfma_f32_32x32x16_f16 v[82:97], v[208:211], v[244:247], v[82:97]
	v_mfma_f32_32x32x16_f16 v[66:81], v[174:177], v[244:247], v[66:81]
	v_mfma_f32_32x32x16_f16 v[50:65], v[208:211], v[248:251], v[50:65]
	v_mfma_f32_32x32x16_f16 v[34:49], v[174:177], v[248:251], v[34:49]
	v_mfma_f32_32x32x16_f16 v[18:33], v[208:211], v[204:207], v[18:33]
	v_mfma_f32_32x32x16_f16 v[2:17], v[174:177], v[204:207], v[2:17]
	ds_read_b128 v[208:211], v213 offset:32
	ds_read_b128 v[240:243], v215 offset:32
	ds_read_b128 v[174:177], v213 offset:4640
	ds_read_b128 v[244:247], v215 offset:4640
	ds_read_b128 v[248:251], v215 offset:9248
	ds_read_b128 v[204:207], v215 offset:13856
	s_waitcnt vmcnt(4)
	ds_write_b128 v179, v[134:137]
	ds_write_b128 v179, v[138:141] offset:16
	ds_write_b128 v179, v[142:145] offset:32
	ds_write_b128 v179, v[146:149] offset:48
	global_load_dwordx4 v[134:137], v[130:131], off offset:1280
	global_load_dwordx4 v[138:141], v[130:131], off offset:1296
	global_load_dwordx4 v[142:145], v[130:131], off offset:1312
	global_load_dwordx4 v[146:149], v[130:131], off offset:1328
	s_waitcnt lgkmcnt(14)
	v_mfma_f32_32x32x16_f16 v[114:129], v[232:235], v[216:219], v[114:129]
	s_waitcnt lgkmcnt(13)
	v_mfma_f32_32x32x16_f16 v[98:113], v[236:239], v[216:219], v[98:113]
	s_waitcnt lgkmcnt(12)
	v_mfma_f32_32x32x16_f16 v[82:97], v[232:235], v[220:223], v[82:97]
	v_mfma_f32_32x32x16_f16 v[66:81], v[236:239], v[220:223], v[66:81]
	s_waitcnt lgkmcnt(11)
	v_mfma_f32_32x32x16_f16 v[50:65], v[232:235], v[224:227], v[50:65]
	v_mfma_f32_32x32x16_f16 v[34:49], v[236:239], v[224:227], v[34:49]
	s_waitcnt lgkmcnt(10)
	v_mfma_f32_32x32x16_f16 v[18:33], v[232:235], v[228:231], v[18:33]
	v_mfma_f32_32x32x16_f16 v[2:17], v[236:239], v[228:231], v[2:17]
	ds_read_b128 v[232:235], v213 offset:64
	ds_read_b128 v[216:219], v215 offset:64
	ds_read_b128 v[236:239], v213 offset:4672
	ds_read_b128 v[220:223], v215 offset:4672
	ds_read_b128 v[224:227], v215 offset:9280
	ds_read_b128 v[228:231], v215 offset:13888
	s_waitcnt vmcnt(4)
	ds_write_b128 v179, v[150:153] offset:36864
	ds_write_b128 v179, v[154:157] offset:36880
	ds_write_b128 v179, v[158:161] offset:36896
	ds_write_b128 v179, v[162:165] offset:36912
	global_load_dwordx4 v[150:153], v[202:203], off offset:1280
	global_load_dwordx4 v[154:157], v[202:203], off offset:1296
	global_load_dwordx4 v[158:161], v[202:203], off offset:1312
	global_load_dwordx4 v[162:165], v[202:203], off offset:1328
	s_waitcnt lgkmcnt(15)
	v_mfma_f32_32x32x16_f16 v[114:129], v[208:211], v[240:243], v[114:129]
	s_waitcnt lgkmcnt(15)
	v_mfma_f32_32x32x16_f16 v[98:113], v[174:177], v[240:243], v[98:113]
	s_waitcnt lgkmcnt(15)
	v_mfma_f32_32x32x16_f16 v[82:97], v[208:211], v[244:247], v[82:97]
	v_mfma_f32_32x32x16_f16 v[66:81], v[174:177], v[244:247], v[66:81]
	s_waitcnt lgkmcnt(15)
	v_mfma_f32_32x32x16_f16 v[50:65], v[208:211], v[248:251], v[50:65]
	v_mfma_f32_32x32x16_f16 v[34:49], v[174:177], v[248:251], v[34:49]
	s_waitcnt lgkmcnt(14)
	v_mfma_f32_32x32x16_f16 v[18:33], v[208:211], v[204:207], v[18:33]
	v_mfma_f32_32x32x16_f16 v[2:17], v[174:177], v[204:207], v[2:17]
	ds_read_b128 v[208:211], v213 offset:96
	ds_read_b128 v[240:243], v215 offset:96
	ds_read_b128 v[174:177], v213 offset:4704
	ds_read_b128 v[244:247], v215 offset:4704
	ds_read_b128 v[248:251], v215 offset:9312
	ds_read_b128 v[204:207], v215 offset:13920
	s_waitcnt lgkmcnt(14)
	v_mfma_f32_32x32x16_f16 v[114:129], v[232:235], v[216:219], v[114:129]
	s_waitcnt lgkmcnt(13)
	v_mfma_f32_32x32x16_f16 v[98:113], v[236:239], v[216:219], v[98:113]
	s_waitcnt lgkmcnt(12)
	v_mfma_f32_32x32x16_f16 v[82:97], v[232:235], v[220:223], v[82:97]
	v_mfma_f32_32x32x16_f16 v[66:81], v[236:239], v[220:223], v[66:81]
	s_waitcnt lgkmcnt(11)
	v_mfma_f32_32x32x16_f16 v[50:65], v[232:235], v[224:227], v[50:65]
	v_mfma_f32_32x32x16_f16 v[34:49], v[236:239], v[224:227], v[34:49]
	s_waitcnt lgkmcnt(10)
	v_mfma_f32_32x32x16_f16 v[18:33], v[232:235], v[228:231], v[18:33]
	v_mfma_f32_32x32x16_f16 v[2:17], v[236:239], v[228:231], v[2:17]
	s_waitcnt lgkmcnt(0)
	s_barrier
; DI f16v mfma32(h8v a, h8v b, f16v c) { return __builtin_amdgcn_mfma_f32_32x32x16_f16(a, b, c, 0, 0, 0); }
; template <bool GATHER>
; DI void gemm256_main(const h16* __restrict__ A, int lda, const int* __restrict__ idx, int m0,
;                      const h16* __restrict__ B, int ldb, int n0, int K, h16* lds, f16v (&acc)[4][2]) {
;     ...
;   for (int kt = 0; kt < nk; ++kt) {
;     const h16* As = lds + (kt & 1) * (512 * LDH);
;     const h16* Bs = As + 256 * LDH;
;     h16* Wn = lds + ((kt & 1) ^ 1) * (512 * LDH);
;     if (kt + 1 < nk) {
; #pragma unroll
;       for (int i = 0; i < 4; ++i) { *(u4v*)&Wn[lr * LDH + lc + 8 * i] = ra[i]; *(u4v*)&Wn[(256 + lr) * LDH + lc + 8 * i] = rb[i]; }
;     }
;     if (kt + 2 < nk) {
; #pragma unroll
;       for (int i = 0; i < 4; ++i) { ra[i] = *(const u4v*)(AP_ + 8 * i); rb[i] = *(const u4v*)(BP_ + 8 * i); }
;       ao += 64; bo += 64;
;     }
; #pragma unroll
;     for (int ks = 0; ks < 4; ++ks) {
;       h8v af[4], bf[2];
; #pragma unroll
;       for (int i = 0; i < 4; ++i) af[i] = *(const h8v*)&As[(wm * 128 + i * 32 + (lane & 31)) * LDH + ks * 16 + 8 * (lane >> 5)];
; #pragma unroll
;       for (int j = 0; j < 2; ++j) bf[j] = *(const h8v*)&Bs[(wn * 64 + j * 32 + (lane & 31)) * LDH + ks * 16 + 8 * (lane >> 5)];
; #pragma unroll
;       for (int i = 0; i < 4; ++i)
; #pragma unroll
;         for (int j = 0; j < 2; ++j) acc[i][j] = mfma32(bf[j], af[i], acc[i][j]);
;     }
;     __syncthreads();
	ds_read_b128 v[232:235], v214
	ds_read_b128 v[216:219], v212
	ds_read_b128 v[236:239], v214 offset:4608
	ds_read_b128 v[220:223], v212 offset:4608
	ds_read_b128 v[224:227], v212 offset:9216
	ds_read_b128 v[228:231], v212 offset:13824
	v_mfma_f32_32x32x16_f16 v[114:129], v[208:211], v[240:243], v[114:129]
	v_mfma_f32_32x32x16_f16 v[98:113], v[174:177], v[240:243], v[98:113]
	v_mfma_f32_32x32x16_f16 v[82:97], v[208:211], v[244:247], v[82:97]
	v_mfma_f32_32x32x16_f16 v[66:81], v[174:177], v[244:247], v[66:81]
	v_mfma_f32_32x32x16_f16 v[50:65], v[208:211], v[248:251], v[50:65]
	v_mfma_f32_32x32x16_f16 v[34:49], v[174:177], v[248:251], v[34:49]
	v_mfma_f32_32x32x16_f16 v[18:33], v[208:211], v[204:207], v[18:33]
	v_mfma_f32_32x32x16_f16 v[2:17], v[174:177], v[204:207], v[2:17]
	ds_read_b128 v[208:211], v214 offset:32
	ds_read_b128 v[240:243], v212 offset:32
	ds_read_b128 v[174:177], v214 offset:4640
	ds_read_b128 v[244:247], v212 offset:4640
	ds_read_b128 v[248:251], v212 offset:9248
	ds_read_b128 v[204:207], v212 offset:13856
	s_waitcnt vmcnt(4)
	ds_write_b128 v178, v[134:137]
	ds_write_b128 v178, v[138:141] offset:16
	ds_write_b128 v178, v[142:145] offset:32
	ds_write_b128 v178, v[146:149] offset:48
	global_load_dwordx4 v[134:137], v[130:131], off offset:1408
	global_load_dwordx4 v[138:141], v[130:131], off offset:1424
	global_load_dwordx4 v[142:145], v[130:131], off offset:1440
	global_load_dwordx4 v[146:149], v[130:131], off offset:1456
	s_waitcnt lgkmcnt(14)
	v_mfma_f32_32x32x16_f16 v[114:129], v[232:235], v[216:219], v[114:129]
	s_waitcnt lgkmcnt(13)
	v_mfma_f32_32x32x16_f16 v[98:113], v[236:239], v[216:219], v[98:113]
	s_waitcnt lgkmcnt(12)
	v_mfma_f32_32x32x16_f16 v[82:97], v[232:235], v[220:223], v[82:97]
	v_mfma_f32_32x32x16_f16 v[66:81], v[236:239], v[220:223], v[66:81]
	s_waitcnt lgkmcnt(11)
	v_mfma_f32_32x32x16_f16 v[50:65], v[232:235], v[224:227], v[50:65]
	v_mfma_f32_32x32x16_f16 v[34:49], v[236:239], v[224:227], v[34:49]
	s_waitcnt lgkmcnt(10)
	v_mfma_f32_32x32x16_f16 v[18:33], v[232:235], v[228:231], v[18:33]
	v_mfma_f32_32x32x16_f16 v[2:17], v[236:239], v[228:231], v[2:17]
	ds_read_b128 v[232:235], v214 offset:64
	ds_read_b128 v[216:219], v212 offset:64
	ds_read_b128 v[236:239], v214 offset:4672
	ds_read_b128 v[220:223], v212 offset:4672
	ds_read_b128 v[224:227], v212 offset:9280
	ds_read_b128 v[228:231], v212 offset:13888
	s_waitcnt vmcnt(4)
	ds_write_b128 v178, v[150:153] offset:36864
	ds_write_b128 v178, v[154:157] offset:36880
	ds_write_b128 v178, v[158:161] offset:36896
	ds_write_b128 v178, v[162:165] offset:36912
	global_load_dwordx4 v[150:153], v[202:203], off offset:1408
	global_load_dwordx4 v[154:157], v[202:203], off offset:1424
	global_load_dwordx4 v[158:161], v[202:203], off offset:1440
	global_load_dwordx4 v[162:165], v[202:203], off offset:1456
	s_waitcnt lgkmcnt(15)
	v_mfma_f32_32x32x16_f16 v[114:129], v[208:211], v[240:243], v[114:129]
	s_waitcnt lgkmcnt(15)
	v_mfma_f32_32x32x16_f16 v[98:113], v[174:177], v[240:243], v[98:113]
	s_waitcnt lgkmcnt(15)
	v_mfma_f32_32x32x16_f16 v[82:97], v[208:211], v[244:247], v[82:97]
	v_mfma_f32_32x32x16_f16 v[66:81], v[174:177], v[244:247], v[66:81]
	s_waitcnt lgkmcnt(15)
	v_mfma_f32_32x32x16_f16 v[50:65], v[208:211], v[248:251], v[50:65]
	v_mfma_f32_32x32x16_f16 v[34:49], v[174:177], v[248:251], v[34:49]
	s_waitcnt lgkmcnt(14)
	v_mfma_f32_32x32x16_f16 v[18:33], v[208:211], v[204:207], v[18:33]
	v_mfma_f32_32x32x16_f16 v[2:17], v[174:177], v[204:207], v[2:17]
	ds_read_b128 v[208:211], v214 offset:96
	ds_read_b128 v[240:243], v212 offset:96
	ds_read_b128 v[174:177], v214 offset:4704
	ds_read_b128 v[244:247], v212 offset:4704
	ds_read_b128 v[248:251], v212 offset:9312
	ds_read_b128 v[204:207], v212 offset:13920
	s_waitcnt lgkmcnt(14)
	v_mfma_f32_32x32x16_f16 v[114:129], v[232:235], v[216:219], v[114:129]
	s_waitcnt lgkmcnt(13)
	v_mfma_f32_32x32x16_f16 v[98:113], v[236:239], v[216:219], v[98:113]
	s_waitcnt lgkmcnt(12)
	v_mfma_f32_32x32x16_f16 v[82:97], v[232:235], v[220:223], v[82:97]
	v_mfma_f32_32x32x16_f16 v[66:81], v[236:239], v[220:223], v[66:81]
	s_waitcnt lgkmcnt(11)
	v_mfma_f32_32x32x16_f16 v[50:65], v[232:235], v[224:227], v[50:65]
	v_mfma_f32_32x32x16_f16 v[34:49], v[236:239], v[224:227], v[34:49]
	s_waitcnt lgkmcnt(10)
	v_mfma_f32_32x32x16_f16 v[18:33], v[232:235], v[228:231], v[18:33]
	v_mfma_f32_32x32x16_f16 v[2:17], v[236:239], v[228:231], v[2:17]
	s_waitcnt lgkmcnt(0)
	s_barrier
; DI f16v mfma32(h8v a, h8v b, f16v c) { return __builtin_amdgcn_mfma_f32_32x32x16_f16(a, b, c, 0, 0, 0); }
; template <bool GATHER>
; DI void gemm256_main(const h16* __restrict__ A, int lda, const int* __restrict__ idx, int m0,
;                      const h16* __restrict__ B, int ldb, int n0, int K, h16* lds, f16v (&acc)[4][2]) {
;     ...
;   for (int kt = 0; kt < nk; ++kt) {
;     const h16* As = lds + (kt & 1) * (512 * LDH);
;     const h16* Bs = As + 256 * LDH;
;     h16* Wn = lds + ((kt & 1) ^ 1) * (512 * LDH);
;     if (kt + 1 < nk) {
; #pragma unroll
;       for (int i = 0; i < 4; ++i) { *(u4v*)&Wn[lr * LDH + lc + 8 * i] = ra[i]; *(u4v*)&Wn[(256 + lr) * LDH + lc + 8 * i] = rb[i]; }
;     }
;     if (kt + 2 < nk) {
; #pragma unroll
;       for (int i = 0; i < 4; ++i) { ra[i] = *(const u4v*)(AP_ + 8 * i); rb[i] = *(const u4v*)(BP_ + 8 * i); }
;       ao += 64; bo += 64;
;     }
; #pragma unroll
;     for (int ks = 0; ks < 4; ++ks) {
;       h8v af[4], bf[2];
; #pragma unroll
;       for (int i = 0; i < 4; ++i) af[i] = *(const h8v*)&As[(wm * 128 + i * 32 + (lane & 31)) * LDH + ks * 16 + 8 * (lane >> 5)];
; #pragma unroll
;       for (int j = 0; j < 2; ++j) bf[j] = *(const h8v*)&Bs[(wn * 64 + j * 32 + (lane & 31)) * LDH + ks * 16 + 8 * (lane >> 5)];
; #pragma unroll
;       for (int i = 0; i < 4; ++i)
; #pragma unroll
;         for (int j = 0; j < 2; ++j) acc[i][j] = mfma32(bf[j], af[i], acc[i][j]);
;     }
;     __syncthreads();
	ds_read_b128 v[232:235], v213
	ds_read_b128 v[216:219], v215
	ds_read_b128 v[236:239], v213 offset:4608
	ds_read_b128 v[220:223], v215 offset:4608
	ds_read_b128 v[224:227], v215 offset:9216
	ds_read_b128 v[228:231], v215 offset:13824
	v_mfma_f32_32x32x16_f16 v[114:129], v[208:211], v[240:243], v[114:129]
	v_mfma_f32_32x32x16_f16 v[98:113], v[174:177], v[240:243], v[98:113]
	v_mfma_f32_32x32x16_f16 v[82:97], v[208:211], v[244:247], v[82:97]
	v_mfma_f32_32x32x16_f16 v[66:81], v[174:177], v[244:247], v[66:81]
	v_mfma_f32_32x32x16_f16 v[50:65], v[208:211], v[248:251], v[50:65]
	v_mfma_f32_32x32x16_f16 v[34:49], v[174:177], v[248:251], v[34:49]
	v_mfma_f32_32x32x16_f16 v[18:33], v[208:211], v[204:207], v[18:33]
	v_mfma_f32_32x32x16_f16 v[2:17], v[174:177], v[204:207], v[2:17]
	ds_read_b128 v[208:211], v213 offset:32
	ds_read_b128 v[240:243], v215 offset:32
	ds_read_b128 v[174:177], v213 offset:4640
	ds_read_b128 v[244:247], v215 offset:4640
	ds_read_b128 v[248:251], v215 offset:9248
	ds_read_b128 v[204:207], v215 offset:13856
	s_waitcnt vmcnt(4)
	ds_write_b128 v179, v[134:137]
	ds_write_b128 v179, v[138:141] offset:16
	ds_write_b128 v179, v[142:145] offset:32
	ds_write_b128 v179, v[146:149] offset:48
	global_load_dwordx4 v[134:137], v[130:131], off offset:1536
	global_load_dwordx4 v[138:141], v[130:131], off offset:1552
	global_load_dwordx4 v[142:145], v[130:131], off offset:1568
	global_load_dwordx4 v[146:149], v[130:131], off offset:1584
	s_waitcnt lgkmcnt(14)
	v_mfma_f32_32x32x16_f16 v[114:129], v[232:235], v[216:219], v[114:129]
	s_waitcnt lgkmcnt(13)
	v_mfma_f32_32x32x16_f16 v[98:113], v[236:239], v[216:219], v[98:113]
	s_waitcnt lgkmcnt(12)
	v_mfma_f32_32x32x16_f16 v[82:97], v[232:235], v[220:223], v[82:97]
	v_mfma_f32_32x32x16_f16 v[66:81], v[236:239], v[220:223], v[66:81]
	s_waitcnt lgkmcnt(11)
	v_mfma_f32_32x32x16_f16 v[50:65], v[232:235], v[224:227], v[50:65]
	v_mfma_f32_32x32x16_f16 v[34:49], v[236:239], v[224:227], v[34:49]
	s_waitcnt lgkmcnt(10)
	v_mfma_f32_32x32x16_f16 v[18:33], v[232:235], v[228:231], v[18:33]
	v_mfma_f32_32x32x16_f16 v[2:17], v[236:239], v[228:231], v[2:17]
	ds_read_b128 v[232:235], v213 offset:64
	ds_read_b128 v[216:219], v215 offset:64
	ds_read_b128 v[236:239], v213 offset:4672
	ds_read_b128 v[220:223], v215 offset:4672
	ds_read_b128 v[224:227], v215 offset:9280
	ds_read_b128 v[228:231], v215 offset:13888
	s_waitcnt vmcnt(4)
	ds_write_b128 v179, v[150:153] offset:36864
	ds_write_b128 v179, v[154:157] offset:36880
	ds_write_b128 v179, v[158:161] offset:36896
	ds_write_b128 v179, v[162:165] offset:36912
	global_load_dwordx4 v[150:153], v[202:203], off offset:1536
	global_load_dwordx4 v[154:157], v[202:203], off offset:1552
	global_load_dwordx4 v[158:161], v[202:203], off offset:1568
	global_load_dwordx4 v[162:165], v[202:203], off offset:1584
	s_waitcnt lgkmcnt(15)
	v_mfma_f32_32x32x16_f16 v[114:129], v[208:211], v[240:243], v[114:129]
	s_waitcnt lgkmcnt(15)
	v_mfma_f32_32x32x16_f16 v[98:113], v[174:177], v[240:243], v[98:113]
	s_waitcnt lgkmcnt(15)
	v_mfma_f32_32x32x16_f16 v[82:97], v[208:211], v[244:247], v[82:97]
	v_mfma_f32_32x32x16_f16 v[66:81], v[174:177], v[244:247], v[66:81]
	s_waitcnt lgkmcnt(15)
	v_mfma_f32_32x32x16_f16 v[50:65], v[208:211], v[248:251], v[50:65]
	v_mfma_f32_32x32x16_f16 v[34:49], v[174:177], v[248:251], v[34:49]
	s_waitcnt lgkmcnt(14)
	v_mfma_f32_32x32x16_f16 v[18:33], v[208:211], v[204:207], v[18:33]
	v_mfma_f32_32x32x16_f16 v[2:17], v[174:177], v[204:207], v[2:17]
	ds_read_b128 v[208:211], v213 offset:96
	ds_read_b128 v[240:243], v215 offset:96
	ds_read_b128 v[174:177], v213 offset:4704
	ds_read_b128 v[244:247], v215 offset:4704
	ds_read_b128 v[248:251], v215 offset:9312
	ds_read_b128 v[204:207], v215 offset:13920
	s_waitcnt lgkmcnt(14)
	v_mfma_f32_32x32x16_f16 v[114:129], v[232:235], v[216:219], v[114:129]
	s_waitcnt lgkmcnt(13)
	v_mfma_f32_32x32x16_f16 v[98:113], v[236:239], v[216:219], v[98:113]
	s_waitcnt lgkmcnt(12)
	v_mfma_f32_32x32x16_f16 v[82:97], v[232:235], v[220:223], v[82:97]
	v_mfma_f32_32x32x16_f16 v[66:81], v[236:239], v[220:223], v[66:81]
	s_waitcnt lgkmcnt(11)
	v_mfma_f32_32x32x16_f16 v[50:65], v[232:235], v[224:227], v[50:65]
	v_mfma_f32_32x32x16_f16 v[34:49], v[236:239], v[224:227], v[34:49]
	s_waitcnt lgkmcnt(10)
	v_mfma_f32_32x32x16_f16 v[18:33], v[232:235], v[228:231], v[18:33]
	v_mfma_f32_32x32x16_f16 v[2:17], v[236:239], v[228:231], v[2:17]
	s_waitcnt lgkmcnt(0)
	s_barrier
; DI f16v mfma32(h8v a, h8v b, f16v c) { return __builtin_amdgcn_mfma_f32_32x32x16_f16(a, b, c, 0, 0, 0); }
; template <bool GATHER>
; DI void gemm256_main(const h16* __restrict__ A, int lda, const int* __restrict__ idx, int m0,
;                      const h16* __restrict__ B, int ldb, int n0, int K, h16* lds, f16v (&acc)[4][2]) {
;     ...
;   for (int kt = 0; kt < nk; ++kt) {
;     const h16* As = lds + (kt & 1) * (512 * LDH);
;     const h16* Bs = As + 256 * LDH;
;     h16* Wn = lds + ((kt & 1) ^ 1) * (512 * LDH);
;     if (kt + 1 < nk) {
; #pragma unroll
;       for (int i = 0; i < 4; ++i) { *(u4v*)&Wn[lr * LDH + lc + 8 * i] = ra[i]; *(u4v*)&Wn[(256 + lr) * LDH + lc + 8 * i] = rb[i]; }
;     }
;     if (kt + 2 < nk) {
; #pragma unroll
;       for (int i = 0; i < 4; ++i) { ra[i] = *(const u4v*)(AP_ + 8 * i); rb[i] = *(const u4v*)(BP_ + 8 * i); }
;       ao += 64; bo += 64;
;     }
; #pragma unroll
;     for (int ks = 0; ks < 4; ++ks) {
;       h8v af[4], bf[2];
; #pragma unroll
;       for (int i = 0; i < 4; ++i) af[i] = *(const h8v*)&As[(wm * 128 + i * 32 + (lane & 31)) * LDH + ks * 16 + 8 * (lane >> 5)];
; #pragma unroll
;       for (int j = 0; j < 2; ++j) bf[j] = *(const h8v*)&Bs[(wn * 64 + j * 32 + (lane & 31)) * LDH + ks * 16 + 8 * (lane >> 5)];
; #pragma unroll
;       for (int i = 0; i < 4; ++i)
; #pragma unroll
;         for (int j = 0; j < 2; ++j) acc[i][j] = mfma32(bf[j], af[i], acc[i][j]);
;     }
;     __syncthreads();
	ds_read_b128 v[232:235], v214
	ds_read_b128 v[216:219], v212
	ds_read_b128 v[236:239], v214 offset:4608
	ds_read_b128 v[220:223], v212 offset:4608
	ds_read_b128 v[224:227], v212 offset:9216
	ds_read_b128 v[228:231], v212 offset:13824
	v_mfma_f32_32x32x16_f16 v[114:129], v[208:211], v[240:243], v[114:129]
	v_mfma_f32_32x32x16_f16 v[98:113], v[174:177], v[240:243], v[98:113]
	v_mfma_f32_32x32x16_f16 v[82:97], v[208:211], v[244:247], v[82:97]
	v_mfma_f32_32x32x16_f16 v[66:81], v[174:177], v[244:247], v[66:81]
	v_mfma_f32_32x32x16_f16 v[50:65], v[208:211], v[248:251], v[50:65]
	v_mfma_f32_32x32x16_f16 v[34:49], v[174:177], v[248:251], v[34:49]
	v_mfma_f32_32x32x16_f16 v[18:33], v[208:211], v[204:207], v[18:33]
	v_mfma_f32_32x32x16_f16 v[2:17], v[174:177], v[204:207], v[2:17]
	ds_read_b128 v[208:211], v214 offset:32
	ds_read_b128 v[240:243], v212 offset:32
	ds_read_b128 v[174:177], v214 offset:4640
	ds_read_b128 v[244:247], v212 offset:4640
	ds_read_b128 v[248:251], v212 offset:9248
	ds_read_b128 v[204:207], v212 offset:13856
	s_waitcnt vmcnt(4)
	ds_write_b128 v178, v[134:137]
	ds_write_b128 v178, v[138:141] offset:16
	ds_write_b128 v178, v[142:145] offset:32
	ds_write_b128 v178, v[146:149] offset:48
	global_load_dwordx4 v[134:137], v[130:131], off offset:1664
	global_load_dwordx4 v[138:141], v[130:131], off offset:1680
	global_load_dwordx4 v[142:145], v[130:131], off offset:1696
	global_load_dwordx4 v[146:149], v[130:131], off offset:1712
	s_waitcnt lgkmcnt(14)
	v_mfma_f32_32x32x16_f16 v[114:129], v[232:235], v[216:219], v[114:129]
	s_waitcnt lgkmcnt(13)
	v_mfma_f32_32x32x16_f16 v[98:113], v[236:239], v[216:219], v[98:113]
	s_waitcnt lgkmcnt(12)
	v_mfma_f32_32x32x16_f16 v[82:97], v[232:235], v[220:223], v[82:97]
	v_mfma_f32_32x32x16_f16 v[66:81], v[236:239], v[220:223], v[66:81]
	s_waitcnt lgkmcnt(11)
	v_mfma_f32_32x32x16_f16 v[50:65], v[232:235], v[224:227], v[50:65]
	v_mfma_f32_32x32x16_f16 v[34:49], v[236:239], v[224:227], v[34:49]
	s_waitcnt lgkmcnt(10)
	v_mfma_f32_32x32x16_f16 v[18:33], v[232:235], v[228:231], v[18:33]
	v_mfma_f32_32x32x16_f16 v[2:17], v[236:239], v[228:231], v[2:17]
	ds_read_b128 v[232:235], v214 offset:64
	ds_read_b128 v[216:219], v212 offset:64
	ds_read_b128 v[236:239], v214 offset:4672
	ds_read_b128 v[220:223], v212 offset:4672
	ds_read_b128 v[224:227], v212 offset:9280
	ds_read_b128 v[228:231], v212 offset:13888
	s_waitcnt vmcnt(4)
	ds_write_b128 v178, v[150:153] offset:36864
	ds_write_b128 v178, v[154:157] offset:36880
	ds_write_b128 v178, v[158:161] offset:36896
	ds_write_b128 v178, v[162:165] offset:36912
	global_load_dwordx4 v[150:153], v[202:203], off offset:1664
	global_load_dwordx4 v[154:157], v[202:203], off offset:1680
	global_load_dwordx4 v[158:161], v[202:203], off offset:1696
	global_load_dwordx4 v[162:165], v[202:203], off offset:1712
	s_waitcnt lgkmcnt(15)
	v_mfma_f32_32x32x16_f16 v[114:129], v[208:211], v[240:243], v[114:129]
	s_waitcnt lgkmcnt(15)
	v_mfma_f32_32x32x16_f16 v[98:113], v[174:177], v[240:243], v[98:113]
	s_waitcnt lgkmcnt(15)
	v_mfma_f32_32x32x16_f16 v[82:97], v[208:211], v[244:247], v[82:97]
	v_mfma_f32_32x32x16_f16 v[66:81], v[174:177], v[244:247], v[66:81]
	s_waitcnt lgkmcnt(15)
	v_mfma_f32_32x32x16_f16 v[50:65], v[208:211], v[248:251], v[50:65]
	v_mfma_f32_32x32x16_f16 v[34:49], v[174:177], v[248:251], v[34:49]
	s_waitcnt lgkmcnt(14)
	v_mfma_f32_32x32x16_f16 v[18:33], v[208:211], v[204:207], v[18:33]
	v_mfma_f32_32x32x16_f16 v[2:17], v[174:177], v[204:207], v[2:17]
	ds_read_b128 v[208:211], v214 offset:96
	ds_read_b128 v[240:243], v212 offset:96
	ds_read_b128 v[174:177], v214 offset:4704
	ds_read_b128 v[244:247], v212 offset:4704
	ds_read_b128 v[248:251], v212 offset:9312
	ds_read_b128 v[204:207], v212 offset:13920
	s_waitcnt lgkmcnt(14)
	v_mfma_f32_32x32x16_f16 v[114:129], v[232:235], v[216:219], v[114:129]
	s_waitcnt lgkmcnt(13)
	v_mfma_f32_32x32x16_f16 v[98:113], v[236:239], v[216:219], v[98:113]
	s_waitcnt lgkmcnt(12)
	v_mfma_f32_32x32x16_f16 v[82:97], v[232:235], v[220:223], v[82:97]
	v_mfma_f32_32x32x16_f16 v[66:81], v[236:239], v[220:223], v[66:81]
	s_waitcnt lgkmcnt(11)
	v_mfma_f32_32x32x16_f16 v[50:65], v[232:235], v[224:227], v[50:65]
	v_mfma_f32_32x32x16_f16 v[34:49], v[236:239], v[224:227], v[34:49]
	s_waitcnt lgkmcnt(10)
	v_mfma_f32_32x32x16_f16 v[18:33], v[232:235], v[228:231], v[18:33]
	v_mfma_f32_32x32x16_f16 v[2:17], v[236:239], v[228:231], v[2:17]
	s_waitcnt lgkmcnt(0)
	s_barrier
; DI f16v mfma32(h8v a, h8v b, f16v c) { return __builtin_amdgcn_mfma_f32_32x32x16_f16(a, b, c, 0, 0, 0); }
; template <bool GATHER>
; DI void gemm256_main(const h16* __restrict__ A, int lda, const int* __restrict__ idx, int m0,
;                      const h16* __restrict__ B, int ldb, int n0, int K, h16* lds, f16v (&acc)[4][2]) {
;     ...
;   for (int kt = 0; kt < nk; ++kt) {
;     const h16* As = lds + (kt & 1) * (512 * LDH);
;     const h16* Bs = As + 256 * LDH;
;     h16* Wn = lds + ((kt & 1) ^ 1) * (512 * LDH);
;     if (kt + 1 < nk) {
; #pragma unroll
;       for (int i = 0; i < 4; ++i) { *(u4v*)&Wn[lr * LDH + lc + 8 * i] = ra[i]; *(u4v*)&Wn[(256 + lr) * LDH + lc + 8 * i] = rb[i]; }
;     }
;     if (kt + 2 < nk) {
; #pragma unroll
;       for (int i = 0; i < 4; ++i) { ra[i] = *(const u4v*)(AP_ + 8 * i); rb[i] = *(const u4v*)(BP_ + 8 * i); }
;       ao += 64; bo += 64;
;     }
; #pragma unroll
;     for (int ks = 0; ks < 4; ++ks) {
;       h8v af[4], bf[2];
; #pragma unroll
;       for (int i = 0; i < 4; ++i) af[i] = *(const h8v*)&As[(wm * 128 + i * 32 + (lane & 31)) * LDH + ks * 16 + 8 * (lane >> 5)];
; #pragma unroll
;       for (int j = 0; j < 2; ++j) bf[j] = *(const h8v*)&Bs[(wn * 64 + j * 32 + (lane & 31)) * LDH + ks * 16 + 8 * (lane >> 5)];
; #pragma unroll
;       for (int i = 0; i < 4; ++i)
; #pragma unroll
;         for (int j = 0; j < 2; ++j) acc[i][j] = mfma32(bf[j], af[i], acc[i][j]);
;     }
;     __syncthreads();
	ds_read_b128 v[232:235], v213
	ds_read_b128 v[216:219], v215
	ds_read_b128 v[236:239], v213 offset:4608
	ds_read_b128 v[220:223], v215 offset:4608
	ds_read_b128 v[224:227], v215 offset:9216
	ds_read_b128 v[228:231], v215 offset:13824
	v_mfma_f32_32x32x16_f16 v[114:129], v[208:211], v[240:243], v[114:129]
	v_mfma_f32_32x32x16_f16 v[98:113], v[174:177], v[240:243], v[98:113]
	v_mfma_f32_32x32x16_f16 v[82:97], v[208:211], v[244:247], v[82:97]
	v_mfma_f32_32x32x16_f16 v[66:81], v[174:177], v[244:247], v[66:81]
	v_mfma_f32_32x32x16_f16 v[50:65], v[208:211], v[248:251], v[50:65]
	v_mfma_f32_32x32x16_f16 v[34:49], v[174:177], v[248:251], v[34:49]
	v_mfma_f32_32x32x16_f16 v[18:33], v[208:211], v[204:207], v[18:33]
	v_mfma_f32_32x32x16_f16 v[2:17], v[174:177], v[204:207], v[2:17]
	ds_read_b128 v[208:211], v213 offset:32
	ds_read_b128 v[240:243], v215 offset:32
	ds_read_b128 v[174:177], v213 offset:4640
	ds_read_b128 v[244:247], v215 offset:4640
	ds_read_b128 v[248:251], v215 offset:9248
	ds_read_b128 v[204:207], v215 offset:13856
	s_waitcnt vmcnt(4)
	ds_write_b128 v179, v[134:137]
	ds_write_b128 v179, v[138:141] offset:16
	ds_write_b128 v179, v[142:145] offset:32
	ds_write_b128 v179, v[146:149] offset:48
	global_load_dwordx4 v[134:137], v[130:131], off offset:1792
	global_load_dwordx4 v[138:141], v[130:131], off offset:1808
	global_load_dwordx4 v[142:145], v[130:131], off offset:1824
	global_load_dwordx4 v[146:149], v[130:131], off offset:1840
	s_waitcnt lgkmcnt(14)
	v_mfma_f32_32x32x16_f16 v[114:129], v[232:235], v[216:219], v[114:129]
	s_waitcnt lgkmcnt(13)
	v_mfma_f32_32x32x16_f16 v[98:113], v[236:239], v[216:219], v[98:113]
	s_waitcnt lgkmcnt(12)
	v_mfma_f32_32x32x16_f16 v[82:97], v[232:235], v[220:223], v[82:97]
	v_mfma_f32_32x32x16_f16 v[66:81], v[236:239], v[220:223], v[66:81]
	s_waitcnt lgkmcnt(11)
	v_mfma_f32_32x32x16_f16 v[50:65], v[232:235], v[224:227], v[50:65]
	v_mfma_f32_32x32x16_f16 v[34:49], v[236:239], v[224:227], v[34:49]
	s_waitcnt lgkmcnt(10)
	v_mfma_f32_32x32x16_f16 v[18:33], v[232:235], v[228:231], v[18:33]
	v_mfma_f32_32x32x16_f16 v[2:17], v[236:239], v[228:231], v[2:17]
	ds_read_b128 v[232:235], v213 offset:64
	ds_read_b128 v[216:219], v215 offset:64
	ds_read_b128 v[236:239], v213 offset:4672
	ds_read_b128 v[220:223], v215 offset:4672
	ds_read_b128 v[224:227], v215 offset:9280
	ds_read_b128 v[228:231], v215 offset:13888
	s_waitcnt vmcnt(4)
	ds_write_b128 v179, v[150:153] offset:36864
	ds_write_b128 v179, v[154:157] offset:36880
	ds_write_b128 v179, v[158:161] offset:36896
	ds_write_b128 v179, v[162:165] offset:36912
	global_load_dwordx4 v[150:153], v[202:203], off offset:1792
	global_load_dwordx4 v[154:157], v[202:203], off offset:1808
	global_load_dwordx4 v[158:161], v[202:203], off offset:1824
	global_load_dwordx4 v[162:165], v[202:203], off offset:1840
	s_waitcnt lgkmcnt(15)
	v_mfma_f32_32x32x16_f16 v[114:129], v[208:211], v[240:243], v[114:129]
	s_waitcnt lgkmcnt(15)
	v_mfma_f32_32x32x16_f16 v[98:113], v[174:177], v[240:243], v[98:113]
	s_waitcnt lgkmcnt(15)
	v_mfma_f32_32x32x16_f16 v[82:97], v[208:211], v[244:247], v[82:97]
	v_mfma_f32_32x32x16_f16 v[66:81], v[174:177], v[244:247], v[66:81]
	s_waitcnt lgkmcnt(15)
	v_mfma_f32_32x32x16_f16 v[50:65], v[208:211], v[248:251], v[50:65]
	v_mfma_f32_32x32x16_f16 v[34:49], v[174:177], v[248:251], v[34:49]
	s_waitcnt lgkmcnt(14)
	v_mfma_f32_32x32x16_f16 v[18:33], v[208:211], v[204:207], v[18:33]
	v_mfma_f32_32x32x16_f16 v[2:17], v[174:177], v[204:207], v[2:17]
	ds_read_b128 v[208:211], v213 offset:96
	ds_read_b128 v[240:243], v215 offset:96
	ds_read_b128 v[174:177], v213 offset:4704
	ds_read_b128 v[244:247], v215 offset:4704
	ds_read_b128 v[248:251], v215 offset:9312
	ds_read_b128 v[204:207], v215 offset:13920
	s_waitcnt lgkmcnt(14)
	v_mfma_f32_32x32x16_f16 v[114:129], v[232:235], v[216:219], v[114:129]
	s_waitcnt lgkmcnt(13)
	v_mfma_f32_32x32x16_f16 v[98:113], v[236:239], v[216:219], v[98:113]
	s_waitcnt lgkmcnt(12)
	v_mfma_f32_32x32x16_f16 v[82:97], v[232:235], v[220:223], v[82:97]
	v_mfma_f32_32x32x16_f16 v[66:81], v[236:239], v[220:223], v[66:81]
	s_waitcnt lgkmcnt(11)
	v_mfma_f32_32x32x16_f16 v[50:65], v[232:235], v[224:227], v[50:65]
	v_mfma_f32_32x32x16_f16 v[34:49], v[236:239], v[224:227], v[34:49]
	s_waitcnt lgkmcnt(10)
	v_mfma_f32_32x32x16_f16 v[18:33], v[232:235], v[228:231], v[18:33]
	v_mfma_f32_32x32x16_f16 v[2:17], v[236:239], v[228:231], v[2:17]
	s_waitcnt lgkmcnt(0)
	s_barrier
; DI f16v mfma32(h8v a, h8v b, f16v c) { return __builtin_amdgcn_mfma_f32_32x32x16_f16(a, b, c, 0, 0, 0); }
; template <bool GATHER>
; DI void gemm256_main(const h16* __restrict__ A, int lda, const int* __restrict__ idx, int m0,
;                      const h16* __restrict__ B, int ldb, int n0, int K, h16* lds, f16v (&acc)[4][2]) {
;     ...
;   for (int kt = 0; kt < nk; ++kt) {
;     const h16* As = lds + (kt & 1) * (512 * LDH);
;     const h16* Bs = As + 256 * LDH;
;     h16* Wn = lds + ((kt & 1) ^ 1) * (512 * LDH);
;     if (kt + 1 < nk) {
; #pragma unroll
;       for (int i = 0; i < 4; ++i) { *(u4v*)&Wn[lr * LDH + lc + 8 * i] = ra[i]; *(u4v*)&Wn[(256 + lr) * LDH + lc + 8 * i] = rb[i]; }
;     }
;     if (kt + 2 < nk) {
; #pragma unroll
;       for (int i = 0; i < 4; ++i) { ra[i] = *(const u4v*)(AP_ + 8 * i); rb[i] = *(const u4v*)(BP_ + 8 * i); }
;       ao += 64; bo += 64;
;     }
; #pragma unroll
;     for (int ks = 0; ks < 4; ++ks) {
;       h8v af[4], bf[2];
; #pragma unroll
;       for (int i = 0; i < 4; ++i) af[i] = *(const h8v*)&As[(wm * 128 + i * 32 + (lane & 31)) * LDH + ks * 16 + 8 * (lane >> 5)];
; #pragma unroll
;       for (int j = 0; j < 2; ++j) bf[j] = *(const h8v*)&Bs[(wn * 64 + j * 32 + (lane & 31)) * LDH + ks * 16 + 8 * (lane >> 5)];
; #pragma unroll
;       for (int i = 0; i < 4; ++i)
; #pragma unroll
;         for (int j = 0; j < 2; ++j) acc[i][j] = mfma32(bf[j], af[i], acc[i][j]);
;     }
;     __syncthreads();
	ds_read_b128 v[232:235], v214
	ds_read_b128 v[216:219], v212
	ds_read_b128 v[236:239], v214 offset:4608
	ds_read_b128 v[220:223], v212 offset:4608
	ds_read_b128 v[224:227], v212 offset:9216
	ds_read_b128 v[228:231], v212 offset:13824
	v_mfma_f32_32x32x16_f16 v[114:129], v[208:211], v[240:243], v[114:129]
	v_mfma_f32_32x32x16_f16 v[98:113], v[174:177], v[240:243], v[98:113]
	v_mfma_f32_32x32x16_f16 v[82:97], v[208:211], v[244:247], v[82:97]
	v_mfma_f32_32x32x16_f16 v[66:81], v[174:177], v[244:247], v[66:81]
	v_mfma_f32_32x32x16_f16 v[50:65], v[208:211], v[248:251], v[50:65]
	v_mfma_f32_32x32x16_f16 v[34:49], v[174:177], v[248:251], v[34:49]
	v_mfma_f32_32x32x16_f16 v[18:33], v[208:211], v[204:207], v[18:33]
	v_mfma_f32_32x32x16_f16 v[2:17], v[174:177], v[204:207], v[2:17]
	ds_read_b128 v[208:211], v214 offset:32
	ds_read_b128 v[240:243], v212 offset:32
	ds_read_b128 v[174:177], v214 offset:4640
	ds_read_b128 v[244:247], v212 offset:4640
	ds_read_b128 v[248:251], v212 offset:9248
	ds_read_b128 v[204:207], v212 offset:13856
	s_waitcnt vmcnt(4)
	ds_write_b128 v178, v[134:137]
	ds_write_b128 v178, v[138:141] offset:16
	ds_write_b128 v178, v[142:145] offset:32
	ds_write_b128 v178, v[146:149] offset:48
	global_load_dwordx4 v[134:137], v[130:131], off offset:1920
	global_load_dwordx4 v[138:141], v[130:131], off offset:1936
	global_load_dwordx4 v[142:145], v[130:131], off offset:1952
	global_load_dwordx4 v[146:149], v[130:131], off offset:1968
	s_waitcnt lgkmcnt(14)
	v_mfma_f32_32x32x16_f16 v[114:129], v[232:235], v[216:219], v[114:129]
	s_waitcnt lgkmcnt(13)
	v_mfma_f32_32x32x16_f16 v[98:113], v[236:239], v[216:219], v[98:113]
	s_waitcnt lgkmcnt(12)
	v_mfma_f32_32x32x16_f16 v[82:97], v[232:235], v[220:223], v[82:97]
	v_mfma_f32_32x32x16_f16 v[66:81], v[236:239], v[220:223], v[66:81]
	s_waitcnt lgkmcnt(11)
	v_mfma_f32_32x32x16_f16 v[50:65], v[232:235], v[224:227], v[50:65]
	v_mfma_f32_32x32x16_f16 v[34:49], v[236:239], v[224:227], v[34:49]
	s_waitcnt lgkmcnt(10)
	v_mfma_f32_32x32x16_f16 v[18:33], v[232:235], v[228:231], v[18:33]
	v_mfma_f32_32x32x16_f16 v[2:17], v[236:239], v[228:231], v[2:17]
	ds_read_b128 v[232:235], v214 offset:64
	ds_read_b128 v[216:219], v212 offset:64
	ds_read_b128 v[236:239], v214 offset:4672
	ds_read_b128 v[220:223], v212 offset:4672
	ds_read_b128 v[224:227], v212 offset:9280
	ds_read_b128 v[228:231], v212 offset:13888
	s_waitcnt vmcnt(4)
	ds_write_b128 v178, v[150:153] offset:36864
	ds_write_b128 v178, v[154:157] offset:36880
	ds_write_b128 v178, v[158:161] offset:36896
	ds_write_b128 v178, v[162:165] offset:36912
	global_load_dwordx4 v[150:153], v[202:203], off offset:1920
	global_load_dwordx4 v[154:157], v[202:203], off offset:1936
	global_load_dwordx4 v[158:161], v[202:203], off offset:1952
	global_load_dwordx4 v[162:165], v[202:203], off offset:1968
	s_waitcnt lgkmcnt(15)
	v_mfma_f32_32x32x16_f16 v[114:129], v[208:211], v[240:243], v[114:129]
	s_waitcnt lgkmcnt(15)
	v_mfma_f32_32x32x16_f16 v[98:113], v[174:177], v[240:243], v[98:113]
	s_waitcnt lgkmcnt(15)
	v_mfma_f32_32x32x16_f16 v[82:97], v[208:211], v[244:247], v[82:97]
	v_mfma_f32_32x32x16_f16 v[66:81], v[174:177], v[244:247], v[66:81]
	s_waitcnt lgkmcnt(15)
	v_mfma_f32_32x32x16_f16 v[50:65], v[208:211], v[248:251], v[50:65]
	v_mfma_f32_32x32x16_f16 v[34:49], v[174:177], v[248:251], v[34:49]
	s_waitcnt lgkmcnt(14)
	v_mfma_f32_32x32x16_f16 v[18:33], v[208:211], v[204:207], v[18:33]
	v_mfma_f32_32x32x16_f16 v[2:17], v[174:177], v[204:207], v[2:17]
	ds_read_b128 v[208:211], v214 offset:96
	ds_read_b128 v[240:243], v212 offset:96
	ds_read_b128 v[174:177], v214 offset:4704
	ds_read_b128 v[244:247], v212 offset:4704
	ds_read_b128 v[248:251], v212 offset:9312
	ds_read_b128 v[204:207], v212 offset:13920
	s_waitcnt lgkmcnt(14)
	v_mfma_f32_32x32x16_f16 v[114:129], v[232:235], v[216:219], v[114:129]
	s_waitcnt lgkmcnt(13)
	v_mfma_f32_32x32x16_f16 v[98:113], v[236:239], v[216:219], v[98:113]
	s_waitcnt lgkmcnt(12)
	v_mfma_f32_32x32x16_f16 v[82:97], v[232:235], v[220:223], v[82:97]
	v_mfma_f32_32x32x16_f16 v[66:81], v[236:239], v[220:223], v[66:81]
	s_waitcnt lgkmcnt(11)
	v_mfma_f32_32x32x16_f16 v[50:65], v[232:235], v[224:227], v[50:65]
	v_mfma_f32_32x32x16_f16 v[34:49], v[236:239], v[224:227], v[34:49]
	s_waitcnt lgkmcnt(10)
	v_mfma_f32_32x32x16_f16 v[18:33], v[232:235], v[228:231], v[18:33]
	v_mfma_f32_32x32x16_f16 v[2:17], v[236:239], v[228:231], v[2:17]
	s_waitcnt lgkmcnt(0)
	s_barrier
; DI f16v mfma32(h8v a, h8v b, f16v c) { return __builtin_amdgcn_mfma_f32_32x32x16_f16(a, b, c, 0, 0, 0); }
; template <bool GATHER>
; DI void gemm256_main(const h16* __restrict__ A, int lda, const int* __restrict__ idx, int m0,
;                      const h16* __restrict__ B, int ldb, int n0, int K, h16* lds, f16v (&acc)[4][2]) {
;     ...
;   for (int kt = 0; kt < nk; ++kt) {
;     const h16* As = lds + (kt & 1) * (512 * LDH);
;     const h16* Bs = As + 256 * LDH;
;     h16* Wn = lds + ((kt & 1) ^ 1) * (512 * LDH);
;     if (kt + 1 < nk) {
; #pragma unroll
;       for (int i = 0; i < 4; ++i) { *(u4v*)&Wn[lr * LDH + lc + 8 * i] = ra[i]; *(u4v*)&Wn[(256 + lr) * LDH + lc + 8 * i] = rb[i]; }
;     }
;     if (kt + 2 < nk) {
; #pragma unroll
;       for (int i = 0; i < 4; ++i) { ra[i] = *(const u4v*)(AP_ + 8 * i); rb[i] = *(const u4v*)(BP_ + 8 * i); }
;       ao += 64; bo += 64;
;     }
; #pragma unroll
;     for (int ks = 0; ks < 4; ++ks) {
;       h8v af[4], bf[2];
; #pragma unroll
;       for (int i = 0; i < 4; ++i) af[i] = *(const h8v*)&As[(wm * 128 + i * 32 + (lane & 31)) * LDH + ks * 16 + 8 * (lane >> 5)];
; #pragma unroll
;       for (int j = 0; j < 2; ++j) bf[j] = *(const h8v*)&Bs[(wn * 64 + j * 32 + (lane & 31)) * LDH + ks * 16 + 8 * (lane >> 5)];
; #pragma unroll
;       for (int i = 0; i < 4; ++i)
; #pragma unroll
;         for (int j = 0; j < 2; ++j) acc[i][j] = mfma32(bf[j], af[i], acc[i][j]);
;     }
;     __syncthreads();
	ds_read_b128 v[232:235], v213
	ds_read_b128 v[216:219], v215
	ds_read_b128 v[236:239], v213 offset:4608
	ds_read_b128 v[220:223], v215 offset:4608
	ds_read_b128 v[224:227], v215 offset:9216
	ds_read_b128 v[228:231], v215 offset:13824
	v_mfma_f32_32x32x16_f16 v[114:129], v[208:211], v[240:243], v[114:129]
	v_mfma_f32_32x32x16_f16 v[98:113], v[174:177], v[240:243], v[98:113]
	v_mfma_f32_32x32x16_f16 v[82:97], v[208:211], v[244:247], v[82:97]
	v_mfma_f32_32x32x16_f16 v[66:81], v[174:177], v[244:247], v[66:81]
	v_mfma_f32_32x32x16_f16 v[50:65], v[208:211], v[248:251], v[50:65]
	v_mfma_f32_32x32x16_f16 v[34:49], v[174:177], v[248:251], v[34:49]
	v_mfma_f32_32x32x16_f16 v[18:33], v[208:211], v[204:207], v[18:33]
	v_mfma_f32_32x32x16_f16 v[2:17], v[174:177], v[204:207], v[2:17]
	ds_read_b128 v[208:211], v213 offset:32
	ds_read_b128 v[240:243], v215 offset:32
	ds_read_b128 v[174:177], v213 offset:4640
	ds_read_b128 v[244:247], v215 offset:4640
	ds_read_b128 v[248:251], v215 offset:9248
	ds_read_b128 v[204:207], v215 offset:13856
	s_waitcnt vmcnt(4)
	ds_write_b128 v179, v[134:137]
	ds_write_b128 v179, v[138:141] offset:16
	ds_write_b128 v179, v[142:145] offset:32
	ds_write_b128 v179, v[146:149] offset:48
	s_waitcnt lgkmcnt(14)
	v_mfma_f32_32x32x16_f16 v[114:129], v[232:235], v[216:219], v[114:129]
	s_waitcnt lgkmcnt(13)
	v_mfma_f32_32x32x16_f16 v[98:113], v[236:239], v[216:219], v[98:113]
	s_waitcnt lgkmcnt(12)
	v_mfma_f32_32x32x16_f16 v[82:97], v[232:235], v[220:223], v[82:97]
	v_mfma_f32_32x32x16_f16 v[66:81], v[236:239], v[220:223], v[66:81]
	s_waitcnt lgkmcnt(11)
	v_mfma_f32_32x32x16_f16 v[50:65], v[232:235], v[224:227], v[50:65]
	v_mfma_f32_32x32x16_f16 v[34:49], v[236:239], v[224:227], v[34:49]
	s_waitcnt lgkmcnt(10)
	v_mfma_f32_32x32x16_f16 v[18:33], v[232:235], v[228:231], v[18:33]
	v_mfma_f32_32x32x16_f16 v[2:17], v[236:239], v[228:231], v[2:17]
	ds_read_b128 v[232:235], v213 offset:64
	ds_read_b128 v[216:219], v215 offset:64
	ds_read_b128 v[236:239], v213 offset:4672
	ds_read_b128 v[220:223], v215 offset:4672
	ds_read_b128 v[224:227], v215 offset:9280
	ds_read_b128 v[228:231], v215 offset:13888
	s_waitcnt vmcnt(0)
	ds_write_b128 v179, v[150:153] offset:36864
	ds_write_b128 v179, v[154:157] offset:36880
	ds_write_b128 v179, v[158:161] offset:36896
	ds_write_b128 v179, v[162:165] offset:36912
	s_waitcnt lgkmcnt(15)
	v_mfma_f32_32x32x16_f16 v[114:129], v[208:211], v[240:243], v[114:129]
	s_waitcnt lgkmcnt(15)
	v_mfma_f32_32x32x16_f16 v[98:113], v[174:177], v[240:243], v[98:113]
	s_waitcnt lgkmcnt(15)
	v_mfma_f32_32x32x16_f16 v[82:97], v[208:211], v[244:247], v[82:97]
	v_mfma_f32_32x32x16_f16 v[66:81], v[174:177], v[244:247], v[66:81]
	s_waitcnt lgkmcnt(15)
	v_mfma_f32_32x32x16_f16 v[50:65], v[208:211], v[248:251], v[50:65]
	v_mfma_f32_32x32x16_f16 v[34:49], v[174:177], v[248:251], v[34:49]
	s_waitcnt lgkmcnt(14)
	v_mfma_f32_32x32x16_f16 v[18:33], v[208:211], v[204:207], v[18:33]
	v_mfma_f32_32x32x16_f16 v[2:17], v[174:177], v[204:207], v[2:17]
	ds_read_b128 v[208:211], v213 offset:96
	ds_read_b128 v[240:243], v215 offset:96
	ds_read_b128 v[174:177], v213 offset:4704
	ds_read_b128 v[244:247], v215 offset:4704
	ds_read_b128 v[248:251], v215 offset:9312
	ds_read_b128 v[204:207], v215 offset:13920
	s_waitcnt lgkmcnt(14)
	v_mfma_f32_32x32x16_f16 v[114:129], v[232:235], v[216:219], v[114:129]
	s_waitcnt lgkmcnt(13)
	v_mfma_f32_32x32x16_f16 v[98:113], v[236:239], v[216:219], v[98:113]
	s_waitcnt lgkmcnt(12)
	v_mfma_f32_32x32x16_f16 v[82:97], v[232:235], v[220:223], v[82:97]
	v_mfma_f32_32x32x16_f16 v[66:81], v[236:239], v[220:223], v[66:81]
	s_waitcnt lgkmcnt(11)
	v_mfma_f32_32x32x16_f16 v[50:65], v[232:235], v[224:227], v[50:65]
	v_mfma_f32_32x32x16_f16 v[34:49], v[236:239], v[224:227], v[34:49]
	s_waitcnt lgkmcnt(10)
	v_mfma_f32_32x32x16_f16 v[18:33], v[232:235], v[228:231], v[18:33]
	v_mfma_f32_32x32x16_f16 v[2:17], v[236:239], v[228:231], v[2:17]
	s_waitcnt lgkmcnt(0)
	s_barrier
	ds_read_b128 v[232:235], v214
	ds_read_b128 v[216:219], v212
	ds_read_b128 v[236:239], v214 offset:4608
	ds_read_b128 v[220:223], v212 offset:4608
	ds_read_b128 v[224:227], v212 offset:9216
	ds_read_b128 v[228:231], v212 offset:13824
	v_mfma_f32_32x32x16_f16 v[114:129], v[208:211], v[240:243], v[114:129]
	v_mfma_f32_32x32x16_f16 v[98:113], v[174:177], v[240:243], v[98:113]
	v_mfma_f32_32x32x16_f16 v[82:97], v[208:211], v[244:247], v[82:97]
	v_mfma_f32_32x32x16_f16 v[66:81], v[174:177], v[244:247], v[66:81]
	v_mfma_f32_32x32x16_f16 v[50:65], v[208:211], v[248:251], v[50:65]
	v_mfma_f32_32x32x16_f16 v[34:49], v[174:177], v[248:251], v[34:49]
	v_mfma_f32_32x32x16_f16 v[18:33], v[208:211], v[204:207], v[18:33]
	v_mfma_f32_32x32x16_f16 v[2:17], v[174:177], v[204:207], v[2:17]
	ds_read_b128 v[208:211], v214 offset:32
	ds_read_b128 v[240:243], v212 offset:32
	ds_read_b128 v[174:177], v214 offset:4640
	ds_read_b128 v[244:247], v212 offset:4640
	ds_read_b128 v[248:251], v212 offset:9248
	ds_read_b128 v[204:207], v212 offset:13856
	s_waitcnt lgkmcnt(10)
	v_mfma_f32_32x32x16_f16 v[114:129], v[232:235], v[216:219], v[114:129]
	s_waitcnt lgkmcnt(9)
	v_mfma_f32_32x32x16_f16 v[98:113], v[236:239], v[216:219], v[98:113]
	s_waitcnt lgkmcnt(8)
	v_mfma_f32_32x32x16_f16 v[82:97], v[232:235], v[220:223], v[82:97]
	v_mfma_f32_32x32x16_f16 v[66:81], v[236:239], v[220:223], v[66:81]
	s_waitcnt lgkmcnt(7)
	v_mfma_f32_32x32x16_f16 v[50:65], v[232:235], v[224:227], v[50:65]
	v_mfma_f32_32x32x16_f16 v[34:49], v[236:239], v[224:227], v[34:49]
	s_waitcnt lgkmcnt(6)
; DI float sigmoid_(float x) { return 1.f / (1.f + __expf(-x)); }
; DI f16v mfma32(h8v a, h8v b, f16v c) { return __builtin_amdgcn_mfma_f32_32x32x16_f16(a, b, c, 0, 0, 0); }
; template <bool GATHER>
; DI void gemm256_main(const h16* __restrict__ A, int lda, const int* __restrict__ idx, int m0,
;                      const h16* __restrict__ B, int ldb, int n0, int K, h16* lds, f16v (&acc)[4][2]) {
;     ...
;   for (int kt = 0; kt < nk; ++kt) {
;     const h16* As = lds + (kt & 1) * (512 * LDH);
;     const h16* Bs = As + 256 * LDH;
;     h16* Wn = lds + ((kt & 1) ^ 1) * (512 * LDH);
;     if (kt + 1 < nk) {
; #pragma unroll
;       for (int i = 0; i < 4; ++i) { *(u4v*)&Wn[lr * LDH + lc + 8 * i] = ra[i]; *(u4v*)&Wn[(256 + lr) * LDH + lc + 8 * i] = rb[i]; }
;     }
;     if (kt + 2 < nk) {
; #pragma unroll
;       for (int i = 0; i < 4; ++i) { ra[i] = *(const u4v*)(AP_ + 8 * i); rb[i] = *(const u4v*)(BP_ + 8 * i); }
;       ao += 64; bo += 64;
;     }
; #pragma unroll
;     for (int ks = 0; ks < 4; ++ks) {
;       h8v af[4], bf[2];
; #pragma unroll
;       for (int i = 0; i < 4; ++i) af[i] = *(const h8v*)&As[(wm * 128 + i * 32 + (lane & 31)) * LDH + ks * 16 + 8 * (lane >> 5)];
; #pragma unroll
;       for (int j = 0; j < 2; ++j) bf[j] = *(const h8v*)&Bs[(wn * 64 + j * 32 + (lane & 31)) * LDH + ks * 16 + 8 * (lane >> 5)];
; #pragma unroll
;       for (int i = 0; i < 4; ++i)
; #pragma unroll
;         for (int j = 0; j < 2; ++j) acc[i][j] = mfma32(bf[j], af[i], acc[i][j]);
;     }
;     __syncthreads();
; DI void phase_gates(const Params& p, int bid, int nb, h16* lds) {
;     ...
;     gemm256_epilogue(acc, m0, n0, [&](int m, int n, f4v v0, f4v v1) {
;       f4v a, b;
; #pragma unroll
;       for (int i = 0; i < 4; ++i) { a[i] = sigmoid_(v0[i]); b[i] = sigmoid_(v1[i]); }
;       st_h4(&G[(size_t)m * 4096 + n], a); st_h4(&G[(size_t)m * 4096 + n + 32], b);
	v_mfma_f32_32x32x16_f16 v[18:33], v[232:235], v[228:231], v[18:33]
	v_mfma_f32_32x32x16_f16 v[2:17], v[236:239], v[228:231], v[2:17]
	ds_read_b128 v[232:235], v214 offset:64
	ds_read_b128 v[216:219], v212 offset:64
	ds_read_b128 v[236:239], v214 offset:4672
	ds_read_b128 v[220:223], v212 offset:4672
	ds_read_b128 v[224:227], v212 offset:9280
	ds_read_b128 v[228:231], v212 offset:13888
	s_waitcnt lgkmcnt(10)
	v_mfma_f32_32x32x16_f16 v[114:129], v[208:211], v[240:243], v[114:129]
	s_waitcnt lgkmcnt(9)
	v_mfma_f32_32x32x16_f16 v[98:113], v[174:177], v[240:243], v[98:113]
	s_waitcnt lgkmcnt(8)
	v_mfma_f32_32x32x16_f16 v[82:97], v[208:211], v[244:247], v[82:97]
	v_mfma_f32_32x32x16_f16 v[66:81], v[174:177], v[244:247], v[66:81]
	s_waitcnt lgkmcnt(7)
	v_mfma_f32_32x32x16_f16 v[50:65], v[208:211], v[248:251], v[50:65]
	v_mfma_f32_32x32x16_f16 v[34:49], v[174:177], v[248:251], v[34:49]
	s_waitcnt lgkmcnt(6)
	v_mfma_f32_32x32x16_f16 v[18:33], v[208:211], v[204:207], v[18:33]
	v_mfma_f32_32x32x16_f16 v[2:17], v[174:177], v[204:207], v[2:17]
	ds_read_b128 v[208:211], v214 offset:96
	ds_read_b128 v[240:243], v212 offset:96
	ds_read_b128 v[174:177], v214 offset:4704
	ds_read_b128 v[244:247], v212 offset:4704
	ds_read_b128 v[248:251], v212 offset:9312
	ds_read_b128 v[204:207], v212 offset:13920
	s_waitcnt lgkmcnt(10)
	v_mfma_f32_32x32x16_f16 v[114:129], v[232:235], v[216:219], v[114:129]
	s_waitcnt lgkmcnt(9)
	v_mfma_f32_32x32x16_f16 v[98:113], v[236:239], v[216:219], v[98:113]
	s_waitcnt lgkmcnt(8)
	v_mfma_f32_32x32x16_f16 v[82:97], v[232:235], v[220:223], v[82:97]
	v_mfma_f32_32x32x16_f16 v[66:81], v[236:239], v[220:223], v[66:81]
	s_waitcnt lgkmcnt(7)
	v_mfma_f32_32x32x16_f16 v[50:65], v[232:235], v[224:227], v[50:65]
	v_mfma_f32_32x32x16_f16 v[34:49], v[236:239], v[224:227], v[34:49]
	s_waitcnt lgkmcnt(6)
	v_mfma_f32_32x32x16_f16 v[18:33], v[232:235], v[228:231], v[18:33]
	v_mfma_f32_32x32x16_f16 v[2:17], v[236:239], v[228:231], v[2:17]
	s_waitcnt lgkmcnt(0)
	v_mfma_f32_32x32x16_f16 v[114:129], v[208:211], v[240:243], v[114:129]
	v_mfma_f32_32x32x16_f16 v[98:113], v[174:177], v[240:243], v[98:113]
	v_mfma_f32_32x32x16_f16 v[82:97], v[208:211], v[244:247], v[82:97]
	v_mfma_f32_32x32x16_f16 v[66:81], v[174:177], v[244:247], v[66:81]
	v_mfma_f32_32x32x16_f16 v[50:65], v[208:211], v[248:251], v[50:65]
	v_mfma_f32_32x32x16_f16 v[34:49], v[174:177], v[248:251], v[34:49]
	v_mfma_f32_32x32x16_f16 v[18:33], v[208:211], v[204:207], v[18:33]
	v_mfma_f32_32x32x16_f16 v[2:17], v[174:177], v[204:207], v[2:17]
	s_nop 15
	v_mov_b32_e32 v192, 0x7f800000
	v_mov_b32_e32 v193, 0x7fc00000
	v_mov_b32_e32 v194, 0xff800000
	v_mov_b32_e32 v204, 0x7fffec00
	v_mov_b32_e32 v205, 0xff7fc99e
	v_mov_b32_e32 v206, 0x840000
	v_mov_b32_e32 v207, 0xb00000
	v_mov_b32_e32 v208, 0xdc0000
	v_mov_b32_e32 v209, 0x1080000
	v_mov_b32_e32 v210, 0x1340000
	v_mov_b32_e32 v211, 0x420000
	v_mov_b32_e32 v212, 0x580000
	v_mov_b32_e32 v213, 0x6e0000
	v_mov_b32_e32 v214, 0x9a0000
	s_cselect_b32 s60, 1, 0
	s_barrier
	v_readfirstlane_b32 s66, v180
	s_mov_b32 s69, s5
	s_mov_b32 s65, s6
	s_lshr_b32 s66, s66, 6
	s_and_b32 s67, s66, 3
	s_lshr_b32 s68, s66, 2
	s_lshl_b32 s70, s67, 6
	s_add_i32 s70, s70, s69
	s_lshl_b32 s71, s68, 7
	s_add_i32 s71, s71, s65
	s_mul_i32 s72, s66, 0x4800
	s_add_i32 s72, s72, 16
	s_mov_b32 s73, 0x2000
	v_and_b32_e32 v146, 63, v180
	v_and_b32_e32 v148, 31, v146
	v_lshrrev_b32_e32 v147, 5, v146
	v_mul_u32_u24_e32 v130, 0x90, v148
	v_lshl_add_u32 v130, v147, 3, v130
	v_add_u32_e32 v130, s72, v130
	v_lshrrev_b32_e32 v149, 3, v146
	v_and_b32_e32 v138, 7, v146
	v_mul_u32_u24_e32 v131, 0x90, v149
	v_lshl_add_u32 v131, v138, 4, v131
	v_add_u32_e32 v131, s72, v131
	v_add_u32_e32 v140, s71, v149
	v_lshl_add_u32 v138, v138, 3, s70
	v_mov_b64_e32 v[132:133], s[0:1]
	v_mad_u64_u32 v[132:133], s[74:75], v140, s73, v[132:133]
	v_lshlrev_b32_e32 v138, 1, v138
	v_mov_b32_e32 v139, v0
	v_lshl_add_u64 v[132:133], v[132:133], 0, v[138:139]
	s_mov_b32 s76, 0x10000
	s_mov_b32 s77, 0
	v_mul_f32_e32 v114, 0xbfb8aa3b, v114
	v_mul_f32_e32 v115, 0xbfb8aa3b, v115
	v_mul_f32_e32 v116, 0xbfb8aa3b, v116
	v_mul_f32_e32 v117, 0xbfb8aa3b, v117
	v_exp_f32_e32 v114, v114
	v_exp_f32_e32 v115, v115
	v_exp_f32_e32 v116, v116
	v_exp_f32_e32 v117, v117
	v_add_f32_e32 v114, 1.0, v114
	v_add_f32_e32 v115, 1.0, v115
	v_add_f32_e32 v116, 1.0, v116
	v_add_f32_e32 v117, 1.0, v117
	v_rcp_f32_e32 v114, v114
	v_rcp_f32_e32 v115, v115
	v_rcp_f32_e32 v116, v116
	v_rcp_f32_e32 v117, v117
	v_cvt_pk_f16_f32 v138, v114, v115
	v_cvt_pk_f16_f32 v139, v116, v117
	ds_write_b64 v130, v[138:139] offset:0
	v_mul_f32_e32 v98, 0xbfb8aa3b, v98
	v_mul_f32_e32 v99, 0xbfb8aa3b, v99
	v_mul_f32_e32 v100, 0xbfb8aa3b, v100
	v_mul_f32_e32 v101, 0xbfb8aa3b, v101
	v_exp_f32_e32 v98, v98
	v_exp_f32_e32 v99, v99
	v_exp_f32_e32 v100, v100
	v_exp_f32_e32 v101, v101
	v_add_f32_e32 v98, 1.0, v98
	v_add_f32_e32 v99, 1.0, v99
	v_add_f32_e32 v100, 1.0, v100
	v_add_f32_e32 v101, 1.0, v101
	v_rcp_f32_e32 v98, v98
	v_rcp_f32_e32 v99, v99
	v_rcp_f32_e32 v100, v100
	v_rcp_f32_e32 v101, v101
	v_cvt_pk_f16_f32 v140, v98, v99
	v_cvt_pk_f16_f32 v141, v100, v101
	ds_write_b64 v130, v[140:141] offset:64
	v_mul_f32_e32 v118, 0xbfb8aa3b, v118
	v_mul_f32_e32 v119, 0xbfb8aa3b, v119
	v_mul_f32_e32 v120, 0xbfb8aa3b, v120
	v_mul_f32_e32 v121, 0xbfb8aa3b, v121
	v_exp_f32_e32 v118, v118
	v_exp_f32_e32 v119, v119
	v_exp_f32_e32 v120, v120
	v_exp_f32_e32 v121, v121
	v_add_f32_e32 v118, 1.0, v118
	v_add_f32_e32 v119, 1.0, v119
	v_add_f32_e32 v120, 1.0, v120
	v_add_f32_e32 v121, 1.0, v121
	v_rcp_f32_e32 v118, v118
	v_rcp_f32_e32 v119, v119
	v_rcp_f32_e32 v120, v120
	v_rcp_f32_e32 v121, v121
; DI float sigmoid_(float x) { return 1.f / (1.f + __expf(-x)); }
; DI void phase_gates(const Params& p, int bid, int nb, h16* lds) {
;     ...
;     gemm256_epilogue(acc, m0, n0, [&](int m, int n, f4v v0, f4v v1) {
;       f4v a, b;
; #pragma unroll
;       for (int i = 0; i < 4; ++i) { a[i] = sigmoid_(v0[i]); b[i] = sigmoid_(v1[i]); }
;       st_h4(&G[(size_t)m * 4096 + n], a); st_h4(&G[(size_t)m * 4096 + n + 32], b);
	v_cvt_pk_f16_f32 v142, v118, v119
	v_cvt_pk_f16_f32 v143, v120, v121
	ds_write_b64 v130, v[142:143] offset:16
	v_mul_f32_e32 v102, 0xbfb8aa3b, v102
	v_mul_f32_e32 v103, 0xbfb8aa3b, v103
	v_mul_f32_e32 v104, 0xbfb8aa3b, v104
	v_mul_f32_e32 v105, 0xbfb8aa3b, v105
	v_exp_f32_e32 v102, v102
	v_exp_f32_e32 v103, v103
	v_exp_f32_e32 v104, v104
	v_exp_f32_e32 v105, v105
	v_add_f32_e32 v102, 1.0, v102
	v_add_f32_e32 v103, 1.0, v103
	v_add_f32_e32 v104, 1.0, v104
	v_add_f32_e32 v105, 1.0, v105
	v_rcp_f32_e32 v102, v102
	v_rcp_f32_e32 v103, v103
	v_rcp_f32_e32 v104, v104
	v_rcp_f32_e32 v105, v105
	v_cvt_pk_f16_f32 v144, v102, v103
	v_cvt_pk_f16_f32 v145, v104, v105
	ds_write_b64 v130, v[144:145] offset:80
	v_mul_f32_e32 v122, 0xbfb8aa3b, v122
	v_mul_f32_e32 v123, 0xbfb8aa3b, v123
	v_mul_f32_e32 v124, 0xbfb8aa3b, v124
	v_mul_f32_e32 v125, 0xbfb8aa3b, v125
	v_exp_f32_e32 v122, v122
	v_exp_f32_e32 v123, v123
	v_exp_f32_e32 v124, v124
	v_exp_f32_e32 v125, v125
	v_add_f32_e32 v122, 1.0, v122
	v_add_f32_e32 v123, 1.0, v123
	v_add_f32_e32 v124, 1.0, v124
	v_add_f32_e32 v125, 1.0, v125
	v_rcp_f32_e32 v122, v122
	v_rcp_f32_e32 v123, v123
	v_rcp_f32_e32 v124, v124
	v_rcp_f32_e32 v125, v125
	v_cvt_pk_f16_f32 v138, v122, v123
	v_cvt_pk_f16_f32 v139, v124, v125
	ds_write_b64 v130, v[138:139] offset:32
	v_mul_f32_e32 v106, 0xbfb8aa3b, v106
	v_mul_f32_e32 v107, 0xbfb8aa3b, v107
	v_mul_f32_e32 v108, 0xbfb8aa3b, v108
	v_mul_f32_e32 v109, 0xbfb8aa3b, v109
	v_exp_f32_e32 v106, v106
	v_exp_f32_e32 v107, v107
	v_exp_f32_e32 v108, v108
	v_exp_f32_e32 v109, v109
	v_add_f32_e32 v106, 1.0, v106
	v_add_f32_e32 v107, 1.0, v107
	v_add_f32_e32 v108, 1.0, v108
	v_add_f32_e32 v109, 1.0, v109
	v_rcp_f32_e32 v106, v106
	v_rcp_f32_e32 v107, v107
	v_rcp_f32_e32 v108, v108
	v_rcp_f32_e32 v109, v109
	v_cvt_pk_f16_f32 v140, v106, v107
	v_cvt_pk_f16_f32 v141, v108, v109
	ds_write_b64 v130, v[140:141] offset:96
	v_mul_f32_e32 v126, 0xbfb8aa3b, v126
	v_mul_f32_e32 v127, 0xbfb8aa3b, v127
	v_mul_f32_e32 v128, 0xbfb8aa3b, v128
	v_mul_f32_e32 v129, 0xbfb8aa3b, v129
	v_exp_f32_e32 v126, v126
	v_exp_f32_e32 v127, v127
	v_exp_f32_e32 v128, v128
	v_exp_f32_e32 v129, v129
	v_add_f32_e32 v126, 1.0, v126
	v_add_f32_e32 v127, 1.0, v127
	v_add_f32_e32 v128, 1.0, v128
	v_add_f32_e32 v129, 1.0, v129
	v_rcp_f32_e32 v126, v126
	v_rcp_f32_e32 v127, v127
	v_rcp_f32_e32 v128, v128
	v_rcp_f32_e32 v129, v129
	v_cvt_pk_f16_f32 v142, v126, v127
	v_cvt_pk_f16_f32 v143, v128, v129
	ds_write_b64 v130, v[142:143] offset:48
	v_mul_f32_e32 v110, 0xbfb8aa3b, v110
	v_mul_f32_e32 v111, 0xbfb8aa3b, v111
	v_mul_f32_e32 v112, 0xbfb8aa3b, v112
	v_mul_f32_e32 v113, 0xbfb8aa3b, v113
	v_exp_f32_e32 v110, v110
	v_exp_f32_e32 v111, v111
	v_exp_f32_e32 v112, v112
	v_exp_f32_e32 v113, v113
	v_add_f32_e32 v110, 1.0, v110
	v_add_f32_e32 v111, 1.0, v111
	v_add_f32_e32 v112, 1.0, v112
	v_add_f32_e32 v113, 1.0, v113
	v_rcp_f32_e32 v110, v110
	v_rcp_f32_e32 v111, v111
	v_rcp_f32_e32 v112, v112
	v_rcp_f32_e32 v113, v113
	v_cvt_pk_f16_f32 v144, v110, v111
	v_cvt_pk_f16_f32 v145, v112, v113
	ds_write_b64 v130, v[144:145] offset:112
	v_mul_f32_e32 v82, 0xbfb8aa3b, v82
	v_mul_f32_e32 v83, 0xbfb8aa3b, v83
	v_mul_f32_e32 v84, 0xbfb8aa3b, v84
	v_mul_f32_e32 v85, 0xbfb8aa3b, v85
	v_exp_f32_e32 v82, v82
	v_exp_f32_e32 v83, v83
	v_exp_f32_e32 v84, v84
	v_exp_f32_e32 v85, v85
	v_add_f32_e32 v82, 1.0, v82
	v_add_f32_e32 v83, 1.0, v83
	v_add_f32_e32 v84, 1.0, v84
	v_add_f32_e32 v85, 1.0, v85
	v_rcp_f32_e32 v82, v82
	v_rcp_f32_e32 v83, v83
	v_rcp_f32_e32 v84, v84
	v_rcp_f32_e32 v85, v85
	v_cvt_pk_f16_f32 v138, v82, v83
	v_cvt_pk_f16_f32 v139, v84, v85
	ds_write_b64 v130, v[138:139] offset:4608
	v_mul_f32_e32 v66, 0xbfb8aa3b, v66
	v_mul_f32_e32 v67, 0xbfb8aa3b, v67
	v_mul_f32_e32 v68, 0xbfb8aa3b, v68
	v_mul_f32_e32 v69, 0xbfb8aa3b, v69
	v_exp_f32_e32 v66, v66
	v_exp_f32_e32 v67, v67
	v_exp_f32_e32 v68, v68
	v_exp_f32_e32 v69, v69
	v_add_f32_e32 v66, 1.0, v66
	v_add_f32_e32 v67, 1.0, v67
	v_add_f32_e32 v68, 1.0, v68
	v_add_f32_e32 v69, 1.0, v69
	v_rcp_f32_e32 v66, v66
	v_rcp_f32_e32 v67, v67
	v_rcp_f32_e32 v68, v68
	v_rcp_f32_e32 v69, v69
	v_cvt_pk_f16_f32 v140, v66, v67
	v_cvt_pk_f16_f32 v141, v68, v69
	ds_write_b64 v130, v[140:141] offset:4672
	v_mul_f32_e32 v86, 0xbfb8aa3b, v86
	v_mul_f32_e32 v87, 0xbfb8aa3b, v87
	v_mul_f32_e32 v88, 0xbfb8aa3b, v88
	v_mul_f32_e32 v89, 0xbfb8aa3b, v89
	v_exp_f32_e32 v86, v86
	v_exp_f32_e32 v87, v87
	v_exp_f32_e32 v88, v88
	v_exp_f32_e32 v89, v89
	v_add_f32_e32 v86, 1.0, v86
	v_add_f32_e32 v87, 1.0, v87
	v_add_f32_e32 v88, 1.0, v88
	v_add_f32_e32 v89, 1.0, v89
	v_rcp_f32_e32 v86, v86
	v_rcp_f32_e32 v87, v87
	v_rcp_f32_e32 v88, v88
	v_rcp_f32_e32 v89, v89
	v_cvt_pk_f16_f32 v142, v86, v87
	v_cvt_pk_f16_f32 v143, v88, v89
	ds_write_b64 v130, v[142:143] offset:4624
	v_mul_f32_e32 v70, 0xbfb8aa3b, v70
	v_mul_f32_e32 v71, 0xbfb8aa3b, v71
	v_mul_f32_e32 v72, 0xbfb8aa3b, v72
	v_mul_f32_e32 v73, 0xbfb8aa3b, v73
	v_exp_f32_e32 v70, v70
	v_exp_f32_e32 v71, v71
	v_exp_f32_e32 v72, v72
	v_exp_f32_e32 v73, v73
	v_add_f32_e32 v70, 1.0, v70
	v_add_f32_e32 v71, 1.0, v71
	v_add_f32_e32 v72, 1.0, v72
	v_add_f32_e32 v73, 1.0, v73
	v_rcp_f32_e32 v70, v70
	v_rcp_f32_e32 v71, v71
	v_rcp_f32_e32 v72, v72
	v_rcp_f32_e32 v73, v73
	v_cvt_pk_f16_f32 v144, v70, v71
	v_cvt_pk_f16_f32 v145, v72, v73
	ds_write_b64 v130, v[144:145] offset:4688
	v_mul_f32_e32 v90, 0xbfb8aa3b, v90
	v_mul_f32_e32 v91, 0xbfb8aa3b, v91
	v_mul_f32_e32 v92, 0xbfb8aa3b, v92
	v_mul_f32_e32 v93, 0xbfb8aa3b, v93
	v_exp_f32_e32 v90, v90
	v_exp_f32_e32 v91, v91
	v_exp_f32_e32 v92, v92
	v_exp_f32_e32 v93, v93
	v_add_f32_e32 v90, 1.0, v90
	v_add_f32_e32 v91, 1.0, v91
; DI float sigmoid_(float x) { return 1.f / (1.f + __expf(-x)); }
; DI void phase_gates(const Params& p, int bid, int nb, h16* lds) {
;     ...
;     gemm256_epilogue(acc, m0, n0, [&](int m, int n, f4v v0, f4v v1) {
;       f4v a, b;
; #pragma unroll
;       for (int i = 0; i < 4; ++i) { a[i] = sigmoid_(v0[i]); b[i] = sigmoid_(v1[i]); }
;       st_h4(&G[(size_t)m * 4096 + n], a); st_h4(&G[(size_t)m * 4096 + n + 32], b);
	v_add_f32_e32 v92, 1.0, v92
	v_add_f32_e32 v93, 1.0, v93
	v_rcp_f32_e32 v90, v90
	v_rcp_f32_e32 v91, v91
	v_rcp_f32_e32 v92, v92
	v_rcp_f32_e32 v93, v93
	v_cvt_pk_f16_f32 v138, v90, v91
	v_cvt_pk_f16_f32 v139, v92, v93
	ds_write_b64 v130, v[138:139] offset:4640
	v_mul_f32_e32 v74, 0xbfb8aa3b, v74
	v_mul_f32_e32 v75, 0xbfb8aa3b, v75
	v_mul_f32_e32 v76, 0xbfb8aa3b, v76
	v_mul_f32_e32 v77, 0xbfb8aa3b, v77
	v_exp_f32_e32 v74, v74
	v_exp_f32_e32 v75, v75
	v_exp_f32_e32 v76, v76
	v_exp_f32_e32 v77, v77
	v_add_f32_e32 v74, 1.0, v74
	v_add_f32_e32 v75, 1.0, v75
	v_add_f32_e32 v76, 1.0, v76
	v_add_f32_e32 v77, 1.0, v77
	v_rcp_f32_e32 v74, v74
	v_rcp_f32_e32 v75, v75
	v_rcp_f32_e32 v76, v76
	v_rcp_f32_e32 v77, v77
	v_cvt_pk_f16_f32 v140, v74, v75
	v_cvt_pk_f16_f32 v141, v76, v77
	ds_write_b64 v130, v[140:141] offset:4704
	v_mul_f32_e32 v94, 0xbfb8aa3b, v94
	v_mul_f32_e32 v95, 0xbfb8aa3b, v95
	v_mul_f32_e32 v96, 0xbfb8aa3b, v96
	v_mul_f32_e32 v97, 0xbfb8aa3b, v97
	v_exp_f32_e32 v94, v94
	v_exp_f32_e32 v95, v95
	v_exp_f32_e32 v96, v96
	v_exp_f32_e32 v97, v97
	v_add_f32_e32 v94, 1.0, v94
	v_add_f32_e32 v95, 1.0, v95
	v_add_f32_e32 v96, 1.0, v96
	v_add_f32_e32 v97, 1.0, v97
	v_rcp_f32_e32 v94, v94
	v_rcp_f32_e32 v95, v95
	v_rcp_f32_e32 v96, v96
	v_rcp_f32_e32 v97, v97
	v_cvt_pk_f16_f32 v142, v94, v95
	v_cvt_pk_f16_f32 v143, v96, v97
	ds_write_b64 v130, v[142:143] offset:4656
	v_mul_f32_e32 v78, 0xbfb8aa3b, v78
	v_mul_f32_e32 v79, 0xbfb8aa3b, v79
	v_mul_f32_e32 v80, 0xbfb8aa3b, v80
	v_mul_f32_e32 v81, 0xbfb8aa3b, v81
	v_exp_f32_e32 v78, v78
	v_exp_f32_e32 v79, v79
	v_exp_f32_e32 v80, v80
	v_exp_f32_e32 v81, v81
	v_add_f32_e32 v78, 1.0, v78
	v_add_f32_e32 v79, 1.0, v79
	v_add_f32_e32 v80, 1.0, v80
	v_add_f32_e32 v81, 1.0, v81
	v_rcp_f32_e32 v78, v78
	v_rcp_f32_e32 v79, v79
	v_rcp_f32_e32 v80, v80
	v_rcp_f32_e32 v81, v81
	v_cvt_pk_f16_f32 v144, v78, v79
	v_cvt_pk_f16_f32 v145, v80, v81
	ds_write_b64 v130, v[144:145] offset:4720
	v_mul_f32_e32 v50, 0xbfb8aa3b, v50
	v_mul_f32_e32 v51, 0xbfb8aa3b, v51
	v_mul_f32_e32 v52, 0xbfb8aa3b, v52
	v_mul_f32_e32 v53, 0xbfb8aa3b, v53
	v_exp_f32_e32 v50, v50
	v_exp_f32_e32 v51, v51
	v_exp_f32_e32 v52, v52
	v_exp_f32_e32 v53, v53
	v_add_f32_e32 v50, 1.0, v50
	v_add_f32_e32 v51, 1.0, v51
	v_add_f32_e32 v52, 1.0, v52
	v_add_f32_e32 v53, 1.0, v53
	v_rcp_f32_e32 v50, v50
	v_rcp_f32_e32 v51, v51
	v_rcp_f32_e32 v52, v52
	v_rcp_f32_e32 v53, v53
	v_cvt_pk_f16_f32 v138, v50, v51
	v_cvt_pk_f16_f32 v139, v52, v53
	ds_write_b64 v130, v[138:139] offset:9216
	v_mul_f32_e32 v34, 0xbfb8aa3b, v34
	v_mul_f32_e32 v35, 0xbfb8aa3b, v35
	v_mul_f32_e32 v36, 0xbfb8aa3b, v36
	v_mul_f32_e32 v37, 0xbfb8aa3b, v37
	v_exp_f32_e32 v34, v34
	v_exp_f32_e32 v35, v35
	v_exp_f32_e32 v36, v36
	v_exp_f32_e32 v37, v37
	v_add_f32_e32 v34, 1.0, v34
	v_add_f32_e32 v35, 1.0, v35
	v_add_f32_e32 v36, 1.0, v36
	v_add_f32_e32 v37, 1.0, v37
	v_rcp_f32_e32 v34, v34
	v_rcp_f32_e32 v35, v35
	v_rcp_f32_e32 v36, v36
	v_rcp_f32_e32 v37, v37
	v_cvt_pk_f16_f32 v140, v34, v35
	v_cvt_pk_f16_f32 v141, v36, v37
	ds_write_b64 v130, v[140:141] offset:9280
	v_mul_f32_e32 v54, 0xbfb8aa3b, v54
	v_mul_f32_e32 v55, 0xbfb8aa3b, v55
	v_mul_f32_e32 v56, 0xbfb8aa3b, v56
	v_mul_f32_e32 v57, 0xbfb8aa3b, v57
	v_exp_f32_e32 v54, v54
	v_exp_f32_e32 v55, v55
	v_exp_f32_e32 v56, v56
	v_exp_f32_e32 v57, v57
	v_add_f32_e32 v54, 1.0, v54
	v_add_f32_e32 v55, 1.0, v55
	v_add_f32_e32 v56, 1.0, v56
	v_add_f32_e32 v57, 1.0, v57
	v_rcp_f32_e32 v54, v54
	v_rcp_f32_e32 v55, v55
	v_rcp_f32_e32 v56, v56
	v_rcp_f32_e32 v57, v57
	v_cvt_pk_f16_f32 v142, v54, v55
	v_cvt_pk_f16_f32 v143, v56, v57
	ds_write_b64 v130, v[142:143] offset:9232
	v_mul_f32_e32 v38, 0xbfb8aa3b, v38
	v_mul_f32_e32 v39, 0xbfb8aa3b, v39
	v_mul_f32_e32 v40, 0xbfb8aa3b, v40
	v_mul_f32_e32 v41, 0xbfb8aa3b, v41
	v_exp_f32_e32 v38, v38
	v_exp_f32_e32 v39, v39
	v_exp_f32_e32 v40, v40
	v_exp_f32_e32 v41, v41
	v_add_f32_e32 v38, 1.0, v38
	v_add_f32_e32 v39, 1.0, v39
	v_add_f32_e32 v40, 1.0, v40
	v_add_f32_e32 v41, 1.0, v41
	v_rcp_f32_e32 v38, v38
	v_rcp_f32_e32 v39, v39
	v_rcp_f32_e32 v40, v40
	v_rcp_f32_e32 v41, v41
	v_cvt_pk_f16_f32 v144, v38, v39
	v_cvt_pk_f16_f32 v145, v40, v41
	ds_write_b64 v130, v[144:145] offset:9296
	v_mul_f32_e32 v58, 0xbfb8aa3b, v58
	v_mul_f32_e32 v59, 0xbfb8aa3b, v59
	v_mul_f32_e32 v60, 0xbfb8aa3b, v60
	v_mul_f32_e32 v61, 0xbfb8aa3b, v61
	v_exp_f32_e32 v58, v58
	v_exp_f32_e32 v59, v59
	v_exp_f32_e32 v60, v60
	v_exp_f32_e32 v61, v61
	v_add_f32_e32 v58, 1.0, v58
	v_add_f32_e32 v59, 1.0, v59
	v_add_f32_e32 v60, 1.0, v60
	v_add_f32_e32 v61, 1.0, v61
	v_rcp_f32_e32 v58, v58
	v_rcp_f32_e32 v59, v59
	v_rcp_f32_e32 v60, v60
	v_rcp_f32_e32 v61, v61
	v_cvt_pk_f16_f32 v138, v58, v59
	v_cvt_pk_f16_f32 v139, v60, v61
	ds_write_b64 v130, v[138:139] offset:9248
	v_mul_f32_e32 v42, 0xbfb8aa3b, v42
	v_mul_f32_e32 v43, 0xbfb8aa3b, v43
	v_mul_f32_e32 v44, 0xbfb8aa3b, v44
	v_mul_f32_e32 v45, 0xbfb8aa3b, v45
	v_exp_f32_e32 v42, v42
	v_exp_f32_e32 v43, v43
	v_exp_f32_e32 v44, v44
	v_exp_f32_e32 v45, v45
	v_add_f32_e32 v42, 1.0, v42
	v_add_f32_e32 v43, 1.0, v43
	v_add_f32_e32 v44, 1.0, v44
	v_add_f32_e32 v45, 1.0, v45
	v_rcp_f32_e32 v42, v42
	v_rcp_f32_e32 v43, v43
	v_rcp_f32_e32 v44, v44
	v_rcp_f32_e32 v45, v45
	v_cvt_pk_f16_f32 v140, v42, v43
	v_cvt_pk_f16_f32 v141, v44, v45
	ds_write_b64 v130, v[140:141] offset:9312
	v_mul_f32_e32 v62, 0xbfb8aa3b, v62
	v_mul_f32_e32 v63, 0xbfb8aa3b, v63
	v_mul_f32_e32 v64, 0xbfb8aa3b, v64
	v_mul_f32_e32 v65, 0xbfb8aa3b, v65
	v_exp_f32_e32 v62, v62
	v_exp_f32_e32 v63, v63
	v_exp_f32_e32 v64, v64
	v_exp_f32_e32 v65, v65
	v_add_f32_e32 v62, 1.0, v62
	v_add_f32_e32 v63, 1.0, v63
	v_add_f32_e32 v64, 1.0, v64
; DI float sigmoid_(float x) { return 1.f / (1.f + __expf(-x)); }
; DI void phase_gates(const Params& p, int bid, int nb, h16* lds) {
;     ...
;     gemm256_epilogue(acc, m0, n0, [&](int m, int n, f4v v0, f4v v1) {
;       f4v a, b;
; #pragma unroll
;       for (int i = 0; i < 4; ++i) { a[i] = sigmoid_(v0[i]); b[i] = sigmoid_(v1[i]); }
;       st_h4(&G[(size_t)m * 4096 + n], a); st_h4(&G[(size_t)m * 4096 + n + 32], b);
	v_add_f32_e32 v65, 1.0, v65
	v_rcp_f32_e32 v62, v62
	v_rcp_f32_e32 v63, v63
	v_rcp_f32_e32 v64, v64
	v_rcp_f32_e32 v65, v65
	v_cvt_pk_f16_f32 v142, v62, v63
	v_cvt_pk_f16_f32 v143, v64, v65
	ds_write_b64 v130, v[142:143] offset:9264
	v_mul_f32_e32 v46, 0xbfb8aa3b, v46
	v_mul_f32_e32 v47, 0xbfb8aa3b, v47
	v_mul_f32_e32 v48, 0xbfb8aa3b, v48
	v_mul_f32_e32 v49, 0xbfb8aa3b, v49
	v_exp_f32_e32 v46, v46
	v_exp_f32_e32 v47, v47
	v_exp_f32_e32 v48, v48
	v_exp_f32_e32 v49, v49
	v_add_f32_e32 v46, 1.0, v46
	v_add_f32_e32 v47, 1.0, v47
	v_add_f32_e32 v48, 1.0, v48
	v_add_f32_e32 v49, 1.0, v49
	v_rcp_f32_e32 v46, v46
	v_rcp_f32_e32 v47, v47
	v_rcp_f32_e32 v48, v48
	v_rcp_f32_e32 v49, v49
	v_cvt_pk_f16_f32 v144, v46, v47
	v_cvt_pk_f16_f32 v145, v48, v49
	ds_write_b64 v130, v[144:145] offset:9328
	v_mul_f32_e32 v18, 0xbfb8aa3b, v18
	v_mul_f32_e32 v19, 0xbfb8aa3b, v19
	v_mul_f32_e32 v20, 0xbfb8aa3b, v20
	v_mul_f32_e32 v21, 0xbfb8aa3b, v21
	v_exp_f32_e32 v18, v18
	v_exp_f32_e32 v19, v19
	v_exp_f32_e32 v20, v20
	v_exp_f32_e32 v21, v21
	v_add_f32_e32 v18, 1.0, v18
	v_add_f32_e32 v19, 1.0, v19
	v_add_f32_e32 v20, 1.0, v20
	v_add_f32_e32 v21, 1.0, v21
	v_rcp_f32_e32 v18, v18
	v_rcp_f32_e32 v19, v19
	v_rcp_f32_e32 v20, v20
	v_rcp_f32_e32 v21, v21
	v_cvt_pk_f16_f32 v138, v18, v19
	v_cvt_pk_f16_f32 v139, v20, v21
	ds_write_b64 v130, v[138:139] offset:13824
	v_mul_f32_e32 v2, 0xbfb8aa3b, v2
	v_mul_f32_e32 v3, 0xbfb8aa3b, v3
	v_mul_f32_e32 v4, 0xbfb8aa3b, v4
	v_mul_f32_e32 v5, 0xbfb8aa3b, v5
	v_exp_f32_e32 v2, v2
	v_exp_f32_e32 v3, v3
	v_exp_f32_e32 v4, v4
	v_exp_f32_e32 v5, v5
	v_add_f32_e32 v2, 1.0, v2
	v_add_f32_e32 v3, 1.0, v3
	v_add_f32_e32 v4, 1.0, v4
	v_add_f32_e32 v5, 1.0, v5
	v_rcp_f32_e32 v2, v2
	v_rcp_f32_e32 v3, v3
	v_rcp_f32_e32 v4, v4
	v_rcp_f32_e32 v5, v5
	v_cvt_pk_f16_f32 v140, v2, v3
	v_cvt_pk_f16_f32 v141, v4, v5
	ds_write_b64 v130, v[140:141] offset:13888
	v_mul_f32_e32 v22, 0xbfb8aa3b, v22
	v_mul_f32_e32 v23, 0xbfb8aa3b, v23
	v_mul_f32_e32 v24, 0xbfb8aa3b, v24
	v_mul_f32_e32 v25, 0xbfb8aa3b, v25
	v_exp_f32_e32 v22, v22
	v_exp_f32_e32 v23, v23
	v_exp_f32_e32 v24, v24
	v_exp_f32_e32 v25, v25
	v_add_f32_e32 v22, 1.0, v22
	v_add_f32_e32 v23, 1.0, v23
	v_add_f32_e32 v24, 1.0, v24
	v_add_f32_e32 v25, 1.0, v25
	v_rcp_f32_e32 v22, v22
	v_rcp_f32_e32 v23, v23
	v_rcp_f32_e32 v24, v24
	v_rcp_f32_e32 v25, v25
	v_cvt_pk_f16_f32 v142, v22, v23
	v_cvt_pk_f16_f32 v143, v24, v25
	ds_write_b64 v130, v[142:143] offset:13840
	v_mul_f32_e32 v6, 0xbfb8aa3b, v6
	v_mul_f32_e32 v7, 0xbfb8aa3b, v7
	v_mul_f32_e32 v8, 0xbfb8aa3b, v8
	v_mul_f32_e32 v9, 0xbfb8aa3b, v9
	v_exp_f32_e32 v6, v6
	v_exp_f32_e32 v7, v7
	v_exp_f32_e32 v8, v8
	v_exp_f32_e32 v9, v9
	v_add_f32_e32 v6, 1.0, v6
	v_add_f32_e32 v7, 1.0, v7
	v_add_f32_e32 v8, 1.0, v8
	v_add_f32_e32 v9, 1.0, v9
	v_rcp_f32_e32 v6, v6
	v_rcp_f32_e32 v7, v7
	v_rcp_f32_e32 v8, v8
	v_rcp_f32_e32 v9, v9
	v_cvt_pk_f16_f32 v144, v6, v7
	v_cvt_pk_f16_f32 v145, v8, v9
	ds_write_b64 v130, v[144:145] offset:13904
	v_mul_f32_e32 v26, 0xbfb8aa3b, v26
	v_mul_f32_e32 v27, 0xbfb8aa3b, v27
	v_mul_f32_e32 v28, 0xbfb8aa3b, v28
	v_mul_f32_e32 v29, 0xbfb8aa3b, v29
	v_exp_f32_e32 v26, v26
	v_exp_f32_e32 v27, v27
	v_exp_f32_e32 v28, v28
	v_exp_f32_e32 v29, v29
	v_add_f32_e32 v26, 1.0, v26
	v_add_f32_e32 v27, 1.0, v27
	v_add_f32_e32 v28, 1.0, v28
	v_add_f32_e32 v29, 1.0, v29
	v_rcp_f32_e32 v26, v26
	v_rcp_f32_e32 v27, v27
	v_rcp_f32_e32 v28, v28
	v_rcp_f32_e32 v29, v29
	v_cvt_pk_f16_f32 v138, v26, v27
	v_cvt_pk_f16_f32 v139, v28, v29
	ds_write_b64 v130, v[138:139] offset:13856
	v_mul_f32_e32 v10, 0xbfb8aa3b, v10
	v_mul_f32_e32 v11, 0xbfb8aa3b, v11
	v_mul_f32_e32 v12, 0xbfb8aa3b, v12
	v_mul_f32_e32 v13, 0xbfb8aa3b, v13
	v_exp_f32_e32 v10, v10
	v_exp_f32_e32 v11, v11
	v_exp_f32_e32 v12, v12
	v_exp_f32_e32 v13, v13
	v_add_f32_e32 v10, 1.0, v10
	v_add_f32_e32 v11, 1.0, v11
	v_add_f32_e32 v12, 1.0, v12
	v_add_f32_e32 v13, 1.0, v13
	v_rcp_f32_e32 v10, v10
	v_rcp_f32_e32 v11, v11
	v_rcp_f32_e32 v12, v12
	v_rcp_f32_e32 v13, v13
	v_cvt_pk_f16_f32 v140, v10, v11
	v_cvt_pk_f16_f32 v141, v12, v13
	ds_write_b64 v130, v[140:141] offset:13920
	v_mul_f32_e32 v30, 0xbfb8aa3b, v30
	v_mul_f32_e32 v31, 0xbfb8aa3b, v31
	v_mul_f32_e32 v32, 0xbfb8aa3b, v32
	v_mul_f32_e32 v33, 0xbfb8aa3b, v33
	v_exp_f32_e32 v30, v30
	v_exp_f32_e32 v31, v31
	v_exp_f32_e32 v32, v32
	v_exp_f32_e32 v33, v33
	v_add_f32_e32 v30, 1.0, v30
	v_add_f32_e32 v31, 1.0, v31
	v_add_f32_e32 v32, 1.0, v32
	v_add_f32_e32 v33, 1.0, v33
	v_rcp_f32_e32 v30, v30
	v_rcp_f32_e32 v31, v31
	v_rcp_f32_e32 v32, v32
	v_rcp_f32_e32 v33, v33
	v_cvt_pk_f16_f32 v142, v30, v31
	v_cvt_pk_f16_f32 v143, v32, v33
	ds_write_b64 v130, v[142:143] offset:13872
	v_mul_f32_e32 v14, 0xbfb8aa3b, v14
	v_mul_f32_e32 v15, 0xbfb8aa3b, v15
	v_mul_f32_e32 v16, 0xbfb8aa3b, v16
	v_mul_f32_e32 v17, 0xbfb8aa3b, v17
	v_exp_f32_e32 v14, v14
	v_exp_f32_e32 v15, v15
	v_exp_f32_e32 v16, v16
	v_exp_f32_e32 v17, v17
	v_add_f32_e32 v14, 1.0, v14
	v_add_f32_e32 v15, 1.0, v15
	v_add_f32_e32 v16, 1.0, v16
	v_add_f32_e32 v17, 1.0, v17
	v_rcp_f32_e32 v14, v14
	v_rcp_f32_e32 v15, v15
	v_rcp_f32_e32 v16, v16
	v_rcp_f32_e32 v17, v17
	v_cvt_pk_f16_f32 v144, v14, v15
	v_cvt_pk_f16_f32 v145, v16, v17
	ds_write_b64 v130, v[144:145] offset:13936
	ds_read_b128 v[150:153], v131 offset:0
	ds_read_b128 v[154:157], v131 offset:1152
	ds_read_b128 v[158:161], v131 offset:2304
	ds_read_b128 v[162:165], v131 offset:3456
	ds_read_b128 v[216:219], v131 offset:4608
	ds_read_b128 v[220:223], v131 offset:5760
	ds_read_b128 v[224:227], v131 offset:6912
	ds_read_b128 v[228:231], v131 offset:8064
	s_waitcnt lgkmcnt(7)
; DI float sigmoid_(float x) { return 1.f / (1.f + __expf(-x)); }
; DI void phase_gates(const Params& p, int bid, int nb, h16* lds) {
;     ...
;   for (int u = bid; u < 64 * 16; u += nb) {
;     const int m0 = (u >> 4) * 256, n0 = (u & 15) * 256;
;     f16v acc[4][2]; acc256_zero(acc);
;     gemm256_main<false>(x16, DM, nullptr, m0, wg, 1024, n0, 1024, lds, acc);
;     gemm256_epilogue(acc, m0, n0, [&](int m, int n, f4v v0, f4v v1) {
;       f4v a, b;
; #pragma unroll
;       for (int i = 0; i < 4; ++i) { a[i] = sigmoid_(v0[i]); b[i] = sigmoid_(v1[i]); }
;       st_h4(&G[(size_t)m * 4096 + n], a); st_h4(&G[(size_t)m * 4096 + n + 32], b);
	global_store_dwordx4 v[132:133], v[150:153], off
	v_lshl_add_u64 v[132:133], v[132:133], 0, s[76:77]
	s_waitcnt lgkmcnt(6)
	global_store_dwordx4 v[132:133], v[154:157], off
	v_lshl_add_u64 v[132:133], v[132:133], 0, s[76:77]
	s_waitcnt lgkmcnt(5)
	global_store_dwordx4 v[132:133], v[158:161], off
	v_lshl_add_u64 v[132:133], v[132:133], 0, s[76:77]
	s_waitcnt lgkmcnt(4)
	global_store_dwordx4 v[132:133], v[162:165], off
	v_lshl_add_u64 v[132:133], v[132:133], 0, s[76:77]
	s_waitcnt lgkmcnt(3)
	global_store_dwordx4 v[132:133], v[216:219], off
	v_lshl_add_u64 v[132:133], v[132:133], 0, s[76:77]
	s_waitcnt lgkmcnt(2)
	global_store_dwordx4 v[132:133], v[220:223], off
	v_lshl_add_u64 v[132:133], v[132:133], 0, s[76:77]
	s_waitcnt lgkmcnt(1)
	global_store_dwordx4 v[132:133], v[224:227], off
	v_lshl_add_u64 v[132:133], v[132:133], 0, s[76:77]
	s_waitcnt lgkmcnt(0)
	global_store_dwordx4 v[132:133], v[228:231], off
	v_lshl_add_u64 v[132:133], v[132:133], 0, s[76:77]
	s_nop 1
	ds_read_b128 v[150:153], v131 offset:9216
	ds_read_b128 v[154:157], v131 offset:10368
	ds_read_b128 v[158:161], v131 offset:11520
	ds_read_b128 v[162:165], v131 offset:12672
	ds_read_b128 v[216:219], v131 offset:13824
	ds_read_b128 v[220:223], v131 offset:14976
	ds_read_b128 v[224:227], v131 offset:16128
	ds_read_b128 v[228:231], v131 offset:17280
	s_waitcnt lgkmcnt(7)
	global_store_dwordx4 v[132:133], v[150:153], off
	v_lshl_add_u64 v[132:133], v[132:133], 0, s[76:77]
	s_waitcnt lgkmcnt(6)
	global_store_dwordx4 v[132:133], v[154:157], off
	v_lshl_add_u64 v[132:133], v[132:133], 0, s[76:77]
	s_waitcnt lgkmcnt(5)
	global_store_dwordx4 v[132:133], v[158:161], off
	v_lshl_add_u64 v[132:133], v[132:133], 0, s[76:77]
	s_waitcnt lgkmcnt(4)
	global_store_dwordx4 v[132:133], v[162:165], off
	v_lshl_add_u64 v[132:133], v[132:133], 0, s[76:77]
	s_waitcnt lgkmcnt(3)
	global_store_dwordx4 v[132:133], v[216:219], off
	v_lshl_add_u64 v[132:133], v[132:133], 0, s[76:77]
	s_waitcnt lgkmcnt(2)
	global_store_dwordx4 v[132:133], v[220:223], off
	v_lshl_add_u64 v[132:133], v[132:133], 0, s[76:77]
	s_waitcnt lgkmcnt(1)
	global_store_dwordx4 v[132:133], v[224:227], off
	v_lshl_add_u64 v[132:133], v[132:133], 0, s[76:77]
	s_waitcnt lgkmcnt(0)
	global_store_dwordx4 v[132:133], v[228:231], off
	v_lshl_add_u64 v[132:133], v[132:133], 0, s[76:77]
	s_cmp_eq_u32 s60, 1
	s_cbranch_scc1 .LBB0_1246

; DI int otid512() { int t = threadIdx.x; asm volatile("" : "+v"(t)); return t; }
; template <bool GATHER>
; DI void gemm256_main(const h16* __restrict__ A, int lda, const int* __restrict__ idx, int m0,
;                      const h16* __restrict__ B, int ldb, int n0, int K, h16* lds, f16v (&acc)[4][2]) {
;   const int tid = otid512(), lane = tid & 63, wv = tid >> 6, wm = wv >> 2, wn = wv & 3;
;   const int lr = tid >> 1, lc = (tid & 1) * 32;
;   unsigned ao = (unsigned)(GATHER ? idx[m0 + lr] : (m0 + lr)) * (unsigned)lda + lc;
;   unsigned bo = (unsigned)(n0 + lr) * (unsigned)ldb + lc;
;   const h16* ap = A; const h16* bp = B;
;     ...
;   u4v ra[4], rb[4];
;   const int nk = K >> 6;
;   __syncthreads();
; #pragma unroll
;   for (int i = 0; i < 4; ++i) { ra[i] = *(const u4v*)(AP_ + 8 * i); rb[i] = *(const u4v*)(BP_ + 8 * i); }
;   ao += 64; bo += 64;
; #pragma unroll
;   for (int i = 0; i < 4; ++i) { *(u4v*)&lds[lr * LDH + lc + 8 * i] = ra[i]; *(u4v*)&lds[(256 + lr) * LDH + lc + 8 * i] = rb[i]; }
; #pragma unroll
;   for (int i = 0; i < 4; ++i) { ra[i] = *(const u4v*)(AP_ + 8 * i); rb[i] = *(const u4v*)(BP_ + 8 * i); }
;   ao += 64; bo += 64;
;   __syncthreads();
;   for (int kt = 0; kt < nk; ++kt) {
;     const h16* As = lds + (kt & 1) * (512 * LDH);
;     const h16* Bs = As + 256 * LDH;
;     h16* Wn = lds + ((kt & 1) ^ 1) * (512 * LDH);
;     if (kt + 1 < nk) {
; #pragma unroll
;       for (int i = 0; i < 4; ++i) { *(u4v*)&Wn[lr * LDH + lc + 8 * i] = ra[i]; *(u4v*)&Wn[(256 + lr) * LDH + lc + 8 * i] = rb[i]; }
;     }
;     if (kt + 2 < nk) {
; #pragma unroll
;       for (int i = 0; i < 4; ++i) { ra[i] = *(const u4v*)(AP_ + 8 * i); rb[i] = *(const u4v*)(BP_ + 8 * i); }
;       ao += 64; bo += 64;
;     }
; DI void phase_ffn1_moe(const Params& p, int bid, int nb, h16* lds) {
;     ...
;   for (int u = bid; u < ntl; u += nb) {
;     const int mt = u / 11, m0 = mt * 256, n0 = (u % 11) * 256;
;     int e = 0;
; #pragma unroll
;     for (int i = 1; i < 8; ++i) if (m0 >= ps[i]) e = i;
;     f16v acc[4][2]; acc256_zero(acc);
;     gemm256_main<true>(x16, DM, st, m0, w13 + (size_t)e * 2816 * 1024, 1024, n0, 1024, lds, acc);
.LBB0_1520:
	s_mul_hi_i32 s6, s5, 0x2e8ba2e9
	s_lshr_b32 s7, s6, 31
	s_ashr_i32 s6, s6, 1
	s_add_i32 s7, s6, s7
	v_mov_b32_e32 v34, v180
	s_lshl_b32 s6, s7, 8
	s_cmp_lt_i32 s6, s2
	v_ashrrev_i32_e32 v35, 1, v34
	v_lshlrev_b32_e32 v4, 5, v34
	v_and_b32_e32 v36, 32, v4
	v_add_u32_e32 v4, s6, v35
	v_ashrrev_i32_e32 v5, 31, v4
	v_lshl_add_u64 v[4:5], v[4:5], 2, s[16:17]
	global_load_dword v4, v[4:5], off
	s_cselect_b32 s8, 0, 0x2c0000
	s_cmp_lt_i32 s6, s3
	s_cselect_b32 s8, s8, 0x580000
	v_cmp_lt_i32_e32 vcc, s6, v1
	v_mov_b32_e32 v2, s8
	s_mulk_i32 s7, 0xb00
	v_cndmask_b32_e32 v2, v206, v2, vcc
	v_cmp_lt_i32_e32 vcc, s6, v171
	v_subrev_u32_e32 v5, s7, v35
	v_mov_b32_e32 v3, v0
	v_cndmask_b32_e32 v2, v207, v2, vcc
	v_cmp_lt_i32_e32 vcc, s6, v178
	v_add_u32_e32 v5, s4, v5
	v_lshl_or_b32 v6, v5, 10, v36
	v_cndmask_b32_e32 v2, v208, v2, vcc
	v_cmp_lt_i32_e32 vcc, s6, v179
	v_mov_b32_e32 v5, v0
	v_mov_b32_e32 v7, v0
	v_cndmask_b32_e32 v2, v209, v2, vcc
	v_cmp_lt_i32_e32 vcc, s6, v215
	s_barrier
	s_nop 0
	v_cndmask_b32_e32 v2, v210, v2, vcc
	v_lshlrev_b64 v[2:3], 1, v[2:3]
	v_lshl_add_u64 v[2:3], s[18:19], 0, v[2:3]
	v_lshl_add_u64 v[176:177], v[6:7], 1, v[2:3]
	v_mul_lo_u32 v37, v35, s33
	s_add_i32 s8, 16, 0x12000
	s_add_i32 s9, 16, 0x1b000
	s_add_i32 s5, s5, s22
	s_waitcnt vmcnt(0)
	v_lshl_or_b32 v4, v4, 10, v36
	v_lshl_add_u64 v[174:175], v[4:5], 1, s[20:21]
	v_mov_b32_e32 v130, v174
	v_mov_b32_e32 v131, v175
	v_mov_b32_e32 v200, v176
	v_mov_b32_e32 v201, v177
	v_lshrrev_b32_e32 v192, 1, v180
	v_and_b32_e32 v193, 1, v180
	v_mul_u32_u24_e32 v192, 0x90, v192
	v_lshl_add_u32 v132, v193, 6, v192
	v_add_u32_e32 v132, 16, v132
	v_add_u32_e32 v133, 0x12000, v132
	v_lshrrev_b32_e32 v192, 8, v180
	v_and_b32_e32 v194, 31, v180
	v_lshl_or_b32 v192, v192, 7, v194
	v_mul_u32_u24_e32 v192, 0x90, v192
	v_bfe_u32 v193, v180, 5, 1
	v_lshl_add_u32 v192, v193, 4, v192
	v_add_u32_e32 v217, 16, v192
	v_add_u32_e32 v212, 0x12000, v217
	v_bfe_u32 v192, v180, 6, 2
	v_lshl_or_b32 v192, v192, 6, v194
	v_mul_u32_u24_e32 v192, 0x90, v192
	v_lshl_add_u32 v192, v193, 4, v192
	v_add_u32_e32 v213, 0x9010, v192
	v_add_u32_e32 v214, 0x12000, v213
	global_load_dwordx4 v[134:137], v[130:131], off offset:0
	global_load_dwordx4 v[138:141], v[130:131], off offset:16
	global_load_dwordx4 v[142:145], v[130:131], off offset:32
	global_load_dwordx4 v[146:149], v[130:131], off offset:48
	global_load_dwordx4 v[150:153], v[200:201], off offset:0
	global_load_dwordx4 v[154:157], v[200:201], off offset:16
	global_load_dwordx4 v[158:161], v[200:201], off offset:32
	global_load_dwordx4 v[162:165], v[200:201], off offset:48
	s_waitcnt vmcnt(0)
	ds_write_b128 v132, v[134:137]
	ds_write_b128 v132, v[138:141] offset:16
	ds_write_b128 v132, v[142:145] offset:32
	ds_write_b128 v132, v[146:149] offset:48
	ds_write_b128 v132, v[150:153] offset:36864
	ds_write_b128 v132, v[154:157] offset:36880
	ds_write_b128 v132, v[158:161] offset:36896
	ds_write_b128 v132, v[162:165] offset:36912
	global_load_dwordx4 v[134:137], v[130:131], off offset:128
	global_load_dwordx4 v[138:141], v[130:131], off offset:144
	global_load_dwordx4 v[142:145], v[130:131], off offset:160
	global_load_dwordx4 v[146:149], v[130:131], off offset:176
	global_load_dwordx4 v[150:153], v[200:201], off offset:128
	global_load_dwordx4 v[154:157], v[200:201], off offset:144
	global_load_dwordx4 v[158:161], v[200:201], off offset:160
	global_load_dwordx4 v[162:165], v[200:201], off offset:176
	s_waitcnt lgkmcnt(0)
	s_barrier
	ds_read_b128 v[234:237], v213
	ds_read_b128 v[218:221], v217
	ds_read_b128 v[238:241], v213 offset:4608
	ds_read_b128 v[222:225], v217 offset:4608
	ds_read_b128 v[226:229], v217 offset:9216
	ds_read_b128 v[230:233], v217 offset:13824
	ds_read_b128 v[188:191], v213 offset:32
	ds_read_b128 v[242:245], v217 offset:32
	ds_read_b128 v[174:177], v213 offset:4640
	ds_read_b128 v[246:249], v217 offset:4640
	ds_read_b128 v[204:207], v217 offset:9248
	ds_read_b128 v[208:211], v217 offset:13856
	s_waitcnt vmcnt(4)
	ds_write_b128 v133, v[134:137]
	ds_write_b128 v133, v[138:141] offset:16
	ds_write_b128 v133, v[142:145] offset:32
	ds_write_b128 v133, v[146:149] offset:48
	global_load_dwordx4 v[134:137], v[130:131], off offset:256
	global_load_dwordx4 v[138:141], v[130:131], off offset:272
	global_load_dwordx4 v[142:145], v[130:131], off offset:288
	global_load_dwordx4 v[146:149], v[130:131], off offset:304
	s_waitcnt lgkmcnt(14)
	v_mfma_f32_32x32x16_f16 v[98:113], v[234:237], v[218:221], 0
	s_waitcnt lgkmcnt(13)
	v_mfma_f32_32x32x16_f16 v[114:129], v[238:241], v[218:221], 0
	s_waitcnt lgkmcnt(12)
	v_mfma_f32_32x32x16_f16 v[66:81], v[234:237], v[222:225], 0
	v_mfma_f32_32x32x16_f16 v[82:97], v[238:241], v[222:225], 0
	s_waitcnt lgkmcnt(11)
	v_mfma_f32_32x32x16_f16 v[34:49], v[234:237], v[226:229], 0
	v_mfma_f32_32x32x16_f16 v[50:65], v[238:241], v[226:229], 0
	s_waitcnt lgkmcnt(10)
	v_mfma_f32_32x32x16_f16 v[2:17], v[234:237], v[230:233], 0
	v_mfma_f32_32x32x16_f16 v[18:33], v[238:241], v[230:233], 0
	ds_read_b128 v[234:237], v213 offset:64
	ds_read_b128 v[218:221], v217 offset:64
	ds_read_b128 v[238:241], v213 offset:4672
	ds_read_b128 v[222:225], v217 offset:4672
	ds_read_b128 v[226:229], v217 offset:9280
	ds_read_b128 v[230:233], v217 offset:13888
	s_waitcnt vmcnt(4)
	ds_write_b128 v133, v[150:153] offset:36864
	ds_write_b128 v133, v[154:157] offset:36880
	ds_write_b128 v133, v[158:161] offset:36896
	ds_write_b128 v133, v[162:165] offset:36912
	global_load_dwordx4 v[150:153], v[200:201], off offset:256
	global_load_dwordx4 v[154:157], v[200:201], off offset:272
	global_load_dwordx4 v[158:161], v[200:201], off offset:288
	global_load_dwordx4 v[162:165], v[200:201], off offset:304
	s_waitcnt lgkmcnt(15)
; DI f16v mfma32(h8v a, h8v b, f16v c) { return __builtin_amdgcn_mfma_f32_32x32x16_f16(a, b, c, 0, 0, 0); }
; template <bool GATHER>
; DI void gemm256_main(const h16* __restrict__ A, int lda, const int* __restrict__ idx, int m0,
;                      const h16* __restrict__ B, int ldb, int n0, int K, h16* lds, f16v (&acc)[4][2]) {
;     ...
;   for (int kt = 0; kt < nk; ++kt) {
;     const h16* As = lds + (kt & 1) * (512 * LDH);
;     const h16* Bs = As + 256 * LDH;
;     h16* Wn = lds + ((kt & 1) ^ 1) * (512 * LDH);
;     if (kt + 1 < nk) {
; #pragma unroll
;       for (int i = 0; i < 4; ++i) { *(u4v*)&Wn[lr * LDH + lc + 8 * i] = ra[i]; *(u4v*)&Wn[(256 + lr) * LDH + lc + 8 * i] = rb[i]; }
;     }
;     if (kt + 2 < nk) {
; #pragma unroll
;       for (int i = 0; i < 4; ++i) { ra[i] = *(const u4v*)(AP_ + 8 * i); rb[i] = *(const u4v*)(BP_ + 8 * i); }
;       ao += 64; bo += 64;
;     }
; #pragma unroll
;     for (int ks = 0; ks < 4; ++ks) {
;       h8v af[4], bf[2];
; #pragma unroll
;       for (int i = 0; i < 4; ++i) af[i] = *(const h8v*)&As[(wm * 128 + i * 32 + (lane & 31)) * LDH + ks * 16 + 8 * (lane >> 5)];
; #pragma unroll
;       for (int j = 0; j < 2; ++j) bf[j] = *(const h8v*)&Bs[(wn * 64 + j * 32 + (lane & 31)) * LDH + ks * 16 + 8 * (lane >> 5)];
; #pragma unroll
;       for (int i = 0; i < 4; ++i)
; #pragma unroll
;         for (int j = 0; j < 2; ++j) acc[i][j] = mfma32(bf[j], af[i], acc[i][j]);
;     }
;     __syncthreads();
	v_mfma_f32_32x32x16_f16 v[98:113], v[188:191], v[242:245], v[98:113]
	s_waitcnt lgkmcnt(15)
	v_mfma_f32_32x32x16_f16 v[114:129], v[174:177], v[242:245], v[114:129]
	s_waitcnt lgkmcnt(15)
	v_mfma_f32_32x32x16_f16 v[66:81], v[188:191], v[246:249], v[66:81]
	v_mfma_f32_32x32x16_f16 v[82:97], v[174:177], v[246:249], v[82:97]
	s_waitcnt lgkmcnt(15)
	v_mfma_f32_32x32x16_f16 v[34:49], v[188:191], v[204:207], v[34:49]
	v_mfma_f32_32x32x16_f16 v[50:65], v[174:177], v[204:207], v[50:65]
	s_waitcnt lgkmcnt(14)
	v_mfma_f32_32x32x16_f16 v[2:17], v[188:191], v[208:211], v[2:17]
	v_mfma_f32_32x32x16_f16 v[18:33], v[174:177], v[208:211], v[18:33]
	ds_read_b128 v[188:191], v213 offset:96
	ds_read_b128 v[242:245], v217 offset:96
	ds_read_b128 v[174:177], v213 offset:4704
	ds_read_b128 v[246:249], v217 offset:4704
	ds_read_b128 v[204:207], v217 offset:9312
	ds_read_b128 v[208:211], v217 offset:13920
	s_waitcnt lgkmcnt(14)
	v_mfma_f32_32x32x16_f16 v[98:113], v[234:237], v[218:221], v[98:113]
	s_waitcnt lgkmcnt(13)
	v_mfma_f32_32x32x16_f16 v[114:129], v[238:241], v[218:221], v[114:129]
	s_waitcnt lgkmcnt(12)
	v_mfma_f32_32x32x16_f16 v[66:81], v[234:237], v[222:225], v[66:81]
	v_mfma_f32_32x32x16_f16 v[82:97], v[238:241], v[222:225], v[82:97]
	s_waitcnt lgkmcnt(11)
	v_mfma_f32_32x32x16_f16 v[34:49], v[234:237], v[226:229], v[34:49]
	v_mfma_f32_32x32x16_f16 v[50:65], v[238:241], v[226:229], v[50:65]
	s_waitcnt lgkmcnt(10)
	v_mfma_f32_32x32x16_f16 v[2:17], v[234:237], v[230:233], v[2:17]
	v_mfma_f32_32x32x16_f16 v[18:33], v[238:241], v[230:233], v[18:33]
	s_waitcnt lgkmcnt(0)
	s_barrier
	ds_read_b128 v[234:237], v214
	ds_read_b128 v[218:221], v212
	ds_read_b128 v[238:241], v214 offset:4608
	ds_read_b128 v[222:225], v212 offset:4608
	ds_read_b128 v[226:229], v212 offset:9216
	ds_read_b128 v[230:233], v212 offset:13824
	v_mfma_f32_32x32x16_f16 v[98:113], v[188:191], v[242:245], v[98:113]
	v_mfma_f32_32x32x16_f16 v[114:129], v[174:177], v[242:245], v[114:129]
	v_mfma_f32_32x32x16_f16 v[66:81], v[188:191], v[246:249], v[66:81]
	v_mfma_f32_32x32x16_f16 v[82:97], v[174:177], v[246:249], v[82:97]
	v_mfma_f32_32x32x16_f16 v[34:49], v[188:191], v[204:207], v[34:49]
	v_mfma_f32_32x32x16_f16 v[50:65], v[174:177], v[204:207], v[50:65]
	v_mfma_f32_32x32x16_f16 v[2:17], v[188:191], v[208:211], v[2:17]
	v_mfma_f32_32x32x16_f16 v[18:33], v[174:177], v[208:211], v[18:33]
	ds_read_b128 v[188:191], v214 offset:32
	ds_read_b128 v[242:245], v212 offset:32
	ds_read_b128 v[174:177], v214 offset:4640
	ds_read_b128 v[246:249], v212 offset:4640
	ds_read_b128 v[204:207], v212 offset:9248
	ds_read_b128 v[208:211], v212 offset:13856
	s_waitcnt vmcnt(4)
	ds_write_b128 v132, v[134:137]
	ds_write_b128 v132, v[138:141] offset:16
	ds_write_b128 v132, v[142:145] offset:32
	ds_write_b128 v132, v[146:149] offset:48
	global_load_dwordx4 v[134:137], v[130:131], off offset:384
	global_load_dwordx4 v[138:141], v[130:131], off offset:400
	global_load_dwordx4 v[142:145], v[130:131], off offset:416
	global_load_dwordx4 v[146:149], v[130:131], off offset:432
	s_waitcnt lgkmcnt(14)
	v_mfma_f32_32x32x16_f16 v[98:113], v[234:237], v[218:221], v[98:113]
	s_waitcnt lgkmcnt(13)
	v_mfma_f32_32x32x16_f16 v[114:129], v[238:241], v[218:221], v[114:129]
	s_waitcnt lgkmcnt(12)
	v_mfma_f32_32x32x16_f16 v[66:81], v[234:237], v[222:225], v[66:81]
	v_mfma_f32_32x32x16_f16 v[82:97], v[238:241], v[222:225], v[82:97]
	s_waitcnt lgkmcnt(11)
	v_mfma_f32_32x32x16_f16 v[34:49], v[234:237], v[226:229], v[34:49]
	v_mfma_f32_32x32x16_f16 v[50:65], v[238:241], v[226:229], v[50:65]
	s_waitcnt lgkmcnt(10)
	v_mfma_f32_32x32x16_f16 v[2:17], v[234:237], v[230:233], v[2:17]
	v_mfma_f32_32x32x16_f16 v[18:33], v[238:241], v[230:233], v[18:33]
	ds_read_b128 v[234:237], v214 offset:64
	ds_read_b128 v[218:221], v212 offset:64
	ds_read_b128 v[238:241], v214 offset:4672
	ds_read_b128 v[222:225], v212 offset:4672
	ds_read_b128 v[226:229], v212 offset:9280
	ds_read_b128 v[230:233], v212 offset:13888
	s_waitcnt vmcnt(4)
	ds_write_b128 v132, v[150:153] offset:36864
	ds_write_b128 v132, v[154:157] offset:36880
	ds_write_b128 v132, v[158:161] offset:36896
	ds_write_b128 v132, v[162:165] offset:36912
	global_load_dwordx4 v[150:153], v[200:201], off offset:384
	global_load_dwordx4 v[154:157], v[200:201], off offset:400
	global_load_dwordx4 v[158:161], v[200:201], off offset:416
	global_load_dwordx4 v[162:165], v[200:201], off offset:432
	s_waitcnt lgkmcnt(15)
	v_mfma_f32_32x32x16_f16 v[98:113], v[188:191], v[242:245], v[98:113]
	s_waitcnt lgkmcnt(15)
	v_mfma_f32_32x32x16_f16 v[114:129], v[174:177], v[242:245], v[114:129]
	s_waitcnt lgkmcnt(15)
	v_mfma_f32_32x32x16_f16 v[66:81], v[188:191], v[246:249], v[66:81]
	v_mfma_f32_32x32x16_f16 v[82:97], v[174:177], v[246:249], v[82:97]
	s_waitcnt lgkmcnt(15)
	v_mfma_f32_32x32x16_f16 v[34:49], v[188:191], v[204:207], v[34:49]
	v_mfma_f32_32x32x16_f16 v[50:65], v[174:177], v[204:207], v[50:65]
	s_waitcnt lgkmcnt(14)
	v_mfma_f32_32x32x16_f16 v[2:17], v[188:191], v[208:211], v[2:17]
	v_mfma_f32_32x32x16_f16 v[18:33], v[174:177], v[208:211], v[18:33]
	ds_read_b128 v[188:191], v214 offset:96
	ds_read_b128 v[242:245], v212 offset:96
	ds_read_b128 v[174:177], v214 offset:4704
	ds_read_b128 v[246:249], v212 offset:4704
	ds_read_b128 v[204:207], v212 offset:9312
	ds_read_b128 v[208:211], v212 offset:13920
	s_waitcnt lgkmcnt(14)
	v_mfma_f32_32x32x16_f16 v[98:113], v[234:237], v[218:221], v[98:113]
	s_waitcnt lgkmcnt(13)
	v_mfma_f32_32x32x16_f16 v[114:129], v[238:241], v[218:221], v[114:129]
	s_waitcnt lgkmcnt(12)
	v_mfma_f32_32x32x16_f16 v[66:81], v[234:237], v[222:225], v[66:81]
	v_mfma_f32_32x32x16_f16 v[82:97], v[238:241], v[222:225], v[82:97]
	s_waitcnt lgkmcnt(11)
	v_mfma_f32_32x32x16_f16 v[34:49], v[234:237], v[226:229], v[34:49]
	v_mfma_f32_32x32x16_f16 v[50:65], v[238:241], v[226:229], v[50:65]
	s_waitcnt lgkmcnt(10)
	v_mfma_f32_32x32x16_f16 v[2:17], v[234:237], v[230:233], v[2:17]
	v_mfma_f32_32x32x16_f16 v[18:33], v[238:241], v[230:233], v[18:33]
	s_waitcnt lgkmcnt(0)
	s_barrier
; DI f16v mfma32(h8v a, h8v b, f16v c) { return __builtin_amdgcn_mfma_f32_32x32x16_f16(a, b, c, 0, 0, 0); }
; template <bool GATHER>
; DI void gemm256_main(const h16* __restrict__ A, int lda, const int* __restrict__ idx, int m0,
;                      const h16* __restrict__ B, int ldb, int n0, int K, h16* lds, f16v (&acc)[4][2]) {
;     ...
;   for (int kt = 0; kt < nk; ++kt) {
;     const h16* As = lds + (kt & 1) * (512 * LDH);
;     const h16* Bs = As + 256 * LDH;
;     h16* Wn = lds + ((kt & 1) ^ 1) * (512 * LDH);
;     if (kt + 1 < nk) {
; #pragma unroll
;       for (int i = 0; i < 4; ++i) { *(u4v*)&Wn[lr * LDH + lc + 8 * i] = ra[i]; *(u4v*)&Wn[(256 + lr) * LDH + lc + 8 * i] = rb[i]; }
;     }
;     if (kt + 2 < nk) {
; #pragma unroll
;       for (int i = 0; i < 4; ++i) { ra[i] = *(const u4v*)(AP_ + 8 * i); rb[i] = *(const u4v*)(BP_ + 8 * i); }
;       ao += 64; bo += 64;
;     }
; #pragma unroll
;     for (int ks = 0; ks < 4; ++ks) {
;       h8v af[4], bf[2];
; #pragma unroll
;       for (int i = 0; i < 4; ++i) af[i] = *(const h8v*)&As[(wm * 128 + i * 32 + (lane & 31)) * LDH + ks * 16 + 8 * (lane >> 5)];
; #pragma unroll
;       for (int j = 0; j < 2; ++j) bf[j] = *(const h8v*)&Bs[(wn * 64 + j * 32 + (lane & 31)) * LDH + ks * 16 + 8 * (lane >> 5)];
; #pragma unroll
;       for (int i = 0; i < 4; ++i)
; #pragma unroll
;         for (int j = 0; j < 2; ++j) acc[i][j] = mfma32(bf[j], af[i], acc[i][j]);
;     }
;     __syncthreads();
	ds_read_b128 v[234:237], v213
	ds_read_b128 v[218:221], v217
	ds_read_b128 v[238:241], v213 offset:4608
	ds_read_b128 v[222:225], v217 offset:4608
	ds_read_b128 v[226:229], v217 offset:9216
	ds_read_b128 v[230:233], v217 offset:13824
	v_mfma_f32_32x32x16_f16 v[98:113], v[188:191], v[242:245], v[98:113]
	v_mfma_f32_32x32x16_f16 v[114:129], v[174:177], v[242:245], v[114:129]
	v_mfma_f32_32x32x16_f16 v[66:81], v[188:191], v[246:249], v[66:81]
	v_mfma_f32_32x32x16_f16 v[82:97], v[174:177], v[246:249], v[82:97]
	v_mfma_f32_32x32x16_f16 v[34:49], v[188:191], v[204:207], v[34:49]
	v_mfma_f32_32x32x16_f16 v[50:65], v[174:177], v[204:207], v[50:65]
	v_mfma_f32_32x32x16_f16 v[2:17], v[188:191], v[208:211], v[2:17]
	v_mfma_f32_32x32x16_f16 v[18:33], v[174:177], v[208:211], v[18:33]
	ds_read_b128 v[188:191], v213 offset:32
	ds_read_b128 v[242:245], v217 offset:32
	ds_read_b128 v[174:177], v213 offset:4640
	ds_read_b128 v[246:249], v217 offset:4640
	ds_read_b128 v[204:207], v217 offset:9248
	ds_read_b128 v[208:211], v217 offset:13856
	s_waitcnt vmcnt(4)
	ds_write_b128 v133, v[134:137]
	ds_write_b128 v133, v[138:141] offset:16
	ds_write_b128 v133, v[142:145] offset:32
	ds_write_b128 v133, v[146:149] offset:48
	global_load_dwordx4 v[134:137], v[130:131], off offset:512
	global_load_dwordx4 v[138:141], v[130:131], off offset:528
	global_load_dwordx4 v[142:145], v[130:131], off offset:544
	global_load_dwordx4 v[146:149], v[130:131], off offset:560
	s_waitcnt lgkmcnt(14)
	v_mfma_f32_32x32x16_f16 v[98:113], v[234:237], v[218:221], v[98:113]
	s_waitcnt lgkmcnt(13)
	v_mfma_f32_32x32x16_f16 v[114:129], v[238:241], v[218:221], v[114:129]
	s_waitcnt lgkmcnt(12)
	v_mfma_f32_32x32x16_f16 v[66:81], v[234:237], v[222:225], v[66:81]
	v_mfma_f32_32x32x16_f16 v[82:97], v[238:241], v[222:225], v[82:97]
	s_waitcnt lgkmcnt(11)
	v_mfma_f32_32x32x16_f16 v[34:49], v[234:237], v[226:229], v[34:49]
	v_mfma_f32_32x32x16_f16 v[50:65], v[238:241], v[226:229], v[50:65]
	s_waitcnt lgkmcnt(10)
	v_mfma_f32_32x32x16_f16 v[2:17], v[234:237], v[230:233], v[2:17]
	v_mfma_f32_32x32x16_f16 v[18:33], v[238:241], v[230:233], v[18:33]
	ds_read_b128 v[234:237], v213 offset:64
	ds_read_b128 v[218:221], v217 offset:64
	ds_read_b128 v[238:241], v213 offset:4672
	ds_read_b128 v[222:225], v217 offset:4672
	ds_read_b128 v[226:229], v217 offset:9280
	ds_read_b128 v[230:233], v217 offset:13888
	s_waitcnt vmcnt(4)
	ds_write_b128 v133, v[150:153] offset:36864
	ds_write_b128 v133, v[154:157] offset:36880
	ds_write_b128 v133, v[158:161] offset:36896
	ds_write_b128 v133, v[162:165] offset:36912
	global_load_dwordx4 v[150:153], v[200:201], off offset:512
	global_load_dwordx4 v[154:157], v[200:201], off offset:528
	global_load_dwordx4 v[158:161], v[200:201], off offset:544
	global_load_dwordx4 v[162:165], v[200:201], off offset:560
	s_waitcnt lgkmcnt(15)
	v_mfma_f32_32x32x16_f16 v[98:113], v[188:191], v[242:245], v[98:113]
	s_waitcnt lgkmcnt(15)
	v_mfma_f32_32x32x16_f16 v[114:129], v[174:177], v[242:245], v[114:129]
	s_waitcnt lgkmcnt(15)
	v_mfma_f32_32x32x16_f16 v[66:81], v[188:191], v[246:249], v[66:81]
	v_mfma_f32_32x32x16_f16 v[82:97], v[174:177], v[246:249], v[82:97]
	s_waitcnt lgkmcnt(15)
	v_mfma_f32_32x32x16_f16 v[34:49], v[188:191], v[204:207], v[34:49]
	v_mfma_f32_32x32x16_f16 v[50:65], v[174:177], v[204:207], v[50:65]
	s_waitcnt lgkmcnt(14)
	v_mfma_f32_32x32x16_f16 v[2:17], v[188:191], v[208:211], v[2:17]
	v_mfma_f32_32x32x16_f16 v[18:33], v[174:177], v[208:211], v[18:33]
	ds_read_b128 v[188:191], v213 offset:96
	ds_read_b128 v[242:245], v217 offset:96
	ds_read_b128 v[174:177], v213 offset:4704
	ds_read_b128 v[246:249], v217 offset:4704
	ds_read_b128 v[204:207], v217 offset:9312
	ds_read_b128 v[208:211], v217 offset:13920
	s_waitcnt lgkmcnt(14)
	v_mfma_f32_32x32x16_f16 v[98:113], v[234:237], v[218:221], v[98:113]
	s_waitcnt lgkmcnt(13)
	v_mfma_f32_32x32x16_f16 v[114:129], v[238:241], v[218:221], v[114:129]
	s_waitcnt lgkmcnt(12)
	v_mfma_f32_32x32x16_f16 v[66:81], v[234:237], v[222:225], v[66:81]
	v_mfma_f32_32x32x16_f16 v[82:97], v[238:241], v[222:225], v[82:97]
	s_waitcnt lgkmcnt(11)
	v_mfma_f32_32x32x16_f16 v[34:49], v[234:237], v[226:229], v[34:49]
	v_mfma_f32_32x32x16_f16 v[50:65], v[238:241], v[226:229], v[50:65]
	s_waitcnt lgkmcnt(10)
	v_mfma_f32_32x32x16_f16 v[2:17], v[234:237], v[230:233], v[2:17]
	v_mfma_f32_32x32x16_f16 v[18:33], v[238:241], v[230:233], v[18:33]
	s_waitcnt lgkmcnt(0)
	s_barrier
; DI f16v mfma32(h8v a, h8v b, f16v c) { return __builtin_amdgcn_mfma_f32_32x32x16_f16(a, b, c, 0, 0, 0); }
; template <bool GATHER>
; DI void gemm256_main(const h16* __restrict__ A, int lda, const int* __restrict__ idx, int m0,
;                      const h16* __restrict__ B, int ldb, int n0, int K, h16* lds, f16v (&acc)[4][2]) {
;     ...
;   for (int kt = 0; kt < nk; ++kt) {
;     const h16* As = lds + (kt & 1) * (512 * LDH);
;     const h16* Bs = As + 256 * LDH;
;     h16* Wn = lds + ((kt & 1) ^ 1) * (512 * LDH);
;     if (kt + 1 < nk) {
; #pragma unroll
;       for (int i = 0; i < 4; ++i) { *(u4v*)&Wn[lr * LDH + lc + 8 * i] = ra[i]; *(u4v*)&Wn[(256 + lr) * LDH + lc + 8 * i] = rb[i]; }
;     }
;     if (kt + 2 < nk) {
; #pragma unroll
;       for (int i = 0; i < 4; ++i) { ra[i] = *(const u4v*)(AP_ + 8 * i); rb[i] = *(const u4v*)(BP_ + 8 * i); }
;       ao += 64; bo += 64;
;     }
; #pragma unroll
;     for (int ks = 0; ks < 4; ++ks) {
;       h8v af[4], bf[2];
; #pragma unroll
;       for (int i = 0; i < 4; ++i) af[i] = *(const h8v*)&As[(wm * 128 + i * 32 + (lane & 31)) * LDH + ks * 16 + 8 * (lane >> 5)];
; #pragma unroll
;       for (int j = 0; j < 2; ++j) bf[j] = *(const h8v*)&Bs[(wn * 64 + j * 32 + (lane & 31)) * LDH + ks * 16 + 8 * (lane >> 5)];
; #pragma unroll
;       for (int i = 0; i < 4; ++i)
; #pragma unroll
;         for (int j = 0; j < 2; ++j) acc[i][j] = mfma32(bf[j], af[i], acc[i][j]);
;     }
;     __syncthreads();
	ds_read_b128 v[234:237], v214
	ds_read_b128 v[218:221], v212
	ds_read_b128 v[238:241], v214 offset:4608
	ds_read_b128 v[222:225], v212 offset:4608
	ds_read_b128 v[226:229], v212 offset:9216
	ds_read_b128 v[230:233], v212 offset:13824
	v_mfma_f32_32x32x16_f16 v[98:113], v[188:191], v[242:245], v[98:113]
	v_mfma_f32_32x32x16_f16 v[114:129], v[174:177], v[242:245], v[114:129]
	v_mfma_f32_32x32x16_f16 v[66:81], v[188:191], v[246:249], v[66:81]
	v_mfma_f32_32x32x16_f16 v[82:97], v[174:177], v[246:249], v[82:97]
	v_mfma_f32_32x32x16_f16 v[34:49], v[188:191], v[204:207], v[34:49]
	v_mfma_f32_32x32x16_f16 v[50:65], v[174:177], v[204:207], v[50:65]
	v_mfma_f32_32x32x16_f16 v[2:17], v[188:191], v[208:211], v[2:17]
	v_mfma_f32_32x32x16_f16 v[18:33], v[174:177], v[208:211], v[18:33]
	ds_read_b128 v[188:191], v214 offset:32
	ds_read_b128 v[242:245], v212 offset:32
	ds_read_b128 v[174:177], v214 offset:4640
	ds_read_b128 v[246:249], v212 offset:4640
	ds_read_b128 v[204:207], v212 offset:9248
	ds_read_b128 v[208:211], v212 offset:13856
	s_waitcnt vmcnt(4)
	ds_write_b128 v132, v[134:137]
	ds_write_b128 v132, v[138:141] offset:16
	ds_write_b128 v132, v[142:145] offset:32
	ds_write_b128 v132, v[146:149] offset:48
	global_load_dwordx4 v[134:137], v[130:131], off offset:640
	global_load_dwordx4 v[138:141], v[130:131], off offset:656
	global_load_dwordx4 v[142:145], v[130:131], off offset:672
	global_load_dwordx4 v[146:149], v[130:131], off offset:688
	s_waitcnt lgkmcnt(14)
	v_mfma_f32_32x32x16_f16 v[98:113], v[234:237], v[218:221], v[98:113]
	s_waitcnt lgkmcnt(13)
	v_mfma_f32_32x32x16_f16 v[114:129], v[238:241], v[218:221], v[114:129]
	s_waitcnt lgkmcnt(12)
	v_mfma_f32_32x32x16_f16 v[66:81], v[234:237], v[222:225], v[66:81]
	v_mfma_f32_32x32x16_f16 v[82:97], v[238:241], v[222:225], v[82:97]
	s_waitcnt lgkmcnt(11)
	v_mfma_f32_32x32x16_f16 v[34:49], v[234:237], v[226:229], v[34:49]
	v_mfma_f32_32x32x16_f16 v[50:65], v[238:241], v[226:229], v[50:65]
	s_waitcnt lgkmcnt(10)
	v_mfma_f32_32x32x16_f16 v[2:17], v[234:237], v[230:233], v[2:17]
	v_mfma_f32_32x32x16_f16 v[18:33], v[238:241], v[230:233], v[18:33]
	ds_read_b128 v[234:237], v214 offset:64
	ds_read_b128 v[218:221], v212 offset:64
	ds_read_b128 v[238:241], v214 offset:4672
	ds_read_b128 v[222:225], v212 offset:4672
	ds_read_b128 v[226:229], v212 offset:9280
	ds_read_b128 v[230:233], v212 offset:13888
	s_waitcnt vmcnt(4)
	ds_write_b128 v132, v[150:153] offset:36864
	ds_write_b128 v132, v[154:157] offset:36880
	ds_write_b128 v132, v[158:161] offset:36896
	ds_write_b128 v132, v[162:165] offset:36912
	global_load_dwordx4 v[150:153], v[200:201], off offset:640
	global_load_dwordx4 v[154:157], v[200:201], off offset:656
	global_load_dwordx4 v[158:161], v[200:201], off offset:672
	global_load_dwordx4 v[162:165], v[200:201], off offset:688
	s_waitcnt lgkmcnt(15)
	v_mfma_f32_32x32x16_f16 v[98:113], v[188:191], v[242:245], v[98:113]
	s_waitcnt lgkmcnt(15)
	v_mfma_f32_32x32x16_f16 v[114:129], v[174:177], v[242:245], v[114:129]
	s_waitcnt lgkmcnt(15)
	v_mfma_f32_32x32x16_f16 v[66:81], v[188:191], v[246:249], v[66:81]
	v_mfma_f32_32x32x16_f16 v[82:97], v[174:177], v[246:249], v[82:97]
	s_waitcnt lgkmcnt(15)
	v_mfma_f32_32x32x16_f16 v[34:49], v[188:191], v[204:207], v[34:49]
	v_mfma_f32_32x32x16_f16 v[50:65], v[174:177], v[204:207], v[50:65]
	s_waitcnt lgkmcnt(14)
	v_mfma_f32_32x32x16_f16 v[2:17], v[188:191], v[208:211], v[2:17]
	v_mfma_f32_32x32x16_f16 v[18:33], v[174:177], v[208:211], v[18:33]
	ds_read_b128 v[188:191], v214 offset:96
	ds_read_b128 v[242:245], v212 offset:96
	ds_read_b128 v[174:177], v214 offset:4704
	ds_read_b128 v[246:249], v212 offset:4704
	ds_read_b128 v[204:207], v212 offset:9312
	ds_read_b128 v[208:211], v212 offset:13920
	s_waitcnt lgkmcnt(14)
	v_mfma_f32_32x32x16_f16 v[98:113], v[234:237], v[218:221], v[98:113]
	s_waitcnt lgkmcnt(13)
	v_mfma_f32_32x32x16_f16 v[114:129], v[238:241], v[218:221], v[114:129]
	s_waitcnt lgkmcnt(12)
	v_mfma_f32_32x32x16_f16 v[66:81], v[234:237], v[222:225], v[66:81]
	v_mfma_f32_32x32x16_f16 v[82:97], v[238:241], v[222:225], v[82:97]
	s_waitcnt lgkmcnt(11)
	v_mfma_f32_32x32x16_f16 v[34:49], v[234:237], v[226:229], v[34:49]
	v_mfma_f32_32x32x16_f16 v[50:65], v[238:241], v[226:229], v[50:65]
	s_waitcnt lgkmcnt(10)
	v_mfma_f32_32x32x16_f16 v[2:17], v[234:237], v[230:233], v[2:17]
	v_mfma_f32_32x32x16_f16 v[18:33], v[238:241], v[230:233], v[18:33]
	s_waitcnt lgkmcnt(0)
	s_barrier
; DI f16v mfma32(h8v a, h8v b, f16v c) { return __builtin_amdgcn_mfma_f32_32x32x16_f16(a, b, c, 0, 0, 0); }
; template <bool GATHER>
; DI void gemm256_main(const h16* __restrict__ A, int lda, const int* __restrict__ idx, int m0,
;                      const h16* __restrict__ B, int ldb, int n0, int K, h16* lds, f16v (&acc)[4][2]) {
;     ...
;   for (int kt = 0; kt < nk; ++kt) {
;     const h16* As = lds + (kt & 1) * (512 * LDH);
;     const h16* Bs = As + 256 * LDH;
;     h16* Wn = lds + ((kt & 1) ^ 1) * (512 * LDH);
;     if (kt + 1 < nk) {
; #pragma unroll
;       for (int i = 0; i < 4; ++i) { *(u4v*)&Wn[lr * LDH + lc + 8 * i] = ra[i]; *(u4v*)&Wn[(256 + lr) * LDH + lc + 8 * i] = rb[i]; }
;     }
;     if (kt + 2 < nk) {
; #pragma unroll
;       for (int i = 0; i < 4; ++i) { ra[i] = *(const u4v*)(AP_ + 8 * i); rb[i] = *(const u4v*)(BP_ + 8 * i); }
;       ao += 64; bo += 64;
;     }
; #pragma unroll
;     for (int ks = 0; ks < 4; ++ks) {
;       h8v af[4], bf[2];
; #pragma unroll
;       for (int i = 0; i < 4; ++i) af[i] = *(const h8v*)&As[(wm * 128 + i * 32 + (lane & 31)) * LDH + ks * 16 + 8 * (lane >> 5)];
; #pragma unroll
;       for (int j = 0; j < 2; ++j) bf[j] = *(const h8v*)&Bs[(wn * 64 + j * 32 + (lane & 31)) * LDH + ks * 16 + 8 * (lane >> 5)];
; #pragma unroll
;       for (int i = 0; i < 4; ++i)
; #pragma unroll
;         for (int j = 0; j < 2; ++j) acc[i][j] = mfma32(bf[j], af[i], acc[i][j]);
;     }
;     __syncthreads();
	ds_read_b128 v[234:237], v213
	ds_read_b128 v[218:221], v217
	ds_read_b128 v[238:241], v213 offset:4608
	ds_read_b128 v[222:225], v217 offset:4608
	ds_read_b128 v[226:229], v217 offset:9216
	ds_read_b128 v[230:233], v217 offset:13824
	v_mfma_f32_32x32x16_f16 v[98:113], v[188:191], v[242:245], v[98:113]
	v_mfma_f32_32x32x16_f16 v[114:129], v[174:177], v[242:245], v[114:129]
	v_mfma_f32_32x32x16_f16 v[66:81], v[188:191], v[246:249], v[66:81]
	v_mfma_f32_32x32x16_f16 v[82:97], v[174:177], v[246:249], v[82:97]
	v_mfma_f32_32x32x16_f16 v[34:49], v[188:191], v[204:207], v[34:49]
	v_mfma_f32_32x32x16_f16 v[50:65], v[174:177], v[204:207], v[50:65]
	v_mfma_f32_32x32x16_f16 v[2:17], v[188:191], v[208:211], v[2:17]
	v_mfma_f32_32x32x16_f16 v[18:33], v[174:177], v[208:211], v[18:33]
	ds_read_b128 v[188:191], v213 offset:32
	ds_read_b128 v[242:245], v217 offset:32
	ds_read_b128 v[174:177], v213 offset:4640
	ds_read_b128 v[246:249], v217 offset:4640
	ds_read_b128 v[204:207], v217 offset:9248
	ds_read_b128 v[208:211], v217 offset:13856
	s_waitcnt vmcnt(4)
	ds_write_b128 v133, v[134:137]
	ds_write_b128 v133, v[138:141] offset:16
	ds_write_b128 v133, v[142:145] offset:32
	ds_write_b128 v133, v[146:149] offset:48
	global_load_dwordx4 v[134:137], v[130:131], off offset:768
	global_load_dwordx4 v[138:141], v[130:131], off offset:784
	global_load_dwordx4 v[142:145], v[130:131], off offset:800
	global_load_dwordx4 v[146:149], v[130:131], off offset:816
	s_waitcnt lgkmcnt(14)
	v_mfma_f32_32x32x16_f16 v[98:113], v[234:237], v[218:221], v[98:113]
	s_waitcnt lgkmcnt(13)
	v_mfma_f32_32x32x16_f16 v[114:129], v[238:241], v[218:221], v[114:129]
	s_waitcnt lgkmcnt(12)
	v_mfma_f32_32x32x16_f16 v[66:81], v[234:237], v[222:225], v[66:81]
	v_mfma_f32_32x32x16_f16 v[82:97], v[238:241], v[222:225], v[82:97]
	s_waitcnt lgkmcnt(11)
	v_mfma_f32_32x32x16_f16 v[34:49], v[234:237], v[226:229], v[34:49]
	v_mfma_f32_32x32x16_f16 v[50:65], v[238:241], v[226:229], v[50:65]
	s_waitcnt lgkmcnt(10)
	v_mfma_f32_32x32x16_f16 v[2:17], v[234:237], v[230:233], v[2:17]
	v_mfma_f32_32x32x16_f16 v[18:33], v[238:241], v[230:233], v[18:33]
	ds_read_b128 v[234:237], v213 offset:64
	ds_read_b128 v[218:221], v217 offset:64
	ds_read_b128 v[238:241], v213 offset:4672
	ds_read_b128 v[222:225], v217 offset:4672
	ds_read_b128 v[226:229], v217 offset:9280
	ds_read_b128 v[230:233], v217 offset:13888
	s_waitcnt vmcnt(4)
	ds_write_b128 v133, v[150:153] offset:36864
	ds_write_b128 v133, v[154:157] offset:36880
	ds_write_b128 v133, v[158:161] offset:36896
	ds_write_b128 v133, v[162:165] offset:36912
	global_load_dwordx4 v[150:153], v[200:201], off offset:768
	global_load_dwordx4 v[154:157], v[200:201], off offset:784
	global_load_dwordx4 v[158:161], v[200:201], off offset:800
	global_load_dwordx4 v[162:165], v[200:201], off offset:816
	s_waitcnt lgkmcnt(15)
	v_mfma_f32_32x32x16_f16 v[98:113], v[188:191], v[242:245], v[98:113]
	s_waitcnt lgkmcnt(15)
	v_mfma_f32_32x32x16_f16 v[114:129], v[174:177], v[242:245], v[114:129]
	s_waitcnt lgkmcnt(15)
	v_mfma_f32_32x32x16_f16 v[66:81], v[188:191], v[246:249], v[66:81]
	v_mfma_f32_32x32x16_f16 v[82:97], v[174:177], v[246:249], v[82:97]
	s_waitcnt lgkmcnt(15)
	v_mfma_f32_32x32x16_f16 v[34:49], v[188:191], v[204:207], v[34:49]
	v_mfma_f32_32x32x16_f16 v[50:65], v[174:177], v[204:207], v[50:65]
	s_waitcnt lgkmcnt(14)
	v_mfma_f32_32x32x16_f16 v[2:17], v[188:191], v[208:211], v[2:17]
	v_mfma_f32_32x32x16_f16 v[18:33], v[174:177], v[208:211], v[18:33]
	ds_read_b128 v[188:191], v213 offset:96
	ds_read_b128 v[242:245], v217 offset:96
	ds_read_b128 v[174:177], v213 offset:4704
	ds_read_b128 v[246:249], v217 offset:4704
	ds_read_b128 v[204:207], v217 offset:9312
	ds_read_b128 v[208:211], v217 offset:13920
	s_waitcnt lgkmcnt(14)
	v_mfma_f32_32x32x16_f16 v[98:113], v[234:237], v[218:221], v[98:113]
	s_waitcnt lgkmcnt(13)
	v_mfma_f32_32x32x16_f16 v[114:129], v[238:241], v[218:221], v[114:129]
	s_waitcnt lgkmcnt(12)
	v_mfma_f32_32x32x16_f16 v[66:81], v[234:237], v[222:225], v[66:81]
	v_mfma_f32_32x32x16_f16 v[82:97], v[238:241], v[222:225], v[82:97]
	s_waitcnt lgkmcnt(11)
	v_mfma_f32_32x32x16_f16 v[34:49], v[234:237], v[226:229], v[34:49]
	v_mfma_f32_32x32x16_f16 v[50:65], v[238:241], v[226:229], v[50:65]
	s_waitcnt lgkmcnt(10)
	v_mfma_f32_32x32x16_f16 v[2:17], v[234:237], v[230:233], v[2:17]
	v_mfma_f32_32x32x16_f16 v[18:33], v[238:241], v[230:233], v[18:33]
	s_waitcnt lgkmcnt(0)
	s_barrier
; DI f16v mfma32(h8v a, h8v b, f16v c) { return __builtin_amdgcn_mfma_f32_32x32x16_f16(a, b, c, 0, 0, 0); }
; template <bool GATHER>
; DI void gemm256_main(const h16* __restrict__ A, int lda, const int* __restrict__ idx, int m0,
;                      const h16* __restrict__ B, int ldb, int n0, int K, h16* lds, f16v (&acc)[4][2]) {
;     ...
;   for (int kt = 0; kt < nk; ++kt) {
;     const h16* As = lds + (kt & 1) * (512 * LDH);
;     const h16* Bs = As + 256 * LDH;
;     h16* Wn = lds + ((kt & 1) ^ 1) * (512 * LDH);
;     if (kt + 1 < nk) {
; #pragma unroll
;       for (int i = 0; i < 4; ++i) { *(u4v*)&Wn[lr * LDH + lc + 8 * i] = ra[i]; *(u4v*)&Wn[(256 + lr) * LDH + lc + 8 * i] = rb[i]; }
;     }
;     if (kt + 2 < nk) {
; #pragma unroll
;       for (int i = 0; i < 4; ++i) { ra[i] = *(const u4v*)(AP_ + 8 * i); rb[i] = *(const u4v*)(BP_ + 8 * i); }
;       ao += 64; bo += 64;
;     }
; #pragma unroll
;     for (int ks = 0; ks < 4; ++ks) {
;       h8v af[4], bf[2];
; #pragma unroll
;       for (int i = 0; i < 4; ++i) af[i] = *(const h8v*)&As[(wm * 128 + i * 32 + (lane & 31)) * LDH + ks * 16 + 8 * (lane >> 5)];
; #pragma unroll
;       for (int j = 0; j < 2; ++j) bf[j] = *(const h8v*)&Bs[(wn * 64 + j * 32 + (lane & 31)) * LDH + ks * 16 + 8 * (lane >> 5)];
; #pragma unroll
;       for (int i = 0; i < 4; ++i)
; #pragma unroll
;         for (int j = 0; j < 2; ++j) acc[i][j] = mfma32(bf[j], af[i], acc[i][j]);
;     }
;     __syncthreads();
	ds_read_b128 v[234:237], v214
	ds_read_b128 v[218:221], v212
	ds_read_b128 v[238:241], v214 offset:4608
	ds_read_b128 v[222:225], v212 offset:4608
	ds_read_b128 v[226:229], v212 offset:9216
	ds_read_b128 v[230:233], v212 offset:13824
	v_mfma_f32_32x32x16_f16 v[98:113], v[188:191], v[242:245], v[98:113]
	v_mfma_f32_32x32x16_f16 v[114:129], v[174:177], v[242:245], v[114:129]
	v_mfma_f32_32x32x16_f16 v[66:81], v[188:191], v[246:249], v[66:81]
	v_mfma_f32_32x32x16_f16 v[82:97], v[174:177], v[246:249], v[82:97]
	v_mfma_f32_32x32x16_f16 v[34:49], v[188:191], v[204:207], v[34:49]
	v_mfma_f32_32x32x16_f16 v[50:65], v[174:177], v[204:207], v[50:65]
	v_mfma_f32_32x32x16_f16 v[2:17], v[188:191], v[208:211], v[2:17]
	v_mfma_f32_32x32x16_f16 v[18:33], v[174:177], v[208:211], v[18:33]
	ds_read_b128 v[188:191], v214 offset:32
	ds_read_b128 v[242:245], v212 offset:32
	ds_read_b128 v[174:177], v214 offset:4640
	ds_read_b128 v[246:249], v212 offset:4640
	ds_read_b128 v[204:207], v212 offset:9248
	ds_read_b128 v[208:211], v212 offset:13856
	s_waitcnt vmcnt(4)
	ds_write_b128 v132, v[134:137]
	ds_write_b128 v132, v[138:141] offset:16
	ds_write_b128 v132, v[142:145] offset:32
	ds_write_b128 v132, v[146:149] offset:48
	global_load_dwordx4 v[134:137], v[130:131], off offset:896
	global_load_dwordx4 v[138:141], v[130:131], off offset:912
	global_load_dwordx4 v[142:145], v[130:131], off offset:928
	global_load_dwordx4 v[146:149], v[130:131], off offset:944
	s_waitcnt lgkmcnt(14)
	v_mfma_f32_32x32x16_f16 v[98:113], v[234:237], v[218:221], v[98:113]
	s_waitcnt lgkmcnt(13)
	v_mfma_f32_32x32x16_f16 v[114:129], v[238:241], v[218:221], v[114:129]
	s_waitcnt lgkmcnt(12)
	v_mfma_f32_32x32x16_f16 v[66:81], v[234:237], v[222:225], v[66:81]
	v_mfma_f32_32x32x16_f16 v[82:97], v[238:241], v[222:225], v[82:97]
	s_waitcnt lgkmcnt(11)
	v_mfma_f32_32x32x16_f16 v[34:49], v[234:237], v[226:229], v[34:49]
	v_mfma_f32_32x32x16_f16 v[50:65], v[238:241], v[226:229], v[50:65]
	s_waitcnt lgkmcnt(10)
	v_mfma_f32_32x32x16_f16 v[2:17], v[234:237], v[230:233], v[2:17]
	v_mfma_f32_32x32x16_f16 v[18:33], v[238:241], v[230:233], v[18:33]
	ds_read_b128 v[234:237], v214 offset:64
	ds_read_b128 v[218:221], v212 offset:64
	ds_read_b128 v[238:241], v214 offset:4672
	ds_read_b128 v[222:225], v212 offset:4672
	ds_read_b128 v[226:229], v212 offset:9280
	ds_read_b128 v[230:233], v212 offset:13888
	s_waitcnt vmcnt(4)
	ds_write_b128 v132, v[150:153] offset:36864
	ds_write_b128 v132, v[154:157] offset:36880
	ds_write_b128 v132, v[158:161] offset:36896
	ds_write_b128 v132, v[162:165] offset:36912
	global_load_dwordx4 v[150:153], v[200:201], off offset:896
	global_load_dwordx4 v[154:157], v[200:201], off offset:912
	global_load_dwordx4 v[158:161], v[200:201], off offset:928
	global_load_dwordx4 v[162:165], v[200:201], off offset:944
	s_waitcnt lgkmcnt(15)
	v_mfma_f32_32x32x16_f16 v[98:113], v[188:191], v[242:245], v[98:113]
	s_waitcnt lgkmcnt(15)
	v_mfma_f32_32x32x16_f16 v[114:129], v[174:177], v[242:245], v[114:129]
	s_waitcnt lgkmcnt(15)
	v_mfma_f32_32x32x16_f16 v[66:81], v[188:191], v[246:249], v[66:81]
	v_mfma_f32_32x32x16_f16 v[82:97], v[174:177], v[246:249], v[82:97]
	s_waitcnt lgkmcnt(15)
	v_mfma_f32_32x32x16_f16 v[34:49], v[188:191], v[204:207], v[34:49]
	v_mfma_f32_32x32x16_f16 v[50:65], v[174:177], v[204:207], v[50:65]
	s_waitcnt lgkmcnt(14)
	v_mfma_f32_32x32x16_f16 v[2:17], v[188:191], v[208:211], v[2:17]
	v_mfma_f32_32x32x16_f16 v[18:33], v[174:177], v[208:211], v[18:33]
	ds_read_b128 v[188:191], v214 offset:96
	ds_read_b128 v[242:245], v212 offset:96
	ds_read_b128 v[174:177], v214 offset:4704
	ds_read_b128 v[246:249], v212 offset:4704
	ds_read_b128 v[204:207], v212 offset:9312
	ds_read_b128 v[208:211], v212 offset:13920
	s_waitcnt lgkmcnt(14)
	v_mfma_f32_32x32x16_f16 v[98:113], v[234:237], v[218:221], v[98:113]
	s_waitcnt lgkmcnt(13)
	v_mfma_f32_32x32x16_f16 v[114:129], v[238:241], v[218:221], v[114:129]
	s_waitcnt lgkmcnt(12)
	v_mfma_f32_32x32x16_f16 v[66:81], v[234:237], v[222:225], v[66:81]
	v_mfma_f32_32x32x16_f16 v[82:97], v[238:241], v[222:225], v[82:97]
	s_waitcnt lgkmcnt(11)
	v_mfma_f32_32x32x16_f16 v[34:49], v[234:237], v[226:229], v[34:49]
	v_mfma_f32_32x32x16_f16 v[50:65], v[238:241], v[226:229], v[50:65]
	s_waitcnt lgkmcnt(10)
	v_mfma_f32_32x32x16_f16 v[2:17], v[234:237], v[230:233], v[2:17]
	v_mfma_f32_32x32x16_f16 v[18:33], v[238:241], v[230:233], v[18:33]
	s_waitcnt lgkmcnt(0)
	s_barrier
; DI f16v mfma32(h8v a, h8v b, f16v c) { return __builtin_amdgcn_mfma_f32_32x32x16_f16(a, b, c, 0, 0, 0); }
; template <bool GATHER>
; DI void gemm256_main(const h16* __restrict__ A, int lda, const int* __restrict__ idx, int m0,
;                      const h16* __restrict__ B, int ldb, int n0, int K, h16* lds, f16v (&acc)[4][2]) {
;     ...
;   for (int kt = 0; kt < nk; ++kt) {
;     const h16* As = lds + (kt & 1) * (512 * LDH);
;     const h16* Bs = As + 256 * LDH;
;     h16* Wn = lds + ((kt & 1) ^ 1) * (512 * LDH);
;     if (kt + 1 < nk) {
; #pragma unroll
;       for (int i = 0; i < 4; ++i) { *(u4v*)&Wn[lr * LDH + lc + 8 * i] = ra[i]; *(u4v*)&Wn[(256 + lr) * LDH + lc + 8 * i] = rb[i]; }
;     }
;     if (kt + 2 < nk) {
; #pragma unroll
;       for (int i = 0; i < 4; ++i) { ra[i] = *(const u4v*)(AP_ + 8 * i); rb[i] = *(const u4v*)(BP_ + 8 * i); }
;       ao += 64; bo += 64;
;     }
; #pragma unroll
;     for (int ks = 0; ks < 4; ++ks) {
;       h8v af[4], bf[2];
; #pragma unroll
;       for (int i = 0; i < 4; ++i) af[i] = *(const h8v*)&As[(wm * 128 + i * 32 + (lane & 31)) * LDH + ks * 16 + 8 * (lane >> 5)];
; #pragma unroll
;       for (int j = 0; j < 2; ++j) bf[j] = *(const h8v*)&Bs[(wn * 64 + j * 32 + (lane & 31)) * LDH + ks * 16 + 8 * (lane >> 5)];
; #pragma unroll
;       for (int i = 0; i < 4; ++i)
; #pragma unroll
;         for (int j = 0; j < 2; ++j) acc[i][j] = mfma32(bf[j], af[i], acc[i][j]);
;     }
;     __syncthreads();
	ds_read_b128 v[234:237], v213
	ds_read_b128 v[218:221], v217
	ds_read_b128 v[238:241], v213 offset:4608
	ds_read_b128 v[222:225], v217 offset:4608
	ds_read_b128 v[226:229], v217 offset:9216
	ds_read_b128 v[230:233], v217 offset:13824
	v_mfma_f32_32x32x16_f16 v[98:113], v[188:191], v[242:245], v[98:113]
	v_mfma_f32_32x32x16_f16 v[114:129], v[174:177], v[242:245], v[114:129]
	v_mfma_f32_32x32x16_f16 v[66:81], v[188:191], v[246:249], v[66:81]
	v_mfma_f32_32x32x16_f16 v[82:97], v[174:177], v[246:249], v[82:97]
	v_mfma_f32_32x32x16_f16 v[34:49], v[188:191], v[204:207], v[34:49]
	v_mfma_f32_32x32x16_f16 v[50:65], v[174:177], v[204:207], v[50:65]
	v_mfma_f32_32x32x16_f16 v[2:17], v[188:191], v[208:211], v[2:17]
	v_mfma_f32_32x32x16_f16 v[18:33], v[174:177], v[208:211], v[18:33]
	ds_read_b128 v[188:191], v213 offset:32
	ds_read_b128 v[242:245], v217 offset:32
	ds_read_b128 v[174:177], v213 offset:4640
	ds_read_b128 v[246:249], v217 offset:4640
	ds_read_b128 v[204:207], v217 offset:9248
	ds_read_b128 v[208:211], v217 offset:13856
	s_waitcnt vmcnt(4)
	ds_write_b128 v133, v[134:137]
	ds_write_b128 v133, v[138:141] offset:16
	ds_write_b128 v133, v[142:145] offset:32
	ds_write_b128 v133, v[146:149] offset:48
	global_load_dwordx4 v[134:137], v[130:131], off offset:1024
	global_load_dwordx4 v[138:141], v[130:131], off offset:1040
	global_load_dwordx4 v[142:145], v[130:131], off offset:1056
	global_load_dwordx4 v[146:149], v[130:131], off offset:1072
	s_waitcnt lgkmcnt(14)
	v_mfma_f32_32x32x16_f16 v[98:113], v[234:237], v[218:221], v[98:113]
	s_waitcnt lgkmcnt(13)
	v_mfma_f32_32x32x16_f16 v[114:129], v[238:241], v[218:221], v[114:129]
	s_waitcnt lgkmcnt(12)
	v_mfma_f32_32x32x16_f16 v[66:81], v[234:237], v[222:225], v[66:81]
	v_mfma_f32_32x32x16_f16 v[82:97], v[238:241], v[222:225], v[82:97]
	s_waitcnt lgkmcnt(11)
	v_mfma_f32_32x32x16_f16 v[34:49], v[234:237], v[226:229], v[34:49]
	v_mfma_f32_32x32x16_f16 v[50:65], v[238:241], v[226:229], v[50:65]
	s_waitcnt lgkmcnt(10)
	v_mfma_f32_32x32x16_f16 v[2:17], v[234:237], v[230:233], v[2:17]
	v_mfma_f32_32x32x16_f16 v[18:33], v[238:241], v[230:233], v[18:33]
	ds_read_b128 v[234:237], v213 offset:64
	ds_read_b128 v[218:221], v217 offset:64
	ds_read_b128 v[238:241], v213 offset:4672
	ds_read_b128 v[222:225], v217 offset:4672
	ds_read_b128 v[226:229], v217 offset:9280
	ds_read_b128 v[230:233], v217 offset:13888
	s_waitcnt vmcnt(4)
	ds_write_b128 v133, v[150:153] offset:36864
	ds_write_b128 v133, v[154:157] offset:36880
	ds_write_b128 v133, v[158:161] offset:36896
	ds_write_b128 v133, v[162:165] offset:36912
	global_load_dwordx4 v[150:153], v[200:201], off offset:1024
	global_load_dwordx4 v[154:157], v[200:201], off offset:1040
	global_load_dwordx4 v[158:161], v[200:201], off offset:1056
	global_load_dwordx4 v[162:165], v[200:201], off offset:1072
	s_waitcnt lgkmcnt(15)
	v_mfma_f32_32x32x16_f16 v[98:113], v[188:191], v[242:245], v[98:113]
	s_waitcnt lgkmcnt(15)
	v_mfma_f32_32x32x16_f16 v[114:129], v[174:177], v[242:245], v[114:129]
	s_waitcnt lgkmcnt(15)
	v_mfma_f32_32x32x16_f16 v[66:81], v[188:191], v[246:249], v[66:81]
	v_mfma_f32_32x32x16_f16 v[82:97], v[174:177], v[246:249], v[82:97]
	s_waitcnt lgkmcnt(15)
	v_mfma_f32_32x32x16_f16 v[34:49], v[188:191], v[204:207], v[34:49]
	v_mfma_f32_32x32x16_f16 v[50:65], v[174:177], v[204:207], v[50:65]
	s_waitcnt lgkmcnt(14)
	v_mfma_f32_32x32x16_f16 v[2:17], v[188:191], v[208:211], v[2:17]
	v_mfma_f32_32x32x16_f16 v[18:33], v[174:177], v[208:211], v[18:33]
	ds_read_b128 v[188:191], v213 offset:96
	ds_read_b128 v[242:245], v217 offset:96
	ds_read_b128 v[174:177], v213 offset:4704
	ds_read_b128 v[246:249], v217 offset:4704
	ds_read_b128 v[204:207], v217 offset:9312
	ds_read_b128 v[208:211], v217 offset:13920
	s_waitcnt lgkmcnt(14)
	v_mfma_f32_32x32x16_f16 v[98:113], v[234:237], v[218:221], v[98:113]
	s_waitcnt lgkmcnt(13)
	v_mfma_f32_32x32x16_f16 v[114:129], v[238:241], v[218:221], v[114:129]
	s_waitcnt lgkmcnt(12)
	v_mfma_f32_32x32x16_f16 v[66:81], v[234:237], v[222:225], v[66:81]
	v_mfma_f32_32x32x16_f16 v[82:97], v[238:241], v[222:225], v[82:97]
	s_waitcnt lgkmcnt(11)
	v_mfma_f32_32x32x16_f16 v[34:49], v[234:237], v[226:229], v[34:49]
	v_mfma_f32_32x32x16_f16 v[50:65], v[238:241], v[226:229], v[50:65]
	s_waitcnt lgkmcnt(10)
	v_mfma_f32_32x32x16_f16 v[2:17], v[234:237], v[230:233], v[2:17]
	v_mfma_f32_32x32x16_f16 v[18:33], v[238:241], v[230:233], v[18:33]
	s_waitcnt lgkmcnt(0)
	s_barrier
; DI f16v mfma32(h8v a, h8v b, f16v c) { return __builtin_amdgcn_mfma_f32_32x32x16_f16(a, b, c, 0, 0, 0); }
; template <bool GATHER>
; DI void gemm256_main(const h16* __restrict__ A, int lda, const int* __restrict__ idx, int m0,
;                      const h16* __restrict__ B, int ldb, int n0, int K, h16* lds, f16v (&acc)[4][2]) {
;     ...
;   for (int kt = 0; kt < nk; ++kt) {
;     const h16* As = lds + (kt & 1) * (512 * LDH);
;     const h16* Bs = As + 256 * LDH;
;     h16* Wn = lds + ((kt & 1) ^ 1) * (512 * LDH);
;     if (kt + 1 < nk) {
; #pragma unroll
;       for (int i = 0; i < 4; ++i) { *(u4v*)&Wn[lr * LDH + lc + 8 * i] = ra[i]; *(u4v*)&Wn[(256 + lr) * LDH + lc + 8 * i] = rb[i]; }
;     }
;     if (kt + 2 < nk) {
; #pragma unroll
;       for (int i = 0; i < 4; ++i) { ra[i] = *(const u4v*)(AP_ + 8 * i); rb[i] = *(const u4v*)(BP_ + 8 * i); }
;       ao += 64; bo += 64;
;     }
; #pragma unroll
;     for (int ks = 0; ks < 4; ++ks) {
;       h8v af[4], bf[2];
; #pragma unroll
;       for (int i = 0; i < 4; ++i) af[i] = *(const h8v*)&As[(wm * 128 + i * 32 + (lane & 31)) * LDH + ks * 16 + 8 * (lane >> 5)];
; #pragma unroll
;       for (int j = 0; j < 2; ++j) bf[j] = *(const h8v*)&Bs[(wn * 64 + j * 32 + (lane & 31)) * LDH + ks * 16 + 8 * (lane >> 5)];
; #pragma unroll
;       for (int i = 0; i < 4; ++i)
; #pragma unroll
;         for (int j = 0; j < 2; ++j) acc[i][j] = mfma32(bf[j], af[i], acc[i][j]);
;     }
;     __syncthreads();
	ds_read_b128 v[234:237], v214
	ds_read_b128 v[218:221], v212
	ds_read_b128 v[238:241], v214 offset:4608
	ds_read_b128 v[222:225], v212 offset:4608
	ds_read_b128 v[226:229], v212 offset:9216
	ds_read_b128 v[230:233], v212 offset:13824
	v_mfma_f32_32x32x16_f16 v[98:113], v[188:191], v[242:245], v[98:113]
	v_mfma_f32_32x32x16_f16 v[114:129], v[174:177], v[242:245], v[114:129]
	v_mfma_f32_32x32x16_f16 v[66:81], v[188:191], v[246:249], v[66:81]
	v_mfma_f32_32x32x16_f16 v[82:97], v[174:177], v[246:249], v[82:97]
	v_mfma_f32_32x32x16_f16 v[34:49], v[188:191], v[204:207], v[34:49]
	v_mfma_f32_32x32x16_f16 v[50:65], v[174:177], v[204:207], v[50:65]
	v_mfma_f32_32x32x16_f16 v[2:17], v[188:191], v[208:211], v[2:17]
	v_mfma_f32_32x32x16_f16 v[18:33], v[174:177], v[208:211], v[18:33]
	ds_read_b128 v[188:191], v214 offset:32
	ds_read_b128 v[242:245], v212 offset:32
	ds_read_b128 v[174:177], v214 offset:4640
	ds_read_b128 v[246:249], v212 offset:4640
	ds_read_b128 v[204:207], v212 offset:9248
	ds_read_b128 v[208:211], v212 offset:13856
	s_waitcnt vmcnt(4)
	ds_write_b128 v132, v[134:137]
	ds_write_b128 v132, v[138:141] offset:16
	ds_write_b128 v132, v[142:145] offset:32
	ds_write_b128 v132, v[146:149] offset:48
	global_load_dwordx4 v[134:137], v[130:131], off offset:1152
	global_load_dwordx4 v[138:141], v[130:131], off offset:1168
	global_load_dwordx4 v[142:145], v[130:131], off offset:1184
	global_load_dwordx4 v[146:149], v[130:131], off offset:1200
	s_waitcnt lgkmcnt(14)
	v_mfma_f32_32x32x16_f16 v[98:113], v[234:237], v[218:221], v[98:113]
	s_waitcnt lgkmcnt(13)
	v_mfma_f32_32x32x16_f16 v[114:129], v[238:241], v[218:221], v[114:129]
	s_waitcnt lgkmcnt(12)
	v_mfma_f32_32x32x16_f16 v[66:81], v[234:237], v[222:225], v[66:81]
	v_mfma_f32_32x32x16_f16 v[82:97], v[238:241], v[222:225], v[82:97]
	s_waitcnt lgkmcnt(11)
	v_mfma_f32_32x32x16_f16 v[34:49], v[234:237], v[226:229], v[34:49]
	v_mfma_f32_32x32x16_f16 v[50:65], v[238:241], v[226:229], v[50:65]
	s_waitcnt lgkmcnt(10)
	v_mfma_f32_32x32x16_f16 v[2:17], v[234:237], v[230:233], v[2:17]
	v_mfma_f32_32x32x16_f16 v[18:33], v[238:241], v[230:233], v[18:33]
	ds_read_b128 v[234:237], v214 offset:64
	ds_read_b128 v[218:221], v212 offset:64
	ds_read_b128 v[238:241], v214 offset:4672
	ds_read_b128 v[222:225], v212 offset:4672
	ds_read_b128 v[226:229], v212 offset:9280
	ds_read_b128 v[230:233], v212 offset:13888
	s_waitcnt vmcnt(4)
	ds_write_b128 v132, v[150:153] offset:36864
	ds_write_b128 v132, v[154:157] offset:36880
	ds_write_b128 v132, v[158:161] offset:36896
	ds_write_b128 v132, v[162:165] offset:36912
	global_load_dwordx4 v[150:153], v[200:201], off offset:1152
	global_load_dwordx4 v[154:157], v[200:201], off offset:1168
	global_load_dwordx4 v[158:161], v[200:201], off offset:1184
	global_load_dwordx4 v[162:165], v[200:201], off offset:1200
	s_waitcnt lgkmcnt(15)
	v_mfma_f32_32x32x16_f16 v[98:113], v[188:191], v[242:245], v[98:113]
	s_waitcnt lgkmcnt(15)
	v_mfma_f32_32x32x16_f16 v[114:129], v[174:177], v[242:245], v[114:129]
	s_waitcnt lgkmcnt(15)
	v_mfma_f32_32x32x16_f16 v[66:81], v[188:191], v[246:249], v[66:81]
	v_mfma_f32_32x32x16_f16 v[82:97], v[174:177], v[246:249], v[82:97]
	s_waitcnt lgkmcnt(15)
	v_mfma_f32_32x32x16_f16 v[34:49], v[188:191], v[204:207], v[34:49]
	v_mfma_f32_32x32x16_f16 v[50:65], v[174:177], v[204:207], v[50:65]
	s_waitcnt lgkmcnt(14)
	v_mfma_f32_32x32x16_f16 v[2:17], v[188:191], v[208:211], v[2:17]
	v_mfma_f32_32x32x16_f16 v[18:33], v[174:177], v[208:211], v[18:33]
	ds_read_b128 v[188:191], v214 offset:96
	ds_read_b128 v[242:245], v212 offset:96
	ds_read_b128 v[174:177], v214 offset:4704
	ds_read_b128 v[246:249], v212 offset:4704
	ds_read_b128 v[204:207], v212 offset:9312
	ds_read_b128 v[208:211], v212 offset:13920
	s_waitcnt lgkmcnt(14)
	v_mfma_f32_32x32x16_f16 v[98:113], v[234:237], v[218:221], v[98:113]
	s_waitcnt lgkmcnt(13)
	v_mfma_f32_32x32x16_f16 v[114:129], v[238:241], v[218:221], v[114:129]
	s_waitcnt lgkmcnt(12)
	v_mfma_f32_32x32x16_f16 v[66:81], v[234:237], v[222:225], v[66:81]
	v_mfma_f32_32x32x16_f16 v[82:97], v[238:241], v[222:225], v[82:97]
	s_waitcnt lgkmcnt(11)
	v_mfma_f32_32x32x16_f16 v[34:49], v[234:237], v[226:229], v[34:49]
	v_mfma_f32_32x32x16_f16 v[50:65], v[238:241], v[226:229], v[50:65]
	s_waitcnt lgkmcnt(10)
	v_mfma_f32_32x32x16_f16 v[2:17], v[234:237], v[230:233], v[2:17]
	v_mfma_f32_32x32x16_f16 v[18:33], v[238:241], v[230:233], v[18:33]
	s_waitcnt lgkmcnt(0)
	s_barrier
; DI f16v mfma32(h8v a, h8v b, f16v c) { return __builtin_amdgcn_mfma_f32_32x32x16_f16(a, b, c, 0, 0, 0); }
; template <bool GATHER>
; DI void gemm256_main(const h16* __restrict__ A, int lda, const int* __restrict__ idx, int m0,
;                      const h16* __restrict__ B, int ldb, int n0, int K, h16* lds, f16v (&acc)[4][2]) {
;     ...
;   for (int kt = 0; kt < nk; ++kt) {
;     const h16* As = lds + (kt & 1) * (512 * LDH);
;     const h16* Bs = As + 256 * LDH;
;     h16* Wn = lds + ((kt & 1) ^ 1) * (512 * LDH);
;     if (kt + 1 < nk) {
; #pragma unroll
;       for (int i = 0; i < 4; ++i) { *(u4v*)&Wn[lr * LDH + lc + 8 * i] = ra[i]; *(u4v*)&Wn[(256 + lr) * LDH + lc + 8 * i] = rb[i]; }
;     }
;     if (kt + 2 < nk) {
; #pragma unroll
;       for (int i = 0; i < 4; ++i) { ra[i] = *(const u4v*)(AP_ + 8 * i); rb[i] = *(const u4v*)(BP_ + 8 * i); }
;       ao += 64; bo += 64;
;     }
; #pragma unroll
;     for (int ks = 0; ks < 4; ++ks) {
;       h8v af[4], bf[2];
; #pragma unroll
;       for (int i = 0; i < 4; ++i) af[i] = *(const h8v*)&As[(wm * 128 + i * 32 + (lane & 31)) * LDH + ks * 16 + 8 * (lane >> 5)];
; #pragma unroll
;       for (int j = 0; j < 2; ++j) bf[j] = *(const h8v*)&Bs[(wn * 64 + j * 32 + (lane & 31)) * LDH + ks * 16 + 8 * (lane >> 5)];
; #pragma unroll
;       for (int i = 0; i < 4; ++i)
; #pragma unroll
;         for (int j = 0; j < 2; ++j) acc[i][j] = mfma32(bf[j], af[i], acc[i][j]);
;     }
;     __syncthreads();
	ds_read_b128 v[234:237], v213
	ds_read_b128 v[218:221], v217
	ds_read_b128 v[238:241], v213 offset:4608
	ds_read_b128 v[222:225], v217 offset:4608
	ds_read_b128 v[226:229], v217 offset:9216
	ds_read_b128 v[230:233], v217 offset:13824
	v_mfma_f32_32x32x16_f16 v[98:113], v[188:191], v[242:245], v[98:113]
	v_mfma_f32_32x32x16_f16 v[114:129], v[174:177], v[242:245], v[114:129]
	v_mfma_f32_32x32x16_f16 v[66:81], v[188:191], v[246:249], v[66:81]
	v_mfma_f32_32x32x16_f16 v[82:97], v[174:177], v[246:249], v[82:97]
	v_mfma_f32_32x32x16_f16 v[34:49], v[188:191], v[204:207], v[34:49]
	v_mfma_f32_32x32x16_f16 v[50:65], v[174:177], v[204:207], v[50:65]
	v_mfma_f32_32x32x16_f16 v[2:17], v[188:191], v[208:211], v[2:17]
	v_mfma_f32_32x32x16_f16 v[18:33], v[174:177], v[208:211], v[18:33]
	ds_read_b128 v[188:191], v213 offset:32
	ds_read_b128 v[242:245], v217 offset:32
	ds_read_b128 v[174:177], v213 offset:4640
	ds_read_b128 v[246:249], v217 offset:4640
	ds_read_b128 v[204:207], v217 offset:9248
	ds_read_b128 v[208:211], v217 offset:13856
	s_waitcnt vmcnt(4)
	ds_write_b128 v133, v[134:137]
	ds_write_b128 v133, v[138:141] offset:16
	ds_write_b128 v133, v[142:145] offset:32
	ds_write_b128 v133, v[146:149] offset:48
	global_load_dwordx4 v[134:137], v[130:131], off offset:1280
	global_load_dwordx4 v[138:141], v[130:131], off offset:1296
	global_load_dwordx4 v[142:145], v[130:131], off offset:1312
	global_load_dwordx4 v[146:149], v[130:131], off offset:1328
	s_waitcnt lgkmcnt(14)
	v_mfma_f32_32x32x16_f16 v[98:113], v[234:237], v[218:221], v[98:113]
	s_waitcnt lgkmcnt(13)
	v_mfma_f32_32x32x16_f16 v[114:129], v[238:241], v[218:221], v[114:129]
	s_waitcnt lgkmcnt(12)
	v_mfma_f32_32x32x16_f16 v[66:81], v[234:237], v[222:225], v[66:81]
	v_mfma_f32_32x32x16_f16 v[82:97], v[238:241], v[222:225], v[82:97]
	s_waitcnt lgkmcnt(11)
	v_mfma_f32_32x32x16_f16 v[34:49], v[234:237], v[226:229], v[34:49]
	v_mfma_f32_32x32x16_f16 v[50:65], v[238:241], v[226:229], v[50:65]
	s_waitcnt lgkmcnt(10)
	v_mfma_f32_32x32x16_f16 v[2:17], v[234:237], v[230:233], v[2:17]
	v_mfma_f32_32x32x16_f16 v[18:33], v[238:241], v[230:233], v[18:33]
	ds_read_b128 v[234:237], v213 offset:64
	ds_read_b128 v[218:221], v217 offset:64
	ds_read_b128 v[238:241], v213 offset:4672
	ds_read_b128 v[222:225], v217 offset:4672
	ds_read_b128 v[226:229], v217 offset:9280
	ds_read_b128 v[230:233], v217 offset:13888
	s_waitcnt vmcnt(4)
	ds_write_b128 v133, v[150:153] offset:36864
	ds_write_b128 v133, v[154:157] offset:36880
	ds_write_b128 v133, v[158:161] offset:36896
	ds_write_b128 v133, v[162:165] offset:36912
	global_load_dwordx4 v[150:153], v[200:201], off offset:1280
	global_load_dwordx4 v[154:157], v[200:201], off offset:1296
	global_load_dwordx4 v[158:161], v[200:201], off offset:1312
	global_load_dwordx4 v[162:165], v[200:201], off offset:1328
	s_waitcnt lgkmcnt(15)
	v_mfma_f32_32x32x16_f16 v[98:113], v[188:191], v[242:245], v[98:113]
	s_waitcnt lgkmcnt(15)
	v_mfma_f32_32x32x16_f16 v[114:129], v[174:177], v[242:245], v[114:129]
	s_waitcnt lgkmcnt(15)
	v_mfma_f32_32x32x16_f16 v[66:81], v[188:191], v[246:249], v[66:81]
	v_mfma_f32_32x32x16_f16 v[82:97], v[174:177], v[246:249], v[82:97]
	s_waitcnt lgkmcnt(15)
	v_mfma_f32_32x32x16_f16 v[34:49], v[188:191], v[204:207], v[34:49]
	v_mfma_f32_32x32x16_f16 v[50:65], v[174:177], v[204:207], v[50:65]
	s_waitcnt lgkmcnt(14)
	v_mfma_f32_32x32x16_f16 v[2:17], v[188:191], v[208:211], v[2:17]
	v_mfma_f32_32x32x16_f16 v[18:33], v[174:177], v[208:211], v[18:33]
	ds_read_b128 v[188:191], v213 offset:96
	ds_read_b128 v[242:245], v217 offset:96
	ds_read_b128 v[174:177], v213 offset:4704
	ds_read_b128 v[246:249], v217 offset:4704
	ds_read_b128 v[204:207], v217 offset:9312
	ds_read_b128 v[208:211], v217 offset:13920
	s_waitcnt lgkmcnt(14)
	v_mfma_f32_32x32x16_f16 v[98:113], v[234:237], v[218:221], v[98:113]
	s_waitcnt lgkmcnt(13)
	v_mfma_f32_32x32x16_f16 v[114:129], v[238:241], v[218:221], v[114:129]
	s_waitcnt lgkmcnt(12)
	v_mfma_f32_32x32x16_f16 v[66:81], v[234:237], v[222:225], v[66:81]
	v_mfma_f32_32x32x16_f16 v[82:97], v[238:241], v[222:225], v[82:97]
	s_waitcnt lgkmcnt(11)
	v_mfma_f32_32x32x16_f16 v[34:49], v[234:237], v[226:229], v[34:49]
	v_mfma_f32_32x32x16_f16 v[50:65], v[238:241], v[226:229], v[50:65]
	s_waitcnt lgkmcnt(10)
	v_mfma_f32_32x32x16_f16 v[2:17], v[234:237], v[230:233], v[2:17]
	v_mfma_f32_32x32x16_f16 v[18:33], v[238:241], v[230:233], v[18:33]
	s_waitcnt lgkmcnt(0)
	s_barrier
; DI f16v mfma32(h8v a, h8v b, f16v c) { return __builtin_amdgcn_mfma_f32_32x32x16_f16(a, b, c, 0, 0, 0); }
; template <bool GATHER>
; DI void gemm256_main(const h16* __restrict__ A, int lda, const int* __restrict__ idx, int m0,
;                      const h16* __restrict__ B, int ldb, int n0, int K, h16* lds, f16v (&acc)[4][2]) {
;     ...
;   for (int kt = 0; kt < nk; ++kt) {
;     const h16* As = lds + (kt & 1) * (512 * LDH);
;     const h16* Bs = As + 256 * LDH;
;     h16* Wn = lds + ((kt & 1) ^ 1) * (512 * LDH);
;     if (kt + 1 < nk) {
; #pragma unroll
;       for (int i = 0; i < 4; ++i) { *(u4v*)&Wn[lr * LDH + lc + 8 * i] = ra[i]; *(u4v*)&Wn[(256 + lr) * LDH + lc + 8 * i] = rb[i]; }
;     }
;     if (kt + 2 < nk) {
; #pragma unroll
;       for (int i = 0; i < 4; ++i) { ra[i] = *(const u4v*)(AP_ + 8 * i); rb[i] = *(const u4v*)(BP_ + 8 * i); }
;       ao += 64; bo += 64;
;     }
; #pragma unroll
;     for (int ks = 0; ks < 4; ++ks) {
;       h8v af[4], bf[2];
; #pragma unroll
;       for (int i = 0; i < 4; ++i) af[i] = *(const h8v*)&As[(wm * 128 + i * 32 + (lane & 31)) * LDH + ks * 16 + 8 * (lane >> 5)];
; #pragma unroll
;       for (int j = 0; j < 2; ++j) bf[j] = *(const h8v*)&Bs[(wn * 64 + j * 32 + (lane & 31)) * LDH + ks * 16 + 8 * (lane >> 5)];
; #pragma unroll
;       for (int i = 0; i < 4; ++i)
; #pragma unroll
;         for (int j = 0; j < 2; ++j) acc[i][j] = mfma32(bf[j], af[i], acc[i][j]);
;     }
;     __syncthreads();
	ds_read_b128 v[234:237], v214
	ds_read_b128 v[218:221], v212
	ds_read_b128 v[238:241], v214 offset:4608
	ds_read_b128 v[222:225], v212 offset:4608
	ds_read_b128 v[226:229], v212 offset:9216
	ds_read_b128 v[230:233], v212 offset:13824
	v_mfma_f32_32x32x16_f16 v[98:113], v[188:191], v[242:245], v[98:113]
	v_mfma_f32_32x32x16_f16 v[114:129], v[174:177], v[242:245], v[114:129]
	v_mfma_f32_32x32x16_f16 v[66:81], v[188:191], v[246:249], v[66:81]
	v_mfma_f32_32x32x16_f16 v[82:97], v[174:177], v[246:249], v[82:97]
	v_mfma_f32_32x32x16_f16 v[34:49], v[188:191], v[204:207], v[34:49]
	v_mfma_f32_32x32x16_f16 v[50:65], v[174:177], v[204:207], v[50:65]
	v_mfma_f32_32x32x16_f16 v[2:17], v[188:191], v[208:211], v[2:17]
	v_mfma_f32_32x32x16_f16 v[18:33], v[174:177], v[208:211], v[18:33]
	ds_read_b128 v[188:191], v214 offset:32
	ds_read_b128 v[242:245], v212 offset:32
	ds_read_b128 v[174:177], v214 offset:4640
	ds_read_b128 v[246:249], v212 offset:4640
	ds_read_b128 v[204:207], v212 offset:9248
	ds_read_b128 v[208:211], v212 offset:13856
	s_waitcnt vmcnt(4)
	ds_write_b128 v132, v[134:137]
	ds_write_b128 v132, v[138:141] offset:16
	ds_write_b128 v132, v[142:145] offset:32
	ds_write_b128 v132, v[146:149] offset:48
	global_load_dwordx4 v[134:137], v[130:131], off offset:1408
	global_load_dwordx4 v[138:141], v[130:131], off offset:1424
	global_load_dwordx4 v[142:145], v[130:131], off offset:1440
	global_load_dwordx4 v[146:149], v[130:131], off offset:1456
	s_waitcnt lgkmcnt(14)
	v_mfma_f32_32x32x16_f16 v[98:113], v[234:237], v[218:221], v[98:113]
	s_waitcnt lgkmcnt(13)
	v_mfma_f32_32x32x16_f16 v[114:129], v[238:241], v[218:221], v[114:129]
	s_waitcnt lgkmcnt(12)
	v_mfma_f32_32x32x16_f16 v[66:81], v[234:237], v[222:225], v[66:81]
	v_mfma_f32_32x32x16_f16 v[82:97], v[238:241], v[222:225], v[82:97]
	s_waitcnt lgkmcnt(11)
	v_mfma_f32_32x32x16_f16 v[34:49], v[234:237], v[226:229], v[34:49]
	v_mfma_f32_32x32x16_f16 v[50:65], v[238:241], v[226:229], v[50:65]
	s_waitcnt lgkmcnt(10)
	v_mfma_f32_32x32x16_f16 v[2:17], v[234:237], v[230:233], v[2:17]
	v_mfma_f32_32x32x16_f16 v[18:33], v[238:241], v[230:233], v[18:33]
	ds_read_b128 v[234:237], v214 offset:64
	ds_read_b128 v[218:221], v212 offset:64
	ds_read_b128 v[238:241], v214 offset:4672
	ds_read_b128 v[222:225], v212 offset:4672
	ds_read_b128 v[226:229], v212 offset:9280
	ds_read_b128 v[230:233], v212 offset:13888
	s_waitcnt vmcnt(4)
	ds_write_b128 v132, v[150:153] offset:36864
	ds_write_b128 v132, v[154:157] offset:36880
	ds_write_b128 v132, v[158:161] offset:36896
	ds_write_b128 v132, v[162:165] offset:36912
	global_load_dwordx4 v[150:153], v[200:201], off offset:1408
	global_load_dwordx4 v[154:157], v[200:201], off offset:1424
	global_load_dwordx4 v[158:161], v[200:201], off offset:1440
	global_load_dwordx4 v[162:165], v[200:201], off offset:1456
	s_waitcnt lgkmcnt(15)
	v_mfma_f32_32x32x16_f16 v[98:113], v[188:191], v[242:245], v[98:113]
	s_waitcnt lgkmcnt(15)
	v_mfma_f32_32x32x16_f16 v[114:129], v[174:177], v[242:245], v[114:129]
	s_waitcnt lgkmcnt(15)
	v_mfma_f32_32x32x16_f16 v[66:81], v[188:191], v[246:249], v[66:81]
	v_mfma_f32_32x32x16_f16 v[82:97], v[174:177], v[246:249], v[82:97]
	s_waitcnt lgkmcnt(15)
	v_mfma_f32_32x32x16_f16 v[34:49], v[188:191], v[204:207], v[34:49]
	v_mfma_f32_32x32x16_f16 v[50:65], v[174:177], v[204:207], v[50:65]
	s_waitcnt lgkmcnt(14)
	v_mfma_f32_32x32x16_f16 v[2:17], v[188:191], v[208:211], v[2:17]
	v_mfma_f32_32x32x16_f16 v[18:33], v[174:177], v[208:211], v[18:33]
	ds_read_b128 v[188:191], v214 offset:96
	ds_read_b128 v[242:245], v212 offset:96
	ds_read_b128 v[174:177], v214 offset:4704
	ds_read_b128 v[246:249], v212 offset:4704
	ds_read_b128 v[204:207], v212 offset:9312
	ds_read_b128 v[208:211], v212 offset:13920
	s_waitcnt lgkmcnt(14)
	v_mfma_f32_32x32x16_f16 v[98:113], v[234:237], v[218:221], v[98:113]
	s_waitcnt lgkmcnt(13)
	v_mfma_f32_32x32x16_f16 v[114:129], v[238:241], v[218:221], v[114:129]
	s_waitcnt lgkmcnt(12)
	v_mfma_f32_32x32x16_f16 v[66:81], v[234:237], v[222:225], v[66:81]
	v_mfma_f32_32x32x16_f16 v[82:97], v[238:241], v[222:225], v[82:97]
	s_waitcnt lgkmcnt(11)
	v_mfma_f32_32x32x16_f16 v[34:49], v[234:237], v[226:229], v[34:49]
	v_mfma_f32_32x32x16_f16 v[50:65], v[238:241], v[226:229], v[50:65]
	s_waitcnt lgkmcnt(10)
	v_mfma_f32_32x32x16_f16 v[2:17], v[234:237], v[230:233], v[2:17]
	v_mfma_f32_32x32x16_f16 v[18:33], v[238:241], v[230:233], v[18:33]
	s_waitcnt lgkmcnt(0)
	s_barrier
; DI f16v mfma32(h8v a, h8v b, f16v c) { return __builtin_amdgcn_mfma_f32_32x32x16_f16(a, b, c, 0, 0, 0); }
; template <bool GATHER>
; DI void gemm256_main(const h16* __restrict__ A, int lda, const int* __restrict__ idx, int m0,
;                      const h16* __restrict__ B, int ldb, int n0, int K, h16* lds, f16v (&acc)[4][2]) {
;     ...
;   for (int kt = 0; kt < nk; ++kt) {
;     const h16* As = lds + (kt & 1) * (512 * LDH);
;     const h16* Bs = As + 256 * LDH;
;     h16* Wn = lds + ((kt & 1) ^ 1) * (512 * LDH);
;     if (kt + 1 < nk) {
; #pragma unroll
;       for (int i = 0; i < 4; ++i) { *(u4v*)&Wn[lr * LDH + lc + 8 * i] = ra[i]; *(u4v*)&Wn[(256 + lr) * LDH + lc + 8 * i] = rb[i]; }
;     }
;     if (kt + 2 < nk) {
; #pragma unroll
;       for (int i = 0; i < 4; ++i) { ra[i] = *(const u4v*)(AP_ + 8 * i); rb[i] = *(const u4v*)(BP_ + 8 * i); }
;       ao += 64; bo += 64;
;     }
; #pragma unroll
;     for (int ks = 0; ks < 4; ++ks) {
;       h8v af[4], bf[2];
; #pragma unroll
;       for (int i = 0; i < 4; ++i) af[i] = *(const h8v*)&As[(wm * 128 + i * 32 + (lane & 31)) * LDH + ks * 16 + 8 * (lane >> 5)];
; #pragma unroll
;       for (int j = 0; j < 2; ++j) bf[j] = *(const h8v*)&Bs[(wn * 64 + j * 32 + (lane & 31)) * LDH + ks * 16 + 8 * (lane >> 5)];
; #pragma unroll
;       for (int i = 0; i < 4; ++i)
; #pragma unroll
;         for (int j = 0; j < 2; ++j) acc[i][j] = mfma32(bf[j], af[i], acc[i][j]);
;     }
;     __syncthreads();
	ds_read_b128 v[234:237], v213
	ds_read_b128 v[218:221], v217
	ds_read_b128 v[238:241], v213 offset:4608
	ds_read_b128 v[222:225], v217 offset:4608
	ds_read_b128 v[226:229], v217 offset:9216
	ds_read_b128 v[230:233], v217 offset:13824
	v_mfma_f32_32x32x16_f16 v[98:113], v[188:191], v[242:245], v[98:113]
	v_mfma_f32_32x32x16_f16 v[114:129], v[174:177], v[242:245], v[114:129]
	v_mfma_f32_32x32x16_f16 v[66:81], v[188:191], v[246:249], v[66:81]
	v_mfma_f32_32x32x16_f16 v[82:97], v[174:177], v[246:249], v[82:97]
	v_mfma_f32_32x32x16_f16 v[34:49], v[188:191], v[204:207], v[34:49]
	v_mfma_f32_32x32x16_f16 v[50:65], v[174:177], v[204:207], v[50:65]
	v_mfma_f32_32x32x16_f16 v[2:17], v[188:191], v[208:211], v[2:17]
	v_mfma_f32_32x32x16_f16 v[18:33], v[174:177], v[208:211], v[18:33]
	ds_read_b128 v[188:191], v213 offset:32
	ds_read_b128 v[242:245], v217 offset:32
	ds_read_b128 v[174:177], v213 offset:4640
	ds_read_b128 v[246:249], v217 offset:4640
	ds_read_b128 v[204:207], v217 offset:9248
	ds_read_b128 v[208:211], v217 offset:13856
	s_waitcnt vmcnt(4)
	ds_write_b128 v133, v[134:137]
	ds_write_b128 v133, v[138:141] offset:16
	ds_write_b128 v133, v[142:145] offset:32
	ds_write_b128 v133, v[146:149] offset:48
	global_load_dwordx4 v[134:137], v[130:131], off offset:1536
	global_load_dwordx4 v[138:141], v[130:131], off offset:1552
	global_load_dwordx4 v[142:145], v[130:131], off offset:1568
	global_load_dwordx4 v[146:149], v[130:131], off offset:1584
	s_waitcnt lgkmcnt(14)
	v_mfma_f32_32x32x16_f16 v[98:113], v[234:237], v[218:221], v[98:113]
	s_waitcnt lgkmcnt(13)
	v_mfma_f32_32x32x16_f16 v[114:129], v[238:241], v[218:221], v[114:129]
	s_waitcnt lgkmcnt(12)
	v_mfma_f32_32x32x16_f16 v[66:81], v[234:237], v[222:225], v[66:81]
	v_mfma_f32_32x32x16_f16 v[82:97], v[238:241], v[222:225], v[82:97]
	s_waitcnt lgkmcnt(11)
	v_mfma_f32_32x32x16_f16 v[34:49], v[234:237], v[226:229], v[34:49]
	v_mfma_f32_32x32x16_f16 v[50:65], v[238:241], v[226:229], v[50:65]
	s_waitcnt lgkmcnt(10)
	v_mfma_f32_32x32x16_f16 v[2:17], v[234:237], v[230:233], v[2:17]
	v_mfma_f32_32x32x16_f16 v[18:33], v[238:241], v[230:233], v[18:33]
	ds_read_b128 v[234:237], v213 offset:64
	ds_read_b128 v[218:221], v217 offset:64
	ds_read_b128 v[238:241], v213 offset:4672
	ds_read_b128 v[222:225], v217 offset:4672
	ds_read_b128 v[226:229], v217 offset:9280
	ds_read_b128 v[230:233], v217 offset:13888
	s_waitcnt vmcnt(4)
	ds_write_b128 v133, v[150:153] offset:36864
	ds_write_b128 v133, v[154:157] offset:36880
	ds_write_b128 v133, v[158:161] offset:36896
	ds_write_b128 v133, v[162:165] offset:36912
	global_load_dwordx4 v[150:153], v[200:201], off offset:1536
	global_load_dwordx4 v[154:157], v[200:201], off offset:1552
	global_load_dwordx4 v[158:161], v[200:201], off offset:1568
	global_load_dwordx4 v[162:165], v[200:201], off offset:1584
	s_waitcnt lgkmcnt(15)
	v_mfma_f32_32x32x16_f16 v[98:113], v[188:191], v[242:245], v[98:113]
	s_waitcnt lgkmcnt(15)
	v_mfma_f32_32x32x16_f16 v[114:129], v[174:177], v[242:245], v[114:129]
	s_waitcnt lgkmcnt(15)
	v_mfma_f32_32x32x16_f16 v[66:81], v[188:191], v[246:249], v[66:81]
	v_mfma_f32_32x32x16_f16 v[82:97], v[174:177], v[246:249], v[82:97]
	s_waitcnt lgkmcnt(15)
	v_mfma_f32_32x32x16_f16 v[34:49], v[188:191], v[204:207], v[34:49]
	v_mfma_f32_32x32x16_f16 v[50:65], v[174:177], v[204:207], v[50:65]
	s_waitcnt lgkmcnt(14)
	v_mfma_f32_32x32x16_f16 v[2:17], v[188:191], v[208:211], v[2:17]
	v_mfma_f32_32x32x16_f16 v[18:33], v[174:177], v[208:211], v[18:33]
	ds_read_b128 v[188:191], v213 offset:96
	ds_read_b128 v[242:245], v217 offset:96
	ds_read_b128 v[174:177], v213 offset:4704
	ds_read_b128 v[246:249], v217 offset:4704
	ds_read_b128 v[204:207], v217 offset:9312
	ds_read_b128 v[208:211], v217 offset:13920
	s_waitcnt lgkmcnt(14)
	v_mfma_f32_32x32x16_f16 v[98:113], v[234:237], v[218:221], v[98:113]
	s_waitcnt lgkmcnt(13)
	v_mfma_f32_32x32x16_f16 v[114:129], v[238:241], v[218:221], v[114:129]
	s_waitcnt lgkmcnt(12)
	v_mfma_f32_32x32x16_f16 v[66:81], v[234:237], v[222:225], v[66:81]
	v_mfma_f32_32x32x16_f16 v[82:97], v[238:241], v[222:225], v[82:97]
	s_waitcnt lgkmcnt(11)
	v_mfma_f32_32x32x16_f16 v[34:49], v[234:237], v[226:229], v[34:49]
	v_mfma_f32_32x32x16_f16 v[50:65], v[238:241], v[226:229], v[50:65]
	s_waitcnt lgkmcnt(10)
	v_mfma_f32_32x32x16_f16 v[2:17], v[234:237], v[230:233], v[2:17]
	v_mfma_f32_32x32x16_f16 v[18:33], v[238:241], v[230:233], v[18:33]
	s_waitcnt lgkmcnt(0)
	s_barrier
; DI f16v mfma32(h8v a, h8v b, f16v c) { return __builtin_amdgcn_mfma_f32_32x32x16_f16(a, b, c, 0, 0, 0); }
; template <bool GATHER>
; DI void gemm256_main(const h16* __restrict__ A, int lda, const int* __restrict__ idx, int m0,
;                      const h16* __restrict__ B, int ldb, int n0, int K, h16* lds, f16v (&acc)[4][2]) {
;     ...
;   for (int kt = 0; kt < nk; ++kt) {
;     const h16* As = lds + (kt & 1) * (512 * LDH);
;     const h16* Bs = As + 256 * LDH;
;     h16* Wn = lds + ((kt & 1) ^ 1) * (512 * LDH);
;     if (kt + 1 < nk) {
; #pragma unroll
;       for (int i = 0; i < 4; ++i) { *(u4v*)&Wn[lr * LDH + lc + 8 * i] = ra[i]; *(u4v*)&Wn[(256 + lr) * LDH + lc + 8 * i] = rb[i]; }
;     }
;     if (kt + 2 < nk) {
; #pragma unroll
;       for (int i = 0; i < 4; ++i) { ra[i] = *(const u4v*)(AP_ + 8 * i); rb[i] = *(const u4v*)(BP_ + 8 * i); }
;       ao += 64; bo += 64;
;     }
; #pragma unroll
;     for (int ks = 0; ks < 4; ++ks) {
;       h8v af[4], bf[2];
; #pragma unroll
;       for (int i = 0; i < 4; ++i) af[i] = *(const h8v*)&As[(wm * 128 + i * 32 + (lane & 31)) * LDH + ks * 16 + 8 * (lane >> 5)];
; #pragma unroll
;       for (int j = 0; j < 2; ++j) bf[j] = *(const h8v*)&Bs[(wn * 64 + j * 32 + (lane & 31)) * LDH + ks * 16 + 8 * (lane >> 5)];
; #pragma unroll
;       for (int i = 0; i < 4; ++i)
; #pragma unroll
;         for (int j = 0; j < 2; ++j) acc[i][j] = mfma32(bf[j], af[i], acc[i][j]);
;     }
;     __syncthreads();
	ds_read_b128 v[234:237], v214
	ds_read_b128 v[218:221], v212
	ds_read_b128 v[238:241], v214 offset:4608
	ds_read_b128 v[222:225], v212 offset:4608
	ds_read_b128 v[226:229], v212 offset:9216
	ds_read_b128 v[230:233], v212 offset:13824
	v_mfma_f32_32x32x16_f16 v[98:113], v[188:191], v[242:245], v[98:113]
	v_mfma_f32_32x32x16_f16 v[114:129], v[174:177], v[242:245], v[114:129]
	v_mfma_f32_32x32x16_f16 v[66:81], v[188:191], v[246:249], v[66:81]
	v_mfma_f32_32x32x16_f16 v[82:97], v[174:177], v[246:249], v[82:97]
	v_mfma_f32_32x32x16_f16 v[34:49], v[188:191], v[204:207], v[34:49]
	v_mfma_f32_32x32x16_f16 v[50:65], v[174:177], v[204:207], v[50:65]
	v_mfma_f32_32x32x16_f16 v[2:17], v[188:191], v[208:211], v[2:17]
	v_mfma_f32_32x32x16_f16 v[18:33], v[174:177], v[208:211], v[18:33]
	ds_read_b128 v[188:191], v214 offset:32
	ds_read_b128 v[242:245], v212 offset:32
	ds_read_b128 v[174:177], v214 offset:4640
	ds_read_b128 v[246:249], v212 offset:4640
	ds_read_b128 v[204:207], v212 offset:9248
	ds_read_b128 v[208:211], v212 offset:13856
	s_waitcnt vmcnt(4)
	ds_write_b128 v132, v[134:137]
	ds_write_b128 v132, v[138:141] offset:16
	ds_write_b128 v132, v[142:145] offset:32
	ds_write_b128 v132, v[146:149] offset:48
	global_load_dwordx4 v[134:137], v[130:131], off offset:1664
	global_load_dwordx4 v[138:141], v[130:131], off offset:1680
	global_load_dwordx4 v[142:145], v[130:131], off offset:1696
	global_load_dwordx4 v[146:149], v[130:131], off offset:1712
	s_waitcnt lgkmcnt(14)
	v_mfma_f32_32x32x16_f16 v[98:113], v[234:237], v[218:221], v[98:113]
	s_waitcnt lgkmcnt(13)
	v_mfma_f32_32x32x16_f16 v[114:129], v[238:241], v[218:221], v[114:129]
	s_waitcnt lgkmcnt(12)
	v_mfma_f32_32x32x16_f16 v[66:81], v[234:237], v[222:225], v[66:81]
	v_mfma_f32_32x32x16_f16 v[82:97], v[238:241], v[222:225], v[82:97]
	s_waitcnt lgkmcnt(11)
	v_mfma_f32_32x32x16_f16 v[34:49], v[234:237], v[226:229], v[34:49]
	v_mfma_f32_32x32x16_f16 v[50:65], v[238:241], v[226:229], v[50:65]
	s_waitcnt lgkmcnt(10)
	v_mfma_f32_32x32x16_f16 v[2:17], v[234:237], v[230:233], v[2:17]
	v_mfma_f32_32x32x16_f16 v[18:33], v[238:241], v[230:233], v[18:33]
	ds_read_b128 v[234:237], v214 offset:64
	ds_read_b128 v[218:221], v212 offset:64
	ds_read_b128 v[238:241], v214 offset:4672
	ds_read_b128 v[222:225], v212 offset:4672
	ds_read_b128 v[226:229], v212 offset:9280
	ds_read_b128 v[230:233], v212 offset:13888
	s_waitcnt vmcnt(4)
	ds_write_b128 v132, v[150:153] offset:36864
	ds_write_b128 v132, v[154:157] offset:36880
	ds_write_b128 v132, v[158:161] offset:36896
	ds_write_b128 v132, v[162:165] offset:36912
	global_load_dwordx4 v[150:153], v[200:201], off offset:1664
	global_load_dwordx4 v[154:157], v[200:201], off offset:1680
	global_load_dwordx4 v[158:161], v[200:201], off offset:1696
	global_load_dwordx4 v[162:165], v[200:201], off offset:1712
	s_waitcnt lgkmcnt(15)
	v_mfma_f32_32x32x16_f16 v[98:113], v[188:191], v[242:245], v[98:113]
	s_waitcnt lgkmcnt(15)
	v_mfma_f32_32x32x16_f16 v[114:129], v[174:177], v[242:245], v[114:129]
	s_waitcnt lgkmcnt(15)
	v_mfma_f32_32x32x16_f16 v[66:81], v[188:191], v[246:249], v[66:81]
	v_mfma_f32_32x32x16_f16 v[82:97], v[174:177], v[246:249], v[82:97]
	s_waitcnt lgkmcnt(15)
	v_mfma_f32_32x32x16_f16 v[34:49], v[188:191], v[204:207], v[34:49]
	v_mfma_f32_32x32x16_f16 v[50:65], v[174:177], v[204:207], v[50:65]
	s_waitcnt lgkmcnt(14)
	v_mfma_f32_32x32x16_f16 v[2:17], v[188:191], v[208:211], v[2:17]
	v_mfma_f32_32x32x16_f16 v[18:33], v[174:177], v[208:211], v[18:33]
	ds_read_b128 v[188:191], v214 offset:96
	ds_read_b128 v[242:245], v212 offset:96
	ds_read_b128 v[174:177], v214 offset:4704
	ds_read_b128 v[246:249], v212 offset:4704
	ds_read_b128 v[204:207], v212 offset:9312
	ds_read_b128 v[208:211], v212 offset:13920
	s_waitcnt lgkmcnt(14)
	v_mfma_f32_32x32x16_f16 v[98:113], v[234:237], v[218:221], v[98:113]
	s_waitcnt lgkmcnt(13)
	v_mfma_f32_32x32x16_f16 v[114:129], v[238:241], v[218:221], v[114:129]
	s_waitcnt lgkmcnt(12)
	v_mfma_f32_32x32x16_f16 v[66:81], v[234:237], v[222:225], v[66:81]
	v_mfma_f32_32x32x16_f16 v[82:97], v[238:241], v[222:225], v[82:97]
	s_waitcnt lgkmcnt(11)
	v_mfma_f32_32x32x16_f16 v[34:49], v[234:237], v[226:229], v[34:49]
	v_mfma_f32_32x32x16_f16 v[50:65], v[238:241], v[226:229], v[50:65]
	s_waitcnt lgkmcnt(10)
	v_mfma_f32_32x32x16_f16 v[2:17], v[234:237], v[230:233], v[2:17]
	v_mfma_f32_32x32x16_f16 v[18:33], v[238:241], v[230:233], v[18:33]
	s_waitcnt lgkmcnt(0)
	s_barrier
; DI f16v mfma32(h8v a, h8v b, f16v c) { return __builtin_amdgcn_mfma_f32_32x32x16_f16(a, b, c, 0, 0, 0); }
; template <bool GATHER>
; DI void gemm256_main(const h16* __restrict__ A, int lda, const int* __restrict__ idx, int m0,
;                      const h16* __restrict__ B, int ldb, int n0, int K, h16* lds, f16v (&acc)[4][2]) {
;     ...
;   for (int kt = 0; kt < nk; ++kt) {
;     const h16* As = lds + (kt & 1) * (512 * LDH);
;     const h16* Bs = As + 256 * LDH;
;     h16* Wn = lds + ((kt & 1) ^ 1) * (512 * LDH);
;     if (kt + 1 < nk) {
; #pragma unroll
;       for (int i = 0; i < 4; ++i) { *(u4v*)&Wn[lr * LDH + lc + 8 * i] = ra[i]; *(u4v*)&Wn[(256 + lr) * LDH + lc + 8 * i] = rb[i]; }
;     }
;     if (kt + 2 < nk) {
; #pragma unroll
;       for (int i = 0; i < 4; ++i) { ra[i] = *(const u4v*)(AP_ + 8 * i); rb[i] = *(const u4v*)(BP_ + 8 * i); }
;       ao += 64; bo += 64;
;     }
; #pragma unroll
;     for (int ks = 0; ks < 4; ++ks) {
;       h8v af[4], bf[2];
; #pragma unroll
;       for (int i = 0; i < 4; ++i) af[i] = *(const h8v*)&As[(wm * 128 + i * 32 + (lane & 31)) * LDH + ks * 16 + 8 * (lane >> 5)];
; #pragma unroll
;       for (int j = 0; j < 2; ++j) bf[j] = *(const h8v*)&Bs[(wn * 64 + j * 32 + (lane & 31)) * LDH + ks * 16 + 8 * (lane >> 5)];
; #pragma unroll
;       for (int i = 0; i < 4; ++i)
; #pragma unroll
;         for (int j = 0; j < 2; ++j) acc[i][j] = mfma32(bf[j], af[i], acc[i][j]);
;     }
;     __syncthreads();
	ds_read_b128 v[234:237], v213
	ds_read_b128 v[218:221], v217
	ds_read_b128 v[238:241], v213 offset:4608
	ds_read_b128 v[222:225], v217 offset:4608
	ds_read_b128 v[226:229], v217 offset:9216
	ds_read_b128 v[230:233], v217 offset:13824
	v_mfma_f32_32x32x16_f16 v[98:113], v[188:191], v[242:245], v[98:113]
	v_mfma_f32_32x32x16_f16 v[114:129], v[174:177], v[242:245], v[114:129]
	v_mfma_f32_32x32x16_f16 v[66:81], v[188:191], v[246:249], v[66:81]
	v_mfma_f32_32x32x16_f16 v[82:97], v[174:177], v[246:249], v[82:97]
	v_mfma_f32_32x32x16_f16 v[34:49], v[188:191], v[204:207], v[34:49]
	v_mfma_f32_32x32x16_f16 v[50:65], v[174:177], v[204:207], v[50:65]
	v_mfma_f32_32x32x16_f16 v[2:17], v[188:191], v[208:211], v[2:17]
	v_mfma_f32_32x32x16_f16 v[18:33], v[174:177], v[208:211], v[18:33]
	ds_read_b128 v[188:191], v213 offset:32
	ds_read_b128 v[242:245], v217 offset:32
	ds_read_b128 v[174:177], v213 offset:4640
	ds_read_b128 v[246:249], v217 offset:4640
	ds_read_b128 v[204:207], v217 offset:9248
	ds_read_b128 v[208:211], v217 offset:13856
	s_waitcnt vmcnt(4)
	ds_write_b128 v133, v[134:137]
	ds_write_b128 v133, v[138:141] offset:16
	ds_write_b128 v133, v[142:145] offset:32
	ds_write_b128 v133, v[146:149] offset:48
	global_load_dwordx4 v[134:137], v[130:131], off offset:1792
	global_load_dwordx4 v[138:141], v[130:131], off offset:1808
	global_load_dwordx4 v[142:145], v[130:131], off offset:1824
	global_load_dwordx4 v[146:149], v[130:131], off offset:1840
	s_waitcnt lgkmcnt(14)
	v_mfma_f32_32x32x16_f16 v[98:113], v[234:237], v[218:221], v[98:113]
	s_waitcnt lgkmcnt(13)
	v_mfma_f32_32x32x16_f16 v[114:129], v[238:241], v[218:221], v[114:129]
	s_waitcnt lgkmcnt(12)
	v_mfma_f32_32x32x16_f16 v[66:81], v[234:237], v[222:225], v[66:81]
	v_mfma_f32_32x32x16_f16 v[82:97], v[238:241], v[222:225], v[82:97]
	s_waitcnt lgkmcnt(11)
	v_mfma_f32_32x32x16_f16 v[34:49], v[234:237], v[226:229], v[34:49]
	v_mfma_f32_32x32x16_f16 v[50:65], v[238:241], v[226:229], v[50:65]
	s_waitcnt lgkmcnt(10)
	v_mfma_f32_32x32x16_f16 v[2:17], v[234:237], v[230:233], v[2:17]
	v_mfma_f32_32x32x16_f16 v[18:33], v[238:241], v[230:233], v[18:33]
	ds_read_b128 v[234:237], v213 offset:64
	ds_read_b128 v[218:221], v217 offset:64
	ds_read_b128 v[238:241], v213 offset:4672
	ds_read_b128 v[222:225], v217 offset:4672
	ds_read_b128 v[226:229], v217 offset:9280
	ds_read_b128 v[230:233], v217 offset:13888
	s_waitcnt vmcnt(4)
	ds_write_b128 v133, v[150:153] offset:36864
	ds_write_b128 v133, v[154:157] offset:36880
	ds_write_b128 v133, v[158:161] offset:36896
	ds_write_b128 v133, v[162:165] offset:36912
	global_load_dwordx4 v[150:153], v[200:201], off offset:1792
	global_load_dwordx4 v[154:157], v[200:201], off offset:1808
	global_load_dwordx4 v[158:161], v[200:201], off offset:1824
	global_load_dwordx4 v[162:165], v[200:201], off offset:1840
	s_waitcnt lgkmcnt(15)
	v_mfma_f32_32x32x16_f16 v[98:113], v[188:191], v[242:245], v[98:113]
	s_waitcnt lgkmcnt(15)
	v_mfma_f32_32x32x16_f16 v[114:129], v[174:177], v[242:245], v[114:129]
	s_waitcnt lgkmcnt(15)
	v_mfma_f32_32x32x16_f16 v[66:81], v[188:191], v[246:249], v[66:81]
	v_mfma_f32_32x32x16_f16 v[82:97], v[174:177], v[246:249], v[82:97]
	s_waitcnt lgkmcnt(15)
	v_mfma_f32_32x32x16_f16 v[34:49], v[188:191], v[204:207], v[34:49]
	v_mfma_f32_32x32x16_f16 v[50:65], v[174:177], v[204:207], v[50:65]
	s_waitcnt lgkmcnt(14)
	v_mfma_f32_32x32x16_f16 v[2:17], v[188:191], v[208:211], v[2:17]
	v_mfma_f32_32x32x16_f16 v[18:33], v[174:177], v[208:211], v[18:33]
	ds_read_b128 v[188:191], v213 offset:96
	ds_read_b128 v[242:245], v217 offset:96
	ds_read_b128 v[174:177], v213 offset:4704
	ds_read_b128 v[246:249], v217 offset:4704
	ds_read_b128 v[204:207], v217 offset:9312
	ds_read_b128 v[208:211], v217 offset:13920
	s_waitcnt lgkmcnt(14)
	v_mfma_f32_32x32x16_f16 v[98:113], v[234:237], v[218:221], v[98:113]
	s_waitcnt lgkmcnt(13)
	v_mfma_f32_32x32x16_f16 v[114:129], v[238:241], v[218:221], v[114:129]
	s_waitcnt lgkmcnt(12)
	v_mfma_f32_32x32x16_f16 v[66:81], v[234:237], v[222:225], v[66:81]
	v_mfma_f32_32x32x16_f16 v[82:97], v[238:241], v[222:225], v[82:97]
	s_waitcnt lgkmcnt(11)
	v_mfma_f32_32x32x16_f16 v[34:49], v[234:237], v[226:229], v[34:49]
	v_mfma_f32_32x32x16_f16 v[50:65], v[238:241], v[226:229], v[50:65]
	s_waitcnt lgkmcnt(10)
	v_mfma_f32_32x32x16_f16 v[2:17], v[234:237], v[230:233], v[2:17]
	v_mfma_f32_32x32x16_f16 v[18:33], v[238:241], v[230:233], v[18:33]
	s_waitcnt lgkmcnt(0)
	s_barrier
; DI f16v mfma32(h8v a, h8v b, f16v c) { return __builtin_amdgcn_mfma_f32_32x32x16_f16(a, b, c, 0, 0, 0); }
; template <bool GATHER>
; DI void gemm256_main(const h16* __restrict__ A, int lda, const int* __restrict__ idx, int m0,
;                      const h16* __restrict__ B, int ldb, int n0, int K, h16* lds, f16v (&acc)[4][2]) {
;     ...
;   for (int kt = 0; kt < nk; ++kt) {
;     const h16* As = lds + (kt & 1) * (512 * LDH);
;     const h16* Bs = As + 256 * LDH;
;     h16* Wn = lds + ((kt & 1) ^ 1) * (512 * LDH);
;     if (kt + 1 < nk) {
; #pragma unroll
;       for (int i = 0; i < 4; ++i) { *(u4v*)&Wn[lr * LDH + lc + 8 * i] = ra[i]; *(u4v*)&Wn[(256 + lr) * LDH + lc + 8 * i] = rb[i]; }
;     }
;     if (kt + 2 < nk) {
; #pragma unroll
;       for (int i = 0; i < 4; ++i) { ra[i] = *(const u4v*)(AP_ + 8 * i); rb[i] = *(const u4v*)(BP_ + 8 * i); }
;       ao += 64; bo += 64;
;     }
; #pragma unroll
;     for (int ks = 0; ks < 4; ++ks) {
;       h8v af[4], bf[2];
; #pragma unroll
;       for (int i = 0; i < 4; ++i) af[i] = *(const h8v*)&As[(wm * 128 + i * 32 + (lane & 31)) * LDH + ks * 16 + 8 * (lane >> 5)];
; #pragma unroll
;       for (int j = 0; j < 2; ++j) bf[j] = *(const h8v*)&Bs[(wn * 64 + j * 32 + (lane & 31)) * LDH + ks * 16 + 8 * (lane >> 5)];
; #pragma unroll
;       for (int i = 0; i < 4; ++i)
; #pragma unroll
;         for (int j = 0; j < 2; ++j) acc[i][j] = mfma32(bf[j], af[i], acc[i][j]);
;     }
;     __syncthreads();
	ds_read_b128 v[234:237], v214
	ds_read_b128 v[218:221], v212
	ds_read_b128 v[238:241], v214 offset:4608
	ds_read_b128 v[222:225], v212 offset:4608
	ds_read_b128 v[226:229], v212 offset:9216
	ds_read_b128 v[230:233], v212 offset:13824
	v_mfma_f32_32x32x16_f16 v[98:113], v[188:191], v[242:245], v[98:113]
	v_mfma_f32_32x32x16_f16 v[114:129], v[174:177], v[242:245], v[114:129]
	v_mfma_f32_32x32x16_f16 v[66:81], v[188:191], v[246:249], v[66:81]
	v_mfma_f32_32x32x16_f16 v[82:97], v[174:177], v[246:249], v[82:97]
	v_mfma_f32_32x32x16_f16 v[34:49], v[188:191], v[204:207], v[34:49]
	v_mfma_f32_32x32x16_f16 v[50:65], v[174:177], v[204:207], v[50:65]
	v_mfma_f32_32x32x16_f16 v[2:17], v[188:191], v[208:211], v[2:17]
	v_mfma_f32_32x32x16_f16 v[18:33], v[174:177], v[208:211], v[18:33]
	ds_read_b128 v[188:191], v214 offset:32
	ds_read_b128 v[242:245], v212 offset:32
	ds_read_b128 v[174:177], v214 offset:4640
	ds_read_b128 v[246:249], v212 offset:4640
	ds_read_b128 v[204:207], v212 offset:9248
	ds_read_b128 v[208:211], v212 offset:13856
	s_waitcnt vmcnt(4)
	ds_write_b128 v132, v[134:137]
	ds_write_b128 v132, v[138:141] offset:16
	ds_write_b128 v132, v[142:145] offset:32
	ds_write_b128 v132, v[146:149] offset:48
	global_load_dwordx4 v[134:137], v[130:131], off offset:1920
	global_load_dwordx4 v[138:141], v[130:131], off offset:1936
	global_load_dwordx4 v[142:145], v[130:131], off offset:1952
	global_load_dwordx4 v[146:149], v[130:131], off offset:1968
	s_waitcnt lgkmcnt(14)
	v_mfma_f32_32x32x16_f16 v[98:113], v[234:237], v[218:221], v[98:113]
	s_waitcnt lgkmcnt(13)
	v_mfma_f32_32x32x16_f16 v[114:129], v[238:241], v[218:221], v[114:129]
	s_waitcnt lgkmcnt(12)
	v_mfma_f32_32x32x16_f16 v[66:81], v[234:237], v[222:225], v[66:81]
	v_mfma_f32_32x32x16_f16 v[82:97], v[238:241], v[222:225], v[82:97]
	s_waitcnt lgkmcnt(11)
	v_mfma_f32_32x32x16_f16 v[34:49], v[234:237], v[226:229], v[34:49]
	v_mfma_f32_32x32x16_f16 v[50:65], v[238:241], v[226:229], v[50:65]
	s_waitcnt lgkmcnt(10)
	v_mfma_f32_32x32x16_f16 v[2:17], v[234:237], v[230:233], v[2:17]
	v_mfma_f32_32x32x16_f16 v[18:33], v[238:241], v[230:233], v[18:33]
	ds_read_b128 v[234:237], v214 offset:64
	ds_read_b128 v[218:221], v212 offset:64
	ds_read_b128 v[238:241], v214 offset:4672
	ds_read_b128 v[222:225], v212 offset:4672
	ds_read_b128 v[226:229], v212 offset:9280
	ds_read_b128 v[230:233], v212 offset:13888
	s_waitcnt vmcnt(4)
	ds_write_b128 v132, v[150:153] offset:36864
	ds_write_b128 v132, v[154:157] offset:36880
	ds_write_b128 v132, v[158:161] offset:36896
	ds_write_b128 v132, v[162:165] offset:36912
	global_load_dwordx4 v[150:153], v[200:201], off offset:1920
	global_load_dwordx4 v[154:157], v[200:201], off offset:1936
	global_load_dwordx4 v[158:161], v[200:201], off offset:1952
	global_load_dwordx4 v[162:165], v[200:201], off offset:1968
	s_waitcnt lgkmcnt(15)
	v_mfma_f32_32x32x16_f16 v[98:113], v[188:191], v[242:245], v[98:113]
	s_waitcnt lgkmcnt(15)
	v_mfma_f32_32x32x16_f16 v[114:129], v[174:177], v[242:245], v[114:129]
	s_waitcnt lgkmcnt(15)
	v_mfma_f32_32x32x16_f16 v[66:81], v[188:191], v[246:249], v[66:81]
	v_mfma_f32_32x32x16_f16 v[82:97], v[174:177], v[246:249], v[82:97]
	s_waitcnt lgkmcnt(15)
	v_mfma_f32_32x32x16_f16 v[34:49], v[188:191], v[204:207], v[34:49]
	v_mfma_f32_32x32x16_f16 v[50:65], v[174:177], v[204:207], v[50:65]
	s_waitcnt lgkmcnt(14)
	v_mfma_f32_32x32x16_f16 v[2:17], v[188:191], v[208:211], v[2:17]
	v_mfma_f32_32x32x16_f16 v[18:33], v[174:177], v[208:211], v[18:33]
	ds_read_b128 v[188:191], v214 offset:96
	ds_read_b128 v[242:245], v212 offset:96
	ds_read_b128 v[174:177], v214 offset:4704
	ds_read_b128 v[246:249], v212 offset:4704
	ds_read_b128 v[204:207], v212 offset:9312
	ds_read_b128 v[208:211], v212 offset:13920
	s_waitcnt lgkmcnt(14)
	v_mfma_f32_32x32x16_f16 v[98:113], v[234:237], v[218:221], v[98:113]
	s_waitcnt lgkmcnt(13)
	v_mfma_f32_32x32x16_f16 v[114:129], v[238:241], v[218:221], v[114:129]
	s_waitcnt lgkmcnt(12)
	v_mfma_f32_32x32x16_f16 v[66:81], v[234:237], v[222:225], v[66:81]
	v_mfma_f32_32x32x16_f16 v[82:97], v[238:241], v[222:225], v[82:97]
	s_waitcnt lgkmcnt(11)
	v_mfma_f32_32x32x16_f16 v[34:49], v[234:237], v[226:229], v[34:49]
	v_mfma_f32_32x32x16_f16 v[50:65], v[238:241], v[226:229], v[50:65]
	s_waitcnt lgkmcnt(10)
	v_mfma_f32_32x32x16_f16 v[2:17], v[234:237], v[230:233], v[2:17]
	v_mfma_f32_32x32x16_f16 v[18:33], v[238:241], v[230:233], v[18:33]
	s_waitcnt lgkmcnt(0)
	s_barrier
; DI f16v mfma32(h8v a, h8v b, f16v c) { return __builtin_amdgcn_mfma_f32_32x32x16_f16(a, b, c, 0, 0, 0); }
; template <bool GATHER>
; DI void gemm256_main(const h16* __restrict__ A, int lda, const int* __restrict__ idx, int m0,
;                      const h16* __restrict__ B, int ldb, int n0, int K, h16* lds, f16v (&acc)[4][2]) {
;     ...
;   for (int kt = 0; kt < nk; ++kt) {
;     const h16* As = lds + (kt & 1) * (512 * LDH);
;     const h16* Bs = As + 256 * LDH;
;     h16* Wn = lds + ((kt & 1) ^ 1) * (512 * LDH);
;     if (kt + 1 < nk) {
; #pragma unroll
;       for (int i = 0; i < 4; ++i) { *(u4v*)&Wn[lr * LDH + lc + 8 * i] = ra[i]; *(u4v*)&Wn[(256 + lr) * LDH + lc + 8 * i] = rb[i]; }
;     }
;     if (kt + 2 < nk) {
; #pragma unroll
;       for (int i = 0; i < 4; ++i) { ra[i] = *(const u4v*)(AP_ + 8 * i); rb[i] = *(const u4v*)(BP_ + 8 * i); }
;       ao += 64; bo += 64;
;     }
; #pragma unroll
;     for (int ks = 0; ks < 4; ++ks) {
;       h8v af[4], bf[2];
; #pragma unroll
;       for (int i = 0; i < 4; ++i) af[i] = *(const h8v*)&As[(wm * 128 + i * 32 + (lane & 31)) * LDH + ks * 16 + 8 * (lane >> 5)];
; #pragma unroll
;       for (int j = 0; j < 2; ++j) bf[j] = *(const h8v*)&Bs[(wn * 64 + j * 32 + (lane & 31)) * LDH + ks * 16 + 8 * (lane >> 5)];
; #pragma unroll
;       for (int i = 0; i < 4; ++i)
; #pragma unroll
;         for (int j = 0; j < 2; ++j) acc[i][j] = mfma32(bf[j], af[i], acc[i][j]);
;     }
;     __syncthreads();
	ds_read_b128 v[234:237], v213
	ds_read_b128 v[218:221], v217
	ds_read_b128 v[238:241], v213 offset:4608
	ds_read_b128 v[222:225], v217 offset:4608
	ds_read_b128 v[226:229], v217 offset:9216
	ds_read_b128 v[230:233], v217 offset:13824
	v_mfma_f32_32x32x16_f16 v[98:113], v[188:191], v[242:245], v[98:113]
	v_mfma_f32_32x32x16_f16 v[114:129], v[174:177], v[242:245], v[114:129]
	v_mfma_f32_32x32x16_f16 v[66:81], v[188:191], v[246:249], v[66:81]
	v_mfma_f32_32x32x16_f16 v[82:97], v[174:177], v[246:249], v[82:97]
	v_mfma_f32_32x32x16_f16 v[34:49], v[188:191], v[204:207], v[34:49]
	v_mfma_f32_32x32x16_f16 v[50:65], v[174:177], v[204:207], v[50:65]
	v_mfma_f32_32x32x16_f16 v[2:17], v[188:191], v[208:211], v[2:17]
	v_mfma_f32_32x32x16_f16 v[18:33], v[174:177], v[208:211], v[18:33]
	ds_read_b128 v[188:191], v213 offset:32
	ds_read_b128 v[242:245], v217 offset:32
	ds_read_b128 v[174:177], v213 offset:4640
	ds_read_b128 v[246:249], v217 offset:4640
	ds_read_b128 v[204:207], v217 offset:9248
	ds_read_b128 v[208:211], v217 offset:13856
	s_waitcnt vmcnt(4)
	ds_write_b128 v133, v[134:137]
	ds_write_b128 v133, v[138:141] offset:16
	ds_write_b128 v133, v[142:145] offset:32
	ds_write_b128 v133, v[146:149] offset:48
	s_waitcnt lgkmcnt(14)
	v_mfma_f32_32x32x16_f16 v[98:113], v[234:237], v[218:221], v[98:113]
	s_waitcnt lgkmcnt(13)
	v_mfma_f32_32x32x16_f16 v[114:129], v[238:241], v[218:221], v[114:129]
	s_waitcnt lgkmcnt(12)
	v_mfma_f32_32x32x16_f16 v[66:81], v[234:237], v[222:225], v[66:81]
	v_mfma_f32_32x32x16_f16 v[82:97], v[238:241], v[222:225], v[82:97]
	s_waitcnt lgkmcnt(11)
	v_mfma_f32_32x32x16_f16 v[34:49], v[234:237], v[226:229], v[34:49]
	v_mfma_f32_32x32x16_f16 v[50:65], v[238:241], v[226:229], v[50:65]
	s_waitcnt lgkmcnt(10)
	v_mfma_f32_32x32x16_f16 v[2:17], v[234:237], v[230:233], v[2:17]
	v_mfma_f32_32x32x16_f16 v[18:33], v[238:241], v[230:233], v[18:33]
	ds_read_b128 v[234:237], v213 offset:64
	ds_read_b128 v[218:221], v217 offset:64
	ds_read_b128 v[238:241], v213 offset:4672
	ds_read_b128 v[222:225], v217 offset:4672
	ds_read_b128 v[226:229], v217 offset:9280
	ds_read_b128 v[230:233], v217 offset:13888
	s_waitcnt vmcnt(0)
	ds_write_b128 v133, v[150:153] offset:36864
	ds_write_b128 v133, v[154:157] offset:36880
	ds_write_b128 v133, v[158:161] offset:36896
	ds_write_b128 v133, v[162:165] offset:36912
	s_waitcnt lgkmcnt(15)
	v_mfma_f32_32x32x16_f16 v[98:113], v[188:191], v[242:245], v[98:113]
	s_waitcnt lgkmcnt(15)
	v_mfma_f32_32x32x16_f16 v[114:129], v[174:177], v[242:245], v[114:129]
	s_waitcnt lgkmcnt(15)
	v_mfma_f32_32x32x16_f16 v[66:81], v[188:191], v[246:249], v[66:81]
	v_mfma_f32_32x32x16_f16 v[82:97], v[174:177], v[246:249], v[82:97]
	s_waitcnt lgkmcnt(15)
	v_mfma_f32_32x32x16_f16 v[34:49], v[188:191], v[204:207], v[34:49]
	v_mfma_f32_32x32x16_f16 v[50:65], v[174:177], v[204:207], v[50:65]
	s_waitcnt lgkmcnt(14)
	v_mfma_f32_32x32x16_f16 v[2:17], v[188:191], v[208:211], v[2:17]
	v_mfma_f32_32x32x16_f16 v[18:33], v[174:177], v[208:211], v[18:33]
	ds_read_b128 v[188:191], v213 offset:96
	ds_read_b128 v[242:245], v217 offset:96
	ds_read_b128 v[174:177], v213 offset:4704
	ds_read_b128 v[246:249], v217 offset:4704
	ds_read_b128 v[204:207], v217 offset:9312
	ds_read_b128 v[208:211], v217 offset:13920
	s_waitcnt lgkmcnt(14)
	v_mfma_f32_32x32x16_f16 v[98:113], v[234:237], v[218:221], v[98:113]
	s_waitcnt lgkmcnt(13)
	v_mfma_f32_32x32x16_f16 v[114:129], v[238:241], v[218:221], v[114:129]
	s_waitcnt lgkmcnt(12)
	v_mfma_f32_32x32x16_f16 v[66:81], v[234:237], v[222:225], v[66:81]
	v_mfma_f32_32x32x16_f16 v[82:97], v[238:241], v[222:225], v[82:97]
	s_waitcnt lgkmcnt(11)
	v_mfma_f32_32x32x16_f16 v[34:49], v[234:237], v[226:229], v[34:49]
	v_mfma_f32_32x32x16_f16 v[50:65], v[238:241], v[226:229], v[50:65]
	s_waitcnt lgkmcnt(10)
	v_mfma_f32_32x32x16_f16 v[2:17], v[234:237], v[230:233], v[2:17]
	v_mfma_f32_32x32x16_f16 v[18:33], v[238:241], v[230:233], v[18:33]
	s_waitcnt lgkmcnt(0)
	s_barrier
	ds_read_b128 v[234:237], v214
	ds_read_b128 v[218:221], v212
	ds_read_b128 v[238:241], v214 offset:4608
	ds_read_b128 v[222:225], v212 offset:4608
	ds_read_b128 v[226:229], v212 offset:9216
	ds_read_b128 v[230:233], v212 offset:13824
	v_mfma_f32_32x32x16_f16 v[98:113], v[188:191], v[242:245], v[98:113]
	v_mfma_f32_32x32x16_f16 v[114:129], v[174:177], v[242:245], v[114:129]
	v_mfma_f32_32x32x16_f16 v[66:81], v[188:191], v[246:249], v[66:81]
	v_mfma_f32_32x32x16_f16 v[82:97], v[174:177], v[246:249], v[82:97]
	v_mfma_f32_32x32x16_f16 v[34:49], v[188:191], v[204:207], v[34:49]
	v_mfma_f32_32x32x16_f16 v[50:65], v[174:177], v[204:207], v[50:65]
	v_mfma_f32_32x32x16_f16 v[2:17], v[188:191], v[208:211], v[2:17]
	v_mfma_f32_32x32x16_f16 v[18:33], v[174:177], v[208:211], v[18:33]
	ds_read_b128 v[188:191], v214 offset:32
	ds_read_b128 v[242:245], v212 offset:32
	ds_read_b128 v[174:177], v214 offset:4640
	ds_read_b128 v[246:249], v212 offset:4640
	ds_read_b128 v[204:207], v212 offset:9248
	ds_read_b128 v[208:211], v212 offset:13856
	s_waitcnt lgkmcnt(10)
	v_mfma_f32_32x32x16_f16 v[98:113], v[234:237], v[218:221], v[98:113]
	s_waitcnt lgkmcnt(9)
	v_mfma_f32_32x32x16_f16 v[114:129], v[238:241], v[218:221], v[114:129]
	s_waitcnt lgkmcnt(8)
	v_mfma_f32_32x32x16_f16 v[66:81], v[234:237], v[222:225], v[66:81]
	v_mfma_f32_32x32x16_f16 v[82:97], v[238:241], v[222:225], v[82:97]
	s_waitcnt lgkmcnt(7)
	v_mfma_f32_32x32x16_f16 v[34:49], v[234:237], v[226:229], v[34:49]
	v_mfma_f32_32x32x16_f16 v[50:65], v[238:241], v[226:229], v[50:65]
	s_waitcnt lgkmcnt(6)
; DI float silu_(float x) { return x / (1.f + __expf(-x)); }
; DI f16v mfma32(h8v a, h8v b, f16v c) { return __builtin_amdgcn_mfma_f32_32x32x16_f16(a, b, c, 0, 0, 0); }
; template <bool GATHER>
; DI void gemm256_main(const h16* __restrict__ A, int lda, const int* __restrict__ idx, int m0,
;                      const h16* __restrict__ B, int ldb, int n0, int K, h16* lds, f16v (&acc)[4][2]) {
;     ...
; #pragma unroll
;     for (int ks = 0; ks < 4; ++ks) {
;       h8v af[4], bf[2];
; #pragma unroll
;       for (int i = 0; i < 4; ++i) af[i] = *(const h8v*)&As[(wm * 128 + i * 32 + (lane & 31)) * LDH + ks * 16 + 8 * (lane >> 5)];
; #pragma unroll
;       for (int j = 0; j < 2; ++j) bf[j] = *(const h8v*)&Bs[(wn * 64 + j * 32 + (lane & 31)) * LDH + ks * 16 + 8 * (lane >> 5)];
; #pragma unroll
;       for (int i = 0; i < 4; ++i)
; #pragma unroll
;         for (int j = 0; j < 2; ++j) acc[i][j] = mfma32(bf[j], af[i], acc[i][j]);
;     }
; DI void phase_ffn1_moe(const Params& p, int bid, int nb, h16* lds) {
;     ...
;     gemm256_epilogue(acc, m0, n0, [&](int m, int n, f4v v0, f4v v1) {
;       f4v hq;
; #pragma unroll
;       for (int i = 0; i < 4; ++i) hq[i] = silu_(v0[i]) * v1[i];
;       st_h4(&H[(size_t)m * 1408 + (n >> 6) * 32 + (n & 31)], hq);
;     });
	v_mfma_f32_32x32x16_f16 v[2:17], v[234:237], v[230:233], v[2:17]
	v_mfma_f32_32x32x16_f16 v[18:33], v[238:241], v[230:233], v[18:33]
	ds_read_b128 v[234:237], v214 offset:64
	ds_read_b128 v[218:221], v212 offset:64
	ds_read_b128 v[238:241], v214 offset:4672
	ds_read_b128 v[222:225], v212 offset:4672
	ds_read_b128 v[226:229], v212 offset:9280
	ds_read_b128 v[230:233], v212 offset:13888
	s_waitcnt lgkmcnt(10)
	v_mfma_f32_32x32x16_f16 v[98:113], v[188:191], v[242:245], v[98:113]
	s_waitcnt lgkmcnt(9)
	v_mfma_f32_32x32x16_f16 v[114:129], v[174:177], v[242:245], v[114:129]
	s_waitcnt lgkmcnt(8)
	v_mfma_f32_32x32x16_f16 v[66:81], v[188:191], v[246:249], v[66:81]
	v_mfma_f32_32x32x16_f16 v[82:97], v[174:177], v[246:249], v[82:97]
	s_waitcnt lgkmcnt(7)
	v_mfma_f32_32x32x16_f16 v[34:49], v[188:191], v[204:207], v[34:49]
	v_mfma_f32_32x32x16_f16 v[50:65], v[174:177], v[204:207], v[50:65]
	s_waitcnt lgkmcnt(6)
	v_mfma_f32_32x32x16_f16 v[2:17], v[188:191], v[208:211], v[2:17]
	v_mfma_f32_32x32x16_f16 v[18:33], v[174:177], v[208:211], v[18:33]
	ds_read_b128 v[188:191], v214 offset:96
	ds_read_b128 v[242:245], v212 offset:96
	ds_read_b128 v[174:177], v214 offset:4704
	ds_read_b128 v[246:249], v212 offset:4704
	ds_read_b128 v[204:207], v212 offset:9312
	ds_read_b128 v[208:211], v212 offset:13920
	s_waitcnt lgkmcnt(10)
	v_mfma_f32_32x32x16_f16 v[98:113], v[234:237], v[218:221], v[98:113]
	s_waitcnt lgkmcnt(9)
	v_mfma_f32_32x32x16_f16 v[114:129], v[238:241], v[218:221], v[114:129]
	s_waitcnt lgkmcnt(8)
	v_mfma_f32_32x32x16_f16 v[66:81], v[234:237], v[222:225], v[66:81]
	v_mfma_f32_32x32x16_f16 v[82:97], v[238:241], v[222:225], v[82:97]
	s_waitcnt lgkmcnt(7)
	v_mfma_f32_32x32x16_f16 v[34:49], v[234:237], v[226:229], v[34:49]
	v_mfma_f32_32x32x16_f16 v[50:65], v[238:241], v[226:229], v[50:65]
	s_waitcnt lgkmcnt(6)
	v_mfma_f32_32x32x16_f16 v[2:17], v[234:237], v[230:233], v[2:17]
	v_mfma_f32_32x32x16_f16 v[18:33], v[238:241], v[230:233], v[18:33]
	s_waitcnt lgkmcnt(0)
	v_mfma_f32_32x32x16_f16 v[98:113], v[188:191], v[242:245], v[98:113]
	v_mfma_f32_32x32x16_f16 v[114:129], v[174:177], v[242:245], v[114:129]
	v_mfma_f32_32x32x16_f16 v[66:81], v[188:191], v[246:249], v[66:81]
	v_mfma_f32_32x32x16_f16 v[82:97], v[174:177], v[246:249], v[82:97]
	v_mfma_f32_32x32x16_f16 v[34:49], v[188:191], v[204:207], v[34:49]
	v_mfma_f32_32x32x16_f16 v[50:65], v[174:177], v[204:207], v[50:65]
	v_mfma_f32_32x32x16_f16 v[2:17], v[188:191], v[208:211], v[2:17]
	v_mfma_f32_32x32x16_f16 v[18:33], v[174:177], v[208:211], v[18:33]
	s_nop 15
	v_mov_b32_e32 v188, 0x358637bd
	v_mov_b32_e32 v189, 0x3727c5ac
	v_mov_b32_e32 v190, 0x2100
	v_mov_b32_e32 v191, 0x1400
	v_mov_b32_e32 v192, 0x7f800000
	v_mov_b32_e32 v193, 0x7fc00000
	v_mov_b32_e32 v194, 0xff800000
	v_mov_b32_e32 v204, 0x7fffec00
	v_mov_b32_e32 v205, 0xff7fc99e
	v_mov_b32_e32 v206, 0x840000
	v_mov_b32_e32 v207, 0xb00000
	v_mov_b32_e32 v208, 0xdc0000
	v_mov_b32_e32 v209, 0x1080000
	v_mov_b32_e32 v210, 0x1340000
	v_mov_b32_e32 v211, 0x420000
	v_mov_b32_e32 v212, 0x580000
	v_mov_b32_e32 v213, 0x6e0000
	v_mov_b32_e32 v214, 0x9a0000
	s_barrier
	v_readfirstlane_b32 s66, v180
	s_sub_i32 s69, s4, s7
	s_mov_b32 s65, s6
	s_lshr_b32 s66, s66, 6
	s_and_b32 s67, s66, 3
	s_lshr_b32 s68, s66, 2
	s_lshr_b32 s70, s69, 1
	s_lshl_b32 s67, s67, 5
	s_add_i32 s70, s70, s67
	s_lshl_b32 s71, s68, 7
	s_add_i32 s71, s71, s65
	s_mul_i32 s72, s66, 0x2800
	s_add_i32 s72, s72, 16
	s_mov_b32 s73, 0xb00
	v_and_b32_e32 v146, 63, v180
	v_and_b32_e32 v148, 31, v146
	v_lshrrev_b32_e32 v147, 5, v146
	v_mul_u32_u24_e32 v130, 0x50, v148
	v_lshl_add_u32 v130, v147, 3, v130
	v_add_u32_e32 v130, s72, v130
	v_lshrrev_b32_e32 v149, 2, v146
	v_and_b32_e32 v138, 3, v146
	v_mul_u32_u24_e32 v131, 0x50, v149
	v_lshl_add_u32 v131, v138, 4, v131
	v_add_u32_e32 v131, s72, v131
	v_add_u32_e32 v140, s71, v149
	v_lshl_add_u32 v138, v138, 3, s70
	v_mov_b64_e32 v[132:133], s[0:1]
	v_mad_u64_u32 v[132:133], s[74:75], v140, s73, v[132:133]
	v_lshlrev_b32_e32 v138, 1, v138
	v_mov_b32_e32 v139, v0
	v_lshl_add_u64 v[132:133], v[132:133], 0, v[138:139]
	s_mov_b32 s76, 0xb000
	s_mov_b32 s77, 0
	v_mul_f32_e32 v234, 0xbfb8aa3b, v98
	v_mul_f32_e32 v235, 0xbfb8aa3b, v99
	v_mul_f32_e32 v236, 0xbfb8aa3b, v100
	v_mul_f32_e32 v237, 0xbfb8aa3b, v101
	v_exp_f32_e32 v234, v234
	v_exp_f32_e32 v235, v235
	v_exp_f32_e32 v236, v236
	v_exp_f32_e32 v237, v237
	v_add_f32_e32 v234, 1.0, v234
	v_add_f32_e32 v235, 1.0, v235
	v_add_f32_e32 v236, 1.0, v236
	v_add_f32_e32 v237, 1.0, v237
	v_rcp_f32_e32 v234, v234
	v_rcp_f32_e32 v235, v235
	v_rcp_f32_e32 v236, v236
	v_rcp_f32_e32 v237, v237
	v_mul_f32_e32 v98, v98, v234
	v_mul_f32_e32 v99, v99, v235
	v_mul_f32_e32 v100, v100, v236
	v_mul_f32_e32 v101, v101, v237
	v_mul_f32_e32 v98, v98, v114
	v_mul_f32_e32 v99, v99, v115
	v_mul_f32_e32 v100, v100, v116
	v_mul_f32_e32 v101, v101, v117
	v_cvt_pk_f16_f32 v138, v98, v99
	v_cvt_pk_f16_f32 v139, v100, v101
	ds_write_b64 v130, v[138:139] offset:0
	v_mul_f32_e32 v234, 0xbfb8aa3b, v102
	v_mul_f32_e32 v235, 0xbfb8aa3b, v103
	v_mul_f32_e32 v236, 0xbfb8aa3b, v104
	v_mul_f32_e32 v237, 0xbfb8aa3b, v105
	v_exp_f32_e32 v234, v234
	v_exp_f32_e32 v235, v235
	v_exp_f32_e32 v236, v236
	v_exp_f32_e32 v237, v237
	v_add_f32_e32 v234, 1.0, v234
	v_add_f32_e32 v235, 1.0, v235
	v_add_f32_e32 v236, 1.0, v236
	v_add_f32_e32 v237, 1.0, v237
	v_rcp_f32_e32 v234, v234
	v_rcp_f32_e32 v235, v235
	v_rcp_f32_e32 v236, v236
	v_rcp_f32_e32 v237, v237
	v_mul_f32_e32 v102, v102, v234
	v_mul_f32_e32 v103, v103, v235
	v_mul_f32_e32 v104, v104, v236
	v_mul_f32_e32 v105, v105, v237
	v_mul_f32_e32 v102, v102, v118
	v_mul_f32_e32 v103, v103, v119
; DI float silu_(float x) { return x / (1.f + __expf(-x)); }
; template <class Epi>
; DI void gemm256_epilogue(f16v (&acc)[4][2], int m0, int n0, Epi epi) {
;     ...
;   for (int i = 0; i < 4; ++i) {
;     const int m = m0 + wm * 128 + i * 32 + (lane & 31);
; #pragma unroll
;     for (int g = 0; g < 4; ++g) {
;       const int n = n0 + wn * 64 + 8 * g + 4 * h;
;       f4v v0 = {acc[i][0][4 * g], acc[i][0][4 * g + 1], acc[i][0][4 * g + 2], acc[i][0][4 * g + 3]};
;       f4v v1 = {acc[i][1][4 * g], acc[i][1][4 * g + 1], acc[i][1][4 * g + 2], acc[i][1][4 * g + 3]};
;       epi(m, n, v0, v1);
; DI void phase_ffn1_moe(const Params& p, int bid, int nb, h16* lds) {
;     ...
;     gemm256_epilogue(acc, m0, n0, [&](int m, int n, f4v v0, f4v v1) {
;       f4v hq;
; #pragma unroll
;       for (int i = 0; i < 4; ++i) hq[i] = silu_(v0[i]) * v1[i];
;       st_h4(&H[(size_t)m * 1408 + (n >> 6) * 32 + (n & 31)], hq);
;     });
	v_mul_f32_e32 v104, v104, v120
	v_mul_f32_e32 v105, v105, v121
	v_cvt_pk_f16_f32 v140, v102, v103
	v_cvt_pk_f16_f32 v141, v104, v105
	ds_write_b64 v130, v[140:141] offset:16
	v_mul_f32_e32 v234, 0xbfb8aa3b, v106
	v_mul_f32_e32 v235, 0xbfb8aa3b, v107
	v_mul_f32_e32 v236, 0xbfb8aa3b, v108
	v_mul_f32_e32 v237, 0xbfb8aa3b, v109
	v_exp_f32_e32 v234, v234
	v_exp_f32_e32 v235, v235
	v_exp_f32_e32 v236, v236
	v_exp_f32_e32 v237, v237
	v_add_f32_e32 v234, 1.0, v234
	v_add_f32_e32 v235, 1.0, v235
	v_add_f32_e32 v236, 1.0, v236
	v_add_f32_e32 v237, 1.0, v237
	v_rcp_f32_e32 v234, v234
	v_rcp_f32_e32 v235, v235
	v_rcp_f32_e32 v236, v236
	v_rcp_f32_e32 v237, v237
	v_mul_f32_e32 v106, v106, v234
	v_mul_f32_e32 v107, v107, v235
	v_mul_f32_e32 v108, v108, v236
	v_mul_f32_e32 v109, v109, v237
	v_mul_f32_e32 v106, v106, v122
	v_mul_f32_e32 v107, v107, v123
	v_mul_f32_e32 v108, v108, v124
	v_mul_f32_e32 v109, v109, v125
	v_cvt_pk_f16_f32 v142, v106, v107
	v_cvt_pk_f16_f32 v143, v108, v109
	ds_write_b64 v130, v[142:143] offset:32
	v_mul_f32_e32 v234, 0xbfb8aa3b, v110
	v_mul_f32_e32 v235, 0xbfb8aa3b, v111
	v_mul_f32_e32 v236, 0xbfb8aa3b, v112
	v_mul_f32_e32 v237, 0xbfb8aa3b, v113
	v_exp_f32_e32 v234, v234
	v_exp_f32_e32 v235, v235
	v_exp_f32_e32 v236, v236
	v_exp_f32_e32 v237, v237
	v_add_f32_e32 v234, 1.0, v234
	v_add_f32_e32 v235, 1.0, v235
	v_add_f32_e32 v236, 1.0, v236
	v_add_f32_e32 v237, 1.0, v237
	v_rcp_f32_e32 v234, v234
	v_rcp_f32_e32 v235, v235
	v_rcp_f32_e32 v236, v236
	v_rcp_f32_e32 v237, v237
	v_mul_f32_e32 v110, v110, v234
	v_mul_f32_e32 v111, v111, v235
	v_mul_f32_e32 v112, v112, v236
	v_mul_f32_e32 v113, v113, v237
	v_mul_f32_e32 v110, v110, v126
	v_mul_f32_e32 v111, v111, v127
	v_mul_f32_e32 v112, v112, v128
	v_mul_f32_e32 v113, v113, v129
	v_cvt_pk_f16_f32 v144, v110, v111
	v_cvt_pk_f16_f32 v145, v112, v113
	ds_write_b64 v130, v[144:145] offset:48
	v_mul_f32_e32 v234, 0xbfb8aa3b, v66
	v_mul_f32_e32 v235, 0xbfb8aa3b, v67
	v_mul_f32_e32 v236, 0xbfb8aa3b, v68
	v_mul_f32_e32 v237, 0xbfb8aa3b, v69
	v_exp_f32_e32 v234, v234
	v_exp_f32_e32 v235, v235
	v_exp_f32_e32 v236, v236
	v_exp_f32_e32 v237, v237
	v_add_f32_e32 v234, 1.0, v234
	v_add_f32_e32 v235, 1.0, v235
	v_add_f32_e32 v236, 1.0, v236
	v_add_f32_e32 v237, 1.0, v237
	v_rcp_f32_e32 v234, v234
	v_rcp_f32_e32 v235, v235
	v_rcp_f32_e32 v236, v236
	v_rcp_f32_e32 v237, v237
	v_mul_f32_e32 v66, v66, v234
	v_mul_f32_e32 v67, v67, v235
	v_mul_f32_e32 v68, v68, v236
	v_mul_f32_e32 v69, v69, v237
	v_mul_f32_e32 v66, v66, v82
	v_mul_f32_e32 v67, v67, v83
	v_mul_f32_e32 v68, v68, v84
	v_mul_f32_e32 v69, v69, v85
	v_cvt_pk_f16_f32 v138, v66, v67
	v_cvt_pk_f16_f32 v139, v68, v69
	ds_write_b64 v130, v[138:139] offset:2560
	v_mul_f32_e32 v234, 0xbfb8aa3b, v70
	v_mul_f32_e32 v235, 0xbfb8aa3b, v71
	v_mul_f32_e32 v236, 0xbfb8aa3b, v72
	v_mul_f32_e32 v237, 0xbfb8aa3b, v73
	v_exp_f32_e32 v234, v234
	v_exp_f32_e32 v235, v235
	v_exp_f32_e32 v236, v236
	v_exp_f32_e32 v237, v237
	v_add_f32_e32 v234, 1.0, v234
	v_add_f32_e32 v235, 1.0, v235
	v_add_f32_e32 v236, 1.0, v236
	v_add_f32_e32 v237, 1.0, v237
	v_rcp_f32_e32 v234, v234
	v_rcp_f32_e32 v235, v235
	v_rcp_f32_e32 v236, v236
	v_rcp_f32_e32 v237, v237
	v_mul_f32_e32 v70, v70, v234
	v_mul_f32_e32 v71, v71, v235
	v_mul_f32_e32 v72, v72, v236
	v_mul_f32_e32 v73, v73, v237
	v_mul_f32_e32 v70, v70, v86
	v_mul_f32_e32 v71, v71, v87
	v_mul_f32_e32 v72, v72, v88
	v_mul_f32_e32 v73, v73, v89
	v_cvt_pk_f16_f32 v140, v70, v71
	v_cvt_pk_f16_f32 v141, v72, v73
	ds_write_b64 v130, v[140:141] offset:2576
	v_mul_f32_e32 v234, 0xbfb8aa3b, v74
	v_mul_f32_e32 v235, 0xbfb8aa3b, v75
	v_mul_f32_e32 v236, 0xbfb8aa3b, v76
	v_mul_f32_e32 v237, 0xbfb8aa3b, v77
	v_exp_f32_e32 v234, v234
	v_exp_f32_e32 v235, v235
	v_exp_f32_e32 v236, v236
	v_exp_f32_e32 v237, v237
	v_add_f32_e32 v234, 1.0, v234
	v_add_f32_e32 v235, 1.0, v235
	v_add_f32_e32 v236, 1.0, v236
	v_add_f32_e32 v237, 1.0, v237
	v_rcp_f32_e32 v234, v234
	v_rcp_f32_e32 v235, v235
	v_rcp_f32_e32 v236, v236
	v_rcp_f32_e32 v237, v237
	v_mul_f32_e32 v74, v74, v234
	v_mul_f32_e32 v75, v75, v235
	v_mul_f32_e32 v76, v76, v236
	v_mul_f32_e32 v77, v77, v237
	v_mul_f32_e32 v74, v74, v90
	v_mul_f32_e32 v75, v75, v91
	v_mul_f32_e32 v76, v76, v92
	v_mul_f32_e32 v77, v77, v93
	v_cvt_pk_f16_f32 v142, v74, v75
	v_cvt_pk_f16_f32 v143, v76, v77
	ds_write_b64 v130, v[142:143] offset:2592
	v_mul_f32_e32 v234, 0xbfb8aa3b, v78
	v_mul_f32_e32 v235, 0xbfb8aa3b, v79
	v_mul_f32_e32 v236, 0xbfb8aa3b, v80
	v_mul_f32_e32 v237, 0xbfb8aa3b, v81
	v_exp_f32_e32 v234, v234
	v_exp_f32_e32 v235, v235
	v_exp_f32_e32 v236, v236
	v_exp_f32_e32 v237, v237
	v_add_f32_e32 v234, 1.0, v234
	v_add_f32_e32 v235, 1.0, v235
	v_add_f32_e32 v236, 1.0, v236
	v_add_f32_e32 v237, 1.0, v237
	v_rcp_f32_e32 v234, v234
	v_rcp_f32_e32 v235, v235
	v_rcp_f32_e32 v236, v236
	v_rcp_f32_e32 v237, v237
	v_mul_f32_e32 v78, v78, v234
	v_mul_f32_e32 v79, v79, v235
	v_mul_f32_e32 v80, v80, v236
	v_mul_f32_e32 v81, v81, v237
	v_mul_f32_e32 v78, v78, v94
	v_mul_f32_e32 v79, v79, v95
	v_mul_f32_e32 v80, v80, v96
	v_mul_f32_e32 v81, v81, v97
	v_cvt_pk_f16_f32 v144, v78, v79
	v_cvt_pk_f16_f32 v145, v80, v81
	ds_write_b64 v130, v[144:145] offset:2608
	v_mul_f32_e32 v234, 0xbfb8aa3b, v34
	v_mul_f32_e32 v235, 0xbfb8aa3b, v35
	v_mul_f32_e32 v236, 0xbfb8aa3b, v36
	v_mul_f32_e32 v237, 0xbfb8aa3b, v37
	v_exp_f32_e32 v234, v234
	v_exp_f32_e32 v235, v235
	v_exp_f32_e32 v236, v236
	v_exp_f32_e32 v237, v237
	v_add_f32_e32 v234, 1.0, v234
	v_add_f32_e32 v235, 1.0, v235
	v_add_f32_e32 v236, 1.0, v236
	v_add_f32_e32 v237, 1.0, v237
	v_rcp_f32_e32 v234, v234
	v_rcp_f32_e32 v235, v235
	v_rcp_f32_e32 v236, v236
; DI float silu_(float x) { return x / (1.f + __expf(-x)); }
; template <class Epi>
; DI void gemm256_epilogue(f16v (&acc)[4][2], int m0, int n0, Epi epi) {
;     ...
;   for (int i = 0; i < 4; ++i) {
;     const int m = m0 + wm * 128 + i * 32 + (lane & 31);
; #pragma unroll
;     for (int g = 0; g < 4; ++g) {
;       const int n = n0 + wn * 64 + 8 * g + 4 * h;
;       f4v v0 = {acc[i][0][4 * g], acc[i][0][4 * g + 1], acc[i][0][4 * g + 2], acc[i][0][4 * g + 3]};
;       f4v v1 = {acc[i][1][4 * g], acc[i][1][4 * g + 1], acc[i][1][4 * g + 2], acc[i][1][4 * g + 3]};
;       epi(m, n, v0, v1);
; DI void phase_ffn1_moe(const Params& p, int bid, int nb, h16* lds) {
;     ...
;     gemm256_epilogue(acc, m0, n0, [&](int m, int n, f4v v0, f4v v1) {
;       f4v hq;
; #pragma unroll
;       for (int i = 0; i < 4; ++i) hq[i] = silu_(v0[i]) * v1[i];
;       st_h4(&H[(size_t)m * 1408 + (n >> 6) * 32 + (n & 31)], hq);
;     });
	v_rcp_f32_e32 v237, v237
	v_mul_f32_e32 v34, v34, v234
	v_mul_f32_e32 v35, v35, v235
	v_mul_f32_e32 v36, v36, v236
	v_mul_f32_e32 v37, v37, v237
	v_mul_f32_e32 v34, v34, v50
	v_mul_f32_e32 v35, v35, v51
	v_mul_f32_e32 v36, v36, v52
	v_mul_f32_e32 v37, v37, v53
	v_cvt_pk_f16_f32 v138, v34, v35
	v_cvt_pk_f16_f32 v139, v36, v37
	ds_write_b64 v130, v[138:139] offset:5120
	v_mul_f32_e32 v234, 0xbfb8aa3b, v38
	v_mul_f32_e32 v235, 0xbfb8aa3b, v39
	v_mul_f32_e32 v236, 0xbfb8aa3b, v40
	v_mul_f32_e32 v237, 0xbfb8aa3b, v41
	v_exp_f32_e32 v234, v234
	v_exp_f32_e32 v235, v235
	v_exp_f32_e32 v236, v236
	v_exp_f32_e32 v237, v237
	v_add_f32_e32 v234, 1.0, v234
	v_add_f32_e32 v235, 1.0, v235
	v_add_f32_e32 v236, 1.0, v236
	v_add_f32_e32 v237, 1.0, v237
	v_rcp_f32_e32 v234, v234
	v_rcp_f32_e32 v235, v235
	v_rcp_f32_e32 v236, v236
	v_rcp_f32_e32 v237, v237
	v_mul_f32_e32 v38, v38, v234
	v_mul_f32_e32 v39, v39, v235
	v_mul_f32_e32 v40, v40, v236
	v_mul_f32_e32 v41, v41, v237
	v_mul_f32_e32 v38, v38, v54
	v_mul_f32_e32 v39, v39, v55
	v_mul_f32_e32 v40, v40, v56
	v_mul_f32_e32 v41, v41, v57
	v_cvt_pk_f16_f32 v140, v38, v39
	v_cvt_pk_f16_f32 v141, v40, v41
	ds_write_b64 v130, v[140:141] offset:5136
	v_mul_f32_e32 v234, 0xbfb8aa3b, v42
	v_mul_f32_e32 v235, 0xbfb8aa3b, v43
	v_mul_f32_e32 v236, 0xbfb8aa3b, v44
	v_mul_f32_e32 v237, 0xbfb8aa3b, v45
	v_exp_f32_e32 v234, v234
	v_exp_f32_e32 v235, v235
	v_exp_f32_e32 v236, v236
	v_exp_f32_e32 v237, v237
	v_add_f32_e32 v234, 1.0, v234
	v_add_f32_e32 v235, 1.0, v235
	v_add_f32_e32 v236, 1.0, v236
	v_add_f32_e32 v237, 1.0, v237
	v_rcp_f32_e32 v234, v234
	v_rcp_f32_e32 v235, v235
	v_rcp_f32_e32 v236, v236
	v_rcp_f32_e32 v237, v237
	v_mul_f32_e32 v42, v42, v234
	v_mul_f32_e32 v43, v43, v235
	v_mul_f32_e32 v44, v44, v236
	v_mul_f32_e32 v45, v45, v237
	v_mul_f32_e32 v42, v42, v58
	v_mul_f32_e32 v43, v43, v59
	v_mul_f32_e32 v44, v44, v60
	v_mul_f32_e32 v45, v45, v61
	v_cvt_pk_f16_f32 v142, v42, v43
	v_cvt_pk_f16_f32 v143, v44, v45
	ds_write_b64 v130, v[142:143] offset:5152
	v_mul_f32_e32 v234, 0xbfb8aa3b, v46
	v_mul_f32_e32 v235, 0xbfb8aa3b, v47
	v_mul_f32_e32 v236, 0xbfb8aa3b, v48
	v_mul_f32_e32 v237, 0xbfb8aa3b, v49
	v_exp_f32_e32 v234, v234
	v_exp_f32_e32 v235, v235
	v_exp_f32_e32 v236, v236
	v_exp_f32_e32 v237, v237
	v_add_f32_e32 v234, 1.0, v234
	v_add_f32_e32 v235, 1.0, v235
	v_add_f32_e32 v236, 1.0, v236
	v_add_f32_e32 v237, 1.0, v237
	v_rcp_f32_e32 v234, v234
	v_rcp_f32_e32 v235, v235
	v_rcp_f32_e32 v236, v236
	v_rcp_f32_e32 v237, v237
	v_mul_f32_e32 v46, v46, v234
	v_mul_f32_e32 v47, v47, v235
	v_mul_f32_e32 v48, v48, v236
	v_mul_f32_e32 v49, v49, v237
	v_mul_f32_e32 v46, v46, v62
	v_mul_f32_e32 v47, v47, v63
	v_mul_f32_e32 v48, v48, v64
	v_mul_f32_e32 v49, v49, v65
	v_cvt_pk_f16_f32 v144, v46, v47
	v_cvt_pk_f16_f32 v145, v48, v49
	ds_write_b64 v130, v[144:145] offset:5168
	v_mul_f32_e32 v234, 0xbfb8aa3b, v2
	v_mul_f32_e32 v235, 0xbfb8aa3b, v3
	v_mul_f32_e32 v236, 0xbfb8aa3b, v4
	v_mul_f32_e32 v237, 0xbfb8aa3b, v5
	v_exp_f32_e32 v234, v234
	v_exp_f32_e32 v235, v235
	v_exp_f32_e32 v236, v236
	v_exp_f32_e32 v237, v237
	v_add_f32_e32 v234, 1.0, v234
	v_add_f32_e32 v235, 1.0, v235
	v_add_f32_e32 v236, 1.0, v236
	v_add_f32_e32 v237, 1.0, v237
	v_rcp_f32_e32 v234, v234
	v_rcp_f32_e32 v235, v235
	v_rcp_f32_e32 v236, v236
	v_rcp_f32_e32 v237, v237
	v_mul_f32_e32 v2, v2, v234
	v_mul_f32_e32 v3, v3, v235
	v_mul_f32_e32 v4, v4, v236
	v_mul_f32_e32 v5, v5, v237
	v_mul_f32_e32 v2, v2, v18
	v_mul_f32_e32 v3, v3, v19
	v_mul_f32_e32 v4, v4, v20
	v_mul_f32_e32 v5, v5, v21
	v_cvt_pk_f16_f32 v138, v2, v3
	v_cvt_pk_f16_f32 v139, v4, v5
	ds_write_b64 v130, v[138:139] offset:7680
	v_mul_f32_e32 v234, 0xbfb8aa3b, v6
	v_mul_f32_e32 v235, 0xbfb8aa3b, v7
	v_mul_f32_e32 v236, 0xbfb8aa3b, v8
	v_mul_f32_e32 v237, 0xbfb8aa3b, v9
	v_exp_f32_e32 v234, v234
	v_exp_f32_e32 v235, v235
	v_exp_f32_e32 v236, v236
	v_exp_f32_e32 v237, v237
	v_add_f32_e32 v234, 1.0, v234
	v_add_f32_e32 v235, 1.0, v235
	v_add_f32_e32 v236, 1.0, v236
	v_add_f32_e32 v237, 1.0, v237
	v_rcp_f32_e32 v234, v234
	v_rcp_f32_e32 v235, v235
	v_rcp_f32_e32 v236, v236
	v_rcp_f32_e32 v237, v237
	v_mul_f32_e32 v6, v6, v234
	v_mul_f32_e32 v7, v7, v235
	v_mul_f32_e32 v8, v8, v236
	v_mul_f32_e32 v9, v9, v237
	v_mul_f32_e32 v6, v6, v22
	v_mul_f32_e32 v7, v7, v23
	v_mul_f32_e32 v8, v8, v24
	v_mul_f32_e32 v9, v9, v25
	v_cvt_pk_f16_f32 v140, v6, v7
	v_cvt_pk_f16_f32 v141, v8, v9
	ds_write_b64 v130, v[140:141] offset:7696
	v_mul_f32_e32 v234, 0xbfb8aa3b, v10
	v_mul_f32_e32 v235, 0xbfb8aa3b, v11
	v_mul_f32_e32 v236, 0xbfb8aa3b, v12
	v_mul_f32_e32 v237, 0xbfb8aa3b, v13
	v_exp_f32_e32 v234, v234
	v_exp_f32_e32 v235, v235
	v_exp_f32_e32 v236, v236
	v_exp_f32_e32 v237, v237
	v_add_f32_e32 v234, 1.0, v234
	v_add_f32_e32 v235, 1.0, v235
	v_add_f32_e32 v236, 1.0, v236
	v_add_f32_e32 v237, 1.0, v237
	v_rcp_f32_e32 v234, v234
	v_rcp_f32_e32 v235, v235
	v_rcp_f32_e32 v236, v236
	v_rcp_f32_e32 v237, v237
	v_mul_f32_e32 v10, v10, v234
	v_mul_f32_e32 v11, v11, v235
	v_mul_f32_e32 v12, v12, v236
	v_mul_f32_e32 v13, v13, v237
	v_mul_f32_e32 v10, v10, v26
	v_mul_f32_e32 v11, v11, v27
	v_mul_f32_e32 v12, v12, v28
	v_mul_f32_e32 v13, v13, v29
	v_cvt_pk_f16_f32 v142, v10, v11
	v_cvt_pk_f16_f32 v143, v12, v13
	ds_write_b64 v130, v[142:143] offset:7712
	v_mul_f32_e32 v234, 0xbfb8aa3b, v14
	v_mul_f32_e32 v235, 0xbfb8aa3b, v15
	v_mul_f32_e32 v236, 0xbfb8aa3b, v16
	v_mul_f32_e32 v237, 0xbfb8aa3b, v17
	v_exp_f32_e32 v234, v234
	v_exp_f32_e32 v235, v235
	v_exp_f32_e32 v236, v236
	v_exp_f32_e32 v237, v237
	v_add_f32_e32 v234, 1.0, v234
	v_add_f32_e32 v235, 1.0, v235
	v_add_f32_e32 v236, 1.0, v236
	v_add_f32_e32 v237, 1.0, v237
	v_rcp_f32_e32 v234, v234
	v_rcp_f32_e32 v235, v235
	v_rcp_f32_e32 v236, v236
	v_rcp_f32_e32 v237, v237
	v_mul_f32_e32 v14, v14, v234
	v_mul_f32_e32 v15, v15, v235
	v_mul_f32_e32 v16, v16, v236
	v_mul_f32_e32 v17, v17, v237
	v_mul_f32_e32 v14, v14, v30
	v_mul_f32_e32 v15, v15, v31
	v_mul_f32_e32 v16, v16, v32
	v_mul_f32_e32 v17, v17, v33
	v_cvt_pk_f16_f32 v144, v14, v15
	v_cvt_pk_f16_f32 v145, v16, v17
	ds_write_b64 v130, v[144:145] offset:7728
	ds_read_b128 v[150:153], v131 offset:0
	ds_read_b128 v[154:157], v131 offset:1280
	ds_read_b128 v[158:161], v131 offset:2560
	ds_read_b128 v[162:165], v131 offset:3840
	ds_read_b128 v[218:221], v131 offset:5120
	ds_read_b128 v[222:225], v131 offset:6400
	ds_read_b128 v[226:229], v131 offset:7680
	ds_read_b128 v[230:233], v131 offset:8960
	s_waitcnt lgkmcnt(7)
; DI float silu_(float x) { return x / (1.f + __expf(-x)); }
; DI void phase_ffn1_moe(const Params& p, int bid, int nb, h16* lds) {
;     ...
;   for (int u = bid; u < ntl; u += nb) {
;     const int mt = u / 11, m0 = mt * 256, n0 = (u % 11) * 256;
;     int e = 0;
; #pragma unroll
;     for (int i = 1; i < 8; ++i) if (m0 >= ps[i]) e = i;
;     f16v acc[4][2]; acc256_zero(acc);
;     gemm256_main<true>(x16, DM, st, m0, w13 + (size_t)e * 2816 * 1024, 1024, n0, 1024, lds, acc);
;     gemm256_epilogue(acc, m0, n0, [&](int m, int n, f4v v0, f4v v1) {
;       f4v hq;
; #pragma unroll
;       for (int i = 0; i < 4; ++i) hq[i] = silu_(v0[i]) * v1[i];
;       st_h4(&H[(size_t)m * 1408 + (n >> 6) * 32 + (n & 31)], hq);
;     });
	global_store_dwordx4 v[132:133], v[150:153], off
	v_lshl_add_u64 v[132:133], v[132:133], 0, s[76:77]
	s_waitcnt lgkmcnt(6)
	global_store_dwordx4 v[132:133], v[154:157], off
	v_lshl_add_u64 v[132:133], v[132:133], 0, s[76:77]
	s_waitcnt lgkmcnt(5)
	global_store_dwordx4 v[132:133], v[158:161], off
	v_lshl_add_u64 v[132:133], v[132:133], 0, s[76:77]
	s_waitcnt lgkmcnt(4)
	global_store_dwordx4 v[132:133], v[162:165], off
	v_lshl_add_u64 v[132:133], v[132:133], 0, s[76:77]
	s_waitcnt lgkmcnt(3)
	global_store_dwordx4 v[132:133], v[218:221], off
	v_lshl_add_u64 v[132:133], v[132:133], 0, s[76:77]
	s_waitcnt lgkmcnt(2)
	global_store_dwordx4 v[132:133], v[222:225], off
	v_lshl_add_u64 v[132:133], v[132:133], 0, s[76:77]
	s_waitcnt lgkmcnt(1)
	global_store_dwordx4 v[132:133], v[226:229], off
	v_lshl_add_u64 v[132:133], v[132:133], 0, s[76:77]
	s_waitcnt lgkmcnt(0)
	global_store_dwordx4 v[132:133], v[230:233], off
	v_lshl_add_u64 v[132:133], v[132:133], 0, s[76:77]
	s_add_i32 s4, s4, s23
	v_cmp_lt_i32_e32 vcc, s5, v216
	s_nop 4
	s_cbranch_vccnz .LBB0_1520
	s_mov_b32 s56, 0xfffff80

; DI int otid512() { int t = threadIdx.x; asm volatile("" : "+v"(t)); return t; }
; template <bool GATHER>
; DI void gemm256_main(const h16* __restrict__ A, int lda, const int* __restrict__ idx, int m0,
;                      const h16* __restrict__ B, int ldb, int n0, int K, h16* lds, f16v (&acc)[4][2]) {
;   const int tid = otid512(), lane = tid & 63, wv = tid >> 6, wm = wv >> 2, wn = wv & 3;
;   const int lr = tid >> 1, lc = (tid & 1) * 32;
;   unsigned ao = (unsigned)(GATHER ? idx[m0 + lr] : (m0 + lr)) * (unsigned)lda + lc;
;   unsigned bo = (unsigned)(n0 + lr) * (unsigned)ldb + lc;
;   const h16* ap = A; const h16* bp = B;
;     ...
;   u4v ra[4], rb[4];
;   const int nk = K >> 6;
;   __syncthreads();
; #pragma unroll
;   for (int i = 0; i < 4; ++i) { ra[i] = *(const u4v*)(AP_ + 8 * i); rb[i] = *(const u4v*)(BP_ + 8 * i); }
;   ao += 64; bo += 64;
; #pragma unroll
;   for (int i = 0; i < 4; ++i) { *(u4v*)&lds[lr * LDH + lc + 8 * i] = ra[i]; *(u4v*)&lds[(256 + lr) * LDH + lc + 8 * i] = rb[i]; }
; #pragma unroll
;   for (int i = 0; i < 4; ++i) { ra[i] = *(const u4v*)(AP_ + 8 * i); rb[i] = *(const u4v*)(BP_ + 8 * i); }
;   ao += 64; bo += 64;
;   __syncthreads();
;   for (int kt = 0; kt < nk; ++kt) {
;     const h16* As = lds + (kt & 1) * (512 * LDH);
;     const h16* Bs = As + 256 * LDH;
;     h16* Wn = lds + ((kt & 1) ^ 1) * (512 * LDH);
;     if (kt + 1 < nk) {
; #pragma unroll
;       for (int i = 0; i < 4; ++i) { *(u4v*)&Wn[lr * LDH + lc + 8 * i] = ra[i]; *(u4v*)&Wn[(256 + lr) * LDH + lc + 8 * i] = rb[i]; }
;     }
;     if (kt + 2 < nk) {
; #pragma unroll
;       for (int i = 0; i < 4; ++i) { ra[i] = *(const u4v*)(AP_ + 8 * i); rb[i] = *(const u4v*)(BP_ + 8 * i); }
;       ao += 64; bo += 64;
;     }
; DI void phase_ffn1_dense(const Params& p, int bid, int nb, h16* lds) {
;     ...
;   for (int u = bid; u < 64 * 22; u += nb) {
;     const int m0 = (u / 22) * 256, n0 = (u % 22) * 256;
;     f16v acc[4][2]; acc256_zero(acc);
;     gemm256_main<false>(x16, DM, nullptr, m0, w13, 1024, n0, 1024, lds, acc);
.LBB0_1626:
	s_mul_hi_i32 s4, s3, 0x2e8ba2e9
	s_lshr_b32 s5, s4, 31
	s_ashr_i32 s4, s4, 2
	s_add_i32 s5, s4, s5
	v_mov_b32_e32 v1, v180
	s_lshl_b32 s4, s5, 8
	s_mulk_i32 s5, 0x1600
	v_ashrrev_i32_e32 v34, 1, v1
	v_lshlrev_b32_e32 v2, 5, v1
	v_subrev_u32_e32 v3, s5, v34
	v_and_b32_e32 v35, 32, v2
	v_add_u32_e32 v2, s4, v34
	v_add_u32_e32 v3, s2, v3
	v_lshl_or_b32 v2, v2, 10, v35
	v_lshl_or_b32 v176, v3, 10, v35
	v_mov_b32_e32 v3, v0
	v_mov_b32_e32 v177, v0
	v_lshl_add_u64 v[174:175], v[2:3], 1, s[20:21]
	v_lshl_add_u64 v[30:31], v[176:177], 1, s[8:9]
	s_barrier
	s_add_i32 s3, s3, s22
	v_mov_b32_e32 v130, v174
	v_mov_b32_e32 v131, v175
	v_mov_b32_e32 v248, v30
	v_mov_b32_e32 v249, v31
	v_lshrrev_b32_e32 v192, 1, v180
	v_and_b32_e32 v193, 1, v180
	v_mul_u32_u24_e32 v192, 0x90, v192
	v_lshl_add_u32 v178, v193, 6, v192
	v_add_u32_e32 v178, 16, v178
	v_add_u32_e32 v179, 0x12000, v178
	v_lshrrev_b32_e32 v192, 8, v180
	v_and_b32_e32 v194, 31, v180
	v_lshl_or_b32 v192, v192, 7, v194
	v_mul_u32_u24_e32 v192, 0x90, v192
	v_bfe_u32 v193, v180, 5, 1
	v_lshl_add_u32 v192, v193, 4, v192
	v_add_u32_e32 v215, 16, v192
	v_add_u32_e32 v212, 0x12000, v215
	v_bfe_u32 v192, v180, 6, 2
	v_lshl_or_b32 v192, v192, 6, v194
	v_mul_u32_u24_e32 v192, 0x90, v192
	v_lshl_add_u32 v192, v193, 4, v192
	v_add_u32_e32 v213, 0x9010, v192
	v_add_u32_e32 v214, 0x12000, v213
	global_load_dwordx4 v[134:137], v[130:131], off offset:0
	global_load_dwordx4 v[138:141], v[130:131], off offset:16
	global_load_dwordx4 v[142:145], v[130:131], off offset:32
	global_load_dwordx4 v[146:149], v[130:131], off offset:48
	global_load_dwordx4 v[150:153], v[248:249], off offset:0
	global_load_dwordx4 v[154:157], v[248:249], off offset:16
	global_load_dwordx4 v[158:161], v[248:249], off offset:32
	global_load_dwordx4 v[162:165], v[248:249], off offset:48
	s_waitcnt vmcnt(0)
	ds_write_b128 v178, v[134:137]
	ds_write_b128 v178, v[138:141] offset:16
	ds_write_b128 v178, v[142:145] offset:32
	ds_write_b128 v178, v[146:149] offset:48
	ds_write_b128 v178, v[150:153] offset:36864
	ds_write_b128 v178, v[154:157] offset:36880
	ds_write_b128 v178, v[158:161] offset:36896
	ds_write_b128 v178, v[162:165] offset:36912
	global_load_dwordx4 v[134:137], v[130:131], off offset:128
	global_load_dwordx4 v[138:141], v[130:131], off offset:144
	global_load_dwordx4 v[142:145], v[130:131], off offset:160
	global_load_dwordx4 v[146:149], v[130:131], off offset:176
	global_load_dwordx4 v[150:153], v[248:249], off offset:128
	global_load_dwordx4 v[154:157], v[248:249], off offset:144
	global_load_dwordx4 v[158:161], v[248:249], off offset:160
	global_load_dwordx4 v[162:165], v[248:249], off offset:176
	s_waitcnt lgkmcnt(0)
	s_barrier
	ds_read_b128 v[232:235], v213
	ds_read_b128 v[216:219], v215
	ds_read_b128 v[236:239], v213 offset:4608
	ds_read_b128 v[220:223], v215 offset:4608
	ds_read_b128 v[224:227], v215 offset:9216
	ds_read_b128 v[228:231], v215 offset:13824
	ds_read_b128 v[208:211], v213 offset:32
	ds_read_b128 v[240:243], v215 offset:32
	ds_read_b128 v[174:177], v213 offset:4640
	ds_read_b128 v[244:247], v215 offset:4640
	ds_read_b128 v[200:203], v215 offset:9248
	ds_read_b128 v[204:207], v215 offset:13856
	s_waitcnt vmcnt(4)
	ds_write_b128 v179, v[134:137]
	ds_write_b128 v179, v[138:141] offset:16
	ds_write_b128 v179, v[142:145] offset:32
	ds_write_b128 v179, v[146:149] offset:48
	global_load_dwordx4 v[134:137], v[130:131], off offset:256
	global_load_dwordx4 v[138:141], v[130:131], off offset:272
	global_load_dwordx4 v[142:145], v[130:131], off offset:288
	global_load_dwordx4 v[146:149], v[130:131], off offset:304
	s_waitcnt lgkmcnt(14)
	v_mfma_f32_32x32x16_f16 v[98:113], v[232:235], v[216:219], 0
	s_waitcnt lgkmcnt(13)
	v_mfma_f32_32x32x16_f16 v[114:129], v[236:239], v[216:219], 0
	s_waitcnt lgkmcnt(12)
	v_mfma_f32_32x32x16_f16 v[66:81], v[232:235], v[220:223], 0
	v_mfma_f32_32x32x16_f16 v[82:97], v[236:239], v[220:223], 0
	s_waitcnt lgkmcnt(11)
	v_mfma_f32_32x32x16_f16 v[34:49], v[232:235], v[224:227], 0
	v_mfma_f32_32x32x16_f16 v[50:65], v[236:239], v[224:227], 0
	s_waitcnt lgkmcnt(10)
	v_mfma_f32_32x32x16_f16 v[2:17], v[232:235], v[228:231], 0
	v_mfma_f32_32x32x16_f16 v[18:33], v[236:239], v[228:231], 0
	ds_read_b128 v[232:235], v213 offset:64
	ds_read_b128 v[216:219], v215 offset:64
	ds_read_b128 v[236:239], v213 offset:4672
	ds_read_b128 v[220:223], v215 offset:4672
	ds_read_b128 v[224:227], v215 offset:9280
	ds_read_b128 v[228:231], v215 offset:13888
	s_waitcnt vmcnt(4)
	ds_write_b128 v179, v[150:153] offset:36864
	ds_write_b128 v179, v[154:157] offset:36880
	ds_write_b128 v179, v[158:161] offset:36896
	ds_write_b128 v179, v[162:165] offset:36912
	global_load_dwordx4 v[150:153], v[248:249], off offset:256
	global_load_dwordx4 v[154:157], v[248:249], off offset:272
	global_load_dwordx4 v[158:161], v[248:249], off offset:288
	global_load_dwordx4 v[162:165], v[248:249], off offset:304
	s_waitcnt lgkmcnt(15)
	v_mfma_f32_32x32x16_f16 v[98:113], v[208:211], v[240:243], v[98:113]
	s_waitcnt lgkmcnt(15)
	v_mfma_f32_32x32x16_f16 v[114:129], v[174:177], v[240:243], v[114:129]
	s_waitcnt lgkmcnt(15)
	v_mfma_f32_32x32x16_f16 v[66:81], v[208:211], v[244:247], v[66:81]
	v_mfma_f32_32x32x16_f16 v[82:97], v[174:177], v[244:247], v[82:97]
	s_waitcnt lgkmcnt(15)
	v_mfma_f32_32x32x16_f16 v[34:49], v[208:211], v[200:203], v[34:49]
	v_mfma_f32_32x32x16_f16 v[50:65], v[174:177], v[200:203], v[50:65]
	s_waitcnt lgkmcnt(14)
	v_mfma_f32_32x32x16_f16 v[2:17], v[208:211], v[204:207], v[2:17]
	v_mfma_f32_32x32x16_f16 v[18:33], v[174:177], v[204:207], v[18:33]
	ds_read_b128 v[208:211], v213 offset:96
	ds_read_b128 v[240:243], v215 offset:96
	ds_read_b128 v[174:177], v213 offset:4704
	ds_read_b128 v[244:247], v215 offset:4704
	ds_read_b128 v[200:203], v215 offset:9312
	ds_read_b128 v[204:207], v215 offset:13920
	s_waitcnt lgkmcnt(14)
	v_mfma_f32_32x32x16_f16 v[98:113], v[232:235], v[216:219], v[98:113]
	s_waitcnt lgkmcnt(13)
	v_mfma_f32_32x32x16_f16 v[114:129], v[236:239], v[216:219], v[114:129]
	s_waitcnt lgkmcnt(12)
	v_mfma_f32_32x32x16_f16 v[66:81], v[232:235], v[220:223], v[66:81]
	v_mfma_f32_32x32x16_f16 v[82:97], v[236:239], v[220:223], v[82:97]
	s_waitcnt lgkmcnt(11)
	v_mfma_f32_32x32x16_f16 v[34:49], v[232:235], v[224:227], v[34:49]
	v_mfma_f32_32x32x16_f16 v[50:65], v[236:239], v[224:227], v[50:65]
	s_waitcnt lgkmcnt(10)
	v_mfma_f32_32x32x16_f16 v[2:17], v[232:235], v[228:231], v[2:17]
	v_mfma_f32_32x32x16_f16 v[18:33], v[236:239], v[228:231], v[18:33]
	s_waitcnt lgkmcnt(0)
	s_barrier
; DI f16v mfma32(h8v a, h8v b, f16v c) { return __builtin_amdgcn_mfma_f32_32x32x16_f16(a, b, c, 0, 0, 0); }
; template <bool GATHER>
; DI void gemm256_main(const h16* __restrict__ A, int lda, const int* __restrict__ idx, int m0,
;                      const h16* __restrict__ B, int ldb, int n0, int K, h16* lds, f16v (&acc)[4][2]) {
;     ...
;   for (int kt = 0; kt < nk; ++kt) {
;     const h16* As = lds + (kt & 1) * (512 * LDH);
;     const h16* Bs = As + 256 * LDH;
;     h16* Wn = lds + ((kt & 1) ^ 1) * (512 * LDH);
;     if (kt + 1 < nk) {
; #pragma unroll
;       for (int i = 0; i < 4; ++i) { *(u4v*)&Wn[lr * LDH + lc + 8 * i] = ra[i]; *(u4v*)&Wn[(256 + lr) * LDH + lc + 8 * i] = rb[i]; }
;     }
;     if (kt + 2 < nk) {
; #pragma unroll
;       for (int i = 0; i < 4; ++i) { ra[i] = *(const u4v*)(AP_ + 8 * i); rb[i] = *(const u4v*)(BP_ + 8 * i); }
;       ao += 64; bo += 64;
;     }
; #pragma unroll
;     for (int ks = 0; ks < 4; ++ks) {
;       h8v af[4], bf[2];
; #pragma unroll
;       for (int i = 0; i < 4; ++i) af[i] = *(const h8v*)&As[(wm * 128 + i * 32 + (lane & 31)) * LDH + ks * 16 + 8 * (lane >> 5)];
; #pragma unroll
;       for (int j = 0; j < 2; ++j) bf[j] = *(const h8v*)&Bs[(wn * 64 + j * 32 + (lane & 31)) * LDH + ks * 16 + 8 * (lane >> 5)];
; #pragma unroll
;       for (int i = 0; i < 4; ++i)
; #pragma unroll
;         for (int j = 0; j < 2; ++j) acc[i][j] = mfma32(bf[j], af[i], acc[i][j]);
;     }
;     __syncthreads();
;   }
	ds_read_b128 v[232:235], v214
	ds_read_b128 v[216:219], v212
	ds_read_b128 v[236:239], v214 offset:4608
	ds_read_b128 v[220:223], v212 offset:4608
	ds_read_b128 v[224:227], v212 offset:9216
	ds_read_b128 v[228:231], v212 offset:13824
	v_mfma_f32_32x32x16_f16 v[98:113], v[208:211], v[240:243], v[98:113]
	v_mfma_f32_32x32x16_f16 v[114:129], v[174:177], v[240:243], v[114:129]
	v_mfma_f32_32x32x16_f16 v[66:81], v[208:211], v[244:247], v[66:81]
	v_mfma_f32_32x32x16_f16 v[82:97], v[174:177], v[244:247], v[82:97]
	v_mfma_f32_32x32x16_f16 v[34:49], v[208:211], v[200:203], v[34:49]
	v_mfma_f32_32x32x16_f16 v[50:65], v[174:177], v[200:203], v[50:65]
	v_mfma_f32_32x32x16_f16 v[2:17], v[208:211], v[204:207], v[2:17]
	v_mfma_f32_32x32x16_f16 v[18:33], v[174:177], v[204:207], v[18:33]
	ds_read_b128 v[208:211], v214 offset:32
	ds_read_b128 v[240:243], v212 offset:32
	ds_read_b128 v[174:177], v214 offset:4640
	ds_read_b128 v[244:247], v212 offset:4640
	ds_read_b128 v[200:203], v212 offset:9248
	ds_read_b128 v[204:207], v212 offset:13856
	s_waitcnt vmcnt(4)
	ds_write_b128 v178, v[134:137]
	ds_write_b128 v178, v[138:141] offset:16
	ds_write_b128 v178, v[142:145] offset:32
	ds_write_b128 v178, v[146:149] offset:48
	global_load_dwordx4 v[134:137], v[130:131], off offset:384
	global_load_dwordx4 v[138:141], v[130:131], off offset:400
	global_load_dwordx4 v[142:145], v[130:131], off offset:416
	global_load_dwordx4 v[146:149], v[130:131], off offset:432
	s_waitcnt lgkmcnt(14)
	v_mfma_f32_32x32x16_f16 v[98:113], v[232:235], v[216:219], v[98:113]
	s_waitcnt lgkmcnt(13)
	v_mfma_f32_32x32x16_f16 v[114:129], v[236:239], v[216:219], v[114:129]
	s_waitcnt lgkmcnt(12)
	v_mfma_f32_32x32x16_f16 v[66:81], v[232:235], v[220:223], v[66:81]
	v_mfma_f32_32x32x16_f16 v[82:97], v[236:239], v[220:223], v[82:97]
	s_waitcnt lgkmcnt(11)
	v_mfma_f32_32x32x16_f16 v[34:49], v[232:235], v[224:227], v[34:49]
	v_mfma_f32_32x32x16_f16 v[50:65], v[236:239], v[224:227], v[50:65]
	s_waitcnt lgkmcnt(10)
	v_mfma_f32_32x32x16_f16 v[2:17], v[232:235], v[228:231], v[2:17]
	v_mfma_f32_32x32x16_f16 v[18:33], v[236:239], v[228:231], v[18:33]
	ds_read_b128 v[232:235], v214 offset:64
	ds_read_b128 v[216:219], v212 offset:64
	ds_read_b128 v[236:239], v214 offset:4672
	ds_read_b128 v[220:223], v212 offset:4672
	ds_read_b128 v[224:227], v212 offset:9280
	ds_read_b128 v[228:231], v212 offset:13888
	s_waitcnt vmcnt(4)
	ds_write_b128 v178, v[150:153] offset:36864
	ds_write_b128 v178, v[154:157] offset:36880
	ds_write_b128 v178, v[158:161] offset:36896
	ds_write_b128 v178, v[162:165] offset:36912
	global_load_dwordx4 v[150:153], v[248:249], off offset:384
	global_load_dwordx4 v[154:157], v[248:249], off offset:400
	global_load_dwordx4 v[158:161], v[248:249], off offset:416
	global_load_dwordx4 v[162:165], v[248:249], off offset:432
	s_waitcnt lgkmcnt(15)
	v_mfma_f32_32x32x16_f16 v[98:113], v[208:211], v[240:243], v[98:113]
	s_waitcnt lgkmcnt(15)
	v_mfma_f32_32x32x16_f16 v[114:129], v[174:177], v[240:243], v[114:129]
	s_waitcnt lgkmcnt(15)
	v_mfma_f32_32x32x16_f16 v[66:81], v[208:211], v[244:247], v[66:81]
	v_mfma_f32_32x32x16_f16 v[82:97], v[174:177], v[244:247], v[82:97]
	s_waitcnt lgkmcnt(15)
	v_mfma_f32_32x32x16_f16 v[34:49], v[208:211], v[200:203], v[34:49]
	v_mfma_f32_32x32x16_f16 v[50:65], v[174:177], v[200:203], v[50:65]
	s_waitcnt lgkmcnt(14)
	v_mfma_f32_32x32x16_f16 v[2:17], v[208:211], v[204:207], v[2:17]
	v_mfma_f32_32x32x16_f16 v[18:33], v[174:177], v[204:207], v[18:33]
	ds_read_b128 v[208:211], v214 offset:96
	ds_read_b128 v[240:243], v212 offset:96
	ds_read_b128 v[174:177], v214 offset:4704
	ds_read_b128 v[244:247], v212 offset:4704
	ds_read_b128 v[200:203], v212 offset:9312
	ds_read_b128 v[204:207], v212 offset:13920
	s_waitcnt lgkmcnt(14)
	v_mfma_f32_32x32x16_f16 v[98:113], v[232:235], v[216:219], v[98:113]
	s_waitcnt lgkmcnt(13)
	v_mfma_f32_32x32x16_f16 v[114:129], v[236:239], v[216:219], v[114:129]
	s_waitcnt lgkmcnt(12)
	v_mfma_f32_32x32x16_f16 v[66:81], v[232:235], v[220:223], v[66:81]
	v_mfma_f32_32x32x16_f16 v[82:97], v[236:239], v[220:223], v[82:97]
	s_waitcnt lgkmcnt(11)
	v_mfma_f32_32x32x16_f16 v[34:49], v[232:235], v[224:227], v[34:49]
	v_mfma_f32_32x32x16_f16 v[50:65], v[236:239], v[224:227], v[50:65]
	s_waitcnt lgkmcnt(10)
	v_mfma_f32_32x32x16_f16 v[2:17], v[232:235], v[228:231], v[2:17]
	v_mfma_f32_32x32x16_f16 v[18:33], v[236:239], v[228:231], v[18:33]
	s_waitcnt lgkmcnt(0)
	s_barrier
; DI f16v mfma32(h8v a, h8v b, f16v c) { return __builtin_amdgcn_mfma_f32_32x32x16_f16(a, b, c, 0, 0, 0); }
; template <bool GATHER>
; DI void gemm256_main(const h16* __restrict__ A, int lda, const int* __restrict__ idx, int m0,
;                      const h16* __restrict__ B, int ldb, int n0, int K, h16* lds, f16v (&acc)[4][2]) {
;     ...
;   for (int kt = 0; kt < nk; ++kt) {
;     const h16* As = lds + (kt & 1) * (512 * LDH);
;     const h16* Bs = As + 256 * LDH;
;     h16* Wn = lds + ((kt & 1) ^ 1) * (512 * LDH);
;     if (kt + 1 < nk) {
; #pragma unroll
;       for (int i = 0; i < 4; ++i) { *(u4v*)&Wn[lr * LDH + lc + 8 * i] = ra[i]; *(u4v*)&Wn[(256 + lr) * LDH + lc + 8 * i] = rb[i]; }
;     }
;     if (kt + 2 < nk) {
; #pragma unroll
;       for (int i = 0; i < 4; ++i) { ra[i] = *(const u4v*)(AP_ + 8 * i); rb[i] = *(const u4v*)(BP_ + 8 * i); }
;       ao += 64; bo += 64;
;     }
; #pragma unroll
;     for (int ks = 0; ks < 4; ++ks) {
;       h8v af[4], bf[2];
; #pragma unroll
;       for (int i = 0; i < 4; ++i) af[i] = *(const h8v*)&As[(wm * 128 + i * 32 + (lane & 31)) * LDH + ks * 16 + 8 * (lane >> 5)];
; #pragma unroll
;       for (int j = 0; j < 2; ++j) bf[j] = *(const h8v*)&Bs[(wn * 64 + j * 32 + (lane & 31)) * LDH + ks * 16 + 8 * (lane >> 5)];
; #pragma unroll
;       for (int i = 0; i < 4; ++i)
; #pragma unroll
;         for (int j = 0; j < 2; ++j) acc[i][j] = mfma32(bf[j], af[i], acc[i][j]);
;     }
;     __syncthreads();
;   }
	ds_read_b128 v[232:235], v213
	ds_read_b128 v[216:219], v215
	ds_read_b128 v[236:239], v213 offset:4608
	ds_read_b128 v[220:223], v215 offset:4608
	ds_read_b128 v[224:227], v215 offset:9216
	ds_read_b128 v[228:231], v215 offset:13824
	v_mfma_f32_32x32x16_f16 v[98:113], v[208:211], v[240:243], v[98:113]
	v_mfma_f32_32x32x16_f16 v[114:129], v[174:177], v[240:243], v[114:129]
	v_mfma_f32_32x32x16_f16 v[66:81], v[208:211], v[244:247], v[66:81]
	v_mfma_f32_32x32x16_f16 v[82:97], v[174:177], v[244:247], v[82:97]
	v_mfma_f32_32x32x16_f16 v[34:49], v[208:211], v[200:203], v[34:49]
	v_mfma_f32_32x32x16_f16 v[50:65], v[174:177], v[200:203], v[50:65]
	v_mfma_f32_32x32x16_f16 v[2:17], v[208:211], v[204:207], v[2:17]
	v_mfma_f32_32x32x16_f16 v[18:33], v[174:177], v[204:207], v[18:33]
	ds_read_b128 v[208:211], v213 offset:32
	ds_read_b128 v[240:243], v215 offset:32
	ds_read_b128 v[174:177], v213 offset:4640
	ds_read_b128 v[244:247], v215 offset:4640
	ds_read_b128 v[200:203], v215 offset:9248
	ds_read_b128 v[204:207], v215 offset:13856
	s_waitcnt vmcnt(4)
	ds_write_b128 v179, v[134:137]
	ds_write_b128 v179, v[138:141] offset:16
	ds_write_b128 v179, v[142:145] offset:32
	ds_write_b128 v179, v[146:149] offset:48
	global_load_dwordx4 v[134:137], v[130:131], off offset:512
	global_load_dwordx4 v[138:141], v[130:131], off offset:528
	global_load_dwordx4 v[142:145], v[130:131], off offset:544
	global_load_dwordx4 v[146:149], v[130:131], off offset:560
	s_waitcnt lgkmcnt(14)
	v_mfma_f32_32x32x16_f16 v[98:113], v[232:235], v[216:219], v[98:113]
	s_waitcnt lgkmcnt(13)
	v_mfma_f32_32x32x16_f16 v[114:129], v[236:239], v[216:219], v[114:129]
	s_waitcnt lgkmcnt(12)
	v_mfma_f32_32x32x16_f16 v[66:81], v[232:235], v[220:223], v[66:81]
	v_mfma_f32_32x32x16_f16 v[82:97], v[236:239], v[220:223], v[82:97]
	s_waitcnt lgkmcnt(11)
	v_mfma_f32_32x32x16_f16 v[34:49], v[232:235], v[224:227], v[34:49]
	v_mfma_f32_32x32x16_f16 v[50:65], v[236:239], v[224:227], v[50:65]
	s_waitcnt lgkmcnt(10)
	v_mfma_f32_32x32x16_f16 v[2:17], v[232:235], v[228:231], v[2:17]
	v_mfma_f32_32x32x16_f16 v[18:33], v[236:239], v[228:231], v[18:33]
	ds_read_b128 v[232:235], v213 offset:64
	ds_read_b128 v[216:219], v215 offset:64
	ds_read_b128 v[236:239], v213 offset:4672
	ds_read_b128 v[220:223], v215 offset:4672
	ds_read_b128 v[224:227], v215 offset:9280
	ds_read_b128 v[228:231], v215 offset:13888
	s_waitcnt vmcnt(4)
	ds_write_b128 v179, v[150:153] offset:36864
	ds_write_b128 v179, v[154:157] offset:36880
	ds_write_b128 v179, v[158:161] offset:36896
	ds_write_b128 v179, v[162:165] offset:36912
	global_load_dwordx4 v[150:153], v[248:249], off offset:512
	global_load_dwordx4 v[154:157], v[248:249], off offset:528
	global_load_dwordx4 v[158:161], v[248:249], off offset:544
	global_load_dwordx4 v[162:165], v[248:249], off offset:560
	s_waitcnt lgkmcnt(15)
	v_mfma_f32_32x32x16_f16 v[98:113], v[208:211], v[240:243], v[98:113]
	s_waitcnt lgkmcnt(15)
	v_mfma_f32_32x32x16_f16 v[114:129], v[174:177], v[240:243], v[114:129]
	s_waitcnt lgkmcnt(15)
	v_mfma_f32_32x32x16_f16 v[66:81], v[208:211], v[244:247], v[66:81]
	v_mfma_f32_32x32x16_f16 v[82:97], v[174:177], v[244:247], v[82:97]
	s_waitcnt lgkmcnt(15)
	v_mfma_f32_32x32x16_f16 v[34:49], v[208:211], v[200:203], v[34:49]
	v_mfma_f32_32x32x16_f16 v[50:65], v[174:177], v[200:203], v[50:65]
	s_waitcnt lgkmcnt(14)
	v_mfma_f32_32x32x16_f16 v[2:17], v[208:211], v[204:207], v[2:17]
	v_mfma_f32_32x32x16_f16 v[18:33], v[174:177], v[204:207], v[18:33]
	ds_read_b128 v[208:211], v213 offset:96
	ds_read_b128 v[240:243], v215 offset:96
	ds_read_b128 v[174:177], v213 offset:4704
	ds_read_b128 v[244:247], v215 offset:4704
	ds_read_b128 v[200:203], v215 offset:9312
	ds_read_b128 v[204:207], v215 offset:13920
	s_waitcnt lgkmcnt(14)
	v_mfma_f32_32x32x16_f16 v[98:113], v[232:235], v[216:219], v[98:113]
	s_waitcnt lgkmcnt(13)
	v_mfma_f32_32x32x16_f16 v[114:129], v[236:239], v[216:219], v[114:129]
	s_waitcnt lgkmcnt(12)
	v_mfma_f32_32x32x16_f16 v[66:81], v[232:235], v[220:223], v[66:81]
	v_mfma_f32_32x32x16_f16 v[82:97], v[236:239], v[220:223], v[82:97]
	s_waitcnt lgkmcnt(11)
	v_mfma_f32_32x32x16_f16 v[34:49], v[232:235], v[224:227], v[34:49]
	v_mfma_f32_32x32x16_f16 v[50:65], v[236:239], v[224:227], v[50:65]
	s_waitcnt lgkmcnt(10)
	v_mfma_f32_32x32x16_f16 v[2:17], v[232:235], v[228:231], v[2:17]
	v_mfma_f32_32x32x16_f16 v[18:33], v[236:239], v[228:231], v[18:33]
	s_waitcnt lgkmcnt(0)
	s_barrier
; DI f16v mfma32(h8v a, h8v b, f16v c) { return __builtin_amdgcn_mfma_f32_32x32x16_f16(a, b, c, 0, 0, 0); }
; template <bool GATHER>
; DI void gemm256_main(const h16* __restrict__ A, int lda, const int* __restrict__ idx, int m0,
;                      const h16* __restrict__ B, int ldb, int n0, int K, h16* lds, f16v (&acc)[4][2]) {
;     ...
;   for (int kt = 0; kt < nk; ++kt) {
;     const h16* As = lds + (kt & 1) * (512 * LDH);
;     const h16* Bs = As + 256 * LDH;
;     h16* Wn = lds + ((kt & 1) ^ 1) * (512 * LDH);
;     if (kt + 1 < nk) {
; #pragma unroll
;       for (int i = 0; i < 4; ++i) { *(u4v*)&Wn[lr * LDH + lc + 8 * i] = ra[i]; *(u4v*)&Wn[(256 + lr) * LDH + lc + 8 * i] = rb[i]; }
;     }
;     if (kt + 2 < nk) {
; #pragma unroll
;       for (int i = 0; i < 4; ++i) { ra[i] = *(const u4v*)(AP_ + 8 * i); rb[i] = *(const u4v*)(BP_ + 8 * i); }
;       ao += 64; bo += 64;
;     }
; #pragma unroll
;     for (int ks = 0; ks < 4; ++ks) {
;       h8v af[4], bf[2];
; #pragma unroll
;       for (int i = 0; i < 4; ++i) af[i] = *(const h8v*)&As[(wm * 128 + i * 32 + (lane & 31)) * LDH + ks * 16 + 8 * (lane >> 5)];
; #pragma unroll
;       for (int j = 0; j < 2; ++j) bf[j] = *(const h8v*)&Bs[(wn * 64 + j * 32 + (lane & 31)) * LDH + ks * 16 + 8 * (lane >> 5)];
; #pragma unroll
;       for (int i = 0; i < 4; ++i)
; #pragma unroll
;         for (int j = 0; j < 2; ++j) acc[i][j] = mfma32(bf[j], af[i], acc[i][j]);
;     }
;     __syncthreads();
;   }
	ds_read_b128 v[232:235], v214
	ds_read_b128 v[216:219], v212
	ds_read_b128 v[236:239], v214 offset:4608
	ds_read_b128 v[220:223], v212 offset:4608
	ds_read_b128 v[224:227], v212 offset:9216
	ds_read_b128 v[228:231], v212 offset:13824
	v_mfma_f32_32x32x16_f16 v[98:113], v[208:211], v[240:243], v[98:113]
	v_mfma_f32_32x32x16_f16 v[114:129], v[174:177], v[240:243], v[114:129]
	v_mfma_f32_32x32x16_f16 v[66:81], v[208:211], v[244:247], v[66:81]
	v_mfma_f32_32x32x16_f16 v[82:97], v[174:177], v[244:247], v[82:97]
	v_mfma_f32_32x32x16_f16 v[34:49], v[208:211], v[200:203], v[34:49]
	v_mfma_f32_32x32x16_f16 v[50:65], v[174:177], v[200:203], v[50:65]
	v_mfma_f32_32x32x16_f16 v[2:17], v[208:211], v[204:207], v[2:17]
	v_mfma_f32_32x32x16_f16 v[18:33], v[174:177], v[204:207], v[18:33]
	ds_read_b128 v[208:211], v214 offset:32
	ds_read_b128 v[240:243], v212 offset:32
	ds_read_b128 v[174:177], v214 offset:4640
	ds_read_b128 v[244:247], v212 offset:4640
	ds_read_b128 v[200:203], v212 offset:9248
	ds_read_b128 v[204:207], v212 offset:13856
	s_waitcnt vmcnt(4)
	ds_write_b128 v178, v[134:137]
	ds_write_b128 v178, v[138:141] offset:16
	ds_write_b128 v178, v[142:145] offset:32
	ds_write_b128 v178, v[146:149] offset:48
	global_load_dwordx4 v[134:137], v[130:131], off offset:640
	global_load_dwordx4 v[138:141], v[130:131], off offset:656
	global_load_dwordx4 v[142:145], v[130:131], off offset:672
	global_load_dwordx4 v[146:149], v[130:131], off offset:688
	s_waitcnt lgkmcnt(14)
	v_mfma_f32_32x32x16_f16 v[98:113], v[232:235], v[216:219], v[98:113]
	s_waitcnt lgkmcnt(13)
	v_mfma_f32_32x32x16_f16 v[114:129], v[236:239], v[216:219], v[114:129]
	s_waitcnt lgkmcnt(12)
	v_mfma_f32_32x32x16_f16 v[66:81], v[232:235], v[220:223], v[66:81]
	v_mfma_f32_32x32x16_f16 v[82:97], v[236:239], v[220:223], v[82:97]
	s_waitcnt lgkmcnt(11)
	v_mfma_f32_32x32x16_f16 v[34:49], v[232:235], v[224:227], v[34:49]
	v_mfma_f32_32x32x16_f16 v[50:65], v[236:239], v[224:227], v[50:65]
	s_waitcnt lgkmcnt(10)
	v_mfma_f32_32x32x16_f16 v[2:17], v[232:235], v[228:231], v[2:17]
	v_mfma_f32_32x32x16_f16 v[18:33], v[236:239], v[228:231], v[18:33]
	ds_read_b128 v[232:235], v214 offset:64
	ds_read_b128 v[216:219], v212 offset:64
	ds_read_b128 v[236:239], v214 offset:4672
	ds_read_b128 v[220:223], v212 offset:4672
	ds_read_b128 v[224:227], v212 offset:9280
	ds_read_b128 v[228:231], v212 offset:13888
	s_waitcnt vmcnt(4)
	ds_write_b128 v178, v[150:153] offset:36864
	ds_write_b128 v178, v[154:157] offset:36880
	ds_write_b128 v178, v[158:161] offset:36896
	ds_write_b128 v178, v[162:165] offset:36912
	global_load_dwordx4 v[150:153], v[248:249], off offset:640
	global_load_dwordx4 v[154:157], v[248:249], off offset:656
	global_load_dwordx4 v[158:161], v[248:249], off offset:672
	global_load_dwordx4 v[162:165], v[248:249], off offset:688
	s_waitcnt lgkmcnt(15)
	v_mfma_f32_32x32x16_f16 v[98:113], v[208:211], v[240:243], v[98:113]
	s_waitcnt lgkmcnt(15)
	v_mfma_f32_32x32x16_f16 v[114:129], v[174:177], v[240:243], v[114:129]
	s_waitcnt lgkmcnt(15)
	v_mfma_f32_32x32x16_f16 v[66:81], v[208:211], v[244:247], v[66:81]
	v_mfma_f32_32x32x16_f16 v[82:97], v[174:177], v[244:247], v[82:97]
	s_waitcnt lgkmcnt(15)
	v_mfma_f32_32x32x16_f16 v[34:49], v[208:211], v[200:203], v[34:49]
	v_mfma_f32_32x32x16_f16 v[50:65], v[174:177], v[200:203], v[50:65]
	s_waitcnt lgkmcnt(14)
	v_mfma_f32_32x32x16_f16 v[2:17], v[208:211], v[204:207], v[2:17]
	v_mfma_f32_32x32x16_f16 v[18:33], v[174:177], v[204:207], v[18:33]
	ds_read_b128 v[208:211], v214 offset:96
	ds_read_b128 v[240:243], v212 offset:96
	ds_read_b128 v[174:177], v214 offset:4704
	ds_read_b128 v[244:247], v212 offset:4704
	ds_read_b128 v[200:203], v212 offset:9312
	ds_read_b128 v[204:207], v212 offset:13920
	s_waitcnt lgkmcnt(14)
	v_mfma_f32_32x32x16_f16 v[98:113], v[232:235], v[216:219], v[98:113]
	s_waitcnt lgkmcnt(13)
	v_mfma_f32_32x32x16_f16 v[114:129], v[236:239], v[216:219], v[114:129]
	s_waitcnt lgkmcnt(12)
	v_mfma_f32_32x32x16_f16 v[66:81], v[232:235], v[220:223], v[66:81]
	v_mfma_f32_32x32x16_f16 v[82:97], v[236:239], v[220:223], v[82:97]
	s_waitcnt lgkmcnt(11)
	v_mfma_f32_32x32x16_f16 v[34:49], v[232:235], v[224:227], v[34:49]
	v_mfma_f32_32x32x16_f16 v[50:65], v[236:239], v[224:227], v[50:65]
	s_waitcnt lgkmcnt(10)
	v_mfma_f32_32x32x16_f16 v[2:17], v[232:235], v[228:231], v[2:17]
	v_mfma_f32_32x32x16_f16 v[18:33], v[236:239], v[228:231], v[18:33]
	s_waitcnt lgkmcnt(0)
	s_barrier
; DI f16v mfma32(h8v a, h8v b, f16v c) { return __builtin_amdgcn_mfma_f32_32x32x16_f16(a, b, c, 0, 0, 0); }
; template <bool GATHER>
; DI void gemm256_main(const h16* __restrict__ A, int lda, const int* __restrict__ idx, int m0,
;                      const h16* __restrict__ B, int ldb, int n0, int K, h16* lds, f16v (&acc)[4][2]) {
;     ...
;   for (int kt = 0; kt < nk; ++kt) {
;     const h16* As = lds + (kt & 1) * (512 * LDH);
;     const h16* Bs = As + 256 * LDH;
;     h16* Wn = lds + ((kt & 1) ^ 1) * (512 * LDH);
;     if (kt + 1 < nk) {
; #pragma unroll
;       for (int i = 0; i < 4; ++i) { *(u4v*)&Wn[lr * LDH + lc + 8 * i] = ra[i]; *(u4v*)&Wn[(256 + lr) * LDH + lc + 8 * i] = rb[i]; }
;     }
;     if (kt + 2 < nk) {
; #pragma unroll
;       for (int i = 0; i < 4; ++i) { ra[i] = *(const u4v*)(AP_ + 8 * i); rb[i] = *(const u4v*)(BP_ + 8 * i); }
;       ao += 64; bo += 64;
;     }
; #pragma unroll
;     for (int ks = 0; ks < 4; ++ks) {
;       h8v af[4], bf[2];
; #pragma unroll
;       for (int i = 0; i < 4; ++i) af[i] = *(const h8v*)&As[(wm * 128 + i * 32 + (lane & 31)) * LDH + ks * 16 + 8 * (lane >> 5)];
; #pragma unroll
;       for (int j = 0; j < 2; ++j) bf[j] = *(const h8v*)&Bs[(wn * 64 + j * 32 + (lane & 31)) * LDH + ks * 16 + 8 * (lane >> 5)];
; #pragma unroll
;       for (int i = 0; i < 4; ++i)
; #pragma unroll
;         for (int j = 0; j < 2; ++j) acc[i][j] = mfma32(bf[j], af[i], acc[i][j]);
;     }
;     __syncthreads();
;   }
	ds_read_b128 v[232:235], v213
	ds_read_b128 v[216:219], v215
	ds_read_b128 v[236:239], v213 offset:4608
	ds_read_b128 v[220:223], v215 offset:4608
	ds_read_b128 v[224:227], v215 offset:9216
	ds_read_b128 v[228:231], v215 offset:13824
	v_mfma_f32_32x32x16_f16 v[98:113], v[208:211], v[240:243], v[98:113]
	v_mfma_f32_32x32x16_f16 v[114:129], v[174:177], v[240:243], v[114:129]
	v_mfma_f32_32x32x16_f16 v[66:81], v[208:211], v[244:247], v[66:81]
	v_mfma_f32_32x32x16_f16 v[82:97], v[174:177], v[244:247], v[82:97]
	v_mfma_f32_32x32x16_f16 v[34:49], v[208:211], v[200:203], v[34:49]
	v_mfma_f32_32x32x16_f16 v[50:65], v[174:177], v[200:203], v[50:65]
	v_mfma_f32_32x32x16_f16 v[2:17], v[208:211], v[204:207], v[2:17]
	v_mfma_f32_32x32x16_f16 v[18:33], v[174:177], v[204:207], v[18:33]
	ds_read_b128 v[208:211], v213 offset:32
	ds_read_b128 v[240:243], v215 offset:32
	ds_read_b128 v[174:177], v213 offset:4640
	ds_read_b128 v[244:247], v215 offset:4640
	ds_read_b128 v[200:203], v215 offset:9248
	ds_read_b128 v[204:207], v215 offset:13856
	s_waitcnt vmcnt(4)
	ds_write_b128 v179, v[134:137]
	ds_write_b128 v179, v[138:141] offset:16
	ds_write_b128 v179, v[142:145] offset:32
	ds_write_b128 v179, v[146:149] offset:48
	global_load_dwordx4 v[134:137], v[130:131], off offset:768
	global_load_dwordx4 v[138:141], v[130:131], off offset:784
	global_load_dwordx4 v[142:145], v[130:131], off offset:800
	global_load_dwordx4 v[146:149], v[130:131], off offset:816
	s_waitcnt lgkmcnt(14)
	v_mfma_f32_32x32x16_f16 v[98:113], v[232:235], v[216:219], v[98:113]
	s_waitcnt lgkmcnt(13)
	v_mfma_f32_32x32x16_f16 v[114:129], v[236:239], v[216:219], v[114:129]
	s_waitcnt lgkmcnt(12)
	v_mfma_f32_32x32x16_f16 v[66:81], v[232:235], v[220:223], v[66:81]
	v_mfma_f32_32x32x16_f16 v[82:97], v[236:239], v[220:223], v[82:97]
	s_waitcnt lgkmcnt(11)
	v_mfma_f32_32x32x16_f16 v[34:49], v[232:235], v[224:227], v[34:49]
	v_mfma_f32_32x32x16_f16 v[50:65], v[236:239], v[224:227], v[50:65]
	s_waitcnt lgkmcnt(10)
	v_mfma_f32_32x32x16_f16 v[2:17], v[232:235], v[228:231], v[2:17]
	v_mfma_f32_32x32x16_f16 v[18:33], v[236:239], v[228:231], v[18:33]
	ds_read_b128 v[232:235], v213 offset:64
	ds_read_b128 v[216:219], v215 offset:64
	ds_read_b128 v[236:239], v213 offset:4672
	ds_read_b128 v[220:223], v215 offset:4672
	ds_read_b128 v[224:227], v215 offset:9280
	ds_read_b128 v[228:231], v215 offset:13888
	s_waitcnt vmcnt(4)
	ds_write_b128 v179, v[150:153] offset:36864
	ds_write_b128 v179, v[154:157] offset:36880
	ds_write_b128 v179, v[158:161] offset:36896
	ds_write_b128 v179, v[162:165] offset:36912
	global_load_dwordx4 v[150:153], v[248:249], off offset:768
	global_load_dwordx4 v[154:157], v[248:249], off offset:784
	global_load_dwordx4 v[158:161], v[248:249], off offset:800
	global_load_dwordx4 v[162:165], v[248:249], off offset:816
	s_waitcnt lgkmcnt(15)
	v_mfma_f32_32x32x16_f16 v[98:113], v[208:211], v[240:243], v[98:113]
	s_waitcnt lgkmcnt(15)
	v_mfma_f32_32x32x16_f16 v[114:129], v[174:177], v[240:243], v[114:129]
	s_waitcnt lgkmcnt(15)
	v_mfma_f32_32x32x16_f16 v[66:81], v[208:211], v[244:247], v[66:81]
	v_mfma_f32_32x32x16_f16 v[82:97], v[174:177], v[244:247], v[82:97]
	s_waitcnt lgkmcnt(15)
	v_mfma_f32_32x32x16_f16 v[34:49], v[208:211], v[200:203], v[34:49]
	v_mfma_f32_32x32x16_f16 v[50:65], v[174:177], v[200:203], v[50:65]
	s_waitcnt lgkmcnt(14)
	v_mfma_f32_32x32x16_f16 v[2:17], v[208:211], v[204:207], v[2:17]
	v_mfma_f32_32x32x16_f16 v[18:33], v[174:177], v[204:207], v[18:33]
	ds_read_b128 v[208:211], v213 offset:96
	ds_read_b128 v[240:243], v215 offset:96
	ds_read_b128 v[174:177], v213 offset:4704
	ds_read_b128 v[244:247], v215 offset:4704
	ds_read_b128 v[200:203], v215 offset:9312
	ds_read_b128 v[204:207], v215 offset:13920
	s_waitcnt lgkmcnt(14)
	v_mfma_f32_32x32x16_f16 v[98:113], v[232:235], v[216:219], v[98:113]
	s_waitcnt lgkmcnt(13)
	v_mfma_f32_32x32x16_f16 v[114:129], v[236:239], v[216:219], v[114:129]
	s_waitcnt lgkmcnt(12)
	v_mfma_f32_32x32x16_f16 v[66:81], v[232:235], v[220:223], v[66:81]
	v_mfma_f32_32x32x16_f16 v[82:97], v[236:239], v[220:223], v[82:97]
	s_waitcnt lgkmcnt(11)
	v_mfma_f32_32x32x16_f16 v[34:49], v[232:235], v[224:227], v[34:49]
	v_mfma_f32_32x32x16_f16 v[50:65], v[236:239], v[224:227], v[50:65]
	s_waitcnt lgkmcnt(10)
	v_mfma_f32_32x32x16_f16 v[2:17], v[232:235], v[228:231], v[2:17]
	v_mfma_f32_32x32x16_f16 v[18:33], v[236:239], v[228:231], v[18:33]
	s_waitcnt lgkmcnt(0)
	s_barrier
; DI f16v mfma32(h8v a, h8v b, f16v c) { return __builtin_amdgcn_mfma_f32_32x32x16_f16(a, b, c, 0, 0, 0); }
; template <bool GATHER>
; DI void gemm256_main(const h16* __restrict__ A, int lda, const int* __restrict__ idx, int m0,
;                      const h16* __restrict__ B, int ldb, int n0, int K, h16* lds, f16v (&acc)[4][2]) {
;     ...
;   for (int kt = 0; kt < nk; ++kt) {
;     const h16* As = lds + (kt & 1) * (512 * LDH);
;     const h16* Bs = As + 256 * LDH;
;     h16* Wn = lds + ((kt & 1) ^ 1) * (512 * LDH);
;     if (kt + 1 < nk) {
; #pragma unroll
;       for (int i = 0; i < 4; ++i) { *(u4v*)&Wn[lr * LDH + lc + 8 * i] = ra[i]; *(u4v*)&Wn[(256 + lr) * LDH + lc + 8 * i] = rb[i]; }
;     }
;     if (kt + 2 < nk) {
; #pragma unroll
;       for (int i = 0; i < 4; ++i) { ra[i] = *(const u4v*)(AP_ + 8 * i); rb[i] = *(const u4v*)(BP_ + 8 * i); }
;       ao += 64; bo += 64;
;     }
; #pragma unroll
;     for (int ks = 0; ks < 4; ++ks) {
;       h8v af[4], bf[2];
; #pragma unroll
;       for (int i = 0; i < 4; ++i) af[i] = *(const h8v*)&As[(wm * 128 + i * 32 + (lane & 31)) * LDH + ks * 16 + 8 * (lane >> 5)];
; #pragma unroll
;       for (int j = 0; j < 2; ++j) bf[j] = *(const h8v*)&Bs[(wn * 64 + j * 32 + (lane & 31)) * LDH + ks * 16 + 8 * (lane >> 5)];
; #pragma unroll
;       for (int i = 0; i < 4; ++i)
; #pragma unroll
;         for (int j = 0; j < 2; ++j) acc[i][j] = mfma32(bf[j], af[i], acc[i][j]);
;     }
;     __syncthreads();
;   }
	ds_read_b128 v[232:235], v214
	ds_read_b128 v[216:219], v212
	ds_read_b128 v[236:239], v214 offset:4608
	ds_read_b128 v[220:223], v212 offset:4608
	ds_read_b128 v[224:227], v212 offset:9216
	ds_read_b128 v[228:231], v212 offset:13824
	v_mfma_f32_32x32x16_f16 v[98:113], v[208:211], v[240:243], v[98:113]
	v_mfma_f32_32x32x16_f16 v[114:129], v[174:177], v[240:243], v[114:129]
	v_mfma_f32_32x32x16_f16 v[66:81], v[208:211], v[244:247], v[66:81]
	v_mfma_f32_32x32x16_f16 v[82:97], v[174:177], v[244:247], v[82:97]
	v_mfma_f32_32x32x16_f16 v[34:49], v[208:211], v[200:203], v[34:49]
	v_mfma_f32_32x32x16_f16 v[50:65], v[174:177], v[200:203], v[50:65]
	v_mfma_f32_32x32x16_f16 v[2:17], v[208:211], v[204:207], v[2:17]
	v_mfma_f32_32x32x16_f16 v[18:33], v[174:177], v[204:207], v[18:33]
	ds_read_b128 v[208:211], v214 offset:32
	ds_read_b128 v[240:243], v212 offset:32
	ds_read_b128 v[174:177], v214 offset:4640
	ds_read_b128 v[244:247], v212 offset:4640
	ds_read_b128 v[200:203], v212 offset:9248
	ds_read_b128 v[204:207], v212 offset:13856
	s_waitcnt vmcnt(4)
	ds_write_b128 v178, v[134:137]
	ds_write_b128 v178, v[138:141] offset:16
	ds_write_b128 v178, v[142:145] offset:32
	ds_write_b128 v178, v[146:149] offset:48
	global_load_dwordx4 v[134:137], v[130:131], off offset:896
	global_load_dwordx4 v[138:141], v[130:131], off offset:912
	global_load_dwordx4 v[142:145], v[130:131], off offset:928
	global_load_dwordx4 v[146:149], v[130:131], off offset:944
	s_waitcnt lgkmcnt(14)
	v_mfma_f32_32x32x16_f16 v[98:113], v[232:235], v[216:219], v[98:113]
	s_waitcnt lgkmcnt(13)
	v_mfma_f32_32x32x16_f16 v[114:129], v[236:239], v[216:219], v[114:129]
	s_waitcnt lgkmcnt(12)
	v_mfma_f32_32x32x16_f16 v[66:81], v[232:235], v[220:223], v[66:81]
	v_mfma_f32_32x32x16_f16 v[82:97], v[236:239], v[220:223], v[82:97]
	s_waitcnt lgkmcnt(11)
	v_mfma_f32_32x32x16_f16 v[34:49], v[232:235], v[224:227], v[34:49]
	v_mfma_f32_32x32x16_f16 v[50:65], v[236:239], v[224:227], v[50:65]
	s_waitcnt lgkmcnt(10)
	v_mfma_f32_32x32x16_f16 v[2:17], v[232:235], v[228:231], v[2:17]
	v_mfma_f32_32x32x16_f16 v[18:33], v[236:239], v[228:231], v[18:33]
	ds_read_b128 v[232:235], v214 offset:64
	ds_read_b128 v[216:219], v212 offset:64
	ds_read_b128 v[236:239], v214 offset:4672
	ds_read_b128 v[220:223], v212 offset:4672
	ds_read_b128 v[224:227], v212 offset:9280
	ds_read_b128 v[228:231], v212 offset:13888
	s_waitcnt vmcnt(4)
	ds_write_b128 v178, v[150:153] offset:36864
	ds_write_b128 v178, v[154:157] offset:36880
	ds_write_b128 v178, v[158:161] offset:36896
	ds_write_b128 v178, v[162:165] offset:36912
	global_load_dwordx4 v[150:153], v[248:249], off offset:896
	global_load_dwordx4 v[154:157], v[248:249], off offset:912
	global_load_dwordx4 v[158:161], v[248:249], off offset:928
	global_load_dwordx4 v[162:165], v[248:249], off offset:944
	s_waitcnt lgkmcnt(15)
	v_mfma_f32_32x32x16_f16 v[98:113], v[208:211], v[240:243], v[98:113]
	s_waitcnt lgkmcnt(15)
	v_mfma_f32_32x32x16_f16 v[114:129], v[174:177], v[240:243], v[114:129]
	s_waitcnt lgkmcnt(15)
	v_mfma_f32_32x32x16_f16 v[66:81], v[208:211], v[244:247], v[66:81]
	v_mfma_f32_32x32x16_f16 v[82:97], v[174:177], v[244:247], v[82:97]
	s_waitcnt lgkmcnt(15)
	v_mfma_f32_32x32x16_f16 v[34:49], v[208:211], v[200:203], v[34:49]
	v_mfma_f32_32x32x16_f16 v[50:65], v[174:177], v[200:203], v[50:65]
	s_waitcnt lgkmcnt(14)
	v_mfma_f32_32x32x16_f16 v[2:17], v[208:211], v[204:207], v[2:17]
	v_mfma_f32_32x32x16_f16 v[18:33], v[174:177], v[204:207], v[18:33]
	ds_read_b128 v[208:211], v214 offset:96
	ds_read_b128 v[240:243], v212 offset:96
	ds_read_b128 v[174:177], v214 offset:4704
	ds_read_b128 v[244:247], v212 offset:4704
	ds_read_b128 v[200:203], v212 offset:9312
	ds_read_b128 v[204:207], v212 offset:13920
	s_waitcnt lgkmcnt(14)
	v_mfma_f32_32x32x16_f16 v[98:113], v[232:235], v[216:219], v[98:113]
	s_waitcnt lgkmcnt(13)
	v_mfma_f32_32x32x16_f16 v[114:129], v[236:239], v[216:219], v[114:129]
	s_waitcnt lgkmcnt(12)
	v_mfma_f32_32x32x16_f16 v[66:81], v[232:235], v[220:223], v[66:81]
	v_mfma_f32_32x32x16_f16 v[82:97], v[236:239], v[220:223], v[82:97]
	s_waitcnt lgkmcnt(11)
	v_mfma_f32_32x32x16_f16 v[34:49], v[232:235], v[224:227], v[34:49]
	v_mfma_f32_32x32x16_f16 v[50:65], v[236:239], v[224:227], v[50:65]
	s_waitcnt lgkmcnt(10)
	v_mfma_f32_32x32x16_f16 v[2:17], v[232:235], v[228:231], v[2:17]
	v_mfma_f32_32x32x16_f16 v[18:33], v[236:239], v[228:231], v[18:33]
	s_waitcnt lgkmcnt(0)
	s_barrier
; DI f16v mfma32(h8v a, h8v b, f16v c) { return __builtin_amdgcn_mfma_f32_32x32x16_f16(a, b, c, 0, 0, 0); }
; template <bool GATHER>
; DI void gemm256_main(const h16* __restrict__ A, int lda, const int* __restrict__ idx, int m0,
;                      const h16* __restrict__ B, int ldb, int n0, int K, h16* lds, f16v (&acc)[4][2]) {
;     ...
;   for (int kt = 0; kt < nk; ++kt) {
;     const h16* As = lds + (kt & 1) * (512 * LDH);
;     const h16* Bs = As + 256 * LDH;
;     h16* Wn = lds + ((kt & 1) ^ 1) * (512 * LDH);
;     if (kt + 1 < nk) {
; #pragma unroll
;       for (int i = 0; i < 4; ++i) { *(u4v*)&Wn[lr * LDH + lc + 8 * i] = ra[i]; *(u4v*)&Wn[(256 + lr) * LDH + lc + 8 * i] = rb[i]; }
;     }
;     if (kt + 2 < nk) {
; #pragma unroll
;       for (int i = 0; i < 4; ++i) { ra[i] = *(const u4v*)(AP_ + 8 * i); rb[i] = *(const u4v*)(BP_ + 8 * i); }
;       ao += 64; bo += 64;
;     }
; #pragma unroll
;     for (int ks = 0; ks < 4; ++ks) {
;       h8v af[4], bf[2];
; #pragma unroll
;       for (int i = 0; i < 4; ++i) af[i] = *(const h8v*)&As[(wm * 128 + i * 32 + (lane & 31)) * LDH + ks * 16 + 8 * (lane >> 5)];
; #pragma unroll
;       for (int j = 0; j < 2; ++j) bf[j] = *(const h8v*)&Bs[(wn * 64 + j * 32 + (lane & 31)) * LDH + ks * 16 + 8 * (lane >> 5)];
; #pragma unroll
;       for (int i = 0; i < 4; ++i)
; #pragma unroll
;         for (int j = 0; j < 2; ++j) acc[i][j] = mfma32(bf[j], af[i], acc[i][j]);
;     }
;     __syncthreads();
;   }
	ds_read_b128 v[232:235], v213
	ds_read_b128 v[216:219], v215
	ds_read_b128 v[236:239], v213 offset:4608
	ds_read_b128 v[220:223], v215 offset:4608
	ds_read_b128 v[224:227], v215 offset:9216
	ds_read_b128 v[228:231], v215 offset:13824
	v_mfma_f32_32x32x16_f16 v[98:113], v[208:211], v[240:243], v[98:113]
	v_mfma_f32_32x32x16_f16 v[114:129], v[174:177], v[240:243], v[114:129]
	v_mfma_f32_32x32x16_f16 v[66:81], v[208:211], v[244:247], v[66:81]
	v_mfma_f32_32x32x16_f16 v[82:97], v[174:177], v[244:247], v[82:97]
	v_mfma_f32_32x32x16_f16 v[34:49], v[208:211], v[200:203], v[34:49]
	v_mfma_f32_32x32x16_f16 v[50:65], v[174:177], v[200:203], v[50:65]
	v_mfma_f32_32x32x16_f16 v[2:17], v[208:211], v[204:207], v[2:17]
	v_mfma_f32_32x32x16_f16 v[18:33], v[174:177], v[204:207], v[18:33]
	ds_read_b128 v[208:211], v213 offset:32
	ds_read_b128 v[240:243], v215 offset:32
	ds_read_b128 v[174:177], v213 offset:4640
	ds_read_b128 v[244:247], v215 offset:4640
	ds_read_b128 v[200:203], v215 offset:9248
	ds_read_b128 v[204:207], v215 offset:13856
	s_waitcnt vmcnt(4)
	ds_write_b128 v179, v[134:137]
	ds_write_b128 v179, v[138:141] offset:16
	ds_write_b128 v179, v[142:145] offset:32
	ds_write_b128 v179, v[146:149] offset:48
	global_load_dwordx4 v[134:137], v[130:131], off offset:1024
	global_load_dwordx4 v[138:141], v[130:131], off offset:1040
	global_load_dwordx4 v[142:145], v[130:131], off offset:1056
	global_load_dwordx4 v[146:149], v[130:131], off offset:1072
	s_waitcnt lgkmcnt(14)
	v_mfma_f32_32x32x16_f16 v[98:113], v[232:235], v[216:219], v[98:113]
	s_waitcnt lgkmcnt(13)
	v_mfma_f32_32x32x16_f16 v[114:129], v[236:239], v[216:219], v[114:129]
	s_waitcnt lgkmcnt(12)
	v_mfma_f32_32x32x16_f16 v[66:81], v[232:235], v[220:223], v[66:81]
	v_mfma_f32_32x32x16_f16 v[82:97], v[236:239], v[220:223], v[82:97]
	s_waitcnt lgkmcnt(11)
	v_mfma_f32_32x32x16_f16 v[34:49], v[232:235], v[224:227], v[34:49]
	v_mfma_f32_32x32x16_f16 v[50:65], v[236:239], v[224:227], v[50:65]
	s_waitcnt lgkmcnt(10)
	v_mfma_f32_32x32x16_f16 v[2:17], v[232:235], v[228:231], v[2:17]
	v_mfma_f32_32x32x16_f16 v[18:33], v[236:239], v[228:231], v[18:33]
	ds_read_b128 v[232:235], v213 offset:64
	ds_read_b128 v[216:219], v215 offset:64
	ds_read_b128 v[236:239], v213 offset:4672
	ds_read_b128 v[220:223], v215 offset:4672
	ds_read_b128 v[224:227], v215 offset:9280
	ds_read_b128 v[228:231], v215 offset:13888
	s_waitcnt vmcnt(4)
	ds_write_b128 v179, v[150:153] offset:36864
	ds_write_b128 v179, v[154:157] offset:36880
	ds_write_b128 v179, v[158:161] offset:36896
	ds_write_b128 v179, v[162:165] offset:36912
	global_load_dwordx4 v[150:153], v[248:249], off offset:1024
	global_load_dwordx4 v[154:157], v[248:249], off offset:1040
	global_load_dwordx4 v[158:161], v[248:249], off offset:1056
	global_load_dwordx4 v[162:165], v[248:249], off offset:1072
	s_waitcnt lgkmcnt(15)
	v_mfma_f32_32x32x16_f16 v[98:113], v[208:211], v[240:243], v[98:113]
	s_waitcnt lgkmcnt(15)
	v_mfma_f32_32x32x16_f16 v[114:129], v[174:177], v[240:243], v[114:129]
	s_waitcnt lgkmcnt(15)
	v_mfma_f32_32x32x16_f16 v[66:81], v[208:211], v[244:247], v[66:81]
	v_mfma_f32_32x32x16_f16 v[82:97], v[174:177], v[244:247], v[82:97]
	s_waitcnt lgkmcnt(15)
	v_mfma_f32_32x32x16_f16 v[34:49], v[208:211], v[200:203], v[34:49]
	v_mfma_f32_32x32x16_f16 v[50:65], v[174:177], v[200:203], v[50:65]
	s_waitcnt lgkmcnt(14)
	v_mfma_f32_32x32x16_f16 v[2:17], v[208:211], v[204:207], v[2:17]
	v_mfma_f32_32x32x16_f16 v[18:33], v[174:177], v[204:207], v[18:33]
	ds_read_b128 v[208:211], v213 offset:96
	ds_read_b128 v[240:243], v215 offset:96
	ds_read_b128 v[174:177], v213 offset:4704
	ds_read_b128 v[244:247], v215 offset:4704
	ds_read_b128 v[200:203], v215 offset:9312
	ds_read_b128 v[204:207], v215 offset:13920
	s_waitcnt lgkmcnt(14)
	v_mfma_f32_32x32x16_f16 v[98:113], v[232:235], v[216:219], v[98:113]
	s_waitcnt lgkmcnt(13)
	v_mfma_f32_32x32x16_f16 v[114:129], v[236:239], v[216:219], v[114:129]
	s_waitcnt lgkmcnt(12)
	v_mfma_f32_32x32x16_f16 v[66:81], v[232:235], v[220:223], v[66:81]
	v_mfma_f32_32x32x16_f16 v[82:97], v[236:239], v[220:223], v[82:97]
	s_waitcnt lgkmcnt(11)
	v_mfma_f32_32x32x16_f16 v[34:49], v[232:235], v[224:227], v[34:49]
	v_mfma_f32_32x32x16_f16 v[50:65], v[236:239], v[224:227], v[50:65]
	s_waitcnt lgkmcnt(10)
	v_mfma_f32_32x32x16_f16 v[2:17], v[232:235], v[228:231], v[2:17]
	v_mfma_f32_32x32x16_f16 v[18:33], v[236:239], v[228:231], v[18:33]
	s_waitcnt lgkmcnt(0)
	s_barrier
; DI f16v mfma32(h8v a, h8v b, f16v c) { return __builtin_amdgcn_mfma_f32_32x32x16_f16(a, b, c, 0, 0, 0); }
; template <bool GATHER>
; DI void gemm256_main(const h16* __restrict__ A, int lda, const int* __restrict__ idx, int m0,
;                      const h16* __restrict__ B, int ldb, int n0, int K, h16* lds, f16v (&acc)[4][2]) {
;     ...
;   for (int kt = 0; kt < nk; ++kt) {
;     const h16* As = lds + (kt & 1) * (512 * LDH);
;     const h16* Bs = As + 256 * LDH;
;     h16* Wn = lds + ((kt & 1) ^ 1) * (512 * LDH);
;     if (kt + 1 < nk) {
; #pragma unroll
;       for (int i = 0; i < 4; ++i) { *(u4v*)&Wn[lr * LDH + lc + 8 * i] = ra[i]; *(u4v*)&Wn[(256 + lr) * LDH + lc + 8 * i] = rb[i]; }
;     }
;     if (kt + 2 < nk) {
; #pragma unroll
;       for (int i = 0; i < 4; ++i) { ra[i] = *(const u4v*)(AP_ + 8 * i); rb[i] = *(const u4v*)(BP_ + 8 * i); }
;       ao += 64; bo += 64;
;     }
; #pragma unroll
;     for (int ks = 0; ks < 4; ++ks) {
;       h8v af[4], bf[2];
; #pragma unroll
;       for (int i = 0; i < 4; ++i) af[i] = *(const h8v*)&As[(wm * 128 + i * 32 + (lane & 31)) * LDH + ks * 16 + 8 * (lane >> 5)];
; #pragma unroll
;       for (int j = 0; j < 2; ++j) bf[j] = *(const h8v*)&Bs[(wn * 64 + j * 32 + (lane & 31)) * LDH + ks * 16 + 8 * (lane >> 5)];
; #pragma unroll
;       for (int i = 0; i < 4; ++i)
; #pragma unroll
;         for (int j = 0; j < 2; ++j) acc[i][j] = mfma32(bf[j], af[i], acc[i][j]);
;     }
;     __syncthreads();
;   }
	ds_read_b128 v[232:235], v214
	ds_read_b128 v[216:219], v212
	ds_read_b128 v[236:239], v214 offset:4608
	ds_read_b128 v[220:223], v212 offset:4608
	ds_read_b128 v[224:227], v212 offset:9216
	ds_read_b128 v[228:231], v212 offset:13824
	v_mfma_f32_32x32x16_f16 v[98:113], v[208:211], v[240:243], v[98:113]
	v_mfma_f32_32x32x16_f16 v[114:129], v[174:177], v[240:243], v[114:129]
	v_mfma_f32_32x32x16_f16 v[66:81], v[208:211], v[244:247], v[66:81]
	v_mfma_f32_32x32x16_f16 v[82:97], v[174:177], v[244:247], v[82:97]
	v_mfma_f32_32x32x16_f16 v[34:49], v[208:211], v[200:203], v[34:49]
	v_mfma_f32_32x32x16_f16 v[50:65], v[174:177], v[200:203], v[50:65]
	v_mfma_f32_32x32x16_f16 v[2:17], v[208:211], v[204:207], v[2:17]
	v_mfma_f32_32x32x16_f16 v[18:33], v[174:177], v[204:207], v[18:33]
	ds_read_b128 v[208:211], v214 offset:32
	ds_read_b128 v[240:243], v212 offset:32
	ds_read_b128 v[174:177], v214 offset:4640
	ds_read_b128 v[244:247], v212 offset:4640
	ds_read_b128 v[200:203], v212 offset:9248
	ds_read_b128 v[204:207], v212 offset:13856
	s_waitcnt vmcnt(4)
	ds_write_b128 v178, v[134:137]
	ds_write_b128 v178, v[138:141] offset:16
	ds_write_b128 v178, v[142:145] offset:32
	ds_write_b128 v178, v[146:149] offset:48
	global_load_dwordx4 v[134:137], v[130:131], off offset:1152
	global_load_dwordx4 v[138:141], v[130:131], off offset:1168
	global_load_dwordx4 v[142:145], v[130:131], off offset:1184
	global_load_dwordx4 v[146:149], v[130:131], off offset:1200
	s_waitcnt lgkmcnt(14)
	v_mfma_f32_32x32x16_f16 v[98:113], v[232:235], v[216:219], v[98:113]
	s_waitcnt lgkmcnt(13)
	v_mfma_f32_32x32x16_f16 v[114:129], v[236:239], v[216:219], v[114:129]
	s_waitcnt lgkmcnt(12)
	v_mfma_f32_32x32x16_f16 v[66:81], v[232:235], v[220:223], v[66:81]
	v_mfma_f32_32x32x16_f16 v[82:97], v[236:239], v[220:223], v[82:97]
	s_waitcnt lgkmcnt(11)
	v_mfma_f32_32x32x16_f16 v[34:49], v[232:235], v[224:227], v[34:49]
	v_mfma_f32_32x32x16_f16 v[50:65], v[236:239], v[224:227], v[50:65]
	s_waitcnt lgkmcnt(10)
	v_mfma_f32_32x32x16_f16 v[2:17], v[232:235], v[228:231], v[2:17]
	v_mfma_f32_32x32x16_f16 v[18:33], v[236:239], v[228:231], v[18:33]
	ds_read_b128 v[232:235], v214 offset:64
	ds_read_b128 v[216:219], v212 offset:64
	ds_read_b128 v[236:239], v214 offset:4672
	ds_read_b128 v[220:223], v212 offset:4672
	ds_read_b128 v[224:227], v212 offset:9280
	ds_read_b128 v[228:231], v212 offset:13888
	s_waitcnt vmcnt(4)
	ds_write_b128 v178, v[150:153] offset:36864
	ds_write_b128 v178, v[154:157] offset:36880
	ds_write_b128 v178, v[158:161] offset:36896
	ds_write_b128 v178, v[162:165] offset:36912
	global_load_dwordx4 v[150:153], v[248:249], off offset:1152
	global_load_dwordx4 v[154:157], v[248:249], off offset:1168
	global_load_dwordx4 v[158:161], v[248:249], off offset:1184
	global_load_dwordx4 v[162:165], v[248:249], off offset:1200
	s_waitcnt lgkmcnt(15)
	v_mfma_f32_32x32x16_f16 v[98:113], v[208:211], v[240:243], v[98:113]
	s_waitcnt lgkmcnt(15)
	v_mfma_f32_32x32x16_f16 v[114:129], v[174:177], v[240:243], v[114:129]
	s_waitcnt lgkmcnt(15)
	v_mfma_f32_32x32x16_f16 v[66:81], v[208:211], v[244:247], v[66:81]
	v_mfma_f32_32x32x16_f16 v[82:97], v[174:177], v[244:247], v[82:97]
	s_waitcnt lgkmcnt(15)
	v_mfma_f32_32x32x16_f16 v[34:49], v[208:211], v[200:203], v[34:49]
	v_mfma_f32_32x32x16_f16 v[50:65], v[174:177], v[200:203], v[50:65]
	s_waitcnt lgkmcnt(14)
	v_mfma_f32_32x32x16_f16 v[2:17], v[208:211], v[204:207], v[2:17]
	v_mfma_f32_32x32x16_f16 v[18:33], v[174:177], v[204:207], v[18:33]
	ds_read_b128 v[208:211], v214 offset:96
	ds_read_b128 v[240:243], v212 offset:96
	ds_read_b128 v[174:177], v214 offset:4704
	ds_read_b128 v[244:247], v212 offset:4704
	ds_read_b128 v[200:203], v212 offset:9312
	ds_read_b128 v[204:207], v212 offset:13920
	s_waitcnt lgkmcnt(14)
	v_mfma_f32_32x32x16_f16 v[98:113], v[232:235], v[216:219], v[98:113]
	s_waitcnt lgkmcnt(13)
	v_mfma_f32_32x32x16_f16 v[114:129], v[236:239], v[216:219], v[114:129]
	s_waitcnt lgkmcnt(12)
	v_mfma_f32_32x32x16_f16 v[66:81], v[232:235], v[220:223], v[66:81]
	v_mfma_f32_32x32x16_f16 v[82:97], v[236:239], v[220:223], v[82:97]
	s_waitcnt lgkmcnt(11)
	v_mfma_f32_32x32x16_f16 v[34:49], v[232:235], v[224:227], v[34:49]
	v_mfma_f32_32x32x16_f16 v[50:65], v[236:239], v[224:227], v[50:65]
	s_waitcnt lgkmcnt(10)
	v_mfma_f32_32x32x16_f16 v[2:17], v[232:235], v[228:231], v[2:17]
	v_mfma_f32_32x32x16_f16 v[18:33], v[236:239], v[228:231], v[18:33]
	s_waitcnt lgkmcnt(0)
	s_barrier
; DI f16v mfma32(h8v a, h8v b, f16v c) { return __builtin_amdgcn_mfma_f32_32x32x16_f16(a, b, c, 0, 0, 0); }
; template <bool GATHER>
; DI void gemm256_main(const h16* __restrict__ A, int lda, const int* __restrict__ idx, int m0,
;                      const h16* __restrict__ B, int ldb, int n0, int K, h16* lds, f16v (&acc)[4][2]) {
;     ...
;   for (int kt = 0; kt < nk; ++kt) {
;     const h16* As = lds + (kt & 1) * (512 * LDH);
;     const h16* Bs = As + 256 * LDH;
;     h16* Wn = lds + ((kt & 1) ^ 1) * (512 * LDH);
;     if (kt + 1 < nk) {
; #pragma unroll
;       for (int i = 0; i < 4; ++i) { *(u4v*)&Wn[lr * LDH + lc + 8 * i] = ra[i]; *(u4v*)&Wn[(256 + lr) * LDH + lc + 8 * i] = rb[i]; }
;     }
;     if (kt + 2 < nk) {
; #pragma unroll
;       for (int i = 0; i < 4; ++i) { ra[i] = *(const u4v*)(AP_ + 8 * i); rb[i] = *(const u4v*)(BP_ + 8 * i); }
;       ao += 64; bo += 64;
;     }
; #pragma unroll
;     for (int ks = 0; ks < 4; ++ks) {
;       h8v af[4], bf[2];
; #pragma unroll
;       for (int i = 0; i < 4; ++i) af[i] = *(const h8v*)&As[(wm * 128 + i * 32 + (lane & 31)) * LDH + ks * 16 + 8 * (lane >> 5)];
; #pragma unroll
;       for (int j = 0; j < 2; ++j) bf[j] = *(const h8v*)&Bs[(wn * 64 + j * 32 + (lane & 31)) * LDH + ks * 16 + 8 * (lane >> 5)];
; #pragma unroll
;       for (int i = 0; i < 4; ++i)
; #pragma unroll
;         for (int j = 0; j < 2; ++j) acc[i][j] = mfma32(bf[j], af[i], acc[i][j]);
;     }
;     __syncthreads();
;   }
	ds_read_b128 v[232:235], v213
	ds_read_b128 v[216:219], v215
	ds_read_b128 v[236:239], v213 offset:4608
	ds_read_b128 v[220:223], v215 offset:4608
	ds_read_b128 v[224:227], v215 offset:9216
	ds_read_b128 v[228:231], v215 offset:13824
	v_mfma_f32_32x32x16_f16 v[98:113], v[208:211], v[240:243], v[98:113]
	v_mfma_f32_32x32x16_f16 v[114:129], v[174:177], v[240:243], v[114:129]
	v_mfma_f32_32x32x16_f16 v[66:81], v[208:211], v[244:247], v[66:81]
	v_mfma_f32_32x32x16_f16 v[82:97], v[174:177], v[244:247], v[82:97]
	v_mfma_f32_32x32x16_f16 v[34:49], v[208:211], v[200:203], v[34:49]
	v_mfma_f32_32x32x16_f16 v[50:65], v[174:177], v[200:203], v[50:65]
	v_mfma_f32_32x32x16_f16 v[2:17], v[208:211], v[204:207], v[2:17]
	v_mfma_f32_32x32x16_f16 v[18:33], v[174:177], v[204:207], v[18:33]
	ds_read_b128 v[208:211], v213 offset:32
	ds_read_b128 v[240:243], v215 offset:32
	ds_read_b128 v[174:177], v213 offset:4640
	ds_read_b128 v[244:247], v215 offset:4640
	ds_read_b128 v[200:203], v215 offset:9248
	ds_read_b128 v[204:207], v215 offset:13856
	s_waitcnt vmcnt(4)
	ds_write_b128 v179, v[134:137]
	ds_write_b128 v179, v[138:141] offset:16
	ds_write_b128 v179, v[142:145] offset:32
	ds_write_b128 v179, v[146:149] offset:48
	global_load_dwordx4 v[134:137], v[130:131], off offset:1280
	global_load_dwordx4 v[138:141], v[130:131], off offset:1296
	global_load_dwordx4 v[142:145], v[130:131], off offset:1312
	global_load_dwordx4 v[146:149], v[130:131], off offset:1328
	s_waitcnt lgkmcnt(14)
	v_mfma_f32_32x32x16_f16 v[98:113], v[232:235], v[216:219], v[98:113]
	s_waitcnt lgkmcnt(13)
	v_mfma_f32_32x32x16_f16 v[114:129], v[236:239], v[216:219], v[114:129]
	s_waitcnt lgkmcnt(12)
	v_mfma_f32_32x32x16_f16 v[66:81], v[232:235], v[220:223], v[66:81]
	v_mfma_f32_32x32x16_f16 v[82:97], v[236:239], v[220:223], v[82:97]
	s_waitcnt lgkmcnt(11)
	v_mfma_f32_32x32x16_f16 v[34:49], v[232:235], v[224:227], v[34:49]
	v_mfma_f32_32x32x16_f16 v[50:65], v[236:239], v[224:227], v[50:65]
	s_waitcnt lgkmcnt(10)
	v_mfma_f32_32x32x16_f16 v[2:17], v[232:235], v[228:231], v[2:17]
	v_mfma_f32_32x32x16_f16 v[18:33], v[236:239], v[228:231], v[18:33]
	ds_read_b128 v[232:235], v213 offset:64
	ds_read_b128 v[216:219], v215 offset:64
	ds_read_b128 v[236:239], v213 offset:4672
	ds_read_b128 v[220:223], v215 offset:4672
	ds_read_b128 v[224:227], v215 offset:9280
	ds_read_b128 v[228:231], v215 offset:13888
	s_waitcnt vmcnt(4)
	ds_write_b128 v179, v[150:153] offset:36864
	ds_write_b128 v179, v[154:157] offset:36880
	ds_write_b128 v179, v[158:161] offset:36896
	ds_write_b128 v179, v[162:165] offset:36912
	global_load_dwordx4 v[150:153], v[248:249], off offset:1280
	global_load_dwordx4 v[154:157], v[248:249], off offset:1296
	global_load_dwordx4 v[158:161], v[248:249], off offset:1312
	global_load_dwordx4 v[162:165], v[248:249], off offset:1328
	s_waitcnt lgkmcnt(15)
	v_mfma_f32_32x32x16_f16 v[98:113], v[208:211], v[240:243], v[98:113]
	s_waitcnt lgkmcnt(15)
	v_mfma_f32_32x32x16_f16 v[114:129], v[174:177], v[240:243], v[114:129]
	s_waitcnt lgkmcnt(15)
	v_mfma_f32_32x32x16_f16 v[66:81], v[208:211], v[244:247], v[66:81]
	v_mfma_f32_32x32x16_f16 v[82:97], v[174:177], v[244:247], v[82:97]
	s_waitcnt lgkmcnt(15)
	v_mfma_f32_32x32x16_f16 v[34:49], v[208:211], v[200:203], v[34:49]
	v_mfma_f32_32x32x16_f16 v[50:65], v[174:177], v[200:203], v[50:65]
	s_waitcnt lgkmcnt(14)
	v_mfma_f32_32x32x16_f16 v[2:17], v[208:211], v[204:207], v[2:17]
	v_mfma_f32_32x32x16_f16 v[18:33], v[174:177], v[204:207], v[18:33]
	ds_read_b128 v[208:211], v213 offset:96
	ds_read_b128 v[240:243], v215 offset:96
	ds_read_b128 v[174:177], v213 offset:4704
	ds_read_b128 v[244:247], v215 offset:4704
	ds_read_b128 v[200:203], v215 offset:9312
	ds_read_b128 v[204:207], v215 offset:13920
	s_waitcnt lgkmcnt(14)
	v_mfma_f32_32x32x16_f16 v[98:113], v[232:235], v[216:219], v[98:113]
	s_waitcnt lgkmcnt(13)
	v_mfma_f32_32x32x16_f16 v[114:129], v[236:239], v[216:219], v[114:129]
	s_waitcnt lgkmcnt(12)
	v_mfma_f32_32x32x16_f16 v[66:81], v[232:235], v[220:223], v[66:81]
	v_mfma_f32_32x32x16_f16 v[82:97], v[236:239], v[220:223], v[82:97]
	s_waitcnt lgkmcnt(11)
	v_mfma_f32_32x32x16_f16 v[34:49], v[232:235], v[224:227], v[34:49]
	v_mfma_f32_32x32x16_f16 v[50:65], v[236:239], v[224:227], v[50:65]
	s_waitcnt lgkmcnt(10)
	v_mfma_f32_32x32x16_f16 v[2:17], v[232:235], v[228:231], v[2:17]
	v_mfma_f32_32x32x16_f16 v[18:33], v[236:239], v[228:231], v[18:33]
	s_waitcnt lgkmcnt(0)
	s_barrier
; DI f16v mfma32(h8v a, h8v b, f16v c) { return __builtin_amdgcn_mfma_f32_32x32x16_f16(a, b, c, 0, 0, 0); }
; template <bool GATHER>
; DI void gemm256_main(const h16* __restrict__ A, int lda, const int* __restrict__ idx, int m0,
;                      const h16* __restrict__ B, int ldb, int n0, int K, h16* lds, f16v (&acc)[4][2]) {
;     ...
;   for (int kt = 0; kt < nk; ++kt) {
;     const h16* As = lds + (kt & 1) * (512 * LDH);
;     const h16* Bs = As + 256 * LDH;
;     h16* Wn = lds + ((kt & 1) ^ 1) * (512 * LDH);
;     if (kt + 1 < nk) {
; #pragma unroll
;       for (int i = 0; i < 4; ++i) { *(u4v*)&Wn[lr * LDH + lc + 8 * i] = ra[i]; *(u4v*)&Wn[(256 + lr) * LDH + lc + 8 * i] = rb[i]; }
;     }
;     if (kt + 2 < nk) {
; #pragma unroll
;       for (int i = 0; i < 4; ++i) { ra[i] = *(const u4v*)(AP_ + 8 * i); rb[i] = *(const u4v*)(BP_ + 8 * i); }
;       ao += 64; bo += 64;
;     }
; #pragma unroll
;     for (int ks = 0; ks < 4; ++ks) {
;       h8v af[4], bf[2];
; #pragma unroll
;       for (int i = 0; i < 4; ++i) af[i] = *(const h8v*)&As[(wm * 128 + i * 32 + (lane & 31)) * LDH + ks * 16 + 8 * (lane >> 5)];
; #pragma unroll
;       for (int j = 0; j < 2; ++j) bf[j] = *(const h8v*)&Bs[(wn * 64 + j * 32 + (lane & 31)) * LDH + ks * 16 + 8 * (lane >> 5)];
; #pragma unroll
;       for (int i = 0; i < 4; ++i)
; #pragma unroll
;         for (int j = 0; j < 2; ++j) acc[i][j] = mfma32(bf[j], af[i], acc[i][j]);
;     }
;     __syncthreads();
;   }
	ds_read_b128 v[232:235], v214
	ds_read_b128 v[216:219], v212
	ds_read_b128 v[236:239], v214 offset:4608
	ds_read_b128 v[220:223], v212 offset:4608
	ds_read_b128 v[224:227], v212 offset:9216
	ds_read_b128 v[228:231], v212 offset:13824
	v_mfma_f32_32x32x16_f16 v[98:113], v[208:211], v[240:243], v[98:113]
	v_mfma_f32_32x32x16_f16 v[114:129], v[174:177], v[240:243], v[114:129]
	v_mfma_f32_32x32x16_f16 v[66:81], v[208:211], v[244:247], v[66:81]
	v_mfma_f32_32x32x16_f16 v[82:97], v[174:177], v[244:247], v[82:97]
	v_mfma_f32_32x32x16_f16 v[34:49], v[208:211], v[200:203], v[34:49]
	v_mfma_f32_32x32x16_f16 v[50:65], v[174:177], v[200:203], v[50:65]
	v_mfma_f32_32x32x16_f16 v[2:17], v[208:211], v[204:207], v[2:17]
	v_mfma_f32_32x32x16_f16 v[18:33], v[174:177], v[204:207], v[18:33]
	ds_read_b128 v[208:211], v214 offset:32
	ds_read_b128 v[240:243], v212 offset:32
	ds_read_b128 v[174:177], v214 offset:4640
	ds_read_b128 v[244:247], v212 offset:4640
	ds_read_b128 v[200:203], v212 offset:9248
	ds_read_b128 v[204:207], v212 offset:13856
	s_waitcnt vmcnt(4)
	ds_write_b128 v178, v[134:137]
	ds_write_b128 v178, v[138:141] offset:16
	ds_write_b128 v178, v[142:145] offset:32
	ds_write_b128 v178, v[146:149] offset:48
	global_load_dwordx4 v[134:137], v[130:131], off offset:1408
	global_load_dwordx4 v[138:141], v[130:131], off offset:1424
	global_load_dwordx4 v[142:145], v[130:131], off offset:1440
	global_load_dwordx4 v[146:149], v[130:131], off offset:1456
	s_waitcnt lgkmcnt(14)
	v_mfma_f32_32x32x16_f16 v[98:113], v[232:235], v[216:219], v[98:113]
	s_waitcnt lgkmcnt(13)
	v_mfma_f32_32x32x16_f16 v[114:129], v[236:239], v[216:219], v[114:129]
	s_waitcnt lgkmcnt(12)
	v_mfma_f32_32x32x16_f16 v[66:81], v[232:235], v[220:223], v[66:81]
	v_mfma_f32_32x32x16_f16 v[82:97], v[236:239], v[220:223], v[82:97]
	s_waitcnt lgkmcnt(11)
	v_mfma_f32_32x32x16_f16 v[34:49], v[232:235], v[224:227], v[34:49]
	v_mfma_f32_32x32x16_f16 v[50:65], v[236:239], v[224:227], v[50:65]
	s_waitcnt lgkmcnt(10)
	v_mfma_f32_32x32x16_f16 v[2:17], v[232:235], v[228:231], v[2:17]
	v_mfma_f32_32x32x16_f16 v[18:33], v[236:239], v[228:231], v[18:33]
	ds_read_b128 v[232:235], v214 offset:64
	ds_read_b128 v[216:219], v212 offset:64
	ds_read_b128 v[236:239], v214 offset:4672
	ds_read_b128 v[220:223], v212 offset:4672
	ds_read_b128 v[224:227], v212 offset:9280
	ds_read_b128 v[228:231], v212 offset:13888
	s_waitcnt vmcnt(4)
	ds_write_b128 v178, v[150:153] offset:36864
	ds_write_b128 v178, v[154:157] offset:36880
	ds_write_b128 v178, v[158:161] offset:36896
	ds_write_b128 v178, v[162:165] offset:36912
	global_load_dwordx4 v[150:153], v[248:249], off offset:1408
	global_load_dwordx4 v[154:157], v[248:249], off offset:1424
	global_load_dwordx4 v[158:161], v[248:249], off offset:1440
	global_load_dwordx4 v[162:165], v[248:249], off offset:1456
	s_waitcnt lgkmcnt(15)
	v_mfma_f32_32x32x16_f16 v[98:113], v[208:211], v[240:243], v[98:113]
	s_waitcnt lgkmcnt(15)
	v_mfma_f32_32x32x16_f16 v[114:129], v[174:177], v[240:243], v[114:129]
	s_waitcnt lgkmcnt(15)
	v_mfma_f32_32x32x16_f16 v[66:81], v[208:211], v[244:247], v[66:81]
	v_mfma_f32_32x32x16_f16 v[82:97], v[174:177], v[244:247], v[82:97]
	s_waitcnt lgkmcnt(15)
	v_mfma_f32_32x32x16_f16 v[34:49], v[208:211], v[200:203], v[34:49]
	v_mfma_f32_32x32x16_f16 v[50:65], v[174:177], v[200:203], v[50:65]
	s_waitcnt lgkmcnt(14)
	v_mfma_f32_32x32x16_f16 v[2:17], v[208:211], v[204:207], v[2:17]
	v_mfma_f32_32x32x16_f16 v[18:33], v[174:177], v[204:207], v[18:33]
	ds_read_b128 v[208:211], v214 offset:96
	ds_read_b128 v[240:243], v212 offset:96
	ds_read_b128 v[174:177], v214 offset:4704
	ds_read_b128 v[244:247], v212 offset:4704
	ds_read_b128 v[200:203], v212 offset:9312
	ds_read_b128 v[204:207], v212 offset:13920
	s_waitcnt lgkmcnt(14)
	v_mfma_f32_32x32x16_f16 v[98:113], v[232:235], v[216:219], v[98:113]
	s_waitcnt lgkmcnt(13)
	v_mfma_f32_32x32x16_f16 v[114:129], v[236:239], v[216:219], v[114:129]
	s_waitcnt lgkmcnt(12)
	v_mfma_f32_32x32x16_f16 v[66:81], v[232:235], v[220:223], v[66:81]
	v_mfma_f32_32x32x16_f16 v[82:97], v[236:239], v[220:223], v[82:97]
	s_waitcnt lgkmcnt(11)
	v_mfma_f32_32x32x16_f16 v[34:49], v[232:235], v[224:227], v[34:49]
	v_mfma_f32_32x32x16_f16 v[50:65], v[236:239], v[224:227], v[50:65]
	s_waitcnt lgkmcnt(10)
	v_mfma_f32_32x32x16_f16 v[2:17], v[232:235], v[228:231], v[2:17]
	v_mfma_f32_32x32x16_f16 v[18:33], v[236:239], v[228:231], v[18:33]
	s_waitcnt lgkmcnt(0)
	s_barrier
; DI f16v mfma32(h8v a, h8v b, f16v c) { return __builtin_amdgcn_mfma_f32_32x32x16_f16(a, b, c, 0, 0, 0); }
; template <bool GATHER>
; DI void gemm256_main(const h16* __restrict__ A, int lda, const int* __restrict__ idx, int m0,
;                      const h16* __restrict__ B, int ldb, int n0, int K, h16* lds, f16v (&acc)[4][2]) {
;     ...
;   for (int kt = 0; kt < nk; ++kt) {
;     const h16* As = lds + (kt & 1) * (512 * LDH);
;     const h16* Bs = As + 256 * LDH;
;     h16* Wn = lds + ((kt & 1) ^ 1) * (512 * LDH);
;     if (kt + 1 < nk) {
; #pragma unroll
;       for (int i = 0; i < 4; ++i) { *(u4v*)&Wn[lr * LDH + lc + 8 * i] = ra[i]; *(u4v*)&Wn[(256 + lr) * LDH + lc + 8 * i] = rb[i]; }
;     }
;     if (kt + 2 < nk) {
; #pragma unroll
;       for (int i = 0; i < 4; ++i) { ra[i] = *(const u4v*)(AP_ + 8 * i); rb[i] = *(const u4v*)(BP_ + 8 * i); }
;       ao += 64; bo += 64;
;     }
; #pragma unroll
;     for (int ks = 0; ks < 4; ++ks) {
;       h8v af[4], bf[2];
; #pragma unroll
;       for (int i = 0; i < 4; ++i) af[i] = *(const h8v*)&As[(wm * 128 + i * 32 + (lane & 31)) * LDH + ks * 16 + 8 * (lane >> 5)];
; #pragma unroll
;       for (int j = 0; j < 2; ++j) bf[j] = *(const h8v*)&Bs[(wn * 64 + j * 32 + (lane & 31)) * LDH + ks * 16 + 8 * (lane >> 5)];
; #pragma unroll
;       for (int i = 0; i < 4; ++i)
; #pragma unroll
;         for (int j = 0; j < 2; ++j) acc[i][j] = mfma32(bf[j], af[i], acc[i][j]);
;     }
;     __syncthreads();
;   }
	ds_read_b128 v[232:235], v213
	ds_read_b128 v[216:219], v215
	ds_read_b128 v[236:239], v213 offset:4608
	ds_read_b128 v[220:223], v215 offset:4608
	ds_read_b128 v[224:227], v215 offset:9216
	ds_read_b128 v[228:231], v215 offset:13824
	v_mfma_f32_32x32x16_f16 v[98:113], v[208:211], v[240:243], v[98:113]
	v_mfma_f32_32x32x16_f16 v[114:129], v[174:177], v[240:243], v[114:129]
	v_mfma_f32_32x32x16_f16 v[66:81], v[208:211], v[244:247], v[66:81]
	v_mfma_f32_32x32x16_f16 v[82:97], v[174:177], v[244:247], v[82:97]
	v_mfma_f32_32x32x16_f16 v[34:49], v[208:211], v[200:203], v[34:49]
	v_mfma_f32_32x32x16_f16 v[50:65], v[174:177], v[200:203], v[50:65]
	v_mfma_f32_32x32x16_f16 v[2:17], v[208:211], v[204:207], v[2:17]
	v_mfma_f32_32x32x16_f16 v[18:33], v[174:177], v[204:207], v[18:33]
	ds_read_b128 v[208:211], v213 offset:32
	ds_read_b128 v[240:243], v215 offset:32
	ds_read_b128 v[174:177], v213 offset:4640
	ds_read_b128 v[244:247], v215 offset:4640
	ds_read_b128 v[200:203], v215 offset:9248
	ds_read_b128 v[204:207], v215 offset:13856
	s_waitcnt vmcnt(4)
	ds_write_b128 v179, v[134:137]
	ds_write_b128 v179, v[138:141] offset:16
	ds_write_b128 v179, v[142:145] offset:32
	ds_write_b128 v179, v[146:149] offset:48
	global_load_dwordx4 v[134:137], v[130:131], off offset:1536
	global_load_dwordx4 v[138:141], v[130:131], off offset:1552
	global_load_dwordx4 v[142:145], v[130:131], off offset:1568
	global_load_dwordx4 v[146:149], v[130:131], off offset:1584
	s_waitcnt lgkmcnt(14)
	v_mfma_f32_32x32x16_f16 v[98:113], v[232:235], v[216:219], v[98:113]
	s_waitcnt lgkmcnt(13)
	v_mfma_f32_32x32x16_f16 v[114:129], v[236:239], v[216:219], v[114:129]
	s_waitcnt lgkmcnt(12)
	v_mfma_f32_32x32x16_f16 v[66:81], v[232:235], v[220:223], v[66:81]
	v_mfma_f32_32x32x16_f16 v[82:97], v[236:239], v[220:223], v[82:97]
	s_waitcnt lgkmcnt(11)
	v_mfma_f32_32x32x16_f16 v[34:49], v[232:235], v[224:227], v[34:49]
	v_mfma_f32_32x32x16_f16 v[50:65], v[236:239], v[224:227], v[50:65]
	s_waitcnt lgkmcnt(10)
	v_mfma_f32_32x32x16_f16 v[2:17], v[232:235], v[228:231], v[2:17]
	v_mfma_f32_32x32x16_f16 v[18:33], v[236:239], v[228:231], v[18:33]
	ds_read_b128 v[232:235], v213 offset:64
	ds_read_b128 v[216:219], v215 offset:64
	ds_read_b128 v[236:239], v213 offset:4672
	ds_read_b128 v[220:223], v215 offset:4672
	ds_read_b128 v[224:227], v215 offset:9280
	ds_read_b128 v[228:231], v215 offset:13888
	s_waitcnt vmcnt(4)
	ds_write_b128 v179, v[150:153] offset:36864
	ds_write_b128 v179, v[154:157] offset:36880
	ds_write_b128 v179, v[158:161] offset:36896
	ds_write_b128 v179, v[162:165] offset:36912
	global_load_dwordx4 v[150:153], v[248:249], off offset:1536
	global_load_dwordx4 v[154:157], v[248:249], off offset:1552
	global_load_dwordx4 v[158:161], v[248:249], off offset:1568
	global_load_dwordx4 v[162:165], v[248:249], off offset:1584
	s_waitcnt lgkmcnt(15)
	v_mfma_f32_32x32x16_f16 v[98:113], v[208:211], v[240:243], v[98:113]
	s_waitcnt lgkmcnt(15)
	v_mfma_f32_32x32x16_f16 v[114:129], v[174:177], v[240:243], v[114:129]
	s_waitcnt lgkmcnt(15)
	v_mfma_f32_32x32x16_f16 v[66:81], v[208:211], v[244:247], v[66:81]
	v_mfma_f32_32x32x16_f16 v[82:97], v[174:177], v[244:247], v[82:97]
	s_waitcnt lgkmcnt(15)
	v_mfma_f32_32x32x16_f16 v[34:49], v[208:211], v[200:203], v[34:49]
	v_mfma_f32_32x32x16_f16 v[50:65], v[174:177], v[200:203], v[50:65]
	s_waitcnt lgkmcnt(14)
	v_mfma_f32_32x32x16_f16 v[2:17], v[208:211], v[204:207], v[2:17]
	v_mfma_f32_32x32x16_f16 v[18:33], v[174:177], v[204:207], v[18:33]
	ds_read_b128 v[208:211], v213 offset:96
	ds_read_b128 v[240:243], v215 offset:96
	ds_read_b128 v[174:177], v213 offset:4704
	ds_read_b128 v[244:247], v215 offset:4704
	ds_read_b128 v[200:203], v215 offset:9312
	ds_read_b128 v[204:207], v215 offset:13920
	s_waitcnt lgkmcnt(14)
	v_mfma_f32_32x32x16_f16 v[98:113], v[232:235], v[216:219], v[98:113]
	s_waitcnt lgkmcnt(13)
	v_mfma_f32_32x32x16_f16 v[114:129], v[236:239], v[216:219], v[114:129]
	s_waitcnt lgkmcnt(12)
	v_mfma_f32_32x32x16_f16 v[66:81], v[232:235], v[220:223], v[66:81]
	v_mfma_f32_32x32x16_f16 v[82:97], v[236:239], v[220:223], v[82:97]
	s_waitcnt lgkmcnt(11)
	v_mfma_f32_32x32x16_f16 v[34:49], v[232:235], v[224:227], v[34:49]
	v_mfma_f32_32x32x16_f16 v[50:65], v[236:239], v[224:227], v[50:65]
	s_waitcnt lgkmcnt(10)
	v_mfma_f32_32x32x16_f16 v[2:17], v[232:235], v[228:231], v[2:17]
	v_mfma_f32_32x32x16_f16 v[18:33], v[236:239], v[228:231], v[18:33]
	s_waitcnt lgkmcnt(0)
	s_barrier
; DI f16v mfma32(h8v a, h8v b, f16v c) { return __builtin_amdgcn_mfma_f32_32x32x16_f16(a, b, c, 0, 0, 0); }
; template <bool GATHER>
; DI void gemm256_main(const h16* __restrict__ A, int lda, const int* __restrict__ idx, int m0,
;                      const h16* __restrict__ B, int ldb, int n0, int K, h16* lds, f16v (&acc)[4][2]) {
;     ...
;   for (int kt = 0; kt < nk; ++kt) {
;     const h16* As = lds + (kt & 1) * (512 * LDH);
;     const h16* Bs = As + 256 * LDH;
;     h16* Wn = lds + ((kt & 1) ^ 1) * (512 * LDH);
;     if (kt + 1 < nk) {
; #pragma unroll
;       for (int i = 0; i < 4; ++i) { *(u4v*)&Wn[lr * LDH + lc + 8 * i] = ra[i]; *(u4v*)&Wn[(256 + lr) * LDH + lc + 8 * i] = rb[i]; }
;     }
;     if (kt + 2 < nk) {
; #pragma unroll
;       for (int i = 0; i < 4; ++i) { ra[i] = *(const u4v*)(AP_ + 8 * i); rb[i] = *(const u4v*)(BP_ + 8 * i); }
;       ao += 64; bo += 64;
;     }
; #pragma unroll
;     for (int ks = 0; ks < 4; ++ks) {
;       h8v af[4], bf[2];
; #pragma unroll
;       for (int i = 0; i < 4; ++i) af[i] = *(const h8v*)&As[(wm * 128 + i * 32 + (lane & 31)) * LDH + ks * 16 + 8 * (lane >> 5)];
; #pragma unroll
;       for (int j = 0; j < 2; ++j) bf[j] = *(const h8v*)&Bs[(wn * 64 + j * 32 + (lane & 31)) * LDH + ks * 16 + 8 * (lane >> 5)];
; #pragma unroll
;       for (int i = 0; i < 4; ++i)
; #pragma unroll
;         for (int j = 0; j < 2; ++j) acc[i][j] = mfma32(bf[j], af[i], acc[i][j]);
;     }
;     __syncthreads();
;   }
	ds_read_b128 v[232:235], v214
	ds_read_b128 v[216:219], v212
	ds_read_b128 v[236:239], v214 offset:4608
	ds_read_b128 v[220:223], v212 offset:4608
	ds_read_b128 v[224:227], v212 offset:9216
	ds_read_b128 v[228:231], v212 offset:13824
	v_mfma_f32_32x32x16_f16 v[98:113], v[208:211], v[240:243], v[98:113]
	v_mfma_f32_32x32x16_f16 v[114:129], v[174:177], v[240:243], v[114:129]
	v_mfma_f32_32x32x16_f16 v[66:81], v[208:211], v[244:247], v[66:81]
	v_mfma_f32_32x32x16_f16 v[82:97], v[174:177], v[244:247], v[82:97]
	v_mfma_f32_32x32x16_f16 v[34:49], v[208:211], v[200:203], v[34:49]
	v_mfma_f32_32x32x16_f16 v[50:65], v[174:177], v[200:203], v[50:65]
	v_mfma_f32_32x32x16_f16 v[2:17], v[208:211], v[204:207], v[2:17]
	v_mfma_f32_32x32x16_f16 v[18:33], v[174:177], v[204:207], v[18:33]
	ds_read_b128 v[208:211], v214 offset:32
	ds_read_b128 v[240:243], v212 offset:32
	ds_read_b128 v[174:177], v214 offset:4640
	ds_read_b128 v[244:247], v212 offset:4640
	ds_read_b128 v[200:203], v212 offset:9248
	ds_read_b128 v[204:207], v212 offset:13856
	s_waitcnt vmcnt(4)
	ds_write_b128 v178, v[134:137]
	ds_write_b128 v178, v[138:141] offset:16
	ds_write_b128 v178, v[142:145] offset:32
	ds_write_b128 v178, v[146:149] offset:48
	global_load_dwordx4 v[134:137], v[130:131], off offset:1664
	global_load_dwordx4 v[138:141], v[130:131], off offset:1680
	global_load_dwordx4 v[142:145], v[130:131], off offset:1696
	global_load_dwordx4 v[146:149], v[130:131], off offset:1712
	s_waitcnt lgkmcnt(14)
	v_mfma_f32_32x32x16_f16 v[98:113], v[232:235], v[216:219], v[98:113]
	s_waitcnt lgkmcnt(13)
	v_mfma_f32_32x32x16_f16 v[114:129], v[236:239], v[216:219], v[114:129]
	s_waitcnt lgkmcnt(12)
	v_mfma_f32_32x32x16_f16 v[66:81], v[232:235], v[220:223], v[66:81]
	v_mfma_f32_32x32x16_f16 v[82:97], v[236:239], v[220:223], v[82:97]
	s_waitcnt lgkmcnt(11)
	v_mfma_f32_32x32x16_f16 v[34:49], v[232:235], v[224:227], v[34:49]
	v_mfma_f32_32x32x16_f16 v[50:65], v[236:239], v[224:227], v[50:65]
	s_waitcnt lgkmcnt(10)
	v_mfma_f32_32x32x16_f16 v[2:17], v[232:235], v[228:231], v[2:17]
	v_mfma_f32_32x32x16_f16 v[18:33], v[236:239], v[228:231], v[18:33]
	ds_read_b128 v[232:235], v214 offset:64
	ds_read_b128 v[216:219], v212 offset:64
	ds_read_b128 v[236:239], v214 offset:4672
	ds_read_b128 v[220:223], v212 offset:4672
	ds_read_b128 v[224:227], v212 offset:9280
	ds_read_b128 v[228:231], v212 offset:13888
	s_waitcnt vmcnt(4)
	ds_write_b128 v178, v[150:153] offset:36864
	ds_write_b128 v178, v[154:157] offset:36880
	ds_write_b128 v178, v[158:161] offset:36896
	ds_write_b128 v178, v[162:165] offset:36912
	global_load_dwordx4 v[150:153], v[248:249], off offset:1664
	global_load_dwordx4 v[154:157], v[248:249], off offset:1680
	global_load_dwordx4 v[158:161], v[248:249], off offset:1696
	global_load_dwordx4 v[162:165], v[248:249], off offset:1712
	s_waitcnt lgkmcnt(15)
	v_mfma_f32_32x32x16_f16 v[98:113], v[208:211], v[240:243], v[98:113]
	s_waitcnt lgkmcnt(15)
	v_mfma_f32_32x32x16_f16 v[114:129], v[174:177], v[240:243], v[114:129]
	s_waitcnt lgkmcnt(15)
	v_mfma_f32_32x32x16_f16 v[66:81], v[208:211], v[244:247], v[66:81]
	v_mfma_f32_32x32x16_f16 v[82:97], v[174:177], v[244:247], v[82:97]
	s_waitcnt lgkmcnt(15)
	v_mfma_f32_32x32x16_f16 v[34:49], v[208:211], v[200:203], v[34:49]
	v_mfma_f32_32x32x16_f16 v[50:65], v[174:177], v[200:203], v[50:65]
	s_waitcnt lgkmcnt(14)
	v_mfma_f32_32x32x16_f16 v[2:17], v[208:211], v[204:207], v[2:17]
	v_mfma_f32_32x32x16_f16 v[18:33], v[174:177], v[204:207], v[18:33]
	ds_read_b128 v[208:211], v214 offset:96
	ds_read_b128 v[240:243], v212 offset:96
	ds_read_b128 v[174:177], v214 offset:4704
	ds_read_b128 v[244:247], v212 offset:4704
	ds_read_b128 v[200:203], v212 offset:9312
	ds_read_b128 v[204:207], v212 offset:13920
	s_waitcnt lgkmcnt(14)
	v_mfma_f32_32x32x16_f16 v[98:113], v[232:235], v[216:219], v[98:113]
	s_waitcnt lgkmcnt(13)
	v_mfma_f32_32x32x16_f16 v[114:129], v[236:239], v[216:219], v[114:129]
	s_waitcnt lgkmcnt(12)
	v_mfma_f32_32x32x16_f16 v[66:81], v[232:235], v[220:223], v[66:81]
	v_mfma_f32_32x32x16_f16 v[82:97], v[236:239], v[220:223], v[82:97]
	s_waitcnt lgkmcnt(11)
	v_mfma_f32_32x32x16_f16 v[34:49], v[232:235], v[224:227], v[34:49]
	v_mfma_f32_32x32x16_f16 v[50:65], v[236:239], v[224:227], v[50:65]
	s_waitcnt lgkmcnt(10)
	v_mfma_f32_32x32x16_f16 v[2:17], v[232:235], v[228:231], v[2:17]
	v_mfma_f32_32x32x16_f16 v[18:33], v[236:239], v[228:231], v[18:33]
	s_waitcnt lgkmcnt(0)
	s_barrier
; DI f16v mfma32(h8v a, h8v b, f16v c) { return __builtin_amdgcn_mfma_f32_32x32x16_f16(a, b, c, 0, 0, 0); }
; template <bool GATHER>
; DI void gemm256_main(const h16* __restrict__ A, int lda, const int* __restrict__ idx, int m0,
;                      const h16* __restrict__ B, int ldb, int n0, int K, h16* lds, f16v (&acc)[4][2]) {
;     ...
;   for (int kt = 0; kt < nk; ++kt) {
;     const h16* As = lds + (kt & 1) * (512 * LDH);
;     const h16* Bs = As + 256 * LDH;
;     h16* Wn = lds + ((kt & 1) ^ 1) * (512 * LDH);
;     if (kt + 1 < nk) {
; #pragma unroll
;       for (int i = 0; i < 4; ++i) { *(u4v*)&Wn[lr * LDH + lc + 8 * i] = ra[i]; *(u4v*)&Wn[(256 + lr) * LDH + lc + 8 * i] = rb[i]; }
;     }
;     if (kt + 2 < nk) {
; #pragma unroll
;       for (int i = 0; i < 4; ++i) { ra[i] = *(const u4v*)(AP_ + 8 * i); rb[i] = *(const u4v*)(BP_ + 8 * i); }
;       ao += 64; bo += 64;
;     }
; #pragma unroll
;     for (int ks = 0; ks < 4; ++ks) {
;       h8v af[4], bf[2];
; #pragma unroll
;       for (int i = 0; i < 4; ++i) af[i] = *(const h8v*)&As[(wm * 128 + i * 32 + (lane & 31)) * LDH + ks * 16 + 8 * (lane >> 5)];
; #pragma unroll
;       for (int j = 0; j < 2; ++j) bf[j] = *(const h8v*)&Bs[(wn * 64 + j * 32 + (lane & 31)) * LDH + ks * 16 + 8 * (lane >> 5)];
; #pragma unroll
;       for (int i = 0; i < 4; ++i)
; #pragma unroll
;         for (int j = 0; j < 2; ++j) acc[i][j] = mfma32(bf[j], af[i], acc[i][j]);
;     }
;     __syncthreads();
;   }
	ds_read_b128 v[232:235], v213
	ds_read_b128 v[216:219], v215
	ds_read_b128 v[236:239], v213 offset:4608
	ds_read_b128 v[220:223], v215 offset:4608
	ds_read_b128 v[224:227], v215 offset:9216
	ds_read_b128 v[228:231], v215 offset:13824
	v_mfma_f32_32x32x16_f16 v[98:113], v[208:211], v[240:243], v[98:113]
	v_mfma_f32_32x32x16_f16 v[114:129], v[174:177], v[240:243], v[114:129]
	v_mfma_f32_32x32x16_f16 v[66:81], v[208:211], v[244:247], v[66:81]
	v_mfma_f32_32x32x16_f16 v[82:97], v[174:177], v[244:247], v[82:97]
	v_mfma_f32_32x32x16_f16 v[34:49], v[208:211], v[200:203], v[34:49]
	v_mfma_f32_32x32x16_f16 v[50:65], v[174:177], v[200:203], v[50:65]
	v_mfma_f32_32x32x16_f16 v[2:17], v[208:211], v[204:207], v[2:17]
	v_mfma_f32_32x32x16_f16 v[18:33], v[174:177], v[204:207], v[18:33]
	ds_read_b128 v[208:211], v213 offset:32
	ds_read_b128 v[240:243], v215 offset:32
	ds_read_b128 v[174:177], v213 offset:4640
	ds_read_b128 v[244:247], v215 offset:4640
	ds_read_b128 v[200:203], v215 offset:9248
	ds_read_b128 v[204:207], v215 offset:13856
	s_waitcnt vmcnt(4)
	ds_write_b128 v179, v[134:137]
	ds_write_b128 v179, v[138:141] offset:16
	ds_write_b128 v179, v[142:145] offset:32
	ds_write_b128 v179, v[146:149] offset:48
	global_load_dwordx4 v[134:137], v[130:131], off offset:1792
	global_load_dwordx4 v[138:141], v[130:131], off offset:1808
	global_load_dwordx4 v[142:145], v[130:131], off offset:1824
	global_load_dwordx4 v[146:149], v[130:131], off offset:1840
	s_waitcnt lgkmcnt(14)
	v_mfma_f32_32x32x16_f16 v[98:113], v[232:235], v[216:219], v[98:113]
	s_waitcnt lgkmcnt(13)
	v_mfma_f32_32x32x16_f16 v[114:129], v[236:239], v[216:219], v[114:129]
	s_waitcnt lgkmcnt(12)
	v_mfma_f32_32x32x16_f16 v[66:81], v[232:235], v[220:223], v[66:81]
	v_mfma_f32_32x32x16_f16 v[82:97], v[236:239], v[220:223], v[82:97]
	s_waitcnt lgkmcnt(11)
	v_mfma_f32_32x32x16_f16 v[34:49], v[232:235], v[224:227], v[34:49]
	v_mfma_f32_32x32x16_f16 v[50:65], v[236:239], v[224:227], v[50:65]
	s_waitcnt lgkmcnt(10)
	v_mfma_f32_32x32x16_f16 v[2:17], v[232:235], v[228:231], v[2:17]
	v_mfma_f32_32x32x16_f16 v[18:33], v[236:239], v[228:231], v[18:33]
	ds_read_b128 v[232:235], v213 offset:64
	ds_read_b128 v[216:219], v215 offset:64
	ds_read_b128 v[236:239], v213 offset:4672
	ds_read_b128 v[220:223], v215 offset:4672
	ds_read_b128 v[224:227], v215 offset:9280
	ds_read_b128 v[228:231], v215 offset:13888
	s_waitcnt vmcnt(4)
	ds_write_b128 v179, v[150:153] offset:36864
	ds_write_b128 v179, v[154:157] offset:36880
	ds_write_b128 v179, v[158:161] offset:36896
	ds_write_b128 v179, v[162:165] offset:36912
	global_load_dwordx4 v[150:153], v[248:249], off offset:1792
	global_load_dwordx4 v[154:157], v[248:249], off offset:1808
	global_load_dwordx4 v[158:161], v[248:249], off offset:1824
	global_load_dwordx4 v[162:165], v[248:249], off offset:1840
	s_waitcnt lgkmcnt(15)
	v_mfma_f32_32x32x16_f16 v[98:113], v[208:211], v[240:243], v[98:113]
	s_waitcnt lgkmcnt(15)
	v_mfma_f32_32x32x16_f16 v[114:129], v[174:177], v[240:243], v[114:129]
	s_waitcnt lgkmcnt(15)
	v_mfma_f32_32x32x16_f16 v[66:81], v[208:211], v[244:247], v[66:81]
	v_mfma_f32_32x32x16_f16 v[82:97], v[174:177], v[244:247], v[82:97]
	s_waitcnt lgkmcnt(15)
	v_mfma_f32_32x32x16_f16 v[34:49], v[208:211], v[200:203], v[34:49]
	v_mfma_f32_32x32x16_f16 v[50:65], v[174:177], v[200:203], v[50:65]
	s_waitcnt lgkmcnt(14)
	v_mfma_f32_32x32x16_f16 v[2:17], v[208:211], v[204:207], v[2:17]
	v_mfma_f32_32x32x16_f16 v[18:33], v[174:177], v[204:207], v[18:33]
	ds_read_b128 v[208:211], v213 offset:96
	ds_read_b128 v[240:243], v215 offset:96
	ds_read_b128 v[174:177], v213 offset:4704
	ds_read_b128 v[244:247], v215 offset:4704
	ds_read_b128 v[200:203], v215 offset:9312
	ds_read_b128 v[204:207], v215 offset:13920
	s_waitcnt lgkmcnt(14)
	v_mfma_f32_32x32x16_f16 v[98:113], v[232:235], v[216:219], v[98:113]
	s_waitcnt lgkmcnt(13)
	v_mfma_f32_32x32x16_f16 v[114:129], v[236:239], v[216:219], v[114:129]
	s_waitcnt lgkmcnt(12)
	v_mfma_f32_32x32x16_f16 v[66:81], v[232:235], v[220:223], v[66:81]
	v_mfma_f32_32x32x16_f16 v[82:97], v[236:239], v[220:223], v[82:97]
	s_waitcnt lgkmcnt(11)
	v_mfma_f32_32x32x16_f16 v[34:49], v[232:235], v[224:227], v[34:49]
	v_mfma_f32_32x32x16_f16 v[50:65], v[236:239], v[224:227], v[50:65]
	s_waitcnt lgkmcnt(10)
	v_mfma_f32_32x32x16_f16 v[2:17], v[232:235], v[228:231], v[2:17]
	v_mfma_f32_32x32x16_f16 v[18:33], v[236:239], v[228:231], v[18:33]
	s_waitcnt lgkmcnt(0)
	s_barrier
; DI f16v mfma32(h8v a, h8v b, f16v c) { return __builtin_amdgcn_mfma_f32_32x32x16_f16(a, b, c, 0, 0, 0); }
; template <bool GATHER>
; DI void gemm256_main(const h16* __restrict__ A, int lda, const int* __restrict__ idx, int m0,
;                      const h16* __restrict__ B, int ldb, int n0, int K, h16* lds, f16v (&acc)[4][2]) {
;     ...
;   for (int kt = 0; kt < nk; ++kt) {
;     const h16* As = lds + (kt & 1) * (512 * LDH);
;     const h16* Bs = As + 256 * LDH;
;     h16* Wn = lds + ((kt & 1) ^ 1) * (512 * LDH);
;     if (kt + 1 < nk) {
; #pragma unroll
;       for (int i = 0; i < 4; ++i) { *(u4v*)&Wn[lr * LDH + lc + 8 * i] = ra[i]; *(u4v*)&Wn[(256 + lr) * LDH + lc + 8 * i] = rb[i]; }
;     }
;     if (kt + 2 < nk) {
; #pragma unroll
;       for (int i = 0; i < 4; ++i) { ra[i] = *(const u4v*)(AP_ + 8 * i); rb[i] = *(const u4v*)(BP_ + 8 * i); }
;       ao += 64; bo += 64;
;     }
; #pragma unroll
;     for (int ks = 0; ks < 4; ++ks) {
;       h8v af[4], bf[2];
; #pragma unroll
;       for (int i = 0; i < 4; ++i) af[i] = *(const h8v*)&As[(wm * 128 + i * 32 + (lane & 31)) * LDH + ks * 16 + 8 * (lane >> 5)];
; #pragma unroll
;       for (int j = 0; j < 2; ++j) bf[j] = *(const h8v*)&Bs[(wn * 64 + j * 32 + (lane & 31)) * LDH + ks * 16 + 8 * (lane >> 5)];
; #pragma unroll
;       for (int i = 0; i < 4; ++i)
; #pragma unroll
;         for (int j = 0; j < 2; ++j) acc[i][j] = mfma32(bf[j], af[i], acc[i][j]);
;     }
;     __syncthreads();
;   }
	ds_read_b128 v[232:235], v214
	ds_read_b128 v[216:219], v212
	ds_read_b128 v[236:239], v214 offset:4608
	ds_read_b128 v[220:223], v212 offset:4608
	ds_read_b128 v[224:227], v212 offset:9216
	ds_read_b128 v[228:231], v212 offset:13824
	v_mfma_f32_32x32x16_f16 v[98:113], v[208:211], v[240:243], v[98:113]
	v_mfma_f32_32x32x16_f16 v[114:129], v[174:177], v[240:243], v[114:129]
	v_mfma_f32_32x32x16_f16 v[66:81], v[208:211], v[244:247], v[66:81]
	v_mfma_f32_32x32x16_f16 v[82:97], v[174:177], v[244:247], v[82:97]
	v_mfma_f32_32x32x16_f16 v[34:49], v[208:211], v[200:203], v[34:49]
	v_mfma_f32_32x32x16_f16 v[50:65], v[174:177], v[200:203], v[50:65]
	v_mfma_f32_32x32x16_f16 v[2:17], v[208:211], v[204:207], v[2:17]
	v_mfma_f32_32x32x16_f16 v[18:33], v[174:177], v[204:207], v[18:33]
	ds_read_b128 v[208:211], v214 offset:32
	ds_read_b128 v[240:243], v212 offset:32
	ds_read_b128 v[174:177], v214 offset:4640
	ds_read_b128 v[244:247], v212 offset:4640
	ds_read_b128 v[200:203], v212 offset:9248
	ds_read_b128 v[204:207], v212 offset:13856
	s_waitcnt vmcnt(4)
	ds_write_b128 v178, v[134:137]
	ds_write_b128 v178, v[138:141] offset:16
	ds_write_b128 v178, v[142:145] offset:32
	ds_write_b128 v178, v[146:149] offset:48
	global_load_dwordx4 v[134:137], v[130:131], off offset:1920
	global_load_dwordx4 v[138:141], v[130:131], off offset:1936
	global_load_dwordx4 v[142:145], v[130:131], off offset:1952
	global_load_dwordx4 v[146:149], v[130:131], off offset:1968
	s_waitcnt lgkmcnt(14)
	v_mfma_f32_32x32x16_f16 v[98:113], v[232:235], v[216:219], v[98:113]
	s_waitcnt lgkmcnt(13)
	v_mfma_f32_32x32x16_f16 v[114:129], v[236:239], v[216:219], v[114:129]
	s_waitcnt lgkmcnt(12)
	v_mfma_f32_32x32x16_f16 v[66:81], v[232:235], v[220:223], v[66:81]
	v_mfma_f32_32x32x16_f16 v[82:97], v[236:239], v[220:223], v[82:97]
	s_waitcnt lgkmcnt(11)
	v_mfma_f32_32x32x16_f16 v[34:49], v[232:235], v[224:227], v[34:49]
	v_mfma_f32_32x32x16_f16 v[50:65], v[236:239], v[224:227], v[50:65]
	s_waitcnt lgkmcnt(10)
	v_mfma_f32_32x32x16_f16 v[2:17], v[232:235], v[228:231], v[2:17]
	v_mfma_f32_32x32x16_f16 v[18:33], v[236:239], v[228:231], v[18:33]
	ds_read_b128 v[232:235], v214 offset:64
	ds_read_b128 v[216:219], v212 offset:64
	ds_read_b128 v[236:239], v214 offset:4672
	ds_read_b128 v[220:223], v212 offset:4672
	ds_read_b128 v[224:227], v212 offset:9280
	ds_read_b128 v[228:231], v212 offset:13888
	s_waitcnt vmcnt(4)
	ds_write_b128 v178, v[150:153] offset:36864
	ds_write_b128 v178, v[154:157] offset:36880
	ds_write_b128 v178, v[158:161] offset:36896
	ds_write_b128 v178, v[162:165] offset:36912
	global_load_dwordx4 v[150:153], v[248:249], off offset:1920
	global_load_dwordx4 v[154:157], v[248:249], off offset:1936
	global_load_dwordx4 v[158:161], v[248:249], off offset:1952
	global_load_dwordx4 v[162:165], v[248:249], off offset:1968
	s_waitcnt lgkmcnt(15)
	v_mfma_f32_32x32x16_f16 v[98:113], v[208:211], v[240:243], v[98:113]
	s_waitcnt lgkmcnt(15)
	v_mfma_f32_32x32x16_f16 v[114:129], v[174:177], v[240:243], v[114:129]
	s_waitcnt lgkmcnt(15)
	v_mfma_f32_32x32x16_f16 v[66:81], v[208:211], v[244:247], v[66:81]
	v_mfma_f32_32x32x16_f16 v[82:97], v[174:177], v[244:247], v[82:97]
	s_waitcnt lgkmcnt(15)
	v_mfma_f32_32x32x16_f16 v[34:49], v[208:211], v[200:203], v[34:49]
	v_mfma_f32_32x32x16_f16 v[50:65], v[174:177], v[200:203], v[50:65]
	s_waitcnt lgkmcnt(14)
	v_mfma_f32_32x32x16_f16 v[2:17], v[208:211], v[204:207], v[2:17]
	v_mfma_f32_32x32x16_f16 v[18:33], v[174:177], v[204:207], v[18:33]
	ds_read_b128 v[208:211], v214 offset:96
	ds_read_b128 v[240:243], v212 offset:96
	ds_read_b128 v[174:177], v214 offset:4704
	ds_read_b128 v[244:247], v212 offset:4704
	ds_read_b128 v[200:203], v212 offset:9312
	ds_read_b128 v[204:207], v212 offset:13920
	s_waitcnt lgkmcnt(14)
	v_mfma_f32_32x32x16_f16 v[98:113], v[232:235], v[216:219], v[98:113]
	s_waitcnt lgkmcnt(13)
	v_mfma_f32_32x32x16_f16 v[114:129], v[236:239], v[216:219], v[114:129]
	s_waitcnt lgkmcnt(12)
	v_mfma_f32_32x32x16_f16 v[66:81], v[232:235], v[220:223], v[66:81]
	v_mfma_f32_32x32x16_f16 v[82:97], v[236:239], v[220:223], v[82:97]
	s_waitcnt lgkmcnt(11)
	v_mfma_f32_32x32x16_f16 v[34:49], v[232:235], v[224:227], v[34:49]
	v_mfma_f32_32x32x16_f16 v[50:65], v[236:239], v[224:227], v[50:65]
	s_waitcnt lgkmcnt(10)
	v_mfma_f32_32x32x16_f16 v[2:17], v[232:235], v[228:231], v[2:17]
	v_mfma_f32_32x32x16_f16 v[18:33], v[236:239], v[228:231], v[18:33]
	s_waitcnt lgkmcnt(0)
	s_barrier
; DI f16v mfma32(h8v a, h8v b, f16v c) { return __builtin_amdgcn_mfma_f32_32x32x16_f16(a, b, c, 0, 0, 0); }
; template <bool GATHER>
; DI void gemm256_main(const h16* __restrict__ A, int lda, const int* __restrict__ idx, int m0,
;                      const h16* __restrict__ B, int ldb, int n0, int K, h16* lds, f16v (&acc)[4][2]) {
;     ...
;   for (int kt = 0; kt < nk; ++kt) {
;     const h16* As = lds + (kt & 1) * (512 * LDH);
;     const h16* Bs = As + 256 * LDH;
;     h16* Wn = lds + ((kt & 1) ^ 1) * (512 * LDH);
;     if (kt + 1 < nk) {
; #pragma unroll
;       for (int i = 0; i < 4; ++i) { *(u4v*)&Wn[lr * LDH + lc + 8 * i] = ra[i]; *(u4v*)&Wn[(256 + lr) * LDH + lc + 8 * i] = rb[i]; }
;     }
;     if (kt + 2 < nk) {
; #pragma unroll
;       for (int i = 0; i < 4; ++i) { ra[i] = *(const u4v*)(AP_ + 8 * i); rb[i] = *(const u4v*)(BP_ + 8 * i); }
;       ao += 64; bo += 64;
;     }
; #pragma unroll
;     for (int ks = 0; ks < 4; ++ks) {
;       h8v af[4], bf[2];
; #pragma unroll
;       for (int i = 0; i < 4; ++i) af[i] = *(const h8v*)&As[(wm * 128 + i * 32 + (lane & 31)) * LDH + ks * 16 + 8 * (lane >> 5)];
; #pragma unroll
;       for (int j = 0; j < 2; ++j) bf[j] = *(const h8v*)&Bs[(wn * 64 + j * 32 + (lane & 31)) * LDH + ks * 16 + 8 * (lane >> 5)];
; #pragma unroll
;       for (int i = 0; i < 4; ++i)
; #pragma unroll
;         for (int j = 0; j < 2; ++j) acc[i][j] = mfma32(bf[j], af[i], acc[i][j]);
;     }
;     __syncthreads();
;   }
	ds_read_b128 v[232:235], v213
	ds_read_b128 v[216:219], v215
	ds_read_b128 v[236:239], v213 offset:4608
	ds_read_b128 v[220:223], v215 offset:4608
	ds_read_b128 v[224:227], v215 offset:9216
	ds_read_b128 v[228:231], v215 offset:13824
	v_mfma_f32_32x32x16_f16 v[98:113], v[208:211], v[240:243], v[98:113]
	v_mfma_f32_32x32x16_f16 v[114:129], v[174:177], v[240:243], v[114:129]
	v_mfma_f32_32x32x16_f16 v[66:81], v[208:211], v[244:247], v[66:81]
	v_mfma_f32_32x32x16_f16 v[82:97], v[174:177], v[244:247], v[82:97]
	v_mfma_f32_32x32x16_f16 v[34:49], v[208:211], v[200:203], v[34:49]
	v_mfma_f32_32x32x16_f16 v[50:65], v[174:177], v[200:203], v[50:65]
	v_mfma_f32_32x32x16_f16 v[2:17], v[208:211], v[204:207], v[2:17]
	v_mfma_f32_32x32x16_f16 v[18:33], v[174:177], v[204:207], v[18:33]
	ds_read_b128 v[208:211], v213 offset:32
	ds_read_b128 v[240:243], v215 offset:32
	ds_read_b128 v[174:177], v213 offset:4640
	ds_read_b128 v[244:247], v215 offset:4640
	ds_read_b128 v[200:203], v215 offset:9248
	ds_read_b128 v[204:207], v215 offset:13856
	s_waitcnt vmcnt(4)
	ds_write_b128 v179, v[134:137]
	ds_write_b128 v179, v[138:141] offset:16
	ds_write_b128 v179, v[142:145] offset:32
	ds_write_b128 v179, v[146:149] offset:48
	s_waitcnt lgkmcnt(14)
	v_mfma_f32_32x32x16_f16 v[98:113], v[232:235], v[216:219], v[98:113]
	s_waitcnt lgkmcnt(13)
	v_mfma_f32_32x32x16_f16 v[114:129], v[236:239], v[216:219], v[114:129]
	s_waitcnt lgkmcnt(12)
	v_mfma_f32_32x32x16_f16 v[66:81], v[232:235], v[220:223], v[66:81]
	v_mfma_f32_32x32x16_f16 v[82:97], v[236:239], v[220:223], v[82:97]
	s_waitcnt lgkmcnt(11)
	v_mfma_f32_32x32x16_f16 v[34:49], v[232:235], v[224:227], v[34:49]
	v_mfma_f32_32x32x16_f16 v[50:65], v[236:239], v[224:227], v[50:65]
	s_waitcnt lgkmcnt(10)
	v_mfma_f32_32x32x16_f16 v[2:17], v[232:235], v[228:231], v[2:17]
	v_mfma_f32_32x32x16_f16 v[18:33], v[236:239], v[228:231], v[18:33]
	ds_read_b128 v[232:235], v213 offset:64
	ds_read_b128 v[216:219], v215 offset:64
	ds_read_b128 v[236:239], v213 offset:4672
	ds_read_b128 v[220:223], v215 offset:4672
	ds_read_b128 v[224:227], v215 offset:9280
	ds_read_b128 v[228:231], v215 offset:13888
	s_waitcnt vmcnt(0)
	ds_write_b128 v179, v[150:153] offset:36864
	ds_write_b128 v179, v[154:157] offset:36880
	ds_write_b128 v179, v[158:161] offset:36896
	ds_write_b128 v179, v[162:165] offset:36912
	s_waitcnt lgkmcnt(15)
	v_mfma_f32_32x32x16_f16 v[98:113], v[208:211], v[240:243], v[98:113]
	s_waitcnt lgkmcnt(15)
	v_mfma_f32_32x32x16_f16 v[114:129], v[174:177], v[240:243], v[114:129]
	s_waitcnt lgkmcnt(15)
	v_mfma_f32_32x32x16_f16 v[66:81], v[208:211], v[244:247], v[66:81]
	v_mfma_f32_32x32x16_f16 v[82:97], v[174:177], v[244:247], v[82:97]
	s_waitcnt lgkmcnt(15)
	v_mfma_f32_32x32x16_f16 v[34:49], v[208:211], v[200:203], v[34:49]
	v_mfma_f32_32x32x16_f16 v[50:65], v[174:177], v[200:203], v[50:65]
	s_waitcnt lgkmcnt(14)
	v_mfma_f32_32x32x16_f16 v[2:17], v[208:211], v[204:207], v[2:17]
	v_mfma_f32_32x32x16_f16 v[18:33], v[174:177], v[204:207], v[18:33]
	ds_read_b128 v[208:211], v213 offset:96
	ds_read_b128 v[240:243], v215 offset:96
	ds_read_b128 v[174:177], v213 offset:4704
	ds_read_b128 v[244:247], v215 offset:4704
	ds_read_b128 v[200:203], v215 offset:9312
	ds_read_b128 v[204:207], v215 offset:13920
	s_waitcnt lgkmcnt(14)
	v_mfma_f32_32x32x16_f16 v[98:113], v[232:235], v[216:219], v[98:113]
	s_waitcnt lgkmcnt(13)
	v_mfma_f32_32x32x16_f16 v[114:129], v[236:239], v[216:219], v[114:129]
	s_waitcnt lgkmcnt(12)
	v_mfma_f32_32x32x16_f16 v[66:81], v[232:235], v[220:223], v[66:81]
	v_mfma_f32_32x32x16_f16 v[82:97], v[236:239], v[220:223], v[82:97]
	s_waitcnt lgkmcnt(11)
	v_mfma_f32_32x32x16_f16 v[34:49], v[232:235], v[224:227], v[34:49]
	v_mfma_f32_32x32x16_f16 v[50:65], v[236:239], v[224:227], v[50:65]
	s_waitcnt lgkmcnt(10)
	v_mfma_f32_32x32x16_f16 v[2:17], v[232:235], v[228:231], v[2:17]
	v_mfma_f32_32x32x16_f16 v[18:33], v[236:239], v[228:231], v[18:33]
	s_waitcnt lgkmcnt(0)
	s_barrier
	ds_read_b128 v[232:235], v214
	ds_read_b128 v[216:219], v212
	ds_read_b128 v[236:239], v214 offset:4608
	ds_read_b128 v[220:223], v212 offset:4608
	ds_read_b128 v[224:227], v212 offset:9216
	ds_read_b128 v[228:231], v212 offset:13824
	v_mfma_f32_32x32x16_f16 v[98:113], v[208:211], v[240:243], v[98:113]
	v_mfma_f32_32x32x16_f16 v[114:129], v[174:177], v[240:243], v[114:129]
	v_mfma_f32_32x32x16_f16 v[66:81], v[208:211], v[244:247], v[66:81]
	v_mfma_f32_32x32x16_f16 v[82:97], v[174:177], v[244:247], v[82:97]
	v_mfma_f32_32x32x16_f16 v[34:49], v[208:211], v[200:203], v[34:49]
	v_mfma_f32_32x32x16_f16 v[50:65], v[174:177], v[200:203], v[50:65]
	v_mfma_f32_32x32x16_f16 v[2:17], v[208:211], v[204:207], v[2:17]
	v_mfma_f32_32x32x16_f16 v[18:33], v[174:177], v[204:207], v[18:33]
	ds_read_b128 v[208:211], v214 offset:32
	ds_read_b128 v[240:243], v212 offset:32
	ds_read_b128 v[174:177], v214 offset:4640
	ds_read_b128 v[244:247], v212 offset:4640
	ds_read_b128 v[200:203], v212 offset:9248
	ds_read_b128 v[204:207], v212 offset:13856
	s_waitcnt lgkmcnt(10)
	v_mfma_f32_32x32x16_f16 v[98:113], v[232:235], v[216:219], v[98:113]
	s_waitcnt lgkmcnt(9)
	v_mfma_f32_32x32x16_f16 v[114:129], v[236:239], v[216:219], v[114:129]
	s_waitcnt lgkmcnt(8)
	v_mfma_f32_32x32x16_f16 v[66:81], v[232:235], v[220:223], v[66:81]
	v_mfma_f32_32x32x16_f16 v[82:97], v[236:239], v[220:223], v[82:97]
	s_waitcnt lgkmcnt(7)
	v_mfma_f32_32x32x16_f16 v[34:49], v[232:235], v[224:227], v[34:49]
	v_mfma_f32_32x32x16_f16 v[50:65], v[236:239], v[224:227], v[50:65]
	s_waitcnt lgkmcnt(6)
; DI float silu_(float x) { return x / (1.f + __expf(-x)); }
; DI f16v mfma32(h8v a, h8v b, f16v c) { return __builtin_amdgcn_mfma_f32_32x32x16_f16(a, b, c, 0, 0, 0); }
; template <bool GATHER>
; DI void gemm256_main(const h16* __restrict__ A, int lda, const int* __restrict__ idx, int m0,
;                      const h16* __restrict__ B, int ldb, int n0, int K, h16* lds, f16v (&acc)[4][2]) {
;     ...
; #pragma unroll
;     for (int ks = 0; ks < 4; ++ks) {
;       h8v af[4], bf[2];
; #pragma unroll
;       for (int i = 0; i < 4; ++i) af[i] = *(const h8v*)&As[(wm * 128 + i * 32 + (lane & 31)) * LDH + ks * 16 + 8 * (lane >> 5)];
; #pragma unroll
;       for (int j = 0; j < 2; ++j) bf[j] = *(const h8v*)&Bs[(wn * 64 + j * 32 + (lane & 31)) * LDH + ks * 16 + 8 * (lane >> 5)];
; #pragma unroll
;       for (int i = 0; i < 4; ++i)
; #pragma unroll
;         for (int j = 0; j < 2; ++j) acc[i][j] = mfma32(bf[j], af[i], acc[i][j]);
;     }
; DI void phase_ffn1_dense(const Params& p, int bid, int nb, h16* lds) {
;     ...
;     gemm256_epilogue(acc, m0, n0, [&](int m, int n, f4v v0, f4v v1) {
;       f4v hq;
; #pragma unroll
;       for (int i = 0; i < 4; ++i) hq[i] = silu_(v0[i]) * v1[i];
;       st_h4(&H[(size_t)m * 2816 + (n >> 6) * 32 + (n & 31)], hq);
;     });
	v_mfma_f32_32x32x16_f16 v[2:17], v[232:235], v[228:231], v[2:17]
	v_mfma_f32_32x32x16_f16 v[18:33], v[236:239], v[228:231], v[18:33]
	ds_read_b128 v[232:235], v214 offset:64
	ds_read_b128 v[216:219], v212 offset:64
	ds_read_b128 v[236:239], v214 offset:4672
	ds_read_b128 v[220:223], v212 offset:4672
	ds_read_b128 v[224:227], v212 offset:9280
	ds_read_b128 v[228:231], v212 offset:13888
	s_waitcnt lgkmcnt(10)
	v_mfma_f32_32x32x16_f16 v[98:113], v[208:211], v[240:243], v[98:113]
	s_waitcnt lgkmcnt(9)
	v_mfma_f32_32x32x16_f16 v[114:129], v[174:177], v[240:243], v[114:129]
	s_waitcnt lgkmcnt(8)
	v_mfma_f32_32x32x16_f16 v[66:81], v[208:211], v[244:247], v[66:81]
	v_mfma_f32_32x32x16_f16 v[82:97], v[174:177], v[244:247], v[82:97]
	s_waitcnt lgkmcnt(7)
	v_mfma_f32_32x32x16_f16 v[34:49], v[208:211], v[200:203], v[34:49]
	v_mfma_f32_32x32x16_f16 v[50:65], v[174:177], v[200:203], v[50:65]
	s_waitcnt lgkmcnt(6)
	v_mfma_f32_32x32x16_f16 v[2:17], v[208:211], v[204:207], v[2:17]
	v_mfma_f32_32x32x16_f16 v[18:33], v[174:177], v[204:207], v[18:33]
	ds_read_b128 v[208:211], v214 offset:96
	ds_read_b128 v[240:243], v212 offset:96
	ds_read_b128 v[174:177], v214 offset:4704
	ds_read_b128 v[244:247], v212 offset:4704
	ds_read_b128 v[200:203], v212 offset:9312
	ds_read_b128 v[204:207], v212 offset:13920
	s_waitcnt lgkmcnt(10)
	v_mfma_f32_32x32x16_f16 v[98:113], v[232:235], v[216:219], v[98:113]
	s_waitcnt lgkmcnt(9)
	v_mfma_f32_32x32x16_f16 v[114:129], v[236:239], v[216:219], v[114:129]
	s_waitcnt lgkmcnt(8)
	v_mfma_f32_32x32x16_f16 v[66:81], v[232:235], v[220:223], v[66:81]
	v_mfma_f32_32x32x16_f16 v[82:97], v[236:239], v[220:223], v[82:97]
	s_waitcnt lgkmcnt(7)
	v_mfma_f32_32x32x16_f16 v[34:49], v[232:235], v[224:227], v[34:49]
	v_mfma_f32_32x32x16_f16 v[50:65], v[236:239], v[224:227], v[50:65]
	s_waitcnt lgkmcnt(6)
	v_mfma_f32_32x32x16_f16 v[2:17], v[232:235], v[228:231], v[2:17]
	v_mfma_f32_32x32x16_f16 v[18:33], v[236:239], v[228:231], v[18:33]
	s_waitcnt lgkmcnt(0)
	v_mfma_f32_32x32x16_f16 v[98:113], v[208:211], v[240:243], v[98:113]
	v_mfma_f32_32x32x16_f16 v[114:129], v[174:177], v[240:243], v[114:129]
	v_mfma_f32_32x32x16_f16 v[66:81], v[208:211], v[244:247], v[66:81]
	v_mfma_f32_32x32x16_f16 v[82:97], v[174:177], v[244:247], v[82:97]
	v_mfma_f32_32x32x16_f16 v[34:49], v[208:211], v[200:203], v[34:49]
	v_mfma_f32_32x32x16_f16 v[50:65], v[174:177], v[200:203], v[50:65]
	v_mfma_f32_32x32x16_f16 v[2:17], v[208:211], v[204:207], v[2:17]
	v_mfma_f32_32x32x16_f16 v[18:33], v[174:177], v[204:207], v[18:33]
	s_nop 15
	v_mov_b32_e32 v192, 0x7f800000
	v_mov_b32_e32 v193, 0x7fc00000
	v_mov_b32_e32 v194, 0xff800000
	v_mov_b32_e32 v204, 0x7fffec00
	v_mov_b32_e32 v205, 0xff7fc99e
	v_mov_b32_e32 v206, 0x840000
	v_mov_b32_e32 v207, 0xb00000
	v_mov_b32_e32 v208, 0xdc0000
	v_mov_b32_e32 v209, 0x1080000
	v_mov_b32_e32 v210, 0x1340000
	v_mov_b32_e32 v211, 0x420000
	v_mov_b32_e32 v212, 0x580000
	v_mov_b32_e32 v213, 0x6e0000
	v_mov_b32_e32 v214, 0x9a0000
	s_barrier
	v_readfirstlane_b32 s66, v180
	s_sub_i32 s69, s2, s5
	s_mov_b32 s65, s4
	s_lshr_b32 s66, s66, 6
	s_and_b32 s67, s66, 3
	s_lshr_b32 s68, s66, 2
	s_lshr_b32 s70, s69, 1
	s_lshl_b32 s67, s67, 5
	s_add_i32 s70, s70, s67
	s_lshl_b32 s71, s68, 7
	s_add_i32 s71, s71, s65
	s_mul_i32 s72, s66, 0x2800
	s_add_i32 s72, s72, 16
	s_mov_b32 s73, 0x1600
	v_and_b32_e32 v146, 63, v180
	v_and_b32_e32 v148, 31, v146
	v_lshrrev_b32_e32 v147, 5, v146
	v_mul_u32_u24_e32 v130, 0x50, v148
	v_lshl_add_u32 v130, v147, 3, v130
	v_add_u32_e32 v130, s72, v130
	v_lshrrev_b32_e32 v149, 2, v146
	v_and_b32_e32 v138, 3, v146
	v_mul_u32_u24_e32 v131, 0x50, v149
	v_lshl_add_u32 v131, v138, 4, v131
	v_add_u32_e32 v131, s72, v131
	v_add_u32_e32 v140, s71, v149
	v_lshl_add_u32 v138, v138, 3, s70
	v_mov_b64_e32 v[132:133], s[0:1]
	v_mad_u64_u32 v[132:133], s[74:75], v140, s73, v[132:133]
	v_lshlrev_b32_e32 v138, 1, v138
	v_mov_b32_e32 v139, v0
	v_lshl_add_u64 v[132:133], v[132:133], 0, v[138:139]
	s_mov_b32 s76, 0x16000
	s_mov_b32 s77, 0
	v_mul_f32_e32 v232, 0xbfb8aa3b, v98
	v_mul_f32_e32 v233, 0xbfb8aa3b, v99
	v_mul_f32_e32 v234, 0xbfb8aa3b, v100
	v_mul_f32_e32 v235, 0xbfb8aa3b, v101
	v_exp_f32_e32 v232, v232
	v_exp_f32_e32 v233, v233
	v_exp_f32_e32 v234, v234
	v_exp_f32_e32 v235, v235
	v_add_f32_e32 v232, 1.0, v232
	v_add_f32_e32 v233, 1.0, v233
	v_add_f32_e32 v234, 1.0, v234
	v_add_f32_e32 v235, 1.0, v235
	v_rcp_f32_e32 v232, v232
	v_rcp_f32_e32 v233, v233
	v_rcp_f32_e32 v234, v234
	v_rcp_f32_e32 v235, v235
	v_mul_f32_e32 v98, v98, v232
	v_mul_f32_e32 v99, v99, v233
	v_mul_f32_e32 v100, v100, v234
	v_mul_f32_e32 v101, v101, v235
	v_mul_f32_e32 v98, v98, v114
	v_mul_f32_e32 v99, v99, v115
	v_mul_f32_e32 v100, v100, v116
	v_mul_f32_e32 v101, v101, v117
	v_cvt_pk_f16_f32 v138, v98, v99
	v_cvt_pk_f16_f32 v139, v100, v101
	ds_write_b64 v130, v[138:139] offset:0
	v_mul_f32_e32 v232, 0xbfb8aa3b, v102
	v_mul_f32_e32 v233, 0xbfb8aa3b, v103
	v_mul_f32_e32 v234, 0xbfb8aa3b, v104
	v_mul_f32_e32 v235, 0xbfb8aa3b, v105
	v_exp_f32_e32 v232, v232
	v_exp_f32_e32 v233, v233
	v_exp_f32_e32 v234, v234
	v_exp_f32_e32 v235, v235
	v_add_f32_e32 v232, 1.0, v232
	v_add_f32_e32 v233, 1.0, v233
	v_add_f32_e32 v234, 1.0, v234
	v_add_f32_e32 v235, 1.0, v235
	v_rcp_f32_e32 v232, v232
	v_rcp_f32_e32 v233, v233
	v_rcp_f32_e32 v234, v234
	v_rcp_f32_e32 v235, v235
	v_mul_f32_e32 v102, v102, v232
	v_mul_f32_e32 v103, v103, v233
	v_mul_f32_e32 v104, v104, v234
	v_mul_f32_e32 v105, v105, v235
	v_mul_f32_e32 v102, v102, v118
	v_mul_f32_e32 v103, v103, v119
	v_mul_f32_e32 v104, v104, v120
	v_mul_f32_e32 v105, v105, v121
	v_cvt_pk_f16_f32 v140, v102, v103
	v_cvt_pk_f16_f32 v141, v104, v105
; DI float silu_(float x) { return x / (1.f + __expf(-x)); }
; DI void phase_ffn1_dense(const Params& p, int bid, int nb, h16* lds) {
;     ...
;     gemm256_epilogue(acc, m0, n0, [&](int m, int n, f4v v0, f4v v1) {
;       f4v hq;
; #pragma unroll
;       for (int i = 0; i < 4; ++i) hq[i] = silu_(v0[i]) * v1[i];
;       st_h4(&H[(size_t)m * 2816 + (n >> 6) * 32 + (n & 31)], hq);
;     });
	ds_write_b64 v130, v[140:141] offset:16
	v_mul_f32_e32 v232, 0xbfb8aa3b, v106
	v_mul_f32_e32 v233, 0xbfb8aa3b, v107
	v_mul_f32_e32 v234, 0xbfb8aa3b, v108
	v_mul_f32_e32 v235, 0xbfb8aa3b, v109
	v_exp_f32_e32 v232, v232
	v_exp_f32_e32 v233, v233
	v_exp_f32_e32 v234, v234
	v_exp_f32_e32 v235, v235
	v_add_f32_e32 v232, 1.0, v232
	v_add_f32_e32 v233, 1.0, v233
	v_add_f32_e32 v234, 1.0, v234
	v_add_f32_e32 v235, 1.0, v235
	v_rcp_f32_e32 v232, v232
	v_rcp_f32_e32 v233, v233
	v_rcp_f32_e32 v234, v234
	v_rcp_f32_e32 v235, v235
	v_mul_f32_e32 v106, v106, v232
	v_mul_f32_e32 v107, v107, v233
	v_mul_f32_e32 v108, v108, v234
	v_mul_f32_e32 v109, v109, v235
	v_mul_f32_e32 v106, v106, v122
	v_mul_f32_e32 v107, v107, v123
	v_mul_f32_e32 v108, v108, v124
	v_mul_f32_e32 v109, v109, v125
	v_cvt_pk_f16_f32 v142, v106, v107
	v_cvt_pk_f16_f32 v143, v108, v109
	ds_write_b64 v130, v[142:143] offset:32
	v_mul_f32_e32 v232, 0xbfb8aa3b, v110
	v_mul_f32_e32 v233, 0xbfb8aa3b, v111
	v_mul_f32_e32 v234, 0xbfb8aa3b, v112
	v_mul_f32_e32 v235, 0xbfb8aa3b, v113
	v_exp_f32_e32 v232, v232
	v_exp_f32_e32 v233, v233
	v_exp_f32_e32 v234, v234
	v_exp_f32_e32 v235, v235
	v_add_f32_e32 v232, 1.0, v232
	v_add_f32_e32 v233, 1.0, v233
	v_add_f32_e32 v234, 1.0, v234
	v_add_f32_e32 v235, 1.0, v235
	v_rcp_f32_e32 v232, v232
	v_rcp_f32_e32 v233, v233
	v_rcp_f32_e32 v234, v234
	v_rcp_f32_e32 v235, v235
	v_mul_f32_e32 v110, v110, v232
	v_mul_f32_e32 v111, v111, v233
	v_mul_f32_e32 v112, v112, v234
	v_mul_f32_e32 v113, v113, v235
	v_mul_f32_e32 v110, v110, v126
	v_mul_f32_e32 v111, v111, v127
	v_mul_f32_e32 v112, v112, v128
	v_mul_f32_e32 v113, v113, v129
	v_cvt_pk_f16_f32 v144, v110, v111
	v_cvt_pk_f16_f32 v145, v112, v113
	ds_write_b64 v130, v[144:145] offset:48
	v_mul_f32_e32 v232, 0xbfb8aa3b, v66
	v_mul_f32_e32 v233, 0xbfb8aa3b, v67
	v_mul_f32_e32 v234, 0xbfb8aa3b, v68
	v_mul_f32_e32 v235, 0xbfb8aa3b, v69
	v_exp_f32_e32 v232, v232
	v_exp_f32_e32 v233, v233
	v_exp_f32_e32 v234, v234
	v_exp_f32_e32 v235, v235
	v_add_f32_e32 v232, 1.0, v232
	v_add_f32_e32 v233, 1.0, v233
	v_add_f32_e32 v234, 1.0, v234
	v_add_f32_e32 v235, 1.0, v235
	v_rcp_f32_e32 v232, v232
	v_rcp_f32_e32 v233, v233
	v_rcp_f32_e32 v234, v234
	v_rcp_f32_e32 v235, v235
	v_mul_f32_e32 v66, v66, v232
	v_mul_f32_e32 v67, v67, v233
	v_mul_f32_e32 v68, v68, v234
	v_mul_f32_e32 v69, v69, v235
	v_mul_f32_e32 v66, v66, v82
	v_mul_f32_e32 v67, v67, v83
	v_mul_f32_e32 v68, v68, v84
	v_mul_f32_e32 v69, v69, v85
	v_cvt_pk_f16_f32 v138, v66, v67
	v_cvt_pk_f16_f32 v139, v68, v69
	ds_write_b64 v130, v[138:139] offset:2560
	v_mul_f32_e32 v232, 0xbfb8aa3b, v70
	v_mul_f32_e32 v233, 0xbfb8aa3b, v71
	v_mul_f32_e32 v234, 0xbfb8aa3b, v72
	v_mul_f32_e32 v235, 0xbfb8aa3b, v73
	v_exp_f32_e32 v232, v232
	v_exp_f32_e32 v233, v233
	v_exp_f32_e32 v234, v234
	v_exp_f32_e32 v235, v235
	v_add_f32_e32 v232, 1.0, v232
	v_add_f32_e32 v233, 1.0, v233
	v_add_f32_e32 v234, 1.0, v234
	v_add_f32_e32 v235, 1.0, v235
	v_rcp_f32_e32 v232, v232
	v_rcp_f32_e32 v233, v233
	v_rcp_f32_e32 v234, v234
	v_rcp_f32_e32 v235, v235
	v_mul_f32_e32 v70, v70, v232
	v_mul_f32_e32 v71, v71, v233
	v_mul_f32_e32 v72, v72, v234
	v_mul_f32_e32 v73, v73, v235
	v_mul_f32_e32 v70, v70, v86
	v_mul_f32_e32 v71, v71, v87
	v_mul_f32_e32 v72, v72, v88
	v_mul_f32_e32 v73, v73, v89
	v_cvt_pk_f16_f32 v140, v70, v71
	v_cvt_pk_f16_f32 v141, v72, v73
	ds_write_b64 v130, v[140:141] offset:2576
	v_mul_f32_e32 v232, 0xbfb8aa3b, v74
	v_mul_f32_e32 v233, 0xbfb8aa3b, v75
	v_mul_f32_e32 v234, 0xbfb8aa3b, v76
	v_mul_f32_e32 v235, 0xbfb8aa3b, v77
	v_exp_f32_e32 v232, v232
	v_exp_f32_e32 v233, v233
	v_exp_f32_e32 v234, v234
	v_exp_f32_e32 v235, v235
	v_add_f32_e32 v232, 1.0, v232
	v_add_f32_e32 v233, 1.0, v233
	v_add_f32_e32 v234, 1.0, v234
	v_add_f32_e32 v235, 1.0, v235
	v_rcp_f32_e32 v232, v232
	v_rcp_f32_e32 v233, v233
	v_rcp_f32_e32 v234, v234
	v_rcp_f32_e32 v235, v235
	v_mul_f32_e32 v74, v74, v232
	v_mul_f32_e32 v75, v75, v233
	v_mul_f32_e32 v76, v76, v234
	v_mul_f32_e32 v77, v77, v235
	v_mul_f32_e32 v74, v74, v90
	v_mul_f32_e32 v75, v75, v91
	v_mul_f32_e32 v76, v76, v92
	v_mul_f32_e32 v77, v77, v93
	v_cvt_pk_f16_f32 v142, v74, v75
	v_cvt_pk_f16_f32 v143, v76, v77
	ds_write_b64 v130, v[142:143] offset:2592
	v_mul_f32_e32 v232, 0xbfb8aa3b, v78
	v_mul_f32_e32 v233, 0xbfb8aa3b, v79
	v_mul_f32_e32 v234, 0xbfb8aa3b, v80
	v_mul_f32_e32 v235, 0xbfb8aa3b, v81
	v_exp_f32_e32 v232, v232
	v_exp_f32_e32 v233, v233
	v_exp_f32_e32 v234, v234
	v_exp_f32_e32 v235, v235
	v_add_f32_e32 v232, 1.0, v232
	v_add_f32_e32 v233, 1.0, v233
	v_add_f32_e32 v234, 1.0, v234
	v_add_f32_e32 v235, 1.0, v235
	v_rcp_f32_e32 v232, v232
	v_rcp_f32_e32 v233, v233
	v_rcp_f32_e32 v234, v234
	v_rcp_f32_e32 v235, v235
	v_mul_f32_e32 v78, v78, v232
	v_mul_f32_e32 v79, v79, v233
	v_mul_f32_e32 v80, v80, v234
	v_mul_f32_e32 v81, v81, v235
	v_mul_f32_e32 v78, v78, v94
	v_mul_f32_e32 v79, v79, v95
	v_mul_f32_e32 v80, v80, v96
	v_mul_f32_e32 v81, v81, v97
	v_cvt_pk_f16_f32 v144, v78, v79
	v_cvt_pk_f16_f32 v145, v80, v81
	ds_write_b64 v130, v[144:145] offset:2608
	v_mul_f32_e32 v232, 0xbfb8aa3b, v34
	v_mul_f32_e32 v233, 0xbfb8aa3b, v35
	v_mul_f32_e32 v234, 0xbfb8aa3b, v36
	v_mul_f32_e32 v235, 0xbfb8aa3b, v37
	v_exp_f32_e32 v232, v232
	v_exp_f32_e32 v233, v233
	v_exp_f32_e32 v234, v234
	v_exp_f32_e32 v235, v235
	v_add_f32_e32 v232, 1.0, v232
	v_add_f32_e32 v233, 1.0, v233
	v_add_f32_e32 v234, 1.0, v234
	v_add_f32_e32 v235, 1.0, v235
	v_rcp_f32_e32 v232, v232
	v_rcp_f32_e32 v233, v233
	v_rcp_f32_e32 v234, v234
	v_rcp_f32_e32 v235, v235
	v_mul_f32_e32 v34, v34, v232
	v_mul_f32_e32 v35, v35, v233
	v_mul_f32_e32 v36, v36, v234
	v_mul_f32_e32 v37, v37, v235
; DI float silu_(float x) { return x / (1.f + __expf(-x)); }
; DI void phase_ffn1_dense(const Params& p, int bid, int nb, h16* lds) {
;     ...
;     gemm256_epilogue(acc, m0, n0, [&](int m, int n, f4v v0, f4v v1) {
;       f4v hq;
; #pragma unroll
;       for (int i = 0; i < 4; ++i) hq[i] = silu_(v0[i]) * v1[i];
;       st_h4(&H[(size_t)m * 2816 + (n >> 6) * 32 + (n & 31)], hq);
;     });
	v_mul_f32_e32 v34, v34, v50
	v_mul_f32_e32 v35, v35, v51
	v_mul_f32_e32 v36, v36, v52
	v_mul_f32_e32 v37, v37, v53
	v_cvt_pk_f16_f32 v138, v34, v35
	v_cvt_pk_f16_f32 v139, v36, v37
	ds_write_b64 v130, v[138:139] offset:5120
	v_mul_f32_e32 v232, 0xbfb8aa3b, v38
	v_mul_f32_e32 v233, 0xbfb8aa3b, v39
	v_mul_f32_e32 v234, 0xbfb8aa3b, v40
	v_mul_f32_e32 v235, 0xbfb8aa3b, v41
	v_exp_f32_e32 v232, v232
	v_exp_f32_e32 v233, v233
	v_exp_f32_e32 v234, v234
	v_exp_f32_e32 v235, v235
	v_add_f32_e32 v232, 1.0, v232
	v_add_f32_e32 v233, 1.0, v233
	v_add_f32_e32 v234, 1.0, v234
	v_add_f32_e32 v235, 1.0, v235
	v_rcp_f32_e32 v232, v232
	v_rcp_f32_e32 v233, v233
	v_rcp_f32_e32 v234, v234
	v_rcp_f32_e32 v235, v235
	v_mul_f32_e32 v38, v38, v232
	v_mul_f32_e32 v39, v39, v233
	v_mul_f32_e32 v40, v40, v234
	v_mul_f32_e32 v41, v41, v235
	v_mul_f32_e32 v38, v38, v54
	v_mul_f32_e32 v39, v39, v55
	v_mul_f32_e32 v40, v40, v56
	v_mul_f32_e32 v41, v41, v57
	v_cvt_pk_f16_f32 v140, v38, v39
	v_cvt_pk_f16_f32 v141, v40, v41
	ds_write_b64 v130, v[140:141] offset:5136
	v_mul_f32_e32 v232, 0xbfb8aa3b, v42
	v_mul_f32_e32 v233, 0xbfb8aa3b, v43
	v_mul_f32_e32 v234, 0xbfb8aa3b, v44
	v_mul_f32_e32 v235, 0xbfb8aa3b, v45
	v_exp_f32_e32 v232, v232
	v_exp_f32_e32 v233, v233
	v_exp_f32_e32 v234, v234
	v_exp_f32_e32 v235, v235
	v_add_f32_e32 v232, 1.0, v232
	v_add_f32_e32 v233, 1.0, v233
	v_add_f32_e32 v234, 1.0, v234
	v_add_f32_e32 v235, 1.0, v235
	v_rcp_f32_e32 v232, v232
	v_rcp_f32_e32 v233, v233
	v_rcp_f32_e32 v234, v234
	v_rcp_f32_e32 v235, v235
	v_mul_f32_e32 v42, v42, v232
	v_mul_f32_e32 v43, v43, v233
	v_mul_f32_e32 v44, v44, v234
	v_mul_f32_e32 v45, v45, v235
	v_mul_f32_e32 v42, v42, v58
	v_mul_f32_e32 v43, v43, v59
	v_mul_f32_e32 v44, v44, v60
	v_mul_f32_e32 v45, v45, v61
	v_cvt_pk_f16_f32 v142, v42, v43
	v_cvt_pk_f16_f32 v143, v44, v45
	ds_write_b64 v130, v[142:143] offset:5152
	v_mul_f32_e32 v232, 0xbfb8aa3b, v46
	v_mul_f32_e32 v233, 0xbfb8aa3b, v47
	v_mul_f32_e32 v234, 0xbfb8aa3b, v48
	v_mul_f32_e32 v235, 0xbfb8aa3b, v49
	v_exp_f32_e32 v232, v232
	v_exp_f32_e32 v233, v233
	v_exp_f32_e32 v234, v234
	v_exp_f32_e32 v235, v235
	v_add_f32_e32 v232, 1.0, v232
	v_add_f32_e32 v233, 1.0, v233
	v_add_f32_e32 v234, 1.0, v234
	v_add_f32_e32 v235, 1.0, v235
	v_rcp_f32_e32 v232, v232
	v_rcp_f32_e32 v233, v233
	v_rcp_f32_e32 v234, v234
	v_rcp_f32_e32 v235, v235
	v_mul_f32_e32 v46, v46, v232
	v_mul_f32_e32 v47, v47, v233
	v_mul_f32_e32 v48, v48, v234
	v_mul_f32_e32 v49, v49, v235
	v_mul_f32_e32 v46, v46, v62
	v_mul_f32_e32 v47, v47, v63
	v_mul_f32_e32 v48, v48, v64
	v_mul_f32_e32 v49, v49, v65
	v_cvt_pk_f16_f32 v144, v46, v47
	v_cvt_pk_f16_f32 v145, v48, v49
	ds_write_b64 v130, v[144:145] offset:5168
	v_mul_f32_e32 v232, 0xbfb8aa3b, v2
	v_mul_f32_e32 v233, 0xbfb8aa3b, v3
	v_mul_f32_e32 v234, 0xbfb8aa3b, v4
	v_mul_f32_e32 v235, 0xbfb8aa3b, v5
	v_exp_f32_e32 v232, v232
	v_exp_f32_e32 v233, v233
	v_exp_f32_e32 v234, v234
	v_exp_f32_e32 v235, v235
	v_add_f32_e32 v232, 1.0, v232
	v_add_f32_e32 v233, 1.0, v233
	v_add_f32_e32 v234, 1.0, v234
	v_add_f32_e32 v235, 1.0, v235
	v_rcp_f32_e32 v232, v232
	v_rcp_f32_e32 v233, v233
	v_rcp_f32_e32 v234, v234
	v_rcp_f32_e32 v235, v235
	v_mul_f32_e32 v2, v2, v232
	v_mul_f32_e32 v3, v3, v233
	v_mul_f32_e32 v4, v4, v234
	v_mul_f32_e32 v5, v5, v235
	v_mul_f32_e32 v2, v2, v18
	v_mul_f32_e32 v3, v3, v19
	v_mul_f32_e32 v4, v4, v20
	v_mul_f32_e32 v5, v5, v21
	v_cvt_pk_f16_f32 v138, v2, v3
	v_cvt_pk_f16_f32 v139, v4, v5
	ds_write_b64 v130, v[138:139] offset:7680
	v_mul_f32_e32 v232, 0xbfb8aa3b, v6
	v_mul_f32_e32 v233, 0xbfb8aa3b, v7
	v_mul_f32_e32 v234, 0xbfb8aa3b, v8
	v_mul_f32_e32 v235, 0xbfb8aa3b, v9
	v_exp_f32_e32 v232, v232
	v_exp_f32_e32 v233, v233
	v_exp_f32_e32 v234, v234
	v_exp_f32_e32 v235, v235
	v_add_f32_e32 v232, 1.0, v232
	v_add_f32_e32 v233, 1.0, v233
	v_add_f32_e32 v234, 1.0, v234
	v_add_f32_e32 v235, 1.0, v235
	v_rcp_f32_e32 v232, v232
	v_rcp_f32_e32 v233, v233
	v_rcp_f32_e32 v234, v234
	v_rcp_f32_e32 v235, v235
	v_mul_f32_e32 v6, v6, v232
	v_mul_f32_e32 v7, v7, v233
	v_mul_f32_e32 v8, v8, v234
	v_mul_f32_e32 v9, v9, v235
	v_mul_f32_e32 v6, v6, v22
	v_mul_f32_e32 v7, v7, v23
	v_mul_f32_e32 v8, v8, v24
	v_mul_f32_e32 v9, v9, v25
	v_cvt_pk_f16_f32 v140, v6, v7
	v_cvt_pk_f16_f32 v141, v8, v9
	ds_write_b64 v130, v[140:141] offset:7696
	v_mul_f32_e32 v232, 0xbfb8aa3b, v10
	v_mul_f32_e32 v233, 0xbfb8aa3b, v11
	v_mul_f32_e32 v234, 0xbfb8aa3b, v12
	v_mul_f32_e32 v235, 0xbfb8aa3b, v13
	v_exp_f32_e32 v232, v232
	v_exp_f32_e32 v233, v233
	v_exp_f32_e32 v234, v234
	v_exp_f32_e32 v235, v235
	v_add_f32_e32 v232, 1.0, v232
	v_add_f32_e32 v233, 1.0, v233
	v_add_f32_e32 v234, 1.0, v234
	v_add_f32_e32 v235, 1.0, v235
	v_rcp_f32_e32 v232, v232
	v_rcp_f32_e32 v233, v233
	v_rcp_f32_e32 v234, v234
	v_rcp_f32_e32 v235, v235
	v_mul_f32_e32 v10, v10, v232
	v_mul_f32_e32 v11, v11, v233
	v_mul_f32_e32 v12, v12, v234
	v_mul_f32_e32 v13, v13, v235
	v_mul_f32_e32 v10, v10, v26
	v_mul_f32_e32 v11, v11, v27
	v_mul_f32_e32 v12, v12, v28
	v_mul_f32_e32 v13, v13, v29
	v_cvt_pk_f16_f32 v142, v10, v11
	v_cvt_pk_f16_f32 v143, v12, v13
	ds_write_b64 v130, v[142:143] offset:7712
	v_mul_f32_e32 v232, 0xbfb8aa3b, v14
	v_mul_f32_e32 v233, 0xbfb8aa3b, v15
	v_mul_f32_e32 v234, 0xbfb8aa3b, v16
	v_mul_f32_e32 v235, 0xbfb8aa3b, v17
	v_exp_f32_e32 v232, v232
	v_exp_f32_e32 v233, v233
	v_exp_f32_e32 v234, v234
	v_exp_f32_e32 v235, v235
	v_add_f32_e32 v232, 1.0, v232
	v_add_f32_e32 v233, 1.0, v233
	v_add_f32_e32 v234, 1.0, v234
	v_add_f32_e32 v235, 1.0, v235
	v_rcp_f32_e32 v232, v232
	v_rcp_f32_e32 v233, v233
	v_rcp_f32_e32 v234, v234
	v_rcp_f32_e32 v235, v235
	v_mul_f32_e32 v14, v14, v232
	v_mul_f32_e32 v15, v15, v233
	v_mul_f32_e32 v16, v16, v234
	v_mul_f32_e32 v17, v17, v235
	v_mul_f32_e32 v14, v14, v30
	v_mul_f32_e32 v15, v15, v31
	v_mul_f32_e32 v16, v16, v32
	v_mul_f32_e32 v17, v17, v33
	v_cvt_pk_f16_f32 v144, v14, v15
	v_cvt_pk_f16_f32 v145, v16, v17
	ds_write_b64 v130, v[144:145] offset:7728
	ds_read_b128 v[150:153], v131 offset:0
	ds_read_b128 v[154:157], v131 offset:1280
	ds_read_b128 v[158:161], v131 offset:2560
	ds_read_b128 v[162:165], v131 offset:3840
	ds_read_b128 v[216:219], v131 offset:5120
	ds_read_b128 v[220:223], v131 offset:6400
	ds_read_b128 v[224:227], v131 offset:7680
	ds_read_b128 v[228:231], v131 offset:8960
	s_waitcnt lgkmcnt(7)
; DI float silu_(float x) { return x / (1.f + __expf(-x)); }
; DI void phase_ffn1_dense(const Params& p, int bid, int nb, h16* lds) {
;     ...
;   for (int u = bid; u < 64 * 22; u += nb) {
;     const int m0 = (u / 22) * 256, n0 = (u % 22) * 256;
;     f16v acc[4][2]; acc256_zero(acc);
;     gemm256_main<false>(x16, DM, nullptr, m0, w13, 1024, n0, 1024, lds, acc);
;     gemm256_epilogue(acc, m0, n0, [&](int m, int n, f4v v0, f4v v1) {
;       f4v hq;
; #pragma unroll
;       for (int i = 0; i < 4; ++i) hq[i] = silu_(v0[i]) * v1[i];
;       st_h4(&H[(size_t)m * 2816 + (n >> 6) * 32 + (n & 31)], hq);
;     });
	global_store_dwordx4 v[132:133], v[150:153], off
	v_lshl_add_u64 v[132:133], v[132:133], 0, s[76:77]
	s_waitcnt lgkmcnt(6)
	global_store_dwordx4 v[132:133], v[154:157], off
	v_lshl_add_u64 v[132:133], v[132:133], 0, s[76:77]
	s_waitcnt lgkmcnt(5)
	global_store_dwordx4 v[132:133], v[158:161], off
	v_lshl_add_u64 v[132:133], v[132:133], 0, s[76:77]
	s_waitcnt lgkmcnt(4)
	global_store_dwordx4 v[132:133], v[162:165], off
	v_lshl_add_u64 v[132:133], v[132:133], 0, s[76:77]
	s_waitcnt lgkmcnt(3)
	global_store_dwordx4 v[132:133], v[216:219], off
	v_lshl_add_u64 v[132:133], v[132:133], 0, s[76:77]
	s_waitcnt lgkmcnt(2)
	global_store_dwordx4 v[132:133], v[220:223], off
	v_lshl_add_u64 v[132:133], v[132:133], 0, s[76:77]
	s_waitcnt lgkmcnt(1)
	global_store_dwordx4 v[132:133], v[224:227], off
	v_lshl_add_u64 v[132:133], v[132:133], 0, s[76:77]
	s_waitcnt lgkmcnt(0)
	global_store_dwordx4 v[132:133], v[228:231], off
	v_lshl_add_u64 v[132:133], v[132:133], 0, s[76:77]
	s_add_i32 s2, s2, s16
	s_cmpk_lt_i32 s3, 0x580
	s_cbranch_scc1 .LBB0_1626
